# v37 plus all 615 flat_load/flat_store converted to global_load/global_store (addresses are global memory; no lgkmcnt coupling)
# baseline (speedup 1.0000x reference)
; __global__ void __launch_bounds__(NWAVES * 64, 2) fwd_kernel(Args args) {
;     ...
;                 for (int i = tid; i < 4 * 192; i += NWAVES * 64) { const int b = i / 192, c2 = i % 192; float s = args.in[5][l * MODW + cg * 192 + c2];
; #pragma unroll
;                     for (int w = 0; w < 8; ++w) s += red[(w * 4 + b) * 192 + c2];
;                     modbuf[(size_t)(l * 4 + b) * MODW + cg * 192 + c2] = s; }
.LBB0_21:
	v_mul_hi_i32 v2, v0, s47
	v_lshrrev_b32_e32 v3, 31, v2
	v_ashrrev_i32_e32 v2, 5, v2
	v_add_u32_e32 v14, v2, v3
	v_mad_u64_u32 v[2:3], s[2:3], v14, s48, v[0:1]
	v_add_u32_e32 v4, s53, v2
	v_ashrrev_i32_e32 v5, 31, v4
	v_lshl_add_u64 v[4:5], v[4:5], 2, s[22:23]
	global_load_dword v15, v[4:5], off
	ds_read2st64_b32 v[4:5], v1 offset1:12
	ds_read2st64_b32 v[6:7], v1 offset0:24 offset1:36
	ds_read2st64_b32 v[8:9], v1 offset0:48 offset1:60
	ds_read2st64_b32 v[10:11], v1 offset0:72 offset1:84
	v_mov_b64_e32 v[12:13], s[62:63]
	v_add_u32_e32 v3, 0x200, v0
	v_cmp_lt_i32_e64 s[2:3], s8, v0
	v_add_u32_e32 v14, s52, v14
	s_or_b64 s[64:65], s[2:3], s[64:65]
	v_mov_b32_e32 v0, v3
	v_ashrrev_i32_e32 v3, 31, v2
	v_mad_i64_i32 v[12:13], s[2:3], v14, s49, v[12:13]
	v_add_u32_e32 v1, 0x800, v1
	v_lshl_add_u64 v[2:3], v[2:3], 2, v[12:13]
	s_waitcnt vmcnt(0) lgkmcnt(0)
	v_add_f32_e32 v4, v15, v4
	v_add_f32_e32 v4, v4, v5
	s_waitcnt lgkmcnt(2)
	v_add_f32_e32 v4, v4, v6
	v_add_f32_e32 v4, v4, v7
	s_waitcnt lgkmcnt(1)
	v_add_f32_e32 v4, v4, v8
	v_add_f32_e32 v4, v4, v9
	s_waitcnt lgkmcnt(0)
	v_add_f32_e32 v4, v4, v10
	v_add_f32_e32 v4, v4, v11
	global_store_dword v[2:3], v4, off
	s_andn2_b64 exec, exec, s[64:65]
	s_cbranch_execnz .LBB0_21
	s_branch .LBB0_14

; __global__ void __launch_bounds__(NWAVES * 64, 2) fwd_kernel(Args args) {
;     ...
;             { v4u* z = (v4u*)((bf16*)(wsl + WS_WC_IN) + (size_t)MLA_IN * D); const int nz = (MLA_IN_PAD - MLA_IN) * D / 8;
;               for (int i = blockIdx.x * (NWAVES * 64) + tid; i < nz; i += G * NWAVES * 64) z[i] = (v4u){0u, 0u, 0u, 0u}; }
.LBB0_139:
	v_add_u32_e32 v4, s2, v4
	v_cmp_lt_i32_e32 vcc, s3, v4
	global_store_dwordx4 v[6:7], v[0:3], off
	s_or_b64 s[14:15], vcc, s[14:15]
	v_lshl_add_u64 v[6:7], v[6:7], 0, s[4:5]
	s_andn2_b64 exec, exec, s[14:15]
	s_cbranch_execnz .LBB0_139

;     __device__ __forceinline__ void operator()(const f32x4 (&acc)[2][2][4][2], const Unit& u, int wr, int wc, int fr, int fq) const {
;     ...
; #pragma unroll
;         for (int ai = 0; ai < 2; ++ai)
; #pragma unroll
;             for (int m = 0; m < 4; ++m) { bf16_t* rowp = O + (size_t)(row0 + ai * HALF + m * 16) * ldc + col0;
;                 if (ACT == 1) {
;                     const int ob = fr * 64 + 16 * fq, sw = ob ^ (((ob >> 9) & 1) << 5);
;                     rowp = O + ((size_t)(u.pm * (ldc / 64) + u.pn * 4 + (wc >> 1)) * 2 + ai) * 8192 + (((wr * 4 + m) * 2 + (wc & 1)) * 1024 + sw) / 2; }
;                 float rc[2][2], rs[2][2];
;                 if (ACT == 2) { const float pos = (float)((row0 + ai * HALF + m * 16) & 2047);
; #pragma unroll
;                     for (int n = 0; n < 2; ++n)
; #pragma unroll
;                         for (int e = 0; e < 2; ++e) { float r = pos * rinv[n][e]; r -= floorf(r); rs[n][e] = do_rope ? __builtin_amdgcn_sinf(r) : 0.f; rc[n][e] = do_rope ? __builtin_amdgcn_cosf(r) : 1.f; } }
; #pragma unroll
;                 for (int bj = 0; bj < 2; ++bj) { f32x4 v0 = acc[ai][bj][m][0], v1 = acc[ai][bj][m][1];
;                     if (ACT == 3) { const float pos = (float)((row0 + ai * HALF + m * 16) & 2047); float c3[4], s3[4];
; #pragma unroll
;                         for (int p = 0; p < 4; ++p) { float r = pos * rinv3[bj][p]; r -= floorf(r); s3[p] = rope3[bj] ? __builtin_amdgcn_sinf(r) : 0.f; c3[p] = rope3[bj] ? __builtin_amdgcn_cosf(r) : 1.f; }
;                         const f32x4 a = v0, b = v1;
;                         v0[0] = a[0] * c3[0] - a[1] * s3[0]; v0[1] = a[1] * c3[0] + a[0] * s3[0]; v0[2] = a[2] * c3[1] - a[3] * s3[1]; v0[3] = a[3] * c3[1] + a[2] * s3[1];
;                         v1[0] = b[0] * c3[2] - b[1] * s3[2]; v1[1] = b[1] * c3[2] + b[0] * s3[2]; v1[2] = b[2] * c3[3] - b[3] * s3[3]; v1[3] = b[3] * c3[3] + b[2] * s3[3]; }
;                     if (ACT == 2) { const f32x4 a = v0, b = v1;
;                         v0[0] = a[0] * rc[0][0] - a[1] * rs[0][0]; v0[1] = a[1] * rc[0][0] + a[0] * rs[0][0]; v0[2] = a[2] * rc[0][1] - a[3] * rs[0][1]; v0[3] = a[3] * rc[0][1] + a[2] * rs[0][1];
;                         v1[0] = b[0] * rc[1][0] - b[1] * rs[1][0]; v1[1] = b[1] * rc[1][0] + b[0] * rs[1][0]; v1[2] = b[2] * rc[1][1] - b[3] * rs[1][1]; v1[3] = b[3] * rc[1][1] + b[2] * rs[1][1]; }
.LBB0_780:
	v_mov_b32_e32 v140, 0
	s_lshl_b32 s51, s78, 8
	v_mbcnt_lo_u32_b32 v140, -1, v140
	v_mbcnt_hi_u32_b32 v140, -1, v140
	v_or_b32_e32 v140, s33, v140
	s_add_i32 s51, s51, s41
	v_and_or_b32 v152, v140, 15, s51
	s_lshl_b32 s50, s50, 8
	v_lshrrev_b32_e32 v140, 1, v140
	v_and_or_b32 v140, v140, 24, s50
	v_or_b32_e32 v140, s42, v140
	v_ashrrev_i32_e32 v141, 31, v140
	v_mov_b64_e32 v[144:145], s[60:61]
	v_mad_i64_i32 v[142:143], s[50:51], v152, s47, v[144:145]
	v_lshlrev_b64 v[146:147], 1, v[140:141]
	v_lshl_add_u64 v[140:141], v[142:143], 0, v[146:147]
	v_cvt_pk_bf16_f32 v120, v120, v121
	v_cvt_pk_bf16_f32 v121, v122, v123
	v_cvt_pk_bf16_f32 v122, v112, v113
	v_cvt_pk_bf16_f32 v123, v114, v115
	global_store_dwordx4 v[140:141], v[120:123], off
	v_cvt_pk_bf16_f32 v112, v124, v125
	v_cvt_pk_bf16_f32 v113, v126, v127
	v_cvt_pk_bf16_f32 v114, v116, v117
	v_cvt_pk_bf16_f32 v115, v118, v119
	global_store_dwordx4 v[140:141], v[112:115], off offset:256
	v_cvt_pk_bf16_f32 v104, v104, v105
	v_cvt_pk_bf16_f32 v105, v106, v107
	v_cvt_pk_bf16_f32 v106, v96, v97
	v_cvt_pk_bf16_f32 v107, v98, v99
	s_andn2_b64 vcc, exec, s[0:1]
	s_nop 0
	v_or_b32_e32 v112, 16, v152
	v_mad_i64_i32 v[112:113], s[50:51], v112, s47, v[144:145]
	v_lshl_add_u64 v[112:113], v[112:113], 0, v[146:147]
	global_store_dwordx4 v[112:113], v[104:107], off
	v_cvt_pk_bf16_f32 v96, v108, v109
	v_cvt_pk_bf16_f32 v97, v110, v111
	v_cvt_pk_bf16_f32 v98, v100, v101
	v_cvt_pk_bf16_f32 v99, v102, v103
	global_store_dwordx4 v[112:113], v[96:99], off offset:256
	v_cvt_pk_bf16_f32 v88, v88, v89
	v_cvt_pk_bf16_f32 v89, v90, v91
	v_cvt_pk_bf16_f32 v90, v80, v81
	v_cvt_pk_bf16_f32 v91, v82, v83
	s_mov_b64 s[0:1], -1
	s_nop 0
	v_or_b32_e32 v96, 32, v152
	v_mad_i64_i32 v[96:97], s[50:51], v96, s47, v[144:145]
	v_lshl_add_u64 v[96:97], v[96:97], 0, v[146:147]
	global_store_dwordx4 v[96:97], v[88:91], off
	v_cvt_pk_bf16_f32 v80, v92, v93
	v_cvt_pk_bf16_f32 v81, v94, v95
	v_cvt_pk_bf16_f32 v82, v84, v85
	v_cvt_pk_bf16_f32 v83, v86, v87
	global_store_dwordx4 v[96:97], v[80:83], off offset:256
	v_cvt_pk_bf16_f32 v56, v56, v57
	v_cvt_pk_bf16_f32 v57, v58, v59
	v_cvt_pk_bf16_f32 v58, v48, v49
	v_cvt_pk_bf16_f32 v59, v50, v51
	s_nop 1
	v_or_b32_e32 v80, 48, v152
	v_mad_i64_i32 v[80:81], s[50:51], v80, s47, v[144:145]
	v_lshl_add_u64 v[80:81], v[80:81], 0, v[146:147]
	global_store_dwordx4 v[80:81], v[56:59], off
	v_cvt_pk_bf16_f32 v48, v60, v61
	v_cvt_pk_bf16_f32 v49, v62, v63
	v_cvt_pk_bf16_f32 v50, v52, v53
	v_cvt_pk_bf16_f32 v51, v54, v55
	global_store_dwordx4 v[80:81], v[48:51], off offset:256
	s_nop 1
	v_add_u32_e32 v48, 0x80, v152
	v_mad_i64_i32 v[48:49], s[50:51], v48, s47, v[144:145]
	v_lshl_add_u64 v[52:53], v[48:49], 0, v[146:147]
	v_cvt_pk_bf16_f32 v48, v72, v73
	v_cvt_pk_bf16_f32 v49, v74, v75
	v_cvt_pk_bf16_f32 v50, v64, v65
	v_cvt_pk_bf16_f32 v51, v66, v67
	global_store_dwordx4 v[52:53], v[48:51], off
	s_nop 1
	v_cvt_pk_bf16_f32 v48, v76, v77
	v_cvt_pk_bf16_f32 v49, v78, v79
	v_cvt_pk_bf16_f32 v50, v68, v69
	v_cvt_pk_bf16_f32 v51, v70, v71
	global_store_dwordx4 v[52:53], v[48:51], off offset:256
	v_cvt_pk_bf16_f32 v40, v40, v41
	v_cvt_pk_bf16_f32 v41, v42, v43
	v_cvt_pk_bf16_f32 v42, v32, v33
	v_cvt_pk_bf16_f32 v43, v34, v35
	s_nop 1
	v_add_u32_e32 v48, 0x90, v152
	v_mad_i64_i32 v[48:49], s[50:51], v48, s47, v[144:145]
	v_lshl_add_u64 v[48:49], v[48:49], 0, v[146:147]
	global_store_dwordx4 v[48:49], v[40:43], off
	v_cvt_pk_bf16_f32 v32, v44, v45
	v_cvt_pk_bf16_f32 v33, v46, v47
	v_cvt_pk_bf16_f32 v34, v36, v37
	v_cvt_pk_bf16_f32 v35, v38, v39
	global_store_dwordx4 v[48:49], v[32:35], off offset:256
	v_cvt_pk_bf16_f32 v24, v24, v25
	v_cvt_pk_bf16_f32 v25, v26, v27
	v_cvt_pk_bf16_f32 v26, v16, v17
	v_cvt_pk_bf16_f32 v27, v18, v19
	s_nop 1
	v_add_u32_e32 v32, 0xa0, v152
	v_mad_i64_i32 v[32:33], s[50:51], v32, s47, v[144:145]
	v_lshl_add_u64 v[32:33], v[32:33], 0, v[146:147]
	global_store_dwordx4 v[32:33], v[24:27], off
	v_cvt_pk_bf16_f32 v16, v28, v29
	v_cvt_pk_bf16_f32 v17, v30, v31
	v_cvt_pk_bf16_f32 v18, v20, v21
	v_cvt_pk_bf16_f32 v19, v22, v23
	global_store_dwordx4 v[32:33], v[16:19], off offset:256
	v_cvt_pk_bf16_f32 v8, v8, v9
	v_cvt_pk_bf16_f32 v9, v10, v11
	v_cvt_pk_bf16_f32 v10, v0, v1
	v_cvt_pk_bf16_f32 v11, v2, v3
	s_nop 1
	v_add_u32_e32 v16, 0xb0, v152
	v_mad_i64_i32 v[16:17], s[50:51], v16, s47, v[144:145]
	v_lshl_add_u64 v[16:17], v[16:17], 0, v[146:147]
	global_store_dwordx4 v[16:17], v[8:11], off
	v_cvt_pk_bf16_f32 v0, v12, v13
	v_cvt_pk_bf16_f32 v1, v14, v15
	v_cvt_pk_bf16_f32 v2, v4, v5
	v_cvt_pk_bf16_f32 v3, v6, v7
	global_store_dwordx4 v[16:17], v[0:3], off offset:256
	s_cbranch_vccnz .LBB0_773
	s_andn2_b64 vcc, exec, s[4:5]
	s_cbranch_vccnz .LBB0_772
	s_barrier
	s_branch .LBB0_772

; __device__ __forceinline__ unsigned cvt_pk_bf16(float lo, float hi) { unsigned r; asm volatile("v_cvt_pk_bf16_f32 %0, %1, %2" : "=v"(r) : "v"(lo), "v"(hi)); return r; }
;     __device__ __forceinline__ void fused(f32x4 (&acc)[2][2][4][2], const Unit& un, int wr, int wc, int fr, int fq, PG8_LAS unsigned char* lds, int wid, int lane) const {
;     ...
;         { f32x4 gv[2][2];
; #pragma unroll
;           for (int bj = 0; bj < 2; ++bj)
; #pragma unroll
;               for (int n = 0; n < 2; ++n) gv[bj][n] = *(const f32x4*)(gate + boff + bj * HALF + n * 4);
; #pragma unroll
;           for (int ai = 0; ai < 2; ++ai)
; #pragma unroll
;               for (int m = 0; m < 4; ++m) { const size_t off = (size_t)(row0 + ai * HALF + m * 16) * ldc + col0;
; #pragma unroll
;                   for (int bj = 0; bj < 2; ++bj) {
; #pragma unroll
;                       for (int n = 0; n < 2; ++n) { f32x4 bs;
;                           if (BASE_F32) bs = *(const f32x4*)((const float*)base + off + bj * HALF + n * 4);
;                           else { const u32x2v hw = *(const u32x2v*)((const bf16_t*)base + off + bj * HALF + n * 4);
;                                  bs = (f32x4){__uint_as_float(hw.x << 16), __uint_as_float(hw.x & 0xffff0000u), __uint_as_float(hw.y << 16), __uint_as_float(hw.y & 0xffff0000u)}; }
;                           acc[ai][bj][m][n] = bs + gv[bj][n] * acc[ai][bj][m][n]; }
;                       if (out_h) { const f32x4 a0 = acc[ai][bj][m][0], a1 = acc[ai][bj][m][1]; u32x4 w; w.x = cvt_pk_bf16(a0[0], a0[1]); w.y = cvt_pk_bf16(a0[2], a0[3]); w.z = cvt_pk_bf16(a1[0], a1[1]); w.w = cvt_pk_bf16(a1[2], a1[3]);
;                           *(u32x4*)(out_h + off + bj * HALF) = w; } }
.LBB0_1046:
	v_mov_b32_e32 v128, 0
	s_barrier
	s_lshl_b32 s4, s9, 5
	v_mbcnt_lo_u32_b32 v128, -1, v128
	s_add_u32 s0, s62, 0x1a600000
	v_mbcnt_hi_u32_b32 v128, -1, v128
	s_addc_u32 s1, s63, 0
	v_or_b32_e32 v152, s33, v128
	s_lshl_b32 s5, s2, 8
	s_or_b32 s4, s5, s4
	v_lshrrev_b32_e32 v128, 1, v152
	v_and_or_b32 v144, v128, 24, s4
	s_ashr_i32 s4, s64, 3
	v_ashrrev_i32_e32 v145, 31, v144
	v_mov_b32_e32 v128, 0x3000
	s_lshl_b32 s14, s64, 8
	v_mad_i64_i32 v[128:129], s[4:5], s4, v128, v[144:145]
	v_and_b32_e32 v153, 15, v152
	s_add_i32 s15, s14, s8
	v_lshl_add_u64 v[146:147], v[128:129], 2, s[62:63]
	s_mov_b32 s21, 0x104000
	v_add_co_u32_e32 v128, vcc, s21, v146
	v_or_b32_e32 v150, s15, v153
	s_nop 0
	v_addc_co_u32_e32 v129, vcc, 0, v147, vcc
	v_ashrrev_i32_e32 v151, 31, v150
	v_readlane_b32 s36, v254, 11
	global_load_dwordx4 v[136:139], v[128:129], off
	v_lshlrev_b64 v[128:129], 11, v[150:151]
	v_readlane_b32 s37, v254, 12
	s_mov_b64 s[4:5], 0x104000
	v_lshl_add_u64 v[148:149], v[128:129], 0, v[144:145]
	s_mov_b64 s[12:13], s[36:37]
	v_lshl_add_u64 v[162:163], v[148:149], 2, s[12:13]
	v_lshl_add_u64 v[128:129], v[146:147], 0, s[4:5]
	global_load_dwordx4 v[154:157], v[162:163], off offset:16
	global_load_dwordx4 v[158:161], v[162:163], off
	global_load_dwordx4 v[140:143], v[128:129], off offset:16
	v_lshl_add_u64 v[164:165], v[148:149], 1, s[0:1]
	global_load_dwordx4 v[132:135], v[128:129], off offset:512
	s_nop 0
	global_load_dwordx4 v[128:131], v[128:129], off offset:528
	s_mov_b64 s[4:5], 0x40000
	v_readlane_b32 s38, v254, 13
	v_readlane_b32 s39, v254, 14
	v_readlane_b32 s40, v254, 15
	v_readlane_b32 s41, v254, 16
	v_readlane_b32 s42, v254, 17
	v_readlane_b32 s43, v254, 18
	v_readlane_b32 s44, v254, 19
	v_readlane_b32 s45, v254, 20
	v_readlane_b32 s46, v254, 21
	v_readlane_b32 s47, v254, 22
	v_readlane_b32 s48, v254, 23
	v_readlane_b32 s49, v254, 24
	v_readlane_b32 s50, v254, 25
	v_readlane_b32 s51, v254, 26
	s_waitcnt vmcnt(0) lgkmcnt(0)
	v_pk_fma_f32 v[10:11], v[10:11], v[138:139], v[160:161]
	v_pk_fma_f32 v[8:9], v[8:9], v[136:137], v[158:159]
	v_pk_fma_f32 v[14:15], v[14:15], v[142:143], v[156:157]
	v_pk_fma_f32 v[12:13], v[12:13], v[140:141], v[154:155]
	v_cvt_pk_bf16_f32 v154, v8, v9
	v_cvt_pk_bf16_f32 v155, v10, v11
	s_nop 0
	v_cvt_pk_bf16_f32 v156, v12, v13
	v_cvt_pk_bf16_f32 v157, v14, v15
	global_store_dwordx4 v[164:165], v[154:157], off
	global_load_dwordx4 v[154:157], v[162:163], off offset:512
	s_nop 0
	global_load_dwordx4 v[158:161], v[162:163], off offset:528
	v_or_b32_e32 v162, 16, v150
	v_ashrrev_i32_e32 v163, 31, v162
	v_lshlrev_b64 v[162:163], 11, v[162:163]
	v_lshl_add_u64 v[162:163], v[162:163], 0, v[144:145]
	v_lshl_add_u64 v[166:167], v[162:163], 2, s[12:13]
	v_lshl_add_u64 v[162:163], v[162:163], 1, s[0:1]
	s_waitcnt vmcnt(0)
	v_pk_fma_f32 v[46:47], v[46:47], v[134:135], v[156:157]
	v_pk_fma_f32 v[44:45], v[44:45], v[132:133], v[154:155]
	v_pk_fma_f32 v[42:43], v[42:43], v[130:131], v[160:161]
	v_pk_fma_f32 v[40:41], v[40:41], v[128:129], v[158:159]
	v_cvt_pk_bf16_f32 v154, v44, v45
	v_cvt_pk_bf16_f32 v155, v46, v47
	s_nop 0
	v_cvt_pk_bf16_f32 v156, v40, v41
	v_cvt_pk_bf16_f32 v157, v42, v43
	global_store_dwordx4 v[164:165], v[154:157], off offset:256
	global_load_dwordx4 v[154:157], v[166:167], off
	global_load_dwordx4 v[158:161], v[166:167], off offset:16
	v_or_b32_e32 v164, 32, v150
	v_ashrrev_i32_e32 v165, 31, v164
	v_lshlrev_b64 v[164:165], 11, v[164:165]
	v_lshl_add_u64 v[164:165], v[164:165], 0, v[144:145]
	v_or_b32_e32 v150, 48, v150
	v_ashrrev_i32_e32 v151, 31, v150
	v_lshlrev_b64 v[150:151], 11, v[150:151]
	v_lshl_add_u64 v[150:151], v[150:151], 0, v[144:145]
	s_waitcnt vmcnt(0)
	v_pk_fma_f32 v[38:39], v[38:39], v[138:139], v[156:157]
	v_pk_fma_f32 v[36:37], v[36:37], v[136:137], v[154:155]
	v_pk_fma_f32 v[34:35], v[34:35], v[142:143], v[160:161]
	v_pk_fma_f32 v[32:33], v[32:33], v[140:141], v[158:159]
	v_cvt_pk_bf16_f32 v154, v36, v37
	v_cvt_pk_bf16_f32 v155, v38, v39
	s_nop 0
	v_cvt_pk_bf16_f32 v156, v32, v33
	v_cvt_pk_bf16_f32 v157, v34, v35
	global_store_dwordx4 v[162:163], v[154:157], off
	global_load_dwordx4 v[154:157], v[166:167], off offset:512
	s_nop 0
	global_load_dwordx4 v[158:161], v[166:167], off offset:528
	v_lshl_add_u64 v[166:167], v[164:165], 2, s[12:13]
	s_waitcnt vmcnt(0)
	v_pk_fma_f32 v[54:55], v[54:55], v[134:135], v[156:157]
	v_pk_fma_f32 v[52:53], v[52:53], v[132:133], v[154:155]
	v_pk_fma_f32 v[50:51], v[50:51], v[130:131], v[160:161]
	v_pk_fma_f32 v[48:49], v[48:49], v[128:129], v[158:159]
	v_cvt_pk_bf16_f32 v154, v52, v53
	v_cvt_pk_bf16_f32 v155, v54, v55
	s_nop 0
	v_cvt_pk_bf16_f32 v156, v48, v49
	v_cvt_pk_bf16_f32 v157, v50, v51
	global_store_dwordx4 v[162:163], v[154:157], off offset:256
	global_load_dwordx4 v[154:157], v[166:167], off
	global_load_dwordx4 v[158:161], v[166:167], off offset:16
	v_lshl_add_u64 v[162:163], v[164:165], 1, s[0:1]
	v_lshl_add_u64 v[164:165], v[150:151], 2, s[12:13]
	v_lshl_add_u64 v[150:151], v[150:151], 1, s[0:1]
	s_waitcnt vmcnt(0)
	v_pk_fma_f32 v[62:63], v[62:63], v[138:139], v[156:157]
	v_pk_fma_f32 v[60:61], v[60:61], v[136:137], v[154:155]
	v_pk_fma_f32 v[58:59], v[58:59], v[142:143], v[160:161]
	v_pk_fma_f32 v[56:57], v[56:57], v[140:141], v[158:159]
	v_cvt_pk_bf16_f32 v154, v60, v61
	v_cvt_pk_bf16_f32 v155, v62, v63
	s_nop 0
	v_cvt_pk_bf16_f32 v156, v56, v57
	v_cvt_pk_bf16_f32 v157, v58, v59
	global_store_dwordx4 v[162:163], v[154:157], off
	global_load_dwordx4 v[154:157], v[166:167], off offset:512
	s_nop 0
	global_load_dwordx4 v[158:161], v[166:167], off offset:528
	s_waitcnt vmcnt(0)
; __device__ __forceinline__ unsigned cvt_pk_bf16(float lo, float hi) { unsigned r; asm volatile("v_cvt_pk_bf16_f32 %0, %1, %2" : "=v"(r) : "v"(lo), "v"(hi)); return r; }
;     __device__ __forceinline__ void fused(f32x4 (&acc)[2][2][4][2], const Unit& un, int wr, int wc, int fr, int fq, PG8_LAS unsigned char* lds, int wid, int lane) const {
;     ...
;           for (int ai = 0; ai < 2; ++ai)
; #pragma unroll
;               for (int m = 0; m < 4; ++m) { const size_t off = (size_t)(row0 + ai * HALF + m * 16) * ldc + col0;
; #pragma unroll
;                   for (int bj = 0; bj < 2; ++bj) {
; #pragma unroll
;                       for (int n = 0; n < 2; ++n) { f32x4 bs;
;                           if (BASE_F32) bs = *(const f32x4*)((const float*)base + off + bj * HALF + n * 4);
;                           else { const u32x2v hw = *(const u32x2v*)((const bf16_t*)base + off + bj * HALF + n * 4);
;                                  bs = (f32x4){__uint_as_float(hw.x << 16), __uint_as_float(hw.x & 0xffff0000u), __uint_as_float(hw.y << 16), __uint_as_float(hw.y & 0xffff0000u)}; }
;                           acc[ai][bj][m][n] = bs + gv[bj][n] * acc[ai][bj][m][n]; }
;                       if (out_h) { const f32x4 a0 = acc[ai][bj][m][0], a1 = acc[ai][bj][m][1]; u32x4 w; w.x = cvt_pk_bf16(a0[0], a0[1]); w.y = cvt_pk_bf16(a0[2], a0[3]); w.z = cvt_pk_bf16(a1[0], a1[1]); w.w = cvt_pk_bf16(a1[2], a1[3]);
;                           *(u32x4*)(out_h + off + bj * HALF) = w; } }
	v_pk_fma_f32 v[70:71], v[70:71], v[134:135], v[156:157]
	v_pk_fma_f32 v[68:69], v[68:69], v[132:133], v[154:155]
	v_pk_fma_f32 v[66:67], v[66:67], v[130:131], v[160:161]
	v_pk_fma_f32 v[64:65], v[64:65], v[128:129], v[158:159]
	v_cvt_pk_bf16_f32 v154, v68, v69
	v_cvt_pk_bf16_f32 v155, v70, v71
	s_nop 0
	v_cvt_pk_bf16_f32 v156, v64, v65
	v_cvt_pk_bf16_f32 v157, v66, v67
	global_store_dwordx4 v[162:163], v[154:157], off offset:256
	global_load_dwordx4 v[154:157], v[164:165], off
	global_load_dwordx4 v[158:161], v[164:165], off offset:16
	v_lshl_add_u64 v[162:163], v[148:149], 0, s[4:5]
	s_mov_b64 s[4:5], 0x48000
	s_waitcnt vmcnt(0)
	v_pk_fma_f32 v[82:83], v[82:83], v[138:139], v[156:157]
	v_pk_fma_f32 v[80:81], v[80:81], v[136:137], v[154:155]
	v_pk_fma_f32 v[74:75], v[74:75], v[142:143], v[160:161]
	v_pk_fma_f32 v[72:73], v[72:73], v[140:141], v[158:159]
	v_cvt_pk_bf16_f32 v154, v80, v81
	v_cvt_pk_bf16_f32 v155, v82, v83
	s_nop 0
	v_cvt_pk_bf16_f32 v156, v72, v73
	v_cvt_pk_bf16_f32 v157, v74, v75
	global_store_dwordx4 v[150:151], v[154:157], off
	global_load_dwordx4 v[154:157], v[164:165], off offset:512
	s_nop 0
	global_load_dwordx4 v[158:161], v[164:165], off offset:528
	v_lshl_add_u64 v[164:165], v[162:163], 2, s[12:13]
	s_waitcnt vmcnt(0)
	v_pk_fma_f32 v[102:103], v[102:103], v[134:135], v[156:157]
	v_pk_fma_f32 v[100:101], v[100:101], v[132:133], v[154:155]
	v_pk_fma_f32 v[98:99], v[98:99], v[130:131], v[160:161]
	v_pk_fma_f32 v[96:97], v[96:97], v[128:129], v[158:159]
	v_cvt_pk_bf16_f32 v154, v100, v101
	v_cvt_pk_bf16_f32 v155, v102, v103
	s_nop 0
	v_cvt_pk_bf16_f32 v156, v96, v97
	v_cvt_pk_bf16_f32 v157, v98, v99
	global_store_dwordx4 v[150:151], v[154:157], off offset:256
	global_load_dwordx4 v[154:157], v[164:165], off
	global_load_dwordx4 v[158:161], v[164:165], off offset:16
	v_lshl_add_u64 v[150:151], v[162:163], 1, s[0:1]
	v_lshl_add_u64 v[162:163], v[148:149], 0, s[4:5]
	s_mov_b64 s[4:5], 0x50000
	s_waitcnt vmcnt(0)
	v_pk_fma_f32 v[110:111], v[110:111], v[138:139], v[156:157]
	v_pk_fma_f32 v[108:109], v[108:109], v[136:137], v[154:155]
	v_pk_fma_f32 v[106:107], v[106:107], v[142:143], v[160:161]
	v_pk_fma_f32 v[104:105], v[104:105], v[140:141], v[158:159]
	v_cvt_pk_bf16_f32 v154, v108, v109
	v_cvt_pk_bf16_f32 v155, v110, v111
	s_nop 0
	v_cvt_pk_bf16_f32 v156, v104, v105
	v_cvt_pk_bf16_f32 v157, v106, v107
	global_store_dwordx4 v[150:151], v[154:157], off
	global_load_dwordx4 v[154:157], v[164:165], off offset:512
	s_nop 0
	global_load_dwordx4 v[158:161], v[164:165], off offset:528
	v_lshl_add_u64 v[164:165], v[162:163], 2, s[12:13]
	s_waitcnt vmcnt(0)
	v_pk_fma_f32 v[118:119], v[118:119], v[134:135], v[156:157]
	v_pk_fma_f32 v[116:117], v[116:117], v[132:133], v[154:155]
	v_pk_fma_f32 v[114:115], v[114:115], v[130:131], v[160:161]
	v_pk_fma_f32 v[112:113], v[112:113], v[128:129], v[158:159]
	v_cvt_pk_bf16_f32 v154, v116, v117
	v_cvt_pk_bf16_f32 v155, v118, v119
	s_nop 0
	v_cvt_pk_bf16_f32 v156, v112, v113
	v_cvt_pk_bf16_f32 v157, v114, v115
	global_store_dwordx4 v[150:151], v[154:157], off offset:256
	global_load_dwordx4 v[154:157], v[164:165], off
	global_load_dwordx4 v[158:161], v[164:165], off offset:16
	v_lshl_add_u64 v[150:151], v[162:163], 1, s[0:1]
	v_lshl_add_u64 v[162:163], v[148:149], 0, s[4:5]
	s_mov_b64 s[4:5], 0x58000
	s_waitcnt vmcnt(0)
	v_pk_fma_f32 v[126:127], v[126:127], v[138:139], v[156:157]
	v_pk_fma_f32 v[124:125], v[124:125], v[136:137], v[154:155]
	v_pk_fma_f32 v[122:123], v[122:123], v[142:143], v[160:161]
	v_pk_fma_f32 v[120:121], v[120:121], v[140:141], v[158:159]
	v_cvt_pk_bf16_f32 v154, v124, v125
	v_cvt_pk_bf16_f32 v155, v126, v127
	s_nop 0
	v_cvt_pk_bf16_f32 v156, v120, v121
	v_cvt_pk_bf16_f32 v157, v122, v123
	global_store_dwordx4 v[150:151], v[154:157], off
	global_load_dwordx4 v[154:157], v[164:165], off offset:512
	s_nop 0
	global_load_dwordx4 v[158:161], v[164:165], off offset:528
	v_lshl_add_u64 v[164:165], v[162:163], 2, s[12:13]
	v_lshl_add_u64 v[162:163], v[162:163], 1, s[0:1]
	s_waitcnt vmcnt(0)
; __device__ __forceinline__ unsigned cvt_pk_bf16(float lo, float hi) { unsigned r; asm volatile("v_cvt_pk_bf16_f32 %0, %1, %2" : "=v"(r) : "v"(lo), "v"(hi)); return r; }
;     __device__ __forceinline__ void fused(f32x4 (&acc)[2][2][4][2], const Unit& un, int wr, int wc, int fr, int fq, PG8_LAS unsigned char* lds, int wid, int lane) const {
;     ...
;           for (int ai = 0; ai < 2; ++ai)
; #pragma unroll
;               for (int m = 0; m < 4; ++m) { const size_t off = (size_t)(row0 + ai * HALF + m * 16) * ldc + col0;
; #pragma unroll
;                   for (int bj = 0; bj < 2; ++bj) {
; #pragma unroll
;                       for (int n = 0; n < 2; ++n) { f32x4 bs;
;                           if (BASE_F32) bs = *(const f32x4*)((const float*)base + off + bj * HALF + n * 4);
;                           else { const u32x2v hw = *(const u32x2v*)((const bf16_t*)base + off + bj * HALF + n * 4);
;                                  bs = (f32x4){__uint_as_float(hw.x << 16), __uint_as_float(hw.x & 0xffff0000u), __uint_as_float(hw.y << 16), __uint_as_float(hw.y & 0xffff0000u)}; }
;                           acc[ai][bj][m][n] = bs + gv[bj][n] * acc[ai][bj][m][n]; }
;                       if (out_h) { const f32x4 a0 = acc[ai][bj][m][0], a1 = acc[ai][bj][m][1]; u32x4 w; w.x = cvt_pk_bf16(a0[0], a0[1]); w.y = cvt_pk_bf16(a0[2], a0[3]); w.z = cvt_pk_bf16(a1[0], a1[1]); w.w = cvt_pk_bf16(a1[2], a1[3]);
;                           *(u32x4*)(out_h + off + bj * HALF) = w; } }
;                   asm volatile("" : "+v"(acc[ai][0][m][0]), "+v"(acc[ai][0][m][1]), "+v"(acc[ai][1][m][0]), "+v"(acc[ai][1][m][1]));
;                   asm volatile("" ::: "memory"); } }
; #pragma unroll
;         for (int ai = 0; ai < 2; ++ai)
; #pragma unroll
;             for (int m = 0; m < 4; ++m) { float s = 0.f;
; #pragma unroll
;                 for (int bj = 0; bj < 2; ++bj)
; #pragma unroll
;                     for (int n = 0; n < 2; ++n) { const f32x4 x = acc[ai][bj][m][n]; s += (x[0] * x[0] + x[1] * x[1]) + (x[2] * x[2] + x[3] * x[3]); }
;                 s += __shfl_xor(s, 16); s += __shfl_xor(s, 32);
;                 if (fq == 0) P[(ai * HALF + wr * 64 + m * 16 + fr) * 4 + wc] = s; }
	v_pk_fma_f32 v[94:95], v[94:95], v[134:135], v[156:157]
	v_pk_fma_f32 v[92:93], v[92:93], v[132:133], v[154:155]
	v_pk_fma_f32 v[90:91], v[90:91], v[130:131], v[160:161]
	v_pk_fma_f32 v[88:89], v[88:89], v[128:129], v[158:159]
	v_cvt_pk_bf16_f32 v154, v92, v93
	v_cvt_pk_bf16_f32 v155, v94, v95
	s_nop 0
	v_cvt_pk_bf16_f32 v156, v88, v89
	v_cvt_pk_bf16_f32 v157, v90, v91
	global_store_dwordx4 v[150:151], v[154:157], off offset:256
	global_load_dwordx4 v[154:157], v[164:165], off
	global_load_dwordx4 v[158:161], v[164:165], off offset:16
	s_waitcnt vmcnt(0)
	v_pk_fma_f32 v[86:87], v[86:87], v[138:139], v[156:157]
	v_pk_fma_f32 v[84:85], v[84:85], v[136:137], v[154:155]
	v_pk_fma_f32 v[78:79], v[78:79], v[142:143], v[160:161]
	v_pk_fma_f32 v[76:77], v[76:77], v[140:141], v[158:159]
	v_cvt_pk_bf16_f32 v154, v84, v85
	v_cvt_pk_bf16_f32 v155, v86, v87
	s_nop 0
	v_cvt_pk_bf16_f32 v156, v76, v77
	v_cvt_pk_bf16_f32 v157, v78, v79
	global_store_dwordx4 v[162:163], v[154:157], off
	global_load_dwordx4 v[154:157], v[164:165], off offset:512
	s_nop 0
	global_load_dwordx4 v[158:161], v[164:165], off offset:528
	v_lshl_add_u64 v[164:165], v[148:149], 0, s[4:5]
	v_lshl_add_u64 v[166:167], v[164:165], 2, s[12:13]
	s_waitcnt vmcnt(0)
	v_pk_fma_f32 v[30:31], v[30:31], v[134:135], v[156:157]
	v_pk_fma_f32 v[28:29], v[28:29], v[132:133], v[154:155]
	v_pk_fma_f32 v[26:27], v[26:27], v[130:131], v[160:161]
	v_pk_fma_f32 v[24:25], v[24:25], v[128:129], v[158:159]
	v_cvt_pk_bf16_f32 v148, v28, v29
	v_cvt_pk_bf16_f32 v149, v30, v31
	v_lshl_add_u64 v[158:159], v[164:165], 1, s[0:1]
	v_cvt_pk_bf16_f32 v150, v24, v25
	v_cvt_pk_bf16_f32 v151, v26, v27
	global_store_dwordx4 v[162:163], v[148:151], off offset:256
	global_load_dwordx4 v[148:151], v[166:167], off
	global_load_dwordx4 v[154:157], v[166:167], off offset:16
	v_mul_f32_e32 v160, v45, v45
	v_mul_f32_e32 v161, v47, v47
	v_mul_f32_e32 v162, v41, v41
	v_mul_f32_e32 v163, v43, v43
	v_fmac_f32_e32 v160, v44, v44
	v_fmac_f32_e32 v161, v46, v46
	v_fmac_f32_e32 v162, v40, v40
	v_fmac_f32_e32 v163, v42, v42
	s_lshl_b32 s0, s9, 2
	s_add_i32 s0, s0, 0
	s_waitcnt vmcnt(0)
	v_pk_fma_f32 v[22:23], v[22:23], v[138:139], v[150:151]
	v_pk_fma_f32 v[20:21], v[20:21], v[136:137], v[148:149]
	v_pk_fma_f32 v[18:19], v[18:19], v[142:143], v[156:157]
	v_pk_fma_f32 v[16:17], v[16:17], v[140:141], v[154:155]
	v_cvt_pk_bf16_f32 v136, v20, v21
	v_cvt_pk_bf16_f32 v137, v22, v23
	v_mul_f32_e32 v140, v9, v9
	v_cvt_pk_bf16_f32 v138, v16, v17
	v_cvt_pk_bf16_f32 v139, v18, v19
	global_store_dwordx4 v[158:159], v[136:139], off
	global_load_dwordx4 v[148:151], v[166:167], off offset:512
	global_load_dwordx4 v[154:157], v[166:167], off offset:528
	v_mbcnt_lo_u32_b32 v136, -1, 0
	v_mbcnt_hi_u32_b32 v136, -1, v136
	v_mul_f32_e32 v141, v11, v11
	v_mul_f32_e32 v142, v13, v13
	v_mul_f32_e32 v143, v15, v15
	v_and_b32_e32 v138, 64, v136
	v_fmac_f32_e32 v140, v8, v8
	v_fmac_f32_e32 v141, v10, v10
	v_fmac_f32_e32 v142, v12, v12
	v_fmac_f32_e32 v143, v14, v14
	v_xor_b32_e32 v137, 16, v136
	v_add_u32_e32 v138, 64, v138
	v_add_f32_e32 v140, v140, v141
	v_add_f32_e32 v141, v142, v143
	v_cmp_lt_i32_e32 vcc, v137, v138
	v_add_f32_e32 v142, v160, v161
	v_add_f32_e32 v140, v140, v141
	v_cndmask_b32_e32 v137, v136, v137, vcc
	v_add_f32_e32 v143, v162, v163
	v_add_f32_e32 v140, v142, v140
	v_lshlrev_b32_e32 v137, 2, v137
	v_add_f32_e32 v140, v143, v140
	ds_bpermute_b32 v141, v137, v140
	v_xor_b32_e32 v139, 32, v136
	v_cmp_lt_i32_e32 vcc, v139, v138
	s_waitcnt vmcnt(0)
	v_pk_fma_f32 v[6:7], v[6:7], v[134:135], v[150:151]
	v_cndmask_b32_e32 v136, v136, v139, vcc
	v_lshlrev_b32_e32 v138, 2, v136
	s_waitcnt lgkmcnt(0)
	v_add_f32_e32 v139, v140, v141
	ds_bpermute_b32 v140, v138, v139
	v_pk_fma_f32 v[4:5], v[4:5], v[132:133], v[148:149]
	v_pk_fma_f32 v[2:3], v[2:3], v[130:131], v[156:157]
	v_pk_fma_f32 v[0:1], v[0:1], v[128:129], v[154:155]
	v_cvt_pk_bf16_f32 v128, v4, v5
	v_cvt_pk_bf16_f32 v129, v6, v7
	v_and_b32_e32 v136, 63, v152
	v_cvt_pk_bf16_f32 v130, v0, v1
	v_cvt_pk_bf16_f32 v131, v2, v3
	global_store_dwordx4 v[158:159], v[128:131], off offset:256
	v_or_b32_e32 v148, s8, v153
	v_cmp_gt_u32_e32 vcc, 16, v136
	v_lshl_add_u32 v128, v148, 4, s0
	s_and_saveexec_b64 s[0:1], vcc
	v_readlane_b32 s96, v254, 47
	s_cbranch_execz .LBB0_1048
	s_waitcnt lgkmcnt(0)
	v_add_f32_e32 v129, v139, v140
	ds_write_b32 v128, v129

;     __device__ __forceinline__ void fused(f32x4 (&acc)[2][2][4][2], const Unit& un, int wr, int wc, int fr, int fq, PG8_LAS unsigned char* lds, int wid, int lane) const {
;     ...
;         asm volatile("s_waitcnt lgkmcnt(0)" ::: "memory"); __builtin_amdgcn_s_barrier(); asm volatile("" ::: "memory");
;         const int row = wid * 32 + (lane & 31);
;         if (lane < 32) { const float tot = (P[row * 4 + 0] + P[row * 4 + 1]) + (P[row * 4 + 2] + P[row * 4 + 3]);
;             __hip_atomic_store(xbuf + ((size_t)(un.pm * BM + row) * 8 + un.pn), __float_as_uint(tot), __ATOMIC_RELAXED, __HIP_MEMORY_SCOPE_AGENT); }
.LBB0_1062:
	s_or_b64 exec, exec, s[0:1]
	s_add_u32 s12, s62, 0x3c600000
	s_addc_u32 s13, s63, 0
	s_lshl_b32 s0, s7, 5
	s_waitcnt lgkmcnt(0)
	s_barrier
	v_and_or_b32 v134, v152, 31, s0
	v_add_u32_e32 v128, s14, v134
	v_cmp_gt_u32_e64 s[0:1], 32, v136
	v_ashrrev_i32_e32 v129, 31, v128
	s_and_saveexec_b64 s[4:5], s[0:1]
	s_cbranch_execz .LBB0_1064
	s_waitcnt lgkmcnt(0)
	v_lshl_add_u32 v130, v134, 4, 0
	ds_read_b128 v[130:133], v130
	v_lshlrev_b64 v[138:139], 5, v[128:129]
	v_lshl_add_u64 v[138:139], s[12:13], 0, v[138:139]
	s_waitcnt lgkmcnt(0)
	v_mov_b32_e32 v140, v131
	v_mov_b32_e32 v141, v132
	v_mov_b32_e32 v131, v133
	v_pk_add_f32 v[130:131], v[140:141], v[130:131]
	v_lshl_add_u64 v[132:133], s[2:3], 2, v[138:139]
	v_pk_add_f32 v[130:131], v[130:131], v[130:131] op_sel:[0,1] op_sel_hi:[1,0]
	global_store_dword v[132:133], v130, off sc1

;     __device__ __forceinline__ void fused(f32x4 (&acc)[2][2][4][2], const Unit& un, int wr, int wc, int fr, int fq, PG8_LAS unsigned char* lds, int wid, int lane) const {
;     ...
;         if (wid == 0) {
;             bool dead = false; const unsigned long long t0 = __builtin_amdgcn_s_memrealtime();
;             for (;;) {
;                 if ((unsigned)__builtin_amdgcn_readfirstlane(__hip_atomic_load(cnt + 64 * un.pm, __ATOMIC_RELAXED, __HIP_MEMORY_SCOPE_AGENT)) >= 64u) break;
;                 if (__builtin_amdgcn_s_memrealtime() - t0 > 2000000ull) {
;                     if (lane == 0) { unsigned expect = 0u; __hip_atomic_compare_exchange_strong(tmo + 1, &expect, code | (unsigned)(un.pm & 0xff), __ATOMIC_RELAXED, __ATOMIC_RELAXED, __HIP_MEMORY_SCOPE_AGENT);
;                                      __hip_atomic_store(tmo, 1u, __ATOMIC_RELAXED, __HIP_MEMORY_SCOPE_AGENT); }
;                     dead = true; break; }
;                 __builtin_amdgcn_s_sleep(2);
;             }
.LBB0_1070:
	global_load_dword v135, v[130:131], off sc1
	s_mov_b64 s[68:69], -1
	s_mov_b64 s[70:71], -1
	s_waitcnt vmcnt(0) lgkmcnt(0)
	v_readfirstlane_b32 s6, v135
	s_cmp_gt_u32 s6, 63
	s_cbranch_scc1 .LBB0_1069
	s_memrealtime s[6:7]
	s_waitcnt lgkmcnt(0)
	s_sub_u32 s6, s6, s66
	s_subb_u32 s7, s7, s67
	v_cmp_lt_u64_e32 vcc, s[6:7], v[132:133]
	s_cbranch_vccz .LBB0_1068
	s_mov_b64 s[70:71], 0
	s_sleep 2
	s_branch .LBB0_1068

;     __device__ __forceinline__ void fused(f32x4 (&acc)[2][2][4][2], const Unit& un, int wr, int wc, int fr, int fq, PG8_LAS unsigned char* lds, int wid, int lane) const {
;     ...
;                 if (__builtin_amdgcn_s_memrealtime() - t0 > 2000000ull) {
;                     if (lane == 0) { unsigned expect = 0u; __hip_atomic_compare_exchange_strong(tmo + 1, &expect, code | (unsigned)(un.pm & 0xff), __ATOMIC_RELAXED, __ATOMIC_RELAXED, __HIP_MEMORY_SCOPE_AGENT);
;                                      __hip_atomic_store(tmo, 1u, __ATOMIC_RELAXED, __HIP_MEMORY_SCOPE_AGENT); }
;                     dead = true; break; }
.LBB0_1076:
	s_or_saveexec_b64 s[66:67], s[4:5]
	s_mov_b64 s[4:5], 0
	s_xor_b64 exec, exec, s[66:67]
	s_cbranch_execz .LBB0_1078
	s_and_b32 s6, s64, 0xff
	s_or_b32 s6, s6, 0x700
	v_mov_b32_e32 v130, s6
	v_mov_b32_e32 v131, 0
	v_mov_b64_e32 v[132:133], s[62:63]
	flat_atomic_cmpswap v[132:133], v[130:131] offset:4
	s_mov_b64 s[4:5], exec
	v_mov_b32_e32 v130, 1
	global_store_dword v[132:133], v130, off sc1

;     __device__ __forceinline__ void fused(f32x4 (&acc)[2][2][4][2], const Unit& un, int wr, int wc, int fr, int fq, PG8_LAS unsigned char* lds, int wid, int lane) const {
;     ...
;         asm volatile("s_waitcnt vmcnt(0) lgkmcnt(0)" ::: "memory"); __builtin_amdgcn_s_barrier(); asm volatile("" ::: "memory");
;         const bool bad = flag[0] != 0u;
;         if (lane < 32) { const unsigned* slot = xbuf + (size_t)(un.pm * BM + row) * 8; float q = 0.f;
; #pragma unroll
;             for (int t = 0; t < 8; ++t) q += __uint_as_float(__hip_atomic_load(slot + t, __ATOMIC_RELAXED, __HIP_MEMORY_SCOPE_AGENT));
;             S[row] = 1.0f / sqrtf(q * (1.0f / 2048.0f) + eps); }
;         asm volatile("s_waitcnt lgkmcnt(0)" ::: "memory"); __builtin_amdgcn_s_barrier(); asm volatile("" ::: "memory");
;         const float qnan = __builtin_nanf("");
;         f32x4 cg[2][2], sh[2][2];
; #pragma unroll
;         for (int bj = 0; bj < 2; ++bj)
; #pragma unroll
;             for (int n = 0; n < 2; ++n) { const f32x4 g4 = *(const f32x4*)(gain + col0 + bj * HALF + n * 4);
;                 if (MODE == 0) { const f32x4 sc4 = *(const f32x4*)(scale + boff + bj * HALF + n * 4); cg[bj][n] = g4 * (sc4 + 1.0f); sh[bj][n] = *(const f32x4*)(shift + boff + bj * HALF + n * 4); }
;                 else { cg[bj][n] = g4; sh[bj][n] = (f32x4){0.f, 0.f, 0.f, 0.f}; } }
; #pragma unroll
;         for (int ai = 0; ai < 2; ++ai)
; #pragma unroll
;             for (int m = 0; m < 4; ++m) { const int r = ai * HALF + wr * 64 + m * 16 + fr; const float rs = S[r]; const size_t off = (size_t)(un.pm * BM + r) * ldc + col0;
; #pragma unroll
;                 for (int bj = 0; bj < 2; ++bj) { f32x4 y0 = (acc[ai][bj][m][0] * rs) * cg[bj][0] + sh[bj][0], y1 = (acc[ai][bj][m][1] * rs) * cg[bj][1] + sh[bj][1];
.LBB0_1084:
	s_waitcnt vmcnt(0) lgkmcnt(0)
	s_barrier
	s_waitcnt lgkmcnt(0)
	v_mov_b32_e32 v130, 0
	ds_read_b32 v150, v130 offset:5120
	s_and_saveexec_b64 s[2:3], s[0:1]
	s_cbranch_execz .LBB0_1086
	v_lshlrev_b64 v[128:129], 5, v[128:129]
	v_lshl_add_u64 v[128:129], s[12:13], 0, v[128:129]
	global_load_dword v130, v[128:129], off sc1
	global_load_dword v131, v[128:129], off offset:4 sc1
	global_load_dword v132, v[128:129], off offset:8 sc1
	global_load_dword v133, v[128:129], off offset:12 sc1
	global_load_dword v135, v[128:129], off offset:16 sc1
	global_load_dword v136, v[128:129], off offset:20 sc1
	global_load_dword v137, v[128:129], off offset:24 sc1
	s_nop 0
	global_load_dword v128, v[128:129], off offset:28 sc1
	v_mov_b32_e32 v129, 0x358637bd
	s_mov_b32 s0, 0xf800000
	s_waitcnt vmcnt(0) lgkmcnt(0)
	v_add_f32_e32 v130, 0, v130
	v_add_f32_e32 v130, v130, v131
	v_add_f32_e32 v130, v130, v132
	v_add_f32_e32 v130, v130, v133
	v_add_f32_e32 v130, v130, v135
	v_add_f32_e32 v130, v130, v136
	v_add_f32_e32 v130, v130, v137
	v_add_f32_e32 v128, v130, v128
	v_fmac_f32_e32 v129, 0x3a000000, v128
	v_mul_f32_e32 v128, 0x4f800000, v129
	v_cmp_gt_f32_e32 vcc, s0, v129
	v_mov_b32_e32 v130, 0x260
	s_nop 0
	v_cndmask_b32_e32 v128, v129, v128, vcc
	v_sqrt_f32_e32 v129, v128
	s_nop 0
	v_add_u32_e32 v131, -1, v129
	v_add_u32_e32 v132, 1, v129
	v_fma_f32 v133, -v131, v129, v128
	v_fma_f32 v135, -v132, v129, v128
	v_cmp_ge_f32_e64 s[0:1], 0, v133
	s_nop 1
	v_cndmask_b32_e64 v129, v129, v131, s[0:1]
	v_cmp_lt_f32_e64 s[0:1], 0, v135
	s_nop 1
	v_cndmask_b32_e64 v129, v129, v132, s[0:1]
	v_mul_f32_e32 v131, 0x37800000, v129
	v_cndmask_b32_e32 v129, v129, v131, vcc
	v_cmp_class_f32_e32 vcc, v128, v130
	s_nop 1
	v_cndmask_b32_e32 v128, v129, v128, vcc
	v_div_scale_f32 v129, s[0:1], v128, v128, 1.0
	v_rcp_f32_e32 v130, v129
	v_div_scale_f32 v131, vcc, 1.0, v128, 1.0
	v_fma_f32 v132, -v129, v130, 1.0
	v_fmac_f32_e32 v130, v132, v130
	v_mul_f32_e32 v132, v131, v130
	v_fma_f32 v133, -v129, v132, v131
	v_fmac_f32_e32 v132, v133, v130
	v_fma_f32 v129, -v129, v132, v131
	v_div_fmas_f32 v129, v129, v130, v132
	v_div_fixup_f32 v128, v129, v128, 1.0
	v_lshl_add_u32 v129, v134, 2, 0
	ds_write_b32 v129, v128 offset:4096
.LBB0_1086:
	s_or_b64 exec, exec, s[2:3]
	s_mov_b32 s2, 0x108000
	v_readlane_b32 s36, v254, 11
	s_mov_b64 s[0:1], 0x108000
	v_add_co_u32_e32 v132, vcc, s2, v146
	s_waitcnt lgkmcnt(0)
	s_barrier
	v_readlane_b32 s42, v254, 17
	v_readlane_b32 s43, v254, 18
	v_lshl_add_u64 v[130:131], v[146:147], 0, s[0:1]
	s_mov_b64 s[0:1], 0x106000
	v_addc_co_u32_e32 v133, vcc, 0, v147, vcc
	v_lshl_add_u64 v[128:129], v[144:145], 2, s[42:43]
	global_load_dwordx4 v[152:155], v[130:131], off offset:16
	global_load_dwordx4 v[156:159], v[130:131], off offset:512
	global_load_dwordx4 v[160:163], v[130:131], off offset:528
	global_load_dwordx4 v[164:167], v[132:133], off
	v_lshl_add_u64 v[132:133], v[146:147], 0, s[0:1]
	s_mov_b32 s0, 0x106000
	global_load_dwordx4 v[168:171], v[128:129], off offset:16
	global_load_dwordx4 v[136:139], v[132:133], off offset:16
	global_load_dwordx4 v[172:175], v[128:129], off offset:512
	global_load_dwordx4 v[176:179], v[128:129], off offset:528
	global_load_dwordx4 v[180:183], v[128:129], off
	v_add_co_u32_e32 v134, vcc, s0, v146
	global_load_dwordx4 v[128:131], v[132:133], off offset:512
	s_nop 0
	v_addc_co_u32_e32 v135, vcc, 0, v147, vcc
	global_load_dwordx4 v[140:143], v[134:135], off
	s_nop 0
	global_load_dwordx4 v[132:135], v[132:133], off offset:528
	v_lshl_add_u32 v149, v148, 2, 0
	ds_read_b32 v184, v149 offset:4096
	v_add_u32_e32 v146, s14, v148
	s_add_u32 s0, s62, 0x1e600000
	v_ashrrev_i32_e32 v147, 31, v146
	v_mov_b32_e32 v148, 0x7fc00000
	s_waitcnt lgkmcnt(0)
	v_pk_mul_f32 v[188:189], v[8:9], v[184:185] op_sel_hi:[1,0]
	v_pk_mul_f32 v[190:191], v[10:11], v[184:185] op_sel_hi:[1,0]
	v_pk_mul_f32 v[196:197], v[44:45], v[184:185] op_sel_hi:[1,0]
	v_pk_mul_f32 v[198:199], v[46:47], v[184:185] op_sel_hi:[1,0]
	v_pk_mul_f32 v[192:193], v[12:13], v[184:185] op_sel_hi:[1,0]
	v_pk_mul_f32 v[194:195], v[14:15], v[184:185] op_sel_hi:[1,0]
	v_pk_mul_f32 v[200:201], v[40:41], v[184:185] op_sel_hi:[1,0]
	v_pk_mul_f32 v[184:185], v[42:43], v[184:185] op_sel_hi:[1,0]
	s_addc_u32 s1, s63, 0
	v_lshlrev_b64 v[186:187], 12, v[146:147]
	v_cmp_eq_u32_e32 vcc, 0, v150
	v_lshlrev_b64 v[144:145], 1, v[144:145]
	v_lshl_add_u64 v[186:187], s[0:1], 0, v[186:187]
	v_lshl_add_u64 v[186:187], v[186:187], 0, v[144:145]
	v_readlane_b32 s37, v254, 12
	v_readlane_b32 s38, v254, 13
	v_readlane_b32 s39, v254, 14
	v_readlane_b32 s40, v254, 15
	v_readlane_b32 s41, v254, 16
	v_readlane_b32 s44, v254, 19
	v_readlane_b32 s45, v254, 20
	v_readlane_b32 s46, v254, 21
	v_readlane_b32 s47, v254, 22
	v_readlane_b32 s48, v254, 23
	v_readlane_b32 s49, v254, 24
	v_readlane_b32 s50, v254, 25
	v_readlane_b32 s51, v254, 26
	s_waitcnt vmcnt(0)
; __device__ __forceinline__ unsigned cvt_pk_bf16(float lo, float hi) { unsigned r; asm volatile("v_cvt_pk_bf16_f32 %0, %1, %2" : "=v"(r) : "v"(lo), "v"(hi)); return r; }
;     __device__ __forceinline__ void fused(f32x4 (&acc)[2][2][4][2], const Unit& un, int wr, int wc, int fr, int fq, PG8_LAS unsigned char* lds, int wid, int lane) const {
;     ...
;             for (int n = 0; n < 2; ++n) { const f32x4 g4 = *(const f32x4*)(gain + col0 + bj * HALF + n * 4);
;                 if (MODE == 0) { const f32x4 sc4 = *(const f32x4*)(scale + boff + bj * HALF + n * 4); cg[bj][n] = g4 * (sc4 + 1.0f); sh[bj][n] = *(const f32x4*)(shift + boff + bj * HALF + n * 4); }
;                 else { cg[bj][n] = g4; sh[bj][n] = (f32x4){0.f, 0.f, 0.f, 0.f}; } }
; #pragma unroll
;         for (int ai = 0; ai < 2; ++ai)
; #pragma unroll
;             for (int m = 0; m < 4; ++m) { const int r = ai * HALF + wr * 64 + m * 16 + fr; const float rs = S[r]; const size_t off = (size_t)(un.pm * BM + r) * ldc + col0;
; #pragma unroll
;                 for (int bj = 0; bj < 2; ++bj) { f32x4 y0 = (acc[ai][bj][m][0] * rs) * cg[bj][0] + sh[bj][0], y1 = (acc[ai][bj][m][1] * rs) * cg[bj][1] + sh[bj][1];
;                     if (bad) { y0 = (f32x4){qnan, qnan, qnan, qnan}; y1 = y0; }
;                     if (MODE == 0) { u32x4 w; w.x = cvt_pk_bf16(y0[0], y0[1]); w.y = cvt_pk_bf16(y0[2], y0[3]); w.z = cvt_pk_bf16(y1[0], y1[1]); w.w = cvt_pk_bf16(y1[2], y1[3]); *(u32x4*)(u + off + bj * HALF) = w; }
	v_pk_add_f32 v[8:9], v[154:155], 1.0 op_sel_hi:[1,0]
	v_pk_add_f32 v[10:11], v[152:153], 1.0 op_sel_hi:[1,0]
	v_pk_add_f32 v[44:45], v[162:163], 1.0 op_sel_hi:[1,0]
	v_pk_add_f32 v[46:47], v[160:161], 1.0 op_sel_hi:[1,0]
	v_pk_add_f32 v[152:153], v[166:167], 1.0 op_sel_hi:[1,0]
	v_pk_add_f32 v[154:155], v[164:165], 1.0 op_sel_hi:[1,0]
	v_pk_mul_f32 v[40:41], v[170:171], v[8:9]
	v_pk_mul_f32 v[42:43], v[168:169], v[10:11]
	v_pk_mul_f32 v[8:9], v[178:179], v[44:45]
	v_pk_mul_f32 v[10:11], v[176:177], v[46:47]
	v_pk_mul_f32 v[44:45], v[182:183], v[152:153]
	v_pk_mul_f32 v[46:47], v[180:181], v[154:155]
	v_pk_fma_f32 v[152:153], v[40:41], v[194:195], v[138:139]
	v_pk_fma_f32 v[154:155], v[42:43], v[192:193], v[136:137]
	v_pk_fma_f32 v[160:161], v[44:45], v[190:191], v[142:143]
	v_pk_fma_f32 v[162:163], v[46:47], v[188:189], v[140:141]
	v_cndmask_b32_e32 v151, v148, v161, vcc
	v_cndmask_b32_e32 v150, v148, v162, vcc
	v_cndmask_b32_e32 v161, v148, v152, vcc
	v_cndmask_b32_e32 v153, v148, v153, vcc
	v_cndmask_b32_e32 v152, v148, v154, vcc
	v_pk_add_f32 v[12:13], v[158:159], 1.0 op_sel_hi:[1,0]
	v_pk_add_f32 v[14:15], v[156:157], 1.0 op_sel_hi:[1,0]
	v_cndmask_b32_e32 v147, v148, v160, vcc
	v_cndmask_b32_e32 v160, v148, v163, vcc
	v_cndmask_b32_e32 v154, v148, v155, vcc
	v_cvt_pk_bf16_f32 v150, v150, v160
	v_cvt_pk_bf16_f32 v151, v147, v151
	v_cvt_pk_bf16_f32 v152, v152, v154
	v_cvt_pk_bf16_f32 v153, v161, v153
	v_pk_mul_f32 v[12:13], v[174:175], v[12:13]
	v_pk_mul_f32 v[14:15], v[172:173], v[14:15]
	global_store_dwordx4 v[186:187], v[150:153], off
	v_pk_fma_f32 v[156:157], v[12:13], v[198:199], v[130:131]
	v_pk_fma_f32 v[158:159], v[14:15], v[196:197], v[128:129]
	v_pk_fma_f32 v[152:153], v[10:11], v[200:201], v[132:133]
	v_pk_fma_f32 v[150:151], v[8:9], v[184:185], v[134:135]
	v_cndmask_b32_e32 v152, v148, v152, vcc
	v_cndmask_b32_e32 v153, v148, v153, vcc
	v_cndmask_b32_e32 v147, v148, v156, vcc
	v_cndmask_b32_e32 v154, v148, v157, vcc
	v_cndmask_b32_e32 v155, v148, v158, vcc
	v_cndmask_b32_e32 v156, v148, v159, vcc
	v_cndmask_b32_e32 v157, v148, v150, vcc
	v_cndmask_b32_e32 v158, v148, v151, vcc
	v_cvt_pk_bf16_f32 v150, v155, v156
	v_cvt_pk_bf16_f32 v151, v147, v154
	v_cvt_pk_bf16_f32 v152, v152, v153
	v_cvt_pk_bf16_f32 v153, v157, v158
	global_store_dwordx4 v[186:187], v[150:153], off offset:256
	ds_read_b32 v150, v149 offset:4160
	s_waitcnt lgkmcnt(0)
	v_pk_mul_f32 v[36:37], v[36:37], v[150:151] op_sel_hi:[1,0]
	v_add_u32_e32 v152, 16, v146
	v_pk_fma_f32 v[36:37], v[46:47], v[36:37], v[140:141]
	v_pk_mul_f32 v[32:33], v[32:33], v[150:151] op_sel_hi:[1,0]
	v_pk_mul_f32 v[34:35], v[34:35], v[150:151] op_sel_hi:[1,0]
	v_ashrrev_i32_e32 v153, 31, v152
	v_pk_fma_f32 v[34:35], v[40:41], v[34:35], v[138:139]
	v_pk_fma_f32 v[32:33], v[42:43], v[32:33], v[136:137]
	v_cndmask_b32_e32 v36, v148, v36, vcc
	v_cndmask_b32_e32 v37, v148, v37, vcc
	v_pk_mul_f32 v[38:39], v[38:39], v[150:151] op_sel_hi:[1,0]
	v_cndmask_b32_e32 v147, v148, v34, vcc
	v_cndmask_b32_e32 v34, v148, v32, vcc
	v_cvt_pk_bf16_f32 v32, v36, v37
	v_lshlrev_b64 v[36:37], 12, v[152:153]
	v_pk_fma_f32 v[38:39], v[44:45], v[38:39], v[142:143]
	v_cndmask_b32_e32 v35, v148, v35, vcc
	v_lshl_add_u64 v[36:37], s[0:1], 0, v[36:37]
	v_cndmask_b32_e32 v38, v148, v38, vcc
	v_cndmask_b32_e32 v39, v148, v39, vcc
	v_cndmask_b32_e32 v151, v148, v33, vcc
	v_cvt_pk_bf16_f32 v33, v38, v39
	v_cvt_pk_bf16_f32 v34, v34, v151
	v_cvt_pk_bf16_f32 v35, v147, v35
	v_lshl_add_u64 v[36:37], v[36:37], 0, v[144:145]
	global_store_dwordx4 v[36:37], v[32:35], off
	v_pk_mul_f32 v[38:39], v[48:49], v[150:151] op_sel_hi:[1,0]
	v_pk_mul_f32 v[48:49], v[50:51], v[150:151] op_sel_hi:[1,0]
	v_pk_mul_f32 v[32:33], v[52:53], v[150:151] op_sel_hi:[1,0]
	v_pk_mul_f32 v[34:35], v[54:55], v[150:151] op_sel_hi:[1,0]
	v_pk_fma_f32 v[32:33], v[14:15], v[32:33], v[128:129]
	v_pk_fma_f32 v[34:35], v[12:13], v[34:35], v[130:131]
	v_pk_fma_f32 v[48:49], v[8:9], v[48:49], v[134:135]
	v_pk_fma_f32 v[38:39], v[10:11], v[38:39], v[132:133]
	v_cndmask_b32_e32 v34, v148, v34, vcc
	v_cndmask_b32_e32 v35, v148, v35, vcc
	v_cndmask_b32_e32 v32, v148, v32, vcc
	v_cndmask_b32_e32 v33, v148, v33, vcc
	v_cndmask_b32_e32 v48, v148, v48, vcc
	v_cndmask_b32_e32 v49, v148, v49, vcc
	v_cndmask_b32_e32 v38, v148, v38, vcc
	v_cndmask_b32_e32 v39, v148, v39, vcc
	v_cvt_pk_bf16_f32 v32, v32, v33
	v_cvt_pk_bf16_f32 v33, v34, v35
	v_cvt_pk_bf16_f32 v34, v38, v39
	v_cvt_pk_bf16_f32 v35, v48, v49
	global_store_dwordx4 v[36:37], v[32:35], off offset:256
	ds_read_b32 v36, v149 offset:4224
	v_add_u32_e32 v38, 32, v146
	v_ashrrev_i32_e32 v39, 31, v38
	v_lshlrev_b64 v[38:39], 12, v[38:39]
	v_lshl_add_u64 v[38:39], s[0:1], 0, v[38:39]
	s_waitcnt lgkmcnt(0)
; __device__ __forceinline__ unsigned cvt_pk_bf16(float lo, float hi) { unsigned r; asm volatile("v_cvt_pk_bf16_f32 %0, %1, %2" : "=v"(r) : "v"(lo), "v"(hi)); return r; }
;     __device__ __forceinline__ void fused(f32x4 (&acc)[2][2][4][2], const Unit& un, int wr, int wc, int fr, int fq, PG8_LAS unsigned char* lds, int wid, int lane) const {
;     ...
;         for (int ai = 0; ai < 2; ++ai)
; #pragma unroll
;             for (int m = 0; m < 4; ++m) { const int r = ai * HALF + wr * 64 + m * 16 + fr; const float rs = S[r]; const size_t off = (size_t)(un.pm * BM + r) * ldc + col0;
; #pragma unroll
;                 for (int bj = 0; bj < 2; ++bj) { f32x4 y0 = (acc[ai][bj][m][0] * rs) * cg[bj][0] + sh[bj][0], y1 = (acc[ai][bj][m][1] * rs) * cg[bj][1] + sh[bj][1];
;                     if (bad) { y0 = (f32x4){qnan, qnan, qnan, qnan}; y1 = y0; }
;                     if (MODE == 0) { u32x4 w; w.x = cvt_pk_bf16(y0[0], y0[1]); w.y = cvt_pk_bf16(y0[2], y0[3]); w.z = cvt_pk_bf16(y1[0], y1[1]); w.w = cvt_pk_bf16(y1[2], y1[3]); *(u32x4*)(u + off + bj * HALF) = w; }
	v_pk_mul_f32 v[32:33], v[60:61], v[36:37] op_sel_hi:[1,0]
	v_pk_mul_f32 v[34:35], v[62:63], v[36:37] op_sel_hi:[1,0]
	v_pk_fma_f32 v[32:33], v[46:47], v[32:33], v[140:141]
	v_pk_fma_f32 v[34:35], v[44:45], v[34:35], v[142:143]
	v_pk_mul_f32 v[48:49], v[56:57], v[36:37] op_sel_hi:[1,0]
	v_pk_mul_f32 v[50:51], v[58:59], v[36:37] op_sel_hi:[1,0]
	v_pk_fma_f32 v[48:49], v[42:43], v[48:49], v[136:137]
	v_pk_fma_f32 v[50:51], v[40:41], v[50:51], v[138:139]
	v_cndmask_b32_e32 v34, v148, v34, vcc
	v_cndmask_b32_e32 v35, v148, v35, vcc
	v_cndmask_b32_e32 v32, v148, v32, vcc
	v_cndmask_b32_e32 v33, v148, v33, vcc
	v_cndmask_b32_e32 v37, v148, v50, vcc
	v_cndmask_b32_e32 v50, v148, v51, vcc
	v_cndmask_b32_e32 v48, v148, v48, vcc
	v_cndmask_b32_e32 v49, v148, v49, vcc
	v_cvt_pk_bf16_f32 v32, v32, v33
	v_cvt_pk_bf16_f32 v33, v34, v35
	v_cvt_pk_bf16_f32 v34, v48, v49
	v_cvt_pk_bf16_f32 v35, v37, v50
	v_lshl_add_u64 v[38:39], v[38:39], 0, v[144:145]
	global_store_dwordx4 v[38:39], v[32:35], off
	v_pk_mul_f32 v[48:49], v[64:65], v[36:37] op_sel_hi:[1,0]
	s_nop 0
	v_pk_mul_f32 v[32:33], v[68:69], v[36:37] op_sel_hi:[1,0]
	v_pk_mul_f32 v[34:35], v[70:71], v[36:37] op_sel_hi:[1,0]
	v_pk_fma_f32 v[32:33], v[14:15], v[32:33], v[128:129]
	v_pk_fma_f32 v[34:35], v[12:13], v[34:35], v[130:131]
	v_pk_mul_f32 v[36:37], v[66:67], v[36:37] op_sel_hi:[1,0]
	v_pk_fma_f32 v[48:49], v[10:11], v[48:49], v[132:133]
	v_pk_fma_f32 v[36:37], v[8:9], v[36:37], v[134:135]
	v_cndmask_b32_e32 v34, v148, v34, vcc
	v_cndmask_b32_e32 v35, v148, v35, vcc
	v_cndmask_b32_e32 v32, v148, v32, vcc
	v_cndmask_b32_e32 v33, v148, v33, vcc
	v_cndmask_b32_e32 v36, v148, v36, vcc
	v_cndmask_b32_e32 v37, v148, v37, vcc
	v_cndmask_b32_e32 v48, v148, v48, vcc
	v_cndmask_b32_e32 v49, v148, v49, vcc
	v_cvt_pk_bf16_f32 v32, v32, v33
	v_cvt_pk_bf16_f32 v33, v34, v35
	v_cvt_pk_bf16_f32 v34, v48, v49
	v_cvt_pk_bf16_f32 v35, v36, v37
	global_store_dwordx4 v[38:39], v[32:35], off offset:256
	ds_read_b32 v36, v149 offset:4288
	v_add_u32_e32 v38, 48, v146
	v_ashrrev_i32_e32 v39, 31, v38
	v_lshlrev_b64 v[38:39], 12, v[38:39]
	v_lshl_add_u64 v[38:39], s[0:1], 0, v[38:39]
	s_waitcnt lgkmcnt(0)
	v_pk_mul_f32 v[32:33], v[80:81], v[36:37] op_sel_hi:[1,0]
	v_pk_mul_f32 v[34:35], v[82:83], v[36:37] op_sel_hi:[1,0]
	v_pk_fma_f32 v[32:33], v[46:47], v[32:33], v[140:141]
	v_pk_fma_f32 v[34:35], v[44:45], v[34:35], v[142:143]
	v_pk_mul_f32 v[48:49], v[72:73], v[36:37] op_sel_hi:[1,0]
	v_pk_mul_f32 v[50:51], v[74:75], v[36:37] op_sel_hi:[1,0]
	v_pk_fma_f32 v[48:49], v[42:43], v[48:49], v[136:137]
	v_pk_fma_f32 v[50:51], v[40:41], v[50:51], v[138:139]
	v_cndmask_b32_e32 v34, v148, v34, vcc
	v_cndmask_b32_e32 v35, v148, v35, vcc
	v_cndmask_b32_e32 v32, v148, v32, vcc
	v_cndmask_b32_e32 v33, v148, v33, vcc
	v_cndmask_b32_e32 v37, v148, v50, vcc
	v_cndmask_b32_e32 v50, v148, v51, vcc
	v_cndmask_b32_e32 v48, v148, v48, vcc
	v_cndmask_b32_e32 v49, v148, v49, vcc
	v_cvt_pk_bf16_f32 v32, v32, v33
	v_cvt_pk_bf16_f32 v33, v34, v35
	v_cvt_pk_bf16_f32 v34, v48, v49
	v_cvt_pk_bf16_f32 v35, v37, v50
	v_lshl_add_u64 v[38:39], v[38:39], 0, v[144:145]
	global_store_dwordx4 v[38:39], v[32:35], off
	v_pk_mul_f32 v[48:49], v[96:97], v[36:37] op_sel_hi:[1,0]
	s_nop 0
	v_pk_mul_f32 v[32:33], v[100:101], v[36:37] op_sel_hi:[1,0]
	v_pk_mul_f32 v[34:35], v[102:103], v[36:37] op_sel_hi:[1,0]
	v_pk_fma_f32 v[32:33], v[14:15], v[32:33], v[128:129]
	v_pk_fma_f32 v[34:35], v[12:13], v[34:35], v[130:131]
	v_pk_mul_f32 v[36:37], v[98:99], v[36:37] op_sel_hi:[1,0]
	v_pk_fma_f32 v[48:49], v[10:11], v[48:49], v[132:133]
	v_pk_fma_f32 v[36:37], v[8:9], v[36:37], v[134:135]
	v_cndmask_b32_e32 v34, v148, v34, vcc
	v_cndmask_b32_e32 v35, v148, v35, vcc
	v_cndmask_b32_e32 v32, v148, v32, vcc
	v_cndmask_b32_e32 v33, v148, v33, vcc
	v_cndmask_b32_e32 v36, v148, v36, vcc
	v_cndmask_b32_e32 v37, v148, v37, vcc
	v_cndmask_b32_e32 v48, v148, v48, vcc
	v_cndmask_b32_e32 v49, v148, v49, vcc
	v_cvt_pk_bf16_f32 v32, v32, v33
	v_cvt_pk_bf16_f32 v33, v34, v35
	v_cvt_pk_bf16_f32 v34, v48, v49
	v_cvt_pk_bf16_f32 v35, v36, v37
	global_store_dwordx4 v[38:39], v[32:35], off offset:256
	ds_read_b32 v36, v149 offset:4608
	v_add_u32_e32 v38, 0x80, v146
	v_ashrrev_i32_e32 v39, 31, v38
	v_lshlrev_b64 v[38:39], 12, v[38:39]
	v_lshl_add_u64 v[38:39], s[0:1], 0, v[38:39]
	s_waitcnt lgkmcnt(0)
	v_pk_mul_f32 v[32:33], v[108:109], v[36:37] op_sel_hi:[1,0]
	v_pk_mul_f32 v[34:35], v[110:111], v[36:37] op_sel_hi:[1,0]
	v_pk_fma_f32 v[32:33], v[46:47], v[32:33], v[140:141]
	v_pk_fma_f32 v[34:35], v[44:45], v[34:35], v[142:143]
	v_pk_mul_f32 v[48:49], v[104:105], v[36:37] op_sel_hi:[1,0]
	v_pk_mul_f32 v[50:51], v[106:107], v[36:37] op_sel_hi:[1,0]
	v_pk_fma_f32 v[48:49], v[42:43], v[48:49], v[136:137]
	v_pk_fma_f32 v[50:51], v[40:41], v[50:51], v[138:139]
	v_cndmask_b32_e32 v34, v148, v34, vcc
	v_cndmask_b32_e32 v35, v148, v35, vcc
	v_cndmask_b32_e32 v32, v148, v32, vcc
	v_cndmask_b32_e32 v33, v148, v33, vcc
	v_cndmask_b32_e32 v37, v148, v50, vcc
	v_cndmask_b32_e32 v50, v148, v51, vcc
	v_cndmask_b32_e32 v48, v148, v48, vcc
	v_cndmask_b32_e32 v49, v148, v49, vcc
	v_cvt_pk_bf16_f32 v32, v32, v33
	v_cvt_pk_bf16_f32 v33, v34, v35
	v_cvt_pk_bf16_f32 v34, v48, v49
	v_cvt_pk_bf16_f32 v35, v37, v50
	v_lshl_add_u64 v[38:39], v[38:39], 0, v[144:145]
	global_store_dwordx4 v[38:39], v[32:35], off
	v_pk_mul_f32 v[48:49], v[112:113], v[36:37] op_sel_hi:[1,0]
	s_nop 0
	v_pk_mul_f32 v[32:33], v[116:117], v[36:37] op_sel_hi:[1,0]
	v_pk_mul_f32 v[34:35], v[118:119], v[36:37] op_sel_hi:[1,0]
	v_pk_fma_f32 v[32:33], v[14:15], v[32:33], v[128:129]
	v_pk_fma_f32 v[34:35], v[12:13], v[34:35], v[130:131]
	v_pk_mul_f32 v[36:37], v[114:115], v[36:37] op_sel_hi:[1,0]
	v_pk_fma_f32 v[48:49], v[10:11], v[48:49], v[132:133]
	v_pk_fma_f32 v[36:37], v[8:9], v[36:37], v[134:135]
	v_cndmask_b32_e32 v34, v148, v34, vcc
	v_cndmask_b32_e32 v35, v148, v35, vcc
	v_cndmask_b32_e32 v32, v148, v32, vcc
	v_cndmask_b32_e32 v33, v148, v33, vcc
	v_cndmask_b32_e32 v36, v148, v36, vcc
	v_cndmask_b32_e32 v37, v148, v37, vcc
	v_cndmask_b32_e32 v48, v148, v48, vcc
	v_cndmask_b32_e32 v49, v148, v49, vcc
	v_cvt_pk_bf16_f32 v32, v32, v33
	v_cvt_pk_bf16_f32 v33, v34, v35
	v_cvt_pk_bf16_f32 v34, v48, v49
	v_cvt_pk_bf16_f32 v35, v36, v37
	global_store_dwordx4 v[38:39], v[32:35], off offset:256
	ds_read_b32 v36, v149 offset:4672
	v_add_u32_e32 v38, 0x90, v146
	v_ashrrev_i32_e32 v39, 31, v38
	v_lshlrev_b64 v[38:39], 12, v[38:39]
	v_lshl_add_u64 v[38:39], s[0:1], 0, v[38:39]
	s_waitcnt lgkmcnt(0)
; __device__ __forceinline__ unsigned cvt_pk_bf16(float lo, float hi) { unsigned r; asm volatile("v_cvt_pk_bf16_f32 %0, %1, %2" : "=v"(r) : "v"(lo), "v"(hi)); return r; }
;     __device__ __forceinline__ void fused(f32x4 (&acc)[2][2][4][2], const Unit& un, int wr, int wc, int fr, int fq, PG8_LAS unsigned char* lds, int wid, int lane) const {
;     ...
;         for (int ai = 0; ai < 2; ++ai)
; #pragma unroll
;             for (int m = 0; m < 4; ++m) { const int r = ai * HALF + wr * 64 + m * 16 + fr; const float rs = S[r]; const size_t off = (size_t)(un.pm * BM + r) * ldc + col0;
; #pragma unroll
;                 for (int bj = 0; bj < 2; ++bj) { f32x4 y0 = (acc[ai][bj][m][0] * rs) * cg[bj][0] + sh[bj][0], y1 = (acc[ai][bj][m][1] * rs) * cg[bj][1] + sh[bj][1];
;                     if (bad) { y0 = (f32x4){qnan, qnan, qnan, qnan}; y1 = y0; }
;                     if (MODE == 0) { u32x4 w; w.x = cvt_pk_bf16(y0[0], y0[1]); w.y = cvt_pk_bf16(y0[2], y0[3]); w.z = cvt_pk_bf16(y1[0], y1[1]); w.w = cvt_pk_bf16(y1[2], y1[3]); *(u32x4*)(u + off + bj * HALF) = w; }
	v_pk_mul_f32 v[32:33], v[124:125], v[36:37] op_sel_hi:[1,0]
	v_pk_mul_f32 v[34:35], v[126:127], v[36:37] op_sel_hi:[1,0]
	v_pk_fma_f32 v[32:33], v[46:47], v[32:33], v[140:141]
	v_pk_fma_f32 v[34:35], v[44:45], v[34:35], v[142:143]
	v_pk_mul_f32 v[48:49], v[120:121], v[36:37] op_sel_hi:[1,0]
	v_pk_mul_f32 v[50:51], v[122:123], v[36:37] op_sel_hi:[1,0]
	v_pk_fma_f32 v[48:49], v[42:43], v[48:49], v[136:137]
	v_pk_fma_f32 v[50:51], v[40:41], v[50:51], v[138:139]
	v_cndmask_b32_e32 v34, v148, v34, vcc
	v_cndmask_b32_e32 v35, v148, v35, vcc
	v_cndmask_b32_e32 v32, v148, v32, vcc
	v_cndmask_b32_e32 v33, v148, v33, vcc
	v_cndmask_b32_e32 v37, v148, v50, vcc
	v_cndmask_b32_e32 v50, v148, v51, vcc
	v_cndmask_b32_e32 v48, v148, v48, vcc
	v_cndmask_b32_e32 v49, v148, v49, vcc
	v_cvt_pk_bf16_f32 v32, v32, v33
	v_cvt_pk_bf16_f32 v33, v34, v35
	v_cvt_pk_bf16_f32 v34, v48, v49
	v_cvt_pk_bf16_f32 v35, v37, v50
	v_lshl_add_u64 v[38:39], v[38:39], 0, v[144:145]
	global_store_dwordx4 v[38:39], v[32:35], off
	v_pk_mul_f32 v[48:49], v[88:89], v[36:37] op_sel_hi:[1,0]
	s_nop 0
	v_pk_mul_f32 v[32:33], v[92:93], v[36:37] op_sel_hi:[1,0]
	v_pk_mul_f32 v[34:35], v[94:95], v[36:37] op_sel_hi:[1,0]
	v_pk_fma_f32 v[32:33], v[14:15], v[32:33], v[128:129]
	v_pk_fma_f32 v[34:35], v[12:13], v[34:35], v[130:131]
	v_pk_mul_f32 v[36:37], v[90:91], v[36:37] op_sel_hi:[1,0]
	v_pk_fma_f32 v[48:49], v[10:11], v[48:49], v[132:133]
	v_pk_fma_f32 v[36:37], v[8:9], v[36:37], v[134:135]
	v_cndmask_b32_e32 v34, v148, v34, vcc
	v_cndmask_b32_e32 v35, v148, v35, vcc
	v_cndmask_b32_e32 v32, v148, v32, vcc
	v_cndmask_b32_e32 v33, v148, v33, vcc
	v_cndmask_b32_e32 v36, v148, v36, vcc
	v_cndmask_b32_e32 v37, v148, v37, vcc
	v_cndmask_b32_e32 v48, v148, v48, vcc
	v_cndmask_b32_e32 v49, v148, v49, vcc
	v_cvt_pk_bf16_f32 v32, v32, v33
	v_cvt_pk_bf16_f32 v33, v34, v35
	v_cvt_pk_bf16_f32 v34, v48, v49
	v_cvt_pk_bf16_f32 v35, v36, v37
	global_store_dwordx4 v[38:39], v[32:35], off offset:256
	ds_read_b32 v36, v149 offset:4736
	v_add_u32_e32 v38, 0xa0, v146
	v_ashrrev_i32_e32 v39, 31, v38
	v_lshlrev_b64 v[38:39], 12, v[38:39]
	v_lshl_add_u64 v[38:39], s[0:1], 0, v[38:39]
	s_waitcnt lgkmcnt(0)
	v_pk_mul_f32 v[50:51], v[78:79], v[36:37] op_sel_hi:[1,0]
	v_pk_mul_f32 v[32:33], v[84:85], v[36:37] op_sel_hi:[1,0]
	v_pk_fma_f32 v[50:51], v[40:41], v[50:51], v[138:139]
	v_pk_mul_f32 v[34:35], v[86:87], v[36:37] op_sel_hi:[1,0]
	v_pk_fma_f32 v[32:33], v[46:47], v[32:33], v[140:141]
	v_pk_mul_f32 v[48:49], v[76:77], v[36:37] op_sel_hi:[1,0]
	v_cndmask_b32_e32 v37, v148, v50, vcc
	v_pk_fma_f32 v[34:35], v[44:45], v[34:35], v[142:143]
	v_cndmask_b32_e32 v32, v148, v32, vcc
	v_pk_mul_f32 v[24:25], v[24:25], v[36:37] op_sel_hi:[1,0]
	v_pk_mul_f32 v[26:27], v[26:27], v[36:37] op_sel_hi:[1,0]
	v_pk_fma_f32 v[48:49], v[42:43], v[48:49], v[136:137]
	v_cndmask_b32_e32 v34, v148, v34, vcc
	v_cndmask_b32_e32 v35, v148, v35, vcc
	v_cndmask_b32_e32 v33, v148, v33, vcc
	v_cvt_pk_bf16_f32 v32, v32, v33
	v_lshl_add_u64 v[38:39], v[38:39], 0, v[144:145]
	v_pk_mul_f32 v[28:29], v[28:29], v[36:37] op_sel_hi:[1,0]
	v_pk_mul_f32 v[30:31], v[30:31], v[36:37] op_sel_hi:[1,0]
	v_pk_fma_f32 v[26:27], v[8:9], v[26:27], v[134:135]
	v_pk_fma_f32 v[24:25], v[10:11], v[24:25], v[132:133]
	v_cndmask_b32_e32 v50, v148, v51, vcc
	v_cndmask_b32_e32 v48, v148, v48, vcc
	v_cndmask_b32_e32 v49, v148, v49, vcc
	v_cvt_pk_bf16_f32 v33, v34, v35
	v_cvt_pk_bf16_f32 v34, v48, v49
	v_cvt_pk_bf16_f32 v35, v37, v50
	global_store_dwordx4 v[38:39], v[32:35], off
	v_pk_fma_f32 v[30:31], v[12:13], v[30:31], v[130:131]
	v_pk_fma_f32 v[28:29], v[14:15], v[28:29], v[128:129]
	v_cndmask_b32_e32 v32, v148, v26, vcc
	v_cndmask_b32_e32 v27, v148, v27, vcc
	v_cndmask_b32_e32 v26, v148, v24, vcc
	v_cndmask_b32_e32 v30, v148, v30, vcc
	v_cndmask_b32_e32 v31, v148, v31, vcc
	v_cndmask_b32_e32 v28, v148, v28, vcc
	v_cndmask_b32_e32 v29, v148, v29, vcc
	v_cndmask_b32_e32 v33, v148, v25, vcc
	v_cvt_pk_bf16_f32 v24, v28, v29
	v_cvt_pk_bf16_f32 v25, v30, v31
	v_cvt_pk_bf16_f32 v26, v26, v33
	v_cvt_pk_bf16_f32 v27, v32, v27
	global_store_dwordx4 v[38:39], v[24:27], off offset:256
	ds_read_b32 v24, v149 offset:4800
	s_waitcnt lgkmcnt(0)
	v_pk_mul_f32 v[20:21], v[20:21], v[24:25] op_sel_hi:[1,0]
	v_pk_mul_f32 v[18:19], v[18:19], v[24:25] op_sel_hi:[1,0]
	v_add_u32_e32 v26, 0xb0, v146
	v_pk_fma_f32 v[20:21], v[46:47], v[20:21], v[140:141]
	v_pk_mul_f32 v[16:17], v[16:17], v[24:25] op_sel_hi:[1,0]
	v_pk_fma_f32 v[18:19], v[40:41], v[18:19], v[138:139]
	v_ashrrev_i32_e32 v27, 31, v26
	v_pk_mul_f32 v[22:23], v[22:23], v[24:25] op_sel_hi:[1,0]
	v_pk_fma_f32 v[16:17], v[42:43], v[16:17], v[136:137]
	v_cndmask_b32_e32 v20, v148, v20, vcc
	v_cndmask_b32_e32 v21, v148, v21, vcc
	v_cndmask_b32_e32 v25, v148, v18, vcc
	v_cndmask_b32_e32 v18, v148, v16, vcc
	v_cvt_pk_bf16_f32 v16, v20, v21
	v_lshlrev_b64 v[20:21], 12, v[26:27]
	v_pk_mul_f32 v[0:1], v[0:1], v[24:25] op_sel_hi:[1,0]
	v_pk_mul_f32 v[2:3], v[2:3], v[24:25] op_sel_hi:[1,0]
	v_lshl_add_u64 v[20:21], s[0:1], 0, v[20:21]
	v_pk_mul_f32 v[4:5], v[4:5], v[24:25] op_sel_hi:[1,0]
	v_pk_mul_f32 v[6:7], v[6:7], v[24:25] op_sel_hi:[1,0]
	v_pk_fma_f32 v[2:3], v[8:9], v[2:3], v[134:135]
	v_pk_fma_f32 v[0:1], v[10:11], v[0:1], v[132:133]
	v_pk_fma_f32 v[22:23], v[44:45], v[22:23], v[142:143]
	v_cndmask_b32_e32 v19, v148, v19, vcc
	v_lshl_add_u64 v[20:21], v[20:21], 0, v[144:145]
	v_pk_fma_f32 v[6:7], v[12:13], v[6:7], v[130:131]
	v_pk_fma_f32 v[4:5], v[14:15], v[4:5], v[128:129]
	v_cndmask_b32_e32 v8, v148, v2, vcc
	v_cndmask_b32_e32 v3, v148, v3, vcc
	v_cndmask_b32_e32 v2, v148, v0, vcc
	v_cndmask_b32_e32 v22, v148, v22, vcc
	v_cndmask_b32_e32 v23, v148, v23, vcc
	v_cndmask_b32_e32 v28, v148, v17, vcc
	v_cvt_pk_bf16_f32 v17, v22, v23
	v_cvt_pk_bf16_f32 v18, v18, v28
	v_cvt_pk_bf16_f32 v19, v25, v19
	global_store_dwordx4 v[20:21], v[16:19], off
	v_cndmask_b32_e32 v6, v148, v6, vcc
	v_cndmask_b32_e32 v7, v148, v7, vcc
	v_cndmask_b32_e32 v4, v148, v4, vcc
	v_cndmask_b32_e32 v5, v148, v5, vcc
	v_cndmask_b32_e32 v9, v148, v1, vcc
	v_cvt_pk_bf16_f32 v0, v4, v5
	v_cvt_pk_bf16_f32 v1, v6, v7
	v_cvt_pk_bf16_f32 v2, v2, v9
	v_cvt_pk_bf16_f32 v3, v8, v3
	global_store_dwordx4 v[20:21], v[0:3], off offset:256

;     __device__ __forceinline__ void operator()(const f32x4 (&acc)[2][2][4][2], const Unit& u, int wr, int wc, int fr, int fq) const {
;     ...
;             for (int m = 0; m < 4; ++m) { bf16_t* rowp = O + (size_t)(row0 + ai * HALF + m * 16) * ldc + col0;
;                 if (ACT == 1) {
;                     const int ob = fr * 64 + 16 * fq, sw = ob ^ (((ob >> 9) & 1) << 5);
;                     rowp = O + ((size_t)(u.pm * (ldc / 64) + u.pn * 4 + (wc >> 1)) * 2 + ai) * 8192 + (((wr * 4 + m) * 2 + (wc & 1)) * 1024 + sw) / 2; }
;                 float rc[2][2], rs[2][2];
;                 if (ACT == 2) { const float pos = (float)((row0 + ai * HALF + m * 16) & 2047);
; #pragma unroll
;                     for (int n = 0; n < 2; ++n)
; #pragma unroll
;                         for (int e = 0; e < 2; ++e) { float r = pos * rinv[n][e]; r -= floorf(r); rs[n][e] = do_rope ? __builtin_amdgcn_sinf(r) : 0.f; rc[n][e] = do_rope ? __builtin_amdgcn_cosf(r) : 1.f; } }
; #pragma unroll
;                 for (int bj = 0; bj < 2; ++bj) { f32x4 v0 = acc[ai][bj][m][0], v1 = acc[ai][bj][m][1];
;                     if (ACT == 3) { const float pos = (float)((row0 + ai * HALF + m * 16) & 2047); float c3[4], s3[4];
; #pragma unroll
;                         for (int p = 0; p < 4; ++p) { float r = pos * rinv3[bj][p]; r -= floorf(r); s3[p] = rope3[bj] ? __builtin_amdgcn_sinf(r) : 0.f; c3[p] = rope3[bj] ? __builtin_amdgcn_cosf(r) : 1.f; }
;                         const f32x4 a = v0, b = v1;
;                         v0[0] = a[0] * c3[0] - a[1] * s3[0]; v0[1] = a[1] * c3[0] + a[0] * s3[0]; v0[2] = a[2] * c3[1] - a[3] * s3[1]; v0[3] = a[3] * c3[1] + a[2] * s3[1];
;                         v1[0] = b[0] * c3[2] - b[1] * s3[2]; v1[1] = b[1] * c3[2] + b[0] * s3[2]; v1[2] = b[2] * c3[3] - b[3] * s3[3]; v1[3] = b[3] * c3[3] + b[2] * s3[3]; }
;                     if (ACT == 2) { const f32x4 a = v0, b = v1;
;                         v0[0] = a[0] * rc[0][0] - a[1] * rs[0][0]; v0[1] = a[1] * rc[0][0] + a[0] * rs[0][0]; v0[2] = a[2] * rc[0][1] - a[3] * rs[0][1]; v0[3] = a[3] * rc[0][1] + a[2] * rs[0][1];
;                         v1[0] = b[0] * rc[1][0] - b[1] * rs[1][0]; v1[1] = b[1] * rc[1][0] + b[0] * rs[1][0]; v1[2] = b[2] * rc[1][1] - b[3] * rs[1][1]; v1[3] = b[3] * rc[1][1] + b[2] * rs[1][1]; }
;                     if (ACT == 1) {
; #pragma unroll
.LBB0_1158:
	v_mov_b32_e32 v148, 0
	s_lshl_b32 s49, s49, 2
	v_mbcnt_lo_u32_b32 v148, -1, v148
	v_mbcnt_hi_u32_b32 v148, -1, v148
	v_or_b32_e32 v148, s33, v148
	s_or_b32 s49, s49, s45
	v_and_b32_e32 v149, 15, v148
	v_and_b32_e32 v150, 48, v148
	v_lshlrev_b32_e32 v148, 2, v148
	s_lshl_b32 s50, s74, 7
	v_lshl_or_b32 v149, v149, 6, v150
	v_and_b32_e32 v148, 32, v148
	s_add_i32 s50, s49, s50
	s_ashr_i32 s51, s50, 31
	v_bitop3_b32 v148, v149, s46, v148 bitop3:0xde
	s_lshl_b64 s[50:51], s[50:51], 15
	v_ashrrev_i32_e32 v148, 1, v148
	s_add_u32 s74, s41, s50
	v_ashrrev_i32_e32 v149, 31, v148
	s_addc_u32 s75, s42, s51
	v_lshlrev_b64 v[150:151], 1, v[148:149]
	v_max_i32_e32 v120, 0, v120
	v_max_i32_e32 v121, 0, v121
	v_max_i32_e32 v122, 0, v122
	v_max_i32_e32 v123, 0, v123
	v_max_i32_e32 v112, 0, v112
	v_max_i32_e32 v116, 0, v116
	v_max_i32_e32 v113, 0, v113
	v_max_i32_e32 v114, 0, v114
	v_lshl_add_u64 v[152:153], s[74:75], 0, v[150:151]
	v_max_i32_e32 v124, 0, v124
	v_mul_f32_e32 v120, v120, v120
	v_max_i32_e32 v125, 0, v125
	v_mul_f32_e32 v121, v121, v121
	v_max_i32_e32 v126, 0, v126
	v_mul_f32_e32 v122, v122, v122
	v_max_i32_e32 v127, 0, v127
	v_mul_f32_e32 v123, v123, v123
	v_mul_f32_e32 v112, v112, v112
	v_mul_f32_e32 v116, v116, v116
	v_max_i32_e32 v117, 0, v117
	v_mul_f32_e32 v113, v113, v113
	v_mul_f32_e32 v114, v114, v114
	v_max_i32_e32 v115, 0, v115
	v_mul_f32_e32 v124, v124, v124
	v_mul_f32_e32 v125, v125, v125
	v_mul_f32_e32 v126, v126, v126
	v_mul_f32_e32 v127, v127, v127
	v_cvt_pk_bf16_f32 v120, v120, v121
	v_cvt_pk_bf16_f32 v121, v122, v123
	v_cvt_pk_bf16_f32 v122, v124, v125
	v_cvt_pk_bf16_f32 v123, v126, v127
	global_store_dwordx4 v[152:153], v[120:123], off
	v_mul_f32_e32 v117, v117, v117
	v_mul_f32_e32 v115, v115, v115
	v_cvt_pk_bf16_f32 v112, v112, v113
	v_cvt_pk_bf16_f32 v113, v114, v115
	v_cvt_pk_bf16_f32 v114, v116, v117
	v_add_co_u32_e32 v116, vcc, s39, v152
	v_max_i32_e32 v104, 0, v104
	v_max_i32_e32 v105, 0, v105
	v_max_i32_e32 v106, 0, v106
	v_max_i32_e32 v107, 0, v107
	v_max_i32_e32 v96, 0, v96
	v_max_i32_e32 v118, 0, v118
	v_max_i32_e32 v119, 0, v119
	v_addc_co_u32_e32 v117, vcc, 0, v153, vcc
	v_max_i32_e32 v108, 0, v108
	v_mul_f32_e32 v104, v104, v104
	v_max_i32_e32 v109, 0, v109
	v_mul_f32_e32 v105, v105, v105
	v_max_i32_e32 v110, 0, v110
	v_mul_f32_e32 v106, v106, v106
	v_max_i32_e32 v111, 0, v111
	v_mul_f32_e32 v107, v107, v107
	v_mul_f32_e32 v96, v96, v96
	v_max_i32_e32 v97, 0, v97
	v_max_i32_e32 v98, 0, v98
	v_max_i32_e32 v99, 0, v99
	v_mul_f32_e32 v118, v118, v118
	v_mul_f32_e32 v119, v119, v119
	v_cvt_pk_bf16_f32 v115, v118, v119
	global_store_dwordx4 v[116:117], v[112:115], off
	v_mul_f32_e32 v108, v108, v108
	v_mul_f32_e32 v109, v109, v109
	v_mul_f32_e32 v110, v110, v110
	v_mul_f32_e32 v111, v111, v111
	v_cvt_pk_bf16_f32 v104, v104, v105
	v_cvt_pk_bf16_f32 v105, v106, v107
	v_cvt_pk_bf16_f32 v106, v108, v109
	v_cvt_pk_bf16_f32 v107, v110, v111
	global_store_dwordx4 v[152:153], v[104:107], off offset:2048
	v_max_i32_e32 v100, 0, v100
	v_max_i32_e32 v101, 0, v101
	v_mul_f32_e32 v97, v97, v97
	v_max_i32_e32 v102, 0, v102
	v_mul_f32_e32 v98, v98, v98
	v_max_i32_e32 v103, 0, v103
	v_mul_f32_e32 v99, v99, v99
	v_cvt_pk_bf16_f32 v96, v96, v97
	v_mul_f32_e32 v100, v100, v100
	v_mul_f32_e32 v101, v101, v101
	v_mul_f32_e32 v102, v102, v102
	v_mul_f32_e32 v103, v103, v103
	v_cvt_pk_bf16_f32 v97, v98, v99
	v_cvt_pk_bf16_f32 v98, v100, v101
	v_cvt_pk_bf16_f32 v99, v102, v103
	global_store_dwordx4 v[116:117], v[96:99], off offset:2048
	v_max_i32_e32 v88, 0, v88
	v_max_i32_e32 v89, 0, v89
	v_or_b32_e32 v96, 0x800, v148
	v_ashrrev_i32_e32 v97, 31, v96
	v_lshlrev_b64 v[96:97], 1, v[96:97]
	v_max_i32_e32 v90, 0, v90
	v_max_i32_e32 v91, 0, v91
	v_max_i32_e32 v80, 0, v80
	v_max_i32_e32 v84, 0, v84
	v_max_i32_e32 v81, 0, v81
	v_max_i32_e32 v82, 0, v82
	v_lshl_add_u64 v[98:99], s[74:75], 0, v[96:97]
	v_max_i32_e32 v92, 0, v92
	v_mul_f32_e32 v88, v88, v88
	v_max_i32_e32 v93, 0, v93
	v_mul_f32_e32 v89, v89, v89
	v_max_i32_e32 v94, 0, v94
	v_mul_f32_e32 v90, v90, v90
	v_max_i32_e32 v95, 0, v95
	v_mul_f32_e32 v91, v91, v91
	v_mul_f32_e32 v80, v80, v80
	v_mul_f32_e32 v84, v84, v84
	v_max_i32_e32 v85, 0, v85
	v_mul_f32_e32 v81, v81, v81
	v_mul_f32_e32 v82, v82, v82
	v_max_i32_e32 v83, 0, v83
	v_mul_f32_e32 v92, v92, v92
	v_mul_f32_e32 v93, v93, v93
	v_mul_f32_e32 v94, v94, v94
	v_mul_f32_e32 v95, v95, v95
	v_cvt_pk_bf16_f32 v88, v88, v89
	v_cvt_pk_bf16_f32 v89, v90, v91
	v_cvt_pk_bf16_f32 v90, v92, v93
	v_cvt_pk_bf16_f32 v91, v94, v95
	global_store_dwordx4 v[98:99], v[88:91], off
	v_mul_f32_e32 v85, v85, v85
	v_mul_f32_e32 v83, v83, v83
	v_cvt_pk_bf16_f32 v80, v80, v81
	v_cvt_pk_bf16_f32 v81, v82, v83
	v_cvt_pk_bf16_f32 v82, v84, v85
	v_add_co_u32_e32 v84, vcc, s39, v98
	v_max_i32_e32 v86, 0, v86
	v_max_i32_e32 v87, 0, v87
	v_addc_co_u32_e32 v85, vcc, 0, v99, vcc
	v_mul_f32_e32 v86, v86, v86
	v_mul_f32_e32 v87, v87, v87
	v_cvt_pk_bf16_f32 v83, v86, v87
	global_store_dwordx4 v[84:85], v[80:83], off
	v_max_i32_e32 v64, 0, v64
	v_max_i32_e32 v65, 0, v65
	v_or_b32_e32 v80, 0xc00, v148
	v_ashrrev_i32_e32 v81, 31, v80
	v_lshlrev_b64 v[80:81], 1, v[80:81]
	v_max_i32_e32 v66, 0, v66
	v_max_i32_e32 v67, 0, v67
	v_max_i32_e32 v48, 0, v48
	v_max_i32_e32 v52, 0, v52
	v_max_i32_e32 v49, 0, v49
	v_max_i32_e32 v50, 0, v50
	v_lshl_add_u64 v[82:83], s[74:75], 0, v[80:81]
	v_max_i32_e32 v68, 0, v68
	v_mul_f32_e32 v64, v64, v64
	v_max_i32_e32 v69, 0, v69
	v_mul_f32_e32 v65, v65, v65
	v_max_i32_e32 v70, 0, v70
	v_mul_f32_e32 v66, v66, v66
	v_max_i32_e32 v71, 0, v71
	v_mul_f32_e32 v67, v67, v67
	v_mul_f32_e32 v48, v48, v48
	v_mul_f32_e32 v52, v52, v52
;     __device__ __forceinline__ void operator()(const f32x4 (&acc)[2][2][4][2], const Unit& u, int wr, int wc, int fr, int fq) const {
;     ...
;                 for (int bj = 0; bj < 2; ++bj) { f32x4 v0 = acc[ai][bj][m][0], v1 = acc[ai][bj][m][1];
;                     if (ACT == 3) { const float pos = (float)((row0 + ai * HALF + m * 16) & 2047); float c3[4], s3[4];
; #pragma unroll
;                         for (int p = 0; p < 4; ++p) { float r = pos * rinv3[bj][p]; r -= floorf(r); s3[p] = rope3[bj] ? __builtin_amdgcn_sinf(r) : 0.f; c3[p] = rope3[bj] ? __builtin_amdgcn_cosf(r) : 1.f; }
;                         const f32x4 a = v0, b = v1;
;                         v0[0] = a[0] * c3[0] - a[1] * s3[0]; v0[1] = a[1] * c3[0] + a[0] * s3[0]; v0[2] = a[2] * c3[1] - a[3] * s3[1]; v0[3] = a[3] * c3[1] + a[2] * s3[1];
;                         v1[0] = b[0] * c3[2] - b[1] * s3[2]; v1[1] = b[1] * c3[2] + b[0] * s3[2]; v1[2] = b[2] * c3[3] - b[3] * s3[3]; v1[3] = b[3] * c3[3] + b[2] * s3[3]; }
;                     if (ACT == 2) { const f32x4 a = v0, b = v1;
;                         v0[0] = a[0] * rc[0][0] - a[1] * rs[0][0]; v0[1] = a[1] * rc[0][0] + a[0] * rs[0][0]; v0[2] = a[2] * rc[0][1] - a[3] * rs[0][1]; v0[3] = a[3] * rc[0][1] + a[2] * rs[0][1];
;                         v1[0] = b[0] * rc[1][0] - b[1] * rs[1][0]; v1[1] = b[1] * rc[1][0] + b[0] * rs[1][0]; v1[2] = b[2] * rc[1][1] - b[3] * rs[1][1]; v1[3] = b[3] * rc[1][1] + b[2] * rs[1][1]; }
;                     if (ACT == 1) {
; #pragma unroll
;                         for (int j = 0; j < 4; ++j) { const float a = __int_as_float(max(__float_as_int(v0[j]), 0)), b = __int_as_float(max(__float_as_int(v1[j]), 0)); v0[j] = a * a; v1[j] = b * b; } }
;                     u32x4 w; w.x = cvt_pk_bf16(v0[0], v0[1]); w.y = cvt_pk_bf16(v0[2], v0[3]); w.z = cvt_pk_bf16(v1[0], v1[1]); w.w = cvt_pk_bf16(v1[2], v1[3]);
;                     *(u32x4*)(rowp + (ACT == 1 ? bj * 2 * 2 * 8192 : bj * HALF)) = w; } }
; template <class Epi, class Sched, bool ALIGN_EPI = false, bool SP2 = false, bool A_TILED = false>
; __device__ __forceinline__ void gemm_phase(PG8_LAS unsigned char* lds, const Gemm g, const Sched& S, const Epi& E, const int wave_s) {
;     ...
;         if constexpr (ALIGN_EPI) { if (wr == 0) PG8_BAR; }
;         if constexpr (!Epi::AFTER_DRAIN) { int te = tid_now(wave_s); asm volatile("" : "+v"(te));
	v_max_i32_e32 v53, 0, v53
	v_mul_f32_e32 v49, v49, v49
	v_mul_f32_e32 v50, v50, v50
	v_max_i32_e32 v51, 0, v51
	v_mul_f32_e32 v68, v68, v68
	v_mul_f32_e32 v69, v69, v69
	v_mul_f32_e32 v70, v70, v70
	v_mul_f32_e32 v71, v71, v71
	v_cvt_pk_bf16_f32 v64, v64, v65
	v_cvt_pk_bf16_f32 v65, v66, v67
	v_cvt_pk_bf16_f32 v66, v68, v69
	v_cvt_pk_bf16_f32 v67, v70, v71
	global_store_dwordx4 v[82:83], v[64:67], off
	v_mul_f32_e32 v53, v53, v53
	v_mul_f32_e32 v51, v51, v51
	v_cvt_pk_bf16_f32 v48, v48, v49
	v_cvt_pk_bf16_f32 v49, v50, v51
	v_cvt_pk_bf16_f32 v50, v52, v53
	v_add_co_u32_e32 v52, vcc, s39, v82
	v_max_i32_e32 v54, 0, v54
	v_max_i32_e32 v55, 0, v55
	v_addc_co_u32_e32 v53, vcc, 0, v83, vcc
	v_mul_f32_e32 v54, v54, v54
	v_mul_f32_e32 v55, v55, v55
	v_cvt_pk_bf16_f32 v51, v54, v55
	global_store_dwordx4 v[52:53], v[48:51], off
	s_add_u32 s74, s74, 0x4000
	s_addc_u32 s75, s75, 0
	v_max_i32_e32 v49, 0, v76
	v_max_i32_e32 v48, 0, v72
	v_mul_f32_e32 v50, v49, v49
	v_max_i32_e32 v49, 0, v73
	v_mul_f32_e32 v48, v48, v48
	v_max_i32_e32 v51, 0, v77
	v_mul_f32_e32 v49, v49, v49
	v_max_i32_e32 v54, 0, v74
	v_max_i32_e32 v64, 0, v75
	v_lshl_add_u64 v[52:53], s[74:75], 0, v[150:151]
	v_mul_f32_e32 v51, v51, v51
	v_max_i32_e32 v55, 0, v78
	v_mul_f32_e32 v54, v54, v54
	v_max_i32_e32 v65, 0, v79
	v_mul_f32_e32 v64, v64, v64
	v_cvt_pk_bf16_f32 v48, v48, v49
	v_cvt_pk_bf16_f32 v49, v54, v64
	v_mul_f32_e32 v55, v55, v55
	v_mul_f32_e32 v65, v65, v65
	v_cvt_pk_bf16_f32 v50, v50, v51
	v_cvt_pk_bf16_f32 v51, v55, v65
	global_store_dwordx4 v[52:53], v[48:51], off
	v_or_b32_e32 v112, 0x400, v148
	v_max_i32_e32 v54, 0, v58
	v_max_i32_e32 v49, 0, v60
	v_max_i32_e32 v48, 0, v56
	v_mul_f32_e32 v50, v49, v49
	v_max_i32_e32 v49, 0, v57
	v_mul_f32_e32 v48, v48, v48
	v_max_i32_e32 v51, 0, v61
	v_mul_f32_e32 v49, v49, v49
	v_max_i32_e32 v56, 0, v59
	v_add_co_u32_e32 v52, vcc, s39, v52
	v_ashrrev_i32_e32 v113, 31, v112
	v_mul_f32_e32 v51, v51, v51
	v_max_i32_e32 v55, 0, v62
	v_mul_f32_e32 v54, v54, v54
	v_max_i32_e32 v57, 0, v63
	v_mul_f32_e32 v56, v56, v56
	v_cvt_pk_bf16_f32 v48, v48, v49
	v_cvt_pk_bf16_f32 v49, v54, v56
	v_addc_co_u32_e32 v53, vcc, 0, v53, vcc
	v_max_i32_e32 v40, 0, v40
	v_max_i32_e32 v41, 0, v41
	v_max_i32_e32 v42, 0, v42
	v_max_i32_e32 v43, 0, v43
	v_max_i32_e32 v32, 0, v32
	v_max_i32_e32 v36, 0, v36
	v_max_i32_e32 v33, 0, v33
	v_max_i32_e32 v34, 0, v34
	v_mul_f32_e32 v55, v55, v55
	v_mul_f32_e32 v57, v57, v57
	v_cvt_pk_bf16_f32 v50, v50, v51
	v_cvt_pk_bf16_f32 v51, v55, v57
	global_store_dwordx4 v[52:53], v[48:51], off
	v_max_i32_e32 v44, 0, v44
	v_mul_f32_e32 v40, v40, v40
	v_lshl_add_u64 v[48:49], v[112:113], 1, s[74:75]
	v_max_i32_e32 v45, 0, v45
	v_mul_f32_e32 v41, v41, v41
	v_max_i32_e32 v46, 0, v46
	v_mul_f32_e32 v42, v42, v42
	v_max_i32_e32 v47, 0, v47
	v_mul_f32_e32 v43, v43, v43
	v_mul_f32_e32 v32, v32, v32
	v_mul_f32_e32 v36, v36, v36
	v_max_i32_e32 v37, 0, v37
	v_mul_f32_e32 v33, v33, v33
	v_mul_f32_e32 v34, v34, v34
	v_max_i32_e32 v35, 0, v35
	v_mul_f32_e32 v44, v44, v44
	v_mul_f32_e32 v45, v45, v45
	v_mul_f32_e32 v46, v46, v46
	v_mul_f32_e32 v47, v47, v47
	v_cvt_pk_bf16_f32 v40, v40, v41
	v_cvt_pk_bf16_f32 v41, v42, v43
	v_cvt_pk_bf16_f32 v42, v44, v45
	v_cvt_pk_bf16_f32 v43, v46, v47
	global_store_dwordx4 v[48:49], v[40:43], off
	v_mul_f32_e32 v37, v37, v37
	v_mul_f32_e32 v35, v35, v35
	v_cvt_pk_bf16_f32 v32, v32, v33
	v_cvt_pk_bf16_f32 v33, v34, v35
	v_cvt_pk_bf16_f32 v34, v36, v37
	v_add_co_u32_e32 v36, vcc, s39, v48
	v_max_i32_e32 v38, 0, v38
	v_max_i32_e32 v39, 0, v39
	v_addc_co_u32_e32 v37, vcc, 0, v49, vcc
	v_max_i32_e32 v24, 0, v24
	v_max_i32_e32 v25, 0, v25
	v_max_i32_e32 v26, 0, v26
	v_max_i32_e32 v27, 0, v27
	v_max_i32_e32 v16, 0, v16
	v_max_i32_e32 v20, 0, v20
	v_max_i32_e32 v17, 0, v17
	v_max_i32_e32 v18, 0, v18
	v_mul_f32_e32 v38, v38, v38
	v_mul_f32_e32 v39, v39, v39
	v_cvt_pk_bf16_f32 v35, v38, v39
	global_store_dwordx4 v[36:37], v[32:35], off
	v_max_i32_e32 v28, 0, v28
	v_mul_f32_e32 v24, v24, v24
	v_lshl_add_u64 v[32:33], s[74:75], 0, v[96:97]
	v_max_i32_e32 v29, 0, v29
	v_mul_f32_e32 v25, v25, v25
	v_max_i32_e32 v30, 0, v30
	v_mul_f32_e32 v26, v26, v26
	v_max_i32_e32 v31, 0, v31
	v_mul_f32_e32 v27, v27, v27
	v_mul_f32_e32 v16, v16, v16
	v_mul_f32_e32 v20, v20, v20
	v_max_i32_e32 v21, 0, v21
	v_mul_f32_e32 v17, v17, v17
	v_mul_f32_e32 v18, v18, v18
	v_max_i32_e32 v19, 0, v19
	v_mul_f32_e32 v28, v28, v28
	v_mul_f32_e32 v29, v29, v29
	v_mul_f32_e32 v30, v30, v30
	v_mul_f32_e32 v31, v31, v31
	v_cvt_pk_bf16_f32 v24, v24, v25
	v_cvt_pk_bf16_f32 v25, v26, v27
	v_cvt_pk_bf16_f32 v26, v28, v29
	v_cvt_pk_bf16_f32 v27, v30, v31
	global_store_dwordx4 v[32:33], v[24:27], off
	v_mul_f32_e32 v21, v21, v21
	v_mul_f32_e32 v19, v19, v19
	v_cvt_pk_bf16_f32 v16, v16, v17
	v_cvt_pk_bf16_f32 v17, v18, v19
	v_cvt_pk_bf16_f32 v18, v20, v21
	v_add_co_u32_e32 v20, vcc, s39, v32
	v_max_i32_e32 v22, 0, v22
	v_max_i32_e32 v23, 0, v23
	v_addc_co_u32_e32 v21, vcc, 0, v33, vcc
	v_max_i32_e32 v8, 0, v8
	v_max_i32_e32 v9, 0, v9
	v_max_i32_e32 v10, 0, v10
	v_max_i32_e32 v11, 0, v11
	v_max_i32_e32 v0, 0, v0
	v_max_i32_e32 v4, 0, v4
	v_max_i32_e32 v1, 0, v1
	v_max_i32_e32 v2, 0, v2
	v_mul_f32_e32 v22, v22, v22
	v_mul_f32_e32 v23, v23, v23
	v_cvt_pk_bf16_f32 v19, v22, v23
	global_store_dwordx4 v[20:21], v[16:19], off
	v_max_i32_e32 v12, 0, v12
	v_mul_f32_e32 v8, v8, v8
	v_lshl_add_u64 v[16:17], s[74:75], 0, v[80:81]
	v_max_i32_e32 v13, 0, v13
	v_mul_f32_e32 v9, v9, v9
	v_max_i32_e32 v14, 0, v14
	v_mul_f32_e32 v10, v10, v10
	v_max_i32_e32 v15, 0, v15
	v_mul_f32_e32 v11, v11, v11
	v_mul_f32_e32 v0, v0, v0
	v_mul_f32_e32 v4, v4, v4
	v_max_i32_e32 v5, 0, v5
	v_mul_f32_e32 v1, v1, v1
	v_mul_f32_e32 v2, v2, v2
	v_max_i32_e32 v3, 0, v3
	v_mul_f32_e32 v12, v12, v12
	v_mul_f32_e32 v13, v13, v13
	v_mul_f32_e32 v14, v14, v14
	v_mul_f32_e32 v15, v15, v15
	v_cvt_pk_bf16_f32 v8, v8, v9
	v_cvt_pk_bf16_f32 v9, v10, v11
	v_cvt_pk_bf16_f32 v10, v12, v13
	v_cvt_pk_bf16_f32 v11, v14, v15
	global_store_dwordx4 v[16:17], v[8:11], off
	v_mul_f32_e32 v5, v5, v5
	v_mul_f32_e32 v3, v3, v3
	v_cvt_pk_bf16_f32 v0, v0, v1
	v_cvt_pk_bf16_f32 v1, v2, v3
	v_cvt_pk_bf16_f32 v2, v4, v5
	v_add_co_u32_e32 v4, vcc, 0x10000, v16
	v_max_i32_e32 v6, 0, v6
	s_nop 0
	v_addc_co_u32_e32 v5, vcc, 0, v17, vcc
	v_max_i32_e32 v7, 0, v7
	s_andn2_b64 vcc, exec, s[0:1]
	s_mov_b64 s[0:1], -1
	v_mul_f32_e32 v6, v6, v6
	v_mul_f32_e32 v7, v7, v7
	v_cvt_pk_bf16_f32 v3, v6, v7
	global_store_dwordx4 v[4:5], v[0:3], off
	s_cbranch_vccnz .LBB0_1147
	s_andn2_b64 vcc, exec, s[4:5]
	s_cbranch_vccnz .LBB0_1146
	s_barrier
	s_branch .LBB0_1146

; __device__ __forceinline__ unsigned cvt_pk_bf16(float lo, float hi) { unsigned r; asm volatile("v_cvt_pk_bf16_f32 %0, %1, %2" : "=v"(r) : "v"(lo), "v"(hi)); return r; }
;     __device__ __forceinline__ void fused(f32x4 (&acc)[2][2][4][2], const Unit& un, int wr, int wc, int fr, int fq, PG8_LAS unsigned char* lds, int wid, int lane) const {
;     ...
;         const size_t boff = (size_t)(un.pm >> 3) * bstride + col0;
;         { f32x4 gv[2][2];
; #pragma unroll
;           for (int bj = 0; bj < 2; ++bj)
; #pragma unroll
;               for (int n = 0; n < 2; ++n) gv[bj][n] = *(const f32x4*)(gate + boff + bj * HALF + n * 4);
; #pragma unroll
;           for (int ai = 0; ai < 2; ++ai)
; #pragma unroll
;               for (int m = 0; m < 4; ++m) { const size_t off = (size_t)(row0 + ai * HALF + m * 16) * ldc + col0;
; #pragma unroll
;                   for (int bj = 0; bj < 2; ++bj) {
; #pragma unroll
;                       for (int n = 0; n < 2; ++n) { f32x4 bs;
;                           if (BASE_F32) bs = *(const f32x4*)((const float*)base + off + bj * HALF + n * 4);
;                           else { const u32x2v hw = *(const u32x2v*)((const bf16_t*)base + off + bj * HALF + n * 4);
;                                  bs = (f32x4){__uint_as_float(hw.x << 16), __uint_as_float(hw.x & 0xffff0000u), __uint_as_float(hw.y << 16), __uint_as_float(hw.y & 0xffff0000u)}; }
;                           acc[ai][bj][m][n] = bs + gv[bj][n] * acc[ai][bj][m][n]; }
;                       if (out_h) { const f32x4 a0 = acc[ai][bj][m][0], a1 = acc[ai][bj][m][1]; u32x4 w; w.x = cvt_pk_bf16(a0[0], a0[1]); w.y = cvt_pk_bf16(a0[2], a0[3]); w.z = cvt_pk_bf16(a1[0], a1[1]); w.w = cvt_pk_bf16(a1[2], a1[3]);
;                           *(u32x4*)(out_h + off + bj * HALF) = w; } }
.LBB0_1231:
	v_mov_b32_e32 v32, 0
	s_barrier
	s_lshl_b32 s4, s7, 5
	v_mbcnt_lo_u32_b32 v32, -1, v32
	s_add_u32 s0, s12, 0x1a600000
	v_mbcnt_hi_u32_b32 v32, -1, v32
	s_addc_u32 s1, s13, 0
	v_or_b32_e32 v158, s33, v32
	s_lshl_b32 s5, s2, 8
	s_lshl_b32 s14, s62, 8
	s_or_b32 s4, s5, s4
	v_lshrrev_b32_e32 v32, 1, v158
	v_and_b32_e32 v159, 15, v158
	s_add_i32 s15, s14, s6
	v_and_or_b32 v152, v32, 24, s4
	s_ashr_i32 s4, s62, 3
	v_ashrrev_i32_e32 v153, 31, v152
	v_mov_b32_e32 v32, 0x3000
	v_or_b32_e32 v156, s15, v159
	v_mad_i64_i32 v[32:33], s[4:5], s4, v32, v[152:153]
	v_ashrrev_i32_e32 v157, 31, v156
	v_lshl_add_u64 v[150:151], v[32:33], 2, s[12:13]
	v_lshlrev_b64 v[32:33], 12, v[156:157]
	v_lshl_add_u64 v[32:33], s[0:1], 0, v[32:33]
	v_lshlrev_b64 v[148:149], 1, v[152:153]
	s_mov_b32 s15, 0x10a000
	v_lshl_add_u64 v[154:155], v[32:33], 0, v[148:149]
	v_add_co_u32_e32 v132, vcc, s15, v150
	s_nop 0
	v_addc_co_u32_e32 v133, vcc, 0, v151, vcc
	s_mov_b64 s[4:5], 0x10a000
	global_load_dwordx4 v[144:147], v[132:133], off
	v_lshl_add_u64 v[132:133], v[150:151], 0, s[4:5]
	global_load_dwordx4 v[140:143], v[132:133], off offset:16
	global_load_dwordx4 v[136:139], v[132:133], off offset:512
	s_nop 0
	global_load_dwordx4 v[132:135], v[132:133], off offset:528
	v_or_b32_e32 v164, 16, v156
	v_ashrrev_i32_e32 v165, 31, v164
	v_lshlrev_b64 v[164:165], 12, v[164:165]
	v_lshl_add_u64 v[164:165], s[0:1], 0, v[164:165]
	v_lshl_add_u64 v[164:165], v[164:165], 0, v[148:149]
	s_mov_b64 s[98:99], 0x10000
	s_mov_b64 s[100:101], 0x80000
	v_lshl_add_u64 v[232:233], v[154:155], 0, 0
	v_lshl_add_u64 v[234:235], v[232:233], 0, s[98:99]
	v_lshl_add_u64 v[236:237], v[234:235], 0, s[98:99]
	v_lshl_add_u64 v[238:239], v[236:237], 0, s[98:99]
	global_load_dwordx4 v[200:203], v[232:233], off
	global_load_dwordx4 v[204:207], v[232:233], off offset:256
	global_load_dwordx4 v[208:211], v[234:235], off
	global_load_dwordx4 v[212:215], v[234:235], off offset:256
	global_load_dwordx4 v[216:219], v[236:237], off
	global_load_dwordx4 v[220:223], v[236:237], off offset:256
	global_load_dwordx4 v[224:227], v[238:239], off
	global_load_dwordx4 v[228:231], v[238:239], off offset:256
	s_waitcnt vmcnt(0) lgkmcnt(0)
	v_lshlrev_b32_e32 v160, 16, v200
	v_and_b32_e32 v161, 0xffff0000, v200
	v_lshlrev_b32_e32 v32, 16, v201
	v_and_b32_e32 v33, 0xffff0000, v201
	v_lshlrev_b32_e32 v162, 16, v202
	v_and_b32_e32 v163, 0xffff0000, v202
	v_lshlrev_b32_e32 v34, 16, v203
	v_and_b32_e32 v35, 0xffff0000, v203
	v_pk_fma_f32 v[10:11], v[10:11], v[146:147], v[32:33]
	v_pk_fma_f32 v[8:9], v[8:9], v[144:145], v[160:161]
	v_pk_fma_f32 v[14:15], v[14:15], v[142:143], v[34:35]
	v_pk_fma_f32 v[12:13], v[12:13], v[140:141], v[162:163]
	v_cvt_pk_bf16_f32 v32, v8, v9
	v_cvt_pk_bf16_f32 v33, v10, v11
	s_nop 0
	v_cvt_pk_bf16_f32 v34, v12, v13
	v_cvt_pk_bf16_f32 v35, v14, v15
	s_nop 0
	global_store_dwordx4 v[154:155], v[32:35], off
	s_nop 1
	s_nop 0
	v_lshlrev_b32_e32 v32, 16, v204
	v_and_b32_e32 v33, 0xffff0000, v204
	v_lshlrev_b32_e32 v34, 16, v205
	v_and_b32_e32 v35, 0xffff0000, v205
	v_lshlrev_b32_e32 v160, 16, v206
	v_and_b32_e32 v161, 0xffff0000, v206
	v_lshlrev_b32_e32 v162, 16, v207
	v_and_b32_e32 v163, 0xffff0000, v207
	v_pk_fma_f32 v[34:35], v[30:31], v[138:139], v[34:35]
	v_pk_fma_f32 v[32:33], v[28:29], v[136:137], v[32:33]
	v_pk_fma_f32 v[30:31], v[18:19], v[134:135], v[162:163]
	v_pk_fma_f32 v[28:29], v[16:17], v[132:133], v[160:161]
	v_cvt_pk_bf16_f32 v16, v32, v33
	v_cvt_pk_bf16_f32 v17, v34, v35
	s_nop 0
	v_cvt_pk_bf16_f32 v18, v28, v29
	v_cvt_pk_bf16_f32 v19, v30, v31
	global_store_dwordx4 v[154:155], v[16:19], off offset:256
	s_nop 1
	v_lshlrev_b32_e32 v160, 16, v208
	v_and_b32_e32 v161, 0xffff0000, v208
	v_lshlrev_b32_e32 v16, 16, v209
	v_and_b32_e32 v17, 0xffff0000, v209
	v_lshlrev_b32_e32 v162, 16, v210
	v_and_b32_e32 v163, 0xffff0000, v210
	v_lshlrev_b32_e32 v166, 16, v211
	v_and_b32_e32 v167, 0xffff0000, v211
	v_pk_fma_f32 v[18:19], v[62:63], v[146:147], v[16:17]
	v_pk_fma_f32 v[16:17], v[60:61], v[144:145], v[160:161]
	v_pk_fma_f32 v[22:23], v[22:23], v[142:143], v[166:167]
	v_pk_fma_f32 v[20:21], v[20:21], v[140:141], v[162:163]
	v_cvt_pk_bf16_f32 v60, v16, v17
	v_cvt_pk_bf16_f32 v61, v18, v19
	v_or_b32_e32 v166, 32, v156
	v_cvt_pk_bf16_f32 v62, v20, v21
	v_cvt_pk_bf16_f32 v63, v22, v23
	v_ashrrev_i32_e32 v167, 31, v166
	v_lshlrev_b64 v[166:167], 12, v[166:167]
	global_store_dwordx4 v[164:165], v[60:63], off
	v_lshl_add_u64 v[166:167], s[0:1], 0, v[166:167]
	v_lshl_add_u64 v[166:167], v[166:167], 0, v[148:149]
	v_or_b32_e32 v156, 48, v156
	v_ashrrev_i32_e32 v157, 31, v156
	v_lshlrev_b64 v[156:157], 12, v[156:157]
	v_lshl_add_u64 v[156:157], s[0:1], 0, v[156:157]
	v_lshl_add_u64 v[156:157], v[156:157], 0, v[148:149]
	s_mov_b32 s0, 0x80000
	s_nop 1
	v_lshlrev_b32_e32 v60, 16, v212
	v_and_b32_e32 v61, 0xffff0000, v212
	v_lshlrev_b32_e32 v62, 16, v213
	v_and_b32_e32 v63, 0xffff0000, v213
	v_lshlrev_b32_e32 v160, 16, v214
	v_and_b32_e32 v161, 0xffff0000, v214
	v_lshlrev_b32_e32 v162, 16, v215
	v_and_b32_e32 v163, 0xffff0000, v215
	v_pk_fma_f32 v[62:63], v[58:59], v[138:139], v[62:63]
	v_pk_fma_f32 v[60:61], v[56:57], v[136:137], v[60:61]
	v_pk_fma_f32 v[58:59], v[50:51], v[134:135], v[162:163]
	v_pk_fma_f32 v[56:57], v[48:49], v[132:133], v[160:161]
	v_cvt_pk_bf16_f32 v48, v60, v61
	v_cvt_pk_bf16_f32 v49, v62, v63
	s_nop 0
	v_cvt_pk_bf16_f32 v50, v56, v57
	v_cvt_pk_bf16_f32 v51, v58, v59
	global_store_dwordx4 v[164:165], v[48:51], off offset:256
	s_nop 1
	v_lshlrev_b32_e32 v160, 16, v216
	v_and_b32_e32 v161, 0xffff0000, v216
	v_lshlrev_b32_e32 v48, 16, v217
	v_and_b32_e32 v49, 0xffff0000, v217
; __device__ __forceinline__ unsigned cvt_pk_bf16(float lo, float hi) { unsigned r; asm volatile("v_cvt_pk_bf16_f32 %0, %1, %2" : "=v"(r) : "v"(lo), "v"(hi)); return r; }
;     __device__ __forceinline__ void fused(f32x4 (&acc)[2][2][4][2], const Unit& un, int wr, int wc, int fr, int fq, PG8_LAS unsigned char* lds, int wid, int lane) const {
;     ...
;           for (int ai = 0; ai < 2; ++ai)
; #pragma unroll
;               for (int m = 0; m < 4; ++m) { const size_t off = (size_t)(row0 + ai * HALF + m * 16) * ldc + col0;
; #pragma unroll
;                   for (int bj = 0; bj < 2; ++bj) {
; #pragma unroll
;                       for (int n = 0; n < 2; ++n) { f32x4 bs;
;                           if (BASE_F32) bs = *(const f32x4*)((const float*)base + off + bj * HALF + n * 4);
;                           else { const u32x2v hw = *(const u32x2v*)((const bf16_t*)base + off + bj * HALF + n * 4);
;                                  bs = (f32x4){__uint_as_float(hw.x << 16), __uint_as_float(hw.x & 0xffff0000u), __uint_as_float(hw.y << 16), __uint_as_float(hw.y & 0xffff0000u)}; }
;                           acc[ai][bj][m][n] = bs + gv[bj][n] * acc[ai][bj][m][n]; }
;                       if (out_h) { const f32x4 a0 = acc[ai][bj][m][0], a1 = acc[ai][bj][m][1]; u32x4 w; w.x = cvt_pk_bf16(a0[0], a0[1]); w.y = cvt_pk_bf16(a0[2], a0[3]); w.z = cvt_pk_bf16(a1[0], a1[1]); w.w = cvt_pk_bf16(a1[2], a1[3]);
;                           *(u32x4*)(out_h + off + bj * HALF) = w; } }
;                   asm volatile("" : "+v"(acc[ai][0][m][0]), "+v"(acc[ai][0][m][1]), "+v"(acc[ai][1][m][0]), "+v"(acc[ai][1][m][1]));
;                   asm volatile("" ::: "memory"); } }
	v_lshlrev_b32_e32 v162, 16, v218
	v_and_b32_e32 v163, 0xffff0000, v218
	v_lshlrev_b32_e32 v164, 16, v219
	v_and_b32_e32 v165, 0xffff0000, v219
	v_pk_fma_f32 v[50:51], v[78:79], v[146:147], v[48:49]
	v_pk_fma_f32 v[48:49], v[76:77], v[144:145], v[160:161]
	v_pk_fma_f32 v[54:55], v[54:55], v[142:143], v[164:165]
	v_pk_fma_f32 v[52:53], v[52:53], v[140:141], v[162:163]
	v_cvt_pk_bf16_f32 v76, v48, v49
	v_cvt_pk_bf16_f32 v77, v50, v51
	s_nop 0
	v_cvt_pk_bf16_f32 v78, v52, v53
	v_cvt_pk_bf16_f32 v79, v54, v55
	s_nop 0
	global_store_dwordx4 v[166:167], v[76:79], off
	s_nop 1
	s_nop 0
	v_lshlrev_b32_e32 v76, 16, v220
	v_and_b32_e32 v77, 0xffff0000, v220
	v_lshlrev_b32_e32 v78, 16, v221
	v_and_b32_e32 v79, 0xffff0000, v221
	v_lshlrev_b32_e32 v160, 16, v222
	v_and_b32_e32 v161, 0xffff0000, v222
	v_lshlrev_b32_e32 v162, 16, v223
	v_and_b32_e32 v163, 0xffff0000, v223
	v_pk_fma_f32 v[78:79], v[74:75], v[138:139], v[78:79]
	v_pk_fma_f32 v[76:77], v[72:73], v[136:137], v[76:77]
	v_pk_fma_f32 v[74:75], v[66:67], v[134:135], v[162:163]
	v_pk_fma_f32 v[72:73], v[64:65], v[132:133], v[160:161]
	v_cvt_pk_bf16_f32 v64, v76, v77
	v_cvt_pk_bf16_f32 v65, v78, v79
	s_nop 0
	v_cvt_pk_bf16_f32 v66, v72, v73
	v_cvt_pk_bf16_f32 v67, v74, v75
	global_store_dwordx4 v[166:167], v[64:67], off offset:256
	s_nop 1
	v_lshlrev_b32_e32 v160, 16, v224
	v_and_b32_e32 v161, 0xffff0000, v224
	v_lshlrev_b32_e32 v64, 16, v225
	v_and_b32_e32 v65, 0xffff0000, v225
	v_lshlrev_b32_e32 v162, 16, v226
	v_and_b32_e32 v163, 0xffff0000, v226
	v_lshlrev_b32_e32 v164, 16, v227
	v_and_b32_e32 v165, 0xffff0000, v227
	v_pk_fma_f32 v[66:67], v[130:131], v[146:147], v[64:65]
	v_pk_fma_f32 v[64:65], v[128:129], v[144:145], v[160:161]
	v_pk_fma_f32 v[70:71], v[70:71], v[142:143], v[164:165]
	v_pk_fma_f32 v[68:69], v[68:69], v[140:141], v[162:163]
	v_cvt_pk_bf16_f32 v128, v64, v65
	v_cvt_pk_bf16_f32 v129, v66, v67
	v_add_co_u32_e32 v164, vcc, s0, v154
	v_cvt_pk_bf16_f32 v130, v68, v69
	v_cvt_pk_bf16_f32 v131, v70, v71
	s_nop 0
	v_addc_co_u32_e32 v165, vcc, 0, v155, vcc
	global_store_dwordx4 v[156:157], v[128:131], off
	s_mov_b64 s[0:1], 0x80000
	s_nop 1
	v_lshlrev_b32_e32 v128, 16, v228
	v_and_b32_e32 v129, 0xffff0000, v228
	v_lshlrev_b32_e32 v130, 16, v229
	v_and_b32_e32 v131, 0xffff0000, v229
	v_lshlrev_b32_e32 v160, 16, v230
	v_and_b32_e32 v161, 0xffff0000, v230
	v_lshlrev_b32_e32 v162, 16, v231
	v_and_b32_e32 v163, 0xffff0000, v231
	v_pk_fma_f32 v[110:111], v[110:111], v[138:139], v[130:131]
	v_pk_fma_f32 v[108:109], v[108:109], v[136:137], v[128:129]
	v_pk_fma_f32 v[98:99], v[98:99], v[134:135], v[162:163]
	v_pk_fma_f32 v[96:97], v[96:97], v[132:133], v[160:161]
	v_cvt_pk_bf16_f32 v128, v108, v109
	v_cvt_pk_bf16_f32 v129, v110, v111
	s_nop 0
	v_cvt_pk_bf16_f32 v130, v96, v97
	v_cvt_pk_bf16_f32 v131, v98, v99
	global_store_dwordx4 v[156:157], v[128:131], off offset:256
	v_lshl_add_u64 v[156:157], v[154:155], 0, s[0:1]
	s_mov_b32 s0, 0x90000
	v_add_co_u32_e32 v166, vcc, s0, v154
	s_mov_b64 s[0:1], 0x90000
	s_nop 0
	v_addc_co_u32_e32 v167, vcc, 0, v155, vcc
	v_lshl_add_u64 v[232:233], v[232:233], 0, s[100:101]
	v_lshl_add_u64 v[234:235], v[234:235], 0, s[100:101]
	v_lshl_add_u64 v[236:237], v[236:237], 0, s[100:101]
	v_lshl_add_u64 v[238:239], v[238:239], 0, s[100:101]
	global_load_dwordx4 v[200:203], v[232:233], off
	global_load_dwordx4 v[204:207], v[232:233], off offset:256
	global_load_dwordx4 v[208:211], v[234:235], off
	global_load_dwordx4 v[212:215], v[234:235], off offset:256
	global_load_dwordx4 v[216:219], v[236:237], off
	global_load_dwordx4 v[220:223], v[236:237], off offset:256
	global_load_dwordx4 v[224:227], v[238:239], off
	global_load_dwordx4 v[228:231], v[238:239], off offset:256
	s_waitcnt vmcnt(0) lgkmcnt(0)
	v_lshlrev_b32_e32 v160, 16, v200
	v_and_b32_e32 v161, 0xffff0000, v200
	v_lshlrev_b32_e32 v128, 16, v201
	v_and_b32_e32 v129, 0xffff0000, v201
	v_lshlrev_b32_e32 v162, 16, v202
	v_and_b32_e32 v163, 0xffff0000, v202
	v_lshlrev_b32_e32 v130, 16, v203
	v_and_b32_e32 v131, 0xffff0000, v203
	v_pk_fma_f32 v[102:103], v[102:103], v[146:147], v[128:129]
	v_pk_fma_f32 v[100:101], v[100:101], v[144:145], v[160:161]
	v_pk_fma_f32 v[106:107], v[106:107], v[142:143], v[130:131]
	v_pk_fma_f32 v[104:105], v[104:105], v[140:141], v[162:163]
	v_cvt_pk_bf16_f32 v128, v100, v101
	v_cvt_pk_bf16_f32 v129, v102, v103
	s_nop 0
	v_cvt_pk_bf16_f32 v130, v104, v105
	v_cvt_pk_bf16_f32 v131, v106, v107
	s_nop 0
	global_store_dwordx4 v[164:165], v[128:131], off
	s_nop 1
	s_nop 0
	v_lshlrev_b32_e32 v128, 16, v204
	v_and_b32_e32 v129, 0xffff0000, v204
	v_lshlrev_b32_e32 v130, 16, v205
	v_and_b32_e32 v131, 0xffff0000, v205
	v_lshlrev_b32_e32 v160, 16, v206
	v_and_b32_e32 v161, 0xffff0000, v206
	v_lshlrev_b32_e32 v162, 16, v207
	v_and_b32_e32 v163, 0xffff0000, v207
	v_pk_fma_f32 v[126:127], v[126:127], v[138:139], v[130:131]
	v_pk_fma_f32 v[124:125], v[124:125], v[136:137], v[128:129]
	v_pk_fma_f32 v[114:115], v[114:115], v[134:135], v[162:163]
	v_pk_fma_f32 v[112:113], v[112:113], v[132:133], v[160:161]
	v_cvt_pk_bf16_f32 v128, v124, v125
	v_cvt_pk_bf16_f32 v129, v126, v127
	s_nop 0
	v_cvt_pk_bf16_f32 v130, v112, v113
	v_cvt_pk_bf16_f32 v131, v114, v115
	global_store_dwordx4 v[156:157], v[128:131], off offset:256
	v_lshl_add_u64 v[156:157], v[154:155], 0, s[0:1]
	s_mov_b32 s0, 0xa0000
	v_add_co_u32_e32 v164, vcc, s0, v154
	s_mov_b64 s[0:1], 0xa0000
	s_nop 0
	v_addc_co_u32_e32 v165, vcc, 0, v155, vcc
	s_nop 1
	v_lshlrev_b32_e32 v160, 16, v208
	v_and_b32_e32 v161, 0xffff0000, v208
	v_lshlrev_b32_e32 v128, 16, v209
	v_and_b32_e32 v129, 0xffff0000, v209
	v_lshlrev_b32_e32 v162, 16, v210
; __device__ __forceinline__ unsigned cvt_pk_bf16(float lo, float hi) { unsigned r; asm volatile("v_cvt_pk_bf16_f32 %0, %1, %2" : "=v"(r) : "v"(lo), "v"(hi)); return r; }
;     __device__ __forceinline__ void fused(f32x4 (&acc)[2][2][4][2], const Unit& un, int wr, int wc, int fr, int fq, PG8_LAS unsigned char* lds, int wid, int lane) const {
;     ...
;           for (int ai = 0; ai < 2; ++ai)
; #pragma unroll
;               for (int m = 0; m < 4; ++m) { const size_t off = (size_t)(row0 + ai * HALF + m * 16) * ldc + col0;
; #pragma unroll
;                   for (int bj = 0; bj < 2; ++bj) {
; #pragma unroll
;                       for (int n = 0; n < 2; ++n) { f32x4 bs;
;                           if (BASE_F32) bs = *(const f32x4*)((const float*)base + off + bj * HALF + n * 4);
;                           else { const u32x2v hw = *(const u32x2v*)((const bf16_t*)base + off + bj * HALF + n * 4);
;                                  bs = (f32x4){__uint_as_float(hw.x << 16), __uint_as_float(hw.x & 0xffff0000u), __uint_as_float(hw.y << 16), __uint_as_float(hw.y & 0xffff0000u)}; }
;                           acc[ai][bj][m][n] = bs + gv[bj][n] * acc[ai][bj][m][n]; }
;                       if (out_h) { const f32x4 a0 = acc[ai][bj][m][0], a1 = acc[ai][bj][m][1]; u32x4 w; w.x = cvt_pk_bf16(a0[0], a0[1]); w.y = cvt_pk_bf16(a0[2], a0[3]); w.z = cvt_pk_bf16(a1[0], a1[1]); w.w = cvt_pk_bf16(a1[2], a1[3]);
;                           *(u32x4*)(out_h + off + bj * HALF) = w; } }
;                   asm volatile("" : "+v"(acc[ai][0][m][0]), "+v"(acc[ai][0][m][1]), "+v"(acc[ai][1][m][0]), "+v"(acc[ai][1][m][1]));
;                   asm volatile("" ::: "memory"); } }
; #pragma unroll
;         for (int ai = 0; ai < 2; ++ai)
; #pragma unroll
;             for (int m = 0; m < 4; ++m) { float s = 0.f;
; #pragma unroll
;                 for (int bj = 0; bj < 2; ++bj)
; #pragma unroll
;                     for (int n = 0; n < 2; ++n) { const f32x4 x = acc[ai][bj][m][n]; s += (x[0] * x[0] + x[1] * x[1]) + (x[2] * x[2] + x[3] * x[3]); }
;                 s += __shfl_xor(s, 16); s += __shfl_xor(s, 32);
;                 if (fq == 0) P[(ai * HALF + wr * 64 + m * 16 + fr) * 4 + wc] = s; }
	v_and_b32_e32 v163, 0xffff0000, v210
	v_lshlrev_b32_e32 v130, 16, v211
	v_and_b32_e32 v131, 0xffff0000, v211
	v_pk_fma_f32 v[118:119], v[118:119], v[146:147], v[128:129]
	v_pk_fma_f32 v[116:117], v[116:117], v[144:145], v[160:161]
	v_pk_fma_f32 v[122:123], v[122:123], v[142:143], v[130:131]
	v_pk_fma_f32 v[120:121], v[120:121], v[140:141], v[162:163]
	v_cvt_pk_bf16_f32 v128, v116, v117
	v_cvt_pk_bf16_f32 v129, v118, v119
	s_nop 0
	v_cvt_pk_bf16_f32 v130, v120, v121
	v_cvt_pk_bf16_f32 v131, v122, v123
	s_nop 0
	global_store_dwordx4 v[166:167], v[128:131], off
	s_nop 1
	s_nop 0
	v_lshlrev_b32_e32 v128, 16, v212
	v_and_b32_e32 v129, 0xffff0000, v212
	v_lshlrev_b32_e32 v130, 16, v213
	v_and_b32_e32 v131, 0xffff0000, v213
	v_lshlrev_b32_e32 v160, 16, v214
	v_and_b32_e32 v161, 0xffff0000, v214
	v_lshlrev_b32_e32 v162, 16, v215
	v_and_b32_e32 v163, 0xffff0000, v215
	v_pk_fma_f32 v[94:95], v[94:95], v[138:139], v[130:131]
	v_pk_fma_f32 v[92:93], v[92:93], v[136:137], v[128:129]
	v_pk_fma_f32 v[90:91], v[90:91], v[134:135], v[162:163]
	v_pk_fma_f32 v[88:89], v[88:89], v[132:133], v[160:161]
	v_cvt_pk_bf16_f32 v128, v92, v93
	v_cvt_pk_bf16_f32 v129, v94, v95
	s_nop 0
	v_cvt_pk_bf16_f32 v130, v88, v89
	v_cvt_pk_bf16_f32 v131, v90, v91
	global_store_dwordx4 v[156:157], v[128:131], off offset:256
	v_lshl_add_u64 v[156:157], v[154:155], 0, s[0:1]
	s_mov_b32 s0, 0xb0000
	v_add_co_u32_e32 v166, vcc, s0, v154
	s_mov_b64 s[0:1], 0xb0000
	s_nop 0
	v_addc_co_u32_e32 v167, vcc, 0, v155, vcc
	s_nop 1
	v_lshlrev_b32_e32 v160, 16, v216
	v_and_b32_e32 v161, 0xffff0000, v216
	v_lshlrev_b32_e32 v128, 16, v217
	v_and_b32_e32 v129, 0xffff0000, v217
	v_lshlrev_b32_e32 v162, 16, v218
	v_and_b32_e32 v163, 0xffff0000, v218
	v_lshlrev_b32_e32 v130, 16, v219
	v_and_b32_e32 v131, 0xffff0000, v219
	v_pk_fma_f32 v[86:87], v[86:87], v[146:147], v[128:129]
	v_pk_fma_f32 v[84:85], v[84:85], v[144:145], v[160:161]
	v_pk_fma_f32 v[82:83], v[82:83], v[142:143], v[130:131]
	v_pk_fma_f32 v[80:81], v[80:81], v[140:141], v[162:163]
	v_cvt_pk_bf16_f32 v128, v84, v85
	v_cvt_pk_bf16_f32 v129, v86, v87
	s_nop 0
	v_cvt_pk_bf16_f32 v130, v80, v81
	v_cvt_pk_bf16_f32 v131, v82, v83
	s_nop 0
	global_store_dwordx4 v[164:165], v[128:131], off
	v_mul_f32_e32 v164, v29, v29
	v_mul_f32_e32 v165, v31, v31
	v_fmac_f32_e32 v164, v28, v28
	v_fmac_f32_e32 v165, v30, v30
	s_nop 1
	v_lshlrev_b32_e32 v128, 16, v220
	v_and_b32_e32 v129, 0xffff0000, v220
	v_lshlrev_b32_e32 v130, 16, v221
	v_and_b32_e32 v131, 0xffff0000, v221
	v_lshlrev_b32_e32 v160, 16, v222
	v_and_b32_e32 v161, 0xffff0000, v222
	v_lshlrev_b32_e32 v162, 16, v223
	v_and_b32_e32 v163, 0xffff0000, v223
	v_pk_fma_f32 v[46:47], v[46:47], v[138:139], v[130:131]
	v_pk_fma_f32 v[44:45], v[44:45], v[136:137], v[128:129]
	v_pk_fma_f32 v[42:43], v[42:43], v[134:135], v[162:163]
	v_pk_fma_f32 v[40:41], v[40:41], v[132:133], v[160:161]
	v_cvt_pk_bf16_f32 v128, v44, v45
	v_cvt_pk_bf16_f32 v129, v46, v47
	v_lshl_add_u64 v[160:161], v[154:155], 0, s[0:1]
	v_cvt_pk_bf16_f32 v130, v40, v41
	v_cvt_pk_bf16_f32 v131, v42, v43
	global_store_dwordx4 v[156:157], v[128:131], off offset:256
	v_mul_f32_e32 v162, v33, v33
	v_mul_f32_e32 v163, v35, v35
	v_fmac_f32_e32 v162, v32, v32
	v_fmac_f32_e32 v163, v34, v34
	s_lshl_b32 s0, s7, 2
	s_add_i32 s0, s0, 0
	s_nop 1
	v_lshlrev_b32_e32 v154, 16, v224
	v_and_b32_e32 v155, 0xffff0000, v224
	v_lshlrev_b32_e32 v128, 16, v225
	v_and_b32_e32 v129, 0xffff0000, v225
	v_lshlrev_b32_e32 v156, 16, v226
	v_and_b32_e32 v157, 0xffff0000, v226
	v_lshlrev_b32_e32 v130, 16, v227
	v_and_b32_e32 v131, 0xffff0000, v227
	v_pk_fma_f32 v[38:39], v[38:39], v[146:147], v[128:129]
	v_pk_fma_f32 v[36:37], v[36:37], v[144:145], v[154:155]
	v_pk_fma_f32 v[26:27], v[26:27], v[142:143], v[130:131]
	v_pk_fma_f32 v[24:25], v[24:25], v[140:141], v[156:157]
	v_cvt_pk_bf16_f32 v142, v36, v37
	v_cvt_pk_bf16_f32 v143, v38, v39
	v_mbcnt_lo_u32_b32 v128, -1, 0
	v_cvt_pk_bf16_f32 v144, v24, v25
	v_cvt_pk_bf16_f32 v145, v26, v27
	v_mbcnt_hi_u32_b32 v129, -1, v128
	v_mul_f32_e32 v140, v9, v9
	v_mul_f32_e32 v141, v11, v11
	v_mul_f32_e32 v146, v13, v13
	v_mul_f32_e32 v147, v15, v15
	v_and_b32_e32 v130, 64, v129
	v_fmac_f32_e32 v140, v8, v8
	v_fmac_f32_e32 v141, v10, v10
	v_fmac_f32_e32 v146, v12, v12
	v_fmac_f32_e32 v147, v14, v14
	v_xor_b32_e32 v128, 16, v129
	v_add_u32_e32 v130, 64, v130
	v_add_f32_e32 v140, v140, v141
	v_add_f32_e32 v141, v146, v147
	v_cmp_lt_i32_e32 vcc, v128, v130
	v_add_f32_e32 v146, v162, v163
	v_add_f32_e32 v140, v140, v141
	v_cndmask_b32_e32 v128, v129, v128, vcc
	v_add_f32_e32 v147, v164, v165
	v_add_f32_e32 v140, v146, v140
	v_lshlrev_b32_e32 v128, 2, v128
	v_add_f32_e32 v140, v147, v140
	ds_bpermute_b32 v141, v128, v140
	v_xor_b32_e32 v131, 32, v129
	v_cmp_lt_i32_e32 vcc, v131, v130
	global_store_dwordx4 v[166:167], v[142:145], off
	v_and_b32_e32 v130, 63, v158
	v_cndmask_b32_e32 v129, v129, v131, vcc
	v_lshlrev_b32_e32 v129, 2, v129
	s_waitcnt lgkmcnt(0)
	v_add_f32_e32 v140, v140, v141
	ds_bpermute_b32 v141, v129, v140
	v_cmp_gt_u32_e32 vcc, 16, v130
	s_waitcnt vmcnt(0)
	v_lshlrev_b32_e32 v142, 16, v228
	v_and_b32_e32 v143, 0xffff0000, v228
	v_lshlrev_b32_e32 v144, 16, v229
	v_and_b32_e32 v145, 0xffff0000, v229
	v_lshlrev_b32_e32 v146, 16, v230
	v_and_b32_e32 v147, 0xffff0000, v230
	v_lshlrev_b32_e32 v154, 16, v231
	v_and_b32_e32 v155, 0xffff0000, v231
	v_pk_fma_f32 v[6:7], v[6:7], v[138:139], v[144:145]
	v_pk_fma_f32 v[4:5], v[4:5], v[136:137], v[142:143]
	v_pk_fma_f32 v[2:3], v[2:3], v[134:135], v[154:155]
	v_pk_fma_f32 v[0:1], v[0:1], v[132:133], v[146:147]
	v_cvt_pk_bf16_f32 v132, v4, v5
	v_cvt_pk_bf16_f32 v133, v6, v7
	v_or_b32_e32 v144, s6, v159
	v_cvt_pk_bf16_f32 v134, v0, v1
	v_cvt_pk_bf16_f32 v135, v2, v3
	global_store_dwordx4 v[160:161], v[132:135], off offset:256
	v_lshl_add_u32 v131, v144, 4, s0
	s_and_saveexec_b64 s[0:1], vcc
	v_readlane_b32 s96, v254, 47
	s_cbranch_execz .LBB0_1233
	s_waitcnt lgkmcnt(0)
	v_add_f32_e32 v132, v140, v141
	ds_write_b32 v131, v132

;     __device__ __forceinline__ void fused(f32x4 (&acc)[2][2][4][2], const Unit& un, int wr, int wc, int fr, int fq, PG8_LAS unsigned char* lds, int wid, int lane) const {
;     ...
;         asm volatile("s_waitcnt lgkmcnt(0)" ::: "memory"); __builtin_amdgcn_s_barrier(); asm volatile("" ::: "memory");
;         const int row = wid * 32 + (lane & 31);
;         if (lane < 32) { const float tot = (P[row * 4 + 0] + P[row * 4 + 1]) + (P[row * 4 + 2] + P[row * 4 + 3]);
;             __hip_atomic_store(xbuf + ((size_t)(un.pm * BM + row) * 8 + un.pn), __float_as_uint(tot), __ATOMIC_RELAXED, __HIP_MEMORY_SCOPE_AGENT); }
.LBB0_1247:
	s_or_b64 exec, exec, s[0:1]
	s_add_u32 s64, s12, 0x3c640000
	s_addc_u32 s65, s13, 0
	s_lshl_b32 s0, s9, 5
	s_waitcnt lgkmcnt(0)
	s_barrier
	v_and_or_b32 v134, v158, 31, s0
	v_add_u32_e32 v128, s14, v134
	v_cmp_gt_u32_e64 s[0:1], 32, v130
	s_waitcnt lgkmcnt(0)
	v_ashrrev_i32_e32 v129, 31, v128
	s_and_saveexec_b64 s[4:5], s[0:1]
	s_cbranch_execz .LBB0_1249
	v_lshl_add_u32 v131, v134, 4, 0
	ds_read_b128 v[136:139], v131
	v_lshlrev_b64 v[132:133], 5, v[128:129]
	v_lshl_add_u64 v[132:133], s[64:65], 0, v[132:133]
	v_lshl_add_u64 v[132:133], s[2:3], 2, v[132:133]
	s_waitcnt lgkmcnt(0)
	v_mov_b32_e32 v140, v137
	v_mov_b32_e32 v141, v138
	v_mov_b32_e32 v137, v139
	v_pk_add_f32 v[136:137], v[140:141], v[136:137]
	s_nop 0
	v_pk_add_f32 v[136:137], v[136:137], v[136:137] op_sel:[0,1] op_sel_hi:[1,0]
	global_store_dword v[132:133], v136, off sc1

;     __device__ __forceinline__ void fused(f32x4 (&acc)[2][2][4][2], const Unit& un, int wr, int wc, int fr, int fq, PG8_LAS unsigned char* lds, int wid, int lane) const {
;     ...
;             for (;;) {
;                 if ((unsigned)__builtin_amdgcn_readfirstlane(__hip_atomic_load(cnt + 64 * un.pm, __ATOMIC_RELAXED, __HIP_MEMORY_SCOPE_AGENT)) >= 64u) break;
;                 if (__builtin_amdgcn_s_memrealtime() - t0 > 2000000ull) {
;                     if (lane == 0) { unsigned expect = 0u; __hip_atomic_compare_exchange_strong(tmo + 1, &expect, code | (unsigned)(un.pm & 0xff), __ATOMIC_RELAXED, __ATOMIC_RELAXED, __HIP_MEMORY_SCOPE_AGENT);
;                                      __hip_atomic_store(tmo, 1u, __ATOMIC_RELAXED, __HIP_MEMORY_SCOPE_AGENT); }
;                     dead = true; break; }
.LBB0_1261:
	s_or_saveexec_b64 s[66:67], s[4:5]
	s_mov_b64 s[4:5], 0
	s_xor_b64 exec, exec, s[66:67]
	s_cbranch_execz .LBB0_1263
	s_and_b32 s6, s62, 0xef
	s_or_b32 s6, s6, 0x710
	v_mov_b32_e32 v130, s6
	v_mov_b32_e32 v131, 0
	v_mov_b64_e32 v[132:133], s[12:13]
	flat_atomic_cmpswap v[132:133], v[130:131] offset:4
	s_mov_b64 s[4:5], exec
	v_mov_b32_e32 v130, 1
	global_store_dword v[132:133], v130, off sc1

;     __device__ __forceinline__ void fused(f32x4 (&acc)[2][2][4][2], const Unit& un, int wr, int wc, int fr, int fq, PG8_LAS unsigned char* lds, int wid, int lane) const {
;     ...
;         asm volatile("s_waitcnt vmcnt(0) lgkmcnt(0)" ::: "memory"); __builtin_amdgcn_s_barrier(); asm volatile("" ::: "memory");
;         const bool bad = flag[0] != 0u;
;         if (lane < 32) { const unsigned* slot = xbuf + (size_t)(un.pm * BM + row) * 8; float q = 0.f;
; #pragma unroll
;             for (int t = 0; t < 8; ++t) q += __uint_as_float(__hip_atomic_load(slot + t, __ATOMIC_RELAXED, __HIP_MEMORY_SCOPE_AGENT));
;             S[row] = 1.0f / sqrtf(q * (1.0f / 2048.0f) + eps); }
;         asm volatile("s_waitcnt lgkmcnt(0)" ::: "memory"); __builtin_amdgcn_s_barrier(); asm volatile("" ::: "memory");
;         const float qnan = __builtin_nanf("");
;         f32x4 cg[2][2], sh[2][2];
; #pragma unroll
;         for (int bj = 0; bj < 2; ++bj)
; #pragma unroll
;             for (int n = 0; n < 2; ++n) { const f32x4 g4 = *(const f32x4*)(gain + col0 + bj * HALF + n * 4);
;                 if (MODE == 0) { const f32x4 sc4 = *(const f32x4*)(scale + boff + bj * HALF + n * 4); cg[bj][n] = g4 * (sc4 + 1.0f); sh[bj][n] = *(const f32x4*)(shift + boff + bj * HALF + n * 4); }
;                 else { cg[bj][n] = g4; sh[bj][n] = (f32x4){0.f, 0.f, 0.f, 0.f}; } }
; #pragma unroll
;         for (int ai = 0; ai < 2; ++ai)
; #pragma unroll
;             for (int m = 0; m < 4; ++m) { const int r = ai * HALF + wr * 64 + m * 16 + fr; const float rs = S[r]; const size_t off = (size_t)(un.pm * BM + r) * ldc + col0;
; #pragma unroll
;                 for (int bj = 0; bj < 2; ++bj) { f32x4 y0 = (acc[ai][bj][m][0] * rs) * cg[bj][0] + sh[bj][0], y1 = (acc[ai][bj][m][1] * rs) * cg[bj][1] + sh[bj][1];
.LBB0_1269:
	s_waitcnt vmcnt(0) lgkmcnt(0)
	s_barrier
	v_mov_b32_e32 v130, 0
	ds_read_b32 v158, v130 offset:5120
	s_and_saveexec_b64 s[2:3], s[0:1]
	s_cbranch_execz .LBB0_1271
	v_lshlrev_b64 v[128:129], 5, v[128:129]
	v_lshl_add_u64 v[128:129], s[64:65], 0, v[128:129]
	global_load_dword v130, v[128:129], off sc1
	global_load_dword v131, v[128:129], off offset:4 sc1
	global_load_dword v132, v[128:129], off offset:8 sc1
	global_load_dword v133, v[128:129], off offset:12 sc1
	global_load_dword v135, v[128:129], off offset:16 sc1
	global_load_dword v136, v[128:129], off offset:20 sc1
	global_load_dword v137, v[128:129], off offset:24 sc1
	s_nop 0
	global_load_dword v128, v[128:129], off offset:28 sc1
	v_mov_b32_e32 v129, 0x358637bd
	s_mov_b32 s0, 0xf800000
	s_waitcnt vmcnt(0) lgkmcnt(0)
	v_add_f32_e32 v130, 0, v130
	v_add_f32_e32 v130, v130, v131
	v_add_f32_e32 v130, v130, v132
	v_add_f32_e32 v130, v130, v133
	v_add_f32_e32 v130, v130, v135
	v_add_f32_e32 v130, v130, v136
	v_add_f32_e32 v130, v130, v137
	v_add_f32_e32 v128, v130, v128
	v_fmac_f32_e32 v129, 0x3a000000, v128
	v_mul_f32_e32 v128, 0x4f800000, v129
	v_cmp_gt_f32_e32 vcc, s0, v129
	v_mov_b32_e32 v130, 0x260
	s_nop 0
	v_cndmask_b32_e32 v128, v129, v128, vcc
	v_sqrt_f32_e32 v129, v128
	s_nop 0
	v_add_u32_e32 v131, -1, v129
	v_add_u32_e32 v132, 1, v129
	v_fma_f32 v133, -v131, v129, v128
	v_fma_f32 v135, -v132, v129, v128
	v_cmp_ge_f32_e64 s[0:1], 0, v133
	s_nop 1
	v_cndmask_b32_e64 v129, v129, v131, s[0:1]
	v_cmp_lt_f32_e64 s[0:1], 0, v135
	s_nop 1
	v_cndmask_b32_e64 v129, v129, v132, s[0:1]
	v_mul_f32_e32 v131, 0x37800000, v129
	v_cndmask_b32_e32 v129, v129, v131, vcc
	v_cmp_class_f32_e32 vcc, v128, v130
	s_nop 1
	v_cndmask_b32_e32 v128, v129, v128, vcc
	v_div_scale_f32 v129, s[0:1], v128, v128, 1.0
	v_rcp_f32_e32 v130, v129
	v_div_scale_f32 v131, vcc, 1.0, v128, 1.0
	v_fma_f32 v132, -v129, v130, 1.0
	v_fmac_f32_e32 v130, v132, v130
	v_mul_f32_e32 v132, v131, v130
	v_fma_f32 v133, -v129, v132, v131
	v_fmac_f32_e32 v132, v133, v130
	v_fma_f32 v129, -v129, v132, v131
	v_div_fmas_f32 v129, v129, v130, v132
	v_div_fixup_f32 v128, v129, v128, 1.0
	v_lshl_add_u32 v129, v134, 2, 0
	ds_write_b32 v129, v128 offset:4096
.LBB0_1271:
	s_or_b64 exec, exec, s[2:3]
	v_readlane_b32 s36, v254, 11
	v_readlane_b32 s40, v254, 15
	v_readlane_b32 s41, v254, 16
	s_mov_b64 s[0:1], 0x2000
	s_waitcnt lgkmcnt(0)
	s_barrier
	v_lshl_add_u64 v[128:129], v[152:153], 2, s[40:41]
	v_lshl_add_u64 v[130:131], v[128:129], 0, s[0:1]
	s_mov_b64 s[0:1], 0x132000
	v_lshl_add_u64 v[136:137], v[150:151], 0, s[0:1]
	s_mov_b64 s[0:1], 0x130000
	v_lshl_add_u64 v[138:139], v[150:151], 0, s[0:1]
	s_movk_i32 s0, 0x2000
	v_add_co_u32_e32 v128, vcc, s0, v128
	s_mov_b32 s0, 0x132000
	s_nop 0
	v_addc_co_u32_e32 v129, vcc, 0, v129, vcc
	global_load_dwordx4 v[160:163], v[128:129], off
	global_load_dwordx4 v[152:155], v[136:137], off offset:16
	v_add_co_u32_e32 v128, vcc, s0, v150
	global_load_dwordx4 v[164:167], v[136:137], off offset:512
	global_load_dwordx4 v[132:135], v[138:139], off offset:16
	global_load_dwordx4 v[168:171], v[136:137], off offset:528
	global_load_dwordx4 v[172:175], v[130:131], off offset:16
	global_load_dwordx4 v[176:179], v[130:131], off offset:512
	v_addc_co_u32_e32 v129, vcc, 0, v151, vcc
	global_load_dwordx4 v[180:183], v[130:131], off offset:528
	global_load_dwordx4 v[184:187], v[128:129], off
	s_mov_b32 s0, 0x130000
	v_add_co_u32_e32 v128, vcc, s0, v150
	v_lshl_add_u32 v157, v144, 2, 0
	s_nop 0
	v_addc_co_u32_e32 v129, vcc, 0, v151, vcc
	global_load_dwordx4 v[140:143], v[128:129], off
	s_nop 0
	global_load_dwordx4 v[128:131], v[138:139], off offset:512
	s_nop 0
	global_load_dwordx4 v[136:139], v[138:139], off offset:528
	ds_read_b32 v188, v157 offset:4096
	v_add_u32_e32 v144, s14, v144
	s_add_u32 s0, s12, 0x1e600000
	v_ashrrev_i32_e32 v145, 31, v144
	s_addc_u32 s1, s13, 0
	v_lshlrev_b64 v[146:147], 12, v[144:145]
	s_waitcnt lgkmcnt(0)
	v_pk_mul_f32 v[192:193], v[8:9], v[188:189] op_sel_hi:[1,0]
	v_pk_mul_f32 v[194:195], v[10:11], v[188:189] op_sel_hi:[1,0]
	v_lshl_add_u64 v[190:191], s[0:1], 0, v[146:147]
	v_pk_mul_f32 v[196:197], v[12:13], v[188:189] op_sel_hi:[1,0]
	v_pk_mul_f32 v[198:199], v[14:15], v[188:189] op_sel_hi:[1,0]
	v_mov_b32_e32 v156, 0x7fc00000
	v_cmp_eq_u32_e32 vcc, 0, v158
	v_pk_mul_f32 v[28:29], v[28:29], v[188:189] op_sel_hi:[1,0]
	v_pk_mul_f32 v[30:31], v[30:31], v[188:189] op_sel_hi:[1,0]
	v_pk_mul_f32 v[32:33], v[32:33], v[188:189] op_sel_hi:[1,0]
	v_pk_mul_f32 v[34:35], v[34:35], v[188:189] op_sel_hi:[1,0]
	v_readlane_b32 s37, v254, 12
	v_readlane_b32 s38, v254, 13
	v_readlane_b32 s39, v254, 14
	v_readlane_b32 s42, v254, 17
	v_readlane_b32 s43, v254, 18
	v_readlane_b32 s44, v254, 19
	v_readlane_b32 s45, v254, 20
	v_readlane_b32 s46, v254, 21
	v_readlane_b32 s47, v254, 22
	v_readlane_b32 s48, v254, 23
	v_readlane_b32 s49, v254, 24
	v_readlane_b32 s50, v254, 25
	v_readlane_b32 s51, v254, 26
	s_waitcnt vmcnt(0)
; __device__ __forceinline__ unsigned cvt_pk_bf16(float lo, float hi) { unsigned r; asm volatile("v_cvt_pk_bf16_f32 %0, %1, %2" : "=v"(r) : "v"(lo), "v"(hi)); return r; }
;     __device__ __forceinline__ void fused(f32x4 (&acc)[2][2][4][2], const Unit& un, int wr, int wc, int fr, int fq, PG8_LAS unsigned char* lds, int wid, int lane) const {
;     ...
;             for (int n = 0; n < 2; ++n) { const f32x4 g4 = *(const f32x4*)(gain + col0 + bj * HALF + n * 4);
;                 if (MODE == 0) { const f32x4 sc4 = *(const f32x4*)(scale + boff + bj * HALF + n * 4); cg[bj][n] = g4 * (sc4 + 1.0f); sh[bj][n] = *(const f32x4*)(shift + boff + bj * HALF + n * 4); }
;                 else { cg[bj][n] = g4; sh[bj][n] = (f32x4){0.f, 0.f, 0.f, 0.f}; } }
; #pragma unroll
;         for (int ai = 0; ai < 2; ++ai)
; #pragma unroll
;             for (int m = 0; m < 4; ++m) { const int r = ai * HALF + wr * 64 + m * 16 + fr; const float rs = S[r]; const size_t off = (size_t)(un.pm * BM + r) * ldc + col0;
; #pragma unroll
;                 for (int bj = 0; bj < 2; ++bj) { f32x4 y0 = (acc[ai][bj][m][0] * rs) * cg[bj][0] + sh[bj][0], y1 = (acc[ai][bj][m][1] * rs) * cg[bj][1] + sh[bj][1];
;                     if (bad) { y0 = (f32x4){qnan, qnan, qnan, qnan}; y1 = y0; }
;                     if (MODE == 0) { u32x4 w; w.x = cvt_pk_bf16(y0[0], y0[1]); w.y = cvt_pk_bf16(y0[2], y0[3]); w.z = cvt_pk_bf16(y1[0], y1[1]); w.w = cvt_pk_bf16(y1[2], y1[3]); *(u32x4*)(u + off + bj * HALF) = w; }
	v_pk_add_f32 v[12:13], v[166:167], 1.0 op_sel_hi:[1,0]
	v_pk_add_f32 v[8:9], v[154:155], 1.0 op_sel_hi:[1,0]
	v_pk_add_f32 v[10:11], v[152:153], 1.0 op_sel_hi:[1,0]
	v_pk_add_f32 v[152:153], v[170:171], 1.0 op_sel_hi:[1,0]
	v_pk_add_f32 v[154:155], v[168:169], 1.0 op_sel_hi:[1,0]
	v_pk_mul_f32 v[146:147], v[174:175], v[8:9]
	v_pk_mul_f32 v[150:151], v[172:173], v[10:11]
	v_pk_mul_f32 v[8:9], v[182:183], v[152:153]
	v_pk_mul_f32 v[10:11], v[180:181], v[154:155]
	v_pk_add_f32 v[152:153], v[186:187], 1.0 op_sel_hi:[1,0]
	v_pk_add_f32 v[154:155], v[184:185], 1.0 op_sel_hi:[1,0]
	v_pk_mul_f32 v[152:153], v[162:163], v[152:153]
	v_pk_mul_f32 v[154:155], v[160:161], v[154:155]
	v_pk_add_f32 v[14:15], v[164:165], 1.0 op_sel_hi:[1,0]
	v_pk_fma_f32 v[164:165], v[146:147], v[198:199], v[134:135]
	v_pk_fma_f32 v[166:167], v[150:151], v[196:197], v[132:133]
	v_pk_fma_f32 v[160:161], v[152:153], v[194:195], v[142:143]
	v_pk_fma_f32 v[162:163], v[154:155], v[192:193], v[140:141]
	v_pk_mul_f32 v[12:13], v[178:179], v[12:13]
	v_pk_mul_f32 v[14:15], v[176:177], v[14:15]
	v_cndmask_b32_e32 v145, v156, v160, vcc
	v_cndmask_b32_e32 v159, v156, v161, vcc
	v_cndmask_b32_e32 v158, v156, v162, vcc
	v_cndmask_b32_e32 v160, v156, v163, vcc
	v_cndmask_b32_e32 v161, v156, v164, vcc
	v_cndmask_b32_e32 v162, v156, v165, vcc
	v_cndmask_b32_e32 v163, v156, v166, vcc
	v_pk_fma_f32 v[30:31], v[8:9], v[30:31], v[138:139]
	v_pk_fma_f32 v[28:29], v[10:11], v[28:29], v[136:137]
	v_cndmask_b32_e32 v164, v156, v167, vcc
	v_cvt_pk_bf16_f32 v158, v158, v160
	v_cvt_pk_bf16_f32 v159, v145, v159
	v_cvt_pk_bf16_f32 v160, v163, v164
	v_cvt_pk_bf16_f32 v161, v161, v162
	v_lshl_add_u64 v[162:163], v[190:191], 0, v[148:149]
	v_pk_fma_f32 v[34:35], v[12:13], v[34:35], v[130:131]
	v_pk_fma_f32 v[32:33], v[14:15], v[32:33], v[128:129]
	v_cndmask_b32_e32 v145, v156, v30, vcc
	v_cndmask_b32_e32 v31, v156, v31, vcc
	v_cndmask_b32_e32 v30, v156, v28, vcc
	global_store_dwordx4 v[162:163], v[158:161], off
	v_cndmask_b32_e32 v34, v156, v34, vcc
	v_cndmask_b32_e32 v35, v156, v35, vcc
	v_cndmask_b32_e32 v32, v156, v32, vcc
	v_cndmask_b32_e32 v33, v156, v33, vcc
	v_cndmask_b32_e32 v158, v156, v29, vcc
	v_cvt_pk_bf16_f32 v28, v32, v33
	v_cvt_pk_bf16_f32 v29, v34, v35
	v_cvt_pk_bf16_f32 v30, v30, v158
	v_cvt_pk_bf16_f32 v31, v145, v31
	global_store_dwordx4 v[162:163], v[28:31], off offset:256
	ds_read_b32 v28, v157 offset:4160
	s_waitcnt lgkmcnt(0)
	v_pk_mul_f32 v[16:17], v[16:17], v[28:29] op_sel_hi:[1,0]
	v_pk_mul_f32 v[18:19], v[18:19], v[28:29] op_sel_hi:[1,0]
	v_pk_mul_f32 v[20:21], v[20:21], v[28:29] op_sel_hi:[1,0]
	v_add_u32_e32 v30, 16, v144
	v_pk_fma_f32 v[18:19], v[152:153], v[18:19], v[142:143]
	v_pk_fma_f32 v[16:17], v[154:155], v[16:17], v[140:141]
	v_pk_fma_f32 v[20:21], v[150:151], v[20:21], v[132:133]
	v_ashrrev_i32_e32 v31, 31, v30
	v_cndmask_b32_e32 v18, v156, v18, vcc
	v_cndmask_b32_e32 v16, v156, v16, vcc
	v_cndmask_b32_e32 v17, v156, v17, vcc
	v_cndmask_b32_e32 v20, v156, v20, vcc
	v_cndmask_b32_e32 v21, v156, v21, vcc
	v_pk_mul_f32 v[22:23], v[22:23], v[28:29] op_sel_hi:[1,0]
	v_cndmask_b32_e32 v19, v156, v19, vcc
	v_cvt_pk_bf16_f32 v16, v16, v17
	v_cvt_pk_bf16_f32 v17, v18, v19
	v_cvt_pk_bf16_f32 v18, v20, v21
	v_lshlrev_b64 v[20:21], 12, v[30:31]
	v_pk_fma_f32 v[22:23], v[146:147], v[22:23], v[134:135]
	v_lshl_add_u64 v[20:21], s[0:1], 0, v[20:21]
	v_cndmask_b32_e32 v22, v156, v22, vcc
	v_cndmask_b32_e32 v23, v156, v23, vcc
	v_cvt_pk_bf16_f32 v19, v22, v23
	v_lshl_add_u64 v[20:21], v[20:21], 0, v[148:149]
	global_store_dwordx4 v[20:21], v[16:19], off
	v_pk_mul_f32 v[22:23], v[56:57], v[28:29] op_sel_hi:[1,0]
	s_nop 0
	v_pk_mul_f32 v[16:17], v[60:61], v[28:29] op_sel_hi:[1,0]
	v_pk_mul_f32 v[18:19], v[62:63], v[28:29] op_sel_hi:[1,0]
	v_pk_fma_f32 v[16:17], v[14:15], v[16:17], v[128:129]
	v_pk_fma_f32 v[18:19], v[12:13], v[18:19], v[130:131]
	v_pk_mul_f32 v[28:29], v[58:59], v[28:29] op_sel_hi:[1,0]
	v_pk_fma_f32 v[22:23], v[10:11], v[22:23], v[136:137]
	v_pk_fma_f32 v[28:29], v[8:9], v[28:29], v[138:139]
	v_cndmask_b32_e32 v18, v156, v18, vcc
	v_cndmask_b32_e32 v19, v156, v19, vcc
	v_cndmask_b32_e32 v16, v156, v16, vcc
	v_cndmask_b32_e32 v17, v156, v17, vcc
	v_cndmask_b32_e32 v28, v156, v28, vcc
	v_cndmask_b32_e32 v29, v156, v29, vcc
	v_cndmask_b32_e32 v22, v156, v22, vcc
	v_cndmask_b32_e32 v23, v156, v23, vcc
	v_cvt_pk_bf16_f32 v16, v16, v17
	v_cvt_pk_bf16_f32 v17, v18, v19
	v_cvt_pk_bf16_f32 v18, v22, v23
	v_cvt_pk_bf16_f32 v19, v28, v29
	global_store_dwordx4 v[20:21], v[16:19], off offset:256
	ds_read_b32 v20, v157 offset:4224
	v_add_u32_e32 v22, 32, v144
	v_ashrrev_i32_e32 v23, 31, v22
	v_lshlrev_b64 v[22:23], 12, v[22:23]
	v_lshl_add_u64 v[22:23], s[0:1], 0, v[22:23]
	s_waitcnt lgkmcnt(0)
; __device__ __forceinline__ unsigned cvt_pk_bf16(float lo, float hi) { unsigned r; asm volatile("v_cvt_pk_bf16_f32 %0, %1, %2" : "=v"(r) : "v"(lo), "v"(hi)); return r; }
;     __device__ __forceinline__ void fused(f32x4 (&acc)[2][2][4][2], const Unit& un, int wr, int wc, int fr, int fq, PG8_LAS unsigned char* lds, int wid, int lane) const {
;     ...
;         for (int ai = 0; ai < 2; ++ai)
; #pragma unroll
;             for (int m = 0; m < 4; ++m) { const int r = ai * HALF + wr * 64 + m * 16 + fr; const float rs = S[r]; const size_t off = (size_t)(un.pm * BM + r) * ldc + col0;
; #pragma unroll
;                 for (int bj = 0; bj < 2; ++bj) { f32x4 y0 = (acc[ai][bj][m][0] * rs) * cg[bj][0] + sh[bj][0], y1 = (acc[ai][bj][m][1] * rs) * cg[bj][1] + sh[bj][1];
;                     if (bad) { y0 = (f32x4){qnan, qnan, qnan, qnan}; y1 = y0; }
;                     if (MODE == 0) { u32x4 w; w.x = cvt_pk_bf16(y0[0], y0[1]); w.y = cvt_pk_bf16(y0[2], y0[3]); w.z = cvt_pk_bf16(y1[0], y1[1]); w.w = cvt_pk_bf16(y1[2], y1[3]); *(u32x4*)(u + off + bj * HALF) = w; }
	v_pk_mul_f32 v[16:17], v[48:49], v[20:21] op_sel_hi:[1,0]
	v_pk_mul_f32 v[18:19], v[50:51], v[20:21] op_sel_hi:[1,0]
	v_pk_fma_f32 v[16:17], v[154:155], v[16:17], v[140:141]
	v_pk_fma_f32 v[18:19], v[152:153], v[18:19], v[142:143]
	v_pk_mul_f32 v[28:29], v[52:53], v[20:21] op_sel_hi:[1,0]
	v_pk_mul_f32 v[30:31], v[54:55], v[20:21] op_sel_hi:[1,0]
	v_pk_fma_f32 v[28:29], v[150:151], v[28:29], v[132:133]
	v_pk_fma_f32 v[30:31], v[146:147], v[30:31], v[134:135]
	v_cndmask_b32_e32 v18, v156, v18, vcc
	v_cndmask_b32_e32 v19, v156, v19, vcc
	v_cndmask_b32_e32 v16, v156, v16, vcc
	v_cndmask_b32_e32 v17, v156, v17, vcc
	v_cndmask_b32_e32 v21, v156, v30, vcc
	v_cndmask_b32_e32 v30, v156, v31, vcc
	v_cndmask_b32_e32 v28, v156, v28, vcc
	v_cndmask_b32_e32 v29, v156, v29, vcc
	v_cvt_pk_bf16_f32 v16, v16, v17
	v_cvt_pk_bf16_f32 v17, v18, v19
	v_cvt_pk_bf16_f32 v18, v28, v29
	v_cvt_pk_bf16_f32 v19, v21, v30
	v_lshl_add_u64 v[22:23], v[22:23], 0, v[148:149]
	global_store_dwordx4 v[22:23], v[16:19], off
	v_pk_mul_f32 v[28:29], v[72:73], v[20:21] op_sel_hi:[1,0]
	s_nop 0
	v_pk_mul_f32 v[16:17], v[76:77], v[20:21] op_sel_hi:[1,0]
	v_pk_mul_f32 v[18:19], v[78:79], v[20:21] op_sel_hi:[1,0]
	v_pk_fma_f32 v[16:17], v[14:15], v[16:17], v[128:129]
	v_pk_fma_f32 v[18:19], v[12:13], v[18:19], v[130:131]
	v_pk_mul_f32 v[20:21], v[74:75], v[20:21] op_sel_hi:[1,0]
	v_pk_fma_f32 v[28:29], v[10:11], v[28:29], v[136:137]
	v_pk_fma_f32 v[20:21], v[8:9], v[20:21], v[138:139]
	v_cndmask_b32_e32 v18, v156, v18, vcc
	v_cndmask_b32_e32 v19, v156, v19, vcc
	v_cndmask_b32_e32 v16, v156, v16, vcc
	v_cndmask_b32_e32 v17, v156, v17, vcc
	v_cndmask_b32_e32 v20, v156, v20, vcc
	v_cndmask_b32_e32 v21, v156, v21, vcc
	v_cndmask_b32_e32 v28, v156, v28, vcc
	v_cndmask_b32_e32 v29, v156, v29, vcc
	v_cvt_pk_bf16_f32 v16, v16, v17
	v_cvt_pk_bf16_f32 v17, v18, v19
	v_cvt_pk_bf16_f32 v18, v28, v29
	v_cvt_pk_bf16_f32 v19, v20, v21
	global_store_dwordx4 v[22:23], v[16:19], off offset:256
	ds_read_b32 v20, v157 offset:4288
	v_add_u32_e32 v22, 48, v144
	v_ashrrev_i32_e32 v23, 31, v22
	v_lshlrev_b64 v[22:23], 12, v[22:23]
	v_lshl_add_u64 v[22:23], s[0:1], 0, v[22:23]
	s_waitcnt lgkmcnt(0)
	v_pk_mul_f32 v[16:17], v[64:65], v[20:21] op_sel_hi:[1,0]
	v_pk_mul_f32 v[18:19], v[66:67], v[20:21] op_sel_hi:[1,0]
	v_pk_fma_f32 v[16:17], v[154:155], v[16:17], v[140:141]
	v_pk_fma_f32 v[18:19], v[152:153], v[18:19], v[142:143]
	v_pk_mul_f32 v[28:29], v[68:69], v[20:21] op_sel_hi:[1,0]
	v_pk_mul_f32 v[30:31], v[70:71], v[20:21] op_sel_hi:[1,0]
	v_pk_fma_f32 v[28:29], v[150:151], v[28:29], v[132:133]
	v_pk_fma_f32 v[30:31], v[146:147], v[30:31], v[134:135]
	v_cndmask_b32_e32 v18, v156, v18, vcc
	v_cndmask_b32_e32 v19, v156, v19, vcc
	v_cndmask_b32_e32 v16, v156, v16, vcc
	v_cndmask_b32_e32 v17, v156, v17, vcc
	v_cndmask_b32_e32 v21, v156, v30, vcc
	v_cndmask_b32_e32 v30, v156, v31, vcc
	v_cndmask_b32_e32 v28, v156, v28, vcc
	v_cndmask_b32_e32 v29, v156, v29, vcc
	v_cvt_pk_bf16_f32 v16, v16, v17
	v_cvt_pk_bf16_f32 v17, v18, v19
	v_cvt_pk_bf16_f32 v18, v28, v29
	v_cvt_pk_bf16_f32 v19, v21, v30
	v_lshl_add_u64 v[22:23], v[22:23], 0, v[148:149]
	global_store_dwordx4 v[22:23], v[16:19], off
	v_pk_mul_f32 v[28:29], v[96:97], v[20:21] op_sel_hi:[1,0]
	s_nop 0
	v_pk_mul_f32 v[16:17], v[108:109], v[20:21] op_sel_hi:[1,0]
	v_pk_mul_f32 v[18:19], v[110:111], v[20:21] op_sel_hi:[1,0]
	v_pk_fma_f32 v[16:17], v[14:15], v[16:17], v[128:129]
	v_pk_fma_f32 v[18:19], v[12:13], v[18:19], v[130:131]
	v_pk_mul_f32 v[20:21], v[98:99], v[20:21] op_sel_hi:[1,0]
	v_pk_fma_f32 v[28:29], v[10:11], v[28:29], v[136:137]
	v_pk_fma_f32 v[20:21], v[8:9], v[20:21], v[138:139]
	v_cndmask_b32_e32 v18, v156, v18, vcc
	v_cndmask_b32_e32 v19, v156, v19, vcc
	v_cndmask_b32_e32 v16, v156, v16, vcc
	v_cndmask_b32_e32 v17, v156, v17, vcc
	v_cndmask_b32_e32 v20, v156, v20, vcc
	v_cndmask_b32_e32 v21, v156, v21, vcc
	v_cndmask_b32_e32 v28, v156, v28, vcc
	v_cndmask_b32_e32 v29, v156, v29, vcc
	v_cvt_pk_bf16_f32 v16, v16, v17
	v_cvt_pk_bf16_f32 v17, v18, v19
	v_cvt_pk_bf16_f32 v18, v28, v29
	v_cvt_pk_bf16_f32 v19, v20, v21
	global_store_dwordx4 v[22:23], v[16:19], off offset:256
	ds_read_b32 v20, v157 offset:4608
	v_add_u32_e32 v22, 0x80, v144
	v_ashrrev_i32_e32 v23, 31, v22
	v_lshlrev_b64 v[22:23], 12, v[22:23]
	v_lshl_add_u64 v[22:23], s[0:1], 0, v[22:23]
	s_waitcnt lgkmcnt(0)
	v_pk_mul_f32 v[16:17], v[100:101], v[20:21] op_sel_hi:[1,0]
	v_pk_mul_f32 v[18:19], v[102:103], v[20:21] op_sel_hi:[1,0]
	v_pk_fma_f32 v[16:17], v[154:155], v[16:17], v[140:141]
	v_pk_fma_f32 v[18:19], v[152:153], v[18:19], v[142:143]
	v_pk_mul_f32 v[28:29], v[104:105], v[20:21] op_sel_hi:[1,0]
	v_pk_mul_f32 v[30:31], v[106:107], v[20:21] op_sel_hi:[1,0]
	v_pk_fma_f32 v[28:29], v[150:151], v[28:29], v[132:133]
	v_pk_fma_f32 v[30:31], v[146:147], v[30:31], v[134:135]
	v_cndmask_b32_e32 v18, v156, v18, vcc
	v_cndmask_b32_e32 v19, v156, v19, vcc
	v_cndmask_b32_e32 v16, v156, v16, vcc
	v_cndmask_b32_e32 v17, v156, v17, vcc
	v_cndmask_b32_e32 v21, v156, v30, vcc
	v_cndmask_b32_e32 v30, v156, v31, vcc
	v_cndmask_b32_e32 v28, v156, v28, vcc
	v_cndmask_b32_e32 v29, v156, v29, vcc
	v_cvt_pk_bf16_f32 v16, v16, v17
	v_cvt_pk_bf16_f32 v17, v18, v19
	v_cvt_pk_bf16_f32 v18, v28, v29
	v_cvt_pk_bf16_f32 v19, v21, v30
	v_lshl_add_u64 v[22:23], v[22:23], 0, v[148:149]
	global_store_dwordx4 v[22:23], v[16:19], off
	v_pk_mul_f32 v[28:29], v[112:113], v[20:21] op_sel_hi:[1,0]
	s_nop 0
	v_pk_mul_f32 v[16:17], v[124:125], v[20:21] op_sel_hi:[1,0]
	v_pk_mul_f32 v[18:19], v[126:127], v[20:21] op_sel_hi:[1,0]
	v_pk_fma_f32 v[16:17], v[14:15], v[16:17], v[128:129]
	v_pk_fma_f32 v[18:19], v[12:13], v[18:19], v[130:131]
	v_pk_mul_f32 v[20:21], v[114:115], v[20:21] op_sel_hi:[1,0]
	v_pk_fma_f32 v[28:29], v[10:11], v[28:29], v[136:137]
	v_pk_fma_f32 v[20:21], v[8:9], v[20:21], v[138:139]
	v_cndmask_b32_e32 v18, v156, v18, vcc
	v_cndmask_b32_e32 v19, v156, v19, vcc
	v_cndmask_b32_e32 v16, v156, v16, vcc
	v_cndmask_b32_e32 v17, v156, v17, vcc
	v_cndmask_b32_e32 v20, v156, v20, vcc
	v_cndmask_b32_e32 v21, v156, v21, vcc
	v_cndmask_b32_e32 v28, v156, v28, vcc
	v_cndmask_b32_e32 v29, v156, v29, vcc
	v_cvt_pk_bf16_f32 v16, v16, v17
	v_cvt_pk_bf16_f32 v17, v18, v19
	v_cvt_pk_bf16_f32 v18, v28, v29
	v_cvt_pk_bf16_f32 v19, v20, v21
	global_store_dwordx4 v[22:23], v[16:19], off offset:256
	ds_read_b32 v20, v157 offset:4672
	v_add_u32_e32 v22, 0x90, v144
	v_ashrrev_i32_e32 v23, 31, v22
	v_lshlrev_b64 v[22:23], 12, v[22:23]
	v_lshl_add_u64 v[22:23], s[0:1], 0, v[22:23]
	s_waitcnt lgkmcnt(0)
; __device__ __forceinline__ unsigned cvt_pk_bf16(float lo, float hi) { unsigned r; asm volatile("v_cvt_pk_bf16_f32 %0, %1, %2" : "=v"(r) : "v"(lo), "v"(hi)); return r; }
;     __device__ __forceinline__ void fused(f32x4 (&acc)[2][2][4][2], const Unit& un, int wr, int wc, int fr, int fq, PG8_LAS unsigned char* lds, int wid, int lane) const {
;     ...
;         for (int ai = 0; ai < 2; ++ai)
; #pragma unroll
;             for (int m = 0; m < 4; ++m) { const int r = ai * HALF + wr * 64 + m * 16 + fr; const float rs = S[r]; const size_t off = (size_t)(un.pm * BM + r) * ldc + col0;
; #pragma unroll
;                 for (int bj = 0; bj < 2; ++bj) { f32x4 y0 = (acc[ai][bj][m][0] * rs) * cg[bj][0] + sh[bj][0], y1 = (acc[ai][bj][m][1] * rs) * cg[bj][1] + sh[bj][1];
;                     if (bad) { y0 = (f32x4){qnan, qnan, qnan, qnan}; y1 = y0; }
;                     if (MODE == 0) { u32x4 w; w.x = cvt_pk_bf16(y0[0], y0[1]); w.y = cvt_pk_bf16(y0[2], y0[3]); w.z = cvt_pk_bf16(y1[0], y1[1]); w.w = cvt_pk_bf16(y1[2], y1[3]); *(u32x4*)(u + off + bj * HALF) = w; }
	v_pk_mul_f32 v[16:17], v[116:117], v[20:21] op_sel_hi:[1,0]
	v_pk_mul_f32 v[18:19], v[118:119], v[20:21] op_sel_hi:[1,0]
	v_pk_fma_f32 v[16:17], v[154:155], v[16:17], v[140:141]
	v_pk_fma_f32 v[18:19], v[152:153], v[18:19], v[142:143]
	v_pk_mul_f32 v[28:29], v[120:121], v[20:21] op_sel_hi:[1,0]
	v_pk_mul_f32 v[30:31], v[122:123], v[20:21] op_sel_hi:[1,0]
	v_pk_fma_f32 v[28:29], v[150:151], v[28:29], v[132:133]
	v_pk_fma_f32 v[30:31], v[146:147], v[30:31], v[134:135]
	v_cndmask_b32_e32 v18, v156, v18, vcc
	v_cndmask_b32_e32 v19, v156, v19, vcc
	v_cndmask_b32_e32 v16, v156, v16, vcc
	v_cndmask_b32_e32 v17, v156, v17, vcc
	v_cndmask_b32_e32 v21, v156, v30, vcc
	v_cndmask_b32_e32 v30, v156, v31, vcc
	v_cndmask_b32_e32 v28, v156, v28, vcc
	v_cndmask_b32_e32 v29, v156, v29, vcc
	v_cvt_pk_bf16_f32 v16, v16, v17
	v_cvt_pk_bf16_f32 v17, v18, v19
	v_cvt_pk_bf16_f32 v18, v28, v29
	v_cvt_pk_bf16_f32 v19, v21, v30
	v_lshl_add_u64 v[22:23], v[22:23], 0, v[148:149]
	global_store_dwordx4 v[22:23], v[16:19], off
	v_pk_mul_f32 v[28:29], v[88:89], v[20:21] op_sel_hi:[1,0]
	s_nop 0
	v_pk_mul_f32 v[16:17], v[92:93], v[20:21] op_sel_hi:[1,0]
	v_pk_mul_f32 v[18:19], v[94:95], v[20:21] op_sel_hi:[1,0]
	v_pk_fma_f32 v[16:17], v[14:15], v[16:17], v[128:129]
	v_pk_fma_f32 v[18:19], v[12:13], v[18:19], v[130:131]
	v_pk_mul_f32 v[20:21], v[90:91], v[20:21] op_sel_hi:[1,0]
	v_pk_fma_f32 v[28:29], v[10:11], v[28:29], v[136:137]
	v_pk_fma_f32 v[20:21], v[8:9], v[20:21], v[138:139]
	v_cndmask_b32_e32 v18, v156, v18, vcc
	v_cndmask_b32_e32 v19, v156, v19, vcc
	v_cndmask_b32_e32 v16, v156, v16, vcc
	v_cndmask_b32_e32 v17, v156, v17, vcc
	v_cndmask_b32_e32 v20, v156, v20, vcc
	v_cndmask_b32_e32 v21, v156, v21, vcc
	v_cndmask_b32_e32 v28, v156, v28, vcc
	v_cndmask_b32_e32 v29, v156, v29, vcc
	v_cvt_pk_bf16_f32 v16, v16, v17
	v_cvt_pk_bf16_f32 v17, v18, v19
	v_cvt_pk_bf16_f32 v18, v28, v29
	v_cvt_pk_bf16_f32 v19, v20, v21
	global_store_dwordx4 v[22:23], v[16:19], off offset:256
	ds_read_b32 v20, v157 offset:4736
	v_add_u32_e32 v22, 0xa0, v144
	v_ashrrev_i32_e32 v23, 31, v22
	v_lshlrev_b64 v[22:23], 12, v[22:23]
	v_lshl_add_u64 v[22:23], s[0:1], 0, v[22:23]
	s_waitcnt lgkmcnt(0)
	v_pk_mul_f32 v[16:17], v[84:85], v[20:21] op_sel_hi:[1,0]
	v_pk_mul_f32 v[18:19], v[86:87], v[20:21] op_sel_hi:[1,0]
	v_pk_fma_f32 v[16:17], v[154:155], v[16:17], v[140:141]
	v_pk_fma_f32 v[18:19], v[152:153], v[18:19], v[142:143]
	v_pk_mul_f32 v[28:29], v[80:81], v[20:21] op_sel_hi:[1,0]
	v_pk_mul_f32 v[30:31], v[82:83], v[20:21] op_sel_hi:[1,0]
	v_pk_fma_f32 v[28:29], v[150:151], v[28:29], v[132:133]
	v_pk_fma_f32 v[30:31], v[146:147], v[30:31], v[134:135]
	v_cndmask_b32_e32 v18, v156, v18, vcc
	v_cndmask_b32_e32 v19, v156, v19, vcc
	v_cndmask_b32_e32 v16, v156, v16, vcc
	v_cndmask_b32_e32 v17, v156, v17, vcc
	v_cndmask_b32_e32 v21, v156, v30, vcc
	v_cndmask_b32_e32 v30, v156, v31, vcc
	v_cndmask_b32_e32 v28, v156, v28, vcc
	v_cndmask_b32_e32 v29, v156, v29, vcc
	v_cvt_pk_bf16_f32 v16, v16, v17
	v_cvt_pk_bf16_f32 v17, v18, v19
	v_cvt_pk_bf16_f32 v18, v28, v29
	v_cvt_pk_bf16_f32 v19, v21, v30
	v_lshl_add_u64 v[22:23], v[22:23], 0, v[148:149]
	global_store_dwordx4 v[22:23], v[16:19], off
	v_pk_mul_f32 v[28:29], v[40:41], v[20:21] op_sel_hi:[1,0]
	s_nop 0
	v_pk_mul_f32 v[16:17], v[44:45], v[20:21] op_sel_hi:[1,0]
	v_pk_mul_f32 v[18:19], v[46:47], v[20:21] op_sel_hi:[1,0]
	v_pk_fma_f32 v[16:17], v[14:15], v[16:17], v[128:129]
	v_pk_fma_f32 v[18:19], v[12:13], v[18:19], v[130:131]
	v_pk_mul_f32 v[20:21], v[42:43], v[20:21] op_sel_hi:[1,0]
	v_pk_fma_f32 v[28:29], v[10:11], v[28:29], v[136:137]
	v_pk_fma_f32 v[20:21], v[8:9], v[20:21], v[138:139]
	v_cndmask_b32_e32 v18, v156, v18, vcc
	v_cndmask_b32_e32 v19, v156, v19, vcc
	v_cndmask_b32_e32 v16, v156, v16, vcc
	v_cndmask_b32_e32 v17, v156, v17, vcc
	v_cndmask_b32_e32 v20, v156, v20, vcc
	v_cndmask_b32_e32 v21, v156, v21, vcc
	v_cndmask_b32_e32 v28, v156, v28, vcc
	v_cndmask_b32_e32 v29, v156, v29, vcc
	v_cvt_pk_bf16_f32 v16, v16, v17
	v_cvt_pk_bf16_f32 v17, v18, v19
	v_cvt_pk_bf16_f32 v18, v28, v29
	v_cvt_pk_bf16_f32 v19, v20, v21
	global_store_dwordx4 v[22:23], v[16:19], off offset:256
	ds_read_b32 v20, v157 offset:4800
	v_add_u32_e32 v22, 0xb0, v144
	v_ashrrev_i32_e32 v23, 31, v22
	v_lshlrev_b64 v[22:23], 12, v[22:23]
	v_lshl_add_u64 v[22:23], s[0:1], 0, v[22:23]
	s_waitcnt lgkmcnt(0)
	v_pk_mul_f32 v[26:27], v[26:27], v[20:21] op_sel_hi:[1,0]
	v_pk_mul_f32 v[16:17], v[36:37], v[20:21] op_sel_hi:[1,0]
	v_pk_fma_f32 v[26:27], v[146:147], v[26:27], v[134:135]
	v_pk_mul_f32 v[18:19], v[38:39], v[20:21] op_sel_hi:[1,0]
	v_pk_mul_f32 v[24:25], v[24:25], v[20:21] op_sel_hi:[1,0]
	v_cndmask_b32_e32 v21, v156, v26, vcc
	v_pk_mul_f32 v[0:1], v[0:1], v[20:21] op_sel_hi:[1,0]
	v_pk_mul_f32 v[2:3], v[2:3], v[20:21] op_sel_hi:[1,0]
	v_pk_fma_f32 v[18:19], v[152:153], v[18:19], v[142:143]
	v_pk_fma_f32 v[16:17], v[154:155], v[16:17], v[140:141]
	v_pk_mul_f32 v[4:5], v[4:5], v[20:21] op_sel_hi:[1,0]
	v_pk_mul_f32 v[6:7], v[6:7], v[20:21] op_sel_hi:[1,0]
	v_pk_fma_f32 v[2:3], v[8:9], v[2:3], v[138:139]
	v_pk_fma_f32 v[0:1], v[10:11], v[0:1], v[136:137]
	v_pk_fma_f32 v[24:25], v[150:151], v[24:25], v[132:133]
	v_cndmask_b32_e32 v18, v156, v18, vcc
	v_cndmask_b32_e32 v19, v156, v19, vcc
	v_cndmask_b32_e32 v16, v156, v16, vcc
	v_cndmask_b32_e32 v17, v156, v17, vcc
	v_lshl_add_u64 v[22:23], v[22:23], 0, v[148:149]
	v_pk_fma_f32 v[6:7], v[12:13], v[6:7], v[130:131]
	v_pk_fma_f32 v[4:5], v[14:15], v[4:5], v[128:129]
	v_cndmask_b32_e32 v8, v156, v2, vcc
	v_cndmask_b32_e32 v3, v156, v3, vcc
	v_cndmask_b32_e32 v2, v156, v0, vcc
	v_cndmask_b32_e32 v26, v156, v27, vcc
	v_cndmask_b32_e32 v24, v156, v24, vcc
	v_cndmask_b32_e32 v25, v156, v25, vcc
	v_cvt_pk_bf16_f32 v16, v16, v17
	v_cvt_pk_bf16_f32 v17, v18, v19
	v_cvt_pk_bf16_f32 v18, v24, v25
	v_cvt_pk_bf16_f32 v19, v21, v26
	global_store_dwordx4 v[22:23], v[16:19], off
	v_cndmask_b32_e32 v6, v156, v6, vcc
	v_cndmask_b32_e32 v7, v156, v7, vcc
	v_cndmask_b32_e32 v4, v156, v4, vcc
	v_cndmask_b32_e32 v5, v156, v5, vcc
	v_cndmask_b32_e32 v9, v156, v1, vcc
	v_cvt_pk_bf16_f32 v0, v4, v5
	v_cvt_pk_bf16_f32 v1, v6, v7
	v_cvt_pk_bf16_f32 v2, v2, v9
	v_cvt_pk_bf16_f32 v3, v8, v3
	global_store_dwordx4 v[22:23], v[0:3], off offset:256

;     __device__ __forceinline__ void operator()(const f32x4 (&acc)[2][2][4][2], const Unit& u, int wr, int wc, int fr, int fq) const {
;         const int row0 = u.pm * BM + wr * 64 + fr; const int col0 = u.pn * BM + wc * 32 + 8 * fq;
;         const bool do_rope = (ACT == 2) && (((u.pn * BM) % 6144) < 4096);
;         float rinv[2][2];
;         if (ACT == 2) {
; #pragma unroll
;             for (int n = 0; n < 2; ++n)
; #pragma unroll
;                 for (int e = 0; e < 2; ++e) rinv[n][e] = exp2f(-(float)(16 * wc + 4 * fq + 2 * n + e) * (13.287712379549449f / 64.0f)) * 0.15915494309189535f;
;         }
;         float rinv3[2][4]; bool rope3[2];
;         if (ACT == 3) {
; #pragma unroll
;             for (int bj = 0; bj < 2; ++bj) { const int jj = (col0 + bj * HALF) % 192; rope3[bj] = jj >= 128; const int i0 = (jj - 128) >> 1;
; #pragma unroll
;                 for (int p = 0; p < 4; ++p) rinv3[bj][p] = exp2f(-(float)(i0 + p) * (13.287712379549449f / 32.0f)) * 0.15915494309189535f; }
;         }
; #pragma unroll
;         for (int ai = 0; ai < 2; ++ai)
; #pragma unroll
;             for (int m = 0; m < 4; ++m) { bf16_t* rowp = O + (size_t)(row0 + ai * HALF + m * 16) * ldc + col0;
;                 if (ACT == 1) {
;                     const int ob = fr * 64 + 16 * fq, sw = ob ^ (((ob >> 9) & 1) << 5);
;                     rowp = O + ((size_t)(u.pm * (ldc / 64) + u.pn * 4 + (wc >> 1)) * 2 + ai) * 8192 + (((wr * 4 + m) * 2 + (wc & 1)) * 1024 + sw) / 2; }
;                 float rc[2][2], rs[2][2];
;                 if (ACT == 2) { const float pos = (float)((row0 + ai * HALF + m * 16) & 2047);
; #pragma unroll
;                     for (int n = 0; n < 2; ++n)
; #pragma unroll
;                         for (int e = 0; e < 2; ++e) { float r = pos * rinv[n][e]; r -= floorf(r); rs[n][e] = do_rope ? __builtin_amdgcn_sinf(r) : 0.f; rc[n][e] = do_rope ? __builtin_amdgcn_cosf(r) : 1.f; } }
; #pragma unroll
;                 for (int bj = 0; bj < 2; ++bj) { f32x4 v0 = acc[ai][bj][m][0], v1 = acc[ai][bj][m][1];
;                     if (ACT == 3) { const float pos = (float)((row0 + ai * HALF + m * 16) & 2047); float c3[4], s3[4];
; #pragma unroll
;                         for (int p = 0; p < 4; ++p) { float r = pos * rinv3[bj][p]; r -= floorf(r); s3[p] = rope3[bj] ? __builtin_amdgcn_sinf(r) : 0.f; c3[p] = rope3[bj] ? __builtin_amdgcn_cosf(r) : 1.f; }
.LBB0_1622:
	v_mov_b32_e32 v140, 0
	s_lshl_b32 s50, s50, 8
	v_mbcnt_lo_u32_b32 v140, -1, v140
	v_mbcnt_hi_u32_b32 v140, -1, v140
	v_or_b32_e32 v140, s33, v140
	s_mul_hi_i32 s52, s50, 0x2aaaaaab
	v_and_b32_e32 v142, 15, v140
	v_bfe_u32 v140, v140, 4, 2
	v_lshl_or_b32 v141, v140, 3, s42
	v_lshl_or_b32 v140, v140, 2, s45
	v_cvt_f32_ubyte0_e32 v143, v140
	v_mul_f32_e32 v144, 0xbe549a78, v143
	v_cmp_gt_f32_e32 vcc, s48, v144
	v_or_b32_e32 v145, 1, v140
	v_cvt_f32_ubyte0_e32 v145, v145
	v_cndmask_b32_e32 v144, 0, v152, vcc
	v_fmac_f32_e32 v144, 0xbe549a78, v143
	v_mul_f32_e32 v146, 0xbe549a78, v145
	v_exp_f32_e32 v143, v144
	v_cndmask_b32_e32 v144, 0, v153, vcc
	v_cmp_gt_f32_e32 vcc, s48, v146
	s_lshr_b32 s53, s52, 31
	v_ldexp_f32 v143, v143, v144
	v_cndmask_b32_e32 v146, 0, v152, vcc
	v_fmac_f32_e32 v146, 0xbe549a78, v145
	v_exp_f32_e32 v145, v146
	v_mul_f32_e32 v155, 0.15915494, v143
	v_cndmask_b32_e32 v143, 0, v153, vcc
	s_lshr_b32 s52, s52, 10
	v_ldexp_f32 v143, v145, v143
	v_mul_f32_e32 v154, 0.15915494, v143
	v_or_b32_e32 v143, 2, v140
	v_cvt_f32_ubyte0_e32 v143, v143
	v_mul_f32_e32 v144, 0xbe549a78, v143
	v_cmp_gt_f32_e32 vcc, s48, v144
	v_or_b32_e32 v140, 3, v140
	v_cvt_f32_ubyte0_e32 v140, v140
	v_cndmask_b32_e32 v144, 0, v152, vcc
	v_fmac_f32_e32 v144, 0xbe549a78, v143
	v_mul_f32_e32 v145, 0xbe549a78, v140
	v_exp_f32_e32 v143, v144
	v_cndmask_b32_e32 v144, 0, v153, vcc
	v_cmp_gt_f32_e32 vcc, s48, v145
	s_lshl_b32 s51, s76, 8
	v_ldexp_f32 v143, v143, v144
	v_cndmask_b32_e32 v145, 0, v152, vcc
	v_fmac_f32_e32 v145, 0xbe549a78, v140
	v_exp_f32_e32 v140, v145
	s_add_i32 s52, s52, s53
	v_mul_f32_e32 v157, 0.15915494, v143
	v_cndmask_b32_e32 v143, 0, v153, vcc
	s_add_i32 s51, s51, s41
	s_mulk_i32 s52, 0x1800
	v_ldexp_f32 v140, v140, v143
	s_sub_i32 s52, s50, s52
	v_mul_f32_e32 v156, 0.15915494, v140
	v_or_b32_e32 v140, s50, v141
	v_mov_b32_e32 v143, s51
	s_movk_i32 s50, 0x7cf
	v_or_b32_e32 v158, s51, v142
	v_bitop3_b32 v142, v142, s50, v143 bitop3:0xc8
	v_cvt_f32_u32_e32 v146, v142
	s_cmpk_lt_i32 s52, 0x1000
	s_cselect_b64 vcc, -1, 0
	v_ashrrev_i32_e32 v141, 31, v140
	v_mul_f32_e32 v147, v155, v146
	v_floor_f32_e32 v147, v147
	v_fma_f32 v147, v155, v146, -v147
	v_sin_f32_e32 v159, v147
	v_cos_f32_e32 v147, v147
	v_mul_f32_e32 v160, v154, v146
	v_mul_f32_e32 v164, v156, v146
	v_floor_f32_e32 v160, v160
	v_cndmask_b32_e32 v162, 1.0, v147, vcc
	v_mul_f32_e32 v147, v157, v146
	v_floor_f32_e32 v147, v147
	v_floor_f32_e32 v164, v164
	v_fma_f32 v160, v154, v146, -v160
	v_fma_f32 v147, v157, v146, -v147
	v_fma_f32 v146, v156, v146, -v164
	v_sin_f32_e32 v163, v147
	v_cos_f32_e32 v147, v147
	v_sin_f32_e32 v164, v146
	v_cos_f32_e32 v146, v146
	v_sin_f32_e32 v161, v160
	v_mov_b64_e32 v[144:145], s[12:13]
	v_cos_f32_e32 v160, v160
	v_mad_i64_i32 v[142:143], s[50:51], v158, s49, v[144:145]
	v_cndmask_b32_e32 v159, 0, v159, vcc
	v_cndmask_b32_e32 v165, 1.0, v147, vcc
	v_cndmask_b32_e32 v166, 1.0, v146, vcc
	v_lshlrev_b64 v[146:147], 1, v[140:141]
	v_lshl_add_u64 v[140:141], v[142:143], 0, v[146:147]
	v_mul_f32_e32 v142, v125, v159
	v_cndmask_b32_e32 v161, 0, v161, vcc
	v_fma_f32 v142, v124, v162, -v142
	v_mul_f32_e32 v124, v124, v159
	v_cndmask_b32_e32 v160, 1.0, v160, vcc
	v_fmac_f32_e32 v124, v125, v162
	v_mul_f32_e32 v125, v127, v161
	v_cndmask_b32_e32 v163, 0, v163, vcc
	v_fma_f32 v125, v126, v160, -v125
	v_mul_f32_e32 v126, v126, v161
	v_cndmask_b32_e32 v164, 0, v164, vcc
	v_fmac_f32_e32 v126, v127, v160
	v_mul_f32_e32 v127, v121, v163
	v_fma_f32 v127, v120, v165, -v127
	v_mul_f32_e32 v143, v120, v163
	v_mul_f32_e32 v120, v123, v164
	v_fma_f32 v167, v122, v166, -v120
	v_mul_f32_e32 v168, v122, v164
	v_cvt_pk_bf16_f32 v120, v142, v124
	v_fmac_f32_e32 v143, v121, v165
	v_fmac_f32_e32 v168, v123, v166
	v_cvt_pk_bf16_f32 v121, v125, v126
	v_cvt_pk_bf16_f32 v122, v127, v143
	v_cvt_pk_bf16_f32 v123, v167, v168
	global_store_dwordx4 v[140:141], v[120:123], off
	s_movk_i32 s50, 0x7df
	s_nop 0
	v_mul_f32_e32 v120, v117, v159
	v_fma_f32 v120, v116, v162, -v120
	v_mul_f32_e32 v116, v116, v159
	v_fmac_f32_e32 v116, v117, v162
	v_mul_f32_e32 v117, v119, v161
	v_fma_f32 v117, v118, v160, -v117
	v_mul_f32_e32 v118, v118, v161
	v_fmac_f32_e32 v118, v119, v160
	v_mul_f32_e32 v119, v113, v163
	v_fma_f32 v119, v112, v165, -v119
	v_mul_f32_e32 v121, v112, v163
	v_mul_f32_e32 v112, v115, v164
	v_fma_f32 v122, v114, v166, -v112
	v_mul_f32_e32 v123, v114, v164
	v_cvt_pk_bf16_f32 v112, v120, v116
	v_fmac_f32_e32 v121, v113, v165
	v_fmac_f32_e32 v123, v115, v166
	v_cvt_pk_bf16_f32 v113, v117, v118
	v_cvt_pk_bf16_f32 v114, v119, v121
	v_cvt_pk_bf16_f32 v115, v122, v123
	global_store_dwordx4 v[140:141], v[112:115], off offset:256
	s_nop 1
	v_bitop3_b32 v112, v158, s50, 16 bitop3:0xc8
	v_cvt_f32_u32_e32 v114, v112
	v_or_b32_e32 v112, 16, v158
	v_mad_i64_i32 v[112:113], s[50:51], v112, s49, v[144:145]
	v_mul_f32_e32 v115, v155, v114
	v_floor_f32_e32 v115, v115
	v_fma_f32 v115, v155, v114, -v115
	v_mul_f32_e32 v117, v154, v114
	v_sin_f32_e32 v116, v115
	v_floor_f32_e32 v117, v117
	v_cos_f32_e32 v115, v115
	v_fma_f32 v117, v154, v114, -v117
	v_mul_f32_e32 v119, v157, v114
	v_sin_f32_e32 v118, v117
	v_floor_f32_e32 v119, v119
	v_mul_f32_e32 v121, v156, v114
	v_cos_f32_e32 v117, v117
	v_fma_f32 v119, v157, v114, -v119
	v_floor_f32_e32 v121, v121
	v_cndmask_b32_e32 v116, 0, v116, vcc
	v_sin_f32_e32 v120, v119
	v_fma_f32 v114, v156, v114, -v121
	v_cndmask_b32_e32 v115, 1.0, v115, vcc
	v_cos_f32_e32 v119, v119
	v_sin_f32_e32 v121, v114
	v_mul_f32_e32 v122, v109, v116
	v_cndmask_b32_e32 v118, 0, v118, vcc
	v_cos_f32_e32 v114, v114
	v_fma_f32 v122, v108, v115, -v122
	v_mul_f32_e32 v108, v108, v116
;     __device__ __forceinline__ void operator()(const f32x4 (&acc)[2][2][4][2], const Unit& u, int wr, int wc, int fr, int fq) const {
;     ...
;                 if (ACT == 2) { const float pos = (float)((row0 + ai * HALF + m * 16) & 2047);
; #pragma unroll
;                     for (int n = 0; n < 2; ++n)
; #pragma unroll
;                         for (int e = 0; e < 2; ++e) { float r = pos * rinv[n][e]; r -= floorf(r); rs[n][e] = do_rope ? __builtin_amdgcn_sinf(r) : 0.f; rc[n][e] = do_rope ? __builtin_amdgcn_cosf(r) : 1.f; } }
; #pragma unroll
;                 for (int bj = 0; bj < 2; ++bj) { f32x4 v0 = acc[ai][bj][m][0], v1 = acc[ai][bj][m][1];
;                     if (ACT == 3) { const float pos = (float)((row0 + ai * HALF + m * 16) & 2047); float c3[4], s3[4];
; #pragma unroll
;                         for (int p = 0; p < 4; ++p) { float r = pos * rinv3[bj][p]; r -= floorf(r); s3[p] = rope3[bj] ? __builtin_amdgcn_sinf(r) : 0.f; c3[p] = rope3[bj] ? __builtin_amdgcn_cosf(r) : 1.f; }
;                         const f32x4 a = v0, b = v1;
;                         v0[0] = a[0] * c3[0] - a[1] * s3[0]; v0[1] = a[1] * c3[0] + a[0] * s3[0]; v0[2] = a[2] * c3[1] - a[3] * s3[1]; v0[3] = a[3] * c3[1] + a[2] * s3[1];
;                         v1[0] = b[0] * c3[2] - b[1] * s3[2]; v1[1] = b[1] * c3[2] + b[0] * s3[2]; v1[2] = b[2] * c3[3] - b[3] * s3[3]; v1[3] = b[3] * c3[3] + b[2] * s3[3]; }
;                     if (ACT == 2) { const f32x4 a = v0, b = v1;
;                         v0[0] = a[0] * rc[0][0] - a[1] * rs[0][0]; v0[1] = a[1] * rc[0][0] + a[0] * rs[0][0]; v0[2] = a[2] * rc[0][1] - a[3] * rs[0][1]; v0[3] = a[3] * rc[0][1] + a[2] * rs[0][1];
;                         v1[0] = b[0] * rc[1][0] - b[1] * rs[1][0]; v1[1] = b[1] * rc[1][0] + b[0] * rs[1][0]; v1[2] = b[2] * rc[1][1] - b[3] * rs[1][1]; v1[3] = b[3] * rc[1][1] + b[2] * rs[1][1]; }
;                     if (ACT == 1) {
; #pragma unroll
;                         for (int j = 0; j < 4; ++j) { const float a = __int_as_float(max(__float_as_int(v0[j]), 0)), b = __int_as_float(max(__float_as_int(v1[j]), 0)); v0[j] = a * a; v1[j] = b * b; } }
;                     u32x4 w; w.x = cvt_pk_bf16(v0[0], v0[1]); w.y = cvt_pk_bf16(v0[2], v0[3]); w.z = cvt_pk_bf16(v1[0], v1[1]); w.w = cvt_pk_bf16(v1[2], v1[3]);
;                     *(u32x4*)(rowp + (ACT == 1 ? bj * 2 * 2 * 8192 : bj * HALF)) = w; } }
	v_cndmask_b32_e32 v117, 1.0, v117, vcc
	v_fmac_f32_e32 v108, v109, v115
	v_mul_f32_e32 v109, v111, v118
	v_cndmask_b32_e32 v120, 0, v120, vcc
	v_fma_f32 v109, v110, v117, -v109
	v_mul_f32_e32 v110, v110, v118
	v_cndmask_b32_e32 v119, 1.0, v119, vcc
	v_cndmask_b32_e32 v121, 0, v121, vcc
	v_fmac_f32_e32 v110, v111, v117
	v_mul_f32_e32 v111, v105, v120
	v_cndmask_b32_e32 v114, 1.0, v114, vcc
	v_fma_f32 v111, v104, v119, -v111
	v_mul_f32_e32 v123, v104, v120
	v_mul_f32_e32 v104, v107, v121
	v_lshl_add_u64 v[112:113], v[112:113], 0, v[146:147]
	v_fma_f32 v124, v106, v114, -v104
	v_mul_f32_e32 v125, v106, v121
	v_cvt_pk_bf16_f32 v104, v122, v108
	v_fmac_f32_e32 v123, v105, v119
	v_fmac_f32_e32 v125, v107, v114
	v_cvt_pk_bf16_f32 v105, v109, v110
	v_cvt_pk_bf16_f32 v106, v111, v123
	v_cvt_pk_bf16_f32 v107, v124, v125
	global_store_dwordx4 v[112:113], v[104:107], off
	s_movk_i32 s50, 0x7ef
	s_nop 0
	v_mul_f32_e32 v104, v101, v116
	v_fma_f32 v104, v100, v115, -v104
	v_mul_f32_e32 v100, v100, v116
	v_fmac_f32_e32 v100, v101, v115
	v_mul_f32_e32 v101, v103, v118
	v_fma_f32 v101, v102, v117, -v101
	v_mul_f32_e32 v102, v102, v118
	v_fmac_f32_e32 v102, v103, v117
	v_mul_f32_e32 v103, v97, v120
	v_fma_f32 v103, v96, v119, -v103
	v_mul_f32_e32 v105, v96, v120
	v_mul_f32_e32 v96, v99, v121
	v_fma_f32 v106, v98, v114, -v96
	v_mul_f32_e32 v107, v98, v121
	v_cvt_pk_bf16_f32 v96, v104, v100
	v_fmac_f32_e32 v105, v97, v119
	v_fmac_f32_e32 v107, v99, v114
	v_cvt_pk_bf16_f32 v97, v101, v102
	v_cvt_pk_bf16_f32 v98, v103, v105
	v_cvt_pk_bf16_f32 v99, v106, v107
	global_store_dwordx4 v[112:113], v[96:99], off offset:256
	s_nop 1
	v_bitop3_b32 v96, v158, s50, 32 bitop3:0xc8
	v_cvt_f32_u32_e32 v98, v96
	v_or_b32_e32 v96, 32, v158
	v_mad_i64_i32 v[96:97], s[50:51], v96, s49, v[144:145]
	v_mul_f32_e32 v99, v155, v98
	v_floor_f32_e32 v99, v99
	v_fma_f32 v99, v155, v98, -v99
	v_mul_f32_e32 v101, v154, v98
	v_sin_f32_e32 v100, v99
	v_floor_f32_e32 v101, v101
	v_cos_f32_e32 v99, v99
	v_fma_f32 v101, v154, v98, -v101
	v_mul_f32_e32 v103, v157, v98
	v_sin_f32_e32 v102, v101
	v_floor_f32_e32 v103, v103
	v_mul_f32_e32 v105, v156, v98
	v_cos_f32_e32 v101, v101
	v_fma_f32 v103, v157, v98, -v103
	v_floor_f32_e32 v105, v105
	v_cndmask_b32_e32 v100, 0, v100, vcc
	v_sin_f32_e32 v104, v103
	v_fma_f32 v98, v156, v98, -v105
	v_cndmask_b32_e32 v99, 1.0, v99, vcc
	v_cos_f32_e32 v103, v103
	v_sin_f32_e32 v105, v98
	v_mul_f32_e32 v106, v93, v100
	v_cndmask_b32_e32 v102, 0, v102, vcc
	v_cos_f32_e32 v98, v98
	v_fma_f32 v106, v92, v99, -v106
	v_mul_f32_e32 v92, v92, v100
	v_cndmask_b32_e32 v101, 1.0, v101, vcc
	v_fmac_f32_e32 v92, v93, v99
	v_mul_f32_e32 v93, v95, v102
	v_cndmask_b32_e32 v104, 0, v104, vcc
	v_fma_f32 v93, v94, v101, -v93
	v_mul_f32_e32 v94, v94, v102
	v_cndmask_b32_e32 v103, 1.0, v103, vcc
	v_cndmask_b32_e32 v105, 0, v105, vcc
	v_fmac_f32_e32 v94, v95, v101
	v_mul_f32_e32 v95, v89, v104
	v_cndmask_b32_e32 v98, 1.0, v98, vcc
	v_fma_f32 v95, v88, v103, -v95
	v_mul_f32_e32 v107, v88, v104
	v_mul_f32_e32 v88, v91, v105
	v_lshl_add_u64 v[96:97], v[96:97], 0, v[146:147]
	v_fma_f32 v108, v90, v98, -v88
	v_mul_f32_e32 v109, v90, v105
	v_cvt_pk_bf16_f32 v88, v106, v92
	v_fmac_f32_e32 v107, v89, v103
	v_fmac_f32_e32 v109, v91, v98
	v_cvt_pk_bf16_f32 v89, v93, v94
	v_cvt_pk_bf16_f32 v90, v95, v107
	v_cvt_pk_bf16_f32 v91, v108, v109
	global_store_dwordx4 v[96:97], v[88:91], off
	s_movk_i32 s50, 0x7ff
	s_nop 0
	v_mul_f32_e32 v88, v85, v100
	v_fma_f32 v88, v84, v99, -v88
	v_mul_f32_e32 v84, v84, v100
	v_fmac_f32_e32 v84, v85, v99
	v_mul_f32_e32 v85, v87, v102
	v_fma_f32 v85, v86, v101, -v85
	v_mul_f32_e32 v86, v86, v102
	v_fmac_f32_e32 v86, v87, v101
	v_mul_f32_e32 v87, v81, v104
	v_fma_f32 v87, v80, v103, -v87
	v_mul_f32_e32 v89, v80, v104
	v_mul_f32_e32 v80, v83, v105
	v_fma_f32 v90, v82, v98, -v80
	v_mul_f32_e32 v91, v82, v105
	v_cvt_pk_bf16_f32 v80, v88, v84
	v_fmac_f32_e32 v89, v81, v103
	v_fmac_f32_e32 v91, v83, v98
	v_cvt_pk_bf16_f32 v81, v85, v86
	v_cvt_pk_bf16_f32 v82, v87, v89
	v_cvt_pk_bf16_f32 v83, v90, v91
	global_store_dwordx4 v[96:97], v[80:83], off offset:256
	s_nop 1
	v_bitop3_b32 v80, v158, s50, 48 bitop3:0xc8
	v_cvt_f32_u32_e32 v82, v80
	v_or_b32_e32 v80, 48, v158
	v_mad_i64_i32 v[80:81], s[50:51], v80, s49, v[144:145]
	v_mul_f32_e32 v83, v155, v82
	v_floor_f32_e32 v83, v83
	v_fma_f32 v83, v155, v82, -v83
	v_mul_f32_e32 v85, v154, v82
	v_sin_f32_e32 v84, v83
	v_floor_f32_e32 v85, v85
	v_cos_f32_e32 v83, v83
	v_fma_f32 v85, v154, v82, -v85
	v_mul_f32_e32 v87, v157, v82
	v_sin_f32_e32 v86, v85
	v_floor_f32_e32 v87, v87
	v_mul_f32_e32 v89, v156, v82
	v_cos_f32_e32 v85, v85
	v_fma_f32 v87, v157, v82, -v87
	v_floor_f32_e32 v89, v89
	v_cndmask_b32_e32 v84, 0, v84, vcc
	v_sin_f32_e32 v88, v87
	v_fma_f32 v82, v156, v82, -v89
	v_cndmask_b32_e32 v83, 1.0, v83, vcc
	v_cos_f32_e32 v87, v87
	v_sin_f32_e32 v89, v82
	v_mul_f32_e32 v90, v77, v84
	v_cndmask_b32_e32 v86, 0, v86, vcc
	v_cos_f32_e32 v82, v82
	v_fma_f32 v90, v76, v83, -v90
	v_mul_f32_e32 v76, v76, v84
	v_cndmask_b32_e32 v85, 1.0, v85, vcc
	v_fmac_f32_e32 v76, v77, v83
	v_mul_f32_e32 v77, v79, v86
	v_cndmask_b32_e32 v88, 0, v88, vcc
	v_fma_f32 v77, v78, v85, -v77
	v_mul_f32_e32 v78, v78, v86
	v_cndmask_b32_e32 v87, 1.0, v87, vcc
	v_cndmask_b32_e32 v89, 0, v89, vcc
	v_fmac_f32_e32 v78, v79, v85
	v_mul_f32_e32 v79, v73, v88
	v_cndmask_b32_e32 v82, 1.0, v82, vcc
	v_fma_f32 v79, v72, v87, -v79
	v_mul_f32_e32 v91, v72, v88
	v_mul_f32_e32 v72, v75, v89
	v_lshl_add_u64 v[80:81], v[80:81], 0, v[146:147]
	v_fma_f32 v92, v74, v82, -v72
	v_mul_f32_e32 v93, v74, v89
	v_cvt_pk_bf16_f32 v72, v90, v76
	v_fmac_f32_e32 v91, v73, v87
;     __device__ __forceinline__ void operator()(const f32x4 (&acc)[2][2][4][2], const Unit& u, int wr, int wc, int fr, int fq) const {
;     ...
;                 if (ACT == 2) { const float pos = (float)((row0 + ai * HALF + m * 16) & 2047);
; #pragma unroll
;                     for (int n = 0; n < 2; ++n)
; #pragma unroll
;                         for (int e = 0; e < 2; ++e) { float r = pos * rinv[n][e]; r -= floorf(r); rs[n][e] = do_rope ? __builtin_amdgcn_sinf(r) : 0.f; rc[n][e] = do_rope ? __builtin_amdgcn_cosf(r) : 1.f; } }
; #pragma unroll
;                 for (int bj = 0; bj < 2; ++bj) { f32x4 v0 = acc[ai][bj][m][0], v1 = acc[ai][bj][m][1];
;                     if (ACT == 3) { const float pos = (float)((row0 + ai * HALF + m * 16) & 2047); float c3[4], s3[4];
; #pragma unroll
;                         for (int p = 0; p < 4; ++p) { float r = pos * rinv3[bj][p]; r -= floorf(r); s3[p] = rope3[bj] ? __builtin_amdgcn_sinf(r) : 0.f; c3[p] = rope3[bj] ? __builtin_amdgcn_cosf(r) : 1.f; }
;                         const f32x4 a = v0, b = v1;
;                         v0[0] = a[0] * c3[0] - a[1] * s3[0]; v0[1] = a[1] * c3[0] + a[0] * s3[0]; v0[2] = a[2] * c3[1] - a[3] * s3[1]; v0[3] = a[3] * c3[1] + a[2] * s3[1];
;                         v1[0] = b[0] * c3[2] - b[1] * s3[2]; v1[1] = b[1] * c3[2] + b[0] * s3[2]; v1[2] = b[2] * c3[3] - b[3] * s3[3]; v1[3] = b[3] * c3[3] + b[2] * s3[3]; }
;                     if (ACT == 2) { const f32x4 a = v0, b = v1;
;                         v0[0] = a[0] * rc[0][0] - a[1] * rs[0][0]; v0[1] = a[1] * rc[0][0] + a[0] * rs[0][0]; v0[2] = a[2] * rc[0][1] - a[3] * rs[0][1]; v0[3] = a[3] * rc[0][1] + a[2] * rs[0][1];
;                         v1[0] = b[0] * rc[1][0] - b[1] * rs[1][0]; v1[1] = b[1] * rc[1][0] + b[0] * rs[1][0]; v1[2] = b[2] * rc[1][1] - b[3] * rs[1][1]; v1[3] = b[3] * rc[1][1] + b[2] * rs[1][1]; }
;                     if (ACT == 1) {
; #pragma unroll
;                         for (int j = 0; j < 4; ++j) { const float a = __int_as_float(max(__float_as_int(v0[j]), 0)), b = __int_as_float(max(__float_as_int(v1[j]), 0)); v0[j] = a * a; v1[j] = b * b; } }
;                     u32x4 w; w.x = cvt_pk_bf16(v0[0], v0[1]); w.y = cvt_pk_bf16(v0[2], v0[3]); w.z = cvt_pk_bf16(v1[0], v1[1]); w.w = cvt_pk_bf16(v1[2], v1[3]);
;                     *(u32x4*)(rowp + (ACT == 1 ? bj * 2 * 2 * 8192 : bj * HALF)) = w; } }
	v_fmac_f32_e32 v93, v75, v82
	v_cvt_pk_bf16_f32 v73, v77, v78
	v_cvt_pk_bf16_f32 v74, v79, v91
	v_cvt_pk_bf16_f32 v75, v92, v93
	global_store_dwordx4 v[80:81], v[72:75], off
	s_nop 1
	v_mul_f32_e32 v72, v69, v84
	v_fma_f32 v72, v68, v83, -v72
	v_mul_f32_e32 v68, v68, v84
	v_fmac_f32_e32 v68, v69, v83
	v_mul_f32_e32 v69, v71, v86
	v_fma_f32 v69, v70, v85, -v69
	v_mul_f32_e32 v70, v70, v86
	v_fmac_f32_e32 v70, v71, v85
	v_mul_f32_e32 v71, v65, v88
	v_fma_f32 v71, v64, v87, -v71
	v_mul_f32_e32 v73, v64, v88
	v_mul_f32_e32 v64, v67, v89
	v_fma_f32 v74, v66, v82, -v64
	v_cvt_pk_bf16_f32 v64, v72, v68
	v_add_u32_e32 v68, 0x80, v158
	v_fmac_f32_e32 v73, v65, v87
	v_cvt_pk_bf16_f32 v65, v69, v70
	v_and_b32_e32 v69, 0x7cf, v68
	v_cvt_f32_u32_e32 v69, v69
	v_mul_f32_e32 v75, v66, v89
	v_cvt_pk_bf16_f32 v66, v71, v73
	v_fmac_f32_e32 v75, v67, v82
	v_cvt_pk_bf16_f32 v67, v74, v75
	global_store_dwordx4 v[80:81], v[64:67], off offset:256
	v_mul_f32_e32 v71, v157, v69
	v_floor_f32_e32 v71, v71
	v_mul_f32_e32 v66, v155, v69
	v_floor_f32_e32 v66, v66
	v_mad_i64_i32 v[64:65], s[50:51], v68, s49, v[144:145]
	v_fma_f32 v66, v155, v69, -v66
	v_mul_f32_e32 v68, v154, v69
	v_sin_f32_e32 v67, v66
	v_floor_f32_e32 v68, v68
	v_cos_f32_e32 v66, v66
	v_fma_f32 v68, v154, v69, -v68
	v_sin_f32_e32 v70, v68
	v_mul_f32_e32 v73, v156, v69
	v_cos_f32_e32 v68, v68
	v_fma_f32 v71, v157, v69, -v71
	v_floor_f32_e32 v73, v73
	v_cndmask_b32_e32 v67, 0, v67, vcc
	v_sin_f32_e32 v72, v71
	v_fma_f32 v69, v156, v69, -v73
	v_cndmask_b32_e32 v66, 1.0, v66, vcc
	v_cos_f32_e32 v71, v71
	v_sin_f32_e32 v73, v69
	v_mul_f32_e32 v74, v61, v67
	v_cndmask_b32_e32 v70, 0, v70, vcc
	v_cos_f32_e32 v69, v69
	v_fma_f32 v74, v60, v66, -v74
	v_mul_f32_e32 v60, v60, v67
	v_cndmask_b32_e32 v68, 1.0, v68, vcc
	v_fmac_f32_e32 v60, v61, v66
	v_mul_f32_e32 v61, v63, v70
	v_cndmask_b32_e32 v72, 0, v72, vcc
	v_fma_f32 v61, v62, v68, -v61
	v_mul_f32_e32 v62, v62, v70
	v_cndmask_b32_e32 v71, 1.0, v71, vcc
	v_cndmask_b32_e32 v73, 0, v73, vcc
	v_fmac_f32_e32 v62, v63, v68
	v_mul_f32_e32 v63, v57, v72
	v_cndmask_b32_e32 v69, 1.0, v69, vcc
	v_fma_f32 v63, v56, v71, -v63
	v_mul_f32_e32 v75, v56, v72
	v_mul_f32_e32 v56, v59, v73
	v_lshl_add_u64 v[64:65], v[64:65], 0, v[146:147]
	v_fma_f32 v76, v58, v69, -v56
	v_mul_f32_e32 v77, v58, v73
	v_cvt_pk_bf16_f32 v56, v74, v60
	v_fmac_f32_e32 v75, v57, v71
	v_fmac_f32_e32 v77, v59, v69
	v_cvt_pk_bf16_f32 v57, v61, v62
	v_cvt_pk_bf16_f32 v58, v63, v75
	v_cvt_pk_bf16_f32 v59, v76, v77
	global_store_dwordx4 v[64:65], v[56:59], off
	s_nop 1
	v_mul_f32_e32 v56, v53, v67
	v_fma_f32 v56, v52, v66, -v56
	v_mul_f32_e32 v52, v52, v67
	v_fmac_f32_e32 v52, v53, v66
	v_mul_f32_e32 v53, v55, v70
	v_fma_f32 v53, v54, v68, -v53
	v_mul_f32_e32 v54, v54, v70
	v_fmac_f32_e32 v54, v55, v68
	v_mul_f32_e32 v55, v49, v72
	v_fma_f32 v55, v48, v71, -v55
	v_mul_f32_e32 v57, v48, v72
	v_mul_f32_e32 v48, v51, v73
	v_fma_f32 v58, v50, v69, -v48
	v_cvt_pk_bf16_f32 v48, v56, v52
	v_add_u32_e32 v52, 0x90, v158
	v_fmac_f32_e32 v57, v49, v71
	v_cvt_pk_bf16_f32 v49, v53, v54
	v_and_b32_e32 v53, 0x7df, v52
	v_cvt_f32_u32_e32 v53, v53
	v_mul_f32_e32 v59, v50, v73
	v_cvt_pk_bf16_f32 v50, v55, v57
	v_fmac_f32_e32 v59, v51, v69
	v_cvt_pk_bf16_f32 v51, v58, v59
	global_store_dwordx4 v[64:65], v[48:51], off offset:256
	v_mul_f32_e32 v55, v157, v53
	v_floor_f32_e32 v55, v55
	v_mul_f32_e32 v50, v155, v53
	v_floor_f32_e32 v50, v50
	v_mad_i64_i32 v[48:49], s[50:51], v52, s49, v[144:145]
	v_fma_f32 v50, v155, v53, -v50
	v_mul_f32_e32 v52, v154, v53
	v_sin_f32_e32 v51, v50
	v_floor_f32_e32 v52, v52
	v_cos_f32_e32 v50, v50
	v_fma_f32 v52, v154, v53, -v52
	v_sin_f32_e32 v54, v52
	v_mul_f32_e32 v57, v156, v53
	v_cos_f32_e32 v52, v52
	v_fma_f32 v55, v157, v53, -v55
	v_floor_f32_e32 v57, v57
	v_cndmask_b32_e32 v51, 0, v51, vcc
	v_sin_f32_e32 v56, v55
	v_fma_f32 v53, v156, v53, -v57
	v_cndmask_b32_e32 v50, 1.0, v50, vcc
	v_cos_f32_e32 v55, v55
	v_sin_f32_e32 v57, v53
	v_mul_f32_e32 v58, v45, v51
	v_cndmask_b32_e32 v54, 0, v54, vcc
	v_cos_f32_e32 v53, v53
	v_fma_f32 v58, v44, v50, -v58
	v_mul_f32_e32 v44, v44, v51
	v_cndmask_b32_e32 v52, 1.0, v52, vcc
	v_fmac_f32_e32 v44, v45, v50
	v_mul_f32_e32 v45, v47, v54
	v_cndmask_b32_e32 v56, 0, v56, vcc
	v_fma_f32 v45, v46, v52, -v45
	v_mul_f32_e32 v46, v46, v54
	v_cndmask_b32_e32 v55, 1.0, v55, vcc
	v_cndmask_b32_e32 v57, 0, v57, vcc
	v_fmac_f32_e32 v46, v47, v52
	v_mul_f32_e32 v47, v41, v56
	v_cndmask_b32_e32 v53, 1.0, v53, vcc
	v_fma_f32 v47, v40, v55, -v47
	v_mul_f32_e32 v59, v40, v56
	v_mul_f32_e32 v40, v43, v57
	v_lshl_add_u64 v[48:49], v[48:49], 0, v[146:147]
	v_fma_f32 v60, v42, v53, -v40
	v_mul_f32_e32 v61, v42, v57
	v_cvt_pk_bf16_f32 v40, v58, v44
	v_fmac_f32_e32 v59, v41, v55
	v_fmac_f32_e32 v61, v43, v53
	v_cvt_pk_bf16_f32 v41, v45, v46
	v_cvt_pk_bf16_f32 v42, v47, v59
	v_cvt_pk_bf16_f32 v43, v60, v61
	global_store_dwordx4 v[48:49], v[40:43], off
	s_nop 1
	v_mul_f32_e32 v40, v37, v51
	v_fma_f32 v40, v36, v50, -v40
	v_mul_f32_e32 v36, v36, v51
	v_fmac_f32_e32 v36, v37, v50
	v_mul_f32_e32 v37, v39, v54
	v_fma_f32 v37, v38, v52, -v37
	v_mul_f32_e32 v38, v38, v54
	v_fmac_f32_e32 v38, v39, v52
	v_mul_f32_e32 v39, v33, v56
	v_fma_f32 v39, v32, v55, -v39
;     __device__ __forceinline__ void operator()(const f32x4 (&acc)[2][2][4][2], const Unit& u, int wr, int wc, int fr, int fq) const {
;     ...
;                 if (ACT == 2) { const float pos = (float)((row0 + ai * HALF + m * 16) & 2047);
; #pragma unroll
;                     for (int n = 0; n < 2; ++n)
; #pragma unroll
;                         for (int e = 0; e < 2; ++e) { float r = pos * rinv[n][e]; r -= floorf(r); rs[n][e] = do_rope ? __builtin_amdgcn_sinf(r) : 0.f; rc[n][e] = do_rope ? __builtin_amdgcn_cosf(r) : 1.f; } }
; #pragma unroll
;                 for (int bj = 0; bj < 2; ++bj) { f32x4 v0 = acc[ai][bj][m][0], v1 = acc[ai][bj][m][1];
;                     if (ACT == 3) { const float pos = (float)((row0 + ai * HALF + m * 16) & 2047); float c3[4], s3[4];
; #pragma unroll
;                         for (int p = 0; p < 4; ++p) { float r = pos * rinv3[bj][p]; r -= floorf(r); s3[p] = rope3[bj] ? __builtin_amdgcn_sinf(r) : 0.f; c3[p] = rope3[bj] ? __builtin_amdgcn_cosf(r) : 1.f; }
;                         const f32x4 a = v0, b = v1;
;                         v0[0] = a[0] * c3[0] - a[1] * s3[0]; v0[1] = a[1] * c3[0] + a[0] * s3[0]; v0[2] = a[2] * c3[1] - a[3] * s3[1]; v0[3] = a[3] * c3[1] + a[2] * s3[1];
;                         v1[0] = b[0] * c3[2] - b[1] * s3[2]; v1[1] = b[1] * c3[2] + b[0] * s3[2]; v1[2] = b[2] * c3[3] - b[3] * s3[3]; v1[3] = b[3] * c3[3] + b[2] * s3[3]; }
;                     if (ACT == 2) { const f32x4 a = v0, b = v1;
;                         v0[0] = a[0] * rc[0][0] - a[1] * rs[0][0]; v0[1] = a[1] * rc[0][0] + a[0] * rs[0][0]; v0[2] = a[2] * rc[0][1] - a[3] * rs[0][1]; v0[3] = a[3] * rc[0][1] + a[2] * rs[0][1];
;                         v1[0] = b[0] * rc[1][0] - b[1] * rs[1][0]; v1[1] = b[1] * rc[1][0] + b[0] * rs[1][0]; v1[2] = b[2] * rc[1][1] - b[3] * rs[1][1]; v1[3] = b[3] * rc[1][1] + b[2] * rs[1][1]; }
;                     if (ACT == 1) {
; #pragma unroll
;                         for (int j = 0; j < 4; ++j) { const float a = __int_as_float(max(__float_as_int(v0[j]), 0)), b = __int_as_float(max(__float_as_int(v1[j]), 0)); v0[j] = a * a; v1[j] = b * b; } }
;                     u32x4 w; w.x = cvt_pk_bf16(v0[0], v0[1]); w.y = cvt_pk_bf16(v0[2], v0[3]); w.z = cvt_pk_bf16(v1[0], v1[1]); w.w = cvt_pk_bf16(v1[2], v1[3]);
;                     *(u32x4*)(rowp + (ACT == 1 ? bj * 2 * 2 * 8192 : bj * HALF)) = w; } }
	v_mul_f32_e32 v41, v32, v56
	v_mul_f32_e32 v32, v35, v57
	v_fma_f32 v42, v34, v53, -v32
	v_cvt_pk_bf16_f32 v32, v40, v36
	v_add_u32_e32 v36, 0xa0, v158
	v_fmac_f32_e32 v41, v33, v55
	v_cvt_pk_bf16_f32 v33, v37, v38
	v_and_b32_e32 v37, 0x7ef, v36
	v_cvt_f32_u32_e32 v37, v37
	v_mul_f32_e32 v43, v34, v57
	v_cvt_pk_bf16_f32 v34, v39, v41
	v_fmac_f32_e32 v43, v35, v53
	v_cvt_pk_bf16_f32 v35, v42, v43
	global_store_dwordx4 v[48:49], v[32:35], off offset:256
	v_mul_f32_e32 v39, v157, v37
	v_floor_f32_e32 v39, v39
	v_mul_f32_e32 v34, v155, v37
	v_floor_f32_e32 v34, v34
	v_mad_i64_i32 v[32:33], s[50:51], v36, s49, v[144:145]
	v_fma_f32 v34, v155, v37, -v34
	v_mul_f32_e32 v36, v154, v37
	v_sin_f32_e32 v35, v34
	v_floor_f32_e32 v36, v36
	v_cos_f32_e32 v34, v34
	v_fma_f32 v36, v154, v37, -v36
	v_sin_f32_e32 v38, v36
	v_mul_f32_e32 v41, v156, v37
	v_cos_f32_e32 v36, v36
	v_fma_f32 v39, v157, v37, -v39
	v_floor_f32_e32 v41, v41
	v_cndmask_b32_e32 v35, 0, v35, vcc
	v_sin_f32_e32 v40, v39
	v_fma_f32 v37, v156, v37, -v41
	v_cndmask_b32_e32 v34, 1.0, v34, vcc
	v_cos_f32_e32 v39, v39
	v_sin_f32_e32 v41, v37
	v_mul_f32_e32 v42, v29, v35
	v_cndmask_b32_e32 v38, 0, v38, vcc
	v_cos_f32_e32 v37, v37
	v_fma_f32 v42, v28, v34, -v42
	v_mul_f32_e32 v28, v28, v35
	v_cndmask_b32_e32 v36, 1.0, v36, vcc
	v_fmac_f32_e32 v28, v29, v34
	v_mul_f32_e32 v29, v31, v38
	v_cndmask_b32_e32 v40, 0, v40, vcc
	v_fma_f32 v29, v30, v36, -v29
	v_mul_f32_e32 v30, v30, v38
	v_cndmask_b32_e32 v39, 1.0, v39, vcc
	v_cndmask_b32_e32 v41, 0, v41, vcc
	v_fmac_f32_e32 v30, v31, v36
	v_mul_f32_e32 v31, v25, v40
	v_cndmask_b32_e32 v37, 1.0, v37, vcc
	v_fma_f32 v31, v24, v39, -v31
	v_mul_f32_e32 v43, v24, v40
	v_mul_f32_e32 v24, v27, v41
	v_lshl_add_u64 v[32:33], v[32:33], 0, v[146:147]
	v_fma_f32 v44, v26, v37, -v24
	v_mul_f32_e32 v45, v26, v41
	v_cvt_pk_bf16_f32 v24, v42, v28
	v_fmac_f32_e32 v43, v25, v39
	v_fmac_f32_e32 v45, v27, v37
	v_cvt_pk_bf16_f32 v25, v29, v30
	v_cvt_pk_bf16_f32 v26, v31, v43
	v_cvt_pk_bf16_f32 v27, v44, v45
	global_store_dwordx4 v[32:33], v[24:27], off
	s_nop 1
	v_mul_f32_e32 v24, v21, v35
	v_fma_f32 v24, v20, v34, -v24
	v_mul_f32_e32 v20, v20, v35
	v_fmac_f32_e32 v20, v21, v34
	v_mul_f32_e32 v21, v23, v38
	v_fma_f32 v21, v22, v36, -v21
	v_mul_f32_e32 v22, v22, v38
	v_fmac_f32_e32 v22, v23, v36
	v_mul_f32_e32 v23, v17, v40
	v_fma_f32 v23, v16, v39, -v23
	v_mul_f32_e32 v25, v16, v40
	v_mul_f32_e32 v16, v19, v41
	v_fma_f32 v26, v18, v37, -v16
	v_cvt_pk_bf16_f32 v16, v24, v20
	v_add_u32_e32 v20, 0xb0, v158
	v_fmac_f32_e32 v25, v17, v39
	v_cvt_pk_bf16_f32 v17, v21, v22
	v_and_b32_e32 v21, 0x7ff, v20
	v_cvt_f32_u32_e32 v21, v21
	v_mul_f32_e32 v27, v18, v41
	v_cvt_pk_bf16_f32 v18, v23, v25
	v_fmac_f32_e32 v27, v19, v37
	v_cvt_pk_bf16_f32 v19, v26, v27
	global_store_dwordx4 v[32:33], v[16:19], off offset:256
	v_mul_f32_e32 v23, v157, v21
	v_floor_f32_e32 v23, v23
	v_mul_f32_e32 v18, v155, v21
	v_floor_f32_e32 v18, v18
	v_mad_i64_i32 v[16:17], s[50:51], v20, s49, v[144:145]
	v_fma_f32 v18, v155, v21, -v18
	v_mul_f32_e32 v20, v154, v21
	v_sin_f32_e32 v19, v18
	v_floor_f32_e32 v20, v20
	v_cos_f32_e32 v18, v18
	v_fma_f32 v20, v154, v21, -v20
	v_sin_f32_e32 v22, v20
	v_mul_f32_e32 v25, v156, v21
	v_cos_f32_e32 v20, v20
	v_fma_f32 v23, v157, v21, -v23
	v_floor_f32_e32 v25, v25
	v_cndmask_b32_e32 v19, 0, v19, vcc
	v_sin_f32_e32 v24, v23
	v_fma_f32 v21, v156, v21, -v25
	v_cndmask_b32_e32 v18, 1.0, v18, vcc
	v_cos_f32_e32 v23, v23
	v_sin_f32_e32 v25, v21
	v_mul_f32_e32 v26, v13, v19
	v_cndmask_b32_e32 v22, 0, v22, vcc
	v_cos_f32_e32 v21, v21
	v_fma_f32 v26, v12, v18, -v26
	v_mul_f32_e32 v12, v12, v19
	v_cndmask_b32_e32 v20, 1.0, v20, vcc
	v_fmac_f32_e32 v12, v13, v18
	v_mul_f32_e32 v13, v15, v22
	v_cndmask_b32_e32 v24, 0, v24, vcc
	v_fma_f32 v13, v14, v20, -v13
	v_mul_f32_e32 v14, v14, v22
	v_cndmask_b32_e32 v23, 1.0, v23, vcc
	v_cndmask_b32_e32 v25, 0, v25, vcc
	v_fmac_f32_e32 v14, v15, v20
	v_mul_f32_e32 v15, v9, v24
	v_cndmask_b32_e32 v21, 1.0, v21, vcc
	v_fma_f32 v15, v8, v23, -v15
	v_mul_f32_e32 v27, v8, v24
	v_mul_f32_e32 v8, v11, v25
	v_lshl_add_u64 v[16:17], v[16:17], 0, v[146:147]
	v_fma_f32 v28, v10, v21, -v8
	v_mul_f32_e32 v29, v10, v25
	v_cvt_pk_bf16_f32 v8, v26, v12
	v_fmac_f32_e32 v27, v9, v23
	v_fmac_f32_e32 v29, v11, v21
	v_cvt_pk_bf16_f32 v9, v13, v14
	v_cvt_pk_bf16_f32 v10, v15, v27
	v_cvt_pk_bf16_f32 v11, v28, v29
	global_store_dwordx4 v[16:17], v[8:11], off
	s_andn2_b64 vcc, exec, s[2:3]
	s_mov_b64 s[2:3], -1
	v_mul_f32_e32 v8, v5, v19
	v_fma_f32 v8, v4, v18, -v8
	v_mul_f32_e32 v4, v4, v19
	v_fmac_f32_e32 v4, v5, v18
	v_mul_f32_e32 v5, v7, v22
	v_fma_f32 v5, v6, v20, -v5
	v_mul_f32_e32 v6, v6, v22
	v_fmac_f32_e32 v6, v7, v20
	v_mul_f32_e32 v7, v1, v24
	v_fma_f32 v7, v0, v23, -v7
	v_mul_f32_e32 v9, v0, v24
	v_mul_f32_e32 v0, v3, v25
	v_mul_f32_e32 v11, v2, v25
	v_fmac_f32_e32 v9, v1, v23
	v_fma_f32 v10, v2, v21, -v0
	v_fmac_f32_e32 v11, v3, v21
	v_cvt_pk_bf16_f32 v0, v8, v4
	v_cvt_pk_bf16_f32 v1, v5, v6
	v_cvt_pk_bf16_f32 v2, v7, v9
	v_cvt_pk_bf16_f32 v3, v10, v11
	global_store_dwordx4 v[16:17], v[0:3], off offset:256
	s_cbranch_vccnz .LBB0_1615
	s_andn2_b64 vcc, exec, s[6:7]
	s_cbranch_vccnz .LBB0_1614
	s_barrier
	s_branch .LBB0_1614

; __device__ __forceinline__ unsigned pk2(float lo, float hi) { return f2bf(lo) | (f2bf(hi) << 16); }
; template <int L>
; __device__ __forceinline__ void layer_body(const Args& args, LAS unsigned char* lds, const int wave, const int G, const int gw, const int NGW, const int lo, const int hi,
;                                            unsigned char* const ws_kernel, const XcdBarrier& bar, int& pid) {
;     ...
;                 for (int m = mlo + gwl; m < mhi; m += NGWH) {
; #pragma unroll
;                     for (int it = 0; it < 4; ++it) { const int e0 = 8 * (lane + 64 * it), h = e0 >> 7;
;                         const float l0 = lsebuf[((size_t)0 * (M / 2) + m) * NH + h], l1 = lsebuf[((size_t)1 * (M / 2) + m) * NH + h], l2 = lsebuf[((size_t)2 * (M / 2) + m) * NH + h];
;                         const float lm = fmaxf(l0, fmaxf(l1, l2)); float w0 = __builtin_amdgcn_exp2f(l0 - lm), w1 = __builtin_amdgcn_exp2f(l1 - lm), w2 = __builtin_amdgcn_exp2f(l2 - lm);
;                         const float wi = 1.0f / (w0 + w1 + w2); w0 *= wi; w1 *= wi; w2 *= wi;
;                         const v4u a = *(const v4u*)(opart + ((size_t)0 * (M / 2) + m) * D + e0), bq = *(const v4u*)(opart + ((size_t)1 * (M / 2) + m) * D + e0), cq2 = *(const v4u*)(opart + ((size_t)2 * (M / 2) + m) * D + e0);
;                         v4u o; o.x = pk2(w0 * bflo(a.x) + w1 * bflo(bq.x) + w2 * bflo(cq2.x), w0 * bfhi(a.x) + w1 * bfhi(bq.x) + w2 * bfhi(cq2.x));
;                         o.y = pk2(w0 * bflo(a.y) + w1 * bflo(bq.y) + w2 * bflo(cq2.y), w0 * bfhi(a.y) + w1 * bfhi(bq.y) + w2 * bfhi(cq2.y));
;                         o.z = pk2(w0 * bflo(a.z) + w1 * bflo(bq.z) + w2 * bflo(cq2.z), w0 * bfhi(a.z) + w1 * bfhi(bq.z) + w2 * bfhi(cq2.z));
;                         o.w = pk2(w0 * bflo(a.w) + w1 * bflo(bq.w) + w2 * bflo(cq2.w), w0 * bfhi(a.w) + w1 * bfhi(bq.w) + w2 * bfhi(cq2.w));
;                         *(v4u*)(obuf + (size_t)m * D + e0) = o; }
.LBB0_1774:
	v_lshl_add_u64 v[14:15], s[6:7], 0, v[2:3]
	v_add_co_u32_e64 v20, s[2:3], s9, v14
	v_lshl_add_u64 v[16:17], s[6:7], 0, v[0:1]
	s_nop 0
	v_addc_co_u32_e64 v21, s[2:3], 0, v15, s[2:3]
	v_add_co_u32_e64 v22, s[2:3], s13, v14
	v_lshl_add_u64 v[18:19], s[6:7], 0, v[8:9]
	s_nop 0
	v_addc_co_u32_e64 v23, s[2:3], 0, v15, s[2:3]
	v_add_co_u32_e64 v24, s[2:3], s14, v14
	v_lshl_add_u64 v[26:27], s[6:7], 0, v[6:7]
	s_nop 0
	v_addc_co_u32_e64 v25, s[2:3], 0, v15, s[2:3]
	v_add_co_u32_e64 v14, s[2:3], s22, v16
	v_lshl_add_u64 v[28:29], s[6:7], 0, v[4:5]
	s_nop 0
	v_addc_co_u32_e64 v15, s[2:3], 0, v17, s[2:3]
	v_add_co_u32_e64 v40, s[2:3], s0, v18
	v_lshl_add_u64 v[12:13], s[6:7], 0, v[10:11]
	s_nop 0
	v_addc_co_u32_e64 v41, s[2:3], 0, v19, s[2:3]
	v_add_co_u32_e64 v42, s[2:3], s1, v18
	v_add_co_u32_e32 v36, vcc, 0x37600000, v12
	s_nop 0
	v_addc_co_u32_e64 v43, s[2:3], 0, v19, s[2:3]
	v_add_co_u32_e64 v44, s[2:3], s8, v18
	v_addc_co_u32_e32 v37, vcc, 0, v13, vcc
	s_nop 0
	v_addc_co_u32_e64 v45, s[2:3], 0, v19, s[2:3]
	v_add_co_u32_e64 v46, s[2:3], s0, v26
	v_add_co_u32_e32 v38, vcc, 0x37640000, v12
	s_nop 0
	v_addc_co_u32_e64 v47, s[2:3], 0, v27, s[2:3]
	v_add_co_u32_e64 v48, s[2:3], s1, v26
	v_addc_co_u32_e32 v39, vcc, 0, v13, vcc
	s_nop 0
	v_addc_co_u32_e64 v49, s[2:3], 0, v27, s[2:3]
	v_add_co_u32_e64 v50, s[2:3], s8, v26
	v_add_co_u32_e32 v12, vcc, 0x37680000, v12
	s_nop 0
	v_addc_co_u32_e64 v51, s[2:3], 0, v27, s[2:3]
	v_add_co_u32_e64 v16, s[2:3], s0, v28
	v_addc_co_u32_e32 v13, vcc, 0, v13, vcc
	s_nop 0
	v_addc_co_u32_e64 v17, s[2:3], 0, v29, s[2:3]
	v_add_co_u32_e64 v18, s[2:3], s1, v28
	s_add_i32 s12, s12, s92
	s_nop 0
	v_addc_co_u32_e64 v19, s[2:3], 0, v29, s[2:3]
	v_add_co_u32_e64 v26, s[2:3], s8, v28
	v_lshl_add_u64 v[0:1], v[0:1], 0, s[60:61]
	s_nop 0
	v_addc_co_u32_e64 v27, s[2:3], 0, v29, s[2:3]
	global_load_dwordx4 v[28:31], v[22:23], off
	global_load_dwordx4 v[32:35], v[24:25], off
	global_load_dword v66, v[36:37], off
	global_load_dword v67, v[38:39], off
	global_load_dword v68, v[12:13], off
	s_nop 0
	global_load_dwordx4 v[36:39], v[20:21], off
	v_lshl_add_u64 v[2:3], v[2:3], 0, s[60:61]
	v_lshl_add_u64 v[4:5], v[4:5], 0, s[62:63]
	v_lshl_add_u64 v[6:7], v[6:7], 0, s[62:63]
	v_lshl_add_u64 v[8:9], v[8:9], 0, s[62:63]
	v_lshl_add_u64 v[10:11], v[10:11], 0, s[62:63]
	s_cmp_lt_i32 s12, s97
	s_waitcnt vmcnt(0) lgkmcnt(0)
	v_lshlrev_b32_e32 v53, 16, v29
	v_and_b32_e32 v57, 0xffff0000, v29
	v_max3_f32 v69, v66, v67, v68
	v_lshlrev_b32_e32 v52, 16, v36
	v_and_b32_e32 v56, 0xffff0000, v36
	v_lshlrev_b32_e32 v60, 16, v38
	v_and_b32_e32 v64, 0xffff0000, v38
	v_sub_f32_e32 v36, v66, v69
	v_sub_f32_e32 v38, v67, v69
	v_lshlrev_b32_e32 v61, 16, v31
	v_and_b32_e32 v65, 0xffff0000, v31
	v_lshlrev_b32_e32 v13, 16, v37
	v_and_b32_e32 v29, 0xffff0000, v37
	v_lshlrev_b32_e32 v59, 16, v39
	v_and_b32_e32 v31, 0xffff0000, v39
	v_sub_f32_e32 v39, v68, v69
	v_exp_f32_e32 v37, v36
	v_exp_f32_e32 v36, v38
	v_exp_f32_e32 v39, v39
	v_lshlrev_b32_e32 v12, 16, v28
	v_and_b32_e32 v28, 0xffff0000, v28
	v_add_f32_e32 v38, v37, v36
	v_add_f32_e32 v38, v39, v38
	v_div_scale_f32 v66, s[2:3], v38, v38, 1.0
	v_rcp_f32_e32 v68, v66
	v_div_scale_f32 v67, vcc, 1.0, v38, 1.0
	v_lshlrev_b32_e32 v58, 16, v30
	v_fma_f32 v69, -v66, v68, 1.0
	v_fmac_f32_e32 v68, v69, v68
	v_mul_f32_e32 v69, v67, v68
	v_fma_f32 v70, -v66, v69, v67
	v_fmac_f32_e32 v69, v70, v68
	v_fma_f32 v66, -v66, v69, v67
	v_div_fmas_f32 v66, v66, v68, v69
	v_div_fixup_f32 v38, v66, v38, 1.0
	v_pk_mul_f32 v[36:37], v[36:37], v[38:39] op_sel_hi:[1,0]
	v_mul_f32_e32 v66, v39, v38
	v_pk_mul_f32 v[38:39], v[36:37], v[52:53] op_sel:[1,0] op_sel_hi:[0,1]
	v_pk_mul_f32 v[52:53], v[36:37], v[56:57] op_sel:[1,0] op_sel_hi:[0,1]
	v_pk_mul_f32 v[56:57], v[36:37], v[60:61] op_sel:[1,0] op_sel_hi:[0,1]
	v_lshlrev_b32_e32 v55, 16, v33
	v_lshlrev_b32_e32 v54, 16, v32
	v_and_b32_e32 v33, 0xffff0000, v33
	v_and_b32_e32 v32, 0xffff0000, v32
	v_lshlrev_b32_e32 v63, 16, v35
	v_lshlrev_b32_e32 v62, 16, v34
	v_and_b32_e32 v30, 0xffff0000, v30
	v_pk_mul_f32 v[60:61], v[36:37], v[64:65] op_sel:[1,0] op_sel_hi:[0,1]
	v_pk_fma_f32 v[12:13], v[36:37], v[12:13], v[38:39]
	v_pk_fma_f32 v[28:29], v[36:37], v[28:29], v[52:53]
	v_pk_fma_f32 v[38:39], v[36:37], v[58:59], v[56:57]
	v_and_b32_e32 v35, 0xffff0000, v35
	v_and_b32_e32 v34, 0xffff0000, v34
	v_pk_fma_f32 v[30:31], v[36:37], v[30:31], v[60:61]
	v_pk_fma_f32 v[12:13], v[66:67], v[54:55], v[12:13] op_sel_hi:[0,1,1]
	v_pk_fma_f32 v[28:29], v[66:67], v[32:33], v[28:29] op_sel_hi:[0,1,1]
	v_pk_fma_f32 v[32:33], v[66:67], v[62:63], v[38:39] op_sel_hi:[0,1,1]
	v_pk_fma_f32 v[30:31], v[66:67], v[34:35], v[30:31] op_sel_hi:[0,1,1]
	v_bfe_u32 v38, v12, 16, 1
	v_bfe_u32 v39, v13, 16, 1
	v_bfe_u32 v52, v32, 16, 1
	v_bfe_u32 v53, v33, 16, 1
	v_bfe_u32 v34, v31, 16, 1
	v_bfe_u32 v35, v30, 16, 1
	v_bfe_u32 v36, v29, 16, 1
	v_bfe_u32 v37, v28, 16, 1
	v_add3_u32 v33, v33, v53, s21
	v_add3_u32 v32, v32, v52, s21
	v_add3_u32 v13, v13, v39, s21
	v_add3_u32 v12, v12, v38, s21
	v_add3_u32 v28, v28, v37, s21
	v_add3_u32 v29, v29, v36, s21
	v_add3_u32 v30, v30, v35, s21
	v_add3_u32 v31, v31, v34, s21
	v_lshrrev_b32_e32 v12, 16, v12
	v_lshrrev_b32_e32 v13, 16, v13
	v_lshrrev_b32_e32 v32, 16, v32
	v_lshrrev_b32_e32 v33, 16, v33
	v_and_or_b32 v31, v31, s15, v33
	v_and_or_b32 v30, v30, s15, v32
	v_and_or_b32 v29, v29, s15, v13
	v_and_or_b32 v28, v28, s15, v12
	global_store_dwordx4 v[14:15], v[28:31], off
	global_load_dword v58, v[40:41], off
	global_load_dword v59, v[42:43], off
	global_load_dword v60, v[44:45], off
	s_nop 0
	global_load_dwordx4 v[28:31], v[20:21], off offset:1024
	global_load_dwordx4 v[32:35], v[22:23], off offset:1024
	global_load_dwordx4 v[36:39], v[24:25], off offset:1024
	s_waitcnt vmcnt(0) lgkmcnt(0)
; __device__ __forceinline__ unsigned pk2(float lo, float hi) { return f2bf(lo) | (f2bf(hi) << 16); }
; template <int L>
; __device__ __forceinline__ void layer_body(const Args& args, LAS unsigned char* lds, const int wave, const int G, const int gw, const int NGW, const int lo, const int hi,
;                                            unsigned char* const ws_kernel, const XcdBarrier& bar, int& pid) {
;     ...
;                     for (int it = 0; it < 4; ++it) { const int e0 = 8 * (lane + 64 * it), h = e0 >> 7;
;                         const float l0 = lsebuf[((size_t)0 * (M / 2) + m) * NH + h], l1 = lsebuf[((size_t)1 * (M / 2) + m) * NH + h], l2 = lsebuf[((size_t)2 * (M / 2) + m) * NH + h];
;                         const float lm = fmaxf(l0, fmaxf(l1, l2)); float w0 = __builtin_amdgcn_exp2f(l0 - lm), w1 = __builtin_amdgcn_exp2f(l1 - lm), w2 = __builtin_amdgcn_exp2f(l2 - lm);
;                         const float wi = 1.0f / (w0 + w1 + w2); w0 *= wi; w1 *= wi; w2 *= wi;
;                         const v4u a = *(const v4u*)(opart + ((size_t)0 * (M / 2) + m) * D + e0), bq = *(const v4u*)(opart + ((size_t)1 * (M / 2) + m) * D + e0), cq2 = *(const v4u*)(opart + ((size_t)2 * (M / 2) + m) * D + e0);
;                         v4u o; o.x = pk2(w0 * bflo(a.x) + w1 * bflo(bq.x) + w2 * bflo(cq2.x), w0 * bfhi(a.x) + w1 * bfhi(bq.x) + w2 * bfhi(cq2.x));
;                         o.y = pk2(w0 * bflo(a.y) + w1 * bflo(bq.y) + w2 * bflo(cq2.y), w0 * bfhi(a.y) + w1 * bfhi(bq.y) + w2 * bfhi(cq2.y));
;                         o.z = pk2(w0 * bflo(a.z) + w1 * bflo(bq.z) + w2 * bflo(cq2.z), w0 * bfhi(a.z) + w1 * bfhi(bq.z) + w2 * bfhi(cq2.z));
;                         o.w = pk2(w0 * bflo(a.w) + w1 * bflo(bq.w) + w2 * bflo(cq2.w), w0 * bfhi(a.w) + w1 * bfhi(bq.w) + w2 * bfhi(cq2.w));
;                         *(v4u*)(obuf + (size_t)m * D + e0) = o; }
	v_max3_f32 v61, v58, v59, v60
	v_lshlrev_b32_e32 v13, 16, v29
	v_lshlrev_b32_e32 v12, 16, v32
	v_lshlrev_b32_e32 v42, 16, v36
	v_and_b32_e32 v44, 0xffff0000, v32
	v_and_b32_e32 v32, 0xffff0000, v36
	v_lshlrev_b32_e32 v36, 16, v34
	v_lshlrev_b32_e32 v54, 16, v38
	v_and_b32_e32 v56, 0xffff0000, v34
	v_and_b32_e32 v34, 0xffff0000, v38
	v_sub_f32_e32 v38, v58, v61
	v_sub_f32_e32 v58, v59, v61
	v_lshlrev_b32_e32 v41, 16, v33
	v_lshlrev_b32_e32 v43, 16, v37
	v_and_b32_e32 v45, 0xffff0000, v29
	v_and_b32_e32 v29, 0xffff0000, v33
	v_and_b32_e32 v33, 0xffff0000, v37
	v_lshlrev_b32_e32 v37, 16, v31
	v_lshlrev_b32_e32 v53, 16, v35
	v_lshlrev_b32_e32 v55, 16, v39
	v_and_b32_e32 v57, 0xffff0000, v31
	v_and_b32_e32 v31, 0xffff0000, v35
	v_and_b32_e32 v35, 0xffff0000, v39
	v_sub_f32_e32 v59, v60, v61
	v_exp_f32_e32 v39, v38
	v_exp_f32_e32 v38, v58
	v_exp_f32_e32 v59, v59
	v_lshlrev_b32_e32 v40, 16, v28
	v_and_b32_e32 v28, 0xffff0000, v28
	v_add_f32_e32 v58, v39, v38
	v_add_f32_e32 v58, v59, v58
	v_div_scale_f32 v60, s[2:3], v58, v58, 1.0
	v_rcp_f32_e32 v62, v60
	v_div_scale_f32 v61, vcc, 1.0, v58, 1.0
	v_lshlrev_b32_e32 v52, 16, v30
	v_fma_f32 v63, -v60, v62, 1.0
	v_fmac_f32_e32 v62, v63, v62
	v_mul_f32_e32 v63, v61, v62
	v_fma_f32 v64, -v60, v63, v61
	v_fmac_f32_e32 v63, v64, v62
	v_fma_f32 v60, -v60, v63, v61
	v_div_fmas_f32 v60, v60, v62, v63
	v_div_fixup_f32 v58, v60, v58, 1.0
	v_pk_mul_f32 v[38:39], v[38:39], v[58:59] op_sel_hi:[1,0]
	v_and_b32_e32 v30, 0xffff0000, v30
	v_pk_mul_f32 v[40:41], v[38:39], v[40:41] op_sel:[1,0] op_sel_hi:[0,1]
	v_pk_mul_f32 v[28:29], v[38:39], v[28:29] op_sel:[1,0] op_sel_hi:[0,1]
	v_pk_mul_f32 v[52:53], v[38:39], v[52:53] op_sel:[1,0] op_sel_hi:[0,1]
	v_mul_f32_e32 v60, v59, v58
	v_pk_mul_f32 v[30:31], v[38:39], v[30:31] op_sel:[1,0] op_sel_hi:[0,1]
	v_pk_fma_f32 v[12:13], v[38:39], v[12:13], v[40:41]
	v_pk_fma_f32 v[28:29], v[38:39], v[44:45], v[28:29]
	v_pk_fma_f32 v[36:37], v[38:39], v[36:37], v[52:53]
	v_pk_fma_f32 v[30:31], v[38:39], v[56:57], v[30:31]
	v_pk_fma_f32 v[12:13], v[60:61], v[42:43], v[12:13] op_sel_hi:[0,1,1]
	v_pk_fma_f32 v[28:29], v[60:61], v[32:33], v[28:29] op_sel_hi:[0,1,1]
	v_pk_fma_f32 v[32:33], v[60:61], v[54:55], v[36:37] op_sel_hi:[0,1,1]
	v_pk_fma_f32 v[30:31], v[60:61], v[34:35], v[30:31] op_sel_hi:[0,1,1]
	v_bfe_u32 v38, v12, 16, 1
	v_bfe_u32 v39, v13, 16, 1
	v_bfe_u32 v40, v32, 16, 1
	v_bfe_u32 v41, v33, 16, 1
	v_bfe_u32 v34, v31, 16, 1
	v_bfe_u32 v35, v30, 16, 1
	v_bfe_u32 v36, v29, 16, 1
	v_bfe_u32 v37, v28, 16, 1
	v_add3_u32 v33, v33, v41, s21
	v_add3_u32 v32, v32, v40, s21
	v_add3_u32 v13, v13, v39, s21
	v_add3_u32 v12, v12, v38, s21
	v_add3_u32 v28, v28, v37, s21
	v_add3_u32 v29, v29, v36, s21
	v_add3_u32 v30, v30, v35, s21
	v_add3_u32 v31, v31, v34, s21
	v_lshrrev_b32_e32 v12, 16, v12
	v_lshrrev_b32_e32 v13, 16, v13
	v_lshrrev_b32_e32 v32, 16, v32
	v_lshrrev_b32_e32 v33, 16, v33
	v_and_or_b32 v31, v31, s15, v33
	v_and_or_b32 v30, v30, s15, v32
	v_and_or_b32 v29, v29, s15, v13
	v_and_or_b32 v28, v28, s15, v12
	global_store_dwordx4 v[14:15], v[28:31], off offset:1024
	global_load_dword v52, v[46:47], off
	global_load_dword v53, v[48:49], off
	global_load_dword v54, v[50:51], off
	s_nop 0
	global_load_dwordx4 v[28:31], v[20:21], off offset:2048
	global_load_dwordx4 v[32:35], v[22:23], off offset:2048
	global_load_dwordx4 v[36:39], v[24:25], off offset:2048
	s_waitcnt vmcnt(0) lgkmcnt(0)
; __device__ __forceinline__ unsigned pk2(float lo, float hi) { return f2bf(lo) | (f2bf(hi) << 16); }
; template <int L>
; __device__ __forceinline__ void layer_body(const Args& args, LAS unsigned char* lds, const int wave, const int G, const int gw, const int NGW, const int lo, const int hi,
;                                            unsigned char* const ws_kernel, const XcdBarrier& bar, int& pid) {
;     ...
;                     for (int it = 0; it < 4; ++it) { const int e0 = 8 * (lane + 64 * it), h = e0 >> 7;
;                         const float l0 = lsebuf[((size_t)0 * (M / 2) + m) * NH + h], l1 = lsebuf[((size_t)1 * (M / 2) + m) * NH + h], l2 = lsebuf[((size_t)2 * (M / 2) + m) * NH + h];
;                         const float lm = fmaxf(l0, fmaxf(l1, l2)); float w0 = __builtin_amdgcn_exp2f(l0 - lm), w1 = __builtin_amdgcn_exp2f(l1 - lm), w2 = __builtin_amdgcn_exp2f(l2 - lm);
;                         const float wi = 1.0f / (w0 + w1 + w2); w0 *= wi; w1 *= wi; w2 *= wi;
;                         const v4u a = *(const v4u*)(opart + ((size_t)0 * (M / 2) + m) * D + e0), bq = *(const v4u*)(opart + ((size_t)1 * (M / 2) + m) * D + e0), cq2 = *(const v4u*)(opart + ((size_t)2 * (M / 2) + m) * D + e0);
;                         v4u o; o.x = pk2(w0 * bflo(a.x) + w1 * bflo(bq.x) + w2 * bflo(cq2.x), w0 * bfhi(a.x) + w1 * bfhi(bq.x) + w2 * bfhi(cq2.x));
;                         o.y = pk2(w0 * bflo(a.y) + w1 * bflo(bq.y) + w2 * bflo(cq2.y), w0 * bfhi(a.y) + w1 * bfhi(bq.y) + w2 * bfhi(cq2.y));
;                         o.z = pk2(w0 * bflo(a.z) + w1 * bflo(bq.z) + w2 * bflo(cq2.z), w0 * bfhi(a.z) + w1 * bfhi(bq.z) + w2 * bfhi(cq2.z));
;                         o.w = pk2(w0 * bflo(a.w) + w1 * bflo(bq.w) + w2 * bflo(cq2.w), w0 * bfhi(a.w) + w1 * bfhi(bq.w) + w2 * bfhi(cq2.w));
;                         *(v4u*)(obuf + (size_t)m * D + e0) = o; }
	v_max3_f32 v55, v52, v53, v54
	v_lshlrev_b32_e32 v13, 16, v29
	v_lshlrev_b32_e32 v12, 16, v32
	v_lshlrev_b32_e32 v42, 16, v36
	v_and_b32_e32 v44, 0xffff0000, v32
	v_and_b32_e32 v32, 0xffff0000, v36
	v_lshlrev_b32_e32 v36, 16, v34
	v_lshlrev_b32_e32 v48, 16, v38
	v_and_b32_e32 v50, 0xffff0000, v34
	v_and_b32_e32 v34, 0xffff0000, v38
	v_sub_f32_e32 v38, v52, v55
	v_sub_f32_e32 v52, v53, v55
	v_lshlrev_b32_e32 v41, 16, v33
	v_lshlrev_b32_e32 v43, 16, v37
	v_and_b32_e32 v45, 0xffff0000, v29
	v_and_b32_e32 v29, 0xffff0000, v33
	v_and_b32_e32 v33, 0xffff0000, v37
	v_lshlrev_b32_e32 v37, 16, v31
	v_lshlrev_b32_e32 v47, 16, v35
	v_lshlrev_b32_e32 v49, 16, v39
	v_and_b32_e32 v51, 0xffff0000, v31
	v_and_b32_e32 v31, 0xffff0000, v35
	v_and_b32_e32 v35, 0xffff0000, v39
	v_sub_f32_e32 v53, v54, v55
	v_exp_f32_e32 v39, v38
	v_exp_f32_e32 v38, v52
	v_exp_f32_e32 v53, v53
	v_lshlrev_b32_e32 v40, 16, v28
	v_and_b32_e32 v28, 0xffff0000, v28
	v_add_f32_e32 v52, v39, v38
	v_add_f32_e32 v52, v53, v52
	v_div_scale_f32 v54, s[2:3], v52, v52, 1.0
	v_rcp_f32_e32 v56, v54
	v_div_scale_f32 v55, vcc, 1.0, v52, 1.0
	v_lshlrev_b32_e32 v46, 16, v30
	v_fma_f32 v57, -v54, v56, 1.0
	v_fmac_f32_e32 v56, v57, v56
	v_mul_f32_e32 v57, v55, v56
	v_fma_f32 v58, -v54, v57, v55
	v_fmac_f32_e32 v57, v58, v56
	v_fma_f32 v54, -v54, v57, v55
	v_div_fmas_f32 v54, v54, v56, v57
	v_div_fixup_f32 v52, v54, v52, 1.0
	v_pk_mul_f32 v[38:39], v[38:39], v[52:53] op_sel_hi:[1,0]
	v_and_b32_e32 v30, 0xffff0000, v30
	v_pk_mul_f32 v[40:41], v[38:39], v[40:41] op_sel:[1,0] op_sel_hi:[0,1]
	v_pk_mul_f32 v[28:29], v[38:39], v[28:29] op_sel:[1,0] op_sel_hi:[0,1]
	v_pk_mul_f32 v[46:47], v[38:39], v[46:47] op_sel:[1,0] op_sel_hi:[0,1]
	v_mul_f32_e32 v54, v53, v52
	v_pk_mul_f32 v[30:31], v[38:39], v[30:31] op_sel:[1,0] op_sel_hi:[0,1]
	v_pk_fma_f32 v[12:13], v[38:39], v[12:13], v[40:41]
	v_pk_fma_f32 v[28:29], v[38:39], v[44:45], v[28:29]
	v_pk_fma_f32 v[36:37], v[38:39], v[36:37], v[46:47]
	v_pk_fma_f32 v[30:31], v[38:39], v[50:51], v[30:31]
	v_pk_fma_f32 v[12:13], v[54:55], v[42:43], v[12:13] op_sel_hi:[0,1,1]
	v_pk_fma_f32 v[28:29], v[54:55], v[32:33], v[28:29] op_sel_hi:[0,1,1]
	v_pk_fma_f32 v[32:33], v[54:55], v[48:49], v[36:37] op_sel_hi:[0,1,1]
	v_pk_fma_f32 v[30:31], v[54:55], v[34:35], v[30:31] op_sel_hi:[0,1,1]
	v_bfe_u32 v38, v12, 16, 1
	v_bfe_u32 v39, v13, 16, 1
	v_bfe_u32 v40, v32, 16, 1
	v_bfe_u32 v41, v33, 16, 1
	v_bfe_u32 v34, v31, 16, 1
	v_bfe_u32 v35, v30, 16, 1
	v_bfe_u32 v36, v29, 16, 1
	v_bfe_u32 v37, v28, 16, 1
	v_add3_u32 v33, v33, v41, s21
	v_add3_u32 v32, v32, v40, s21
	v_add3_u32 v13, v13, v39, s21
	v_add3_u32 v12, v12, v38, s21
	v_add3_u32 v28, v28, v37, s21
	v_add3_u32 v29, v29, v36, s21
	v_add3_u32 v30, v30, v35, s21
	v_add3_u32 v31, v31, v34, s21
	v_lshrrev_b32_e32 v12, 16, v12
	v_lshrrev_b32_e32 v13, 16, v13
	v_lshrrev_b32_e32 v32, 16, v32
	v_lshrrev_b32_e32 v33, 16, v33
	v_and_or_b32 v31, v31, s15, v33
	v_and_or_b32 v30, v30, s15, v32
	v_and_or_b32 v29, v29, s15, v13
	v_and_or_b32 v28, v28, s15, v12
	global_store_dwordx4 v[14:15], v[28:31], off offset:2048
	global_load_dword v40, v[16:17], off
	global_load_dword v41, v[18:19], off
	global_load_dword v42, v[26:27], off
	s_nop 0
	global_load_dwordx4 v[16:19], v[20:21], off offset:3072
	s_nop 0
	global_load_dwordx4 v[20:23], v[22:23], off offset:3072
	s_nop 0
	global_load_dwordx4 v[24:27], v[24:25], off offset:3072
	s_waitcnt vmcnt(0) lgkmcnt(0)
	v_max3_f32 v43, v40, v41, v42
	v_lshlrev_b32_e32 v13, 16, v17
	v_lshlrev_b32_e32 v12, 16, v20
	v_lshlrev_b32_e32 v30, 16, v24
	v_and_b32_e32 v32, 0xffff0000, v20
	v_and_b32_e32 v20, 0xffff0000, v24
	v_lshlrev_b32_e32 v24, 16, v22
	v_lshlrev_b32_e32 v36, 16, v26
	v_and_b32_e32 v38, 0xffff0000, v22
	v_and_b32_e32 v22, 0xffff0000, v26
	v_sub_f32_e32 v26, v40, v43
	v_sub_f32_e32 v40, v41, v43
	v_lshlrev_b32_e32 v29, 16, v21
	v_lshlrev_b32_e32 v31, 16, v25
	v_and_b32_e32 v33, 0xffff0000, v17
	v_and_b32_e32 v17, 0xffff0000, v21
	v_and_b32_e32 v21, 0xffff0000, v25
	v_lshlrev_b32_e32 v25, 16, v19
	v_lshlrev_b32_e32 v35, 16, v23
	v_lshlrev_b32_e32 v37, 16, v27
	v_and_b32_e32 v39, 0xffff0000, v19
	v_and_b32_e32 v19, 0xffff0000, v23
	v_and_b32_e32 v23, 0xffff0000, v27
	v_sub_f32_e32 v41, v42, v43
	v_exp_f32_e32 v27, v26
	v_exp_f32_e32 v26, v40
	v_exp_f32_e32 v41, v41
	v_lshlrev_b32_e32 v28, 16, v16
	v_and_b32_e32 v16, 0xffff0000, v16
	v_add_f32_e32 v40, v27, v26
	v_add_f32_e32 v40, v41, v40
	v_div_scale_f32 v42, s[2:3], v40, v40, 1.0
	v_rcp_f32_e32 v44, v42
	v_div_scale_f32 v43, vcc, 1.0, v40, 1.0
	v_lshlrev_b32_e32 v34, 16, v18
	v_fma_f32 v45, -v42, v44, 1.0
	v_fmac_f32_e32 v44, v45, v44
	v_mul_f32_e32 v45, v43, v44
	v_fma_f32 v46, -v42, v45, v43
	v_fmac_f32_e32 v45, v46, v44
	v_fma_f32 v42, -v42, v45, v43
	v_div_fmas_f32 v42, v42, v44, v45
	v_div_fixup_f32 v40, v42, v40, 1.0
	v_pk_mul_f32 v[26:27], v[26:27], v[40:41] op_sel_hi:[1,0]
	v_and_b32_e32 v18, 0xffff0000, v18
	v_pk_mul_f32 v[28:29], v[26:27], v[28:29] op_sel:[1,0] op_sel_hi:[0,1]
	v_pk_mul_f32 v[16:17], v[26:27], v[16:17] op_sel:[1,0] op_sel_hi:[0,1]
	v_pk_mul_f32 v[34:35], v[26:27], v[34:35] op_sel:[1,0] op_sel_hi:[0,1]
	v_mul_f32_e32 v42, v41, v40
	v_pk_mul_f32 v[18:19], v[26:27], v[18:19] op_sel:[1,0] op_sel_hi:[0,1]
	v_pk_fma_f32 v[12:13], v[26:27], v[12:13], v[28:29]
	v_pk_fma_f32 v[16:17], v[26:27], v[32:33], v[16:17]
	v_pk_fma_f32 v[24:25], v[26:27], v[24:25], v[34:35]
	v_pk_fma_f32 v[18:19], v[26:27], v[38:39], v[18:19]
	v_pk_fma_f32 v[12:13], v[42:43], v[30:31], v[12:13] op_sel_hi:[0,1,1]
	v_pk_fma_f32 v[16:17], v[42:43], v[20:21], v[16:17] op_sel_hi:[0,1,1]
	v_pk_fma_f32 v[20:21], v[42:43], v[36:37], v[24:25] op_sel_hi:[0,1,1]
	v_pk_fma_f32 v[18:19], v[42:43], v[22:23], v[18:19] op_sel_hi:[0,1,1]
	v_bfe_u32 v26, v12, 16, 1
	v_bfe_u32 v27, v13, 16, 1
	v_bfe_u32 v28, v20, 16, 1
	v_bfe_u32 v29, v21, 16, 1
	v_bfe_u32 v22, v19, 16, 1
	v_bfe_u32 v23, v18, 16, 1
	v_bfe_u32 v24, v17, 16, 1
	v_bfe_u32 v25, v16, 16, 1
	v_add3_u32 v21, v21, v29, s21
	v_add3_u32 v20, v20, v28, s21
	v_add3_u32 v13, v13, v27, s21
	v_add3_u32 v12, v12, v26, s21
	v_add3_u32 v16, v16, v25, s21
	v_add3_u32 v17, v17, v24, s21
	v_add3_u32 v18, v18, v23, s21
	v_add3_u32 v19, v19, v22, s21
	v_lshrrev_b32_e32 v12, 16, v12
	v_lshrrev_b32_e32 v13, 16, v13
	v_lshrrev_b32_e32 v20, 16, v20
	v_lshrrev_b32_e32 v21, 16, v21
	v_and_or_b32 v19, v19, s15, v21
	v_and_or_b32 v18, v18, s15, v20
	v_and_or_b32 v17, v17, s15, v13
	v_and_or_b32 v16, v16, s15, v12
	global_store_dwordx4 v[14:15], v[16:19], off offset:3072
	s_cbranch_scc1 .LBB0_1774

; __device__ __forceinline__ unsigned cvt_pk_bf16(float lo, float hi) { unsigned r; asm volatile("v_cvt_pk_bf16_f32 %0, %1, %2" : "=v"(r) : "v"(lo), "v"(hi)); return r; }
;     __device__ __forceinline__ void fused(f32x4 (&acc)[2][2][4][2], const Unit& un, int wr, int wc, int fr, int fq, PG8_LAS unsigned char* lds, int wid, int lane) const {
;     ...
;         const int row0 = un.pm * BM + wr * 64 + fr, col0 = un.pn * BM + wc * 32 + 8 * fq;
;         const size_t boff = (size_t)(un.pm >> 3) * bstride + col0;
;         { f32x4 gv[2][2];
; #pragma unroll
;           for (int bj = 0; bj < 2; ++bj)
; #pragma unroll
;               for (int n = 0; n < 2; ++n) gv[bj][n] = *(const f32x4*)(gate + boff + bj * HALF + n * 4);
; #pragma unroll
;           for (int ai = 0; ai < 2; ++ai)
; #pragma unroll
;               for (int m = 0; m < 4; ++m) { const size_t off = (size_t)(row0 + ai * HALF + m * 16) * ldc + col0;
; #pragma unroll
;                   for (int bj = 0; bj < 2; ++bj) {
; #pragma unroll
;                       for (int n = 0; n < 2; ++n) { f32x4 bs;
;                           if (BASE_F32) bs = *(const f32x4*)((const float*)base + off + bj * HALF + n * 4);
;                           else { const u32x2v hw = *(const u32x2v*)((const bf16_t*)base + off + bj * HALF + n * 4);
;                                  bs = (f32x4){__uint_as_float(hw.x << 16), __uint_as_float(hw.x & 0xffff0000u), __uint_as_float(hw.y << 16), __uint_as_float(hw.y & 0xffff0000u)}; }
;                           acc[ai][bj][m][n] = bs + gv[bj][n] * acc[ai][bj][m][n]; }
;                       if (out_h) { const f32x4 a0 = acc[ai][bj][m][0], a1 = acc[ai][bj][m][1]; u32x4 w; w.x = cvt_pk_bf16(a0[0], a0[1]); w.y = cvt_pk_bf16(a0[2], a0[3]); w.z = cvt_pk_bf16(a1[0], a1[1]); w.w = cvt_pk_bf16(a1[2], a1[3]);
;                           *(u32x4*)(out_h + off + bj * HALF) = w; } }
.LBB0_1844:
	v_mov_b32_e32 v32, 0
	s_barrier
	s_lshl_b32 s6, s9, 5
	v_mbcnt_lo_u32_b32 v32, -1, v32
	s_add_u32 s2, s60, 0x1a600000
	v_mbcnt_hi_u32_b32 v32, -1, v32
	s_addc_u32 s3, s61, 0
	v_or_b32_e32 v158, s33, v32
	s_lshl_b32 s7, s4, 8
	s_lshl_b32 s14, s62, 8
	s_or_b32 s6, s7, s6
	v_lshrrev_b32_e32 v32, 1, v158
	v_and_b32_e32 v159, 15, v158
	s_add_i32 s15, s14, s8
	v_and_or_b32 v152, v32, 24, s6
	s_ashr_i32 s6, s62, 3
	v_ashrrev_i32_e32 v153, 31, v152
	v_mov_b32_e32 v32, 0x3000
	v_or_b32_e32 v156, s15, v159
	v_mad_i64_i32 v[32:33], s[6:7], s6, v32, v[152:153]
	v_ashrrev_i32_e32 v157, 31, v156
	v_lshl_add_u64 v[150:151], v[32:33], 2, s[60:61]
	v_lshlrev_b64 v[32:33], 12, v[156:157]
	v_lshl_add_u64 v[32:33], s[2:3], 0, v[32:33]
	v_lshlrev_b64 v[148:149], 1, v[152:153]
	s_mov_b32 s15, 0x134000
	v_lshl_add_u64 v[154:155], v[32:33], 0, v[148:149]
	v_add_co_u32_e32 v132, vcc, s15, v150
	s_nop 0
	v_addc_co_u32_e32 v133, vcc, 0, v151, vcc
	s_mov_b64 s[6:7], 0x134000
	global_load_dwordx4 v[144:147], v[132:133], off
	v_lshl_add_u64 v[132:133], v[150:151], 0, s[6:7]
	global_load_dwordx4 v[140:143], v[132:133], off offset:16
	global_load_dwordx4 v[136:139], v[132:133], off offset:512
	s_nop 0
	global_load_dwordx4 v[132:135], v[132:133], off offset:528
	v_or_b32_e32 v164, 16, v156
	v_ashrrev_i32_e32 v165, 31, v164
	v_lshlrev_b64 v[164:165], 12, v[164:165]
	v_lshl_add_u64 v[164:165], s[2:3], 0, v[164:165]
	v_lshl_add_u64 v[164:165], v[164:165], 0, v[148:149]
	s_mov_b64 s[98:99], 0x10000
	s_mov_b64 s[100:101], 0x80000
	v_lshl_add_u64 v[232:233], v[154:155], 0, 0
	v_lshl_add_u64 v[234:235], v[232:233], 0, s[98:99]
	v_lshl_add_u64 v[236:237], v[234:235], 0, s[98:99]
	v_lshl_add_u64 v[238:239], v[236:237], 0, s[98:99]
	global_load_dwordx4 v[200:203], v[232:233], off
	global_load_dwordx4 v[204:207], v[232:233], off offset:256
	global_load_dwordx4 v[208:211], v[234:235], off
	global_load_dwordx4 v[212:215], v[234:235], off offset:256
	global_load_dwordx4 v[216:219], v[236:237], off
	global_load_dwordx4 v[220:223], v[236:237], off offset:256
	global_load_dwordx4 v[224:227], v[238:239], off
	global_load_dwordx4 v[228:231], v[238:239], off offset:256
	s_waitcnt vmcnt(0) lgkmcnt(0)
	v_lshlrev_b32_e32 v160, 16, v200
	v_and_b32_e32 v161, 0xffff0000, v200
	v_lshlrev_b32_e32 v32, 16, v201
	v_and_b32_e32 v33, 0xffff0000, v201
	v_lshlrev_b32_e32 v162, 16, v202
	v_and_b32_e32 v163, 0xffff0000, v202
	v_lshlrev_b32_e32 v34, 16, v203
	v_and_b32_e32 v35, 0xffff0000, v203
	v_pk_fma_f32 v[10:11], v[10:11], v[146:147], v[32:33]
	v_pk_fma_f32 v[8:9], v[8:9], v[144:145], v[160:161]
	v_pk_fma_f32 v[14:15], v[14:15], v[142:143], v[34:35]
	v_pk_fma_f32 v[12:13], v[12:13], v[140:141], v[162:163]
	v_cvt_pk_bf16_f32 v32, v8, v9
	v_cvt_pk_bf16_f32 v33, v10, v11
	s_nop 0
	v_cvt_pk_bf16_f32 v34, v12, v13
	v_cvt_pk_bf16_f32 v35, v14, v15
	s_nop 0
	global_store_dwordx4 v[154:155], v[32:35], off
	s_nop 1
	s_nop 0
	v_lshlrev_b32_e32 v32, 16, v204
	v_and_b32_e32 v33, 0xffff0000, v204
	v_lshlrev_b32_e32 v34, 16, v205
	v_and_b32_e32 v35, 0xffff0000, v205
	v_lshlrev_b32_e32 v160, 16, v206
	v_and_b32_e32 v161, 0xffff0000, v206
	v_lshlrev_b32_e32 v162, 16, v207
	v_and_b32_e32 v163, 0xffff0000, v207
	v_pk_fma_f32 v[34:35], v[26:27], v[138:139], v[34:35]
	v_pk_fma_f32 v[32:33], v[24:25], v[136:137], v[32:33]
	v_pk_fma_f32 v[26:27], v[18:19], v[134:135], v[162:163]
	v_pk_fma_f32 v[24:25], v[16:17], v[132:133], v[160:161]
	v_cvt_pk_bf16_f32 v16, v32, v33
	v_cvt_pk_bf16_f32 v17, v34, v35
	s_nop 0
	v_cvt_pk_bf16_f32 v18, v24, v25
	v_cvt_pk_bf16_f32 v19, v26, v27
	global_store_dwordx4 v[154:155], v[16:19], off offset:256
	s_nop 1
	v_lshlrev_b32_e32 v160, 16, v208
	v_and_b32_e32 v161, 0xffff0000, v208
	v_lshlrev_b32_e32 v16, 16, v209
	v_and_b32_e32 v17, 0xffff0000, v209
	v_lshlrev_b32_e32 v162, 16, v210
	v_and_b32_e32 v163, 0xffff0000, v210
	v_lshlrev_b32_e32 v166, 16, v211
	v_and_b32_e32 v167, 0xffff0000, v211
	v_pk_fma_f32 v[18:19], v[62:63], v[146:147], v[16:17]
	v_pk_fma_f32 v[16:17], v[60:61], v[144:145], v[160:161]
	v_pk_fma_f32 v[22:23], v[22:23], v[142:143], v[166:167]
	v_pk_fma_f32 v[20:21], v[20:21], v[140:141], v[162:163]
	v_cvt_pk_bf16_f32 v60, v16, v17
	v_cvt_pk_bf16_f32 v61, v18, v19
	v_or_b32_e32 v166, 32, v156
	v_cvt_pk_bf16_f32 v62, v20, v21
	v_cvt_pk_bf16_f32 v63, v22, v23
	v_ashrrev_i32_e32 v167, 31, v166
	v_lshlrev_b64 v[166:167], 12, v[166:167]
	global_store_dwordx4 v[164:165], v[60:63], off
	v_lshl_add_u64 v[166:167], s[2:3], 0, v[166:167]
	v_lshl_add_u64 v[166:167], v[166:167], 0, v[148:149]
	v_or_b32_e32 v156, 48, v156
	v_ashrrev_i32_e32 v157, 31, v156
	v_lshlrev_b64 v[156:157], 12, v[156:157]
	v_lshl_add_u64 v[156:157], s[2:3], 0, v[156:157]
	v_lshl_add_u64 v[156:157], v[156:157], 0, v[148:149]
	s_mov_b32 s2, 0x80000
	s_nop 1
	v_lshlrev_b32_e32 v60, 16, v212
	v_and_b32_e32 v61, 0xffff0000, v212
	v_lshlrev_b32_e32 v62, 16, v213
	v_and_b32_e32 v63, 0xffff0000, v213
	v_lshlrev_b32_e32 v160, 16, v214
	v_and_b32_e32 v161, 0xffff0000, v214
	v_lshlrev_b32_e32 v162, 16, v215
	v_and_b32_e32 v163, 0xffff0000, v215
	v_pk_fma_f32 v[62:63], v[58:59], v[138:139], v[62:63]
	v_pk_fma_f32 v[60:61], v[56:57], v[136:137], v[60:61]
	v_pk_fma_f32 v[58:59], v[50:51], v[134:135], v[162:163]
	v_pk_fma_f32 v[56:57], v[48:49], v[132:133], v[160:161]
	v_cvt_pk_bf16_f32 v48, v60, v61
	v_cvt_pk_bf16_f32 v49, v62, v63
	s_nop 0
	v_cvt_pk_bf16_f32 v50, v56, v57
	v_cvt_pk_bf16_f32 v51, v58, v59
	global_store_dwordx4 v[164:165], v[48:51], off offset:256
	s_nop 1
	v_lshlrev_b32_e32 v160, 16, v216
	v_and_b32_e32 v161, 0xffff0000, v216
	v_lshlrev_b32_e32 v48, 16, v217
	v_and_b32_e32 v49, 0xffff0000, v217
; __device__ __forceinline__ unsigned cvt_pk_bf16(float lo, float hi) { unsigned r; asm volatile("v_cvt_pk_bf16_f32 %0, %1, %2" : "=v"(r) : "v"(lo), "v"(hi)); return r; }
;     __device__ __forceinline__ void fused(f32x4 (&acc)[2][2][4][2], const Unit& un, int wr, int wc, int fr, int fq, PG8_LAS unsigned char* lds, int wid, int lane) const {
;     ...
;               for (int m = 0; m < 4; ++m) { const size_t off = (size_t)(row0 + ai * HALF + m * 16) * ldc + col0;
; #pragma unroll
;                   for (int bj = 0; bj < 2; ++bj) {
; #pragma unroll
;                       for (int n = 0; n < 2; ++n) { f32x4 bs;
;                           if (BASE_F32) bs = *(const f32x4*)((const float*)base + off + bj * HALF + n * 4);
;                           else { const u32x2v hw = *(const u32x2v*)((const bf16_t*)base + off + bj * HALF + n * 4);
;                                  bs = (f32x4){__uint_as_float(hw.x << 16), __uint_as_float(hw.x & 0xffff0000u), __uint_as_float(hw.y << 16), __uint_as_float(hw.y & 0xffff0000u)}; }
;                           acc[ai][bj][m][n] = bs + gv[bj][n] * acc[ai][bj][m][n]; }
;                       if (out_h) { const f32x4 a0 = acc[ai][bj][m][0], a1 = acc[ai][bj][m][1]; u32x4 w; w.x = cvt_pk_bf16(a0[0], a0[1]); w.y = cvt_pk_bf16(a0[2], a0[3]); w.z = cvt_pk_bf16(a1[0], a1[1]); w.w = cvt_pk_bf16(a1[2], a1[3]);
;                           *(u32x4*)(out_h + off + bj * HALF) = w; } }
	v_lshlrev_b32_e32 v162, 16, v218
	v_and_b32_e32 v163, 0xffff0000, v218
	v_lshlrev_b32_e32 v164, 16, v219
	v_and_b32_e32 v165, 0xffff0000, v219
	v_pk_fma_f32 v[50:51], v[78:79], v[146:147], v[48:49]
	v_pk_fma_f32 v[48:49], v[76:77], v[144:145], v[160:161]
	v_pk_fma_f32 v[54:55], v[54:55], v[142:143], v[164:165]
	v_pk_fma_f32 v[52:53], v[52:53], v[140:141], v[162:163]
	v_cvt_pk_bf16_f32 v76, v48, v49
	v_cvt_pk_bf16_f32 v77, v50, v51
	s_nop 0
	v_cvt_pk_bf16_f32 v78, v52, v53
	v_cvt_pk_bf16_f32 v79, v54, v55
	s_nop 0
	global_store_dwordx4 v[166:167], v[76:79], off
	s_nop 1
	s_nop 0
	v_lshlrev_b32_e32 v76, 16, v220
	v_and_b32_e32 v77, 0xffff0000, v220
	v_lshlrev_b32_e32 v78, 16, v221
	v_and_b32_e32 v79, 0xffff0000, v221
	v_lshlrev_b32_e32 v160, 16, v222
	v_and_b32_e32 v161, 0xffff0000, v222
	v_lshlrev_b32_e32 v162, 16, v223
	v_and_b32_e32 v163, 0xffff0000, v223
	v_pk_fma_f32 v[78:79], v[74:75], v[138:139], v[78:79]
	v_pk_fma_f32 v[76:77], v[72:73], v[136:137], v[76:77]
	v_pk_fma_f32 v[74:75], v[66:67], v[134:135], v[162:163]
	v_pk_fma_f32 v[72:73], v[64:65], v[132:133], v[160:161]
	v_cvt_pk_bf16_f32 v64, v76, v77
	v_cvt_pk_bf16_f32 v65, v78, v79
	s_nop 0
	v_cvt_pk_bf16_f32 v66, v72, v73
	v_cvt_pk_bf16_f32 v67, v74, v75
	global_store_dwordx4 v[166:167], v[64:67], off offset:256
	s_nop 1
	v_lshlrev_b32_e32 v160, 16, v224
	v_and_b32_e32 v161, 0xffff0000, v224
	v_lshlrev_b32_e32 v64, 16, v225
	v_and_b32_e32 v65, 0xffff0000, v225
	v_lshlrev_b32_e32 v162, 16, v226
	v_and_b32_e32 v163, 0xffff0000, v226
	v_lshlrev_b32_e32 v164, 16, v227
	v_and_b32_e32 v165, 0xffff0000, v227
	v_pk_fma_f32 v[66:67], v[130:131], v[146:147], v[64:65]
	v_pk_fma_f32 v[64:65], v[128:129], v[144:145], v[160:161]
	v_pk_fma_f32 v[70:71], v[70:71], v[142:143], v[164:165]
	v_pk_fma_f32 v[68:69], v[68:69], v[140:141], v[162:163]
	v_cvt_pk_bf16_f32 v128, v64, v65
	v_cvt_pk_bf16_f32 v129, v66, v67
	v_add_co_u32_e32 v164, vcc, s2, v154
	v_cvt_pk_bf16_f32 v130, v68, v69
	v_cvt_pk_bf16_f32 v131, v70, v71
	s_nop 0
	v_addc_co_u32_e32 v165, vcc, 0, v155, vcc
	global_store_dwordx4 v[156:157], v[128:131], off
	s_mov_b64 s[2:3], 0x80000
	s_nop 1
	v_lshlrev_b32_e32 v128, 16, v228
	v_and_b32_e32 v129, 0xffff0000, v228
	v_lshlrev_b32_e32 v130, 16, v229
	v_and_b32_e32 v131, 0xffff0000, v229
	v_lshlrev_b32_e32 v160, 16, v230
	v_and_b32_e32 v161, 0xffff0000, v230
	v_lshlrev_b32_e32 v162, 16, v231
	v_and_b32_e32 v163, 0xffff0000, v231
	v_pk_fma_f32 v[110:111], v[110:111], v[138:139], v[130:131]
	v_pk_fma_f32 v[108:109], v[108:109], v[136:137], v[128:129]
	v_pk_fma_f32 v[98:99], v[98:99], v[134:135], v[162:163]
	v_pk_fma_f32 v[96:97], v[96:97], v[132:133], v[160:161]
	v_cvt_pk_bf16_f32 v128, v108, v109
	v_cvt_pk_bf16_f32 v129, v110, v111
	s_nop 0
	v_cvt_pk_bf16_f32 v130, v96, v97
	v_cvt_pk_bf16_f32 v131, v98, v99
	global_store_dwordx4 v[156:157], v[128:131], off offset:256
	v_lshl_add_u64 v[156:157], v[154:155], 0, s[2:3]
	s_mov_b32 s2, 0x90000
	v_add_co_u32_e32 v166, vcc, s2, v154
	s_mov_b64 s[2:3], 0x90000
	s_nop 0
	v_addc_co_u32_e32 v167, vcc, 0, v155, vcc
	v_lshl_add_u64 v[232:233], v[232:233], 0, s[100:101]
	v_lshl_add_u64 v[234:235], v[234:235], 0, s[100:101]
	v_lshl_add_u64 v[236:237], v[236:237], 0, s[100:101]
	v_lshl_add_u64 v[238:239], v[238:239], 0, s[100:101]
	global_load_dwordx4 v[200:203], v[232:233], off
	global_load_dwordx4 v[204:207], v[232:233], off offset:256
	global_load_dwordx4 v[208:211], v[234:235], off
	global_load_dwordx4 v[212:215], v[234:235], off offset:256
	global_load_dwordx4 v[216:219], v[236:237], off
	global_load_dwordx4 v[220:223], v[236:237], off offset:256
	global_load_dwordx4 v[224:227], v[238:239], off
	global_load_dwordx4 v[228:231], v[238:239], off offset:256
	s_waitcnt vmcnt(0) lgkmcnt(0)
	v_lshlrev_b32_e32 v160, 16, v200
	v_and_b32_e32 v161, 0xffff0000, v200
	v_lshlrev_b32_e32 v128, 16, v201
	v_and_b32_e32 v129, 0xffff0000, v201
	v_lshlrev_b32_e32 v162, 16, v202
	v_and_b32_e32 v163, 0xffff0000, v202
	v_lshlrev_b32_e32 v130, 16, v203
	v_and_b32_e32 v131, 0xffff0000, v203
	v_pk_fma_f32 v[102:103], v[102:103], v[146:147], v[128:129]
	v_pk_fma_f32 v[100:101], v[100:101], v[144:145], v[160:161]
	v_pk_fma_f32 v[106:107], v[106:107], v[142:143], v[130:131]
	v_pk_fma_f32 v[104:105], v[104:105], v[140:141], v[162:163]
	v_cvt_pk_bf16_f32 v128, v100, v101
	v_cvt_pk_bf16_f32 v129, v102, v103
	s_nop 0
	v_cvt_pk_bf16_f32 v130, v104, v105
	v_cvt_pk_bf16_f32 v131, v106, v107
	s_nop 0
	global_store_dwordx4 v[164:165], v[128:131], off
	s_nop 1
	s_nop 0
	v_lshlrev_b32_e32 v128, 16, v204
	v_and_b32_e32 v129, 0xffff0000, v204
	v_lshlrev_b32_e32 v130, 16, v205
	v_and_b32_e32 v131, 0xffff0000, v205
	v_lshlrev_b32_e32 v160, 16, v206
	v_and_b32_e32 v161, 0xffff0000, v206
	v_lshlrev_b32_e32 v162, 16, v207
	v_and_b32_e32 v163, 0xffff0000, v207
	v_pk_fma_f32 v[126:127], v[126:127], v[138:139], v[130:131]
	v_pk_fma_f32 v[124:125], v[124:125], v[136:137], v[128:129]
	v_pk_fma_f32 v[114:115], v[114:115], v[134:135], v[162:163]
	v_pk_fma_f32 v[112:113], v[112:113], v[132:133], v[160:161]
	v_cvt_pk_bf16_f32 v128, v124, v125
	v_cvt_pk_bf16_f32 v129, v126, v127
	s_nop 0
	v_cvt_pk_bf16_f32 v130, v112, v113
	v_cvt_pk_bf16_f32 v131, v114, v115
	global_store_dwordx4 v[156:157], v[128:131], off offset:256
	v_lshl_add_u64 v[156:157], v[154:155], 0, s[2:3]
	s_mov_b32 s2, 0xa0000
	v_add_co_u32_e32 v164, vcc, s2, v154
	s_mov_b64 s[2:3], 0xa0000
	s_nop 0
	v_addc_co_u32_e32 v165, vcc, 0, v155, vcc
	s_nop 1
	v_lshlrev_b32_e32 v160, 16, v208
	v_and_b32_e32 v161, 0xffff0000, v208
	v_lshlrev_b32_e32 v128, 16, v209
	v_and_b32_e32 v129, 0xffff0000, v209
	v_lshlrev_b32_e32 v162, 16, v210
; __device__ __forceinline__ unsigned cvt_pk_bf16(float lo, float hi) { unsigned r; asm volatile("v_cvt_pk_bf16_f32 %0, %1, %2" : "=v"(r) : "v"(lo), "v"(hi)); return r; }
;     __device__ __forceinline__ void fused(f32x4 (&acc)[2][2][4][2], const Unit& un, int wr, int wc, int fr, int fq, PG8_LAS unsigned char* lds, int wid, int lane) const {
;     ...
;               for (int m = 0; m < 4; ++m) { const size_t off = (size_t)(row0 + ai * HALF + m * 16) * ldc + col0;
; #pragma unroll
;                   for (int bj = 0; bj < 2; ++bj) {
; #pragma unroll
;                       for (int n = 0; n < 2; ++n) { f32x4 bs;
;                           if (BASE_F32) bs = *(const f32x4*)((const float*)base + off + bj * HALF + n * 4);
;                           else { const u32x2v hw = *(const u32x2v*)((const bf16_t*)base + off + bj * HALF + n * 4);
;                                  bs = (f32x4){__uint_as_float(hw.x << 16), __uint_as_float(hw.x & 0xffff0000u), __uint_as_float(hw.y << 16), __uint_as_float(hw.y & 0xffff0000u)}; }
;                           acc[ai][bj][m][n] = bs + gv[bj][n] * acc[ai][bj][m][n]; }
;                       if (out_h) { const f32x4 a0 = acc[ai][bj][m][0], a1 = acc[ai][bj][m][1]; u32x4 w; w.x = cvt_pk_bf16(a0[0], a0[1]); w.y = cvt_pk_bf16(a0[2], a0[3]); w.z = cvt_pk_bf16(a1[0], a1[1]); w.w = cvt_pk_bf16(a1[2], a1[3]);
;                           *(u32x4*)(out_h + off + bj * HALF) = w; } }
;                   asm volatile("" : "+v"(acc[ai][0][m][0]), "+v"(acc[ai][0][m][1]), "+v"(acc[ai][1][m][0]), "+v"(acc[ai][1][m][1]));
;                   asm volatile("" ::: "memory"); } }
; #pragma unroll
;         for (int ai = 0; ai < 2; ++ai)
; #pragma unroll
;             for (int m = 0; m < 4; ++m) { float s = 0.f;
; #pragma unroll
;                 for (int bj = 0; bj < 2; ++bj)
; #pragma unroll
;                     for (int n = 0; n < 2; ++n) { const f32x4 x = acc[ai][bj][m][n]; s += (x[0] * x[0] + x[1] * x[1]) + (x[2] * x[2] + x[3] * x[3]); }
;                 s += __shfl_xor(s, 16); s += __shfl_xor(s, 32);
;                 if (fq == 0) P[(ai * HALF + wr * 64 + m * 16 + fr) * 4 + wc] = s; }
	v_and_b32_e32 v163, 0xffff0000, v210
	v_lshlrev_b32_e32 v130, 16, v211
	v_and_b32_e32 v131, 0xffff0000, v211
	v_pk_fma_f32 v[118:119], v[118:119], v[146:147], v[128:129]
	v_pk_fma_f32 v[116:117], v[116:117], v[144:145], v[160:161]
	v_pk_fma_f32 v[122:123], v[122:123], v[142:143], v[130:131]
	v_pk_fma_f32 v[120:121], v[120:121], v[140:141], v[162:163]
	v_cvt_pk_bf16_f32 v128, v116, v117
	v_cvt_pk_bf16_f32 v129, v118, v119
	s_nop 0
	v_cvt_pk_bf16_f32 v130, v120, v121
	v_cvt_pk_bf16_f32 v131, v122, v123
	s_nop 0
	global_store_dwordx4 v[166:167], v[128:131], off
	s_nop 1
	s_nop 0
	v_lshlrev_b32_e32 v128, 16, v212
	v_and_b32_e32 v129, 0xffff0000, v212
	v_lshlrev_b32_e32 v130, 16, v213
	v_and_b32_e32 v131, 0xffff0000, v213
	v_lshlrev_b32_e32 v160, 16, v214
	v_and_b32_e32 v161, 0xffff0000, v214
	v_lshlrev_b32_e32 v162, 16, v215
	v_and_b32_e32 v163, 0xffff0000, v215
	v_pk_fma_f32 v[94:95], v[94:95], v[138:139], v[130:131]
	v_pk_fma_f32 v[92:93], v[92:93], v[136:137], v[128:129]
	v_pk_fma_f32 v[90:91], v[90:91], v[134:135], v[162:163]
	v_pk_fma_f32 v[88:89], v[88:89], v[132:133], v[160:161]
	v_cvt_pk_bf16_f32 v128, v92, v93
	v_cvt_pk_bf16_f32 v129, v94, v95
	s_nop 0
	v_cvt_pk_bf16_f32 v130, v88, v89
	v_cvt_pk_bf16_f32 v131, v90, v91
	global_store_dwordx4 v[156:157], v[128:131], off offset:256
	v_lshl_add_u64 v[156:157], v[154:155], 0, s[2:3]
	s_mov_b32 s2, 0xb0000
	v_add_co_u32_e32 v166, vcc, s2, v154
	s_mov_b64 s[2:3], 0xb0000
	s_nop 0
	v_addc_co_u32_e32 v167, vcc, 0, v155, vcc
	s_nop 1
	v_lshlrev_b32_e32 v160, 16, v216
	v_and_b32_e32 v161, 0xffff0000, v216
	v_lshlrev_b32_e32 v128, 16, v217
	v_and_b32_e32 v129, 0xffff0000, v217
	v_lshlrev_b32_e32 v162, 16, v218
	v_and_b32_e32 v163, 0xffff0000, v218
	v_lshlrev_b32_e32 v130, 16, v219
	v_and_b32_e32 v131, 0xffff0000, v219
	v_pk_fma_f32 v[86:87], v[86:87], v[146:147], v[128:129]
	v_pk_fma_f32 v[84:85], v[84:85], v[144:145], v[160:161]
	v_pk_fma_f32 v[82:83], v[82:83], v[142:143], v[130:131]
	v_pk_fma_f32 v[80:81], v[80:81], v[140:141], v[162:163]
	v_cvt_pk_bf16_f32 v128, v84, v85
	v_cvt_pk_bf16_f32 v129, v86, v87
	s_nop 0
	v_cvt_pk_bf16_f32 v130, v80, v81
	v_cvt_pk_bf16_f32 v131, v82, v83
	s_nop 0
	global_store_dwordx4 v[164:165], v[128:131], off
	v_mul_f32_e32 v164, v25, v25
	v_mul_f32_e32 v165, v27, v27
	v_fmac_f32_e32 v164, v24, v24
	v_fmac_f32_e32 v165, v26, v26
	s_nop 1
	v_lshlrev_b32_e32 v128, 16, v220
	v_and_b32_e32 v129, 0xffff0000, v220
	v_lshlrev_b32_e32 v130, 16, v221
	v_and_b32_e32 v131, 0xffff0000, v221
	v_lshlrev_b32_e32 v160, 16, v222
	v_and_b32_e32 v161, 0xffff0000, v222
	v_lshlrev_b32_e32 v162, 16, v223
	v_and_b32_e32 v163, 0xffff0000, v223
	v_pk_fma_f32 v[46:47], v[46:47], v[138:139], v[130:131]
	v_pk_fma_f32 v[44:45], v[44:45], v[136:137], v[128:129]
	v_pk_fma_f32 v[42:43], v[42:43], v[134:135], v[162:163]
	v_pk_fma_f32 v[40:41], v[40:41], v[132:133], v[160:161]
	v_cvt_pk_bf16_f32 v128, v44, v45
	v_cvt_pk_bf16_f32 v129, v46, v47
	v_lshl_add_u64 v[160:161], v[154:155], 0, s[2:3]
	v_cvt_pk_bf16_f32 v130, v40, v41
	v_cvt_pk_bf16_f32 v131, v42, v43
	global_store_dwordx4 v[156:157], v[128:131], off offset:256
	v_mul_f32_e32 v162, v33, v33
	v_mul_f32_e32 v163, v35, v35
	v_fmac_f32_e32 v162, v32, v32
	v_fmac_f32_e32 v163, v34, v34
	s_lshl_b32 s2, s9, 2
	s_add_i32 s2, s2, 0
	s_nop 1
	v_lshlrev_b32_e32 v154, 16, v224
	v_and_b32_e32 v155, 0xffff0000, v224
	v_lshlrev_b32_e32 v128, 16, v225
	v_and_b32_e32 v129, 0xffff0000, v225
	v_lshlrev_b32_e32 v156, 16, v226
	v_and_b32_e32 v157, 0xffff0000, v226
	v_lshlrev_b32_e32 v130, 16, v227
	v_and_b32_e32 v131, 0xffff0000, v227
	v_pk_fma_f32 v[38:39], v[38:39], v[146:147], v[128:129]
	v_pk_fma_f32 v[36:37], v[36:37], v[144:145], v[154:155]
	v_pk_fma_f32 v[30:31], v[30:31], v[142:143], v[130:131]
	v_pk_fma_f32 v[28:29], v[28:29], v[140:141], v[156:157]
	v_cvt_pk_bf16_f32 v142, v36, v37
	v_cvt_pk_bf16_f32 v143, v38, v39
	v_mbcnt_lo_u32_b32 v128, -1, 0
	v_cvt_pk_bf16_f32 v144, v28, v29
	v_cvt_pk_bf16_f32 v145, v30, v31
	v_mbcnt_hi_u32_b32 v129, -1, v128
	v_mul_f32_e32 v140, v9, v9
	v_mul_f32_e32 v141, v11, v11
	v_mul_f32_e32 v146, v13, v13
	v_mul_f32_e32 v147, v15, v15
	v_and_b32_e32 v130, 64, v129
	v_fmac_f32_e32 v140, v8, v8
	v_fmac_f32_e32 v141, v10, v10
	v_fmac_f32_e32 v146, v12, v12
	v_fmac_f32_e32 v147, v14, v14
	v_xor_b32_e32 v128, 16, v129
	v_add_u32_e32 v130, 64, v130
	v_add_f32_e32 v140, v140, v141
	v_add_f32_e32 v141, v146, v147
	v_cmp_lt_i32_e32 vcc, v128, v130
	v_add_f32_e32 v146, v162, v163
	v_add_f32_e32 v140, v140, v141
	v_cndmask_b32_e32 v128, v129, v128, vcc
	v_add_f32_e32 v147, v164, v165
	v_add_f32_e32 v140, v146, v140
	v_lshlrev_b32_e32 v128, 2, v128
	v_add_f32_e32 v140, v147, v140
	ds_bpermute_b32 v141, v128, v140
	v_xor_b32_e32 v131, 32, v129
	v_cmp_lt_i32_e32 vcc, v131, v130
	global_store_dwordx4 v[166:167], v[142:145], off
	v_and_b32_e32 v130, 63, v158
	v_cndmask_b32_e32 v129, v129, v131, vcc
	v_lshlrev_b32_e32 v129, 2, v129
	s_waitcnt lgkmcnt(0)
	v_add_f32_e32 v140, v140, v141
	ds_bpermute_b32 v141, v129, v140
	v_cmp_gt_u32_e32 vcc, 16, v130
	s_waitcnt vmcnt(0)
	v_lshlrev_b32_e32 v142, 16, v228
	v_and_b32_e32 v143, 0xffff0000, v228
	v_lshlrev_b32_e32 v144, 16, v229
	v_and_b32_e32 v145, 0xffff0000, v229
	v_lshlrev_b32_e32 v146, 16, v230
	v_and_b32_e32 v147, 0xffff0000, v230
	v_lshlrev_b32_e32 v154, 16, v231
	v_and_b32_e32 v155, 0xffff0000, v231
	v_pk_fma_f32 v[6:7], v[6:7], v[138:139], v[144:145]
	v_pk_fma_f32 v[4:5], v[4:5], v[136:137], v[142:143]
	v_pk_fma_f32 v[2:3], v[2:3], v[134:135], v[154:155]
	v_pk_fma_f32 v[0:1], v[0:1], v[132:133], v[146:147]
	v_cvt_pk_bf16_f32 v132, v4, v5
	v_cvt_pk_bf16_f32 v133, v6, v7
	v_or_b32_e32 v144, s8, v159
	v_cvt_pk_bf16_f32 v134, v0, v1
	v_cvt_pk_bf16_f32 v135, v2, v3
	global_store_dwordx4 v[160:161], v[132:135], off offset:256
	v_lshl_add_u32 v131, v144, 4, s2
	s_and_saveexec_b64 s[2:3], vcc
	v_readlane_b32 s96, v254, 47
	s_cbranch_execz .LBB0_1846
	s_waitcnt lgkmcnt(0)
	v_add_f32_e32 v132, v140, v141
	ds_write_b32 v131, v132

;     __device__ __forceinline__ void fused(f32x4 (&acc)[2][2][4][2], const Unit& un, int wr, int wc, int fr, int fq, PG8_LAS unsigned char* lds, int wid, int lane) const {
;     ...
;         asm volatile("s_waitcnt lgkmcnt(0)" ::: "memory"); __builtin_amdgcn_s_barrier(); asm volatile("" ::: "memory");
;         const int row = wid * 32 + (lane & 31);
;         if (lane < 32) { const float tot = (P[row * 4 + 0] + P[row * 4 + 1]) + (P[row * 4 + 2] + P[row * 4 + 3]);
;             __hip_atomic_store(xbuf + ((size_t)(un.pm * BM + row) * 8 + un.pn), __float_as_uint(tot), __ATOMIC_RELAXED, __HIP_MEMORY_SCOPE_AGENT); }
.LBB0_1860:
	s_or_b64 exec, exec, s[2:3]
	s_add_u32 s64, s60, 0x3c680000
	s_addc_u32 s65, s61, 0
	s_lshl_b32 s1, s1, 5
	s_waitcnt lgkmcnt(0)
	s_barrier
	v_and_or_b32 v134, v158, 31, s1
	v_add_u32_e32 v128, s14, v134
	v_cmp_gt_u32_e64 s[2:3], 32, v130
	s_waitcnt lgkmcnt(0)
	v_ashrrev_i32_e32 v129, 31, v128
	s_and_saveexec_b64 s[6:7], s[2:3]
	s_cbranch_execz .LBB0_1862
	v_lshl_add_u32 v131, v134, 4, 0
	ds_read_b128 v[136:139], v131
	v_lshlrev_b64 v[132:133], 5, v[128:129]
	v_lshl_add_u64 v[132:133], s[64:65], 0, v[132:133]
	v_lshl_add_u64 v[132:133], s[4:5], 2, v[132:133]
	s_waitcnt lgkmcnt(0)
	v_mov_b32_e32 v140, v137
	v_mov_b32_e32 v141, v138
	v_mov_b32_e32 v137, v139
	v_pk_add_f32 v[136:137], v[140:141], v[136:137]
	s_nop 0
	v_pk_add_f32 v[136:137], v[136:137], v[136:137] op_sel:[0,1] op_sel_hi:[1,0]
	global_store_dword v[132:133], v136, off sc1

;     __device__ __forceinline__ void fused(f32x4 (&acc)[2][2][4][2], const Unit& un, int wr, int wc, int fr, int fq, PG8_LAS unsigned char* lds, int wid, int lane) const {
;     ...
;             for (;;) {
;                 if ((unsigned)__builtin_amdgcn_readfirstlane(__hip_atomic_load(cnt + 64 * un.pm, __ATOMIC_RELAXED, __HIP_MEMORY_SCOPE_AGENT)) >= 64u) break;
;                 if (__builtin_amdgcn_s_memrealtime() - t0 > 2000000ull) {
;                     if (lane == 0) { unsigned expect = 0u; __hip_atomic_compare_exchange_strong(tmo + 1, &expect, code | (unsigned)(un.pm & 0xff), __ATOMIC_RELAXED, __ATOMIC_RELAXED, __HIP_MEMORY_SCOPE_AGENT);
;                                      __hip_atomic_store(tmo, 1u, __ATOMIC_RELAXED, __HIP_MEMORY_SCOPE_AGENT); }
;                     dead = true; break; }
;                 __builtin_amdgcn_s_sleep(2);
;             }
.LBB0_1868:
	global_load_dword v135, v[130:131], off sc1
	s_mov_b64 s[68:69], -1
	s_mov_b64 s[70:71], -1
	s_waitcnt vmcnt(0) lgkmcnt(0)
	v_readfirstlane_b32 s0, v135
	s_cmp_gt_u32 s0, 63
	s_cbranch_scc1 .LBB0_1867
	s_memrealtime s[0:1]
	s_waitcnt lgkmcnt(0)
	s_sub_u32 s0, s0, s66
	s_subb_u32 s1, s1, s67
	v_cmp_lt_u64_e32 vcc, s[0:1], v[132:133]
	s_cbranch_vccz .LBB0_1866
	s_mov_b64 s[70:71], 0
	s_sleep 2
	s_branch .LBB0_1866

;     __device__ __forceinline__ void fused(f32x4 (&acc)[2][2][4][2], const Unit& un, int wr, int wc, int fr, int fq, PG8_LAS unsigned char* lds, int wid, int lane) const {
;     ...
;                 if (__builtin_amdgcn_s_memrealtime() - t0 > 2000000ull) {
;                     if (lane == 0) { unsigned expect = 0u; __hip_atomic_compare_exchange_strong(tmo + 1, &expect, code | (unsigned)(un.pm & 0xff), __ATOMIC_RELAXED, __ATOMIC_RELAXED, __HIP_MEMORY_SCOPE_AGENT);
;                                      __hip_atomic_store(tmo, 1u, __ATOMIC_RELAXED, __HIP_MEMORY_SCOPE_AGENT); }
;                     dead = true; break; }
.LBB0_1874:
	s_or_saveexec_b64 s[66:67], s[6:7]
	s_mov_b64 s[6:7], 0
	s_xor_b64 exec, exec, s[66:67]
	s_cbranch_execz .LBB0_1876
	s_and_b32 s0, s62, 0xdf
	s_or_b32 s0, s0, 0x720
	v_mov_b32_e32 v130, s0
	v_mov_b32_e32 v131, 0
	v_mov_b64_e32 v[132:133], s[60:61]
	flat_atomic_cmpswap v[132:133], v[130:131] offset:4
	s_mov_b64 s[6:7], exec
	v_mov_b32_e32 v130, 1
	global_store_dword v[132:133], v130, off sc1

;     __device__ __forceinline__ void fused(f32x4 (&acc)[2][2][4][2], const Unit& un, int wr, int wc, int fr, int fq, PG8_LAS unsigned char* lds, int wid, int lane) const {
;     ...
;         asm volatile("s_waitcnt vmcnt(0) lgkmcnt(0)" ::: "memory"); __builtin_amdgcn_s_barrier(); asm volatile("" ::: "memory");
;         const bool bad = flag[0] != 0u;
;         if (lane < 32) { const unsigned* slot = xbuf + (size_t)(un.pm * BM + row) * 8; float q = 0.f;
; #pragma unroll
;             for (int t = 0; t < 8; ++t) q += __uint_as_float(__hip_atomic_load(slot + t, __ATOMIC_RELAXED, __HIP_MEMORY_SCOPE_AGENT));
;             S[row] = 1.0f / sqrtf(q * (1.0f / 2048.0f) + eps); }
;         asm volatile("s_waitcnt lgkmcnt(0)" ::: "memory"); __builtin_amdgcn_s_barrier(); asm volatile("" ::: "memory");
;         const float qnan = __builtin_nanf("");
;         f32x4 cg[2][2], sh[2][2];
; #pragma unroll
;         for (int bj = 0; bj < 2; ++bj)
; #pragma unroll
;             for (int n = 0; n < 2; ++n) { const f32x4 g4 = *(const f32x4*)(gain + col0 + bj * HALF + n * 4);
;                 if (MODE == 0) { const f32x4 sc4 = *(const f32x4*)(scale + boff + bj * HALF + n * 4); cg[bj][n] = g4 * (sc4 + 1.0f); sh[bj][n] = *(const f32x4*)(shift + boff + bj * HALF + n * 4); }
;                 else { cg[bj][n] = g4; sh[bj][n] = (f32x4){0.f, 0.f, 0.f, 0.f}; } }
; #pragma unroll
;         for (int ai = 0; ai < 2; ++ai)
; #pragma unroll
;             for (int m = 0; m < 4; ++m) { const int r = ai * HALF + wr * 64 + m * 16 + fr; const float rs = S[r]; const size_t off = (size_t)(un.pm * BM + r) * ldc + col0;
; #pragma unroll
;                 for (int bj = 0; bj < 2; ++bj) { f32x4 y0 = (acc[ai][bj][m][0] * rs) * cg[bj][0] + sh[bj][0], y1 = (acc[ai][bj][m][1] * rs) * cg[bj][1] + sh[bj][1];
.LBB0_1882:
	s_waitcnt vmcnt(0) lgkmcnt(0)
	s_barrier
	v_mov_b32_e32 v130, 0
	ds_read_b32 v158, v130 offset:5120
	s_and_saveexec_b64 s[4:5], s[2:3]
	s_cbranch_execz .LBB0_1884
	v_lshlrev_b64 v[128:129], 5, v[128:129]
	v_lshl_add_u64 v[128:129], s[64:65], 0, v[128:129]
	global_load_dword v130, v[128:129], off sc1
	global_load_dword v131, v[128:129], off offset:4 sc1
	global_load_dword v132, v[128:129], off offset:8 sc1
	global_load_dword v133, v[128:129], off offset:12 sc1
	global_load_dword v135, v[128:129], off offset:16 sc1
	global_load_dword v136, v[128:129], off offset:20 sc1
	global_load_dword v137, v[128:129], off offset:24 sc1
	s_nop 0
	global_load_dword v128, v[128:129], off offset:28 sc1
	v_mov_b32_e32 v129, 0x358637bd
	s_mov_b32 s0, 0xf800000
	s_waitcnt vmcnt(0) lgkmcnt(0)
	v_add_f32_e32 v130, 0, v130
	v_add_f32_e32 v130, v130, v131
	v_add_f32_e32 v130, v130, v132
	v_add_f32_e32 v130, v130, v133
	v_add_f32_e32 v130, v130, v135
	v_add_f32_e32 v130, v130, v136
	v_add_f32_e32 v130, v130, v137
	v_add_f32_e32 v128, v130, v128
	v_fmac_f32_e32 v129, 0x3a000000, v128
	v_mul_f32_e32 v128, 0x4f800000, v129
	v_cmp_gt_f32_e32 vcc, s0, v129
	v_mov_b32_e32 v130, 0x260
	s_nop 0
	v_cndmask_b32_e32 v128, v129, v128, vcc
	v_sqrt_f32_e32 v129, v128
	s_nop 0
	v_add_u32_e32 v131, -1, v129
	v_add_u32_e32 v132, 1, v129
	v_fma_f32 v133, -v131, v129, v128
	v_fma_f32 v135, -v132, v129, v128
	v_cmp_ge_f32_e64 s[2:3], 0, v133
	s_nop 1
	v_cndmask_b32_e64 v129, v129, v131, s[2:3]
	v_cmp_lt_f32_e64 s[2:3], 0, v135
	s_nop 1
	v_cndmask_b32_e64 v129, v129, v132, s[2:3]
	v_mul_f32_e32 v131, 0x37800000, v129
	v_cndmask_b32_e32 v129, v129, v131, vcc
	v_cmp_class_f32_e32 vcc, v128, v130
	s_nop 1
	v_cndmask_b32_e32 v128, v129, v128, vcc
	v_div_scale_f32 v129, s[0:1], v128, v128, 1.0
	v_rcp_f32_e32 v130, v129
	v_div_scale_f32 v131, vcc, 1.0, v128, 1.0
	v_fma_f32 v132, -v129, v130, 1.0
	v_fmac_f32_e32 v130, v132, v130
	v_mul_f32_e32 v132, v131, v130
	v_fma_f32 v133, -v129, v132, v131
	v_fmac_f32_e32 v132, v133, v130
	v_fma_f32 v129, -v129, v132, v131
	v_div_fmas_f32 v129, v129, v130, v132
	v_div_fixup_f32 v128, v129, v128, 1.0
	v_lshl_add_u32 v129, v134, 2, 0
	ds_write_b32 v129, v128 offset:4096
.LBB0_1884:
	s_or_b64 exec, exec, s[4:5]
	v_readlane_b32 s36, v254, 11
	v_readlane_b32 s42, v254, 17
	v_readlane_b32 s43, v254, 18
	s_mov_b64 s[0:1], 0x2000
	s_waitcnt lgkmcnt(0)
	s_barrier
	v_lshl_add_u64 v[128:129], v[152:153], 2, s[42:43]
	v_lshl_add_u64 v[130:131], v[128:129], 0, s[0:1]
	s_mov_b64 s[0:1], 0x138000
	v_lshl_add_u64 v[136:137], v[150:151], 0, s[0:1]
	s_mov_b64 s[0:1], 0x136000
	v_lshl_add_u64 v[138:139], v[150:151], 0, s[0:1]
	s_movk_i32 s0, 0x2000
	v_add_co_u32_e32 v128, vcc, s0, v128
	s_mov_b32 s0, 0x138000
	s_nop 0
	v_addc_co_u32_e32 v129, vcc, 0, v129, vcc
	global_load_dwordx4 v[160:163], v[128:129], off
	global_load_dwordx4 v[152:155], v[136:137], off offset:16
	v_add_co_u32_e32 v128, vcc, s0, v150
	global_load_dwordx4 v[164:167], v[136:137], off offset:512
	global_load_dwordx4 v[132:135], v[138:139], off offset:16
	global_load_dwordx4 v[168:171], v[136:137], off offset:528
	global_load_dwordx4 v[172:175], v[130:131], off offset:16
	global_load_dwordx4 v[176:179], v[130:131], off offset:512
	v_addc_co_u32_e32 v129, vcc, 0, v151, vcc
	global_load_dwordx4 v[180:183], v[130:131], off offset:528
	global_load_dwordx4 v[184:187], v[128:129], off
	s_mov_b32 s0, 0x136000
	v_add_co_u32_e32 v128, vcc, s0, v150
	v_lshl_add_u32 v157, v144, 2, 0
	s_nop 0
	v_addc_co_u32_e32 v129, vcc, 0, v151, vcc
	global_load_dwordx4 v[140:143], v[128:129], off
	s_nop 0
	global_load_dwordx4 v[128:131], v[138:139], off offset:512
	s_nop 0
	global_load_dwordx4 v[136:139], v[138:139], off offset:528
	ds_read_b32 v188, v157 offset:4096
	v_add_u32_e32 v144, s14, v144
	s_add_u32 s2, s60, 0x1e600000
	v_ashrrev_i32_e32 v145, 31, v144
	s_addc_u32 s3, s61, 0
	v_lshlrev_b64 v[146:147], 12, v[144:145]
	s_waitcnt lgkmcnt(0)
	v_pk_mul_f32 v[192:193], v[8:9], v[188:189] op_sel_hi:[1,0]
	v_pk_mul_f32 v[194:195], v[10:11], v[188:189] op_sel_hi:[1,0]
	v_lshl_add_u64 v[190:191], s[2:3], 0, v[146:147]
	v_pk_mul_f32 v[196:197], v[12:13], v[188:189] op_sel_hi:[1,0]
	v_pk_mul_f32 v[198:199], v[14:15], v[188:189] op_sel_hi:[1,0]
	v_mov_b32_e32 v156, 0x7fc00000
	v_cmp_eq_u32_e32 vcc, 0, v158
	v_pk_mul_f32 v[24:25], v[24:25], v[188:189] op_sel_hi:[1,0]
	v_pk_mul_f32 v[26:27], v[26:27], v[188:189] op_sel_hi:[1,0]
	v_pk_mul_f32 v[32:33], v[32:33], v[188:189] op_sel_hi:[1,0]
	v_pk_mul_f32 v[34:35], v[34:35], v[188:189] op_sel_hi:[1,0]
	v_readlane_b32 s37, v254, 12
	v_readlane_b32 s38, v254, 13
	v_readlane_b32 s39, v254, 14
	v_readlane_b32 s40, v254, 15
	v_readlane_b32 s41, v254, 16
	v_readlane_b32 s44, v254, 19
	v_readlane_b32 s45, v254, 20
	v_readlane_b32 s46, v254, 21
	v_readlane_b32 s47, v254, 22
	v_readlane_b32 s48, v254, 23
	v_readlane_b32 s49, v254, 24
	v_readlane_b32 s50, v254, 25
	v_readlane_b32 s51, v254, 26
	s_waitcnt vmcnt(0)
; __device__ __forceinline__ unsigned cvt_pk_bf16(float lo, float hi) { unsigned r; asm volatile("v_cvt_pk_bf16_f32 %0, %1, %2" : "=v"(r) : "v"(lo), "v"(hi)); return r; }
;     __device__ __forceinline__ void fused(f32x4 (&acc)[2][2][4][2], const Unit& un, int wr, int wc, int fr, int fq, PG8_LAS unsigned char* lds, int wid, int lane) const {
;     ...
;         for (int ai = 0; ai < 2; ++ai)
; #pragma unroll
;             for (int m = 0; m < 4; ++m) { const int r = ai * HALF + wr * 64 + m * 16 + fr; const float rs = S[r]; const size_t off = (size_t)(un.pm * BM + r) * ldc + col0;
; #pragma unroll
;                 for (int bj = 0; bj < 2; ++bj) { f32x4 y0 = (acc[ai][bj][m][0] * rs) * cg[bj][0] + sh[bj][0], y1 = (acc[ai][bj][m][1] * rs) * cg[bj][1] + sh[bj][1];
;                     if (bad) { y0 = (f32x4){qnan, qnan, qnan, qnan}; y1 = y0; }
;                     if (MODE == 0) { u32x4 w; w.x = cvt_pk_bf16(y0[0], y0[1]); w.y = cvt_pk_bf16(y0[2], y0[3]); w.z = cvt_pk_bf16(y1[0], y1[1]); w.w = cvt_pk_bf16(y1[2], y1[3]); *(u32x4*)(u + off + bj * HALF) = w; }
;                     else { *(f32x4*)(outf + off + bj * HALF) = y0; *(f32x4*)(outf + off + bj * HALF + 4) = y1; } } }
	v_pk_add_f32 v[12:13], v[166:167], 1.0 op_sel_hi:[1,0]
	v_pk_add_f32 v[8:9], v[154:155], 1.0 op_sel_hi:[1,0]
	v_pk_add_f32 v[10:11], v[152:153], 1.0 op_sel_hi:[1,0]
	v_pk_add_f32 v[152:153], v[170:171], 1.0 op_sel_hi:[1,0]
	v_pk_add_f32 v[154:155], v[168:169], 1.0 op_sel_hi:[1,0]
	v_pk_mul_f32 v[146:147], v[174:175], v[8:9]
	v_pk_mul_f32 v[150:151], v[172:173], v[10:11]
	v_pk_mul_f32 v[8:9], v[182:183], v[152:153]
	v_pk_mul_f32 v[10:11], v[180:181], v[154:155]
	v_pk_add_f32 v[152:153], v[186:187], 1.0 op_sel_hi:[1,0]
	v_pk_add_f32 v[154:155], v[184:185], 1.0 op_sel_hi:[1,0]
	v_pk_mul_f32 v[152:153], v[162:163], v[152:153]
	v_pk_mul_f32 v[154:155], v[160:161], v[154:155]
	v_pk_add_f32 v[14:15], v[164:165], 1.0 op_sel_hi:[1,0]
	v_pk_fma_f32 v[164:165], v[146:147], v[198:199], v[134:135]
	v_pk_fma_f32 v[166:167], v[150:151], v[196:197], v[132:133]
	v_pk_fma_f32 v[160:161], v[152:153], v[194:195], v[142:143]
	v_pk_fma_f32 v[162:163], v[154:155], v[192:193], v[140:141]
	v_pk_mul_f32 v[12:13], v[178:179], v[12:13]
	v_pk_mul_f32 v[14:15], v[176:177], v[14:15]
	v_cndmask_b32_e32 v145, v156, v160, vcc
	v_cndmask_b32_e32 v159, v156, v161, vcc
	v_cndmask_b32_e32 v158, v156, v162, vcc
	v_cndmask_b32_e32 v160, v156, v163, vcc
	v_cndmask_b32_e32 v161, v156, v164, vcc
	v_cndmask_b32_e32 v162, v156, v165, vcc
	v_cndmask_b32_e32 v163, v156, v166, vcc
	v_pk_fma_f32 v[26:27], v[8:9], v[26:27], v[138:139]
	v_pk_fma_f32 v[24:25], v[10:11], v[24:25], v[136:137]
	v_cndmask_b32_e32 v164, v156, v167, vcc
	v_cvt_pk_bf16_f32 v158, v158, v160
	v_cvt_pk_bf16_f32 v159, v145, v159
	v_cvt_pk_bf16_f32 v160, v163, v164
	v_cvt_pk_bf16_f32 v161, v161, v162
	v_lshl_add_u64 v[162:163], v[190:191], 0, v[148:149]
	v_pk_fma_f32 v[34:35], v[12:13], v[34:35], v[130:131]
	v_pk_fma_f32 v[32:33], v[14:15], v[32:33], v[128:129]
	v_cndmask_b32_e32 v145, v156, v26, vcc
	v_cndmask_b32_e32 v27, v156, v27, vcc
	v_cndmask_b32_e32 v26, v156, v24, vcc
	global_store_dwordx4 v[162:163], v[158:161], off
	v_cndmask_b32_e32 v34, v156, v34, vcc
	v_cndmask_b32_e32 v35, v156, v35, vcc
	v_cndmask_b32_e32 v32, v156, v32, vcc
	v_cndmask_b32_e32 v33, v156, v33, vcc
	v_cndmask_b32_e32 v158, v156, v25, vcc
	v_cvt_pk_bf16_f32 v24, v32, v33
	v_cvt_pk_bf16_f32 v25, v34, v35
	v_cvt_pk_bf16_f32 v26, v26, v158
	v_cvt_pk_bf16_f32 v27, v145, v27
	global_store_dwordx4 v[162:163], v[24:27], off offset:256
	ds_read_b32 v24, v157 offset:4160
	s_waitcnt lgkmcnt(0)
	v_pk_mul_f32 v[16:17], v[16:17], v[24:25] op_sel_hi:[1,0]
	v_pk_mul_f32 v[18:19], v[18:19], v[24:25] op_sel_hi:[1,0]
	v_pk_mul_f32 v[20:21], v[20:21], v[24:25] op_sel_hi:[1,0]
	v_add_u32_e32 v26, 16, v144
	v_pk_fma_f32 v[18:19], v[152:153], v[18:19], v[142:143]
	v_pk_fma_f32 v[16:17], v[154:155], v[16:17], v[140:141]
	v_pk_fma_f32 v[20:21], v[150:151], v[20:21], v[132:133]
	v_ashrrev_i32_e32 v27, 31, v26
	v_cndmask_b32_e32 v18, v156, v18, vcc
	v_cndmask_b32_e32 v16, v156, v16, vcc
	v_cndmask_b32_e32 v17, v156, v17, vcc
	v_cndmask_b32_e32 v20, v156, v20, vcc
	v_cndmask_b32_e32 v21, v156, v21, vcc
	v_pk_mul_f32 v[22:23], v[22:23], v[24:25] op_sel_hi:[1,0]
	v_cndmask_b32_e32 v19, v156, v19, vcc
	v_cvt_pk_bf16_f32 v16, v16, v17
	v_cvt_pk_bf16_f32 v17, v18, v19
	v_cvt_pk_bf16_f32 v18, v20, v21
	v_lshlrev_b64 v[20:21], 12, v[26:27]
	v_pk_fma_f32 v[22:23], v[146:147], v[22:23], v[134:135]
	v_lshl_add_u64 v[20:21], s[2:3], 0, v[20:21]
	v_cndmask_b32_e32 v22, v156, v22, vcc
	v_cndmask_b32_e32 v23, v156, v23, vcc
	v_cvt_pk_bf16_f32 v19, v22, v23
	v_lshl_add_u64 v[20:21], v[20:21], 0, v[148:149]
	global_store_dwordx4 v[20:21], v[16:19], off
	v_pk_mul_f32 v[22:23], v[56:57], v[24:25] op_sel_hi:[1,0]
	s_nop 0
	v_pk_mul_f32 v[16:17], v[60:61], v[24:25] op_sel_hi:[1,0]
	v_pk_mul_f32 v[18:19], v[62:63], v[24:25] op_sel_hi:[1,0]
	v_pk_fma_f32 v[16:17], v[14:15], v[16:17], v[128:129]
	v_pk_fma_f32 v[18:19], v[12:13], v[18:19], v[130:131]
	v_pk_mul_f32 v[24:25], v[58:59], v[24:25] op_sel_hi:[1,0]
	v_pk_fma_f32 v[22:23], v[10:11], v[22:23], v[136:137]
	v_pk_fma_f32 v[24:25], v[8:9], v[24:25], v[138:139]
	v_cndmask_b32_e32 v18, v156, v18, vcc
	v_cndmask_b32_e32 v19, v156, v19, vcc
	v_cndmask_b32_e32 v16, v156, v16, vcc
	v_cndmask_b32_e32 v17, v156, v17, vcc
	v_cndmask_b32_e32 v24, v156, v24, vcc
	v_cndmask_b32_e32 v25, v156, v25, vcc
	v_cndmask_b32_e32 v22, v156, v22, vcc
	v_cndmask_b32_e32 v23, v156, v23, vcc
	v_cvt_pk_bf16_f32 v16, v16, v17
	v_cvt_pk_bf16_f32 v17, v18, v19
	v_cvt_pk_bf16_f32 v18, v22, v23
	v_cvt_pk_bf16_f32 v19, v24, v25
	global_store_dwordx4 v[20:21], v[16:19], off offset:256
	ds_read_b32 v20, v157 offset:4224
	v_add_u32_e32 v22, 32, v144
	v_ashrrev_i32_e32 v23, 31, v22
	v_lshlrev_b64 v[22:23], 12, v[22:23]
	v_lshl_add_u64 v[22:23], s[2:3], 0, v[22:23]
	s_waitcnt lgkmcnt(0)
; __device__ __forceinline__ unsigned cvt_pk_bf16(float lo, float hi) { unsigned r; asm volatile("v_cvt_pk_bf16_f32 %0, %1, %2" : "=v"(r) : "v"(lo), "v"(hi)); return r; }
;     __device__ __forceinline__ void fused(f32x4 (&acc)[2][2][4][2], const Unit& un, int wr, int wc, int fr, int fq, PG8_LAS unsigned char* lds, int wid, int lane) const {
;     ...
;         for (int ai = 0; ai < 2; ++ai)
; #pragma unroll
;             for (int m = 0; m < 4; ++m) { const int r = ai * HALF + wr * 64 + m * 16 + fr; const float rs = S[r]; const size_t off = (size_t)(un.pm * BM + r) * ldc + col0;
; #pragma unroll
;                 for (int bj = 0; bj < 2; ++bj) { f32x4 y0 = (acc[ai][bj][m][0] * rs) * cg[bj][0] + sh[bj][0], y1 = (acc[ai][bj][m][1] * rs) * cg[bj][1] + sh[bj][1];
;                     if (bad) { y0 = (f32x4){qnan, qnan, qnan, qnan}; y1 = y0; }
;                     if (MODE == 0) { u32x4 w; w.x = cvt_pk_bf16(y0[0], y0[1]); w.y = cvt_pk_bf16(y0[2], y0[3]); w.z = cvt_pk_bf16(y1[0], y1[1]); w.w = cvt_pk_bf16(y1[2], y1[3]); *(u32x4*)(u + off + bj * HALF) = w; }
;                     else { *(f32x4*)(outf + off + bj * HALF) = y0; *(f32x4*)(outf + off + bj * HALF + 4) = y1; } } }
	v_pk_mul_f32 v[16:17], v[48:49], v[20:21] op_sel_hi:[1,0]
	v_pk_mul_f32 v[18:19], v[50:51], v[20:21] op_sel_hi:[1,0]
	v_pk_fma_f32 v[16:17], v[154:155], v[16:17], v[140:141]
	v_pk_fma_f32 v[18:19], v[152:153], v[18:19], v[142:143]
	v_pk_mul_f32 v[24:25], v[52:53], v[20:21] op_sel_hi:[1,0]
	v_pk_mul_f32 v[26:27], v[54:55], v[20:21] op_sel_hi:[1,0]
	v_pk_fma_f32 v[24:25], v[150:151], v[24:25], v[132:133]
	v_pk_fma_f32 v[26:27], v[146:147], v[26:27], v[134:135]
	v_cndmask_b32_e32 v18, v156, v18, vcc
	v_cndmask_b32_e32 v19, v156, v19, vcc
	v_cndmask_b32_e32 v16, v156, v16, vcc
	v_cndmask_b32_e32 v17, v156, v17, vcc
	v_cndmask_b32_e32 v21, v156, v26, vcc
	v_cndmask_b32_e32 v26, v156, v27, vcc
	v_cndmask_b32_e32 v24, v156, v24, vcc
	v_cndmask_b32_e32 v25, v156, v25, vcc
	v_cvt_pk_bf16_f32 v16, v16, v17
	v_cvt_pk_bf16_f32 v17, v18, v19
	v_cvt_pk_bf16_f32 v18, v24, v25
	v_cvt_pk_bf16_f32 v19, v21, v26
	v_lshl_add_u64 v[22:23], v[22:23], 0, v[148:149]
	global_store_dwordx4 v[22:23], v[16:19], off
	v_pk_mul_f32 v[24:25], v[72:73], v[20:21] op_sel_hi:[1,0]
	s_nop 0
	v_pk_mul_f32 v[16:17], v[76:77], v[20:21] op_sel_hi:[1,0]
	v_pk_mul_f32 v[18:19], v[78:79], v[20:21] op_sel_hi:[1,0]
	v_pk_fma_f32 v[16:17], v[14:15], v[16:17], v[128:129]
	v_pk_fma_f32 v[18:19], v[12:13], v[18:19], v[130:131]
	v_pk_mul_f32 v[20:21], v[74:75], v[20:21] op_sel_hi:[1,0]
	v_pk_fma_f32 v[24:25], v[10:11], v[24:25], v[136:137]
	v_pk_fma_f32 v[20:21], v[8:9], v[20:21], v[138:139]
	v_cndmask_b32_e32 v18, v156, v18, vcc
	v_cndmask_b32_e32 v19, v156, v19, vcc
	v_cndmask_b32_e32 v16, v156, v16, vcc
	v_cndmask_b32_e32 v17, v156, v17, vcc
	v_cndmask_b32_e32 v20, v156, v20, vcc
	v_cndmask_b32_e32 v21, v156, v21, vcc
	v_cndmask_b32_e32 v24, v156, v24, vcc
	v_cndmask_b32_e32 v25, v156, v25, vcc
	v_cvt_pk_bf16_f32 v16, v16, v17
	v_cvt_pk_bf16_f32 v17, v18, v19
	v_cvt_pk_bf16_f32 v18, v24, v25
	v_cvt_pk_bf16_f32 v19, v20, v21
	global_store_dwordx4 v[22:23], v[16:19], off offset:256
	ds_read_b32 v20, v157 offset:4288
	v_add_u32_e32 v22, 48, v144
	v_ashrrev_i32_e32 v23, 31, v22
	v_lshlrev_b64 v[22:23], 12, v[22:23]
	v_lshl_add_u64 v[22:23], s[2:3], 0, v[22:23]
	s_waitcnt lgkmcnt(0)
	v_pk_mul_f32 v[16:17], v[64:65], v[20:21] op_sel_hi:[1,0]
	v_pk_mul_f32 v[18:19], v[66:67], v[20:21] op_sel_hi:[1,0]
	v_pk_fma_f32 v[16:17], v[154:155], v[16:17], v[140:141]
	v_pk_fma_f32 v[18:19], v[152:153], v[18:19], v[142:143]
	v_pk_mul_f32 v[24:25], v[68:69], v[20:21] op_sel_hi:[1,0]
	v_pk_mul_f32 v[26:27], v[70:71], v[20:21] op_sel_hi:[1,0]
	v_pk_fma_f32 v[24:25], v[150:151], v[24:25], v[132:133]
	v_pk_fma_f32 v[26:27], v[146:147], v[26:27], v[134:135]
	v_cndmask_b32_e32 v18, v156, v18, vcc
	v_cndmask_b32_e32 v19, v156, v19, vcc
	v_cndmask_b32_e32 v16, v156, v16, vcc
	v_cndmask_b32_e32 v17, v156, v17, vcc
	v_cndmask_b32_e32 v21, v156, v26, vcc
	v_cndmask_b32_e32 v26, v156, v27, vcc
	v_cndmask_b32_e32 v24, v156, v24, vcc
	v_cndmask_b32_e32 v25, v156, v25, vcc
	v_cvt_pk_bf16_f32 v16, v16, v17
	v_cvt_pk_bf16_f32 v17, v18, v19
	v_cvt_pk_bf16_f32 v18, v24, v25
	v_cvt_pk_bf16_f32 v19, v21, v26
	v_lshl_add_u64 v[22:23], v[22:23], 0, v[148:149]
	global_store_dwordx4 v[22:23], v[16:19], off
	v_pk_mul_f32 v[24:25], v[96:97], v[20:21] op_sel_hi:[1,0]
	s_nop 0
	v_pk_mul_f32 v[16:17], v[108:109], v[20:21] op_sel_hi:[1,0]
	v_pk_mul_f32 v[18:19], v[110:111], v[20:21] op_sel_hi:[1,0]
	v_pk_fma_f32 v[16:17], v[14:15], v[16:17], v[128:129]
	v_pk_fma_f32 v[18:19], v[12:13], v[18:19], v[130:131]
	v_pk_mul_f32 v[20:21], v[98:99], v[20:21] op_sel_hi:[1,0]
	v_pk_fma_f32 v[24:25], v[10:11], v[24:25], v[136:137]
	v_pk_fma_f32 v[20:21], v[8:9], v[20:21], v[138:139]
	v_cndmask_b32_e32 v18, v156, v18, vcc
	v_cndmask_b32_e32 v19, v156, v19, vcc
	v_cndmask_b32_e32 v16, v156, v16, vcc
	v_cndmask_b32_e32 v17, v156, v17, vcc
	v_cndmask_b32_e32 v20, v156, v20, vcc
	v_cndmask_b32_e32 v21, v156, v21, vcc
	v_cndmask_b32_e32 v24, v156, v24, vcc
	v_cndmask_b32_e32 v25, v156, v25, vcc
	v_cvt_pk_bf16_f32 v16, v16, v17
	v_cvt_pk_bf16_f32 v17, v18, v19
	v_cvt_pk_bf16_f32 v18, v24, v25
	v_cvt_pk_bf16_f32 v19, v20, v21
	global_store_dwordx4 v[22:23], v[16:19], off offset:256
	ds_read_b32 v20, v157 offset:4608
	v_add_u32_e32 v22, 0x80, v144
	v_ashrrev_i32_e32 v23, 31, v22
	v_lshlrev_b64 v[22:23], 12, v[22:23]
	v_lshl_add_u64 v[22:23], s[2:3], 0, v[22:23]
	s_waitcnt lgkmcnt(0)
	v_pk_mul_f32 v[16:17], v[100:101], v[20:21] op_sel_hi:[1,0]
	v_pk_mul_f32 v[18:19], v[102:103], v[20:21] op_sel_hi:[1,0]
	v_pk_fma_f32 v[16:17], v[154:155], v[16:17], v[140:141]
	v_pk_fma_f32 v[18:19], v[152:153], v[18:19], v[142:143]
	v_pk_mul_f32 v[24:25], v[104:105], v[20:21] op_sel_hi:[1,0]
	v_pk_mul_f32 v[26:27], v[106:107], v[20:21] op_sel_hi:[1,0]
	v_pk_fma_f32 v[24:25], v[150:151], v[24:25], v[132:133]
	v_pk_fma_f32 v[26:27], v[146:147], v[26:27], v[134:135]
	v_cndmask_b32_e32 v18, v156, v18, vcc
	v_cndmask_b32_e32 v19, v156, v19, vcc
	v_cndmask_b32_e32 v16, v156, v16, vcc
	v_cndmask_b32_e32 v17, v156, v17, vcc
	v_cndmask_b32_e32 v21, v156, v26, vcc
	v_cndmask_b32_e32 v26, v156, v27, vcc
	v_cndmask_b32_e32 v24, v156, v24, vcc
	v_cndmask_b32_e32 v25, v156, v25, vcc
	v_cvt_pk_bf16_f32 v16, v16, v17
	v_cvt_pk_bf16_f32 v17, v18, v19
	v_cvt_pk_bf16_f32 v18, v24, v25
	v_cvt_pk_bf16_f32 v19, v21, v26
	v_lshl_add_u64 v[22:23], v[22:23], 0, v[148:149]
	global_store_dwordx4 v[22:23], v[16:19], off
	v_pk_mul_f32 v[24:25], v[112:113], v[20:21] op_sel_hi:[1,0]
	s_nop 0
	v_pk_mul_f32 v[16:17], v[124:125], v[20:21] op_sel_hi:[1,0]
	v_pk_mul_f32 v[18:19], v[126:127], v[20:21] op_sel_hi:[1,0]
	v_pk_fma_f32 v[16:17], v[14:15], v[16:17], v[128:129]
	v_pk_fma_f32 v[18:19], v[12:13], v[18:19], v[130:131]
	v_pk_mul_f32 v[20:21], v[114:115], v[20:21] op_sel_hi:[1,0]
	v_pk_fma_f32 v[24:25], v[10:11], v[24:25], v[136:137]
	v_pk_fma_f32 v[20:21], v[8:9], v[20:21], v[138:139]
	v_cndmask_b32_e32 v18, v156, v18, vcc
	v_cndmask_b32_e32 v19, v156, v19, vcc
	v_cndmask_b32_e32 v16, v156, v16, vcc
	v_cndmask_b32_e32 v17, v156, v17, vcc
	v_cndmask_b32_e32 v20, v156, v20, vcc
	v_cndmask_b32_e32 v21, v156, v21, vcc
	v_cndmask_b32_e32 v24, v156, v24, vcc
	v_cndmask_b32_e32 v25, v156, v25, vcc
	v_cvt_pk_bf16_f32 v16, v16, v17
	v_cvt_pk_bf16_f32 v17, v18, v19
	v_cvt_pk_bf16_f32 v18, v24, v25
	v_cvt_pk_bf16_f32 v19, v20, v21
	global_store_dwordx4 v[22:23], v[16:19], off offset:256
	ds_read_b32 v20, v157 offset:4672
	v_add_u32_e32 v22, 0x90, v144
	v_ashrrev_i32_e32 v23, 31, v22
	v_lshlrev_b64 v[22:23], 12, v[22:23]
	v_lshl_add_u64 v[22:23], s[2:3], 0, v[22:23]
	s_waitcnt lgkmcnt(0)
; __device__ __forceinline__ unsigned cvt_pk_bf16(float lo, float hi) { unsigned r; asm volatile("v_cvt_pk_bf16_f32 %0, %1, %2" : "=v"(r) : "v"(lo), "v"(hi)); return r; }
;     __device__ __forceinline__ void fused(f32x4 (&acc)[2][2][4][2], const Unit& un, int wr, int wc, int fr, int fq, PG8_LAS unsigned char* lds, int wid, int lane) const {
;     ...
;         for (int ai = 0; ai < 2; ++ai)
; #pragma unroll
;             for (int m = 0; m < 4; ++m) { const int r = ai * HALF + wr * 64 + m * 16 + fr; const float rs = S[r]; const size_t off = (size_t)(un.pm * BM + r) * ldc + col0;
; #pragma unroll
;                 for (int bj = 0; bj < 2; ++bj) { f32x4 y0 = (acc[ai][bj][m][0] * rs) * cg[bj][0] + sh[bj][0], y1 = (acc[ai][bj][m][1] * rs) * cg[bj][1] + sh[bj][1];
;                     if (bad) { y0 = (f32x4){qnan, qnan, qnan, qnan}; y1 = y0; }
;                     if (MODE == 0) { u32x4 w; w.x = cvt_pk_bf16(y0[0], y0[1]); w.y = cvt_pk_bf16(y0[2], y0[3]); w.z = cvt_pk_bf16(y1[0], y1[1]); w.w = cvt_pk_bf16(y1[2], y1[3]); *(u32x4*)(u + off + bj * HALF) = w; }
;                     else { *(f32x4*)(outf + off + bj * HALF) = y0; *(f32x4*)(outf + off + bj * HALF + 4) = y1; } } }
	v_pk_mul_f32 v[16:17], v[116:117], v[20:21] op_sel_hi:[1,0]
	v_pk_mul_f32 v[18:19], v[118:119], v[20:21] op_sel_hi:[1,0]
	v_pk_fma_f32 v[16:17], v[154:155], v[16:17], v[140:141]
	v_pk_fma_f32 v[18:19], v[152:153], v[18:19], v[142:143]
	v_pk_mul_f32 v[24:25], v[120:121], v[20:21] op_sel_hi:[1,0]
	v_pk_mul_f32 v[26:27], v[122:123], v[20:21] op_sel_hi:[1,0]
	v_pk_fma_f32 v[24:25], v[150:151], v[24:25], v[132:133]
	v_pk_fma_f32 v[26:27], v[146:147], v[26:27], v[134:135]
	v_cndmask_b32_e32 v18, v156, v18, vcc
	v_cndmask_b32_e32 v19, v156, v19, vcc
	v_cndmask_b32_e32 v16, v156, v16, vcc
	v_cndmask_b32_e32 v17, v156, v17, vcc
	v_cndmask_b32_e32 v21, v156, v26, vcc
	v_cndmask_b32_e32 v26, v156, v27, vcc
	v_cndmask_b32_e32 v24, v156, v24, vcc
	v_cndmask_b32_e32 v25, v156, v25, vcc
	v_cvt_pk_bf16_f32 v16, v16, v17
	v_cvt_pk_bf16_f32 v17, v18, v19
	v_cvt_pk_bf16_f32 v18, v24, v25
	v_cvt_pk_bf16_f32 v19, v21, v26
	v_lshl_add_u64 v[22:23], v[22:23], 0, v[148:149]
	global_store_dwordx4 v[22:23], v[16:19], off
	v_pk_mul_f32 v[24:25], v[88:89], v[20:21] op_sel_hi:[1,0]
	s_nop 0
	v_pk_mul_f32 v[16:17], v[92:93], v[20:21] op_sel_hi:[1,0]
	v_pk_mul_f32 v[18:19], v[94:95], v[20:21] op_sel_hi:[1,0]
	v_pk_fma_f32 v[16:17], v[14:15], v[16:17], v[128:129]
	v_pk_fma_f32 v[18:19], v[12:13], v[18:19], v[130:131]
	v_pk_mul_f32 v[20:21], v[90:91], v[20:21] op_sel_hi:[1,0]
	v_pk_fma_f32 v[24:25], v[10:11], v[24:25], v[136:137]
	v_pk_fma_f32 v[20:21], v[8:9], v[20:21], v[138:139]
	v_cndmask_b32_e32 v18, v156, v18, vcc
	v_cndmask_b32_e32 v19, v156, v19, vcc
	v_cndmask_b32_e32 v16, v156, v16, vcc
	v_cndmask_b32_e32 v17, v156, v17, vcc
	v_cndmask_b32_e32 v20, v156, v20, vcc
	v_cndmask_b32_e32 v21, v156, v21, vcc
	v_cndmask_b32_e32 v24, v156, v24, vcc
	v_cndmask_b32_e32 v25, v156, v25, vcc
	v_cvt_pk_bf16_f32 v16, v16, v17
	v_cvt_pk_bf16_f32 v17, v18, v19
	v_cvt_pk_bf16_f32 v18, v24, v25
	v_cvt_pk_bf16_f32 v19, v20, v21
	global_store_dwordx4 v[22:23], v[16:19], off offset:256
	ds_read_b32 v20, v157 offset:4736
	v_add_u32_e32 v22, 0xa0, v144
	v_ashrrev_i32_e32 v23, 31, v22
	v_lshlrev_b64 v[22:23], 12, v[22:23]
	v_lshl_add_u64 v[22:23], s[2:3], 0, v[22:23]
	s_waitcnt lgkmcnt(0)
	v_pk_mul_f32 v[16:17], v[84:85], v[20:21] op_sel_hi:[1,0]
	v_pk_mul_f32 v[18:19], v[86:87], v[20:21] op_sel_hi:[1,0]
	v_pk_fma_f32 v[16:17], v[154:155], v[16:17], v[140:141]
	v_pk_fma_f32 v[18:19], v[152:153], v[18:19], v[142:143]
	v_pk_mul_f32 v[24:25], v[80:81], v[20:21] op_sel_hi:[1,0]
	v_pk_mul_f32 v[26:27], v[82:83], v[20:21] op_sel_hi:[1,0]
	v_pk_fma_f32 v[24:25], v[150:151], v[24:25], v[132:133]
	v_pk_fma_f32 v[26:27], v[146:147], v[26:27], v[134:135]
	v_cndmask_b32_e32 v18, v156, v18, vcc
	v_cndmask_b32_e32 v19, v156, v19, vcc
	v_cndmask_b32_e32 v16, v156, v16, vcc
	v_cndmask_b32_e32 v17, v156, v17, vcc
	v_cndmask_b32_e32 v21, v156, v26, vcc
	v_cndmask_b32_e32 v26, v156, v27, vcc
	v_cndmask_b32_e32 v24, v156, v24, vcc
	v_cndmask_b32_e32 v25, v156, v25, vcc
	v_cvt_pk_bf16_f32 v16, v16, v17
	v_cvt_pk_bf16_f32 v17, v18, v19
	v_cvt_pk_bf16_f32 v18, v24, v25
	v_cvt_pk_bf16_f32 v19, v21, v26
	v_lshl_add_u64 v[22:23], v[22:23], 0, v[148:149]
	global_store_dwordx4 v[22:23], v[16:19], off
	v_pk_mul_f32 v[24:25], v[40:41], v[20:21] op_sel_hi:[1,0]
	s_nop 0
	v_pk_mul_f32 v[16:17], v[44:45], v[20:21] op_sel_hi:[1,0]
	v_pk_mul_f32 v[18:19], v[46:47], v[20:21] op_sel_hi:[1,0]
	v_pk_fma_f32 v[16:17], v[14:15], v[16:17], v[128:129]
	v_pk_fma_f32 v[18:19], v[12:13], v[18:19], v[130:131]
	v_pk_mul_f32 v[20:21], v[42:43], v[20:21] op_sel_hi:[1,0]
	v_pk_fma_f32 v[24:25], v[10:11], v[24:25], v[136:137]
	v_pk_fma_f32 v[20:21], v[8:9], v[20:21], v[138:139]
	v_cndmask_b32_e32 v18, v156, v18, vcc
	v_cndmask_b32_e32 v19, v156, v19, vcc
	v_cndmask_b32_e32 v16, v156, v16, vcc
	v_cndmask_b32_e32 v17, v156, v17, vcc
	v_cndmask_b32_e32 v20, v156, v20, vcc
	v_cndmask_b32_e32 v21, v156, v21, vcc
	v_cndmask_b32_e32 v24, v156, v24, vcc
	v_cndmask_b32_e32 v25, v156, v25, vcc
	v_cvt_pk_bf16_f32 v16, v16, v17
	v_cvt_pk_bf16_f32 v17, v18, v19
	v_cvt_pk_bf16_f32 v18, v24, v25
	v_cvt_pk_bf16_f32 v19, v20, v21
	global_store_dwordx4 v[22:23], v[16:19], off offset:256
	ds_read_b32 v20, v157 offset:4800
	v_add_u32_e32 v22, 0xb0, v144
	v_ashrrev_i32_e32 v23, 31, v22
	v_lshlrev_b64 v[22:23], 12, v[22:23]
	v_lshl_add_u64 v[22:23], s[2:3], 0, v[22:23]
	s_waitcnt lgkmcnt(0)
	v_pk_mul_f32 v[26:27], v[30:31], v[20:21] op_sel_hi:[1,0]
	v_pk_mul_f32 v[16:17], v[36:37], v[20:21] op_sel_hi:[1,0]
	v_pk_fma_f32 v[26:27], v[146:147], v[26:27], v[134:135]
	v_pk_mul_f32 v[18:19], v[38:39], v[20:21] op_sel_hi:[1,0]
	v_pk_mul_f32 v[24:25], v[28:29], v[20:21] op_sel_hi:[1,0]
	v_cndmask_b32_e32 v21, v156, v26, vcc
	v_pk_mul_f32 v[0:1], v[0:1], v[20:21] op_sel_hi:[1,0]
	v_pk_mul_f32 v[2:3], v[2:3], v[20:21] op_sel_hi:[1,0]
	v_pk_fma_f32 v[18:19], v[152:153], v[18:19], v[142:143]
	v_pk_fma_f32 v[16:17], v[154:155], v[16:17], v[140:141]
	v_pk_mul_f32 v[4:5], v[4:5], v[20:21] op_sel_hi:[1,0]
	v_pk_mul_f32 v[6:7], v[6:7], v[20:21] op_sel_hi:[1,0]
	v_pk_fma_f32 v[2:3], v[8:9], v[2:3], v[138:139]
	v_pk_fma_f32 v[0:1], v[10:11], v[0:1], v[136:137]
	v_pk_fma_f32 v[24:25], v[150:151], v[24:25], v[132:133]
	v_cndmask_b32_e32 v18, v156, v18, vcc
	v_cndmask_b32_e32 v19, v156, v19, vcc
	v_cndmask_b32_e32 v16, v156, v16, vcc
	v_cndmask_b32_e32 v17, v156, v17, vcc
	v_lshl_add_u64 v[22:23], v[22:23], 0, v[148:149]
	v_pk_fma_f32 v[6:7], v[12:13], v[6:7], v[130:131]
	v_pk_fma_f32 v[4:5], v[14:15], v[4:5], v[128:129]
	v_cndmask_b32_e32 v8, v156, v2, vcc
	v_cndmask_b32_e32 v3, v156, v3, vcc
	v_cndmask_b32_e32 v2, v156, v0, vcc
	v_cndmask_b32_e32 v26, v156, v27, vcc
	v_cndmask_b32_e32 v24, v156, v24, vcc
	v_cndmask_b32_e32 v25, v156, v25, vcc
	v_cvt_pk_bf16_f32 v16, v16, v17
	v_cvt_pk_bf16_f32 v17, v18, v19
	v_cvt_pk_bf16_f32 v18, v24, v25
	v_cvt_pk_bf16_f32 v19, v21, v26
	global_store_dwordx4 v[22:23], v[16:19], off
	v_cndmask_b32_e32 v6, v156, v6, vcc
	v_cndmask_b32_e32 v7, v156, v7, vcc
	v_cndmask_b32_e32 v4, v156, v4, vcc
	v_cndmask_b32_e32 v5, v156, v5, vcc
	v_cndmask_b32_e32 v9, v156, v1, vcc
	v_cvt_pk_bf16_f32 v0, v4, v5
	v_cvt_pk_bf16_f32 v1, v6, v7
	v_cvt_pk_bf16_f32 v2, v2, v9
	v_cvt_pk_bf16_f32 v3, v8, v3
	global_store_dwordx4 v[22:23], v[0:3], off offset:256

;     __device__ __forceinline__ void operator()(const f32x4 (&acc)[2][2][4][2], const Unit& u, int wr, int wc, int fr, int fq) const {
;     ...
;         for (int ai = 0; ai < 2; ++ai)
; #pragma unroll
;             for (int m = 0; m < 4; ++m) { bf16_t* rowp = O + (size_t)(row0 + ai * HALF + m * 16) * ldc + col0;
;                 if (ACT == 1) {
;                     const int ob = fr * 64 + 16 * fq, sw = ob ^ (((ob >> 9) & 1) << 5);
;                     rowp = O + ((size_t)(u.pm * (ldc / 64) + u.pn * 4 + (wc >> 1)) * 2 + ai) * 8192 + (((wr * 4 + m) * 2 + (wc & 1)) * 1024 + sw) / 2; }
;                 float rc[2][2], rs[2][2];
;                 if (ACT == 2) { const float pos = (float)((row0 + ai * HALF + m * 16) & 2047);
; #pragma unroll
;                     for (int n = 0; n < 2; ++n)
; #pragma unroll
;                         for (int e = 0; e < 2; ++e) { float r = pos * rinv[n][e]; r -= floorf(r); rs[n][e] = do_rope ? __builtin_amdgcn_sinf(r) : 0.f; rc[n][e] = do_rope ? __builtin_amdgcn_cosf(r) : 1.f; } }
; #pragma unroll
;                 for (int bj = 0; bj < 2; ++bj) { f32x4 v0 = acc[ai][bj][m][0], v1 = acc[ai][bj][m][1];
;                     if (ACT == 3) { const float pos = (float)((row0 + ai * HALF + m * 16) & 2047); float c3[4], s3[4];
; #pragma unroll
;                         for (int p = 0; p < 4; ++p) { float r = pos * rinv3[bj][p]; r -= floorf(r); s3[p] = rope3[bj] ? __builtin_amdgcn_sinf(r) : 0.f; c3[p] = rope3[bj] ? __builtin_amdgcn_cosf(r) : 1.f; }
;                         const f32x4 a = v0, b = v1;
;                         v0[0] = a[0] * c3[0] - a[1] * s3[0]; v0[1] = a[1] * c3[0] + a[0] * s3[0]; v0[2] = a[2] * c3[1] - a[3] * s3[1]; v0[3] = a[3] * c3[1] + a[2] * s3[1];
;                         v1[0] = b[0] * c3[2] - b[1] * s3[2]; v1[1] = b[1] * c3[2] + b[0] * s3[2]; v1[2] = b[2] * c3[3] - b[3] * s3[3]; v1[3] = b[3] * c3[3] + b[2] * s3[3]; }
;                     if (ACT == 2) { const f32x4 a = v0, b = v1;
;                         v0[0] = a[0] * rc[0][0] - a[1] * rs[0][0]; v0[1] = a[1] * rc[0][0] + a[0] * rs[0][0]; v0[2] = a[2] * rc[0][1] - a[3] * rs[0][1]; v0[3] = a[3] * rc[0][1] + a[2] * rs[0][1];
;                         v1[0] = b[0] * rc[1][0] - b[1] * rs[1][0]; v1[1] = b[1] * rc[1][0] + b[0] * rs[1][0]; v1[2] = b[2] * rc[1][1] - b[3] * rs[1][1]; v1[3] = b[3] * rc[1][1] + b[2] * rs[1][1]; }
;                     if (ACT == 1) {
.LBB0_1956:
	v_mov_b32_e32 v148, 0
	s_lshl_b32 s49, s49, 2
	v_mbcnt_lo_u32_b32 v148, -1, v148
	v_mbcnt_hi_u32_b32 v148, -1, v148
	v_or_b32_e32 v148, s33, v148
	s_or_b32 s49, s49, s45
	v_and_b32_e32 v149, 15, v148
	v_and_b32_e32 v150, 48, v148
	v_lshlrev_b32_e32 v148, 2, v148
	s_lshl_b32 s50, s74, 7
	v_lshl_or_b32 v149, v149, 6, v150
	v_and_b32_e32 v148, 32, v148
	s_add_i32 s50, s49, s50
	s_ashr_i32 s51, s50, 31
	v_bitop3_b32 v148, v149, s46, v148 bitop3:0xde
	s_lshl_b64 s[50:51], s[50:51], 15
	v_ashrrev_i32_e32 v148, 1, v148
	s_add_u32 s74, s41, s50
	v_ashrrev_i32_e32 v149, 31, v148
	s_addc_u32 s75, s42, s51
	v_lshlrev_b64 v[150:151], 1, v[148:149]
	v_max_i32_e32 v120, 0, v120
	v_max_i32_e32 v121, 0, v121
	v_max_i32_e32 v122, 0, v122
	v_max_i32_e32 v123, 0, v123
	v_max_i32_e32 v112, 0, v112
	v_max_i32_e32 v116, 0, v116
	v_max_i32_e32 v113, 0, v113
	v_max_i32_e32 v114, 0, v114
	v_lshl_add_u64 v[152:153], s[74:75], 0, v[150:151]
	v_max_i32_e32 v124, 0, v124
	v_mul_f32_e32 v120, v120, v120
	v_max_i32_e32 v125, 0, v125
	v_mul_f32_e32 v121, v121, v121
	v_max_i32_e32 v126, 0, v126
	v_mul_f32_e32 v122, v122, v122
	v_max_i32_e32 v127, 0, v127
	v_mul_f32_e32 v123, v123, v123
	v_mul_f32_e32 v112, v112, v112
	v_mul_f32_e32 v116, v116, v116
	v_max_i32_e32 v117, 0, v117
	v_mul_f32_e32 v113, v113, v113
	v_mul_f32_e32 v114, v114, v114
	v_max_i32_e32 v115, 0, v115
	v_mul_f32_e32 v124, v124, v124
	v_mul_f32_e32 v125, v125, v125
	v_mul_f32_e32 v126, v126, v126
	v_mul_f32_e32 v127, v127, v127
	v_cvt_pk_bf16_f32 v120, v120, v121
	v_cvt_pk_bf16_f32 v121, v122, v123
	v_cvt_pk_bf16_f32 v122, v124, v125
	v_cvt_pk_bf16_f32 v123, v126, v127
	global_store_dwordx4 v[152:153], v[120:123], off
	v_mul_f32_e32 v117, v117, v117
	v_mul_f32_e32 v115, v115, v115
	v_cvt_pk_bf16_f32 v112, v112, v113
	v_cvt_pk_bf16_f32 v113, v114, v115
	v_cvt_pk_bf16_f32 v114, v116, v117
	v_add_co_u32_e32 v116, vcc, s39, v152
	v_max_i32_e32 v104, 0, v104
	v_max_i32_e32 v105, 0, v105
	v_max_i32_e32 v106, 0, v106
	v_max_i32_e32 v107, 0, v107
	v_max_i32_e32 v96, 0, v96
	v_max_i32_e32 v118, 0, v118
	v_max_i32_e32 v119, 0, v119
	v_addc_co_u32_e32 v117, vcc, 0, v153, vcc
	v_max_i32_e32 v108, 0, v108
	v_mul_f32_e32 v104, v104, v104
	v_max_i32_e32 v109, 0, v109
	v_mul_f32_e32 v105, v105, v105
	v_max_i32_e32 v110, 0, v110
	v_mul_f32_e32 v106, v106, v106
	v_max_i32_e32 v111, 0, v111
	v_mul_f32_e32 v107, v107, v107
	v_mul_f32_e32 v96, v96, v96
	v_max_i32_e32 v97, 0, v97
	v_max_i32_e32 v98, 0, v98
	v_max_i32_e32 v99, 0, v99
	v_mul_f32_e32 v118, v118, v118
	v_mul_f32_e32 v119, v119, v119
	v_cvt_pk_bf16_f32 v115, v118, v119
	global_store_dwordx4 v[116:117], v[112:115], off
	v_mul_f32_e32 v108, v108, v108
	v_mul_f32_e32 v109, v109, v109
	v_mul_f32_e32 v110, v110, v110
	v_mul_f32_e32 v111, v111, v111
	v_cvt_pk_bf16_f32 v104, v104, v105
	v_cvt_pk_bf16_f32 v105, v106, v107
	v_cvt_pk_bf16_f32 v106, v108, v109
	v_cvt_pk_bf16_f32 v107, v110, v111
	global_store_dwordx4 v[152:153], v[104:107], off offset:2048
	v_max_i32_e32 v100, 0, v100
	v_max_i32_e32 v101, 0, v101
	v_mul_f32_e32 v97, v97, v97
	v_max_i32_e32 v102, 0, v102
	v_mul_f32_e32 v98, v98, v98
	v_max_i32_e32 v103, 0, v103
	v_mul_f32_e32 v99, v99, v99
	v_cvt_pk_bf16_f32 v96, v96, v97
	v_mul_f32_e32 v100, v100, v100
	v_mul_f32_e32 v101, v101, v101
	v_mul_f32_e32 v102, v102, v102
	v_mul_f32_e32 v103, v103, v103
	v_cvt_pk_bf16_f32 v97, v98, v99
	v_cvt_pk_bf16_f32 v98, v100, v101
	v_cvt_pk_bf16_f32 v99, v102, v103
	global_store_dwordx4 v[116:117], v[96:99], off offset:2048
	v_max_i32_e32 v88, 0, v88
	v_max_i32_e32 v89, 0, v89
	v_or_b32_e32 v96, 0x800, v148
	v_ashrrev_i32_e32 v97, 31, v96
	v_lshlrev_b64 v[96:97], 1, v[96:97]
	v_max_i32_e32 v90, 0, v90
	v_max_i32_e32 v91, 0, v91
	v_max_i32_e32 v80, 0, v80
	v_max_i32_e32 v84, 0, v84
	v_max_i32_e32 v81, 0, v81
	v_max_i32_e32 v82, 0, v82
	v_lshl_add_u64 v[98:99], s[74:75], 0, v[96:97]
	v_max_i32_e32 v92, 0, v92
	v_mul_f32_e32 v88, v88, v88
	v_max_i32_e32 v93, 0, v93
	v_mul_f32_e32 v89, v89, v89
	v_max_i32_e32 v94, 0, v94
	v_mul_f32_e32 v90, v90, v90
	v_max_i32_e32 v95, 0, v95
	v_mul_f32_e32 v91, v91, v91
	v_mul_f32_e32 v80, v80, v80
	v_mul_f32_e32 v84, v84, v84
	v_max_i32_e32 v85, 0, v85
	v_mul_f32_e32 v81, v81, v81
	v_mul_f32_e32 v82, v82, v82
	v_max_i32_e32 v83, 0, v83
	v_mul_f32_e32 v92, v92, v92
	v_mul_f32_e32 v93, v93, v93
	v_mul_f32_e32 v94, v94, v94
	v_mul_f32_e32 v95, v95, v95
	v_cvt_pk_bf16_f32 v88, v88, v89
	v_cvt_pk_bf16_f32 v89, v90, v91
	v_cvt_pk_bf16_f32 v90, v92, v93
	v_cvt_pk_bf16_f32 v91, v94, v95
	global_store_dwordx4 v[98:99], v[88:91], off
	v_mul_f32_e32 v85, v85, v85
	v_mul_f32_e32 v83, v83, v83
	v_cvt_pk_bf16_f32 v80, v80, v81
	v_cvt_pk_bf16_f32 v81, v82, v83
	v_cvt_pk_bf16_f32 v82, v84, v85
	v_add_co_u32_e32 v84, vcc, s39, v98
	v_max_i32_e32 v86, 0, v86
	v_max_i32_e32 v87, 0, v87
	v_addc_co_u32_e32 v85, vcc, 0, v99, vcc
	v_mul_f32_e32 v86, v86, v86
	v_mul_f32_e32 v87, v87, v87
	v_cvt_pk_bf16_f32 v83, v86, v87
	global_store_dwordx4 v[84:85], v[80:83], off
	v_max_i32_e32 v64, 0, v64
	v_max_i32_e32 v65, 0, v65
	v_or_b32_e32 v80, 0xc00, v148
	v_ashrrev_i32_e32 v81, 31, v80
	v_lshlrev_b64 v[80:81], 1, v[80:81]
	v_max_i32_e32 v66, 0, v66
	v_max_i32_e32 v67, 0, v67
	v_max_i32_e32 v48, 0, v48
	v_max_i32_e32 v52, 0, v52
	v_max_i32_e32 v49, 0, v49
	v_max_i32_e32 v50, 0, v50
	v_lshl_add_u64 v[82:83], s[74:75], 0, v[80:81]
	v_max_i32_e32 v68, 0, v68
	v_mul_f32_e32 v64, v64, v64
	v_max_i32_e32 v69, 0, v69
	v_mul_f32_e32 v65, v65, v65
	v_max_i32_e32 v70, 0, v70
	v_mul_f32_e32 v66, v66, v66
	v_max_i32_e32 v71, 0, v71
	v_mul_f32_e32 v67, v67, v67
	v_mul_f32_e32 v48, v48, v48
	v_mul_f32_e32 v52, v52, v52
;     __device__ __forceinline__ void operator()(const f32x4 (&acc)[2][2][4][2], const Unit& u, int wr, int wc, int fr, int fq) const {
;     ...
;         for (int ai = 0; ai < 2; ++ai)
; #pragma unroll
;             for (int m = 0; m < 4; ++m) { bf16_t* rowp = O + (size_t)(row0 + ai * HALF + m * 16) * ldc + col0;
;                 if (ACT == 1) {
;                     const int ob = fr * 64 + 16 * fq, sw = ob ^ (((ob >> 9) & 1) << 5);
;                     rowp = O + ((size_t)(u.pm * (ldc / 64) + u.pn * 4 + (wc >> 1)) * 2 + ai) * 8192 + (((wr * 4 + m) * 2 + (wc & 1)) * 1024 + sw) / 2; }
;                 float rc[2][2], rs[2][2];
;                 if (ACT == 2) { const float pos = (float)((row0 + ai * HALF + m * 16) & 2047);
; #pragma unroll
;                     for (int n = 0; n < 2; ++n)
; #pragma unroll
;                         for (int e = 0; e < 2; ++e) { float r = pos * rinv[n][e]; r -= floorf(r); rs[n][e] = do_rope ? __builtin_amdgcn_sinf(r) : 0.f; rc[n][e] = do_rope ? __builtin_amdgcn_cosf(r) : 1.f; } }
; #pragma unroll
;                 for (int bj = 0; bj < 2; ++bj) { f32x4 v0 = acc[ai][bj][m][0], v1 = acc[ai][bj][m][1];
;                     if (ACT == 3) { const float pos = (float)((row0 + ai * HALF + m * 16) & 2047); float c3[4], s3[4];
; #pragma unroll
;                         for (int p = 0; p < 4; ++p) { float r = pos * rinv3[bj][p]; r -= floorf(r); s3[p] = rope3[bj] ? __builtin_amdgcn_sinf(r) : 0.f; c3[p] = rope3[bj] ? __builtin_amdgcn_cosf(r) : 1.f; }
;                         const f32x4 a = v0, b = v1;
;                         v0[0] = a[0] * c3[0] - a[1] * s3[0]; v0[1] = a[1] * c3[0] + a[0] * s3[0]; v0[2] = a[2] * c3[1] - a[3] * s3[1]; v0[3] = a[3] * c3[1] + a[2] * s3[1];
;                         v1[0] = b[0] * c3[2] - b[1] * s3[2]; v1[1] = b[1] * c3[2] + b[0] * s3[2]; v1[2] = b[2] * c3[3] - b[3] * s3[3]; v1[3] = b[3] * c3[3] + b[2] * s3[3]; }
;                     if (ACT == 2) { const f32x4 a = v0, b = v1;
;                         v0[0] = a[0] * rc[0][0] - a[1] * rs[0][0]; v0[1] = a[1] * rc[0][0] + a[0] * rs[0][0]; v0[2] = a[2] * rc[0][1] - a[3] * rs[0][1]; v0[3] = a[3] * rc[0][1] + a[2] * rs[0][1];
;                         v1[0] = b[0] * rc[1][0] - b[1] * rs[1][0]; v1[1] = b[1] * rc[1][0] + b[0] * rs[1][0]; v1[2] = b[2] * rc[1][1] - b[3] * rs[1][1]; v1[3] = b[3] * rc[1][1] + b[2] * rs[1][1]; }
;                     if (ACT == 1) {
	v_max_i32_e32 v53, 0, v53
	v_mul_f32_e32 v49, v49, v49
	v_mul_f32_e32 v50, v50, v50
	v_max_i32_e32 v51, 0, v51
	v_mul_f32_e32 v68, v68, v68
	v_mul_f32_e32 v69, v69, v69
	v_mul_f32_e32 v70, v70, v70
	v_mul_f32_e32 v71, v71, v71
	v_cvt_pk_bf16_f32 v64, v64, v65
	v_cvt_pk_bf16_f32 v65, v66, v67
	v_cvt_pk_bf16_f32 v66, v68, v69
	v_cvt_pk_bf16_f32 v67, v70, v71
	global_store_dwordx4 v[82:83], v[64:67], off
	v_mul_f32_e32 v53, v53, v53
	v_mul_f32_e32 v51, v51, v51
	v_cvt_pk_bf16_f32 v48, v48, v49
	v_cvt_pk_bf16_f32 v49, v50, v51
	v_cvt_pk_bf16_f32 v50, v52, v53
	v_add_co_u32_e32 v52, vcc, s39, v82
	v_max_i32_e32 v54, 0, v54
	v_max_i32_e32 v55, 0, v55
	v_addc_co_u32_e32 v53, vcc, 0, v83, vcc
	v_mul_f32_e32 v54, v54, v54
	v_mul_f32_e32 v55, v55, v55
	v_cvt_pk_bf16_f32 v51, v54, v55
	global_store_dwordx4 v[52:53], v[48:51], off
	s_add_u32 s74, s74, 0x4000
	s_addc_u32 s75, s75, 0
	v_max_i32_e32 v49, 0, v76
	v_max_i32_e32 v48, 0, v72
	v_mul_f32_e32 v50, v49, v49
	v_max_i32_e32 v49, 0, v73
	v_mul_f32_e32 v48, v48, v48
	v_max_i32_e32 v51, 0, v77
	v_mul_f32_e32 v49, v49, v49
	v_max_i32_e32 v54, 0, v74
	v_max_i32_e32 v64, 0, v75
	v_lshl_add_u64 v[52:53], s[74:75], 0, v[150:151]
	v_mul_f32_e32 v51, v51, v51
	v_max_i32_e32 v55, 0, v78
	v_mul_f32_e32 v54, v54, v54
	v_max_i32_e32 v65, 0, v79
	v_mul_f32_e32 v64, v64, v64
	v_cvt_pk_bf16_f32 v48, v48, v49
	v_cvt_pk_bf16_f32 v49, v54, v64
	v_mul_f32_e32 v55, v55, v55
	v_mul_f32_e32 v65, v65, v65
	v_cvt_pk_bf16_f32 v50, v50, v51
	v_cvt_pk_bf16_f32 v51, v55, v65
	global_store_dwordx4 v[52:53], v[48:51], off
	v_or_b32_e32 v112, 0x400, v148
	v_max_i32_e32 v54, 0, v58
	v_max_i32_e32 v49, 0, v60
	v_max_i32_e32 v48, 0, v56
	v_mul_f32_e32 v50, v49, v49
	v_max_i32_e32 v49, 0, v57
	v_mul_f32_e32 v48, v48, v48
	v_max_i32_e32 v51, 0, v61
	v_mul_f32_e32 v49, v49, v49
	v_max_i32_e32 v56, 0, v59
	v_add_co_u32_e32 v52, vcc, s39, v52
	v_ashrrev_i32_e32 v113, 31, v112
	v_mul_f32_e32 v51, v51, v51
	v_max_i32_e32 v55, 0, v62
	v_mul_f32_e32 v54, v54, v54
	v_max_i32_e32 v57, 0, v63
	v_mul_f32_e32 v56, v56, v56
	v_cvt_pk_bf16_f32 v48, v48, v49
	v_cvt_pk_bf16_f32 v49, v54, v56
	v_addc_co_u32_e32 v53, vcc, 0, v53, vcc
	v_max_i32_e32 v40, 0, v40
	v_max_i32_e32 v41, 0, v41
	v_max_i32_e32 v42, 0, v42
	v_max_i32_e32 v43, 0, v43
	v_max_i32_e32 v32, 0, v32
	v_max_i32_e32 v36, 0, v36
	v_max_i32_e32 v33, 0, v33
	v_max_i32_e32 v34, 0, v34
	v_mul_f32_e32 v55, v55, v55
	v_mul_f32_e32 v57, v57, v57
	v_cvt_pk_bf16_f32 v50, v50, v51
	v_cvt_pk_bf16_f32 v51, v55, v57
	global_store_dwordx4 v[52:53], v[48:51], off
	v_max_i32_e32 v44, 0, v44
	v_mul_f32_e32 v40, v40, v40
	v_lshl_add_u64 v[48:49], v[112:113], 1, s[74:75]
	v_max_i32_e32 v45, 0, v45
	v_mul_f32_e32 v41, v41, v41
	v_max_i32_e32 v46, 0, v46
	v_mul_f32_e32 v42, v42, v42
	v_max_i32_e32 v47, 0, v47
	v_mul_f32_e32 v43, v43, v43
	v_mul_f32_e32 v32, v32, v32
	v_mul_f32_e32 v36, v36, v36
	v_max_i32_e32 v37, 0, v37
	v_mul_f32_e32 v33, v33, v33
	v_mul_f32_e32 v34, v34, v34
	v_max_i32_e32 v35, 0, v35
	v_mul_f32_e32 v44, v44, v44
	v_mul_f32_e32 v45, v45, v45
	v_mul_f32_e32 v46, v46, v46
	v_mul_f32_e32 v47, v47, v47
	v_cvt_pk_bf16_f32 v40, v40, v41
	v_cvt_pk_bf16_f32 v41, v42, v43
	v_cvt_pk_bf16_f32 v42, v44, v45
	v_cvt_pk_bf16_f32 v43, v46, v47
	global_store_dwordx4 v[48:49], v[40:43], off
	v_mul_f32_e32 v37, v37, v37
	v_mul_f32_e32 v35, v35, v35
	v_cvt_pk_bf16_f32 v32, v32, v33
	v_cvt_pk_bf16_f32 v33, v34, v35
	v_cvt_pk_bf16_f32 v34, v36, v37
	v_add_co_u32_e32 v36, vcc, s39, v48
	v_max_i32_e32 v38, 0, v38
	v_max_i32_e32 v39, 0, v39
	v_addc_co_u32_e32 v37, vcc, 0, v49, vcc
	v_max_i32_e32 v24, 0, v24
	v_max_i32_e32 v25, 0, v25
	v_max_i32_e32 v26, 0, v26
	v_max_i32_e32 v27, 0, v27
	v_max_i32_e32 v16, 0, v16
	v_max_i32_e32 v20, 0, v20
	v_max_i32_e32 v17, 0, v17
	v_max_i32_e32 v18, 0, v18
	v_mul_f32_e32 v38, v38, v38
	v_mul_f32_e32 v39, v39, v39
	v_cvt_pk_bf16_f32 v35, v38, v39
	global_store_dwordx4 v[36:37], v[32:35], off
	v_max_i32_e32 v28, 0, v28
	v_mul_f32_e32 v24, v24, v24
	v_lshl_add_u64 v[32:33], s[74:75], 0, v[96:97]
	v_max_i32_e32 v29, 0, v29
	v_mul_f32_e32 v25, v25, v25
	v_max_i32_e32 v30, 0, v30
	v_mul_f32_e32 v26, v26, v26
	v_max_i32_e32 v31, 0, v31
	v_mul_f32_e32 v27, v27, v27
	v_mul_f32_e32 v16, v16, v16
	v_mul_f32_e32 v20, v20, v20
	v_max_i32_e32 v21, 0, v21
	v_mul_f32_e32 v17, v17, v17
	v_mul_f32_e32 v18, v18, v18
	v_max_i32_e32 v19, 0, v19
	v_mul_f32_e32 v28, v28, v28
	v_mul_f32_e32 v29, v29, v29
	v_mul_f32_e32 v30, v30, v30
	v_mul_f32_e32 v31, v31, v31
	v_cvt_pk_bf16_f32 v24, v24, v25
	v_cvt_pk_bf16_f32 v25, v26, v27
	v_cvt_pk_bf16_f32 v26, v28, v29
	v_cvt_pk_bf16_f32 v27, v30, v31
	global_store_dwordx4 v[32:33], v[24:27], off
	v_mul_f32_e32 v21, v21, v21
	v_mul_f32_e32 v19, v19, v19
	v_cvt_pk_bf16_f32 v16, v16, v17
	v_cvt_pk_bf16_f32 v17, v18, v19
	v_cvt_pk_bf16_f32 v18, v20, v21
	v_add_co_u32_e32 v20, vcc, s39, v32
	v_max_i32_e32 v22, 0, v22
	v_max_i32_e32 v23, 0, v23
	v_addc_co_u32_e32 v21, vcc, 0, v33, vcc
	v_max_i32_e32 v8, 0, v8
	v_max_i32_e32 v9, 0, v9
	v_max_i32_e32 v10, 0, v10
	v_max_i32_e32 v11, 0, v11
	v_max_i32_e32 v0, 0, v0
	v_max_i32_e32 v4, 0, v4
	v_max_i32_e32 v1, 0, v1
	v_max_i32_e32 v2, 0, v2
	v_mul_f32_e32 v22, v22, v22
	v_mul_f32_e32 v23, v23, v23
	v_cvt_pk_bf16_f32 v19, v22, v23
	global_store_dwordx4 v[20:21], v[16:19], off
	v_max_i32_e32 v12, 0, v12
	v_mul_f32_e32 v8, v8, v8
	v_lshl_add_u64 v[16:17], s[74:75], 0, v[80:81]
	v_max_i32_e32 v13, 0, v13
	v_mul_f32_e32 v9, v9, v9
	v_max_i32_e32 v14, 0, v14
	v_mul_f32_e32 v10, v10, v10
	v_max_i32_e32 v15, 0, v15
	v_mul_f32_e32 v11, v11, v11
	v_mul_f32_e32 v0, v0, v0
	v_mul_f32_e32 v4, v4, v4
	v_max_i32_e32 v5, 0, v5
	v_mul_f32_e32 v1, v1, v1
	v_mul_f32_e32 v2, v2, v2
	v_max_i32_e32 v3, 0, v3
	v_mul_f32_e32 v12, v12, v12
	v_mul_f32_e32 v13, v13, v13
	v_mul_f32_e32 v14, v14, v14
	v_mul_f32_e32 v15, v15, v15
	v_cvt_pk_bf16_f32 v8, v8, v9
	v_cvt_pk_bf16_f32 v9, v10, v11
	v_cvt_pk_bf16_f32 v10, v12, v13
	v_cvt_pk_bf16_f32 v11, v14, v15
	global_store_dwordx4 v[16:17], v[8:11], off
	v_mul_f32_e32 v5, v5, v5
	v_mul_f32_e32 v3, v3, v3
	v_cvt_pk_bf16_f32 v0, v0, v1
	v_cvt_pk_bf16_f32 v1, v2, v3
	v_cvt_pk_bf16_f32 v2, v4, v5
	v_add_co_u32_e32 v4, vcc, 0x10000, v16
	v_max_i32_e32 v6, 0, v6
	s_nop 0
	v_addc_co_u32_e32 v5, vcc, 0, v17, vcc
	v_max_i32_e32 v7, 0, v7
	s_andn2_b64 vcc, exec, s[2:3]
	s_mov_b64 s[2:3], -1
	v_mul_f32_e32 v6, v6, v6
	v_mul_f32_e32 v7, v7, v7
	v_cvt_pk_bf16_f32 v3, v6, v7
	global_store_dwordx4 v[4:5], v[0:3], off
	s_cbranch_vccnz .LBB0_1945
	s_andn2_b64 vcc, exec, s[6:7]
	s_cbranch_vccnz .LBB0_1944
	s_barrier
	s_branch .LBB0_1944

; __device__ __forceinline__ unsigned cvt_pk_bf16(float lo, float hi) { unsigned r; asm volatile("v_cvt_pk_bf16_f32 %0, %1, %2" : "=v"(r) : "v"(lo), "v"(hi)); return r; }
;     __device__ __forceinline__ void fused(f32x4 (&acc)[2][2][4][2], const Unit& un, int wr, int wc, int fr, int fq, PG8_LAS unsigned char* lds, int wid, int lane) const {
;     ...
;         const int row0 = un.pm * BM + wr * 64 + fr, col0 = un.pn * BM + wc * 32 + 8 * fq;
;         const size_t boff = (size_t)(un.pm >> 3) * bstride + col0;
;         { f32x4 gv[2][2];
; #pragma unroll
;           for (int bj = 0; bj < 2; ++bj)
; #pragma unroll
;               for (int n = 0; n < 2; ++n) gv[bj][n] = *(const f32x4*)(gate + boff + bj * HALF + n * 4);
; #pragma unroll
;           for (int ai = 0; ai < 2; ++ai)
; #pragma unroll
;               for (int m = 0; m < 4; ++m) { const size_t off = (size_t)(row0 + ai * HALF + m * 16) * ldc + col0;
; #pragma unroll
;                   for (int bj = 0; bj < 2; ++bj) {
; #pragma unroll
;                       for (int n = 0; n < 2; ++n) { f32x4 bs;
;                           if (BASE_F32) bs = *(const f32x4*)((const float*)base + off + bj * HALF + n * 4);
;                           else { const u32x2v hw = *(const u32x2v*)((const bf16_t*)base + off + bj * HALF + n * 4);
;                                  bs = (f32x4){__uint_as_float(hw.x << 16), __uint_as_float(hw.x & 0xffff0000u), __uint_as_float(hw.y << 16), __uint_as_float(hw.y & 0xffff0000u)}; }
;                           acc[ai][bj][m][n] = bs + gv[bj][n] * acc[ai][bj][m][n]; }
;                       if (out_h) { const f32x4 a0 = acc[ai][bj][m][0], a1 = acc[ai][bj][m][1]; u32x4 w; w.x = cvt_pk_bf16(a0[0], a0[1]); w.y = cvt_pk_bf16(a0[2], a0[3]); w.z = cvt_pk_bf16(a1[0], a1[1]); w.w = cvt_pk_bf16(a1[2], a1[3]);
;                           *(u32x4*)(out_h + off + bj * HALF) = w; } }
.LBB0_2029:
	v_mov_b32_e32 v32, 0
	s_barrier
	s_lshl_b32 s6, s9, 5
	v_mbcnt_lo_u32_b32 v32, -1, v32
	s_add_u32 s2, s60, 0x1a600000
	v_mbcnt_hi_u32_b32 v32, -1, v32
	s_addc_u32 s3, s61, 0
	v_or_b32_e32 v158, s33, v32
	s_lshl_b32 s7, s4, 8
	s_lshl_b32 s14, s62, 8
	s_or_b32 s6, s7, s6
	v_lshrrev_b32_e32 v32, 1, v158
	v_and_b32_e32 v159, 15, v158
	s_add_i32 s15, s14, s8
	v_and_or_b32 v152, v32, 24, s6
	s_ashr_i32 s6, s62, 3
	v_ashrrev_i32_e32 v153, 31, v152
	v_mov_b32_e32 v32, 0x3000
	v_or_b32_e32 v156, s15, v159
	v_mad_i64_i32 v[32:33], s[6:7], s6, v32, v[152:153]
	v_ashrrev_i32_e32 v157, 31, v156
	v_lshl_add_u64 v[150:151], v[32:33], 2, s[60:61]
	v_lshlrev_b64 v[32:33], 12, v[156:157]
	v_lshl_add_u64 v[32:33], s[2:3], 0, v[32:33]
	v_lshlrev_b64 v[148:149], 1, v[152:153]
	s_mov_b32 s15, 0x13a000
	v_lshl_add_u64 v[154:155], v[32:33], 0, v[148:149]
	v_add_co_u32_e32 v132, vcc, s15, v150
	s_nop 0
	v_addc_co_u32_e32 v133, vcc, 0, v151, vcc
	s_mov_b64 s[6:7], 0x13a000
	global_load_dwordx4 v[144:147], v[132:133], off
	v_lshl_add_u64 v[132:133], v[150:151], 0, s[6:7]
	global_load_dwordx4 v[140:143], v[132:133], off offset:16
	global_load_dwordx4 v[136:139], v[132:133], off offset:512
	s_nop 0
	global_load_dwordx4 v[132:135], v[132:133], off offset:528
	v_or_b32_e32 v164, 16, v156
	v_ashrrev_i32_e32 v165, 31, v164
	v_lshlrev_b64 v[164:165], 12, v[164:165]
	v_lshl_add_u64 v[164:165], s[2:3], 0, v[164:165]
	v_lshl_add_u64 v[164:165], v[164:165], 0, v[148:149]
	s_mov_b64 s[98:99], 0x10000
	s_mov_b64 s[100:101], 0x80000
	v_lshl_add_u64 v[232:233], v[154:155], 0, 0
	v_lshl_add_u64 v[234:235], v[232:233], 0, s[98:99]
	v_lshl_add_u64 v[236:237], v[234:235], 0, s[98:99]
	v_lshl_add_u64 v[238:239], v[236:237], 0, s[98:99]
	global_load_dwordx4 v[200:203], v[232:233], off
	global_load_dwordx4 v[204:207], v[232:233], off offset:256
	global_load_dwordx4 v[208:211], v[234:235], off
	global_load_dwordx4 v[212:215], v[234:235], off offset:256
	global_load_dwordx4 v[216:219], v[236:237], off
	global_load_dwordx4 v[220:223], v[236:237], off offset:256
	global_load_dwordx4 v[224:227], v[238:239], off
	global_load_dwordx4 v[228:231], v[238:239], off offset:256
	s_waitcnt vmcnt(0) lgkmcnt(0)
	v_lshlrev_b32_e32 v160, 16, v200
	v_and_b32_e32 v161, 0xffff0000, v200
	v_lshlrev_b32_e32 v32, 16, v201
	v_and_b32_e32 v33, 0xffff0000, v201
	v_lshlrev_b32_e32 v162, 16, v202
	v_and_b32_e32 v163, 0xffff0000, v202
	v_lshlrev_b32_e32 v34, 16, v203
	v_and_b32_e32 v35, 0xffff0000, v203
	v_pk_fma_f32 v[10:11], v[10:11], v[146:147], v[32:33]
	v_pk_fma_f32 v[8:9], v[8:9], v[144:145], v[160:161]
	v_pk_fma_f32 v[14:15], v[14:15], v[142:143], v[34:35]
	v_pk_fma_f32 v[12:13], v[12:13], v[140:141], v[162:163]
	v_cvt_pk_bf16_f32 v32, v8, v9
	v_cvt_pk_bf16_f32 v33, v10, v11
	s_nop 0
	v_cvt_pk_bf16_f32 v34, v12, v13
	v_cvt_pk_bf16_f32 v35, v14, v15
	s_nop 0
	global_store_dwordx4 v[154:155], v[32:35], off
	s_nop 1
	s_nop 0
	v_lshlrev_b32_e32 v32, 16, v204
	v_and_b32_e32 v33, 0xffff0000, v204
	v_lshlrev_b32_e32 v34, 16, v205
	v_and_b32_e32 v35, 0xffff0000, v205
	v_lshlrev_b32_e32 v160, 16, v206
	v_and_b32_e32 v161, 0xffff0000, v206
	v_lshlrev_b32_e32 v162, 16, v207
	v_and_b32_e32 v163, 0xffff0000, v207
	v_pk_fma_f32 v[34:35], v[30:31], v[138:139], v[34:35]
	v_pk_fma_f32 v[32:33], v[28:29], v[136:137], v[32:33]
	v_pk_fma_f32 v[30:31], v[18:19], v[134:135], v[162:163]
	v_pk_fma_f32 v[28:29], v[16:17], v[132:133], v[160:161]
	v_cvt_pk_bf16_f32 v16, v32, v33
	v_cvt_pk_bf16_f32 v17, v34, v35
	s_nop 0
	v_cvt_pk_bf16_f32 v18, v28, v29
	v_cvt_pk_bf16_f32 v19, v30, v31
	global_store_dwordx4 v[154:155], v[16:19], off offset:256
	s_nop 1
	v_lshlrev_b32_e32 v160, 16, v208
	v_and_b32_e32 v161, 0xffff0000, v208
	v_lshlrev_b32_e32 v16, 16, v209
	v_and_b32_e32 v17, 0xffff0000, v209
	v_lshlrev_b32_e32 v162, 16, v210
	v_and_b32_e32 v163, 0xffff0000, v210
	v_lshlrev_b32_e32 v166, 16, v211
	v_and_b32_e32 v167, 0xffff0000, v211
	v_pk_fma_f32 v[18:19], v[62:63], v[146:147], v[16:17]
	v_pk_fma_f32 v[16:17], v[60:61], v[144:145], v[160:161]
	v_pk_fma_f32 v[22:23], v[22:23], v[142:143], v[166:167]
	v_pk_fma_f32 v[20:21], v[20:21], v[140:141], v[162:163]
	v_cvt_pk_bf16_f32 v60, v16, v17
	v_cvt_pk_bf16_f32 v61, v18, v19
	v_or_b32_e32 v166, 32, v156
	v_cvt_pk_bf16_f32 v62, v20, v21
	v_cvt_pk_bf16_f32 v63, v22, v23
	v_ashrrev_i32_e32 v167, 31, v166
	v_lshlrev_b64 v[166:167], 12, v[166:167]
	global_store_dwordx4 v[164:165], v[60:63], off
	v_lshl_add_u64 v[166:167], s[2:3], 0, v[166:167]
	v_lshl_add_u64 v[166:167], v[166:167], 0, v[148:149]
	v_or_b32_e32 v156, 48, v156
	v_ashrrev_i32_e32 v157, 31, v156
	v_lshlrev_b64 v[156:157], 12, v[156:157]
	v_lshl_add_u64 v[156:157], s[2:3], 0, v[156:157]
	v_lshl_add_u64 v[156:157], v[156:157], 0, v[148:149]
	s_mov_b32 s2, 0x80000
	s_nop 1
	v_lshlrev_b32_e32 v60, 16, v212
	v_and_b32_e32 v61, 0xffff0000, v212
	v_lshlrev_b32_e32 v62, 16, v213
	v_and_b32_e32 v63, 0xffff0000, v213
	v_lshlrev_b32_e32 v160, 16, v214
	v_and_b32_e32 v161, 0xffff0000, v214
	v_lshlrev_b32_e32 v162, 16, v215
	v_and_b32_e32 v163, 0xffff0000, v215
	v_pk_fma_f32 v[62:63], v[58:59], v[138:139], v[62:63]
	v_pk_fma_f32 v[60:61], v[56:57], v[136:137], v[60:61]
	v_pk_fma_f32 v[58:59], v[50:51], v[134:135], v[162:163]
	v_pk_fma_f32 v[56:57], v[48:49], v[132:133], v[160:161]
	v_cvt_pk_bf16_f32 v48, v60, v61
	v_cvt_pk_bf16_f32 v49, v62, v63
	s_nop 0
	v_cvt_pk_bf16_f32 v50, v56, v57
	v_cvt_pk_bf16_f32 v51, v58, v59
	global_store_dwordx4 v[164:165], v[48:51], off offset:256
	s_nop 1
	v_lshlrev_b32_e32 v160, 16, v216
	v_and_b32_e32 v161, 0xffff0000, v216
	v_lshlrev_b32_e32 v48, 16, v217
	v_and_b32_e32 v49, 0xffff0000, v217
; __device__ __forceinline__ unsigned cvt_pk_bf16(float lo, float hi) { unsigned r; asm volatile("v_cvt_pk_bf16_f32 %0, %1, %2" : "=v"(r) : "v"(lo), "v"(hi)); return r; }
;     __device__ __forceinline__ void fused(f32x4 (&acc)[2][2][4][2], const Unit& un, int wr, int wc, int fr, int fq, PG8_LAS unsigned char* lds, int wid, int lane) const {
;     ...
;               for (int m = 0; m < 4; ++m) { const size_t off = (size_t)(row0 + ai * HALF + m * 16) * ldc + col0;
; #pragma unroll
;                   for (int bj = 0; bj < 2; ++bj) {
; #pragma unroll
;                       for (int n = 0; n < 2; ++n) { f32x4 bs;
;                           if (BASE_F32) bs = *(const f32x4*)((const float*)base + off + bj * HALF + n * 4);
;                           else { const u32x2v hw = *(const u32x2v*)((const bf16_t*)base + off + bj * HALF + n * 4);
;                                  bs = (f32x4){__uint_as_float(hw.x << 16), __uint_as_float(hw.x & 0xffff0000u), __uint_as_float(hw.y << 16), __uint_as_float(hw.y & 0xffff0000u)}; }
;                           acc[ai][bj][m][n] = bs + gv[bj][n] * acc[ai][bj][m][n]; }
;                       if (out_h) { const f32x4 a0 = acc[ai][bj][m][0], a1 = acc[ai][bj][m][1]; u32x4 w; w.x = cvt_pk_bf16(a0[0], a0[1]); w.y = cvt_pk_bf16(a0[2], a0[3]); w.z = cvt_pk_bf16(a1[0], a1[1]); w.w = cvt_pk_bf16(a1[2], a1[3]);
;                           *(u32x4*)(out_h + off + bj * HALF) = w; } }
	v_lshlrev_b32_e32 v162, 16, v218
	v_and_b32_e32 v163, 0xffff0000, v218
	v_lshlrev_b32_e32 v164, 16, v219
	v_and_b32_e32 v165, 0xffff0000, v219
	v_pk_fma_f32 v[50:51], v[78:79], v[146:147], v[48:49]
	v_pk_fma_f32 v[48:49], v[76:77], v[144:145], v[160:161]
	v_pk_fma_f32 v[54:55], v[54:55], v[142:143], v[164:165]
	v_pk_fma_f32 v[52:53], v[52:53], v[140:141], v[162:163]
	v_cvt_pk_bf16_f32 v76, v48, v49
	v_cvt_pk_bf16_f32 v77, v50, v51
	s_nop 0
	v_cvt_pk_bf16_f32 v78, v52, v53
	v_cvt_pk_bf16_f32 v79, v54, v55
	s_nop 0
	global_store_dwordx4 v[166:167], v[76:79], off
	s_nop 1
	s_nop 0
	v_lshlrev_b32_e32 v76, 16, v220
	v_and_b32_e32 v77, 0xffff0000, v220
	v_lshlrev_b32_e32 v78, 16, v221
	v_and_b32_e32 v79, 0xffff0000, v221
	v_lshlrev_b32_e32 v160, 16, v222
	v_and_b32_e32 v161, 0xffff0000, v222
	v_lshlrev_b32_e32 v162, 16, v223
	v_and_b32_e32 v163, 0xffff0000, v223
	v_pk_fma_f32 v[78:79], v[74:75], v[138:139], v[78:79]
	v_pk_fma_f32 v[76:77], v[72:73], v[136:137], v[76:77]
	v_pk_fma_f32 v[74:75], v[66:67], v[134:135], v[162:163]
	v_pk_fma_f32 v[72:73], v[64:65], v[132:133], v[160:161]
	v_cvt_pk_bf16_f32 v64, v76, v77
	v_cvt_pk_bf16_f32 v65, v78, v79
	s_nop 0
	v_cvt_pk_bf16_f32 v66, v72, v73
	v_cvt_pk_bf16_f32 v67, v74, v75
	global_store_dwordx4 v[166:167], v[64:67], off offset:256
	s_nop 1
	v_lshlrev_b32_e32 v160, 16, v224
	v_and_b32_e32 v161, 0xffff0000, v224
	v_lshlrev_b32_e32 v64, 16, v225
	v_and_b32_e32 v65, 0xffff0000, v225
	v_lshlrev_b32_e32 v162, 16, v226
	v_and_b32_e32 v163, 0xffff0000, v226
	v_lshlrev_b32_e32 v164, 16, v227
	v_and_b32_e32 v165, 0xffff0000, v227
	v_pk_fma_f32 v[66:67], v[130:131], v[146:147], v[64:65]
	v_pk_fma_f32 v[64:65], v[128:129], v[144:145], v[160:161]
	v_pk_fma_f32 v[70:71], v[70:71], v[142:143], v[164:165]
	v_pk_fma_f32 v[68:69], v[68:69], v[140:141], v[162:163]
	v_cvt_pk_bf16_f32 v128, v64, v65
	v_cvt_pk_bf16_f32 v129, v66, v67
	v_add_co_u32_e32 v164, vcc, s2, v154
	v_cvt_pk_bf16_f32 v130, v68, v69
	v_cvt_pk_bf16_f32 v131, v70, v71
	s_nop 0
	v_addc_co_u32_e32 v165, vcc, 0, v155, vcc
	global_store_dwordx4 v[156:157], v[128:131], off
	s_mov_b64 s[2:3], 0x80000
	s_nop 1
	v_lshlrev_b32_e32 v128, 16, v228
	v_and_b32_e32 v129, 0xffff0000, v228
	v_lshlrev_b32_e32 v130, 16, v229
	v_and_b32_e32 v131, 0xffff0000, v229
	v_lshlrev_b32_e32 v160, 16, v230
	v_and_b32_e32 v161, 0xffff0000, v230
	v_lshlrev_b32_e32 v162, 16, v231
	v_and_b32_e32 v163, 0xffff0000, v231
	v_pk_fma_f32 v[110:111], v[110:111], v[138:139], v[130:131]
	v_pk_fma_f32 v[108:109], v[108:109], v[136:137], v[128:129]
	v_pk_fma_f32 v[98:99], v[98:99], v[134:135], v[162:163]
	v_pk_fma_f32 v[96:97], v[96:97], v[132:133], v[160:161]
	v_cvt_pk_bf16_f32 v128, v108, v109
	v_cvt_pk_bf16_f32 v129, v110, v111
	s_nop 0
	v_cvt_pk_bf16_f32 v130, v96, v97
	v_cvt_pk_bf16_f32 v131, v98, v99
	global_store_dwordx4 v[156:157], v[128:131], off offset:256
	v_lshl_add_u64 v[156:157], v[154:155], 0, s[2:3]
	s_mov_b32 s2, 0x90000
	v_add_co_u32_e32 v166, vcc, s2, v154
	s_mov_b64 s[2:3], 0x90000
	s_nop 0
	v_addc_co_u32_e32 v167, vcc, 0, v155, vcc
	v_lshl_add_u64 v[232:233], v[232:233], 0, s[100:101]
	v_lshl_add_u64 v[234:235], v[234:235], 0, s[100:101]
	v_lshl_add_u64 v[236:237], v[236:237], 0, s[100:101]
	v_lshl_add_u64 v[238:239], v[238:239], 0, s[100:101]
	global_load_dwordx4 v[200:203], v[232:233], off
	global_load_dwordx4 v[204:207], v[232:233], off offset:256
	global_load_dwordx4 v[208:211], v[234:235], off
	global_load_dwordx4 v[212:215], v[234:235], off offset:256
	global_load_dwordx4 v[216:219], v[236:237], off
	global_load_dwordx4 v[220:223], v[236:237], off offset:256
	global_load_dwordx4 v[224:227], v[238:239], off
	global_load_dwordx4 v[228:231], v[238:239], off offset:256
	s_waitcnt vmcnt(0) lgkmcnt(0)
	v_lshlrev_b32_e32 v160, 16, v200
	v_and_b32_e32 v161, 0xffff0000, v200
	v_lshlrev_b32_e32 v128, 16, v201
	v_and_b32_e32 v129, 0xffff0000, v201
	v_lshlrev_b32_e32 v162, 16, v202
	v_and_b32_e32 v163, 0xffff0000, v202
	v_lshlrev_b32_e32 v130, 16, v203
	v_and_b32_e32 v131, 0xffff0000, v203
	v_pk_fma_f32 v[102:103], v[102:103], v[146:147], v[128:129]
	v_pk_fma_f32 v[100:101], v[100:101], v[144:145], v[160:161]
	v_pk_fma_f32 v[106:107], v[106:107], v[142:143], v[130:131]
	v_pk_fma_f32 v[104:105], v[104:105], v[140:141], v[162:163]
	v_cvt_pk_bf16_f32 v128, v100, v101
	v_cvt_pk_bf16_f32 v129, v102, v103
	s_nop 0
	v_cvt_pk_bf16_f32 v130, v104, v105
	v_cvt_pk_bf16_f32 v131, v106, v107
	s_nop 0
	global_store_dwordx4 v[164:165], v[128:131], off
	s_nop 1
	s_nop 0
	v_lshlrev_b32_e32 v128, 16, v204
	v_and_b32_e32 v129, 0xffff0000, v204
	v_lshlrev_b32_e32 v130, 16, v205
	v_and_b32_e32 v131, 0xffff0000, v205
	v_lshlrev_b32_e32 v160, 16, v206
	v_and_b32_e32 v161, 0xffff0000, v206
	v_lshlrev_b32_e32 v162, 16, v207
	v_and_b32_e32 v163, 0xffff0000, v207
	v_pk_fma_f32 v[126:127], v[126:127], v[138:139], v[130:131]
	v_pk_fma_f32 v[124:125], v[124:125], v[136:137], v[128:129]
	v_pk_fma_f32 v[114:115], v[114:115], v[134:135], v[162:163]
	v_pk_fma_f32 v[112:113], v[112:113], v[132:133], v[160:161]
	v_cvt_pk_bf16_f32 v128, v124, v125
	v_cvt_pk_bf16_f32 v129, v126, v127
	s_nop 0
	v_cvt_pk_bf16_f32 v130, v112, v113
	v_cvt_pk_bf16_f32 v131, v114, v115
	global_store_dwordx4 v[156:157], v[128:131], off offset:256
	v_lshl_add_u64 v[156:157], v[154:155], 0, s[2:3]
	s_mov_b32 s2, 0xa0000
	v_add_co_u32_e32 v164, vcc, s2, v154
	s_mov_b64 s[2:3], 0xa0000
	s_nop 0
	v_addc_co_u32_e32 v165, vcc, 0, v155, vcc
	s_nop 1
	v_lshlrev_b32_e32 v160, 16, v208
	v_and_b32_e32 v161, 0xffff0000, v208
	v_lshlrev_b32_e32 v128, 16, v209
	v_and_b32_e32 v129, 0xffff0000, v209
	v_lshlrev_b32_e32 v162, 16, v210
; __device__ __forceinline__ unsigned cvt_pk_bf16(float lo, float hi) { unsigned r; asm volatile("v_cvt_pk_bf16_f32 %0, %1, %2" : "=v"(r) : "v"(lo), "v"(hi)); return r; }
;     __device__ __forceinline__ void fused(f32x4 (&acc)[2][2][4][2], const Unit& un, int wr, int wc, int fr, int fq, PG8_LAS unsigned char* lds, int wid, int lane) const {
;     ...
;               for (int m = 0; m < 4; ++m) { const size_t off = (size_t)(row0 + ai * HALF + m * 16) * ldc + col0;
; #pragma unroll
;                   for (int bj = 0; bj < 2; ++bj) {
; #pragma unroll
;                       for (int n = 0; n < 2; ++n) { f32x4 bs;
;                           if (BASE_F32) bs = *(const f32x4*)((const float*)base + off + bj * HALF + n * 4);
;                           else { const u32x2v hw = *(const u32x2v*)((const bf16_t*)base + off + bj * HALF + n * 4);
;                                  bs = (f32x4){__uint_as_float(hw.x << 16), __uint_as_float(hw.x & 0xffff0000u), __uint_as_float(hw.y << 16), __uint_as_float(hw.y & 0xffff0000u)}; }
;                           acc[ai][bj][m][n] = bs + gv[bj][n] * acc[ai][bj][m][n]; }
;                       if (out_h) { const f32x4 a0 = acc[ai][bj][m][0], a1 = acc[ai][bj][m][1]; u32x4 w; w.x = cvt_pk_bf16(a0[0], a0[1]); w.y = cvt_pk_bf16(a0[2], a0[3]); w.z = cvt_pk_bf16(a1[0], a1[1]); w.w = cvt_pk_bf16(a1[2], a1[3]);
;                           *(u32x4*)(out_h + off + bj * HALF) = w; } }
;                   asm volatile("" : "+v"(acc[ai][0][m][0]), "+v"(acc[ai][0][m][1]), "+v"(acc[ai][1][m][0]), "+v"(acc[ai][1][m][1]));
;                   asm volatile("" ::: "memory"); } }
; #pragma unroll
;         for (int ai = 0; ai < 2; ++ai)
; #pragma unroll
;             for (int m = 0; m < 4; ++m) { float s = 0.f;
; #pragma unroll
;                 for (int bj = 0; bj < 2; ++bj)
; #pragma unroll
;                     for (int n = 0; n < 2; ++n) { const f32x4 x = acc[ai][bj][m][n]; s += (x[0] * x[0] + x[1] * x[1]) + (x[2] * x[2] + x[3] * x[3]); }
;                 s += __shfl_xor(s, 16); s += __shfl_xor(s, 32);
;                 if (fq == 0) P[(ai * HALF + wr * 64 + m * 16 + fr) * 4 + wc] = s; }
	v_and_b32_e32 v163, 0xffff0000, v210
	v_lshlrev_b32_e32 v130, 16, v211
	v_and_b32_e32 v131, 0xffff0000, v211
	v_pk_fma_f32 v[118:119], v[118:119], v[146:147], v[128:129]
	v_pk_fma_f32 v[116:117], v[116:117], v[144:145], v[160:161]
	v_pk_fma_f32 v[122:123], v[122:123], v[142:143], v[130:131]
	v_pk_fma_f32 v[120:121], v[120:121], v[140:141], v[162:163]
	v_cvt_pk_bf16_f32 v128, v116, v117
	v_cvt_pk_bf16_f32 v129, v118, v119
	s_nop 0
	v_cvt_pk_bf16_f32 v130, v120, v121
	v_cvt_pk_bf16_f32 v131, v122, v123
	s_nop 0
	global_store_dwordx4 v[166:167], v[128:131], off
	s_nop 1
	s_nop 0
	v_lshlrev_b32_e32 v128, 16, v212
	v_and_b32_e32 v129, 0xffff0000, v212
	v_lshlrev_b32_e32 v130, 16, v213
	v_and_b32_e32 v131, 0xffff0000, v213
	v_lshlrev_b32_e32 v160, 16, v214
	v_and_b32_e32 v161, 0xffff0000, v214
	v_lshlrev_b32_e32 v162, 16, v215
	v_and_b32_e32 v163, 0xffff0000, v215
	v_pk_fma_f32 v[94:95], v[94:95], v[138:139], v[130:131]
	v_pk_fma_f32 v[92:93], v[92:93], v[136:137], v[128:129]
	v_pk_fma_f32 v[90:91], v[90:91], v[134:135], v[162:163]
	v_pk_fma_f32 v[88:89], v[88:89], v[132:133], v[160:161]
	v_cvt_pk_bf16_f32 v128, v92, v93
	v_cvt_pk_bf16_f32 v129, v94, v95
	s_nop 0
	v_cvt_pk_bf16_f32 v130, v88, v89
	v_cvt_pk_bf16_f32 v131, v90, v91
	global_store_dwordx4 v[156:157], v[128:131], off offset:256
	v_lshl_add_u64 v[156:157], v[154:155], 0, s[2:3]
	s_mov_b32 s2, 0xb0000
	v_add_co_u32_e32 v166, vcc, s2, v154
	s_mov_b64 s[2:3], 0xb0000
	s_nop 0
	v_addc_co_u32_e32 v167, vcc, 0, v155, vcc
	s_nop 1
	v_lshlrev_b32_e32 v160, 16, v216
	v_and_b32_e32 v161, 0xffff0000, v216
	v_lshlrev_b32_e32 v128, 16, v217
	v_and_b32_e32 v129, 0xffff0000, v217
	v_lshlrev_b32_e32 v162, 16, v218
	v_and_b32_e32 v163, 0xffff0000, v218
	v_lshlrev_b32_e32 v130, 16, v219
	v_and_b32_e32 v131, 0xffff0000, v219
	v_pk_fma_f32 v[86:87], v[86:87], v[146:147], v[128:129]
	v_pk_fma_f32 v[84:85], v[84:85], v[144:145], v[160:161]
	v_pk_fma_f32 v[82:83], v[82:83], v[142:143], v[130:131]
	v_pk_fma_f32 v[80:81], v[80:81], v[140:141], v[162:163]
	v_cvt_pk_bf16_f32 v128, v84, v85
	v_cvt_pk_bf16_f32 v129, v86, v87
	s_nop 0
	v_cvt_pk_bf16_f32 v130, v80, v81
	v_cvt_pk_bf16_f32 v131, v82, v83
	s_nop 0
	global_store_dwordx4 v[164:165], v[128:131], off
	v_mul_f32_e32 v164, v29, v29
	v_mul_f32_e32 v165, v31, v31
	v_fmac_f32_e32 v164, v28, v28
	v_fmac_f32_e32 v165, v30, v30
	s_nop 1
	v_lshlrev_b32_e32 v128, 16, v220
	v_and_b32_e32 v129, 0xffff0000, v220
	v_lshlrev_b32_e32 v130, 16, v221
	v_and_b32_e32 v131, 0xffff0000, v221
	v_lshlrev_b32_e32 v160, 16, v222
	v_and_b32_e32 v161, 0xffff0000, v222
	v_lshlrev_b32_e32 v162, 16, v223
	v_and_b32_e32 v163, 0xffff0000, v223
	v_pk_fma_f32 v[46:47], v[46:47], v[138:139], v[130:131]
	v_pk_fma_f32 v[44:45], v[44:45], v[136:137], v[128:129]
	v_pk_fma_f32 v[42:43], v[42:43], v[134:135], v[162:163]
	v_pk_fma_f32 v[40:41], v[40:41], v[132:133], v[160:161]
	v_cvt_pk_bf16_f32 v128, v44, v45
	v_cvt_pk_bf16_f32 v129, v46, v47
	v_lshl_add_u64 v[160:161], v[154:155], 0, s[2:3]
	v_cvt_pk_bf16_f32 v130, v40, v41
	v_cvt_pk_bf16_f32 v131, v42, v43
	global_store_dwordx4 v[156:157], v[128:131], off offset:256
	v_mul_f32_e32 v162, v33, v33
	v_mul_f32_e32 v163, v35, v35
	v_fmac_f32_e32 v162, v32, v32
	v_fmac_f32_e32 v163, v34, v34
	s_lshl_b32 s2, s9, 2
	s_add_i32 s2, s2, 0
	s_nop 1
	v_lshlrev_b32_e32 v154, 16, v224
	v_and_b32_e32 v155, 0xffff0000, v224
	v_lshlrev_b32_e32 v128, 16, v225
	v_and_b32_e32 v129, 0xffff0000, v225
	v_lshlrev_b32_e32 v156, 16, v226
	v_and_b32_e32 v157, 0xffff0000, v226
	v_lshlrev_b32_e32 v130, 16, v227
	v_and_b32_e32 v131, 0xffff0000, v227
	v_pk_fma_f32 v[38:39], v[38:39], v[146:147], v[128:129]
	v_pk_fma_f32 v[36:37], v[36:37], v[144:145], v[154:155]
	v_pk_fma_f32 v[26:27], v[26:27], v[142:143], v[130:131]
	v_pk_fma_f32 v[24:25], v[24:25], v[140:141], v[156:157]
	v_cvt_pk_bf16_f32 v142, v36, v37
	v_cvt_pk_bf16_f32 v143, v38, v39
	v_mbcnt_lo_u32_b32 v128, -1, 0
	v_cvt_pk_bf16_f32 v144, v24, v25
	v_cvt_pk_bf16_f32 v145, v26, v27
	v_mbcnt_hi_u32_b32 v129, -1, v128
	v_mul_f32_e32 v140, v9, v9
	v_mul_f32_e32 v141, v11, v11
	v_mul_f32_e32 v146, v13, v13
	v_mul_f32_e32 v147, v15, v15
	v_and_b32_e32 v130, 64, v129
	v_fmac_f32_e32 v140, v8, v8
	v_fmac_f32_e32 v141, v10, v10
	v_fmac_f32_e32 v146, v12, v12
	v_fmac_f32_e32 v147, v14, v14
	v_xor_b32_e32 v128, 16, v129
	v_add_u32_e32 v130, 64, v130
	v_add_f32_e32 v140, v140, v141
	v_add_f32_e32 v141, v146, v147
	v_cmp_lt_i32_e32 vcc, v128, v130
	v_add_f32_e32 v146, v162, v163
	v_add_f32_e32 v140, v140, v141
	v_cndmask_b32_e32 v128, v129, v128, vcc
	v_add_f32_e32 v147, v164, v165
	v_add_f32_e32 v140, v146, v140
	v_lshlrev_b32_e32 v128, 2, v128
	v_add_f32_e32 v140, v147, v140
	ds_bpermute_b32 v141, v128, v140
	v_xor_b32_e32 v131, 32, v129
	v_cmp_lt_i32_e32 vcc, v131, v130
	global_store_dwordx4 v[166:167], v[142:145], off
	v_and_b32_e32 v130, 63, v158
	v_cndmask_b32_e32 v129, v129, v131, vcc
	v_lshlrev_b32_e32 v129, 2, v129
	s_waitcnt lgkmcnt(0)
	v_add_f32_e32 v140, v140, v141
	ds_bpermute_b32 v141, v129, v140
	v_cmp_gt_u32_e32 vcc, 16, v130
	s_waitcnt vmcnt(0)
	v_lshlrev_b32_e32 v142, 16, v228
	v_and_b32_e32 v143, 0xffff0000, v228
	v_lshlrev_b32_e32 v144, 16, v229
	v_and_b32_e32 v145, 0xffff0000, v229
	v_lshlrev_b32_e32 v146, 16, v230
	v_and_b32_e32 v147, 0xffff0000, v230
	v_lshlrev_b32_e32 v154, 16, v231
	v_and_b32_e32 v155, 0xffff0000, v231
	v_pk_fma_f32 v[6:7], v[6:7], v[138:139], v[144:145]
	v_pk_fma_f32 v[4:5], v[4:5], v[136:137], v[142:143]
	v_pk_fma_f32 v[2:3], v[2:3], v[134:135], v[154:155]
	v_pk_fma_f32 v[0:1], v[0:1], v[132:133], v[146:147]
	v_cvt_pk_bf16_f32 v132, v4, v5
	v_cvt_pk_bf16_f32 v133, v6, v7
	v_or_b32_e32 v144, s8, v159
	v_cvt_pk_bf16_f32 v134, v0, v1
	v_cvt_pk_bf16_f32 v135, v2, v3
	global_store_dwordx4 v[160:161], v[132:135], off offset:256
	v_lshl_add_u32 v131, v144, 4, s2
	s_and_saveexec_b64 s[2:3], vcc
	v_readlane_b32 s96, v254, 47
	s_cbranch_execz .LBB0_2031
	s_waitcnt lgkmcnt(0)
	v_add_f32_e32 v132, v140, v141
	ds_write_b32 v131, v132

;     __device__ __forceinline__ void fused(f32x4 (&acc)[2][2][4][2], const Unit& un, int wr, int wc, int fr, int fq, PG8_LAS unsigned char* lds, int wid, int lane) const {
;     ...
;         asm volatile("s_waitcnt lgkmcnt(0)" ::: "memory"); __builtin_amdgcn_s_barrier(); asm volatile("" ::: "memory");
;         const int row = wid * 32 + (lane & 31);
;         if (lane < 32) { const float tot = (P[row * 4 + 0] + P[row * 4 + 1]) + (P[row * 4 + 2] + P[row * 4 + 3]);
;             __hip_atomic_store(xbuf + ((size_t)(un.pm * BM + row) * 8 + un.pn), __float_as_uint(tot), __ATOMIC_RELAXED, __HIP_MEMORY_SCOPE_AGENT); }
.LBB0_2045:
	s_or_b64 exec, exec, s[2:3]
	s_add_u32 s64, s60, 0x3c6c0000
	s_addc_u32 s65, s61, 0
	s_lshl_b32 s1, s1, 5
	s_waitcnt lgkmcnt(0)
	s_barrier
	v_and_or_b32 v134, v158, 31, s1
	v_add_u32_e32 v128, s14, v134
	v_cmp_gt_u32_e64 s[2:3], 32, v130
	s_waitcnt lgkmcnt(0)
	v_ashrrev_i32_e32 v129, 31, v128
	s_and_saveexec_b64 s[6:7], s[2:3]
	s_cbranch_execz .LBB0_2047
	v_lshl_add_u32 v131, v134, 4, 0
	ds_read_b128 v[136:139], v131
	v_lshlrev_b64 v[132:133], 5, v[128:129]
	v_lshl_add_u64 v[132:133], s[64:65], 0, v[132:133]
	v_lshl_add_u64 v[132:133], s[4:5], 2, v[132:133]
	s_waitcnt lgkmcnt(0)
	v_mov_b32_e32 v140, v137
	v_mov_b32_e32 v141, v138
	v_mov_b32_e32 v137, v139
	v_pk_add_f32 v[136:137], v[140:141], v[136:137]
	s_nop 0
	v_pk_add_f32 v[136:137], v[136:137], v[136:137] op_sel:[0,1] op_sel_hi:[1,0]
	global_store_dword v[132:133], v136, off sc1

;     __device__ __forceinline__ void fused(f32x4 (&acc)[2][2][4][2], const Unit& un, int wr, int wc, int fr, int fq, PG8_LAS unsigned char* lds, int wid, int lane) const {
;     ...
;                 if (__builtin_amdgcn_s_memrealtime() - t0 > 2000000ull) {
;                     if (lane == 0) { unsigned expect = 0u; __hip_atomic_compare_exchange_strong(tmo + 1, &expect, code | (unsigned)(un.pm & 0xff), __ATOMIC_RELAXED, __ATOMIC_RELAXED, __HIP_MEMORY_SCOPE_AGENT);
;                                      __hip_atomic_store(tmo, 1u, __ATOMIC_RELAXED, __HIP_MEMORY_SCOPE_AGENT); }
;                     dead = true; break; }
.LBB0_2059:
	s_or_saveexec_b64 s[66:67], s[6:7]
	s_mov_b64 s[6:7], 0
	s_xor_b64 exec, exec, s[66:67]
	s_cbranch_execz .LBB0_2061
	s_and_b32 s0, s62, 0xcf
	s_or_b32 s0, s0, 0x730
	v_mov_b32_e32 v130, s0
	v_mov_b32_e32 v131, 0
	v_mov_b64_e32 v[132:133], s[60:61]
	flat_atomic_cmpswap v[132:133], v[130:131] offset:4
	s_mov_b64 s[6:7], exec
	v_mov_b32_e32 v130, 1
	global_store_dword v[132:133], v130, off sc1

; __device__ __forceinline__ unsigned cvt_pk_bf16(float lo, float hi) { unsigned r; asm volatile("v_cvt_pk_bf16_f32 %0, %1, %2" : "=v"(r) : "v"(lo), "v"(hi)); return r; }
;     __device__ __forceinline__ void fused(f32x4 (&acc)[2][2][4][2], const Unit& un, int wr, int wc, int fr, int fq, PG8_LAS unsigned char* lds, int wid, int lane) const {
;     ...
;         asm volatile("s_waitcnt lgkmcnt(0)" ::: "memory"); __builtin_amdgcn_s_barrier(); asm volatile("" ::: "memory");
;         const float qnan = __builtin_nanf("");
;         f32x4 cg[2][2], sh[2][2];
; #pragma unroll
;         for (int bj = 0; bj < 2; ++bj)
; #pragma unroll
;             for (int n = 0; n < 2; ++n) { const f32x4 g4 = *(const f32x4*)(gain + col0 + bj * HALF + n * 4);
;                 if (MODE == 0) { const f32x4 sc4 = *(const f32x4*)(scale + boff + bj * HALF + n * 4); cg[bj][n] = g4 * (sc4 + 1.0f); sh[bj][n] = *(const f32x4*)(shift + boff + bj * HALF + n * 4); }
;                 else { cg[bj][n] = g4; sh[bj][n] = (f32x4){0.f, 0.f, 0.f, 0.f}; } }
; #pragma unroll
;         for (int ai = 0; ai < 2; ++ai)
; #pragma unroll
;             for (int m = 0; m < 4; ++m) { const int r = ai * HALF + wr * 64 + m * 16 + fr; const float rs = S[r]; const size_t off = (size_t)(un.pm * BM + r) * ldc + col0;
; #pragma unroll
;                 for (int bj = 0; bj < 2; ++bj) { f32x4 y0 = (acc[ai][bj][m][0] * rs) * cg[bj][0] + sh[bj][0], y1 = (acc[ai][bj][m][1] * rs) * cg[bj][1] + sh[bj][1];
;                     if (bad) { y0 = (f32x4){qnan, qnan, qnan, qnan}; y1 = y0; }
;                     if (MODE == 0) { u32x4 w; w.x = cvt_pk_bf16(y0[0], y0[1]); w.y = cvt_pk_bf16(y0[2], y0[3]); w.z = cvt_pk_bf16(y1[0], y1[1]); w.w = cvt_pk_bf16(y1[2], y1[3]); *(u32x4*)(u + off + bj * HALF) = w; }
;                     else { *(f32x4*)(outf + off + bj * HALF) = y0; *(f32x4*)(outf + off + bj * HALF + 4) = y1; } } }
.LBB0_2069:
	s_or_b64 exec, exec, s[4:5]
	v_readlane_b32 s36, v254, 11
	v_readlane_b32 s40, v254, 15
	v_readlane_b32 s41, v254, 16
	s_mov_b64 s[0:1], 0x4000
	s_waitcnt lgkmcnt(0)
	s_barrier
	v_lshl_add_u64 v[128:129], v[152:153], 2, s[40:41]
	v_lshl_add_u64 v[130:131], v[128:129], 0, s[0:1]
	s_mov_b64 s[0:1], 0x162000
	v_lshl_add_u64 v[136:137], v[150:151], 0, s[0:1]
	s_mov_b64 s[0:1], 0x160000
	v_lshl_add_u64 v[138:139], v[150:151], 0, s[0:1]
	s_movk_i32 s0, 0x4000
	v_add_co_u32_e32 v128, vcc, s0, v128
	s_mov_b32 s0, 0x162000
	s_nop 0
	v_addc_co_u32_e32 v129, vcc, 0, v129, vcc
	global_load_dwordx4 v[160:163], v[128:129], off
	global_load_dwordx4 v[152:155], v[136:137], off offset:16
	v_add_co_u32_e32 v128, vcc, s0, v150
	global_load_dwordx4 v[164:167], v[136:137], off offset:512
	global_load_dwordx4 v[132:135], v[138:139], off offset:16
	global_load_dwordx4 v[168:171], v[136:137], off offset:528
	global_load_dwordx4 v[172:175], v[130:131], off offset:16
	global_load_dwordx4 v[176:179], v[130:131], off offset:512
	v_addc_co_u32_e32 v129, vcc, 0, v151, vcc
	global_load_dwordx4 v[180:183], v[130:131], off offset:528
	global_load_dwordx4 v[184:187], v[128:129], off
	s_mov_b32 s0, 0x160000
	v_add_co_u32_e32 v128, vcc, s0, v150
	v_lshl_add_u32 v157, v144, 2, 0
	s_nop 0
	v_addc_co_u32_e32 v129, vcc, 0, v151, vcc
	global_load_dwordx4 v[140:143], v[128:129], off
	s_nop 0
	global_load_dwordx4 v[128:131], v[138:139], off offset:512
	s_nop 0
	global_load_dwordx4 v[136:139], v[138:139], off offset:528
	ds_read_b32 v188, v157 offset:4096
	v_add_u32_e32 v144, s14, v144
	s_add_u32 s2, s60, 0x1e600000
	v_ashrrev_i32_e32 v145, 31, v144
	s_addc_u32 s3, s61, 0
	v_lshlrev_b64 v[146:147], 12, v[144:145]
	s_waitcnt lgkmcnt(0)
	v_pk_mul_f32 v[192:193], v[8:9], v[188:189] op_sel_hi:[1,0]
	v_pk_mul_f32 v[194:195], v[10:11], v[188:189] op_sel_hi:[1,0]
	v_lshl_add_u64 v[190:191], s[2:3], 0, v[146:147]
	v_pk_mul_f32 v[196:197], v[12:13], v[188:189] op_sel_hi:[1,0]
	v_pk_mul_f32 v[198:199], v[14:15], v[188:189] op_sel_hi:[1,0]
	v_mov_b32_e32 v156, 0x7fc00000
	v_cmp_eq_u32_e32 vcc, 0, v158
	v_pk_mul_f32 v[28:29], v[28:29], v[188:189] op_sel_hi:[1,0]
	v_pk_mul_f32 v[30:31], v[30:31], v[188:189] op_sel_hi:[1,0]
	v_pk_mul_f32 v[32:33], v[32:33], v[188:189] op_sel_hi:[1,0]
	v_pk_mul_f32 v[34:35], v[34:35], v[188:189] op_sel_hi:[1,0]
	v_readlane_b32 s37, v254, 12
	v_readlane_b32 s38, v254, 13
	v_readlane_b32 s39, v254, 14
	v_readlane_b32 s42, v254, 17
	v_readlane_b32 s43, v254, 18
	v_readlane_b32 s44, v254, 19
	v_readlane_b32 s45, v254, 20
	v_readlane_b32 s46, v254, 21
	v_readlane_b32 s47, v254, 22
	v_readlane_b32 s48, v254, 23
	v_readlane_b32 s49, v254, 24
	v_readlane_b32 s50, v254, 25
	v_readlane_b32 s51, v254, 26
	s_waitcnt vmcnt(0)
	v_pk_add_f32 v[12:13], v[166:167], 1.0 op_sel_hi:[1,0]
	v_pk_add_f32 v[8:9], v[154:155], 1.0 op_sel_hi:[1,0]
	v_pk_add_f32 v[10:11], v[152:153], 1.0 op_sel_hi:[1,0]
	v_pk_add_f32 v[152:153], v[170:171], 1.0 op_sel_hi:[1,0]
	v_pk_add_f32 v[154:155], v[168:169], 1.0 op_sel_hi:[1,0]
	v_pk_mul_f32 v[146:147], v[174:175], v[8:9]
	v_pk_mul_f32 v[150:151], v[172:173], v[10:11]
	v_pk_mul_f32 v[8:9], v[182:183], v[152:153]
	v_pk_mul_f32 v[10:11], v[180:181], v[154:155]
	v_pk_add_f32 v[152:153], v[186:187], 1.0 op_sel_hi:[1,0]
	v_pk_add_f32 v[154:155], v[184:185], 1.0 op_sel_hi:[1,0]
	v_pk_mul_f32 v[152:153], v[162:163], v[152:153]
	v_pk_mul_f32 v[154:155], v[160:161], v[154:155]
	v_pk_add_f32 v[14:15], v[164:165], 1.0 op_sel_hi:[1,0]
	v_pk_fma_f32 v[164:165], v[146:147], v[198:199], v[134:135]
	v_pk_fma_f32 v[166:167], v[150:151], v[196:197], v[132:133]
	v_pk_fma_f32 v[160:161], v[152:153], v[194:195], v[142:143]
	v_pk_fma_f32 v[162:163], v[154:155], v[192:193], v[140:141]
	v_pk_mul_f32 v[12:13], v[178:179], v[12:13]
	v_pk_mul_f32 v[14:15], v[176:177], v[14:15]
	v_cndmask_b32_e32 v145, v156, v160, vcc
	v_cndmask_b32_e32 v159, v156, v161, vcc
	v_cndmask_b32_e32 v158, v156, v162, vcc
	v_cndmask_b32_e32 v160, v156, v163, vcc
	v_cndmask_b32_e32 v161, v156, v164, vcc
	v_cndmask_b32_e32 v162, v156, v165, vcc
	v_cndmask_b32_e32 v163, v156, v166, vcc
	v_pk_fma_f32 v[30:31], v[8:9], v[30:31], v[138:139]
	v_pk_fma_f32 v[28:29], v[10:11], v[28:29], v[136:137]
	v_cndmask_b32_e32 v164, v156, v167, vcc
	v_cvt_pk_bf16_f32 v158, v158, v160
	v_cvt_pk_bf16_f32 v159, v145, v159
	v_cvt_pk_bf16_f32 v160, v163, v164
	v_cvt_pk_bf16_f32 v161, v161, v162
	v_lshl_add_u64 v[162:163], v[190:191], 0, v[148:149]
	v_pk_fma_f32 v[34:35], v[12:13], v[34:35], v[130:131]
	v_pk_fma_f32 v[32:33], v[14:15], v[32:33], v[128:129]
	v_cndmask_b32_e32 v145, v156, v30, vcc
	v_cndmask_b32_e32 v31, v156, v31, vcc
	v_cndmask_b32_e32 v30, v156, v28, vcc
	global_store_dwordx4 v[162:163], v[158:161], off
	v_cndmask_b32_e32 v34, v156, v34, vcc
	v_cndmask_b32_e32 v35, v156, v35, vcc
	v_cndmask_b32_e32 v32, v156, v32, vcc
	v_cndmask_b32_e32 v33, v156, v33, vcc
	v_cndmask_b32_e32 v158, v156, v29, vcc
	v_cvt_pk_bf16_f32 v28, v32, v33
	v_cvt_pk_bf16_f32 v29, v34, v35
	v_cvt_pk_bf16_f32 v30, v30, v158
	v_cvt_pk_bf16_f32 v31, v145, v31
	global_store_dwordx4 v[162:163], v[28:31], off offset:256
	ds_read_b32 v28, v157 offset:4160
	s_waitcnt lgkmcnt(0)
; __device__ __forceinline__ unsigned cvt_pk_bf16(float lo, float hi) { unsigned r; asm volatile("v_cvt_pk_bf16_f32 %0, %1, %2" : "=v"(r) : "v"(lo), "v"(hi)); return r; }
;     __device__ __forceinline__ void fused(f32x4 (&acc)[2][2][4][2], const Unit& un, int wr, int wc, int fr, int fq, PG8_LAS unsigned char* lds, int wid, int lane) const {
;     ...
;         for (int ai = 0; ai < 2; ++ai)
; #pragma unroll
;             for (int m = 0; m < 4; ++m) { const int r = ai * HALF + wr * 64 + m * 16 + fr; const float rs = S[r]; const size_t off = (size_t)(un.pm * BM + r) * ldc + col0;
; #pragma unroll
;                 for (int bj = 0; bj < 2; ++bj) { f32x4 y0 = (acc[ai][bj][m][0] * rs) * cg[bj][0] + sh[bj][0], y1 = (acc[ai][bj][m][1] * rs) * cg[bj][1] + sh[bj][1];
;                     if (bad) { y0 = (f32x4){qnan, qnan, qnan, qnan}; y1 = y0; }
;                     if (MODE == 0) { u32x4 w; w.x = cvt_pk_bf16(y0[0], y0[1]); w.y = cvt_pk_bf16(y0[2], y0[3]); w.z = cvt_pk_bf16(y1[0], y1[1]); w.w = cvt_pk_bf16(y1[2], y1[3]); *(u32x4*)(u + off + bj * HALF) = w; }
;                     else { *(f32x4*)(outf + off + bj * HALF) = y0; *(f32x4*)(outf + off + bj * HALF + 4) = y1; } } }
	v_pk_mul_f32 v[16:17], v[16:17], v[28:29] op_sel_hi:[1,0]
	v_pk_mul_f32 v[18:19], v[18:19], v[28:29] op_sel_hi:[1,0]
	v_pk_mul_f32 v[20:21], v[20:21], v[28:29] op_sel_hi:[1,0]
	v_add_u32_e32 v30, 16, v144
	v_pk_fma_f32 v[18:19], v[152:153], v[18:19], v[142:143]
	v_pk_fma_f32 v[16:17], v[154:155], v[16:17], v[140:141]
	v_pk_fma_f32 v[20:21], v[150:151], v[20:21], v[132:133]
	v_ashrrev_i32_e32 v31, 31, v30
	v_cndmask_b32_e32 v18, v156, v18, vcc
	v_cndmask_b32_e32 v16, v156, v16, vcc
	v_cndmask_b32_e32 v17, v156, v17, vcc
	v_cndmask_b32_e32 v20, v156, v20, vcc
	v_cndmask_b32_e32 v21, v156, v21, vcc
	v_pk_mul_f32 v[22:23], v[22:23], v[28:29] op_sel_hi:[1,0]
	v_cndmask_b32_e32 v19, v156, v19, vcc
	v_cvt_pk_bf16_f32 v16, v16, v17
	v_cvt_pk_bf16_f32 v17, v18, v19
	v_cvt_pk_bf16_f32 v18, v20, v21
	v_lshlrev_b64 v[20:21], 12, v[30:31]
	v_pk_fma_f32 v[22:23], v[146:147], v[22:23], v[134:135]
	v_lshl_add_u64 v[20:21], s[2:3], 0, v[20:21]
	v_cndmask_b32_e32 v22, v156, v22, vcc
	v_cndmask_b32_e32 v23, v156, v23, vcc
	v_cvt_pk_bf16_f32 v19, v22, v23
	v_lshl_add_u64 v[20:21], v[20:21], 0, v[148:149]
	global_store_dwordx4 v[20:21], v[16:19], off
	v_pk_mul_f32 v[22:23], v[56:57], v[28:29] op_sel_hi:[1,0]
	s_nop 0
	v_pk_mul_f32 v[16:17], v[60:61], v[28:29] op_sel_hi:[1,0]
	v_pk_mul_f32 v[18:19], v[62:63], v[28:29] op_sel_hi:[1,0]
	v_pk_fma_f32 v[16:17], v[14:15], v[16:17], v[128:129]
	v_pk_fma_f32 v[18:19], v[12:13], v[18:19], v[130:131]
	v_pk_mul_f32 v[28:29], v[58:59], v[28:29] op_sel_hi:[1,0]
	v_pk_fma_f32 v[22:23], v[10:11], v[22:23], v[136:137]
	v_pk_fma_f32 v[28:29], v[8:9], v[28:29], v[138:139]
	v_cndmask_b32_e32 v18, v156, v18, vcc
	v_cndmask_b32_e32 v19, v156, v19, vcc
	v_cndmask_b32_e32 v16, v156, v16, vcc
	v_cndmask_b32_e32 v17, v156, v17, vcc
	v_cndmask_b32_e32 v28, v156, v28, vcc
	v_cndmask_b32_e32 v29, v156, v29, vcc
	v_cndmask_b32_e32 v22, v156, v22, vcc
	v_cndmask_b32_e32 v23, v156, v23, vcc
	v_cvt_pk_bf16_f32 v16, v16, v17
	v_cvt_pk_bf16_f32 v17, v18, v19
	v_cvt_pk_bf16_f32 v18, v22, v23
	v_cvt_pk_bf16_f32 v19, v28, v29
	global_store_dwordx4 v[20:21], v[16:19], off offset:256
	ds_read_b32 v20, v157 offset:4224
	v_add_u32_e32 v22, 32, v144
	v_ashrrev_i32_e32 v23, 31, v22
	v_lshlrev_b64 v[22:23], 12, v[22:23]
	v_lshl_add_u64 v[22:23], s[2:3], 0, v[22:23]
	s_waitcnt lgkmcnt(0)
	v_pk_mul_f32 v[16:17], v[48:49], v[20:21] op_sel_hi:[1,0]
	v_pk_mul_f32 v[18:19], v[50:51], v[20:21] op_sel_hi:[1,0]
	v_pk_fma_f32 v[16:17], v[154:155], v[16:17], v[140:141]
	v_pk_fma_f32 v[18:19], v[152:153], v[18:19], v[142:143]
	v_pk_mul_f32 v[28:29], v[52:53], v[20:21] op_sel_hi:[1,0]
	v_pk_mul_f32 v[30:31], v[54:55], v[20:21] op_sel_hi:[1,0]
	v_pk_fma_f32 v[28:29], v[150:151], v[28:29], v[132:133]
	v_pk_fma_f32 v[30:31], v[146:147], v[30:31], v[134:135]
	v_cndmask_b32_e32 v18, v156, v18, vcc
	v_cndmask_b32_e32 v19, v156, v19, vcc
	v_cndmask_b32_e32 v16, v156, v16, vcc
	v_cndmask_b32_e32 v17, v156, v17, vcc
	v_cndmask_b32_e32 v21, v156, v30, vcc
	v_cndmask_b32_e32 v30, v156, v31, vcc
	v_cndmask_b32_e32 v28, v156, v28, vcc
	v_cndmask_b32_e32 v29, v156, v29, vcc
	v_cvt_pk_bf16_f32 v16, v16, v17
	v_cvt_pk_bf16_f32 v17, v18, v19
	v_cvt_pk_bf16_f32 v18, v28, v29
	v_cvt_pk_bf16_f32 v19, v21, v30
	v_lshl_add_u64 v[22:23], v[22:23], 0, v[148:149]
	global_store_dwordx4 v[22:23], v[16:19], off
	v_pk_mul_f32 v[28:29], v[72:73], v[20:21] op_sel_hi:[1,0]
	s_nop 0
	v_pk_mul_f32 v[16:17], v[76:77], v[20:21] op_sel_hi:[1,0]
	v_pk_mul_f32 v[18:19], v[78:79], v[20:21] op_sel_hi:[1,0]
	v_pk_fma_f32 v[16:17], v[14:15], v[16:17], v[128:129]
	v_pk_fma_f32 v[18:19], v[12:13], v[18:19], v[130:131]
	v_pk_mul_f32 v[20:21], v[74:75], v[20:21] op_sel_hi:[1,0]
	v_pk_fma_f32 v[28:29], v[10:11], v[28:29], v[136:137]
	v_pk_fma_f32 v[20:21], v[8:9], v[20:21], v[138:139]
	v_cndmask_b32_e32 v18, v156, v18, vcc
	v_cndmask_b32_e32 v19, v156, v19, vcc
	v_cndmask_b32_e32 v16, v156, v16, vcc
	v_cndmask_b32_e32 v17, v156, v17, vcc
	v_cndmask_b32_e32 v20, v156, v20, vcc
	v_cndmask_b32_e32 v21, v156, v21, vcc
	v_cndmask_b32_e32 v28, v156, v28, vcc
	v_cndmask_b32_e32 v29, v156, v29, vcc
	v_cvt_pk_bf16_f32 v16, v16, v17
	v_cvt_pk_bf16_f32 v17, v18, v19
	v_cvt_pk_bf16_f32 v18, v28, v29
	v_cvt_pk_bf16_f32 v19, v20, v21
	global_store_dwordx4 v[22:23], v[16:19], off offset:256
	ds_read_b32 v20, v157 offset:4288
	v_add_u32_e32 v22, 48, v144
	v_ashrrev_i32_e32 v23, 31, v22
	v_lshlrev_b64 v[22:23], 12, v[22:23]
	v_lshl_add_u64 v[22:23], s[2:3], 0, v[22:23]
	s_waitcnt lgkmcnt(0)
	v_pk_mul_f32 v[16:17], v[64:65], v[20:21] op_sel_hi:[1,0]
	v_pk_mul_f32 v[18:19], v[66:67], v[20:21] op_sel_hi:[1,0]
	v_pk_fma_f32 v[16:17], v[154:155], v[16:17], v[140:141]
	v_pk_fma_f32 v[18:19], v[152:153], v[18:19], v[142:143]
	v_pk_mul_f32 v[28:29], v[68:69], v[20:21] op_sel_hi:[1,0]
	v_pk_mul_f32 v[30:31], v[70:71], v[20:21] op_sel_hi:[1,0]
	v_pk_fma_f32 v[28:29], v[150:151], v[28:29], v[132:133]
	v_pk_fma_f32 v[30:31], v[146:147], v[30:31], v[134:135]
	v_cndmask_b32_e32 v18, v156, v18, vcc
	v_cndmask_b32_e32 v19, v156, v19, vcc
	v_cndmask_b32_e32 v16, v156, v16, vcc
	v_cndmask_b32_e32 v17, v156, v17, vcc
	v_cndmask_b32_e32 v21, v156, v30, vcc
	v_cndmask_b32_e32 v30, v156, v31, vcc
	v_cndmask_b32_e32 v28, v156, v28, vcc
	v_cndmask_b32_e32 v29, v156, v29, vcc
	v_cvt_pk_bf16_f32 v16, v16, v17
	v_cvt_pk_bf16_f32 v17, v18, v19
	v_cvt_pk_bf16_f32 v18, v28, v29
	v_cvt_pk_bf16_f32 v19, v21, v30
	v_lshl_add_u64 v[22:23], v[22:23], 0, v[148:149]
	global_store_dwordx4 v[22:23], v[16:19], off
	v_pk_mul_f32 v[28:29], v[96:97], v[20:21] op_sel_hi:[1,0]
	s_nop 0
	v_pk_mul_f32 v[16:17], v[108:109], v[20:21] op_sel_hi:[1,0]
	v_pk_mul_f32 v[18:19], v[110:111], v[20:21] op_sel_hi:[1,0]
	v_pk_fma_f32 v[16:17], v[14:15], v[16:17], v[128:129]
	v_pk_fma_f32 v[18:19], v[12:13], v[18:19], v[130:131]
	v_pk_mul_f32 v[20:21], v[98:99], v[20:21] op_sel_hi:[1,0]
	v_pk_fma_f32 v[28:29], v[10:11], v[28:29], v[136:137]
	v_pk_fma_f32 v[20:21], v[8:9], v[20:21], v[138:139]
	v_cndmask_b32_e32 v18, v156, v18, vcc
	v_cndmask_b32_e32 v19, v156, v19, vcc
	v_cndmask_b32_e32 v16, v156, v16, vcc
	v_cndmask_b32_e32 v17, v156, v17, vcc
	v_cndmask_b32_e32 v20, v156, v20, vcc
	v_cndmask_b32_e32 v21, v156, v21, vcc
	v_cndmask_b32_e32 v28, v156, v28, vcc
	v_cndmask_b32_e32 v29, v156, v29, vcc
	v_cvt_pk_bf16_f32 v16, v16, v17
	v_cvt_pk_bf16_f32 v17, v18, v19
	v_cvt_pk_bf16_f32 v18, v28, v29
	v_cvt_pk_bf16_f32 v19, v20, v21
	global_store_dwordx4 v[22:23], v[16:19], off offset:256
	ds_read_b32 v20, v157 offset:4608
	v_add_u32_e32 v22, 0x80, v144
	v_ashrrev_i32_e32 v23, 31, v22
	v_lshlrev_b64 v[22:23], 12, v[22:23]
	v_lshl_add_u64 v[22:23], s[2:3], 0, v[22:23]
	s_waitcnt lgkmcnt(0)
; __device__ __forceinline__ unsigned cvt_pk_bf16(float lo, float hi) { unsigned r; asm volatile("v_cvt_pk_bf16_f32 %0, %1, %2" : "=v"(r) : "v"(lo), "v"(hi)); return r; }
;     __device__ __forceinline__ void fused(f32x4 (&acc)[2][2][4][2], const Unit& un, int wr, int wc, int fr, int fq, PG8_LAS unsigned char* lds, int wid, int lane) const {
;     ...
;         for (int ai = 0; ai < 2; ++ai)
; #pragma unroll
;             for (int m = 0; m < 4; ++m) { const int r = ai * HALF + wr * 64 + m * 16 + fr; const float rs = S[r]; const size_t off = (size_t)(un.pm * BM + r) * ldc + col0;
; #pragma unroll
;                 for (int bj = 0; bj < 2; ++bj) { f32x4 y0 = (acc[ai][bj][m][0] * rs) * cg[bj][0] + sh[bj][0], y1 = (acc[ai][bj][m][1] * rs) * cg[bj][1] + sh[bj][1];
;                     if (bad) { y0 = (f32x4){qnan, qnan, qnan, qnan}; y1 = y0; }
;                     if (MODE == 0) { u32x4 w; w.x = cvt_pk_bf16(y0[0], y0[1]); w.y = cvt_pk_bf16(y0[2], y0[3]); w.z = cvt_pk_bf16(y1[0], y1[1]); w.w = cvt_pk_bf16(y1[2], y1[3]); *(u32x4*)(u + off + bj * HALF) = w; }
;                     else { *(f32x4*)(outf + off + bj * HALF) = y0; *(f32x4*)(outf + off + bj * HALF + 4) = y1; } } }
	v_pk_mul_f32 v[16:17], v[100:101], v[20:21] op_sel_hi:[1,0]
	v_pk_mul_f32 v[18:19], v[102:103], v[20:21] op_sel_hi:[1,0]
	v_pk_fma_f32 v[16:17], v[154:155], v[16:17], v[140:141]
	v_pk_fma_f32 v[18:19], v[152:153], v[18:19], v[142:143]
	v_pk_mul_f32 v[28:29], v[104:105], v[20:21] op_sel_hi:[1,0]
	v_pk_mul_f32 v[30:31], v[106:107], v[20:21] op_sel_hi:[1,0]
	v_pk_fma_f32 v[28:29], v[150:151], v[28:29], v[132:133]
	v_pk_fma_f32 v[30:31], v[146:147], v[30:31], v[134:135]
	v_cndmask_b32_e32 v18, v156, v18, vcc
	v_cndmask_b32_e32 v19, v156, v19, vcc
	v_cndmask_b32_e32 v16, v156, v16, vcc
	v_cndmask_b32_e32 v17, v156, v17, vcc
	v_cndmask_b32_e32 v21, v156, v30, vcc
	v_cndmask_b32_e32 v30, v156, v31, vcc
	v_cndmask_b32_e32 v28, v156, v28, vcc
	v_cndmask_b32_e32 v29, v156, v29, vcc
	v_cvt_pk_bf16_f32 v16, v16, v17
	v_cvt_pk_bf16_f32 v17, v18, v19
	v_cvt_pk_bf16_f32 v18, v28, v29
	v_cvt_pk_bf16_f32 v19, v21, v30
	v_lshl_add_u64 v[22:23], v[22:23], 0, v[148:149]
	global_store_dwordx4 v[22:23], v[16:19], off
	v_pk_mul_f32 v[28:29], v[112:113], v[20:21] op_sel_hi:[1,0]
	s_nop 0
	v_pk_mul_f32 v[16:17], v[124:125], v[20:21] op_sel_hi:[1,0]
	v_pk_mul_f32 v[18:19], v[126:127], v[20:21] op_sel_hi:[1,0]
	v_pk_fma_f32 v[16:17], v[14:15], v[16:17], v[128:129]
	v_pk_fma_f32 v[18:19], v[12:13], v[18:19], v[130:131]
	v_pk_mul_f32 v[20:21], v[114:115], v[20:21] op_sel_hi:[1,0]
	v_pk_fma_f32 v[28:29], v[10:11], v[28:29], v[136:137]
	v_pk_fma_f32 v[20:21], v[8:9], v[20:21], v[138:139]
	v_cndmask_b32_e32 v18, v156, v18, vcc
	v_cndmask_b32_e32 v19, v156, v19, vcc
	v_cndmask_b32_e32 v16, v156, v16, vcc
	v_cndmask_b32_e32 v17, v156, v17, vcc
	v_cndmask_b32_e32 v20, v156, v20, vcc
	v_cndmask_b32_e32 v21, v156, v21, vcc
	v_cndmask_b32_e32 v28, v156, v28, vcc
	v_cndmask_b32_e32 v29, v156, v29, vcc
	v_cvt_pk_bf16_f32 v16, v16, v17
	v_cvt_pk_bf16_f32 v17, v18, v19
	v_cvt_pk_bf16_f32 v18, v28, v29
	v_cvt_pk_bf16_f32 v19, v20, v21
	global_store_dwordx4 v[22:23], v[16:19], off offset:256
	ds_read_b32 v20, v157 offset:4672
	v_add_u32_e32 v22, 0x90, v144
	v_ashrrev_i32_e32 v23, 31, v22
	v_lshlrev_b64 v[22:23], 12, v[22:23]
	v_lshl_add_u64 v[22:23], s[2:3], 0, v[22:23]
	s_waitcnt lgkmcnt(0)
	v_pk_mul_f32 v[16:17], v[116:117], v[20:21] op_sel_hi:[1,0]
	v_pk_mul_f32 v[18:19], v[118:119], v[20:21] op_sel_hi:[1,0]
	v_pk_fma_f32 v[16:17], v[154:155], v[16:17], v[140:141]
	v_pk_fma_f32 v[18:19], v[152:153], v[18:19], v[142:143]
	v_pk_mul_f32 v[28:29], v[120:121], v[20:21] op_sel_hi:[1,0]
	v_pk_mul_f32 v[30:31], v[122:123], v[20:21] op_sel_hi:[1,0]
	v_pk_fma_f32 v[28:29], v[150:151], v[28:29], v[132:133]
	v_pk_fma_f32 v[30:31], v[146:147], v[30:31], v[134:135]
	v_cndmask_b32_e32 v18, v156, v18, vcc
	v_cndmask_b32_e32 v19, v156, v19, vcc
	v_cndmask_b32_e32 v16, v156, v16, vcc
	v_cndmask_b32_e32 v17, v156, v17, vcc
	v_cndmask_b32_e32 v21, v156, v30, vcc
	v_cndmask_b32_e32 v30, v156, v31, vcc
	v_cndmask_b32_e32 v28, v156, v28, vcc
	v_cndmask_b32_e32 v29, v156, v29, vcc
	v_cvt_pk_bf16_f32 v16, v16, v17
	v_cvt_pk_bf16_f32 v17, v18, v19
	v_cvt_pk_bf16_f32 v18, v28, v29
	v_cvt_pk_bf16_f32 v19, v21, v30
	v_lshl_add_u64 v[22:23], v[22:23], 0, v[148:149]
	global_store_dwordx4 v[22:23], v[16:19], off
	v_pk_mul_f32 v[28:29], v[88:89], v[20:21] op_sel_hi:[1,0]
	s_nop 0
	v_pk_mul_f32 v[16:17], v[92:93], v[20:21] op_sel_hi:[1,0]
	v_pk_mul_f32 v[18:19], v[94:95], v[20:21] op_sel_hi:[1,0]
	v_pk_fma_f32 v[16:17], v[14:15], v[16:17], v[128:129]
	v_pk_fma_f32 v[18:19], v[12:13], v[18:19], v[130:131]
	v_pk_mul_f32 v[20:21], v[90:91], v[20:21] op_sel_hi:[1,0]
	v_pk_fma_f32 v[28:29], v[10:11], v[28:29], v[136:137]
	v_pk_fma_f32 v[20:21], v[8:9], v[20:21], v[138:139]
	v_cndmask_b32_e32 v18, v156, v18, vcc
	v_cndmask_b32_e32 v19, v156, v19, vcc
	v_cndmask_b32_e32 v16, v156, v16, vcc
	v_cndmask_b32_e32 v17, v156, v17, vcc
	v_cndmask_b32_e32 v20, v156, v20, vcc
	v_cndmask_b32_e32 v21, v156, v21, vcc
	v_cndmask_b32_e32 v28, v156, v28, vcc
	v_cndmask_b32_e32 v29, v156, v29, vcc
	v_cvt_pk_bf16_f32 v16, v16, v17
	v_cvt_pk_bf16_f32 v17, v18, v19
	v_cvt_pk_bf16_f32 v18, v28, v29
	v_cvt_pk_bf16_f32 v19, v20, v21
	global_store_dwordx4 v[22:23], v[16:19], off offset:256
	ds_read_b32 v20, v157 offset:4736
	v_add_u32_e32 v22, 0xa0, v144
	v_ashrrev_i32_e32 v23, 31, v22
	v_lshlrev_b64 v[22:23], 12, v[22:23]
	v_lshl_add_u64 v[22:23], s[2:3], 0, v[22:23]
	s_waitcnt lgkmcnt(0)
; __device__ __forceinline__ unsigned cvt_pk_bf16(float lo, float hi) { unsigned r; asm volatile("v_cvt_pk_bf16_f32 %0, %1, %2" : "=v"(r) : "v"(lo), "v"(hi)); return r; }
;     __device__ __forceinline__ void fused(f32x4 (&acc)[2][2][4][2], const Unit& un, int wr, int wc, int fr, int fq, PG8_LAS unsigned char* lds, int wid, int lane) const {
;     ...
;         for (int ai = 0; ai < 2; ++ai)
; #pragma unroll
;             for (int m = 0; m < 4; ++m) { const int r = ai * HALF + wr * 64 + m * 16 + fr; const float rs = S[r]; const size_t off = (size_t)(un.pm * BM + r) * ldc + col0;
; #pragma unroll
;                 for (int bj = 0; bj < 2; ++bj) { f32x4 y0 = (acc[ai][bj][m][0] * rs) * cg[bj][0] + sh[bj][0], y1 = (acc[ai][bj][m][1] * rs) * cg[bj][1] + sh[bj][1];
;                     if (bad) { y0 = (f32x4){qnan, qnan, qnan, qnan}; y1 = y0; }
;                     if (MODE == 0) { u32x4 w; w.x = cvt_pk_bf16(y0[0], y0[1]); w.y = cvt_pk_bf16(y0[2], y0[3]); w.z = cvt_pk_bf16(y1[0], y1[1]); w.w = cvt_pk_bf16(y1[2], y1[3]); *(u32x4*)(u + off + bj * HALF) = w; }
;                     else { *(f32x4*)(outf + off + bj * HALF) = y0; *(f32x4*)(outf + off + bj * HALF + 4) = y1; } } }
	v_pk_mul_f32 v[16:17], v[84:85], v[20:21] op_sel_hi:[1,0]
	v_pk_mul_f32 v[18:19], v[86:87], v[20:21] op_sel_hi:[1,0]
	v_pk_fma_f32 v[16:17], v[154:155], v[16:17], v[140:141]
	v_pk_fma_f32 v[18:19], v[152:153], v[18:19], v[142:143]
	v_pk_mul_f32 v[28:29], v[80:81], v[20:21] op_sel_hi:[1,0]
	v_pk_mul_f32 v[30:31], v[82:83], v[20:21] op_sel_hi:[1,0]
	v_pk_fma_f32 v[28:29], v[150:151], v[28:29], v[132:133]
	v_pk_fma_f32 v[30:31], v[146:147], v[30:31], v[134:135]
	v_cndmask_b32_e32 v18, v156, v18, vcc
	v_cndmask_b32_e32 v19, v156, v19, vcc
	v_cndmask_b32_e32 v16, v156, v16, vcc
	v_cndmask_b32_e32 v17, v156, v17, vcc
	v_cndmask_b32_e32 v21, v156, v30, vcc
	v_cndmask_b32_e32 v30, v156, v31, vcc
	v_cndmask_b32_e32 v28, v156, v28, vcc
	v_cndmask_b32_e32 v29, v156, v29, vcc
	v_cvt_pk_bf16_f32 v16, v16, v17
	v_cvt_pk_bf16_f32 v17, v18, v19
	v_cvt_pk_bf16_f32 v18, v28, v29
	v_cvt_pk_bf16_f32 v19, v21, v30
	v_lshl_add_u64 v[22:23], v[22:23], 0, v[148:149]
	global_store_dwordx4 v[22:23], v[16:19], off
	v_pk_mul_f32 v[28:29], v[40:41], v[20:21] op_sel_hi:[1,0]
	s_nop 0
	v_pk_mul_f32 v[16:17], v[44:45], v[20:21] op_sel_hi:[1,0]
	v_pk_mul_f32 v[18:19], v[46:47], v[20:21] op_sel_hi:[1,0]
	v_pk_fma_f32 v[16:17], v[14:15], v[16:17], v[128:129]
	v_pk_fma_f32 v[18:19], v[12:13], v[18:19], v[130:131]
	v_pk_mul_f32 v[20:21], v[42:43], v[20:21] op_sel_hi:[1,0]
	v_pk_fma_f32 v[28:29], v[10:11], v[28:29], v[136:137]
	v_pk_fma_f32 v[20:21], v[8:9], v[20:21], v[138:139]
	v_cndmask_b32_e32 v18, v156, v18, vcc
	v_cndmask_b32_e32 v19, v156, v19, vcc
	v_cndmask_b32_e32 v16, v156, v16, vcc
	v_cndmask_b32_e32 v17, v156, v17, vcc
	v_cndmask_b32_e32 v20, v156, v20, vcc
	v_cndmask_b32_e32 v21, v156, v21, vcc
	v_cndmask_b32_e32 v28, v156, v28, vcc
	v_cndmask_b32_e32 v29, v156, v29, vcc
	v_cvt_pk_bf16_f32 v16, v16, v17
	v_cvt_pk_bf16_f32 v17, v18, v19
	v_cvt_pk_bf16_f32 v18, v28, v29
	v_cvt_pk_bf16_f32 v19, v20, v21
	global_store_dwordx4 v[22:23], v[16:19], off offset:256
	ds_read_b32 v20, v157 offset:4800
	v_add_u32_e32 v22, 0xb0, v144
	v_ashrrev_i32_e32 v23, 31, v22
	v_lshlrev_b64 v[22:23], 12, v[22:23]
	v_lshl_add_u64 v[22:23], s[2:3], 0, v[22:23]
	s_waitcnt lgkmcnt(0)
	v_pk_mul_f32 v[26:27], v[26:27], v[20:21] op_sel_hi:[1,0]
	v_pk_mul_f32 v[16:17], v[36:37], v[20:21] op_sel_hi:[1,0]
	v_pk_fma_f32 v[26:27], v[146:147], v[26:27], v[134:135]
	v_pk_mul_f32 v[18:19], v[38:39], v[20:21] op_sel_hi:[1,0]
	v_pk_mul_f32 v[24:25], v[24:25], v[20:21] op_sel_hi:[1,0]
	v_cndmask_b32_e32 v21, v156, v26, vcc
	v_pk_mul_f32 v[0:1], v[0:1], v[20:21] op_sel_hi:[1,0]
	v_pk_mul_f32 v[2:3], v[2:3], v[20:21] op_sel_hi:[1,0]
	v_pk_fma_f32 v[18:19], v[152:153], v[18:19], v[142:143]
	v_pk_fma_f32 v[16:17], v[154:155], v[16:17], v[140:141]
	v_pk_mul_f32 v[4:5], v[4:5], v[20:21] op_sel_hi:[1,0]
	v_pk_mul_f32 v[6:7], v[6:7], v[20:21] op_sel_hi:[1,0]
	v_pk_fma_f32 v[2:3], v[8:9], v[2:3], v[138:139]
	v_pk_fma_f32 v[0:1], v[10:11], v[0:1], v[136:137]
	v_pk_fma_f32 v[24:25], v[150:151], v[24:25], v[132:133]
	v_cndmask_b32_e32 v18, v156, v18, vcc
	v_cndmask_b32_e32 v19, v156, v19, vcc
	v_cndmask_b32_e32 v16, v156, v16, vcc
	v_cndmask_b32_e32 v17, v156, v17, vcc
	v_lshl_add_u64 v[22:23], v[22:23], 0, v[148:149]
	v_pk_fma_f32 v[6:7], v[12:13], v[6:7], v[130:131]
	v_pk_fma_f32 v[4:5], v[14:15], v[4:5], v[128:129]
	v_cndmask_b32_e32 v8, v156, v2, vcc
	v_cndmask_b32_e32 v3, v156, v3, vcc
	v_cndmask_b32_e32 v2, v156, v0, vcc
	v_cndmask_b32_e32 v26, v156, v27, vcc
	v_cndmask_b32_e32 v24, v156, v24, vcc
	v_cndmask_b32_e32 v25, v156, v25, vcc
	v_cvt_pk_bf16_f32 v16, v16, v17
	v_cvt_pk_bf16_f32 v17, v18, v19
	v_cvt_pk_bf16_f32 v18, v24, v25
	v_cvt_pk_bf16_f32 v19, v21, v26
	global_store_dwordx4 v[22:23], v[16:19], off
	v_cndmask_b32_e32 v6, v156, v6, vcc
	v_cndmask_b32_e32 v7, v156, v7, vcc
	v_cndmask_b32_e32 v4, v156, v4, vcc
	v_cndmask_b32_e32 v5, v156, v5, vcc
	v_cndmask_b32_e32 v9, v156, v1, vcc
	v_cvt_pk_bf16_f32 v0, v4, v5
	v_cvt_pk_bf16_f32 v1, v6, v7
	v_cvt_pk_bf16_f32 v2, v2, v9
	v_cvt_pk_bf16_f32 v3, v8, v3
	global_store_dwordx4 v[22:23], v[0:3], off offset:256

;     __device__ __forceinline__ void operator()(const f32x4 (&acc)[2][2][4][2], const Unit& u, int wr, int wc, int fr, int fq) const {
;         const int row0 = u.pm * BM + wr * 64 + fr, col0 = u.pn * BM + wc * 32 + 4 * fq;
; #pragma unroll
;         for (int ai = 0; ai < 2; ++ai)
; #pragma unroll
;             for (int m = 0; m < 4; ++m) { float* rowp = C + (size_t)(row0 + ai * HALF + m * 16) * ldc + col0;
; #pragma unroll
;                 for (int bj = 0; bj < 2; ++bj)
; #pragma unroll
;                     for (int n = 0; n < 2; ++n) *(f32x4*)(rowp + bj * HALF + n * 16) = acc[ai][bj][m][n]; }
.LBB0_2420:
	v_mov_b32_e32 v136, 0
	s_lshl_b32 s50, s60, 8
	v_mbcnt_lo_u32_b32 v136, -1, v136
	v_mbcnt_hi_u32_b32 v136, -1, v136
	v_or_b32_e32 v136, s33, v136
	s_add_i32 s50, s50, s40
	v_and_or_b32 v146, v136, 15, s50
	s_lshl_b32 s44, s44, 8
	v_lshrrev_b32_e32 v136, 2, v136
	v_and_or_b32 v136, v136, 12, s44
	v_or_b32_e32 v136, s41, v136
	v_ashrrev_i32_e32 v137, 31, v136
	v_mov_b64_e32 v[138:139], s[12:13]
	v_mad_i64_i32 v[144:145], s[50:51], v146, s47, v[138:139]
	v_lshlrev_b64 v[136:137], 2, v[136:137]
	v_lshl_add_u64 v[144:145], v[144:145], 0, v[136:137]
	global_store_dwordx4 v[144:145], v[24:27], off
	global_store_dwordx4 v[144:145], v[28:31], off offset:64
	global_store_dwordx4 v[144:145], v[56:59], off offset:512
	global_store_dwordx4 v[144:145], v[60:63], off offset:576
	v_or_b32_e32 v24, 16, v146
	v_mad_i64_i32 v[24:25], s[50:51], v24, s47, v[138:139]
	v_lshl_add_u64 v[24:25], v[24:25], 0, v[136:137]
	global_store_dwordx4 v[24:25], v[16:19], off
	global_store_dwordx4 v[24:25], v[20:23], off offset:64
	global_store_dwordx4 v[24:25], v[48:51], off offset:512
	global_store_dwordx4 v[24:25], v[52:55], off offset:576
	v_or_b32_e32 v16, 32, v146
	v_mad_i64_i32 v[16:17], s[50:51], v16, s47, v[138:139]
	v_lshl_add_u64 v[16:17], v[16:17], 0, v[136:137]
	global_store_dwordx4 v[16:17], v[8:11], off
	global_store_dwordx4 v[16:17], v[12:15], off offset:64
	global_store_dwordx4 v[16:17], v[40:43], off offset:512
	global_store_dwordx4 v[16:17], v[44:47], off offset:576
	v_or_b32_e32 v8, 48, v146
	v_mad_i64_i32 v[8:9], s[50:51], v8, s47, v[138:139]
	v_lshl_add_u64 v[8:9], v[8:9], 0, v[136:137]
	global_store_dwordx4 v[8:9], v[0:3], off
	global_store_dwordx4 v[8:9], v[4:7], off offset:64
	global_store_dwordx4 v[8:9], v[32:35], off offset:512
	global_store_dwordx4 v[8:9], v[36:39], off offset:576
	v_add_u32_e32 v0, 0x80, v146
	v_mad_i64_i32 v[0:1], s[50:51], v0, s47, v[138:139]
	v_lshl_add_u64 v[0:1], v[0:1], 0, v[136:137]
	global_store_dwordx4 v[0:1], v[88:91], off
	global_store_dwordx4 v[0:1], v[92:95], off offset:64
	global_store_dwordx4 v[0:1], v[120:123], off offset:512
	global_store_dwordx4 v[0:1], v[124:127], off offset:576
	v_add_u32_e32 v0, 0x90, v146
	v_mad_i64_i32 v[0:1], s[50:51], v0, s47, v[138:139]
	v_lshl_add_u64 v[0:1], v[0:1], 0, v[136:137]
	global_store_dwordx4 v[0:1], v[80:83], off
	global_store_dwordx4 v[0:1], v[84:87], off offset:64
	global_store_dwordx4 v[0:1], v[112:115], off offset:512
	global_store_dwordx4 v[0:1], v[116:119], off offset:576
	v_add_u32_e32 v0, 0xa0, v146
	v_mad_i64_i32 v[0:1], s[50:51], v0, s47, v[138:139]
	v_lshl_add_u64 v[0:1], v[0:1], 0, v[136:137]
	global_store_dwordx4 v[0:1], v[72:75], off
	global_store_dwordx4 v[0:1], v[76:79], off offset:64
	global_store_dwordx4 v[0:1], v[104:107], off offset:512
	global_store_dwordx4 v[0:1], v[108:111], off offset:576
	v_add_u32_e32 v0, 0xb0, v146
	v_mad_i64_i32 v[0:1], s[50:51], v0, s47, v[138:139]
	v_lshl_add_u64 v[0:1], v[0:1], 0, v[136:137]
	s_andn2_b64 vcc, exec, s[2:3]
	s_mov_b64 s[2:3], -1
	global_store_dwordx4 v[0:1], v[64:67], off
	global_store_dwordx4 v[0:1], v[68:71], off offset:64
	global_store_dwordx4 v[0:1], v[96:99], off offset:512
	global_store_dwordx4 v[0:1], v[100:103], off offset:576
	s_cbranch_vccnz .LBB0_2413
	s_andn2_b64 vcc, exec, s[6:7]
	s_cbranch_vccnz .LBB0_2412
	s_barrier
	s_branch .LBB0_2412

; __device__ __forceinline__ unsigned pk2(float lo, float hi) { return f2bf(lo) | (f2bf(hi) << 16); }
; template <int L>
; __device__ __forceinline__ void layer_body(const Args& args, LAS unsigned char* lds, const int wave, const int G, const int gw, const int NGW, const int lo, const int hi,
;                                            unsigned char* const ws_kernel, const XcdBarrier& bar, int& pid) {
;     ...
;                 for (int m = mlo + gwl; m < mhi; m += NGWH) {
;                     const float* hr = mla_hcat + (size_t)m * MLA_IN_PAD; const int s = m & 2047;
; #pragma unroll
;                     for (int part = 0; part < 2; ++part) {
;                         const float* src = hr + part * 512 + 8 * lane; const float* gn = (part == 0 ? qn : kn) + 8 * lane;
;                         const f32x4 a = *(const f32x4*)src, b4 = *(const f32x4*)(src + 4);
;                         const float ss = wave_sum((a.x * a.x + a.y * a.y) + (a.z * a.z + a.w * a.w) + (b4.x * b4.x + b4.y * b4.y) + (b4.z * b4.z + b4.w * b4.w));
;                         const float rstd = 1.0f / sqrtf(ss * (1.0f / 512.0f) + EPS);
;                         const f32x4 g0 = *(const f32x4*)gn, g1 = *(const f32x4*)(gn + 4);
;                         v4u o; o.x = pk2(a.x * rstd * g0.x, a.y * rstd * g0.y); o.y = pk2(a.z * rstd * g0.z, a.w * rstd * g0.w);
;                         o.z = pk2(b4.x * rstd * g1.x, b4.y * rstd * g1.y); o.w = pk2(b4.z * rstd * g1.z, b4.w * rstd * g1.w);
;                         *(v4u*)((part == 0 ? mla_cq : mla_ckv) + (size_t)m * 512 + 8 * lane) = o;
.LBB0_2481:
	v_lshl_add_u64 v[32:33], s[12:13], 0, v[14:15]
	v_add_co_u32_e64 v40, s[4:5], s9, v32
	v_lshl_add_u64 v[20:21], s[12:13], 0, v[18:19]
	s_nop 0
	v_addc_co_u32_e64 v41, s[4:5], 0, v33, s[4:5]
	v_add_co_u32_e64 v42, s[4:5], s14, v32
	v_lshl_add_u64 v[34:35], s[12:13], 0, v[16:17]
	v_add_co_u32_e32 v20, vcc, 0x22600000, v20
	v_addc_co_u32_e64 v43, s[4:5], 0, v33, s[4:5]
	v_add_co_u32_e64 v44, s[4:5], s15, v34
	v_addc_co_u32_e32 v21, vcc, 0, v21, vcc
	global_load_dwordx4 v[0:3], v[8:9], off offset:16
	global_load_dwordx4 v[4:7], v[8:9], off
	v_addc_co_u32_e64 v45, s[4:5], 0, v35, s[4:5]
	global_load_dwordx4 v[32:35], v[20:21], off
	global_load_dwordx4 v[36:39], v[20:21], off offset:16
	v_lshl_add_u64 v[14:15], v[14:15], 0, s[46:47]
	v_lshl_add_u64 v[16:17], v[16:17], 0, s[62:63]
	v_lshl_add_u64 v[18:19], v[18:19], 0, s[62:63]
	s_waitcnt vmcnt(0)
	v_mov_b32_e32 v46, v4
	v_mov_b32_e32 v47, v6
	v_mov_b32_e32 v6, v5
	v_mov_b32_e32 v4, v0
	v_mov_b32_e32 v5, v2
	v_mov_b32_e32 v2, v1
	s_waitcnt lgkmcnt(0)
	v_mul_f32_e32 v31, v33, v33
	v_mul_f32_e32 v54, v35, v35
	v_pk_mul_f32 v[0:1], v[38:39], v[38:39]
	v_pk_mul_f32 v[48:49], v[36:37], v[36:37]
	v_mov_b32_e32 v52, v36
	v_mov_b32_e32 v53, v38
	v_mov_b32_e32 v38, v37
	v_fmac_f32_e32 v31, v32, v32
	v_fmac_f32_e32 v54, v34, v34
	v_mov_b32_e32 v36, v0
	v_mov_b32_e32 v37, v48
	v_mov_b32_e32 v48, v1
	v_add_f32_e32 v31, v31, v54
	v_pk_add_f32 v[0:1], v[36:37], v[48:49]
	v_mov_b32_e32 v50, v32
	v_add_f32_e32 v1, v31, v1
	v_add_f32_e32 v0, v0, v1
	ds_bpermute_b32 v1, v23, v0
	v_mov_b32_e32 v51, v34
	v_mov_b32_e32 v34, v33
	s_waitcnt lgkmcnt(0)
	v_add_f32_e32 v0, v0, v1
	ds_bpermute_b32 v1, v24, v0
	s_waitcnt lgkmcnt(0)
	v_add_f32_e32 v0, v0, v1
	ds_bpermute_b32 v1, v25, v0
	s_waitcnt lgkmcnt(0)
	v_add_f32_e32 v0, v0, v1
	ds_bpermute_b32 v1, v26, v0
	s_waitcnt lgkmcnt(0)
	v_add_f32_e32 v0, v0, v1
	ds_bpermute_b32 v1, v27, v0
	s_waitcnt lgkmcnt(0)
	v_add_f32_e32 v0, v0, v1
	ds_bpermute_b32 v1, v28, v0
	s_waitcnt lgkmcnt(0)
	v_add_f32_e32 v0, v0, v1
	v_fmamk_f32 v0, v0, 0x3b000000, v29
	v_mul_f32_e32 v1, 0x4f800000, v0
	v_cmp_gt_f32_e32 vcc, s0, v0
	s_nop 1
	v_cndmask_b32_e32 v0, v0, v1, vcc
	v_sqrt_f32_e32 v1, v0
	s_nop 0
	v_add_u32_e32 v31, -1, v1
	v_add_u32_e32 v32, 1, v1
	v_fma_f32 v33, -v31, v1, v0
	v_fma_f32 v36, -v32, v1, v0
	v_cmp_ge_f32_e64 s[4:5], 0, v33
	s_nop 1
	v_cndmask_b32_e64 v1, v1, v31, s[4:5]
	v_cmp_lt_f32_e64 s[4:5], 0, v36
	s_nop 1
	v_cndmask_b32_e64 v1, v1, v32, s[4:5]
	v_mul_f32_e32 v31, 0x37800000, v1
	v_cndmask_b32_e32 v1, v1, v31, vcc
	v_cmp_class_f32_e32 vcc, v0, v30
	s_nop 1
	v_cndmask_b32_e32 v0, v1, v0, vcc
	v_div_scale_f32 v1, s[4:5], v0, v0, 1.0
	v_rcp_f32_e32 v32, v1
	v_div_scale_f32 v31, vcc, 1.0, v0, 1.0
	v_fma_f32 v33, -v1, v32, 1.0
	v_fmac_f32_e32 v32, v33, v32
	v_mul_f32_e32 v33, v31, v32
	v_fma_f32 v36, -v1, v33, v31
	v_fmac_f32_e32 v33, v36, v32
	v_fma_f32 v1, -v1, v33, v31
	v_div_fmas_f32 v1, v1, v32, v33
	v_div_fixup_f32 v0, v1, v0, 1.0
	v_pk_mul_f32 v[32:33], v[50:51], v[0:1] op_sel_hi:[1,0]
	v_pk_mul_f32 v[34:35], v[34:35], v[0:1] op_sel_hi:[1,0]
	v_pk_mul_f32 v[36:37], v[52:53], v[0:1] op_sel_hi:[1,0]
	v_pk_mul_f32 v[0:1], v[38:39], v[0:1] op_sel_hi:[1,0]
	v_pk_mul_f32 v[32:33], v[46:47], v[32:33]
	v_pk_mul_f32 v[4:5], v[4:5], v[36:37]
	v_pk_mul_f32 v[0:1], v[2:3], v[0:1]
	v_pk_mul_f32 v[6:7], v[6:7], v[34:35]
	v_bfe_u32 v2, v1, 16, 1
	v_bfe_u32 v3, v0, 16, 1
	v_bfe_u32 v35, v32, 16, 1
	v_bfe_u32 v36, v33, 16, 1
	v_bfe_u32 v37, v4, 16, 1
	v_bfe_u32 v38, v5, 16, 1
	v_bfe_u32 v31, v7, 16, 1
	v_bfe_u32 v34, v6, 16, 1
	v_add3_u32 v0, v0, v3, s1
	v_add3_u32 v1, v1, v2, s1
	v_add3_u32 v2, v5, v38, s1
	v_add3_u32 v3, v4, v37, s1
	v_add3_u32 v4, v33, v36, s1
	v_add3_u32 v5, v32, v35, s1
	v_add3_u32 v6, v6, v34, s1
	v_add3_u32 v7, v7, v31, s1
	v_lshrrev_b32_e32 v5, 16, v5
	v_lshrrev_b32_e32 v4, 16, v4
	v_lshrrev_b32_e32 v31, 16, v3
	v_lshrrev_b32_e32 v2, 16, v2
	v_and_or_b32 v3, v1, s8, v2
	v_and_or_b32 v2, v0, s8, v31
	v_and_or_b32 v1, v7, s8, v4
	v_and_or_b32 v0, v6, s8, v5
	global_store_dwordx4 v[40:41], v[0:3], off
	global_load_dwordx4 v[0:3], v[20:21], off offset:2048
	s_nop 0
	global_load_dwordx4 v[4:7], v[20:21], off offset:2064
	global_load_dwordx4 v[32:35], v[10:11], off
	global_load_dwordx4 v[36:39], v[10:11], off offset:16
	s_waitcnt vmcnt(0) lgkmcnt(0)
; __device__ __forceinline__ unsigned f2bf(float f) { unsigned u = __builtin_bit_cast(unsigned, f); return (u + 0x7fffu + ((u >> 16) & 1u)) >> 16; }
; __device__ __forceinline__ unsigned pk2(float lo, float hi) { return f2bf(lo) | (f2bf(hi) << 16); }
; template <int L>
; __device__ __forceinline__ void layer_body(const Args& args, LAS unsigned char* lds, const int wave, const int G, const int gw, const int NGW, const int lo, const int hi,
;                                            unsigned char* const ws_kernel, const XcdBarrier& bar, int& pid) {
;     ...
;                     for (int part = 0; part < 2; ++part) {
;                         const float* src = hr + part * 512 + 8 * lane; const float* gn = (part == 0 ? qn : kn) + 8 * lane;
;                         const f32x4 a = *(const f32x4*)src, b4 = *(const f32x4*)(src + 4);
;                         const float ss = wave_sum((a.x * a.x + a.y * a.y) + (a.z * a.z + a.w * a.w) + (b4.x * b4.x + b4.y * b4.y) + (b4.z * b4.z + b4.w * b4.w));
;                         const float rstd = 1.0f / sqrtf(ss * (1.0f / 512.0f) + EPS);
;                         const f32x4 g0 = *(const f32x4*)gn, g1 = *(const f32x4*)(gn + 4);
;                         v4u o; o.x = pk2(a.x * rstd * g0.x, a.y * rstd * g0.y); o.y = pk2(a.z * rstd * g0.z, a.w * rstd * g0.w);
;                         o.z = pk2(b4.x * rstd * g1.x, b4.y * rstd * g1.y); o.w = pk2(b4.z * rstd * g1.z, b4.w * rstd * g1.w);
;                         *(v4u*)((part == 0 ? mla_cq : mla_ckv) + (size_t)m * 512 + 8 * lane) = o;
;                     }
;                     { const int i = lane & 31; const float x1 = hr[1024 + i], x2 = hr[1024 + 32 + i]; float sn, cs; sincos_rev((float)s * kinv, sn, cs);
;                       const float o = (lane < 32) ? (x1 * cs - x2 * sn) : (x2 * cs + x1 * sn);
;                       mla_kr[(size_t)m * 64 + 2 * (lane & 31) + (lane >> 5)] = (bf16)f2bf(o); }
	v_mul_f32_e32 v31, v1, v1
	v_mul_f32_e32 v52, v3, v3
	v_pk_mul_f32 v[20:21], v[6:7], v[6:7]
	v_pk_mul_f32 v[40:41], v[4:5], v[4:5]
	v_mov_b32_e32 v48, v32
	v_mov_b32_e32 v49, v34
	v_mov_b32_e32 v34, v33
	v_mov_b32_e32 v32, v4
	v_mov_b32_e32 v33, v6
	v_mov_b32_e32 v6, v5
	v_fmac_f32_e32 v31, v0, v0
	v_fmac_f32_e32 v52, v2, v2
	v_mov_b32_e32 v4, v20
	v_mov_b32_e32 v5, v40
	v_mov_b32_e32 v40, v21
	v_mov_b32_e32 v46, v0
	v_mov_b32_e32 v47, v2
	v_mov_b32_e32 v2, v1
	v_add_f32_e32 v20, v31, v52
	v_pk_add_f32 v[0:1], v[4:5], v[40:41]
	v_mov_b32_e32 v50, v36
	v_add_f32_e32 v1, v20, v1
	v_add_f32_e32 v0, v0, v1
	ds_bpermute_b32 v1, v23, v0
	v_mov_b32_e32 v51, v38
	v_mov_b32_e32 v38, v37
	s_waitcnt lgkmcnt(0)
	v_add_f32_e32 v0, v0, v1
	ds_bpermute_b32 v1, v24, v0
	s_waitcnt lgkmcnt(0)
	v_add_f32_e32 v0, v0, v1
	ds_bpermute_b32 v1, v25, v0
	s_waitcnt lgkmcnt(0)
	v_add_f32_e32 v0, v0, v1
	ds_bpermute_b32 v1, v26, v0
	s_waitcnt lgkmcnt(0)
	v_add_f32_e32 v0, v0, v1
	ds_bpermute_b32 v1, v27, v0
	s_waitcnt lgkmcnt(0)
	v_add_f32_e32 v0, v0, v1
	ds_bpermute_b32 v1, v28, v0
	s_waitcnt lgkmcnt(0)
	v_add_f32_e32 v0, v0, v1
	v_fmamk_f32 v0, v0, 0x3b000000, v29
	v_mul_f32_e32 v1, 0x4f800000, v0
	v_cmp_gt_f32_e32 vcc, s0, v0
	s_nop 1
	v_cndmask_b32_e32 v0, v0, v1, vcc
	v_sqrt_f32_e32 v1, v0
	s_nop 0
	v_add_u32_e32 v4, -1, v1
	v_add_u32_e32 v5, 1, v1
	v_fma_f32 v20, -v4, v1, v0
	v_fma_f32 v21, -v5, v1, v0
	v_cmp_ge_f32_e64 s[4:5], 0, v20
	s_nop 1
	v_cndmask_b32_e64 v1, v1, v4, s[4:5]
	v_cmp_lt_f32_e64 s[4:5], 0, v21
	s_nop 1
	v_cndmask_b32_e64 v1, v1, v5, s[4:5]
	v_mul_f32_e32 v4, 0x37800000, v1
	v_cndmask_b32_e32 v1, v1, v4, vcc
	v_cmp_class_f32_e32 vcc, v0, v30
	s_nop 1
	v_cndmask_b32_e32 v0, v1, v0, vcc
	v_div_scale_f32 v1, s[4:5], v0, v0, 1.0
	v_rcp_f32_e32 v5, v1
	v_div_scale_f32 v4, vcc, 1.0, v0, 1.0
	s_and_b32 s4, s60, 0x7ff
	v_fma_f32 v20, -v1, v5, 1.0
	v_fmac_f32_e32 v5, v20, v5
	v_mul_f32_e32 v20, v4, v5
	v_fma_f32 v21, -v1, v20, v4
	v_fmac_f32_e32 v20, v21, v5
	v_fma_f32 v1, -v1, v20, v4
	v_div_fmas_f32 v1, v1, v5, v20
	v_div_fixup_f32 v0, v1, v0, 1.0
	v_pk_mul_f32 v[4:5], v[46:47], v[0:1] op_sel_hi:[1,0]
	v_pk_mul_f32 v[2:3], v[2:3], v[0:1] op_sel_hi:[1,0]
	v_pk_mul_f32 v[20:21], v[32:33], v[0:1] op_sel_hi:[1,0]
	v_pk_mul_f32 v[0:1], v[6:7], v[0:1] op_sel_hi:[1,0]
	v_pk_mul_f32 v[4:5], v[48:49], v[4:5]
	v_pk_mul_f32 v[2:3], v[34:35], v[2:3]
	v_pk_mul_f32 v[6:7], v[50:51], v[20:21]
	v_pk_mul_f32 v[0:1], v[38:39], v[0:1]
	v_bfe_u32 v31, v3, 16, 1
	v_bfe_u32 v32, v2, 16, 1
	v_bfe_u32 v33, v4, 16, 1
	v_bfe_u32 v34, v5, 16, 1
	v_bfe_u32 v35, v6, 16, 1
	v_bfe_u32 v36, v7, 16, 1
	v_bfe_u32 v20, v1, 16, 1
	v_bfe_u32 v21, v0, 16, 1
	v_add3_u32 v32, v2, v32, s1
	v_add3_u32 v31, v3, v31, s1
	v_add3_u32 v2, v7, v36, s1
	v_add3_u32 v3, v6, v35, s1
	v_add3_u32 v5, v5, v34, s1
	v_add3_u32 v4, v4, v33, s1
	v_add3_u32 v0, v0, v21, s1
	v_add3_u32 v1, v1, v20, s1
	v_lshrrev_b32_e32 v4, 16, v4
	v_lshrrev_b32_e32 v5, 16, v5
	v_lshrrev_b32_e32 v6, 16, v3
	v_lshrrev_b32_e32 v2, 16, v2
	v_and_or_b32 v3, v1, s8, v2
	v_and_or_b32 v2, v0, s8, v6
	v_and_or_b32 v1, v31, s8, v5
	v_and_or_b32 v0, v32, s8, v4
	global_store_dwordx4 v[42:43], v[0:3], off
	global_load_dword v0, v[44:45], off
	s_nop 0
	global_load_dword v1, v[44:45], off offset:128
	v_cvt_f32_u32_e32 v4, s4
	s_add_i32 s60, s60, s92
	v_lshl_add_u64 v[2:3], s[12:13], 0, v[12:13]
	v_lshl_add_u64 v[12:13], v[12:13], 0, s[44:45]
	v_mul_f32_e32 v4, v22, v4
	v_mul_f32_e32 v5, 0.15915494, v4
	v_floor_f32_e32 v5, v5
	v_fma_f32 v4, v4, 0.15915494, -v5
	v_sin_f32_e32 v5, v4
	v_cos_f32_e32 v4, v4
	s_cmp_lt_i32 s60, s97
	v_mov_b32_e32 v6, v5
	v_mov_b32_e32 v7, v4
	s_waitcnt vmcnt(0) lgkmcnt(0)
	v_pk_mul_f32 v[4:5], v[4:5], v[0:1]
	v_pk_mul_f32 v[0:1], v[6:7], v[0:1]
	v_sub_f32_e32 v4, v4, v5
	v_add_f32_e32 v0, v0, v1
	v_cndmask_b32_e64 v0, v0, v4, s[2:3]
	v_bfe_u32 v1, v0, 16, 1
	v_add3_u32 v0, v0, v1, s1
	global_store_short_d16_hi v[2:3], v0, off
	s_cbranch_scc1 .LBB0_2481

;     __device__ __forceinline__ void operator()(const f32x4 (&acc)[2][2][4][2], const Unit& u, int wr, int wc, int fr, int fq) const {
;     ...
;         float rinv3[2][4]; bool rope3[2];
;         if (ACT == 3) {
; #pragma unroll
;             for (int bj = 0; bj < 2; ++bj) { const int jj = (col0 + bj * HALF) % 192; rope3[bj] = jj >= 128; const int i0 = (jj - 128) >> 1;
; #pragma unroll
;                 for (int p = 0; p < 4; ++p) rinv3[bj][p] = exp2f(-(float)(i0 + p) * (13.287712379549449f / 32.0f)) * 0.15915494309189535f; }
;         }
; #pragma unroll
;         for (int ai = 0; ai < 2; ++ai)
; #pragma unroll
;             for (int m = 0; m < 4; ++m) { bf16_t* rowp = O + (size_t)(row0 + ai * HALF + m * 16) * ldc + col0;
;                 if (ACT == 1) {
;                     const int ob = fr * 64 + 16 * fq, sw = ob ^ (((ob >> 9) & 1) << 5);
;                     rowp = O + ((size_t)(u.pm * (ldc / 64) + u.pn * 4 + (wc >> 1)) * 2 + ai) * 8192 + (((wr * 4 + m) * 2 + (wc & 1)) * 1024 + sw) / 2; }
;                 float rc[2][2], rs[2][2];
;                 if (ACT == 2) { const float pos = (float)((row0 + ai * HALF + m * 16) & 2047);
; #pragma unroll
;                     for (int n = 0; n < 2; ++n)
; #pragma unroll
;                         for (int e = 0; e < 2; ++e) { float r = pos * rinv[n][e]; r -= floorf(r); rs[n][e] = do_rope ? __builtin_amdgcn_sinf(r) : 0.f; rc[n][e] = do_rope ? __builtin_amdgcn_cosf(r) : 1.f; } }
; #pragma unroll
;                 for (int bj = 0; bj < 2; ++bj) { f32x4 v0 = acc[ai][bj][m][0], v1 = acc[ai][bj][m][1];
;                     if (ACT == 3) { const float pos = (float)((row0 + ai * HALF + m * 16) & 2047); float c3[4], s3[4];
; #pragma unroll
;                         for (int p = 0; p < 4; ++p) { float r = pos * rinv3[bj][p]; r -= floorf(r); s3[p] = rope3[bj] ? __builtin_amdgcn_sinf(r) : 0.f; c3[p] = rope3[bj] ? __builtin_amdgcn_cosf(r) : 1.f; }
;                         const f32x4 a = v0, b = v1;
;                         v0[0] = a[0] * c3[0] - a[1] * s3[0]; v0[1] = a[1] * c3[0] + a[0] * s3[0]; v0[2] = a[2] * c3[1] - a[3] * s3[1]; v0[3] = a[3] * c3[1] + a[2] * s3[1];
;                         v1[0] = b[0] * c3[2] - b[1] * s3[2]; v1[1] = b[1] * c3[2] + b[0] * s3[2]; v1[2] = b[2] * c3[3] - b[3] * s3[3]; v1[3] = b[3] * c3[3] + b[2] * s3[3]; }
;                     if (ACT == 2) { const f32x4 a = v0, b = v1;
.LBB0_2549:
	v_mov_b32_e32 v140, 0
	s_lshl_b32 s5, s5, 8
	v_mbcnt_lo_u32_b32 v140, -1, v140
	v_mbcnt_hi_u32_b32 v140, -1, v140
	v_or_b32_e32 v141, s33, v140
	s_lshl_b32 s4, s4, 8
	v_lshrrev_b32_e32 v140, 1, v141
	v_and_or_b32 v140, v140, 24, s5
	v_or_b32_e32 v140, s50, v140
	v_mul_hi_i32 v142, v140, s43
	v_lshrrev_b32_e32 v143, 31, v142
	v_lshrrev_b32_e32 v142, 5, v142
	v_add_u32_e32 v142, v142, v143
	v_mul_lo_u32 v142, v142, s42
	v_sub_u32_e32 v163, v140, v142
	v_add_u32_e32 v142, 0xffffff80, v163
	v_ashrrev_i32_e32 v142, 1, v142
	v_cvt_f32_i32_e32 v143, v142
	v_and_b32_e32 v146, 15, v141
	s_add_i32 s4, s4, s49
	v_or_b32_e32 v162, s4, v146
	v_mul_f32_e32 v141, 0xbed49a78, v143
	v_cmp_gt_f32_e32 vcc, s55, v141
	s_movk_i32 s8, 0x7df
	s_nop 0
	v_cndmask_b32_e32 v141, 0, v152, vcc
	v_fmac_f32_e32 v141, 0xbed49a78, v143
	v_exp_f32_e32 v141, v141
	v_or_b32_e32 v143, 1, v142
	v_cvt_f32_i32_e32 v143, v143
	v_cndmask_b32_e32 v144, 0, v153, vcc
	v_ldexp_f32 v141, v141, v144
	v_mul_f32_e32 v154, 0.15915494, v141
	v_mul_f32_e32 v141, 0xbed49a78, v143
	v_cmp_gt_f32_e32 vcc, s55, v141
	s_nop 1
	v_cndmask_b32_e32 v141, 0, v152, vcc
	v_fmac_f32_e32 v141, 0xbed49a78, v143
	v_exp_f32_e32 v141, v141
	v_or_b32_e32 v143, 2, v142
	v_cvt_f32_i32_e32 v143, v143
	v_cndmask_b32_e32 v144, 0, v153, vcc
	v_ldexp_f32 v141, v141, v144
	v_mul_f32_e32 v156, 0.15915494, v141
	v_mul_f32_e32 v141, 0xbed49a78, v143
	v_cmp_gt_f32_e32 vcc, s55, v141
	v_or_b32_e32 v142, 3, v142
	v_cvt_f32_i32_e32 v142, v142
	v_cndmask_b32_e32 v141, 0, v152, vcc
	v_fmac_f32_e32 v141, 0xbed49a78, v143
	v_exp_f32_e32 v141, v141
	v_cndmask_b32_e32 v143, 0, v153, vcc
	v_ldexp_f32 v141, v141, v143
	v_mul_f32_e32 v158, 0.15915494, v141
	v_mul_f32_e32 v141, 0xbed49a78, v142
	v_cmp_gt_f32_e32 vcc, s55, v141
	s_nop 1
	v_cndmask_b32_e32 v141, 0, v152, vcc
	v_fmac_f32_e32 v141, 0xbed49a78, v142
	v_or_b32_e32 v142, 0x80, v140
	v_mul_hi_i32 v143, v142, s43
	v_lshrrev_b32_e32 v144, 31, v143
	v_lshrrev_b32_e32 v143, 5, v143
	v_add_u32_e32 v143, v143, v144
	v_mul_lo_u32 v143, v143, s42
	v_sub_u32_e32 v164, v142, v143
	v_add_u32_e32 v142, 0xffffff80, v164
	v_exp_f32_e32 v141, v141
	v_ashrrev_i32_e32 v142, 1, v142
	v_cvt_f32_i32_e32 v143, v142
	v_cndmask_b32_e32 v144, 0, v153, vcc
	v_ldexp_f32 v141, v141, v144
	v_mul_f32_e32 v161, 0.15915494, v141
	v_mul_f32_e32 v141, 0xbed49a78, v143
	v_cmp_gt_f32_e32 vcc, s55, v141
	s_nop 1
	v_cndmask_b32_e32 v141, 0, v152, vcc
	v_fmac_f32_e32 v141, 0xbed49a78, v143
	v_exp_f32_e32 v141, v141
	v_add_u32_e32 v143, 1, v142
	v_cvt_f32_i32_e32 v143, v143
	v_cndmask_b32_e32 v144, 0, v153, vcc
	v_ldexp_f32 v141, v141, v144
	v_mul_f32_e32 v155, 0.15915494, v141
	v_mul_f32_e32 v141, 0xbed49a78, v143
	v_cmp_gt_f32_e32 vcc, s55, v141
	s_nop 1
	v_cndmask_b32_e32 v141, 0, v152, vcc
	v_fmac_f32_e32 v141, 0xbed49a78, v143
	v_exp_f32_e32 v141, v141
	v_add_u32_e32 v143, 2, v142
	v_cvt_f32_i32_e32 v143, v143
	v_add_u32_e32 v142, 3, v142
	v_cndmask_b32_e32 v144, 0, v153, vcc
	v_cvt_f32_i32_e32 v142, v142
	v_ldexp_f32 v141, v141, v144
	v_mul_f32_e32 v157, 0.15915494, v141
	v_mul_f32_e32 v141, 0xbed49a78, v143
	v_cmp_gt_f32_e32 vcc, s55, v141
	v_mul_f32_e32 v144, 0xbed49a78, v142
	s_nop 0
	v_cndmask_b32_e32 v141, 0, v152, vcc
	v_fmac_f32_e32 v141, 0xbed49a78, v143
	v_cndmask_b32_e32 v143, 0, v153, vcc
	v_cmp_gt_f32_e32 vcc, s55, v144
	v_exp_f32_e32 v141, v141
	s_nop 0
	v_cndmask_b32_e32 v144, 0, v152, vcc
	v_fmac_f32_e32 v144, 0xbed49a78, v142
	v_exp_f32_e32 v142, v144
	v_ldexp_f32 v141, v141, v143
	v_mul_f32_e32 v160, 0.15915494, v141
	v_cndmask_b32_e32 v141, 0, v153, vcc
	v_ldexp_f32 v141, v142, v141
	v_mov_b32_e32 v142, s4
	s_movk_i32 s4, 0x7cf
	v_bitop3_b32 v142, v146, s4, v142 bitop3:0xc8
	v_cvt_f32_u32_e32 v165, v142
	v_mul_f32_e32 v159, 0.15915494, v141
	v_ashrrev_i32_e32 v141, 31, v140
	v_mov_b64_e32 v[144:145], s[60:61]
	v_mul_f32_e32 v166, v156, v165
	v_floor_f32_e32 v166, v166
	v_fma_f32 v166, v156, v165, -v166
	v_sin_f32_e32 v167, v166
	v_mad_i64_i32 v[142:143], s[4:5], v162, s57, v[144:145]
	v_lshlrev_b64 v[146:147], 1, v[140:141]
	v_lshl_add_u64 v[140:141], v[142:143], 0, v[146:147]
	v_mul_f32_e32 v142, v154, v165
	v_floor_f32_e32 v142, v142
	v_cmp_lt_i32_e32 vcc, s56, v163
	v_fma_f32 v142, v154, v165, -v142
	v_sin_f32_e32 v143, v142
	v_cndmask_b32_e32 v163, 0, v167, vcc
	v_mul_f32_e32 v167, v158, v165
	v_cos_f32_e32 v142, v142
	v_floor_f32_e32 v167, v167
	v_mul_f32_e32 v169, v161, v165
	v_cos_f32_e32 v166, v166
	v_fma_f32 v167, v158, v165, -v167
	v_floor_f32_e32 v169, v169
	v_sin_f32_e32 v168, v167
	v_cos_f32_e32 v167, v167
	v_fma_f32 v169, v161, v165, -v169
	v_sin_f32_e32 v170, v169
	v_cos_f32_e32 v169, v169
	v_cndmask_b32_e32 v143, 0, v143, vcc
	v_cndmask_b32_e32 v142, 1.0, v142, vcc
	v_cndmask_b32_e32 v166, 1.0, v166, vcc
	v_mul_f32_e32 v171, v125, v143
	v_mul_f32_e32 v125, v125, v142
	v_cndmask_b32_e32 v168, 0, v168, vcc
	v_cndmask_b32_e32 v167, 1.0, v167, vcc
	v_fma_f32 v171, v124, v142, -v171
	v_fmac_f32_e32 v125, v124, v143
	v_mul_f32_e32 v124, v127, v163
	v_mul_f32_e32 v127, v127, v166
	v_cndmask_b32_e32 v170, 0, v170, vcc
	v_cndmask_b32_e32 v169, 1.0, v169, vcc
	v_fma_f32 v124, v126, v166, -v124
	v_fmac_f32_e32 v127, v126, v163
	v_mul_f32_e32 v126, v121, v168
	v_mul_f32_e32 v142, v121, v167
	v_fma_f32 v126, v120, v167, -v126
	v_fmac_f32_e32 v142, v120, v168
	v_mul_f32_e32 v120, v123, v170
	v_mul_f32_e32 v123, v123, v169
	v_fma_f32 v143, v122, v169, -v120
	v_fmac_f32_e32 v123, v122, v170
	v_cvt_pk_bf16_f32 v120, v171, v125
	v_cvt_pk_bf16_f32 v121, v124, v127
	v_cvt_pk_bf16_f32 v122, v126, v142
	v_cvt_pk_bf16_f32 v123, v143, v123
	global_store_dwordx4 v[140:141], v[120:123], off
; __device__ __forceinline__ unsigned cvt_pk_bf16(float lo, float hi) { unsigned r; asm volatile("v_cvt_pk_bf16_f32 %0, %1, %2" : "=v"(r) : "v"(lo), "v"(hi)); return r; }
;     __device__ __forceinline__ void operator()(const f32x4 (&acc)[2][2][4][2], const Unit& u, int wr, int wc, int fr, int fq) const {
;     ...
;                     if (ACT == 3) { const float pos = (float)((row0 + ai * HALF + m * 16) & 2047); float c3[4], s3[4];
; #pragma unroll
;                         for (int p = 0; p < 4; ++p) { float r = pos * rinv3[bj][p]; r -= floorf(r); s3[p] = rope3[bj] ? __builtin_amdgcn_sinf(r) : 0.f; c3[p] = rope3[bj] ? __builtin_amdgcn_cosf(r) : 1.f; }
;                         const f32x4 a = v0, b = v1;
;                         v0[0] = a[0] * c3[0] - a[1] * s3[0]; v0[1] = a[1] * c3[0] + a[0] * s3[0]; v0[2] = a[2] * c3[1] - a[3] * s3[1]; v0[3] = a[3] * c3[1] + a[2] * s3[1];
;                         v1[0] = b[0] * c3[2] - b[1] * s3[2]; v1[1] = b[1] * c3[2] + b[0] * s3[2]; v1[2] = b[2] * c3[3] - b[3] * s3[3]; v1[3] = b[3] * c3[3] + b[2] * s3[3]; }
;                     if (ACT == 2) { const f32x4 a = v0, b = v1;
;                         v0[0] = a[0] * rc[0][0] - a[1] * rs[0][0]; v0[1] = a[1] * rc[0][0] + a[0] * rs[0][0]; v0[2] = a[2] * rc[0][1] - a[3] * rs[0][1]; v0[3] = a[3] * rc[0][1] + a[2] * rs[0][1];
;                         v1[0] = b[0] * rc[1][0] - b[1] * rs[1][0]; v1[1] = b[1] * rc[1][0] + b[0] * rs[1][0]; v1[2] = b[2] * rc[1][1] - b[3] * rs[1][1]; v1[3] = b[3] * rc[1][1] + b[2] * rs[1][1]; }
;                     if (ACT == 1) {
; #pragma unroll
;                         for (int j = 0; j < 4; ++j) { const float a = __int_as_float(max(__float_as_int(v0[j]), 0)), b = __int_as_float(max(__float_as_int(v1[j]), 0)); v0[j] = a * a; v1[j] = b * b; } }
;                     u32x4 w; w.x = cvt_pk_bf16(v0[0], v0[1]); w.y = cvt_pk_bf16(v0[2], v0[3]); w.z = cvt_pk_bf16(v1[0], v1[1]); w.w = cvt_pk_bf16(v1[2], v1[3]);
;                     *(u32x4*)(rowp + (ACT == 1 ? bj * 2 * 2 * 8192 : bj * HALF)) = w; } }
	v_mul_f32_e32 v124, v160, v165
	v_floor_f32_e32 v124, v124
	v_mul_f32_e32 v120, v155, v165
	v_floor_f32_e32 v120, v120
	v_mul_f32_e32 v122, v157, v165
	v_fma_f32 v120, v155, v165, -v120
	v_floor_f32_e32 v122, v122
	v_sin_f32_e32 v121, v120
	v_cos_f32_e32 v120, v120
	v_fma_f32 v122, v157, v165, -v122
	v_mul_f32_e32 v126, v159, v165
	v_sin_f32_e32 v123, v122
	v_cos_f32_e32 v122, v122
	v_fma_f32 v124, v160, v165, -v124
	v_floor_f32_e32 v126, v126
	v_sin_f32_e32 v125, v124
	v_cos_f32_e32 v124, v124
	v_fma_f32 v126, v159, v165, -v126
	v_cmp_lt_i32_e64 s[4:5], s56, v164
	v_sin_f32_e32 v127, v126
	v_cos_f32_e32 v126, v126
	v_cndmask_b32_e64 v121, 0, v121, s[4:5]
	v_cndmask_b32_e64 v120, 1.0, v120, s[4:5]
	v_cndmask_b32_e64 v123, 0, v123, s[4:5]
	v_cndmask_b32_e64 v122, 1.0, v122, s[4:5]
	v_mul_f32_e32 v142, v117, v121
	v_mul_f32_e32 v117, v117, v120
	v_cndmask_b32_e64 v125, 0, v125, s[4:5]
	v_cndmask_b32_e64 v124, 1.0, v124, s[4:5]
	v_fma_f32 v142, v116, v120, -v142
	v_fmac_f32_e32 v117, v116, v121
	v_mul_f32_e32 v116, v119, v123
	v_mul_f32_e32 v119, v119, v122
	v_cndmask_b32_e64 v127, 0, v127, s[4:5]
	v_cndmask_b32_e64 v126, 1.0, v126, s[4:5]
	v_fma_f32 v116, v118, v122, -v116
	v_fmac_f32_e32 v119, v118, v123
	v_mul_f32_e32 v118, v113, v125
	v_mul_f32_e32 v120, v113, v124
	v_fma_f32 v118, v112, v124, -v118
	v_fmac_f32_e32 v120, v112, v125
	v_mul_f32_e32 v112, v115, v127
	v_mul_f32_e32 v115, v115, v126
	v_fma_f32 v121, v114, v126, -v112
	v_fmac_f32_e32 v115, v114, v127
	v_cvt_pk_bf16_f32 v112, v142, v117
	v_cvt_pk_bf16_f32 v113, v116, v119
	v_cvt_pk_bf16_f32 v114, v118, v120
	v_cvt_pk_bf16_f32 v115, v121, v115
	global_store_dwordx4 v[140:141], v[112:115], off offset:256
	s_nop 1
	v_bitop3_b32 v113, v162, s8, 16 bitop3:0xc8
	v_cvt_f32_u32_e32 v114, v113
	v_or_b32_e32 v112, 16, v162
	v_mad_i64_i32 v[112:113], s[44:45], v112, s57, v[144:145]
	v_mul_f32_e32 v115, v154, v114
	v_floor_f32_e32 v115, v115
	v_mul_f32_e32 v117, v156, v114
	v_fma_f32 v115, v154, v114, -v115
	v_floor_f32_e32 v117, v117
	v_mul_f32_e32 v119, v158, v114
	v_sin_f32_e32 v116, v115
	v_cos_f32_e32 v115, v115
	v_fma_f32 v117, v156, v114, -v117
	v_floor_f32_e32 v119, v119
	v_mul_f32_e32 v121, v161, v114
	v_sin_f32_e32 v118, v117
	v_cos_f32_e32 v117, v117
	v_fma_f32 v119, v158, v114, -v119
	v_floor_f32_e32 v121, v121
	v_sin_f32_e32 v120, v119
	v_cos_f32_e32 v119, v119
	v_fma_f32 v121, v161, v114, -v121
	v_sin_f32_e32 v122, v121
	v_cos_f32_e32 v121, v121
	v_cndmask_b32_e32 v116, 0, v116, vcc
	v_cndmask_b32_e32 v115, 1.0, v115, vcc
	v_cndmask_b32_e32 v118, 0, v118, vcc
	v_cndmask_b32_e32 v117, 1.0, v117, vcc
	v_mul_f32_e32 v123, v109, v116
	v_mul_f32_e32 v109, v109, v115
	v_cndmask_b32_e32 v120, 0, v120, vcc
	v_cndmask_b32_e32 v119, 1.0, v119, vcc
	v_fma_f32 v123, v108, v115, -v123
	v_fmac_f32_e32 v109, v108, v116
	v_mul_f32_e32 v108, v111, v118
	v_mul_f32_e32 v111, v111, v117
	v_cndmask_b32_e32 v122, 0, v122, vcc
	v_cndmask_b32_e32 v121, 1.0, v121, vcc
	v_fma_f32 v108, v110, v117, -v108
	v_fmac_f32_e32 v111, v110, v118
	v_mul_f32_e32 v110, v105, v120
	v_mul_f32_e32 v115, v105, v119
	v_fma_f32 v110, v104, v119, -v110
	v_fmac_f32_e32 v115, v104, v120
	v_mul_f32_e32 v104, v107, v122
	v_mul_f32_e32 v107, v107, v121
	v_lshl_add_u64 v[112:113], v[112:113], 0, v[146:147]
	v_fma_f32 v116, v106, v121, -v104
	v_fmac_f32_e32 v107, v106, v122
	v_cvt_pk_bf16_f32 v104, v123, v109
	v_cvt_pk_bf16_f32 v105, v108, v111
	v_cvt_pk_bf16_f32 v106, v110, v115
	v_cvt_pk_bf16_f32 v107, v116, v107
	global_store_dwordx4 v[112:113], v[104:107], off
	v_mul_f32_e32 v108, v160, v114
	v_floor_f32_e32 v108, v108
	v_mul_f32_e32 v104, v155, v114
	v_floor_f32_e32 v104, v104
	v_mul_f32_e32 v106, v157, v114
	v_fma_f32 v104, v155, v114, -v104
	v_floor_f32_e32 v106, v106
	v_sin_f32_e32 v105, v104
	v_cos_f32_e32 v104, v104
	v_fma_f32 v106, v157, v114, -v106
	v_mul_f32_e32 v110, v159, v114
	v_sin_f32_e32 v107, v106
	v_cos_f32_e32 v106, v106
	v_fma_f32 v108, v160, v114, -v108
	v_floor_f32_e32 v110, v110
	v_sin_f32_e32 v109, v108
	v_cos_f32_e32 v108, v108
	v_fma_f32 v110, v159, v114, -v110
	v_sin_f32_e32 v111, v110
	v_cos_f32_e32 v110, v110
	v_cndmask_b32_e64 v105, 0, v105, s[4:5]
	v_cndmask_b32_e64 v104, 1.0, v104, s[4:5]
	v_cndmask_b32_e64 v107, 0, v107, s[4:5]
	v_cndmask_b32_e64 v106, 1.0, v106, s[4:5]
	v_mul_f32_e32 v114, v101, v105
	v_mul_f32_e32 v101, v101, v104
	v_cndmask_b32_e64 v109, 0, v109, s[4:5]
	v_cndmask_b32_e64 v108, 1.0, v108, s[4:5]
	v_fma_f32 v114, v100, v104, -v114
	v_fmac_f32_e32 v101, v100, v105
	v_mul_f32_e32 v100, v103, v107
	v_mul_f32_e32 v103, v103, v106
	v_cndmask_b32_e64 v111, 0, v111, s[4:5]
	v_cndmask_b32_e64 v110, 1.0, v110, s[4:5]
	v_fma_f32 v100, v102, v106, -v100
	v_fmac_f32_e32 v103, v102, v107
	v_mul_f32_e32 v102, v97, v109
	v_mul_f32_e32 v104, v97, v108
	v_fma_f32 v102, v96, v108, -v102
	v_fmac_f32_e32 v104, v96, v109
	v_mul_f32_e32 v96, v99, v111
	v_mul_f32_e32 v99, v99, v110
	v_fma_f32 v105, v98, v110, -v96
	v_fmac_f32_e32 v99, v98, v111
	v_cvt_pk_bf16_f32 v96, v114, v101
	v_cvt_pk_bf16_f32 v97, v100, v103
	s_movk_i32 s8, 0x7ef
	v_cvt_pk_bf16_f32 v98, v102, v104
	v_cvt_pk_bf16_f32 v99, v105, v99
	global_store_dwordx4 v[112:113], v[96:99], off offset:256
	s_nop 1
	v_bitop3_b32 v97, v162, s8, 32 bitop3:0xc8
	v_cvt_f32_u32_e32 v98, v97
	v_or_b32_e32 v96, 32, v162
	v_mad_i64_i32 v[96:97], s[44:45], v96, s57, v[144:145]
	v_mul_f32_e32 v99, v154, v98
	v_floor_f32_e32 v99, v99
	v_mul_f32_e32 v101, v156, v98
	v_fma_f32 v99, v154, v98, -v99
	v_floor_f32_e32 v101, v101
	v_mul_f32_e32 v103, v158, v98
	v_sin_f32_e32 v100, v99
	v_cos_f32_e32 v99, v99
	v_fma_f32 v101, v156, v98, -v101
; __device__ __forceinline__ unsigned cvt_pk_bf16(float lo, float hi) { unsigned r; asm volatile("v_cvt_pk_bf16_f32 %0, %1, %2" : "=v"(r) : "v"(lo), "v"(hi)); return r; }
;     __device__ __forceinline__ void operator()(const f32x4 (&acc)[2][2][4][2], const Unit& u, int wr, int wc, int fr, int fq) const {
;     ...
;                 for (int bj = 0; bj < 2; ++bj) { f32x4 v0 = acc[ai][bj][m][0], v1 = acc[ai][bj][m][1];
;                     if (ACT == 3) { const float pos = (float)((row0 + ai * HALF + m * 16) & 2047); float c3[4], s3[4];
; #pragma unroll
;                         for (int p = 0; p < 4; ++p) { float r = pos * rinv3[bj][p]; r -= floorf(r); s3[p] = rope3[bj] ? __builtin_amdgcn_sinf(r) : 0.f; c3[p] = rope3[bj] ? __builtin_amdgcn_cosf(r) : 1.f; }
;                         const f32x4 a = v0, b = v1;
;                         v0[0] = a[0] * c3[0] - a[1] * s3[0]; v0[1] = a[1] * c3[0] + a[0] * s3[0]; v0[2] = a[2] * c3[1] - a[3] * s3[1]; v0[3] = a[3] * c3[1] + a[2] * s3[1];
;                         v1[0] = b[0] * c3[2] - b[1] * s3[2]; v1[1] = b[1] * c3[2] + b[0] * s3[2]; v1[2] = b[2] * c3[3] - b[3] * s3[3]; v1[3] = b[3] * c3[3] + b[2] * s3[3]; }
;                     if (ACT == 2) { const f32x4 a = v0, b = v1;
;                         v0[0] = a[0] * rc[0][0] - a[1] * rs[0][0]; v0[1] = a[1] * rc[0][0] + a[0] * rs[0][0]; v0[2] = a[2] * rc[0][1] - a[3] * rs[0][1]; v0[3] = a[3] * rc[0][1] + a[2] * rs[0][1];
;                         v1[0] = b[0] * rc[1][0] - b[1] * rs[1][0]; v1[1] = b[1] * rc[1][0] + b[0] * rs[1][0]; v1[2] = b[2] * rc[1][1] - b[3] * rs[1][1]; v1[3] = b[3] * rc[1][1] + b[2] * rs[1][1]; }
;                     if (ACT == 1) {
; #pragma unroll
;                         for (int j = 0; j < 4; ++j) { const float a = __int_as_float(max(__float_as_int(v0[j]), 0)), b = __int_as_float(max(__float_as_int(v1[j]), 0)); v0[j] = a * a; v1[j] = b * b; } }
;                     u32x4 w; w.x = cvt_pk_bf16(v0[0], v0[1]); w.y = cvt_pk_bf16(v0[2], v0[3]); w.z = cvt_pk_bf16(v1[0], v1[1]); w.w = cvt_pk_bf16(v1[2], v1[3]);
;                     *(u32x4*)(rowp + (ACT == 1 ? bj * 2 * 2 * 8192 : bj * HALF)) = w; } }
	v_floor_f32_e32 v103, v103
	v_mul_f32_e32 v105, v161, v98
	v_sin_f32_e32 v102, v101
	v_cos_f32_e32 v101, v101
	v_fma_f32 v103, v158, v98, -v103
	v_floor_f32_e32 v105, v105
	v_sin_f32_e32 v104, v103
	v_cos_f32_e32 v103, v103
	v_fma_f32 v105, v161, v98, -v105
	v_sin_f32_e32 v106, v105
	v_cos_f32_e32 v105, v105
	v_cndmask_b32_e32 v100, 0, v100, vcc
	v_cndmask_b32_e32 v99, 1.0, v99, vcc
	v_cndmask_b32_e32 v102, 0, v102, vcc
	v_cndmask_b32_e32 v101, 1.0, v101, vcc
	v_mul_f32_e32 v107, v93, v100
	v_mul_f32_e32 v93, v93, v99
	v_cndmask_b32_e32 v104, 0, v104, vcc
	v_cndmask_b32_e32 v103, 1.0, v103, vcc
	v_fma_f32 v107, v92, v99, -v107
	v_fmac_f32_e32 v93, v92, v100
	v_mul_f32_e32 v92, v95, v102
	v_mul_f32_e32 v95, v95, v101
	v_cndmask_b32_e32 v106, 0, v106, vcc
	v_cndmask_b32_e32 v105, 1.0, v105, vcc
	v_fma_f32 v92, v94, v101, -v92
	v_fmac_f32_e32 v95, v94, v102
	v_mul_f32_e32 v94, v89, v104
	v_mul_f32_e32 v99, v89, v103
	v_fma_f32 v94, v88, v103, -v94
	v_fmac_f32_e32 v99, v88, v104
	v_mul_f32_e32 v88, v91, v106
	v_mul_f32_e32 v91, v91, v105
	v_lshl_add_u64 v[96:97], v[96:97], 0, v[146:147]
	v_fma_f32 v100, v90, v105, -v88
	v_fmac_f32_e32 v91, v90, v106
	v_cvt_pk_bf16_f32 v88, v107, v93
	v_cvt_pk_bf16_f32 v89, v92, v95
	v_cvt_pk_bf16_f32 v90, v94, v99
	v_cvt_pk_bf16_f32 v91, v100, v91
	global_store_dwordx4 v[96:97], v[88:91], off
	v_mul_f32_e32 v92, v160, v98
	v_floor_f32_e32 v92, v92
	v_mul_f32_e32 v88, v155, v98
	v_floor_f32_e32 v88, v88
	v_mul_f32_e32 v90, v157, v98
	v_fma_f32 v88, v155, v98, -v88
	v_floor_f32_e32 v90, v90
	v_sin_f32_e32 v89, v88
	v_cos_f32_e32 v88, v88
	v_fma_f32 v90, v157, v98, -v90
	v_mul_f32_e32 v94, v159, v98
	v_sin_f32_e32 v91, v90
	v_cos_f32_e32 v90, v90
	v_fma_f32 v92, v160, v98, -v92
	v_floor_f32_e32 v94, v94
	v_sin_f32_e32 v93, v92
	v_cos_f32_e32 v92, v92
	v_fma_f32 v94, v159, v98, -v94
	v_sin_f32_e32 v95, v94
	v_cos_f32_e32 v94, v94
	v_cndmask_b32_e64 v89, 0, v89, s[4:5]
	v_cndmask_b32_e64 v88, 1.0, v88, s[4:5]
	v_cndmask_b32_e64 v91, 0, v91, s[4:5]
	v_cndmask_b32_e64 v90, 1.0, v90, s[4:5]
	v_mul_f32_e32 v98, v85, v89
	v_mul_f32_e32 v85, v85, v88
	v_cndmask_b32_e64 v93, 0, v93, s[4:5]
	v_cndmask_b32_e64 v92, 1.0, v92, s[4:5]
	v_fma_f32 v98, v84, v88, -v98
	v_fmac_f32_e32 v85, v84, v89
	v_mul_f32_e32 v84, v87, v91
	v_mul_f32_e32 v87, v87, v90
	v_cndmask_b32_e64 v95, 0, v95, s[4:5]
	v_cndmask_b32_e64 v94, 1.0, v94, s[4:5]
	v_fma_f32 v84, v86, v90, -v84
	v_fmac_f32_e32 v87, v86, v91
	v_mul_f32_e32 v86, v81, v93
	v_mul_f32_e32 v88, v81, v92
	v_fma_f32 v86, v80, v92, -v86
	v_fmac_f32_e32 v88, v80, v93
	v_mul_f32_e32 v80, v83, v95
	v_mul_f32_e32 v83, v83, v94
	v_fma_f32 v89, v82, v94, -v80
	v_fmac_f32_e32 v83, v82, v95
	v_cvt_pk_bf16_f32 v80, v98, v85
	v_cvt_pk_bf16_f32 v81, v84, v87
	s_movk_i32 s8, 0x7ff
	v_cvt_pk_bf16_f32 v82, v86, v88
	v_cvt_pk_bf16_f32 v83, v89, v83
	global_store_dwordx4 v[96:97], v[80:83], off offset:256
	s_nop 1
	v_bitop3_b32 v81, v162, s8, 48 bitop3:0xc8
	v_cvt_f32_u32_e32 v82, v81
	v_or_b32_e32 v80, 48, v162
	v_mad_i64_i32 v[80:81], s[44:45], v80, s57, v[144:145]
	v_mul_f32_e32 v83, v154, v82
	v_floor_f32_e32 v83, v83
	v_mul_f32_e32 v85, v156, v82
	v_fma_f32 v83, v154, v82, -v83
	v_floor_f32_e32 v85, v85
	v_mul_f32_e32 v87, v158, v82
	v_sin_f32_e32 v84, v83
	v_cos_f32_e32 v83, v83
	v_fma_f32 v85, v156, v82, -v85
	v_floor_f32_e32 v87, v87
	v_mul_f32_e32 v89, v161, v82
	v_sin_f32_e32 v86, v85
	v_cos_f32_e32 v85, v85
	v_fma_f32 v87, v158, v82, -v87
	v_floor_f32_e32 v89, v89
	v_sin_f32_e32 v88, v87
	v_cos_f32_e32 v87, v87
	v_fma_f32 v89, v161, v82, -v89
	v_sin_f32_e32 v90, v89
	v_cos_f32_e32 v89, v89
	v_cndmask_b32_e32 v84, 0, v84, vcc
	v_cndmask_b32_e32 v83, 1.0, v83, vcc
	v_cndmask_b32_e32 v86, 0, v86, vcc
	v_cndmask_b32_e32 v85, 1.0, v85, vcc
	v_mul_f32_e32 v91, v77, v84
	v_mul_f32_e32 v77, v77, v83
	v_cndmask_b32_e32 v88, 0, v88, vcc
	v_cndmask_b32_e32 v87, 1.0, v87, vcc
	v_fma_f32 v91, v76, v83, -v91
	v_fmac_f32_e32 v77, v76, v84
	v_mul_f32_e32 v76, v79, v86
	v_mul_f32_e32 v79, v79, v85
	v_cndmask_b32_e32 v90, 0, v90, vcc
	v_cndmask_b32_e32 v89, 1.0, v89, vcc
	v_fma_f32 v76, v78, v85, -v76
	v_fmac_f32_e32 v79, v78, v86
	v_mul_f32_e32 v78, v73, v88
	v_mul_f32_e32 v83, v73, v87
	v_fma_f32 v78, v72, v87, -v78
	v_fmac_f32_e32 v83, v72, v88
	v_mul_f32_e32 v72, v75, v90
	v_mul_f32_e32 v75, v75, v89
	v_lshl_add_u64 v[80:81], v[80:81], 0, v[146:147]
	v_fma_f32 v84, v74, v89, -v72
	v_fmac_f32_e32 v75, v74, v90
	v_cvt_pk_bf16_f32 v72, v91, v77
	v_cvt_pk_bf16_f32 v73, v76, v79
	v_cvt_pk_bf16_f32 v74, v78, v83
	v_cvt_pk_bf16_f32 v75, v84, v75
	global_store_dwordx4 v[80:81], v[72:75], off
	v_mul_f32_e32 v76, v160, v82
	v_floor_f32_e32 v76, v76
	v_mul_f32_e32 v72, v155, v82
	v_floor_f32_e32 v72, v72
	v_mul_f32_e32 v74, v157, v82
	v_fma_f32 v72, v155, v82, -v72
	v_floor_f32_e32 v74, v74
	v_sin_f32_e32 v73, v72
	v_cos_f32_e32 v72, v72
	v_fma_f32 v74, v157, v82, -v74
	v_mul_f32_e32 v78, v159, v82
	v_sin_f32_e32 v75, v74
	v_cos_f32_e32 v74, v74
	v_fma_f32 v76, v160, v82, -v76
	v_floor_f32_e32 v78, v78
	v_sin_f32_e32 v77, v76
	v_cos_f32_e32 v76, v76
	v_fma_f32 v78, v159, v82, -v78
	v_sin_f32_e32 v79, v78
	v_cos_f32_e32 v78, v78
	v_cndmask_b32_e64 v73, 0, v73, s[4:5]
	v_cndmask_b32_e64 v72, 1.0, v72, s[4:5]
	v_cndmask_b32_e64 v75, 0, v75, s[4:5]
	v_cndmask_b32_e64 v74, 1.0, v74, s[4:5]
	v_mul_f32_e32 v82, v69, v73
	v_mul_f32_e32 v69, v69, v72
	v_cndmask_b32_e64 v77, 0, v77, s[4:5]
	v_cndmask_b32_e64 v76, 1.0, v76, s[4:5]
	v_fma_f32 v82, v68, v72, -v82
	v_fmac_f32_e32 v69, v68, v73
	v_mul_f32_e32 v68, v71, v75
	v_mul_f32_e32 v71, v71, v74
	v_cndmask_b32_e64 v79, 0, v79, s[4:5]
	v_cndmask_b32_e64 v78, 1.0, v78, s[4:5]
; __device__ __forceinline__ unsigned cvt_pk_bf16(float lo, float hi) { unsigned r; asm volatile("v_cvt_pk_bf16_f32 %0, %1, %2" : "=v"(r) : "v"(lo), "v"(hi)); return r; }
;     __device__ __forceinline__ void operator()(const f32x4 (&acc)[2][2][4][2], const Unit& u, int wr, int wc, int fr, int fq) const {
;     ...
;                 for (int bj = 0; bj < 2; ++bj) { f32x4 v0 = acc[ai][bj][m][0], v1 = acc[ai][bj][m][1];
;                     if (ACT == 3) { const float pos = (float)((row0 + ai * HALF + m * 16) & 2047); float c3[4], s3[4];
; #pragma unroll
;                         for (int p = 0; p < 4; ++p) { float r = pos * rinv3[bj][p]; r -= floorf(r); s3[p] = rope3[bj] ? __builtin_amdgcn_sinf(r) : 0.f; c3[p] = rope3[bj] ? __builtin_amdgcn_cosf(r) : 1.f; }
;                         const f32x4 a = v0, b = v1;
;                         v0[0] = a[0] * c3[0] - a[1] * s3[0]; v0[1] = a[1] * c3[0] + a[0] * s3[0]; v0[2] = a[2] * c3[1] - a[3] * s3[1]; v0[3] = a[3] * c3[1] + a[2] * s3[1];
;                         v1[0] = b[0] * c3[2] - b[1] * s3[2]; v1[1] = b[1] * c3[2] + b[0] * s3[2]; v1[2] = b[2] * c3[3] - b[3] * s3[3]; v1[3] = b[3] * c3[3] + b[2] * s3[3]; }
;                     if (ACT == 2) { const f32x4 a = v0, b = v1;
;                         v0[0] = a[0] * rc[0][0] - a[1] * rs[0][0]; v0[1] = a[1] * rc[0][0] + a[0] * rs[0][0]; v0[2] = a[2] * rc[0][1] - a[3] * rs[0][1]; v0[3] = a[3] * rc[0][1] + a[2] * rs[0][1];
;                         v1[0] = b[0] * rc[1][0] - b[1] * rs[1][0]; v1[1] = b[1] * rc[1][0] + b[0] * rs[1][0]; v1[2] = b[2] * rc[1][1] - b[3] * rs[1][1]; v1[3] = b[3] * rc[1][1] + b[2] * rs[1][1]; }
;                     if (ACT == 1) {
; #pragma unroll
;                         for (int j = 0; j < 4; ++j) { const float a = __int_as_float(max(__float_as_int(v0[j]), 0)), b = __int_as_float(max(__float_as_int(v1[j]), 0)); v0[j] = a * a; v1[j] = b * b; } }
;                     u32x4 w; w.x = cvt_pk_bf16(v0[0], v0[1]); w.y = cvt_pk_bf16(v0[2], v0[3]); w.z = cvt_pk_bf16(v1[0], v1[1]); w.w = cvt_pk_bf16(v1[2], v1[3]);
;                     *(u32x4*)(rowp + (ACT == 1 ? bj * 2 * 2 * 8192 : bj * HALF)) = w; } }
	v_fma_f32 v68, v70, v74, -v68
	v_fmac_f32_e32 v71, v70, v75
	v_mul_f32_e32 v70, v65, v77
	v_mul_f32_e32 v72, v65, v76
	v_fma_f32 v70, v64, v76, -v70
	v_fmac_f32_e32 v72, v64, v77
	v_mul_f32_e32 v64, v67, v79
	v_mul_f32_e32 v67, v67, v78
	v_fma_f32 v73, v66, v78, -v64
	v_fmac_f32_e32 v67, v66, v79
	v_cvt_pk_bf16_f32 v64, v82, v69
	v_cvt_pk_bf16_f32 v65, v68, v71
	v_cvt_pk_bf16_f32 v66, v70, v72
	v_cvt_pk_bf16_f32 v67, v73, v67
	global_store_dwordx4 v[80:81], v[64:67], off offset:256
	s_nop 1
	v_add_u32_e32 v64, 0x80, v162
	v_and_b32_e32 v65, 0x7cf, v64
	v_cvt_f32_u32_e32 v66, v65
	v_mad_i64_i32 v[64:65], s[44:45], v64, s57, v[144:145]
	v_lshl_add_u64 v[64:65], v[64:65], 0, v[146:147]
	v_mul_f32_e32 v67, v154, v66
	v_floor_f32_e32 v67, v67
	v_mul_f32_e32 v69, v156, v66
	v_fma_f32 v67, v154, v66, -v67
	v_floor_f32_e32 v69, v69
	v_mul_f32_e32 v71, v158, v66
	v_sin_f32_e32 v68, v67
	v_cos_f32_e32 v67, v67
	v_fma_f32 v69, v156, v66, -v69
	v_floor_f32_e32 v71, v71
	v_mul_f32_e32 v73, v161, v66
	v_sin_f32_e32 v70, v69
	v_cos_f32_e32 v69, v69
	v_fma_f32 v71, v158, v66, -v71
	v_floor_f32_e32 v73, v73
	v_sin_f32_e32 v72, v71
	v_cos_f32_e32 v71, v71
	v_fma_f32 v73, v161, v66, -v73
	v_sin_f32_e32 v74, v73
	v_cos_f32_e32 v73, v73
	v_cndmask_b32_e32 v68, 0, v68, vcc
	v_cndmask_b32_e32 v67, 1.0, v67, vcc
	v_cndmask_b32_e32 v70, 0, v70, vcc
	v_cndmask_b32_e32 v69, 1.0, v69, vcc
	v_mul_f32_e32 v75, v61, v68
	v_mul_f32_e32 v61, v61, v67
	v_cndmask_b32_e32 v72, 0, v72, vcc
	v_cndmask_b32_e32 v71, 1.0, v71, vcc
	v_fma_f32 v75, v60, v67, -v75
	v_fmac_f32_e32 v61, v60, v68
	v_mul_f32_e32 v60, v63, v70
	v_mul_f32_e32 v63, v63, v69
	v_cndmask_b32_e32 v74, 0, v74, vcc
	v_cndmask_b32_e32 v73, 1.0, v73, vcc
	v_fma_f32 v60, v62, v69, -v60
	v_fmac_f32_e32 v63, v62, v70
	v_mul_f32_e32 v62, v57, v72
	v_mul_f32_e32 v67, v57, v71
	v_fma_f32 v62, v56, v71, -v62
	v_fmac_f32_e32 v67, v56, v72
	v_mul_f32_e32 v56, v59, v74
	v_mul_f32_e32 v59, v59, v73
	v_fma_f32 v68, v58, v73, -v56
	v_fmac_f32_e32 v59, v58, v74
	v_cvt_pk_bf16_f32 v56, v75, v61
	v_cvt_pk_bf16_f32 v57, v60, v63
	v_cvt_pk_bf16_f32 v58, v62, v67
	v_cvt_pk_bf16_f32 v59, v68, v59
	global_store_dwordx4 v[64:65], v[56:59], off
	v_mul_f32_e32 v60, v160, v66
	v_floor_f32_e32 v60, v60
	v_mul_f32_e32 v56, v155, v66
	v_floor_f32_e32 v56, v56
	v_mul_f32_e32 v58, v157, v66
	v_fma_f32 v56, v155, v66, -v56
	v_floor_f32_e32 v58, v58
	v_sin_f32_e32 v57, v56
	v_cos_f32_e32 v56, v56
	v_fma_f32 v58, v157, v66, -v58
	v_mul_f32_e32 v62, v159, v66
	v_sin_f32_e32 v59, v58
	v_cos_f32_e32 v58, v58
	v_fma_f32 v60, v160, v66, -v60
	v_floor_f32_e32 v62, v62
	v_sin_f32_e32 v61, v60
	v_cos_f32_e32 v60, v60
	v_fma_f32 v62, v159, v66, -v62
	v_sin_f32_e32 v63, v62
	v_cos_f32_e32 v62, v62
	v_cndmask_b32_e64 v57, 0, v57, s[4:5]
	v_cndmask_b32_e64 v56, 1.0, v56, s[4:5]
	v_cndmask_b32_e64 v59, 0, v59, s[4:5]
	v_cndmask_b32_e64 v58, 1.0, v58, s[4:5]
	v_mul_f32_e32 v66, v53, v57
	v_mul_f32_e32 v53, v53, v56
	v_cndmask_b32_e64 v61, 0, v61, s[4:5]
	v_cndmask_b32_e64 v60, 1.0, v60, s[4:5]
	v_fma_f32 v66, v52, v56, -v66
	v_fmac_f32_e32 v53, v52, v57
	v_mul_f32_e32 v52, v55, v59
	v_mul_f32_e32 v55, v55, v58
	v_cndmask_b32_e64 v63, 0, v63, s[4:5]
	v_cndmask_b32_e64 v62, 1.0, v62, s[4:5]
	v_fma_f32 v52, v54, v58, -v52
	v_fmac_f32_e32 v55, v54, v59
	v_mul_f32_e32 v54, v49, v61
	v_mul_f32_e32 v56, v49, v60
	v_fma_f32 v54, v48, v60, -v54
	v_fmac_f32_e32 v56, v48, v61
	v_mul_f32_e32 v48, v51, v63
	v_mul_f32_e32 v51, v51, v62
	v_fma_f32 v57, v50, v62, -v48
	v_fmac_f32_e32 v51, v50, v63
	v_cvt_pk_bf16_f32 v48, v66, v53
	v_cvt_pk_bf16_f32 v49, v52, v55
	v_cvt_pk_bf16_f32 v50, v54, v56
	v_cvt_pk_bf16_f32 v51, v57, v51
	global_store_dwordx4 v[64:65], v[48:51], off offset:256
	s_nop 1
	v_add_u32_e32 v48, 0x90, v162
	v_and_b32_e32 v49, 0x7df, v48
	v_cvt_f32_u32_e32 v50, v49
	v_mad_i64_i32 v[48:49], s[44:45], v48, s57, v[144:145]
	v_lshl_add_u64 v[48:49], v[48:49], 0, v[146:147]
	v_mul_f32_e32 v51, v154, v50
	v_floor_f32_e32 v51, v51
	v_mul_f32_e32 v53, v156, v50
	v_fma_f32 v51, v154, v50, -v51
	v_floor_f32_e32 v53, v53
	v_mul_f32_e32 v55, v158, v50
	v_sin_f32_e32 v52, v51
	v_cos_f32_e32 v51, v51
	v_fma_f32 v53, v156, v50, -v53
	v_floor_f32_e32 v55, v55
	v_mul_f32_e32 v57, v161, v50
	v_sin_f32_e32 v54, v53
	v_cos_f32_e32 v53, v53
	v_fma_f32 v55, v158, v50, -v55
	v_floor_f32_e32 v57, v57
	v_sin_f32_e32 v56, v55
	v_cos_f32_e32 v55, v55
	v_fma_f32 v57, v161, v50, -v57
	v_sin_f32_e32 v58, v57
	v_cos_f32_e32 v57, v57
	v_cndmask_b32_e32 v52, 0, v52, vcc
	v_cndmask_b32_e32 v51, 1.0, v51, vcc
	v_cndmask_b32_e32 v54, 0, v54, vcc
	v_cndmask_b32_e32 v53, 1.0, v53, vcc
	v_mul_f32_e32 v59, v45, v52
	v_mul_f32_e32 v45, v45, v51
	v_cndmask_b32_e32 v56, 0, v56, vcc
	v_cndmask_b32_e32 v55, 1.0, v55, vcc
	v_fma_f32 v59, v44, v51, -v59
	v_fmac_f32_e32 v45, v44, v52
	v_mul_f32_e32 v44, v47, v54
	v_mul_f32_e32 v47, v47, v53
	v_cndmask_b32_e32 v58, 0, v58, vcc
	v_cndmask_b32_e32 v57, 1.0, v57, vcc
	v_fma_f32 v44, v46, v53, -v44
	v_fmac_f32_e32 v47, v46, v54
	v_mul_f32_e32 v46, v41, v56
	v_mul_f32_e32 v51, v41, v55
	v_fma_f32 v46, v40, v55, -v46
	v_fmac_f32_e32 v51, v40, v56
	v_mul_f32_e32 v40, v43, v58
	v_mul_f32_e32 v43, v43, v57
	v_fma_f32 v52, v42, v57, -v40
	v_fmac_f32_e32 v43, v42, v58
	v_cvt_pk_bf16_f32 v40, v59, v45
	v_cvt_pk_bf16_f32 v41, v44, v47
	v_cvt_pk_bf16_f32 v42, v46, v51
	v_cvt_pk_bf16_f32 v43, v52, v43
	global_store_dwordx4 v[48:49], v[40:43], off
	v_mul_f32_e32 v44, v160, v50
	v_floor_f32_e32 v44, v44
	v_mul_f32_e32 v40, v155, v50
	v_floor_f32_e32 v40, v40
	v_mul_f32_e32 v42, v157, v50
	v_fma_f32 v40, v155, v50, -v40
	v_floor_f32_e32 v42, v42
	v_sin_f32_e32 v41, v40
; __device__ __forceinline__ unsigned cvt_pk_bf16(float lo, float hi) { unsigned r; asm volatile("v_cvt_pk_bf16_f32 %0, %1, %2" : "=v"(r) : "v"(lo), "v"(hi)); return r; }
;     __device__ __forceinline__ void operator()(const f32x4 (&acc)[2][2][4][2], const Unit& u, int wr, int wc, int fr, int fq) const {
;     ...
;                 for (int bj = 0; bj < 2; ++bj) { f32x4 v0 = acc[ai][bj][m][0], v1 = acc[ai][bj][m][1];
;                     if (ACT == 3) { const float pos = (float)((row0 + ai * HALF + m * 16) & 2047); float c3[4], s3[4];
; #pragma unroll
;                         for (int p = 0; p < 4; ++p) { float r = pos * rinv3[bj][p]; r -= floorf(r); s3[p] = rope3[bj] ? __builtin_amdgcn_sinf(r) : 0.f; c3[p] = rope3[bj] ? __builtin_amdgcn_cosf(r) : 1.f; }
;                         const f32x4 a = v0, b = v1;
;                         v0[0] = a[0] * c3[0] - a[1] * s3[0]; v0[1] = a[1] * c3[0] + a[0] * s3[0]; v0[2] = a[2] * c3[1] - a[3] * s3[1]; v0[3] = a[3] * c3[1] + a[2] * s3[1];
;                         v1[0] = b[0] * c3[2] - b[1] * s3[2]; v1[1] = b[1] * c3[2] + b[0] * s3[2]; v1[2] = b[2] * c3[3] - b[3] * s3[3]; v1[3] = b[3] * c3[3] + b[2] * s3[3]; }
;                     if (ACT == 2) { const f32x4 a = v0, b = v1;
;                         v0[0] = a[0] * rc[0][0] - a[1] * rs[0][0]; v0[1] = a[1] * rc[0][0] + a[0] * rs[0][0]; v0[2] = a[2] * rc[0][1] - a[3] * rs[0][1]; v0[3] = a[3] * rc[0][1] + a[2] * rs[0][1];
;                         v1[0] = b[0] * rc[1][0] - b[1] * rs[1][0]; v1[1] = b[1] * rc[1][0] + b[0] * rs[1][0]; v1[2] = b[2] * rc[1][1] - b[3] * rs[1][1]; v1[3] = b[3] * rc[1][1] + b[2] * rs[1][1]; }
;                     if (ACT == 1) {
; #pragma unroll
;                         for (int j = 0; j < 4; ++j) { const float a = __int_as_float(max(__float_as_int(v0[j]), 0)), b = __int_as_float(max(__float_as_int(v1[j]), 0)); v0[j] = a * a; v1[j] = b * b; } }
;                     u32x4 w; w.x = cvt_pk_bf16(v0[0], v0[1]); w.y = cvt_pk_bf16(v0[2], v0[3]); w.z = cvt_pk_bf16(v1[0], v1[1]); w.w = cvt_pk_bf16(v1[2], v1[3]);
;                     *(u32x4*)(rowp + (ACT == 1 ? bj * 2 * 2 * 8192 : bj * HALF)) = w; } }
	v_cos_f32_e32 v40, v40
	v_fma_f32 v42, v157, v50, -v42
	v_mul_f32_e32 v46, v159, v50
	v_sin_f32_e32 v43, v42
	v_cos_f32_e32 v42, v42
	v_fma_f32 v44, v160, v50, -v44
	v_floor_f32_e32 v46, v46
	v_sin_f32_e32 v45, v44
	v_cos_f32_e32 v44, v44
	v_fma_f32 v46, v159, v50, -v46
	v_sin_f32_e32 v47, v46
	v_cos_f32_e32 v46, v46
	v_cndmask_b32_e64 v41, 0, v41, s[4:5]
	v_cndmask_b32_e64 v40, 1.0, v40, s[4:5]
	v_cndmask_b32_e64 v43, 0, v43, s[4:5]
	v_cndmask_b32_e64 v42, 1.0, v42, s[4:5]
	v_mul_f32_e32 v50, v37, v41
	v_mul_f32_e32 v37, v37, v40
	v_cndmask_b32_e64 v45, 0, v45, s[4:5]
	v_cndmask_b32_e64 v44, 1.0, v44, s[4:5]
	v_fma_f32 v50, v36, v40, -v50
	v_fmac_f32_e32 v37, v36, v41
	v_mul_f32_e32 v36, v39, v43
	v_mul_f32_e32 v39, v39, v42
	v_cndmask_b32_e64 v47, 0, v47, s[4:5]
	v_cndmask_b32_e64 v46, 1.0, v46, s[4:5]
	v_fma_f32 v36, v38, v42, -v36
	v_fmac_f32_e32 v39, v38, v43
	v_mul_f32_e32 v38, v33, v45
	v_mul_f32_e32 v40, v33, v44
	v_fma_f32 v38, v32, v44, -v38
	v_fmac_f32_e32 v40, v32, v45
	v_mul_f32_e32 v32, v35, v47
	v_mul_f32_e32 v35, v35, v46
	v_fma_f32 v41, v34, v46, -v32
	v_fmac_f32_e32 v35, v34, v47
	v_cvt_pk_bf16_f32 v32, v50, v37
	v_cvt_pk_bf16_f32 v33, v36, v39
	v_cvt_pk_bf16_f32 v34, v38, v40
	v_cvt_pk_bf16_f32 v35, v41, v35
	global_store_dwordx4 v[48:49], v[32:35], off offset:256
	s_nop 1
	v_add_u32_e32 v32, 0xa0, v162
	v_and_b32_e32 v33, 0x7ef, v32
	v_cvt_f32_u32_e32 v34, v33
	v_mad_i64_i32 v[32:33], s[44:45], v32, s57, v[144:145]
	v_lshl_add_u64 v[32:33], v[32:33], 0, v[146:147]
	v_mul_f32_e32 v35, v154, v34
	v_floor_f32_e32 v35, v35
	v_mul_f32_e32 v37, v156, v34
	v_fma_f32 v35, v154, v34, -v35
	v_floor_f32_e32 v37, v37
	v_mul_f32_e32 v39, v158, v34
	v_sin_f32_e32 v36, v35
	v_cos_f32_e32 v35, v35
	v_fma_f32 v37, v156, v34, -v37
	v_floor_f32_e32 v39, v39
	v_mul_f32_e32 v41, v161, v34
	v_sin_f32_e32 v38, v37
	v_cos_f32_e32 v37, v37
	v_fma_f32 v39, v158, v34, -v39
	v_floor_f32_e32 v41, v41
	v_sin_f32_e32 v40, v39
	v_cos_f32_e32 v39, v39
	v_fma_f32 v41, v161, v34, -v41
	v_sin_f32_e32 v42, v41
	v_cos_f32_e32 v41, v41
	v_cndmask_b32_e32 v36, 0, v36, vcc
	v_cndmask_b32_e32 v35, 1.0, v35, vcc
	v_cndmask_b32_e32 v38, 0, v38, vcc
	v_cndmask_b32_e32 v37, 1.0, v37, vcc
	v_mul_f32_e32 v43, v29, v36
	v_mul_f32_e32 v29, v29, v35
	v_cndmask_b32_e32 v40, 0, v40, vcc
	v_cndmask_b32_e32 v39, 1.0, v39, vcc
	v_fma_f32 v43, v28, v35, -v43
	v_fmac_f32_e32 v29, v28, v36
	v_mul_f32_e32 v28, v31, v38
	v_mul_f32_e32 v31, v31, v37
	v_cndmask_b32_e32 v42, 0, v42, vcc
	v_cndmask_b32_e32 v41, 1.0, v41, vcc
	v_fma_f32 v28, v30, v37, -v28
	v_fmac_f32_e32 v31, v30, v38
	v_mul_f32_e32 v30, v25, v40
	v_mul_f32_e32 v35, v25, v39
	v_fma_f32 v30, v24, v39, -v30
	v_fmac_f32_e32 v35, v24, v40
	v_mul_f32_e32 v24, v27, v42
	v_mul_f32_e32 v27, v27, v41
	v_fma_f32 v36, v26, v41, -v24
	v_fmac_f32_e32 v27, v26, v42
	v_cvt_pk_bf16_f32 v24, v43, v29
	v_cvt_pk_bf16_f32 v25, v28, v31
	v_cvt_pk_bf16_f32 v26, v30, v35
	v_cvt_pk_bf16_f32 v27, v36, v27
	global_store_dwordx4 v[32:33], v[24:27], off
	v_mul_f32_e32 v28, v160, v34
	v_floor_f32_e32 v28, v28
	v_mul_f32_e32 v24, v155, v34
	v_floor_f32_e32 v24, v24
	v_mul_f32_e32 v26, v157, v34
	v_fma_f32 v24, v155, v34, -v24
	v_floor_f32_e32 v26, v26
	v_sin_f32_e32 v25, v24
	v_cos_f32_e32 v24, v24
	v_fma_f32 v26, v157, v34, -v26
	v_mul_f32_e32 v30, v159, v34
	v_sin_f32_e32 v27, v26
	v_cos_f32_e32 v26, v26
	v_fma_f32 v28, v160, v34, -v28
	v_floor_f32_e32 v30, v30
	v_sin_f32_e32 v29, v28
	v_cos_f32_e32 v28, v28
	v_fma_f32 v30, v159, v34, -v30
	v_sin_f32_e32 v31, v30
	v_cos_f32_e32 v30, v30
	v_cndmask_b32_e64 v25, 0, v25, s[4:5]
	v_cndmask_b32_e64 v24, 1.0, v24, s[4:5]
	v_cndmask_b32_e64 v27, 0, v27, s[4:5]
	v_cndmask_b32_e64 v26, 1.0, v26, s[4:5]
	v_mul_f32_e32 v34, v21, v25
	v_mul_f32_e32 v21, v21, v24
	v_cndmask_b32_e64 v29, 0, v29, s[4:5]
	v_cndmask_b32_e64 v28, 1.0, v28, s[4:5]
	v_fma_f32 v34, v20, v24, -v34
	v_fmac_f32_e32 v21, v20, v25
	v_mul_f32_e32 v20, v23, v27
; #define PG8_BAR __builtin_amdgcn_s_barrier()
;     __device__ __forceinline__ void operator()(const f32x4 (&acc)[2][2][4][2], const Unit& u, int wr, int wc, int fr, int fq) const {
;     ...
;                 for (int bj = 0; bj < 2; ++bj) { f32x4 v0 = acc[ai][bj][m][0], v1 = acc[ai][bj][m][1];
;                     if (ACT == 3) { const float pos = (float)((row0 + ai * HALF + m * 16) & 2047); float c3[4], s3[4];
; #pragma unroll
;                         for (int p = 0; p < 4; ++p) { float r = pos * rinv3[bj][p]; r -= floorf(r); s3[p] = rope3[bj] ? __builtin_amdgcn_sinf(r) : 0.f; c3[p] = rope3[bj] ? __builtin_amdgcn_cosf(r) : 1.f; }
;                         const f32x4 a = v0, b = v1;
;                         v0[0] = a[0] * c3[0] - a[1] * s3[0]; v0[1] = a[1] * c3[0] + a[0] * s3[0]; v0[2] = a[2] * c3[1] - a[3] * s3[1]; v0[3] = a[3] * c3[1] + a[2] * s3[1];
;                         v1[0] = b[0] * c3[2] - b[1] * s3[2]; v1[1] = b[1] * c3[2] + b[0] * s3[2]; v1[2] = b[2] * c3[3] - b[3] * s3[3]; v1[3] = b[3] * c3[3] + b[2] * s3[3]; }
;                     if (ACT == 2) { const f32x4 a = v0, b = v1;
;                         v0[0] = a[0] * rc[0][0] - a[1] * rs[0][0]; v0[1] = a[1] * rc[0][0] + a[0] * rs[0][0]; v0[2] = a[2] * rc[0][1] - a[3] * rs[0][1]; v0[3] = a[3] * rc[0][1] + a[2] * rs[0][1];
;                         v1[0] = b[0] * rc[1][0] - b[1] * rs[1][0]; v1[1] = b[1] * rc[1][0] + b[0] * rs[1][0]; v1[2] = b[2] * rc[1][1] - b[3] * rs[1][1]; v1[3] = b[3] * rc[1][1] + b[2] * rs[1][1]; }
;                     if (ACT == 1) {
; #pragma unroll
;                         for (int j = 0; j < 4; ++j) { const float a = __int_as_float(max(__float_as_int(v0[j]), 0)), b = __int_as_float(max(__float_as_int(v1[j]), 0)); v0[j] = a * a; v1[j] = b * b; } }
;                     u32x4 w; w.x = cvt_pk_bf16(v0[0], v0[1]); w.y = cvt_pk_bf16(v0[2], v0[3]); w.z = cvt_pk_bf16(v1[0], v1[1]); w.w = cvt_pk_bf16(v1[2], v1[3]);
;                     *(u32x4*)(rowp + (ACT == 1 ? bj * 2 * 2 * 8192 : bj * HALF)) = w; } }
; template <class Epi, class Sched, bool ALIGN_EPI = false, bool SP2 = false, bool A_TILED = false>
; __device__ __forceinline__ void gemm_phase(PG8_LAS unsigned char* lds, const Gemm g, const Sched& S, const Epi& E, const int wave_s) {
;     ...
;         if (!has_next) break;
;         cur = nxt; cA = nA; cB = nB; ++ui;
;         if constexpr (ALIGN_EPI) { if (wr == 1) PG8_BAR; }
	v_mul_f32_e32 v23, v23, v26
	v_cndmask_b32_e64 v31, 0, v31, s[4:5]
	v_cndmask_b32_e64 v30, 1.0, v30, s[4:5]
	v_fma_f32 v20, v22, v26, -v20
	v_fmac_f32_e32 v23, v22, v27
	v_mul_f32_e32 v22, v17, v29
	v_mul_f32_e32 v24, v17, v28
	v_fma_f32 v22, v16, v28, -v22
	v_fmac_f32_e32 v24, v16, v29
	v_mul_f32_e32 v16, v19, v31
	v_mul_f32_e32 v19, v19, v30
	v_fma_f32 v25, v18, v30, -v16
	v_fmac_f32_e32 v19, v18, v31
	v_cvt_pk_bf16_f32 v16, v34, v21
	v_cvt_pk_bf16_f32 v17, v20, v23
	v_cvt_pk_bf16_f32 v18, v22, v24
	v_cvt_pk_bf16_f32 v19, v25, v19
	global_store_dwordx4 v[32:33], v[16:19], off offset:256
	s_nop 1
	v_add_u32_e32 v16, 0xb0, v162
	v_and_b32_e32 v17, 0x7ff, v16
	v_cvt_f32_u32_e32 v18, v17
	v_mad_i64_i32 v[16:17], s[44:45], v16, s57, v[144:145]
	v_lshl_add_u64 v[16:17], v[16:17], 0, v[146:147]
	v_mul_f32_e32 v19, v154, v18
	v_floor_f32_e32 v19, v19
	v_mul_f32_e32 v21, v156, v18
	v_fma_f32 v19, v154, v18, -v19
	v_floor_f32_e32 v21, v21
	v_mul_f32_e32 v23, v158, v18
	v_sin_f32_e32 v20, v19
	v_cos_f32_e32 v19, v19
	v_fma_f32 v21, v156, v18, -v21
	v_floor_f32_e32 v23, v23
	v_mul_f32_e32 v25, v161, v18
	v_sin_f32_e32 v22, v21
	v_cos_f32_e32 v21, v21
	v_fma_f32 v23, v158, v18, -v23
	v_floor_f32_e32 v25, v25
	v_sin_f32_e32 v24, v23
	v_cos_f32_e32 v23, v23
	v_fma_f32 v25, v161, v18, -v25
	v_sin_f32_e32 v26, v25
	v_cos_f32_e32 v25, v25
	v_cndmask_b32_e32 v20, 0, v20, vcc
	v_cndmask_b32_e32 v19, 1.0, v19, vcc
	v_cndmask_b32_e32 v22, 0, v22, vcc
	v_cndmask_b32_e32 v21, 1.0, v21, vcc
	v_mul_f32_e32 v27, v13, v20
	v_mul_f32_e32 v13, v13, v19
	v_cndmask_b32_e32 v24, 0, v24, vcc
	v_cndmask_b32_e32 v23, 1.0, v23, vcc
	v_fma_f32 v27, v12, v19, -v27
	v_fmac_f32_e32 v13, v12, v20
	v_mul_f32_e32 v12, v15, v22
	v_mul_f32_e32 v15, v15, v21
	v_cndmask_b32_e32 v26, 0, v26, vcc
	v_cndmask_b32_e32 v25, 1.0, v25, vcc
	v_fma_f32 v12, v14, v21, -v12
	v_fmac_f32_e32 v15, v14, v22
	v_mul_f32_e32 v14, v9, v24
	v_mul_f32_e32 v19, v9, v23
	v_fma_f32 v14, v8, v23, -v14
	v_fmac_f32_e32 v19, v8, v24
	v_mul_f32_e32 v8, v11, v26
	v_mul_f32_e32 v11, v11, v25
	v_fma_f32 v20, v10, v25, -v8
	v_fmac_f32_e32 v11, v10, v26
	v_cvt_pk_bf16_f32 v8, v27, v13
	v_cvt_pk_bf16_f32 v9, v12, v15
	v_cvt_pk_bf16_f32 v10, v14, v19
	v_cvt_pk_bf16_f32 v11, v20, v11
	global_store_dwordx4 v[16:17], v[8:11], off
	v_mul_f32_e32 v12, v160, v18
	v_floor_f32_e32 v12, v12
	v_mul_f32_e32 v8, v155, v18
	v_floor_f32_e32 v8, v8
	v_mul_f32_e32 v10, v157, v18
	v_fma_f32 v8, v155, v18, -v8
	v_floor_f32_e32 v10, v10
	v_sin_f32_e32 v9, v8
	v_cos_f32_e32 v8, v8
	v_fma_f32 v10, v157, v18, -v10
	v_mul_f32_e32 v14, v159, v18
	v_sin_f32_e32 v11, v10
	v_cos_f32_e32 v10, v10
	v_fma_f32 v12, v160, v18, -v12
	v_floor_f32_e32 v14, v14
	v_sin_f32_e32 v13, v12
	v_cos_f32_e32 v12, v12
	v_fma_f32 v14, v159, v18, -v14
	v_sin_f32_e32 v15, v14
	v_cos_f32_e32 v14, v14
	v_cndmask_b32_e64 v9, 0, v9, s[4:5]
	v_cndmask_b32_e64 v8, 1.0, v8, s[4:5]
	v_cndmask_b32_e64 v11, 0, v11, s[4:5]
	v_cndmask_b32_e64 v10, 1.0, v10, s[4:5]
	v_mul_f32_e32 v18, v5, v9
	v_mul_f32_e32 v5, v5, v8
	v_cndmask_b32_e64 v13, 0, v13, s[4:5]
	v_cndmask_b32_e64 v12, 1.0, v12, s[4:5]
	v_fma_f32 v18, v4, v8, -v18
	v_fmac_f32_e32 v5, v4, v9
	v_mul_f32_e32 v4, v7, v11
	v_mul_f32_e32 v7, v7, v10
	v_cndmask_b32_e64 v15, 0, v15, s[4:5]
	v_cndmask_b32_e64 v14, 1.0, v14, s[4:5]
	v_fma_f32 v4, v6, v10, -v4
	v_fmac_f32_e32 v7, v6, v11
	v_mul_f32_e32 v6, v1, v13
	v_mul_f32_e32 v8, v1, v12
	v_fma_f32 v6, v0, v12, -v6
	v_fmac_f32_e32 v8, v0, v13
	v_mul_f32_e32 v0, v3, v15
	v_mul_f32_e32 v3, v3, v14
	v_fmac_f32_e32 v3, v2, v15
	s_andn2_b64 vcc, exec, s[2:3]
	s_mov_b64 s[2:3], -1
	v_fma_f32 v9, v2, v14, -v0
	v_cvt_pk_bf16_f32 v0, v18, v5
	v_cvt_pk_bf16_f32 v1, v4, v7
	v_cvt_pk_bf16_f32 v2, v6, v8
	v_cvt_pk_bf16_f32 v3, v9, v3
	global_store_dwordx4 v[16:17], v[0:3], off offset:256
	s_cbranch_vccnz .LBB0_2542
	s_andn2_b64 vcc, exec, s[46:47]
	s_cbranch_vccnz .LBB0_2541
	s_barrier
	s_branch .LBB0_2541

;     __device__ __forceinline__ void operator()(const f32x4 (&acc)[2][2][4][2], const Unit& u, int wr, int wc, int fr, int fq) const {
;     ...
; #pragma unroll
;         for (int ai = 0; ai < 2; ++ai)
; #pragma unroll
;             for (int m = 0; m < 4; ++m) { bf16_t* rowp = O + (size_t)(row0 + ai * HALF + m * 16) * ldc + col0;
;                 if (ACT == 1) {
;                     const int ob = fr * 64 + 16 * fq, sw = ob ^ (((ob >> 9) & 1) << 5);
;                     rowp = O + ((size_t)(u.pm * (ldc / 64) + u.pn * 4 + (wc >> 1)) * 2 + ai) * 8192 + (((wr * 4 + m) * 2 + (wc & 1)) * 1024 + sw) / 2; }
;                 float rc[2][2], rs[2][2];
;                 if (ACT == 2) { const float pos = (float)((row0 + ai * HALF + m * 16) & 2047);
; #pragma unroll
;                     for (int n = 0; n < 2; ++n)
; #pragma unroll
;                         for (int e = 0; e < 2; ++e) { float r = pos * rinv[n][e]; r -= floorf(r); rs[n][e] = do_rope ? __builtin_amdgcn_sinf(r) : 0.f; rc[n][e] = do_rope ? __builtin_amdgcn_cosf(r) : 1.f; } }
; #pragma unroll
;                 for (int bj = 0; bj < 2; ++bj) { f32x4 v0 = acc[ai][bj][m][0], v1 = acc[ai][bj][m][1];
;                     if (ACT == 3) { const float pos = (float)((row0 + ai * HALF + m * 16) & 2047); float c3[4], s3[4];
; #pragma unroll
;                         for (int p = 0; p < 4; ++p) { float r = pos * rinv3[bj][p]; r -= floorf(r); s3[p] = rope3[bj] ? __builtin_amdgcn_sinf(r) : 0.f; c3[p] = rope3[bj] ? __builtin_amdgcn_cosf(r) : 1.f; }
;                         const f32x4 a = v0, b = v1;
;                         v0[0] = a[0] * c3[0] - a[1] * s3[0]; v0[1] = a[1] * c3[0] + a[0] * s3[0]; v0[2] = a[2] * c3[1] - a[3] * s3[1]; v0[3] = a[3] * c3[1] + a[2] * s3[1];
;                         v1[0] = b[0] * c3[2] - b[1] * s3[2]; v1[1] = b[1] * c3[2] + b[0] * s3[2]; v1[2] = b[2] * c3[3] - b[3] * s3[3]; v1[3] = b[3] * c3[3] + b[2] * s3[3]; }
;                     if (ACT == 2) { const f32x4 a = v0, b = v1;
;                         v0[0] = a[0] * rc[0][0] - a[1] * rs[0][0]; v0[1] = a[1] * rc[0][0] + a[0] * rs[0][0]; v0[2] = a[2] * rc[0][1] - a[3] * rs[0][1]; v0[3] = a[3] * rc[0][1] + a[2] * rs[0][1];
;                         v1[0] = b[0] * rc[1][0] - b[1] * rs[1][0]; v1[1] = b[1] * rc[1][0] + b[0] * rs[1][0]; v1[2] = b[2] * rc[1][1] - b[3] * rs[1][1]; v1[3] = b[3] * rc[1][1] + b[2] * rs[1][1]; }
.LBB0_2569:
	v_mov_b32_e32 v140, 0
	s_lshl_b32 s51, s70, 8
	v_mbcnt_lo_u32_b32 v140, -1, v140
	v_mbcnt_hi_u32_b32 v140, -1, v140
	v_or_b32_e32 v141, s33, v140
	s_add_i32 s51, s51, s40
	v_and_or_b32 v140, v141, 15, s51
	s_lshl_b32 s50, s50, 8
	v_lshrrev_b32_e32 v141, 1, v141
	v_and_or_b32 v141, v141, 24, s50
	v_or_b32_e32 v142, s41, v141
	v_ashrrev_i32_e32 v141, 31, v140
	v_ashrrev_i32_e32 v143, 31, v142
	v_lshlrev_b64 v[144:145], 13, v[140:141]
	v_lshl_add_u64 v[144:145], s[12:13], 0, v[144:145]
	v_lshlrev_b64 v[142:143], 1, v[142:143]
	v_lshl_add_u64 v[144:145], v[144:145], 0, v[142:143]
	v_cvt_pk_bf16_f32 v120, v120, v121
	v_cvt_pk_bf16_f32 v121, v122, v123
	v_cvt_pk_bf16_f32 v122, v112, v113
	v_cvt_pk_bf16_f32 v123, v114, v115
	global_store_dwordx4 v[144:145], v[120:123], off
	v_cvt_pk_bf16_f32 v112, v124, v125
	v_cvt_pk_bf16_f32 v113, v126, v127
	v_cvt_pk_bf16_f32 v114, v116, v117
	v_cvt_pk_bf16_f32 v115, v118, v119
	global_store_dwordx4 v[144:145], v[112:115], off offset:256
	v_cvt_pk_bf16_f32 v104, v104, v105
	v_cvt_pk_bf16_f32 v105, v106, v107
	v_cvt_pk_bf16_f32 v106, v96, v97
	v_cvt_pk_bf16_f32 v107, v98, v99
	s_mov_b64 s[50:51], 0x100000
	s_nop 0
	v_or_b32_e32 v112, 16, v140
	v_ashrrev_i32_e32 v113, 31, v112
	v_lshlrev_b64 v[112:113], 13, v[112:113]
	v_lshl_add_u64 v[112:113], s[12:13], 0, v[112:113]
	v_lshl_add_u64 v[112:113], v[112:113], 0, v[142:143]
	global_store_dwordx4 v[112:113], v[104:107], off
	v_cvt_pk_bf16_f32 v96, v108, v109
	v_cvt_pk_bf16_f32 v97, v110, v111
	v_cvt_pk_bf16_f32 v98, v100, v101
	v_cvt_pk_bf16_f32 v99, v102, v103
	global_store_dwordx4 v[112:113], v[96:99], off offset:256
	v_cvt_pk_bf16_f32 v88, v88, v89
	v_cvt_pk_bf16_f32 v89, v90, v91
	v_cvt_pk_bf16_f32 v90, v80, v81
	v_cvt_pk_bf16_f32 v91, v82, v83
	s_nop 1
	v_or_b32_e32 v96, 32, v140
	v_ashrrev_i32_e32 v97, 31, v96
	v_lshlrev_b64 v[96:97], 13, v[96:97]
	v_lshl_add_u64 v[96:97], s[12:13], 0, v[96:97]
	v_lshl_add_u64 v[96:97], v[96:97], 0, v[142:143]
	global_store_dwordx4 v[96:97], v[88:91], off
	v_cvt_pk_bf16_f32 v80, v92, v93
	v_cvt_pk_bf16_f32 v81, v94, v95
	v_cvt_pk_bf16_f32 v82, v84, v85
	v_cvt_pk_bf16_f32 v83, v86, v87
	global_store_dwordx4 v[96:97], v[80:83], off offset:256
	v_cvt_pk_bf16_f32 v56, v56, v57
	v_cvt_pk_bf16_f32 v57, v58, v59
	v_cvt_pk_bf16_f32 v58, v48, v49
	v_cvt_pk_bf16_f32 v59, v50, v51
	s_nop 1
	v_or_b32_e32 v80, 48, v140
	v_ashrrev_i32_e32 v81, 31, v80
	v_lshlrev_b64 v[80:81], 13, v[80:81]
	v_lshl_add_u64 v[80:81], s[12:13], 0, v[80:81]
	v_lshl_add_u64 v[80:81], v[80:81], 0, v[142:143]
	global_store_dwordx4 v[80:81], v[56:59], off
	v_cvt_pk_bf16_f32 v48, v60, v61
	v_cvt_pk_bf16_f32 v49, v62, v63
	v_cvt_pk_bf16_f32 v50, v52, v53
	v_lshl_add_u64 v[52:53], v[144:145], 0, s[50:51]
	s_mov_b32 s50, 0x100000
	v_cvt_pk_bf16_f32 v51, v54, v55
	v_add_co_u32_e32 v54, vcc, s50, v144
	global_store_dwordx4 v[80:81], v[48:51], off offset:256
	s_nop 0
	v_addc_co_u32_e32 v55, vcc, 0, v145, vcc
	v_cvt_pk_bf16_f32 v48, v76, v77
	v_cvt_pk_bf16_f32 v49, v78, v79
	v_cvt_pk_bf16_f32 v50, v72, v73
	v_cvt_pk_bf16_f32 v51, v74, v75
	global_store_dwordx4 v[54:55], v[48:51], off
	s_mov_b64 s[50:51], 0x120000
	s_nop 0
	v_cvt_pk_bf16_f32 v48, v68, v69
	v_cvt_pk_bf16_f32 v49, v70, v71
	v_cvt_pk_bf16_f32 v50, v64, v65
	v_cvt_pk_bf16_f32 v51, v66, v67
	global_store_dwordx4 v[52:53], v[48:51], off offset:256
	v_cvt_pk_bf16_f32 v44, v44, v45
	v_cvt_pk_bf16_f32 v45, v46, v47
	v_cvt_pk_bf16_f32 v46, v40, v41
	v_cvt_pk_bf16_f32 v47, v42, v43
	s_nop 1
	v_lshl_add_u64 v[48:49], v[144:145], 0, s[50:51]
	s_mov_b32 s50, 0x120000
	v_add_co_u32_e32 v40, vcc, s50, v144
	s_mov_b64 s[50:51], 0x140000
	s_nop 0
	v_addc_co_u32_e32 v41, vcc, 0, v145, vcc
	global_store_dwordx4 v[40:41], v[44:47], off
	v_cvt_pk_bf16_f32 v36, v36, v37
	v_cvt_pk_bf16_f32 v37, v38, v39
	v_cvt_pk_bf16_f32 v38, v32, v33
	v_lshl_add_u64 v[32:33], v[144:145], 0, s[50:51]
	s_mov_b32 s50, 0x140000
	v_cvt_pk_bf16_f32 v39, v34, v35
	global_store_dwordx4 v[48:49], v[36:39], off offset:256
	v_cvt_pk_bf16_f32 v28, v28, v29
	v_cvt_pk_bf16_f32 v29, v30, v31
	v_cvt_pk_bf16_f32 v30, v24, v25
	v_add_co_u32_e32 v24, vcc, s50, v144
	s_mov_b64 s[50:51], 0x160000
	s_nop 0
	v_addc_co_u32_e32 v25, vcc, 0, v145, vcc
	v_cvt_pk_bf16_f32 v31, v26, v27
	global_store_dwordx4 v[24:25], v[28:31], off
	v_cvt_pk_bf16_f32 v20, v20, v21
	v_cvt_pk_bf16_f32 v21, v22, v23
	v_cvt_pk_bf16_f32 v22, v16, v17
	v_lshl_add_u64 v[16:17], v[144:145], 0, s[50:51]
	s_mov_b32 s50, 0x160000
	v_cvt_pk_bf16_f32 v23, v18, v19
	global_store_dwordx4 v[32:33], v[20:23], off offset:256
	v_cvt_pk_bf16_f32 v12, v12, v13
	v_cvt_pk_bf16_f32 v13, v14, v15
	v_cvt_pk_bf16_f32 v14, v8, v9
	v_add_co_u32_e32 v8, vcc, s50, v144
	v_cvt_pk_bf16_f32 v15, v10, v11
	s_nop 1
	v_addc_co_u32_e32 v9, vcc, 0, v145, vcc
	s_andn2_b64 vcc, exec, s[2:3]
	s_mov_b64 s[2:3], -1
	global_store_dwordx4 v[8:9], v[12:15], off
	v_cvt_pk_bf16_f32 v4, v4, v5
	v_cvt_pk_bf16_f32 v5, v6, v7
	v_cvt_pk_bf16_f32 v6, v0, v1
	v_cvt_pk_bf16_f32 v7, v2, v3
	global_store_dwordx4 v[16:17], v[4:7], off offset:256
	s_cbranch_vccnz .LBB0_2558
	s_andn2_b64 vcc, exec, s[4:5]
	s_cbranch_vccnz .LBB0_2557
	s_barrier
	s_branch .LBB0_2557

;     __device__ __forceinline__ void fused(f32x4 (&acc)[2][2][4][2], const Unit& un, int wr, int wc, int fr, int fq, PG8_LAS unsigned char* lds, int wid, int lane) const {
;     ...
;         const int row0 = un.pm * BM + wr * 64 + fr, col0 = un.pn * BM + wc * 32 + 8 * fq;
;         const size_t boff = (size_t)(un.pm >> 3) * bstride + col0;
;         { f32x4 gv[2][2];
; #pragma unroll
;           for (int bj = 0; bj < 2; ++bj)
; #pragma unroll
;               for (int n = 0; n < 2; ++n) gv[bj][n] = *(const f32x4*)(gate + boff + bj * HALF + n * 4);
; #pragma unroll
;           for (int ai = 0; ai < 2; ++ai)
; #pragma unroll
;               for (int m = 0; m < 4; ++m) { const size_t off = (size_t)(row0 + ai * HALF + m * 16) * ldc + col0;
; #pragma unroll
;                   for (int bj = 0; bj < 2; ++bj) {
; #pragma unroll
;                       for (int n = 0; n < 2; ++n) { f32x4 bs;
;                           if (BASE_F32) bs = *(const f32x4*)((const float*)base + off + bj * HALF + n * 4);
;                           else { const u32x2v hw = *(const u32x2v*)((const bf16_t*)base + off + bj * HALF + n * 4);
;                                  bs = (f32x4){__uint_as_float(hw.x << 16), __uint_as_float(hw.x & 0xffff0000u), __uint_as_float(hw.y << 16), __uint_as_float(hw.y & 0xffff0000u)}; }
;                           acc[ai][bj][m][n] = bs + gv[bj][n] * acc[ai][bj][m][n]; }
;                       if (out_h) { const f32x4 a0 = acc[ai][bj][m][0], a1 = acc[ai][bj][m][1]; u32x4 w; w.x = cvt_pk_bf16(a0[0], a0[1]); w.y = cvt_pk_bf16(a0[2], a0[3]); w.z = cvt_pk_bf16(a1[0], a1[1]); w.w = cvt_pk_bf16(a1[2], a1[3]);
;                           *(u32x4*)(out_h + off + bj * HALF) = w; } }
;                   asm volatile("" : "+v"(acc[ai][0][m][0]), "+v"(acc[ai][0][m][1]), "+v"(acc[ai][1][m][0]), "+v"(acc[ai][1][m][1]));
;                   asm volatile("" ::: "memory"); } }
; #pragma unroll
;         for (int ai = 0; ai < 2; ++ai)
; #pragma unroll
;             for (int m = 0; m < 4; ++m) { float s = 0.f;
; #pragma unroll
;                 for (int bj = 0; bj < 2; ++bj)
; #pragma unroll
;                     for (int n = 0; n < 2; ++n) { const f32x4 x = acc[ai][bj][m][n]; s += (x[0] * x[0] + x[1] * x[1]) + (x[2] * x[2] + x[3] * x[3]); }
;                 s += __shfl_xor(s, 16); s += __shfl_xor(s, 32);
.LBB0_2732:
	v_mov_b32_e32 v32, 0
	s_barrier
	s_lshl_b32 s6, s9, 5
	v_mbcnt_lo_u32_b32 v32, -1, v32
	s_add_u32 s2, s44, 0x1a600000
	v_mbcnt_hi_u32_b32 v32, -1, v32
	s_addc_u32 s3, s45, 0
	v_or_b32_e32 v158, s33, v32
	s_lshl_b32 s7, s4, 8
	s_lshl_b32 s14, s46, 8
	s_or_b32 s6, s7, s6
	v_lshrrev_b32_e32 v32, 1, v158
	v_and_b32_e32 v159, 15, v158
	s_add_i32 s15, s14, s8
	v_and_or_b32 v152, v32, 24, s6
	s_ashr_i32 s6, s46, 3
	v_ashrrev_i32_e32 v153, 31, v152
	v_mov_b32_e32 v32, 0x3000
	v_or_b32_e32 v156, s15, v159
	v_mad_i64_i32 v[32:33], s[6:7], s6, v32, v[152:153]
	v_ashrrev_i32_e32 v157, 31, v156
	v_lshl_add_u64 v[150:151], v[32:33], 2, s[44:45]
	v_lshlrev_b64 v[32:33], 12, v[156:157]
	v_lshl_add_u64 v[32:33], s[2:3], 0, v[32:33]
	v_lshlrev_b64 v[148:149], 1, v[152:153]
	s_mov_b32 s15, 0x164000
	v_lshl_add_u64 v[154:155], v[32:33], 0, v[148:149]
	v_add_co_u32_e32 v132, vcc, s15, v150
	s_nop 0
	v_addc_co_u32_e32 v133, vcc, 0, v151, vcc
	s_mov_b64 s[6:7], 0x164000
	global_load_dwordx4 v[144:147], v[132:133], off
	v_lshl_add_u64 v[132:133], v[150:151], 0, s[6:7]
	global_load_dwordx4 v[140:143], v[132:133], off offset:16
	global_load_dwordx4 v[136:139], v[132:133], off offset:512
	s_nop 0
	global_load_dwordx4 v[132:135], v[132:133], off offset:528
	v_or_b32_e32 v164, 16, v156
	v_ashrrev_i32_e32 v165, 31, v164
	v_lshlrev_b64 v[164:165], 12, v[164:165]
	v_lshl_add_u64 v[164:165], s[2:3], 0, v[164:165]
	v_lshl_add_u64 v[164:165], v[164:165], 0, v[148:149]
	s_mov_b64 s[98:99], 0x10000
	s_mov_b64 s[100:101], 0x80000
	v_lshl_add_u64 v[232:233], v[154:155], 0, 0
	v_lshl_add_u64 v[234:235], v[232:233], 0, s[98:99]
	v_lshl_add_u64 v[236:237], v[234:235], 0, s[98:99]
	v_lshl_add_u64 v[238:239], v[236:237], 0, s[98:99]
	global_load_dwordx4 v[200:203], v[232:233], off
	global_load_dwordx4 v[204:207], v[232:233], off offset:256
	global_load_dwordx4 v[208:211], v[234:235], off
	global_load_dwordx4 v[212:215], v[234:235], off offset:256
	global_load_dwordx4 v[216:219], v[236:237], off
	global_load_dwordx4 v[220:223], v[236:237], off offset:256
	global_load_dwordx4 v[224:227], v[238:239], off
	global_load_dwordx4 v[228:231], v[238:239], off offset:256
	s_waitcnt vmcnt(0) lgkmcnt(0)
	v_lshlrev_b32_e32 v160, 16, v200
	v_and_b32_e32 v161, 0xffff0000, v200
	v_lshlrev_b32_e32 v32, 16, v201
	v_and_b32_e32 v33, 0xffff0000, v201
	v_lshlrev_b32_e32 v162, 16, v202
	v_and_b32_e32 v163, 0xffff0000, v202
	v_lshlrev_b32_e32 v34, 16, v203
	v_and_b32_e32 v35, 0xffff0000, v203
	v_pk_fma_f32 v[10:11], v[10:11], v[146:147], v[32:33]
	v_pk_fma_f32 v[8:9], v[8:9], v[144:145], v[160:161]
	v_pk_fma_f32 v[14:15], v[14:15], v[142:143], v[34:35]
	v_pk_fma_f32 v[12:13], v[12:13], v[140:141], v[162:163]
	v_cvt_pk_bf16_f32 v32, v8, v9
	v_cvt_pk_bf16_f32 v33, v10, v11
	s_nop 0
	v_cvt_pk_bf16_f32 v34, v12, v13
	v_cvt_pk_bf16_f32 v35, v14, v15
	s_nop 0
	global_store_dwordx4 v[154:155], v[32:35], off
	s_nop 1
	s_nop 0
	v_lshlrev_b32_e32 v32, 16, v204
	v_and_b32_e32 v33, 0xffff0000, v204
	v_lshlrev_b32_e32 v34, 16, v205
	v_and_b32_e32 v35, 0xffff0000, v205
	v_lshlrev_b32_e32 v160, 16, v206
	v_and_b32_e32 v161, 0xffff0000, v206
	v_lshlrev_b32_e32 v162, 16, v207
	v_and_b32_e32 v163, 0xffff0000, v207
	v_pk_fma_f32 v[34:35], v[26:27], v[138:139], v[34:35]
	v_pk_fma_f32 v[32:33], v[24:25], v[136:137], v[32:33]
	v_pk_fma_f32 v[26:27], v[18:19], v[134:135], v[162:163]
	v_pk_fma_f32 v[24:25], v[16:17], v[132:133], v[160:161]
	v_cvt_pk_bf16_f32 v16, v32, v33
	v_cvt_pk_bf16_f32 v17, v34, v35
	s_nop 0
	v_cvt_pk_bf16_f32 v18, v24, v25
	v_cvt_pk_bf16_f32 v19, v26, v27
	global_store_dwordx4 v[154:155], v[16:19], off offset:256
	s_nop 1
	v_lshlrev_b32_e32 v160, 16, v208
	v_and_b32_e32 v161, 0xffff0000, v208
	v_lshlrev_b32_e32 v16, 16, v209
	v_and_b32_e32 v17, 0xffff0000, v209
	v_lshlrev_b32_e32 v162, 16, v210
	v_and_b32_e32 v163, 0xffff0000, v210
	v_lshlrev_b32_e32 v166, 16, v211
	v_and_b32_e32 v167, 0xffff0000, v211
	v_pk_fma_f32 v[18:19], v[62:63], v[146:147], v[16:17]
	v_pk_fma_f32 v[16:17], v[60:61], v[144:145], v[160:161]
	v_pk_fma_f32 v[22:23], v[22:23], v[142:143], v[166:167]
	v_pk_fma_f32 v[20:21], v[20:21], v[140:141], v[162:163]
	v_cvt_pk_bf16_f32 v60, v16, v17
	v_cvt_pk_bf16_f32 v61, v18, v19
	v_or_b32_e32 v166, 32, v156
	v_cvt_pk_bf16_f32 v62, v20, v21
	v_cvt_pk_bf16_f32 v63, v22, v23
	v_ashrrev_i32_e32 v167, 31, v166
	v_lshlrev_b64 v[166:167], 12, v[166:167]
	global_store_dwordx4 v[164:165], v[60:63], off
	v_lshl_add_u64 v[166:167], s[2:3], 0, v[166:167]
	v_lshl_add_u64 v[166:167], v[166:167], 0, v[148:149]
	v_or_b32_e32 v156, 48, v156
	v_ashrrev_i32_e32 v157, 31, v156
	v_lshlrev_b64 v[156:157], 12, v[156:157]
	v_lshl_add_u64 v[156:157], s[2:3], 0, v[156:157]
	v_lshl_add_u64 v[156:157], v[156:157], 0, v[148:149]
	s_mov_b32 s2, 0x80000
	s_nop 1
	v_lshlrev_b32_e32 v60, 16, v212
	v_and_b32_e32 v61, 0xffff0000, v212
	v_lshlrev_b32_e32 v62, 16, v213
	v_and_b32_e32 v63, 0xffff0000, v213
	v_lshlrev_b32_e32 v160, 16, v214
	v_and_b32_e32 v161, 0xffff0000, v214
	v_lshlrev_b32_e32 v162, 16, v215
	v_and_b32_e32 v163, 0xffff0000, v215
	v_pk_fma_f32 v[62:63], v[58:59], v[138:139], v[62:63]
	v_pk_fma_f32 v[60:61], v[56:57], v[136:137], v[60:61]
	v_pk_fma_f32 v[58:59], v[50:51], v[134:135], v[162:163]
	v_pk_fma_f32 v[56:57], v[48:49], v[132:133], v[160:161]
	v_cvt_pk_bf16_f32 v48, v60, v61
	v_cvt_pk_bf16_f32 v49, v62, v63
	s_nop 0
	v_cvt_pk_bf16_f32 v50, v56, v57
	v_cvt_pk_bf16_f32 v51, v58, v59
	global_store_dwordx4 v[164:165], v[48:51], off offset:256
	s_nop 1
	v_lshlrev_b32_e32 v160, 16, v216
	v_and_b32_e32 v161, 0xffff0000, v216
	v_lshlrev_b32_e32 v48, 16, v217
	v_and_b32_e32 v49, 0xffff0000, v217
; __device__ __forceinline__ unsigned cvt_pk_bf16(float lo, float hi) { unsigned r; asm volatile("v_cvt_pk_bf16_f32 %0, %1, %2" : "=v"(r) : "v"(lo), "v"(hi)); return r; }
;     __device__ __forceinline__ void fused(f32x4 (&acc)[2][2][4][2], const Unit& un, int wr, int wc, int fr, int fq, PG8_LAS unsigned char* lds, int wid, int lane) const {
;     ...
;           for (int ai = 0; ai < 2; ++ai)
; #pragma unroll
;               for (int m = 0; m < 4; ++m) { const size_t off = (size_t)(row0 + ai * HALF + m * 16) * ldc + col0;
; #pragma unroll
;                   for (int bj = 0; bj < 2; ++bj) {
; #pragma unroll
;                       for (int n = 0; n < 2; ++n) { f32x4 bs;
;                           if (BASE_F32) bs = *(const f32x4*)((const float*)base + off + bj * HALF + n * 4);
;                           else { const u32x2v hw = *(const u32x2v*)((const bf16_t*)base + off + bj * HALF + n * 4);
;                                  bs = (f32x4){__uint_as_float(hw.x << 16), __uint_as_float(hw.x & 0xffff0000u), __uint_as_float(hw.y << 16), __uint_as_float(hw.y & 0xffff0000u)}; }
;                           acc[ai][bj][m][n] = bs + gv[bj][n] * acc[ai][bj][m][n]; }
;                       if (out_h) { const f32x4 a0 = acc[ai][bj][m][0], a1 = acc[ai][bj][m][1]; u32x4 w; w.x = cvt_pk_bf16(a0[0], a0[1]); w.y = cvt_pk_bf16(a0[2], a0[3]); w.z = cvt_pk_bf16(a1[0], a1[1]); w.w = cvt_pk_bf16(a1[2], a1[3]);
;                           *(u32x4*)(out_h + off + bj * HALF) = w; } }
;                   asm volatile("" : "+v"(acc[ai][0][m][0]), "+v"(acc[ai][0][m][1]), "+v"(acc[ai][1][m][0]), "+v"(acc[ai][1][m][1]));
;                   asm volatile("" ::: "memory"); } }
	v_lshlrev_b32_e32 v162, 16, v218
	v_and_b32_e32 v163, 0xffff0000, v218
	v_lshlrev_b32_e32 v164, 16, v219
	v_and_b32_e32 v165, 0xffff0000, v219
	v_pk_fma_f32 v[50:51], v[78:79], v[146:147], v[48:49]
	v_pk_fma_f32 v[48:49], v[76:77], v[144:145], v[160:161]
	v_pk_fma_f32 v[54:55], v[54:55], v[142:143], v[164:165]
	v_pk_fma_f32 v[52:53], v[52:53], v[140:141], v[162:163]
	v_cvt_pk_bf16_f32 v76, v48, v49
	v_cvt_pk_bf16_f32 v77, v50, v51
	s_nop 0
	v_cvt_pk_bf16_f32 v78, v52, v53
	v_cvt_pk_bf16_f32 v79, v54, v55
	s_nop 0
	global_store_dwordx4 v[166:167], v[76:79], off
	s_nop 1
	s_nop 0
	v_lshlrev_b32_e32 v76, 16, v220
	v_and_b32_e32 v77, 0xffff0000, v220
	v_lshlrev_b32_e32 v78, 16, v221
	v_and_b32_e32 v79, 0xffff0000, v221
	v_lshlrev_b32_e32 v160, 16, v222
	v_and_b32_e32 v161, 0xffff0000, v222
	v_lshlrev_b32_e32 v162, 16, v223
	v_and_b32_e32 v163, 0xffff0000, v223
	v_pk_fma_f32 v[78:79], v[74:75], v[138:139], v[78:79]
	v_pk_fma_f32 v[76:77], v[72:73], v[136:137], v[76:77]
	v_pk_fma_f32 v[74:75], v[66:67], v[134:135], v[162:163]
	v_pk_fma_f32 v[72:73], v[64:65], v[132:133], v[160:161]
	v_cvt_pk_bf16_f32 v64, v76, v77
	v_cvt_pk_bf16_f32 v65, v78, v79
	s_nop 0
	v_cvt_pk_bf16_f32 v66, v72, v73
	v_cvt_pk_bf16_f32 v67, v74, v75
	global_store_dwordx4 v[166:167], v[64:67], off offset:256
	s_nop 1
	v_lshlrev_b32_e32 v160, 16, v224
	v_and_b32_e32 v161, 0xffff0000, v224
	v_lshlrev_b32_e32 v64, 16, v225
	v_and_b32_e32 v65, 0xffff0000, v225
	v_lshlrev_b32_e32 v162, 16, v226
	v_and_b32_e32 v163, 0xffff0000, v226
	v_lshlrev_b32_e32 v164, 16, v227
	v_and_b32_e32 v165, 0xffff0000, v227
	v_pk_fma_f32 v[66:67], v[130:131], v[146:147], v[64:65]
	v_pk_fma_f32 v[64:65], v[128:129], v[144:145], v[160:161]
	v_pk_fma_f32 v[70:71], v[70:71], v[142:143], v[164:165]
	v_pk_fma_f32 v[68:69], v[68:69], v[140:141], v[162:163]
	v_cvt_pk_bf16_f32 v128, v64, v65
	v_cvt_pk_bf16_f32 v129, v66, v67
	v_add_co_u32_e32 v164, vcc, s2, v154
	v_cvt_pk_bf16_f32 v130, v68, v69
	v_cvt_pk_bf16_f32 v131, v70, v71
	s_nop 0
	v_addc_co_u32_e32 v165, vcc, 0, v155, vcc
	global_store_dwordx4 v[156:157], v[128:131], off
	s_mov_b64 s[2:3], 0x80000
	s_nop 1
	v_lshlrev_b32_e32 v128, 16, v228
	v_and_b32_e32 v129, 0xffff0000, v228
	v_lshlrev_b32_e32 v130, 16, v229
	v_and_b32_e32 v131, 0xffff0000, v229
	v_lshlrev_b32_e32 v160, 16, v230
	v_and_b32_e32 v161, 0xffff0000, v230
	v_lshlrev_b32_e32 v162, 16, v231
	v_and_b32_e32 v163, 0xffff0000, v231
	v_pk_fma_f32 v[110:111], v[110:111], v[138:139], v[130:131]
	v_pk_fma_f32 v[108:109], v[108:109], v[136:137], v[128:129]
	v_pk_fma_f32 v[98:99], v[98:99], v[134:135], v[162:163]
	v_pk_fma_f32 v[96:97], v[96:97], v[132:133], v[160:161]
	v_cvt_pk_bf16_f32 v128, v108, v109
	v_cvt_pk_bf16_f32 v129, v110, v111
	s_nop 0
	v_cvt_pk_bf16_f32 v130, v96, v97
	v_cvt_pk_bf16_f32 v131, v98, v99
	global_store_dwordx4 v[156:157], v[128:131], off offset:256
	v_lshl_add_u64 v[156:157], v[154:155], 0, s[2:3]
	s_mov_b32 s2, 0x90000
	v_add_co_u32_e32 v166, vcc, s2, v154
	s_mov_b64 s[2:3], 0x90000
	s_nop 0
	v_addc_co_u32_e32 v167, vcc, 0, v155, vcc
	v_lshl_add_u64 v[232:233], v[232:233], 0, s[100:101]
	v_lshl_add_u64 v[234:235], v[234:235], 0, s[100:101]
	v_lshl_add_u64 v[236:237], v[236:237], 0, s[100:101]
	v_lshl_add_u64 v[238:239], v[238:239], 0, s[100:101]
	global_load_dwordx4 v[200:203], v[232:233], off
	global_load_dwordx4 v[204:207], v[232:233], off offset:256
	global_load_dwordx4 v[208:211], v[234:235], off
	global_load_dwordx4 v[212:215], v[234:235], off offset:256
	global_load_dwordx4 v[216:219], v[236:237], off
	global_load_dwordx4 v[220:223], v[236:237], off offset:256
	global_load_dwordx4 v[224:227], v[238:239], off
	global_load_dwordx4 v[228:231], v[238:239], off offset:256
	s_waitcnt vmcnt(0) lgkmcnt(0)
	v_lshlrev_b32_e32 v160, 16, v200
	v_and_b32_e32 v161, 0xffff0000, v200
	v_lshlrev_b32_e32 v128, 16, v201
	v_and_b32_e32 v129, 0xffff0000, v201
	v_lshlrev_b32_e32 v162, 16, v202
	v_and_b32_e32 v163, 0xffff0000, v202
	v_lshlrev_b32_e32 v130, 16, v203
	v_and_b32_e32 v131, 0xffff0000, v203
	v_pk_fma_f32 v[102:103], v[102:103], v[146:147], v[128:129]
	v_pk_fma_f32 v[100:101], v[100:101], v[144:145], v[160:161]
	v_pk_fma_f32 v[106:107], v[106:107], v[142:143], v[130:131]
	v_pk_fma_f32 v[104:105], v[104:105], v[140:141], v[162:163]
	v_cvt_pk_bf16_f32 v128, v100, v101
	v_cvt_pk_bf16_f32 v129, v102, v103
	s_nop 0
	v_cvt_pk_bf16_f32 v130, v104, v105
	v_cvt_pk_bf16_f32 v131, v106, v107
	s_nop 0
	global_store_dwordx4 v[164:165], v[128:131], off
	s_nop 1
	s_nop 0
	v_lshlrev_b32_e32 v128, 16, v204
	v_and_b32_e32 v129, 0xffff0000, v204
	v_lshlrev_b32_e32 v130, 16, v205
	v_and_b32_e32 v131, 0xffff0000, v205
	v_lshlrev_b32_e32 v160, 16, v206
	v_and_b32_e32 v161, 0xffff0000, v206
	v_lshlrev_b32_e32 v162, 16, v207
	v_and_b32_e32 v163, 0xffff0000, v207
	v_pk_fma_f32 v[126:127], v[126:127], v[138:139], v[130:131]
	v_pk_fma_f32 v[124:125], v[124:125], v[136:137], v[128:129]
	v_pk_fma_f32 v[114:115], v[114:115], v[134:135], v[162:163]
	v_pk_fma_f32 v[112:113], v[112:113], v[132:133], v[160:161]
	v_cvt_pk_bf16_f32 v128, v124, v125
	v_cvt_pk_bf16_f32 v129, v126, v127
	s_nop 0
	v_cvt_pk_bf16_f32 v130, v112, v113
	v_cvt_pk_bf16_f32 v131, v114, v115
	global_store_dwordx4 v[156:157], v[128:131], off offset:256
	v_lshl_add_u64 v[156:157], v[154:155], 0, s[2:3]
	s_mov_b32 s2, 0xa0000
	v_add_co_u32_e32 v164, vcc, s2, v154
	s_mov_b64 s[2:3], 0xa0000
	s_nop 0
	v_addc_co_u32_e32 v165, vcc, 0, v155, vcc
	s_nop 1
	v_lshlrev_b32_e32 v160, 16, v208
	v_and_b32_e32 v161, 0xffff0000, v208
	v_lshlrev_b32_e32 v128, 16, v209
	v_and_b32_e32 v129, 0xffff0000, v209
	v_lshlrev_b32_e32 v162, 16, v210
; __device__ __forceinline__ unsigned cvt_pk_bf16(float lo, float hi) { unsigned r; asm volatile("v_cvt_pk_bf16_f32 %0, %1, %2" : "=v"(r) : "v"(lo), "v"(hi)); return r; }
;     __device__ __forceinline__ void fused(f32x4 (&acc)[2][2][4][2], const Unit& un, int wr, int wc, int fr, int fq, PG8_LAS unsigned char* lds, int wid, int lane) const {
;     ...
;           for (int ai = 0; ai < 2; ++ai)
; #pragma unroll
;               for (int m = 0; m < 4; ++m) { const size_t off = (size_t)(row0 + ai * HALF + m * 16) * ldc + col0;
; #pragma unroll
;                   for (int bj = 0; bj < 2; ++bj) {
; #pragma unroll
;                       for (int n = 0; n < 2; ++n) { f32x4 bs;
;                           if (BASE_F32) bs = *(const f32x4*)((const float*)base + off + bj * HALF + n * 4);
;                           else { const u32x2v hw = *(const u32x2v*)((const bf16_t*)base + off + bj * HALF + n * 4);
;                                  bs = (f32x4){__uint_as_float(hw.x << 16), __uint_as_float(hw.x & 0xffff0000u), __uint_as_float(hw.y << 16), __uint_as_float(hw.y & 0xffff0000u)}; }
;                           acc[ai][bj][m][n] = bs + gv[bj][n] * acc[ai][bj][m][n]; }
;                       if (out_h) { const f32x4 a0 = acc[ai][bj][m][0], a1 = acc[ai][bj][m][1]; u32x4 w; w.x = cvt_pk_bf16(a0[0], a0[1]); w.y = cvt_pk_bf16(a0[2], a0[3]); w.z = cvt_pk_bf16(a1[0], a1[1]); w.w = cvt_pk_bf16(a1[2], a1[3]);
;                           *(u32x4*)(out_h + off + bj * HALF) = w; } }
;                   asm volatile("" : "+v"(acc[ai][0][m][0]), "+v"(acc[ai][0][m][1]), "+v"(acc[ai][1][m][0]), "+v"(acc[ai][1][m][1]));
;                   asm volatile("" ::: "memory"); } }
; #pragma unroll
;         for (int ai = 0; ai < 2; ++ai)
; #pragma unroll
;             for (int m = 0; m < 4; ++m) { float s = 0.f;
; #pragma unroll
;                 for (int bj = 0; bj < 2; ++bj)
; #pragma unroll
;                     for (int n = 0; n < 2; ++n) { const f32x4 x = acc[ai][bj][m][n]; s += (x[0] * x[0] + x[1] * x[1]) + (x[2] * x[2] + x[3] * x[3]); }
;                 s += __shfl_xor(s, 16); s += __shfl_xor(s, 32);
;                 if (fq == 0) P[(ai * HALF + wr * 64 + m * 16 + fr) * 4 + wc] = s; }
	v_and_b32_e32 v163, 0xffff0000, v210
	v_lshlrev_b32_e32 v130, 16, v211
	v_and_b32_e32 v131, 0xffff0000, v211
	v_pk_fma_f32 v[118:119], v[118:119], v[146:147], v[128:129]
	v_pk_fma_f32 v[116:117], v[116:117], v[144:145], v[160:161]
	v_pk_fma_f32 v[122:123], v[122:123], v[142:143], v[130:131]
	v_pk_fma_f32 v[120:121], v[120:121], v[140:141], v[162:163]
	v_cvt_pk_bf16_f32 v128, v116, v117
	v_cvt_pk_bf16_f32 v129, v118, v119
	s_nop 0
	v_cvt_pk_bf16_f32 v130, v120, v121
	v_cvt_pk_bf16_f32 v131, v122, v123
	s_nop 0
	global_store_dwordx4 v[166:167], v[128:131], off
	s_nop 1
	s_nop 0
	v_lshlrev_b32_e32 v128, 16, v212
	v_and_b32_e32 v129, 0xffff0000, v212
	v_lshlrev_b32_e32 v130, 16, v213
	v_and_b32_e32 v131, 0xffff0000, v213
	v_lshlrev_b32_e32 v160, 16, v214
	v_and_b32_e32 v161, 0xffff0000, v214
	v_lshlrev_b32_e32 v162, 16, v215
	v_and_b32_e32 v163, 0xffff0000, v215
	v_pk_fma_f32 v[94:95], v[94:95], v[138:139], v[130:131]
	v_pk_fma_f32 v[92:93], v[92:93], v[136:137], v[128:129]
	v_pk_fma_f32 v[90:91], v[90:91], v[134:135], v[162:163]
	v_pk_fma_f32 v[88:89], v[88:89], v[132:133], v[160:161]
	v_cvt_pk_bf16_f32 v128, v92, v93
	v_cvt_pk_bf16_f32 v129, v94, v95
	s_nop 0
	v_cvt_pk_bf16_f32 v130, v88, v89
	v_cvt_pk_bf16_f32 v131, v90, v91
	global_store_dwordx4 v[156:157], v[128:131], off offset:256
	v_lshl_add_u64 v[156:157], v[154:155], 0, s[2:3]
	s_mov_b32 s2, 0xb0000
	v_add_co_u32_e32 v166, vcc, s2, v154
	s_mov_b64 s[2:3], 0xb0000
	s_nop 0
	v_addc_co_u32_e32 v167, vcc, 0, v155, vcc
	s_nop 1
	v_lshlrev_b32_e32 v160, 16, v216
	v_and_b32_e32 v161, 0xffff0000, v216
	v_lshlrev_b32_e32 v128, 16, v217
	v_and_b32_e32 v129, 0xffff0000, v217
	v_lshlrev_b32_e32 v162, 16, v218
	v_and_b32_e32 v163, 0xffff0000, v218
	v_lshlrev_b32_e32 v130, 16, v219
	v_and_b32_e32 v131, 0xffff0000, v219
	v_pk_fma_f32 v[86:87], v[86:87], v[146:147], v[128:129]
	v_pk_fma_f32 v[84:85], v[84:85], v[144:145], v[160:161]
	v_pk_fma_f32 v[82:83], v[82:83], v[142:143], v[130:131]
	v_pk_fma_f32 v[80:81], v[80:81], v[140:141], v[162:163]
	v_cvt_pk_bf16_f32 v128, v84, v85
	v_cvt_pk_bf16_f32 v129, v86, v87
	s_nop 0
	v_cvt_pk_bf16_f32 v130, v80, v81
	v_cvt_pk_bf16_f32 v131, v82, v83
	s_nop 0
	global_store_dwordx4 v[164:165], v[128:131], off
	v_mul_f32_e32 v164, v25, v25
	v_mul_f32_e32 v165, v27, v27
	v_fmac_f32_e32 v164, v24, v24
	v_fmac_f32_e32 v165, v26, v26
	s_nop 1
	v_lshlrev_b32_e32 v128, 16, v220
	v_and_b32_e32 v129, 0xffff0000, v220
	v_lshlrev_b32_e32 v130, 16, v221
	v_and_b32_e32 v131, 0xffff0000, v221
	v_lshlrev_b32_e32 v160, 16, v222
	v_and_b32_e32 v161, 0xffff0000, v222
	v_lshlrev_b32_e32 v162, 16, v223
	v_and_b32_e32 v163, 0xffff0000, v223
	v_pk_fma_f32 v[46:47], v[46:47], v[138:139], v[130:131]
	v_pk_fma_f32 v[44:45], v[44:45], v[136:137], v[128:129]
	v_pk_fma_f32 v[42:43], v[42:43], v[134:135], v[162:163]
	v_pk_fma_f32 v[40:41], v[40:41], v[132:133], v[160:161]
	v_cvt_pk_bf16_f32 v128, v44, v45
	v_cvt_pk_bf16_f32 v129, v46, v47
	v_lshl_add_u64 v[160:161], v[154:155], 0, s[2:3]
	v_cvt_pk_bf16_f32 v130, v40, v41
	v_cvt_pk_bf16_f32 v131, v42, v43
	global_store_dwordx4 v[156:157], v[128:131], off offset:256
	v_mul_f32_e32 v162, v33, v33
	v_mul_f32_e32 v163, v35, v35
	v_fmac_f32_e32 v162, v32, v32
	v_fmac_f32_e32 v163, v34, v34
	s_lshl_b32 s2, s9, 2
	s_add_i32 s2, s2, 0
	s_nop 1
	v_lshlrev_b32_e32 v154, 16, v224
	v_and_b32_e32 v155, 0xffff0000, v224
	v_lshlrev_b32_e32 v128, 16, v225
	v_and_b32_e32 v129, 0xffff0000, v225
	v_lshlrev_b32_e32 v156, 16, v226
	v_and_b32_e32 v157, 0xffff0000, v226
	v_lshlrev_b32_e32 v130, 16, v227
	v_and_b32_e32 v131, 0xffff0000, v227
	v_pk_fma_f32 v[38:39], v[38:39], v[146:147], v[128:129]
	v_pk_fma_f32 v[36:37], v[36:37], v[144:145], v[154:155]
	v_pk_fma_f32 v[30:31], v[30:31], v[142:143], v[130:131]
	v_pk_fma_f32 v[28:29], v[28:29], v[140:141], v[156:157]
	v_cvt_pk_bf16_f32 v142, v36, v37
	v_cvt_pk_bf16_f32 v143, v38, v39
	v_mbcnt_lo_u32_b32 v128, -1, 0
	v_cvt_pk_bf16_f32 v144, v28, v29
	v_cvt_pk_bf16_f32 v145, v30, v31
	v_mbcnt_hi_u32_b32 v129, -1, v128
	v_mul_f32_e32 v140, v9, v9
	v_mul_f32_e32 v141, v11, v11
	v_mul_f32_e32 v146, v13, v13
	v_mul_f32_e32 v147, v15, v15
	v_and_b32_e32 v130, 64, v129
	v_fmac_f32_e32 v140, v8, v8
	v_fmac_f32_e32 v141, v10, v10
	v_fmac_f32_e32 v146, v12, v12
	v_fmac_f32_e32 v147, v14, v14
	v_xor_b32_e32 v128, 16, v129
	v_add_u32_e32 v130, 64, v130
	v_add_f32_e32 v140, v140, v141
	v_add_f32_e32 v141, v146, v147
	v_cmp_lt_i32_e32 vcc, v128, v130
	v_add_f32_e32 v146, v162, v163
	v_add_f32_e32 v140, v140, v141
	v_cndmask_b32_e32 v128, v129, v128, vcc
	v_add_f32_e32 v147, v164, v165
	v_add_f32_e32 v140, v146, v140
	v_lshlrev_b32_e32 v128, 2, v128
	v_add_f32_e32 v140, v147, v140
	ds_bpermute_b32 v141, v128, v140
	v_xor_b32_e32 v131, 32, v129
	v_cmp_lt_i32_e32 vcc, v131, v130
	global_store_dwordx4 v[166:167], v[142:145], off
	v_and_b32_e32 v130, 63, v158
	v_cndmask_b32_e32 v129, v129, v131, vcc
	v_lshlrev_b32_e32 v129, 2, v129
	s_waitcnt lgkmcnt(0)
	v_add_f32_e32 v140, v140, v141
	ds_bpermute_b32 v141, v129, v140
	v_cmp_gt_u32_e32 vcc, 16, v130
	s_waitcnt vmcnt(0)
	v_lshlrev_b32_e32 v142, 16, v228
	v_and_b32_e32 v143, 0xffff0000, v228
	v_lshlrev_b32_e32 v144, 16, v229
	v_and_b32_e32 v145, 0xffff0000, v229
	v_lshlrev_b32_e32 v146, 16, v230
	v_and_b32_e32 v147, 0xffff0000, v230
	v_lshlrev_b32_e32 v154, 16, v231
	v_and_b32_e32 v155, 0xffff0000, v231
	v_pk_fma_f32 v[6:7], v[6:7], v[138:139], v[144:145]
	v_pk_fma_f32 v[4:5], v[4:5], v[136:137], v[142:143]
	v_pk_fma_f32 v[2:3], v[2:3], v[134:135], v[154:155]
	v_pk_fma_f32 v[0:1], v[0:1], v[132:133], v[146:147]
	v_cvt_pk_bf16_f32 v132, v4, v5
	v_cvt_pk_bf16_f32 v133, v6, v7
	v_or_b32_e32 v144, s8, v159
	v_cvt_pk_bf16_f32 v134, v0, v1
	v_cvt_pk_bf16_f32 v135, v2, v3
	global_store_dwordx4 v[160:161], v[132:135], off offset:256
	v_lshl_add_u32 v131, v144, 4, s2
	s_and_saveexec_b64 s[2:3], vcc
	v_readlane_b32 s96, v254, 47
	s_cbranch_execz .LBB0_2734
	s_waitcnt lgkmcnt(0)
	v_add_f32_e32 v132, v140, v141
	ds_write_b32 v131, v132

;     __device__ __forceinline__ void fused(f32x4 (&acc)[2][2][4][2], const Unit& un, int wr, int wc, int fr, int fq, PG8_LAS unsigned char* lds, int wid, int lane) const {
;     ...
;         asm volatile("s_waitcnt lgkmcnt(0)" ::: "memory"); __builtin_amdgcn_s_barrier(); asm volatile("" ::: "memory");
;         const int row = wid * 32 + (lane & 31);
;         if (lane < 32) { const float tot = (P[row * 4 + 0] + P[row * 4 + 1]) + (P[row * 4 + 2] + P[row * 4 + 3]);
;             __hip_atomic_store(xbuf + ((size_t)(un.pm * BM + row) * 8 + un.pn), __float_as_uint(tot), __ATOMIC_RELAXED, __HIP_MEMORY_SCOPE_AGENT); }
.LBB0_2748:
	s_or_b64 exec, exec, s[2:3]
	s_add_u32 s60, s44, 0x3c700000
	s_addc_u32 s61, s45, 0
	s_lshl_b32 s1, s1, 5
	s_waitcnt lgkmcnt(0)
	s_barrier
	v_and_or_b32 v134, v158, 31, s1
	v_add_u32_e32 v128, s14, v134
	v_cmp_gt_u32_e64 s[2:3], 32, v130
	s_waitcnt lgkmcnt(0)
	v_ashrrev_i32_e32 v129, 31, v128
	s_and_saveexec_b64 s[6:7], s[2:3]
	s_cbranch_execz .LBB0_2750
	v_lshl_add_u32 v131, v134, 4, 0
	ds_read_b128 v[136:139], v131
	v_lshlrev_b64 v[132:133], 5, v[128:129]
	v_lshl_add_u64 v[132:133], s[60:61], 0, v[132:133]
	v_lshl_add_u64 v[132:133], s[4:5], 2, v[132:133]
	s_waitcnt lgkmcnt(0)
	v_mov_b32_e32 v140, v137
	v_mov_b32_e32 v141, v138
	v_mov_b32_e32 v137, v139
	v_pk_add_f32 v[136:137], v[140:141], v[136:137]
	s_nop 0
	v_pk_add_f32 v[136:137], v[136:137], v[136:137] op_sel:[0,1] op_sel_hi:[1,0]
	global_store_dword v[132:133], v136, off sc1

;     __device__ __forceinline__ void fused(f32x4 (&acc)[2][2][4][2], const Unit& un, int wr, int wc, int fr, int fq, PG8_LAS unsigned char* lds, int wid, int lane) const {
;     ...
;         if (wid == 0) {
;             bool dead = false; const unsigned long long t0 = __builtin_amdgcn_s_memrealtime();
;             for (;;) {
;                 if ((unsigned)__builtin_amdgcn_readfirstlane(__hip_atomic_load(cnt + 64 * un.pm, __ATOMIC_RELAXED, __HIP_MEMORY_SCOPE_AGENT)) >= 64u) break;
;                 if (__builtin_amdgcn_s_memrealtime() - t0 > 2000000ull) {
;                     if (lane == 0) { unsigned expect = 0u; __hip_atomic_compare_exchange_strong(tmo + 1, &expect, code | (unsigned)(un.pm & 0xff), __ATOMIC_RELAXED, __ATOMIC_RELAXED, __HIP_MEMORY_SCOPE_AGENT);
;                                      __hip_atomic_store(tmo, 1u, __ATOMIC_RELAXED, __HIP_MEMORY_SCOPE_AGENT); }
;                     dead = true; break; }
;                 __builtin_amdgcn_s_sleep(2);
;             }
.LBB0_2756:
	global_load_dword v135, v[130:131], off sc1
	s_mov_b64 s[64:65], -1
	s_mov_b64 s[66:67], -1
	s_waitcnt vmcnt(0) lgkmcnt(0)
	v_readfirstlane_b32 s0, v135
	s_cmp_gt_u32 s0, 63
	s_cbranch_scc1 .LBB0_2755
	s_memrealtime s[0:1]
	s_waitcnt lgkmcnt(0)
	s_sub_u32 s0, s0, s62
	s_subb_u32 s1, s1, s63
	v_cmp_lt_u64_e32 vcc, s[0:1], v[132:133]
	s_cbranch_vccz .LBB0_2754
	s_mov_b64 s[66:67], 0
	s_sleep 2
	s_branch .LBB0_2754

;     __device__ __forceinline__ void fused(f32x4 (&acc)[2][2][4][2], const Unit& un, int wr, int wc, int fr, int fq, PG8_LAS unsigned char* lds, int wid, int lane) const {
;     ...
;                 if (__builtin_amdgcn_s_memrealtime() - t0 > 2000000ull) {
;                     if (lane == 0) { unsigned expect = 0u; __hip_atomic_compare_exchange_strong(tmo + 1, &expect, code | (unsigned)(un.pm & 0xff), __ATOMIC_RELAXED, __ATOMIC_RELAXED, __HIP_MEMORY_SCOPE_AGENT);
;                                      __hip_atomic_store(tmo, 1u, __ATOMIC_RELAXED, __HIP_MEMORY_SCOPE_AGENT); }
;                     dead = true; break; }
.LBB0_2762:
	s_or_saveexec_b64 s[62:63], s[6:7]
	s_mov_b64 s[6:7], 0
	s_xor_b64 exec, exec, s[62:63]
	s_cbranch_execz .LBB0_2764
	s_and_b32 s0, s46, 0xbf
	s_or_b32 s0, s0, 0x740
	v_mov_b32_e32 v130, s0
	v_mov_b32_e32 v131, 0
	v_mov_b64_e32 v[132:133], s[44:45]
	flat_atomic_cmpswap v[132:133], v[130:131] offset:4
	s_mov_b64 s[6:7], exec
	v_mov_b32_e32 v130, 1
	global_store_dword v[132:133], v130, off sc1

;     __device__ __forceinline__ void fused(f32x4 (&acc)[2][2][4][2], const Unit& un, int wr, int wc, int fr, int fq, PG8_LAS unsigned char* lds, int wid, int lane) const {
;     ...
;         asm volatile("s_waitcnt vmcnt(0) lgkmcnt(0)" ::: "memory"); __builtin_amdgcn_s_barrier(); asm volatile("" ::: "memory");
;         const bool bad = flag[0] != 0u;
;         if (lane < 32) { const unsigned* slot = xbuf + (size_t)(un.pm * BM + row) * 8; float q = 0.f;
; #pragma unroll
;             for (int t = 0; t < 8; ++t) q += __uint_as_float(__hip_atomic_load(slot + t, __ATOMIC_RELAXED, __HIP_MEMORY_SCOPE_AGENT));
;             S[row] = 1.0f / sqrtf(q * (1.0f / 2048.0f) + eps); }
;         asm volatile("s_waitcnt lgkmcnt(0)" ::: "memory"); __builtin_amdgcn_s_barrier(); asm volatile("" ::: "memory");
;         const float qnan = __builtin_nanf("");
;         f32x4 cg[2][2], sh[2][2];
; #pragma unroll
;         for (int bj = 0; bj < 2; ++bj)
; #pragma unroll
;             for (int n = 0; n < 2; ++n) { const f32x4 g4 = *(const f32x4*)(gain + col0 + bj * HALF + n * 4);
;                 if (MODE == 0) { const f32x4 sc4 = *(const f32x4*)(scale + boff + bj * HALF + n * 4); cg[bj][n] = g4 * (sc4 + 1.0f); sh[bj][n] = *(const f32x4*)(shift + boff + bj * HALF + n * 4); }
;                 else { cg[bj][n] = g4; sh[bj][n] = (f32x4){0.f, 0.f, 0.f, 0.f}; } }
; #pragma unroll
;         for (int ai = 0; ai < 2; ++ai)
; #pragma unroll
;             for (int m = 0; m < 4; ++m) { const int r = ai * HALF + wr * 64 + m * 16 + fr; const float rs = S[r]; const size_t off = (size_t)(un.pm * BM + r) * ldc + col0;
.LBB0_2770:
	s_waitcnt vmcnt(0) lgkmcnt(0)
	s_barrier
	v_mov_b32_e32 v130, 0
	ds_read_b32 v158, v130 offset:5120
	s_and_saveexec_b64 s[4:5], s[2:3]
	s_cbranch_execz .LBB0_2772
	v_lshlrev_b64 v[128:129], 5, v[128:129]
	v_lshl_add_u64 v[128:129], s[60:61], 0, v[128:129]
	global_load_dword v130, v[128:129], off sc1
	global_load_dword v131, v[128:129], off offset:4 sc1
	global_load_dword v132, v[128:129], off offset:8 sc1
	global_load_dword v133, v[128:129], off offset:12 sc1
	global_load_dword v135, v[128:129], off offset:16 sc1
	global_load_dword v136, v[128:129], off offset:20 sc1
	global_load_dword v137, v[128:129], off offset:24 sc1
	s_nop 0
	global_load_dword v128, v[128:129], off offset:28 sc1
	v_mov_b32_e32 v129, 0x358637bd
	s_mov_b32 s0, 0xf800000
	s_waitcnt vmcnt(0) lgkmcnt(0)
	v_add_f32_e32 v130, 0, v130
	v_add_f32_e32 v130, v130, v131
	v_add_f32_e32 v130, v130, v132
	v_add_f32_e32 v130, v130, v133
	v_add_f32_e32 v130, v130, v135
	v_add_f32_e32 v130, v130, v136
	v_add_f32_e32 v130, v130, v137
	v_add_f32_e32 v128, v130, v128
	v_fmac_f32_e32 v129, 0x3a000000, v128
	v_mul_f32_e32 v128, 0x4f800000, v129
	v_cmp_gt_f32_e32 vcc, s0, v129
	v_mov_b32_e32 v130, 0x260
	s_nop 0
	v_cndmask_b32_e32 v128, v129, v128, vcc
	v_sqrt_f32_e32 v129, v128
	s_nop 0
	v_add_u32_e32 v131, -1, v129
	v_add_u32_e32 v132, 1, v129
	v_fma_f32 v133, -v131, v129, v128
	v_fma_f32 v135, -v132, v129, v128
	v_cmp_ge_f32_e64 s[2:3], 0, v133
	s_nop 1
	v_cndmask_b32_e64 v129, v129, v131, s[2:3]
	v_cmp_lt_f32_e64 s[2:3], 0, v135
	s_nop 1
	v_cndmask_b32_e64 v129, v129, v132, s[2:3]
	v_mul_f32_e32 v131, 0x37800000, v129
	v_cndmask_b32_e32 v129, v129, v131, vcc
	v_cmp_class_f32_e32 vcc, v128, v130
	s_nop 1
	v_cndmask_b32_e32 v128, v129, v128, vcc
	v_div_scale_f32 v129, s[0:1], v128, v128, 1.0
	v_rcp_f32_e32 v130, v129
	v_div_scale_f32 v131, vcc, 1.0, v128, 1.0
	v_fma_f32 v132, -v129, v130, 1.0
	v_fmac_f32_e32 v130, v132, v130
	v_mul_f32_e32 v132, v131, v130
	v_fma_f32 v133, -v129, v132, v131
	v_fmac_f32_e32 v132, v133, v130
	v_fma_f32 v129, -v129, v132, v131
	v_div_fmas_f32 v129, v129, v130, v132
	v_div_fixup_f32 v128, v129, v128, 1.0
	v_lshl_add_u32 v129, v134, 2, 0
	ds_write_b32 v129, v128 offset:4096
.LBB0_2772:
	s_or_b64 exec, exec, s[4:5]
	v_readlane_b32 s48, v254, 11
	v_readlane_b32 s54, v254, 17
	v_readlane_b32 s55, v254, 18
	s_mov_b64 s[0:1], 0x4000
	s_waitcnt lgkmcnt(0)
	s_barrier
	v_lshl_add_u64 v[128:129], v[152:153], 2, s[54:55]
	v_lshl_add_u64 v[130:131], v[128:129], 0, s[0:1]
	s_mov_b64 s[0:1], 0x168000
	v_lshl_add_u64 v[136:137], v[150:151], 0, s[0:1]
	s_mov_b64 s[0:1], 0x166000
	v_lshl_add_u64 v[138:139], v[150:151], 0, s[0:1]
	s_movk_i32 s0, 0x4000
	v_add_co_u32_e32 v128, vcc, s0, v128
	s_mov_b32 s0, 0x168000
	s_nop 0
	v_addc_co_u32_e32 v129, vcc, 0, v129, vcc
	global_load_dwordx4 v[160:163], v[128:129], off
	global_load_dwordx4 v[152:155], v[136:137], off offset:16
	v_add_co_u32_e32 v128, vcc, s0, v150
	global_load_dwordx4 v[164:167], v[136:137], off offset:512
	global_load_dwordx4 v[132:135], v[138:139], off offset:16
	global_load_dwordx4 v[168:171], v[136:137], off offset:528
	global_load_dwordx4 v[172:175], v[130:131], off offset:16
	global_load_dwordx4 v[176:179], v[130:131], off offset:512
	v_addc_co_u32_e32 v129, vcc, 0, v151, vcc
	global_load_dwordx4 v[180:183], v[130:131], off offset:528
	global_load_dwordx4 v[184:187], v[128:129], off
	s_mov_b32 s0, 0x166000
	v_add_co_u32_e32 v128, vcc, s0, v150
	v_lshl_add_u32 v157, v144, 2, 0
	s_nop 0
	v_addc_co_u32_e32 v129, vcc, 0, v151, vcc
	global_load_dwordx4 v[140:143], v[128:129], off
	s_nop 0
	global_load_dwordx4 v[128:131], v[138:139], off offset:512
	s_nop 0
	global_load_dwordx4 v[136:139], v[138:139], off offset:528
	ds_read_b32 v188, v157 offset:4096
	v_add_u32_e32 v144, s14, v144
	s_add_u32 s2, s44, 0x1e600000
	v_ashrrev_i32_e32 v145, 31, v144
	s_addc_u32 s3, s45, 0
	v_lshlrev_b64 v[146:147], 12, v[144:145]
	s_waitcnt lgkmcnt(0)
	v_pk_mul_f32 v[192:193], v[8:9], v[188:189] op_sel_hi:[1,0]
	v_pk_mul_f32 v[194:195], v[10:11], v[188:189] op_sel_hi:[1,0]
	v_lshl_add_u64 v[190:191], s[2:3], 0, v[146:147]
	v_pk_mul_f32 v[196:197], v[12:13], v[188:189] op_sel_hi:[1,0]
	v_pk_mul_f32 v[198:199], v[14:15], v[188:189] op_sel_hi:[1,0]
	v_mov_b32_e32 v156, 0x7fc00000
	v_cmp_eq_u32_e32 vcc, 0, v158
	v_pk_mul_f32 v[24:25], v[24:25], v[188:189] op_sel_hi:[1,0]
	v_pk_mul_f32 v[26:27], v[26:27], v[188:189] op_sel_hi:[1,0]
	v_pk_mul_f32 v[32:33], v[32:33], v[188:189] op_sel_hi:[1,0]
	v_pk_mul_f32 v[34:35], v[34:35], v[188:189] op_sel_hi:[1,0]
	v_readlane_b32 s49, v254, 12
	v_readlane_b32 s50, v254, 13
	v_readlane_b32 s51, v254, 14
	v_readlane_b32 s52, v254, 15
	v_readlane_b32 s53, v254, 16
	v_readlane_b32 s56, v254, 19
	v_readlane_b32 s57, v254, 20
	v_readlane_b32 s58, v254, 21
	v_readlane_b32 s59, v254, 22
	v_readlane_b32 s60, v254, 23
	v_readlane_b32 s61, v254, 24
	v_readlane_b32 s62, v254, 25
	v_readlane_b32 s63, v254, 26
	s_waitcnt vmcnt(0)
; __device__ __forceinline__ unsigned cvt_pk_bf16(float lo, float hi) { unsigned r; asm volatile("v_cvt_pk_bf16_f32 %0, %1, %2" : "=v"(r) : "v"(lo), "v"(hi)); return r; }
;     __device__ __forceinline__ void fused(f32x4 (&acc)[2][2][4][2], const Unit& un, int wr, int wc, int fr, int fq, PG8_LAS unsigned char* lds, int wid, int lane) const {
;     ...
;             for (int n = 0; n < 2; ++n) { const f32x4 g4 = *(const f32x4*)(gain + col0 + bj * HALF + n * 4);
;                 if (MODE == 0) { const f32x4 sc4 = *(const f32x4*)(scale + boff + bj * HALF + n * 4); cg[bj][n] = g4 * (sc4 + 1.0f); sh[bj][n] = *(const f32x4*)(shift + boff + bj * HALF + n * 4); }
;                 else { cg[bj][n] = g4; sh[bj][n] = (f32x4){0.f, 0.f, 0.f, 0.f}; } }
; #pragma unroll
;         for (int ai = 0; ai < 2; ++ai)
; #pragma unroll
;             for (int m = 0; m < 4; ++m) { const int r = ai * HALF + wr * 64 + m * 16 + fr; const float rs = S[r]; const size_t off = (size_t)(un.pm * BM + r) * ldc + col0;
; #pragma unroll
;                 for (int bj = 0; bj < 2; ++bj) { f32x4 y0 = (acc[ai][bj][m][0] * rs) * cg[bj][0] + sh[bj][0], y1 = (acc[ai][bj][m][1] * rs) * cg[bj][1] + sh[bj][1];
;                     if (bad) { y0 = (f32x4){qnan, qnan, qnan, qnan}; y1 = y0; }
;                     if (MODE == 0) { u32x4 w; w.x = cvt_pk_bf16(y0[0], y0[1]); w.y = cvt_pk_bf16(y0[2], y0[3]); w.z = cvt_pk_bf16(y1[0], y1[1]); w.w = cvt_pk_bf16(y1[2], y1[3]); *(u32x4*)(u + off + bj * HALF) = w; }
	v_pk_add_f32 v[12:13], v[166:167], 1.0 op_sel_hi:[1,0]
	v_pk_add_f32 v[8:9], v[154:155], 1.0 op_sel_hi:[1,0]
	v_pk_add_f32 v[10:11], v[152:153], 1.0 op_sel_hi:[1,0]
	v_pk_add_f32 v[152:153], v[170:171], 1.0 op_sel_hi:[1,0]
	v_pk_add_f32 v[154:155], v[168:169], 1.0 op_sel_hi:[1,0]
	v_pk_mul_f32 v[146:147], v[174:175], v[8:9]
	v_pk_mul_f32 v[150:151], v[172:173], v[10:11]
	v_pk_mul_f32 v[8:9], v[182:183], v[152:153]
	v_pk_mul_f32 v[10:11], v[180:181], v[154:155]
	v_pk_add_f32 v[152:153], v[186:187], 1.0 op_sel_hi:[1,0]
	v_pk_add_f32 v[154:155], v[184:185], 1.0 op_sel_hi:[1,0]
	v_pk_mul_f32 v[152:153], v[162:163], v[152:153]
	v_pk_mul_f32 v[154:155], v[160:161], v[154:155]
	v_pk_add_f32 v[14:15], v[164:165], 1.0 op_sel_hi:[1,0]
	v_pk_fma_f32 v[164:165], v[146:147], v[198:199], v[134:135]
	v_pk_fma_f32 v[166:167], v[150:151], v[196:197], v[132:133]
	v_pk_fma_f32 v[160:161], v[152:153], v[194:195], v[142:143]
	v_pk_fma_f32 v[162:163], v[154:155], v[192:193], v[140:141]
	v_pk_mul_f32 v[12:13], v[178:179], v[12:13]
	v_pk_mul_f32 v[14:15], v[176:177], v[14:15]
	v_cndmask_b32_e32 v145, v156, v160, vcc
	v_cndmask_b32_e32 v159, v156, v161, vcc
	v_cndmask_b32_e32 v158, v156, v162, vcc
	v_cndmask_b32_e32 v160, v156, v163, vcc
	v_cndmask_b32_e32 v161, v156, v164, vcc
	v_cndmask_b32_e32 v162, v156, v165, vcc
	v_cndmask_b32_e32 v163, v156, v166, vcc
	v_pk_fma_f32 v[26:27], v[8:9], v[26:27], v[138:139]
	v_pk_fma_f32 v[24:25], v[10:11], v[24:25], v[136:137]
	v_cndmask_b32_e32 v164, v156, v167, vcc
	v_cvt_pk_bf16_f32 v158, v158, v160
	v_cvt_pk_bf16_f32 v159, v145, v159
	v_cvt_pk_bf16_f32 v160, v163, v164
	v_cvt_pk_bf16_f32 v161, v161, v162
	v_lshl_add_u64 v[162:163], v[190:191], 0, v[148:149]
	v_pk_fma_f32 v[34:35], v[12:13], v[34:35], v[130:131]
	v_pk_fma_f32 v[32:33], v[14:15], v[32:33], v[128:129]
	v_cndmask_b32_e32 v145, v156, v26, vcc
	v_cndmask_b32_e32 v27, v156, v27, vcc
	v_cndmask_b32_e32 v26, v156, v24, vcc
	global_store_dwordx4 v[162:163], v[158:161], off
	v_cndmask_b32_e32 v34, v156, v34, vcc
	v_cndmask_b32_e32 v35, v156, v35, vcc
	v_cndmask_b32_e32 v32, v156, v32, vcc
	v_cndmask_b32_e32 v33, v156, v33, vcc
	v_cndmask_b32_e32 v158, v156, v25, vcc
	v_cvt_pk_bf16_f32 v24, v32, v33
	v_cvt_pk_bf16_f32 v25, v34, v35
	v_cvt_pk_bf16_f32 v26, v26, v158
	v_cvt_pk_bf16_f32 v27, v145, v27
	global_store_dwordx4 v[162:163], v[24:27], off offset:256
	ds_read_b32 v24, v157 offset:4160
	s_waitcnt lgkmcnt(0)
	v_pk_mul_f32 v[16:17], v[16:17], v[24:25] op_sel_hi:[1,0]
	v_pk_mul_f32 v[18:19], v[18:19], v[24:25] op_sel_hi:[1,0]
	v_pk_mul_f32 v[20:21], v[20:21], v[24:25] op_sel_hi:[1,0]
	v_add_u32_e32 v26, 16, v144
	v_pk_fma_f32 v[18:19], v[152:153], v[18:19], v[142:143]
	v_pk_fma_f32 v[16:17], v[154:155], v[16:17], v[140:141]
	v_pk_fma_f32 v[20:21], v[150:151], v[20:21], v[132:133]
	v_ashrrev_i32_e32 v27, 31, v26
	v_cndmask_b32_e32 v18, v156, v18, vcc
	v_cndmask_b32_e32 v16, v156, v16, vcc
	v_cndmask_b32_e32 v17, v156, v17, vcc
	v_cndmask_b32_e32 v20, v156, v20, vcc
	v_cndmask_b32_e32 v21, v156, v21, vcc
	v_pk_mul_f32 v[22:23], v[22:23], v[24:25] op_sel_hi:[1,0]
	v_cndmask_b32_e32 v19, v156, v19, vcc
	v_cvt_pk_bf16_f32 v16, v16, v17
	v_cvt_pk_bf16_f32 v17, v18, v19
	v_cvt_pk_bf16_f32 v18, v20, v21
	v_lshlrev_b64 v[20:21], 12, v[26:27]
	v_pk_fma_f32 v[22:23], v[146:147], v[22:23], v[134:135]
	v_lshl_add_u64 v[20:21], s[2:3], 0, v[20:21]
	v_cndmask_b32_e32 v22, v156, v22, vcc
	v_cndmask_b32_e32 v23, v156, v23, vcc
	v_cvt_pk_bf16_f32 v19, v22, v23
	v_lshl_add_u64 v[20:21], v[20:21], 0, v[148:149]
	global_store_dwordx4 v[20:21], v[16:19], off
	v_pk_mul_f32 v[22:23], v[56:57], v[24:25] op_sel_hi:[1,0]
	s_nop 0
	v_pk_mul_f32 v[16:17], v[60:61], v[24:25] op_sel_hi:[1,0]
	v_pk_mul_f32 v[18:19], v[62:63], v[24:25] op_sel_hi:[1,0]
	v_pk_fma_f32 v[16:17], v[14:15], v[16:17], v[128:129]
	v_pk_fma_f32 v[18:19], v[12:13], v[18:19], v[130:131]
	v_pk_mul_f32 v[24:25], v[58:59], v[24:25] op_sel_hi:[1,0]
	v_pk_fma_f32 v[22:23], v[10:11], v[22:23], v[136:137]
	v_pk_fma_f32 v[24:25], v[8:9], v[24:25], v[138:139]
	v_cndmask_b32_e32 v18, v156, v18, vcc
	v_cndmask_b32_e32 v19, v156, v19, vcc
	v_cndmask_b32_e32 v16, v156, v16, vcc
	v_cndmask_b32_e32 v17, v156, v17, vcc
	v_cndmask_b32_e32 v24, v156, v24, vcc
	v_cndmask_b32_e32 v25, v156, v25, vcc
	v_cndmask_b32_e32 v22, v156, v22, vcc
	v_cndmask_b32_e32 v23, v156, v23, vcc
	v_cvt_pk_bf16_f32 v16, v16, v17
	v_cvt_pk_bf16_f32 v17, v18, v19
	v_cvt_pk_bf16_f32 v18, v22, v23
	v_cvt_pk_bf16_f32 v19, v24, v25
	global_store_dwordx4 v[20:21], v[16:19], off offset:256
	ds_read_b32 v20, v157 offset:4224
	v_add_u32_e32 v22, 32, v144
	v_ashrrev_i32_e32 v23, 31, v22
	v_lshlrev_b64 v[22:23], 12, v[22:23]
	v_lshl_add_u64 v[22:23], s[2:3], 0, v[22:23]
	s_waitcnt lgkmcnt(0)
; __device__ __forceinline__ unsigned cvt_pk_bf16(float lo, float hi) { unsigned r; asm volatile("v_cvt_pk_bf16_f32 %0, %1, %2" : "=v"(r) : "v"(lo), "v"(hi)); return r; }
;     __device__ __forceinline__ void fused(f32x4 (&acc)[2][2][4][2], const Unit& un, int wr, int wc, int fr, int fq, PG8_LAS unsigned char* lds, int wid, int lane) const {
;     ...
;         for (int ai = 0; ai < 2; ++ai)
; #pragma unroll
;             for (int m = 0; m < 4; ++m) { const int r = ai * HALF + wr * 64 + m * 16 + fr; const float rs = S[r]; const size_t off = (size_t)(un.pm * BM + r) * ldc + col0;
; #pragma unroll
;                 for (int bj = 0; bj < 2; ++bj) { f32x4 y0 = (acc[ai][bj][m][0] * rs) * cg[bj][0] + sh[bj][0], y1 = (acc[ai][bj][m][1] * rs) * cg[bj][1] + sh[bj][1];
;                     if (bad) { y0 = (f32x4){qnan, qnan, qnan, qnan}; y1 = y0; }
;                     if (MODE == 0) { u32x4 w; w.x = cvt_pk_bf16(y0[0], y0[1]); w.y = cvt_pk_bf16(y0[2], y0[3]); w.z = cvt_pk_bf16(y1[0], y1[1]); w.w = cvt_pk_bf16(y1[2], y1[3]); *(u32x4*)(u + off + bj * HALF) = w; }
	v_pk_mul_f32 v[16:17], v[48:49], v[20:21] op_sel_hi:[1,0]
	v_pk_mul_f32 v[18:19], v[50:51], v[20:21] op_sel_hi:[1,0]
	v_pk_fma_f32 v[16:17], v[154:155], v[16:17], v[140:141]
	v_pk_fma_f32 v[18:19], v[152:153], v[18:19], v[142:143]
	v_pk_mul_f32 v[24:25], v[52:53], v[20:21] op_sel_hi:[1,0]
	v_pk_mul_f32 v[26:27], v[54:55], v[20:21] op_sel_hi:[1,0]
	v_pk_fma_f32 v[24:25], v[150:151], v[24:25], v[132:133]
	v_pk_fma_f32 v[26:27], v[146:147], v[26:27], v[134:135]
	v_cndmask_b32_e32 v18, v156, v18, vcc
	v_cndmask_b32_e32 v19, v156, v19, vcc
	v_cndmask_b32_e32 v16, v156, v16, vcc
	v_cndmask_b32_e32 v17, v156, v17, vcc
	v_cndmask_b32_e32 v21, v156, v26, vcc
	v_cndmask_b32_e32 v26, v156, v27, vcc
	v_cndmask_b32_e32 v24, v156, v24, vcc
	v_cndmask_b32_e32 v25, v156, v25, vcc
	v_cvt_pk_bf16_f32 v16, v16, v17
	v_cvt_pk_bf16_f32 v17, v18, v19
	v_cvt_pk_bf16_f32 v18, v24, v25
	v_cvt_pk_bf16_f32 v19, v21, v26
	v_lshl_add_u64 v[22:23], v[22:23], 0, v[148:149]
	global_store_dwordx4 v[22:23], v[16:19], off
	v_pk_mul_f32 v[24:25], v[72:73], v[20:21] op_sel_hi:[1,0]
	s_nop 0
	v_pk_mul_f32 v[16:17], v[76:77], v[20:21] op_sel_hi:[1,0]
	v_pk_mul_f32 v[18:19], v[78:79], v[20:21] op_sel_hi:[1,0]
	v_pk_fma_f32 v[16:17], v[14:15], v[16:17], v[128:129]
	v_pk_fma_f32 v[18:19], v[12:13], v[18:19], v[130:131]
	v_pk_mul_f32 v[20:21], v[74:75], v[20:21] op_sel_hi:[1,0]
	v_pk_fma_f32 v[24:25], v[10:11], v[24:25], v[136:137]
	v_pk_fma_f32 v[20:21], v[8:9], v[20:21], v[138:139]
	v_cndmask_b32_e32 v18, v156, v18, vcc
	v_cndmask_b32_e32 v19, v156, v19, vcc
	v_cndmask_b32_e32 v16, v156, v16, vcc
	v_cndmask_b32_e32 v17, v156, v17, vcc
	v_cndmask_b32_e32 v20, v156, v20, vcc
	v_cndmask_b32_e32 v21, v156, v21, vcc
	v_cndmask_b32_e32 v24, v156, v24, vcc
	v_cndmask_b32_e32 v25, v156, v25, vcc
	v_cvt_pk_bf16_f32 v16, v16, v17
	v_cvt_pk_bf16_f32 v17, v18, v19
	v_cvt_pk_bf16_f32 v18, v24, v25
	v_cvt_pk_bf16_f32 v19, v20, v21
	global_store_dwordx4 v[22:23], v[16:19], off offset:256
	ds_read_b32 v20, v157 offset:4288
	v_add_u32_e32 v22, 48, v144
	v_ashrrev_i32_e32 v23, 31, v22
	v_lshlrev_b64 v[22:23], 12, v[22:23]
	v_lshl_add_u64 v[22:23], s[2:3], 0, v[22:23]
	s_waitcnt lgkmcnt(0)
	v_pk_mul_f32 v[16:17], v[64:65], v[20:21] op_sel_hi:[1,0]
	v_pk_mul_f32 v[18:19], v[66:67], v[20:21] op_sel_hi:[1,0]
	v_pk_fma_f32 v[16:17], v[154:155], v[16:17], v[140:141]
	v_pk_fma_f32 v[18:19], v[152:153], v[18:19], v[142:143]
	v_pk_mul_f32 v[24:25], v[68:69], v[20:21] op_sel_hi:[1,0]
	v_pk_mul_f32 v[26:27], v[70:71], v[20:21] op_sel_hi:[1,0]
	v_pk_fma_f32 v[24:25], v[150:151], v[24:25], v[132:133]
	v_pk_fma_f32 v[26:27], v[146:147], v[26:27], v[134:135]
	v_cndmask_b32_e32 v18, v156, v18, vcc
	v_cndmask_b32_e32 v19, v156, v19, vcc
	v_cndmask_b32_e32 v16, v156, v16, vcc
	v_cndmask_b32_e32 v17, v156, v17, vcc
	v_cndmask_b32_e32 v21, v156, v26, vcc
	v_cndmask_b32_e32 v26, v156, v27, vcc
	v_cndmask_b32_e32 v24, v156, v24, vcc
	v_cndmask_b32_e32 v25, v156, v25, vcc
	v_cvt_pk_bf16_f32 v16, v16, v17
	v_cvt_pk_bf16_f32 v17, v18, v19
	v_cvt_pk_bf16_f32 v18, v24, v25
	v_cvt_pk_bf16_f32 v19, v21, v26
	v_lshl_add_u64 v[22:23], v[22:23], 0, v[148:149]
	global_store_dwordx4 v[22:23], v[16:19], off
	v_pk_mul_f32 v[24:25], v[96:97], v[20:21] op_sel_hi:[1,0]
	s_nop 0
	v_pk_mul_f32 v[16:17], v[108:109], v[20:21] op_sel_hi:[1,0]
	v_pk_mul_f32 v[18:19], v[110:111], v[20:21] op_sel_hi:[1,0]
	v_pk_fma_f32 v[16:17], v[14:15], v[16:17], v[128:129]
	v_pk_fma_f32 v[18:19], v[12:13], v[18:19], v[130:131]
	v_pk_mul_f32 v[20:21], v[98:99], v[20:21] op_sel_hi:[1,0]
	v_pk_fma_f32 v[24:25], v[10:11], v[24:25], v[136:137]
	v_pk_fma_f32 v[20:21], v[8:9], v[20:21], v[138:139]
	v_cndmask_b32_e32 v18, v156, v18, vcc
	v_cndmask_b32_e32 v19, v156, v19, vcc
	v_cndmask_b32_e32 v16, v156, v16, vcc
	v_cndmask_b32_e32 v17, v156, v17, vcc
	v_cndmask_b32_e32 v20, v156, v20, vcc
	v_cndmask_b32_e32 v21, v156, v21, vcc
	v_cndmask_b32_e32 v24, v156, v24, vcc
	v_cndmask_b32_e32 v25, v156, v25, vcc
	v_cvt_pk_bf16_f32 v16, v16, v17
	v_cvt_pk_bf16_f32 v17, v18, v19
	v_cvt_pk_bf16_f32 v18, v24, v25
	v_cvt_pk_bf16_f32 v19, v20, v21
	global_store_dwordx4 v[22:23], v[16:19], off offset:256
	ds_read_b32 v20, v157 offset:4608
	v_add_u32_e32 v22, 0x80, v144
	v_ashrrev_i32_e32 v23, 31, v22
	v_lshlrev_b64 v[22:23], 12, v[22:23]
	v_lshl_add_u64 v[22:23], s[2:3], 0, v[22:23]
	s_waitcnt lgkmcnt(0)
	v_pk_mul_f32 v[16:17], v[100:101], v[20:21] op_sel_hi:[1,0]
	v_pk_mul_f32 v[18:19], v[102:103], v[20:21] op_sel_hi:[1,0]
	v_pk_fma_f32 v[16:17], v[154:155], v[16:17], v[140:141]
	v_pk_fma_f32 v[18:19], v[152:153], v[18:19], v[142:143]
	v_pk_mul_f32 v[24:25], v[104:105], v[20:21] op_sel_hi:[1,0]
	v_pk_mul_f32 v[26:27], v[106:107], v[20:21] op_sel_hi:[1,0]
	v_pk_fma_f32 v[24:25], v[150:151], v[24:25], v[132:133]
	v_pk_fma_f32 v[26:27], v[146:147], v[26:27], v[134:135]
	v_cndmask_b32_e32 v18, v156, v18, vcc
	v_cndmask_b32_e32 v19, v156, v19, vcc
	v_cndmask_b32_e32 v16, v156, v16, vcc
	v_cndmask_b32_e32 v17, v156, v17, vcc
	v_cndmask_b32_e32 v21, v156, v26, vcc
	v_cndmask_b32_e32 v26, v156, v27, vcc
	v_cndmask_b32_e32 v24, v156, v24, vcc
	v_cndmask_b32_e32 v25, v156, v25, vcc
	v_cvt_pk_bf16_f32 v16, v16, v17
	v_cvt_pk_bf16_f32 v17, v18, v19
	v_cvt_pk_bf16_f32 v18, v24, v25
	v_cvt_pk_bf16_f32 v19, v21, v26
	v_lshl_add_u64 v[22:23], v[22:23], 0, v[148:149]
	global_store_dwordx4 v[22:23], v[16:19], off
	v_pk_mul_f32 v[24:25], v[112:113], v[20:21] op_sel_hi:[1,0]
	s_nop 0
	v_pk_mul_f32 v[16:17], v[124:125], v[20:21] op_sel_hi:[1,0]
	v_pk_mul_f32 v[18:19], v[126:127], v[20:21] op_sel_hi:[1,0]
	v_pk_fma_f32 v[16:17], v[14:15], v[16:17], v[128:129]
	v_pk_fma_f32 v[18:19], v[12:13], v[18:19], v[130:131]
	v_pk_mul_f32 v[20:21], v[114:115], v[20:21] op_sel_hi:[1,0]
	v_pk_fma_f32 v[24:25], v[10:11], v[24:25], v[136:137]
	v_pk_fma_f32 v[20:21], v[8:9], v[20:21], v[138:139]
	v_cndmask_b32_e32 v18, v156, v18, vcc
	v_cndmask_b32_e32 v19, v156, v19, vcc
	v_cndmask_b32_e32 v16, v156, v16, vcc
	v_cndmask_b32_e32 v17, v156, v17, vcc
	v_cndmask_b32_e32 v20, v156, v20, vcc
	v_cndmask_b32_e32 v21, v156, v21, vcc
	v_cndmask_b32_e32 v24, v156, v24, vcc
	v_cndmask_b32_e32 v25, v156, v25, vcc
	v_cvt_pk_bf16_f32 v16, v16, v17
	v_cvt_pk_bf16_f32 v17, v18, v19
	v_cvt_pk_bf16_f32 v18, v24, v25
	v_cvt_pk_bf16_f32 v19, v20, v21
	global_store_dwordx4 v[22:23], v[16:19], off offset:256
	ds_read_b32 v20, v157 offset:4672
	v_add_u32_e32 v22, 0x90, v144
	v_ashrrev_i32_e32 v23, 31, v22
	v_lshlrev_b64 v[22:23], 12, v[22:23]
	v_lshl_add_u64 v[22:23], s[2:3], 0, v[22:23]
	s_waitcnt lgkmcnt(0)
; __device__ __forceinline__ unsigned cvt_pk_bf16(float lo, float hi) { unsigned r; asm volatile("v_cvt_pk_bf16_f32 %0, %1, %2" : "=v"(r) : "v"(lo), "v"(hi)); return r; }
;     __device__ __forceinline__ void fused(f32x4 (&acc)[2][2][4][2], const Unit& un, int wr, int wc, int fr, int fq, PG8_LAS unsigned char* lds, int wid, int lane) const {
;     ...
;         for (int ai = 0; ai < 2; ++ai)
; #pragma unroll
;             for (int m = 0; m < 4; ++m) { const int r = ai * HALF + wr * 64 + m * 16 + fr; const float rs = S[r]; const size_t off = (size_t)(un.pm * BM + r) * ldc + col0;
; #pragma unroll
;                 for (int bj = 0; bj < 2; ++bj) { f32x4 y0 = (acc[ai][bj][m][0] * rs) * cg[bj][0] + sh[bj][0], y1 = (acc[ai][bj][m][1] * rs) * cg[bj][1] + sh[bj][1];
;                     if (bad) { y0 = (f32x4){qnan, qnan, qnan, qnan}; y1 = y0; }
;                     if (MODE == 0) { u32x4 w; w.x = cvt_pk_bf16(y0[0], y0[1]); w.y = cvt_pk_bf16(y0[2], y0[3]); w.z = cvt_pk_bf16(y1[0], y1[1]); w.w = cvt_pk_bf16(y1[2], y1[3]); *(u32x4*)(u + off + bj * HALF) = w; }
	v_pk_mul_f32 v[16:17], v[116:117], v[20:21] op_sel_hi:[1,0]
	v_pk_mul_f32 v[18:19], v[118:119], v[20:21] op_sel_hi:[1,0]
	v_pk_fma_f32 v[16:17], v[154:155], v[16:17], v[140:141]
	v_pk_fma_f32 v[18:19], v[152:153], v[18:19], v[142:143]
	v_pk_mul_f32 v[24:25], v[120:121], v[20:21] op_sel_hi:[1,0]
	v_pk_mul_f32 v[26:27], v[122:123], v[20:21] op_sel_hi:[1,0]
	v_pk_fma_f32 v[24:25], v[150:151], v[24:25], v[132:133]
	v_pk_fma_f32 v[26:27], v[146:147], v[26:27], v[134:135]
	v_cndmask_b32_e32 v18, v156, v18, vcc
	v_cndmask_b32_e32 v19, v156, v19, vcc
	v_cndmask_b32_e32 v16, v156, v16, vcc
	v_cndmask_b32_e32 v17, v156, v17, vcc
	v_cndmask_b32_e32 v21, v156, v26, vcc
	v_cndmask_b32_e32 v26, v156, v27, vcc
	v_cndmask_b32_e32 v24, v156, v24, vcc
	v_cndmask_b32_e32 v25, v156, v25, vcc
	v_cvt_pk_bf16_f32 v16, v16, v17
	v_cvt_pk_bf16_f32 v17, v18, v19
	v_cvt_pk_bf16_f32 v18, v24, v25
	v_cvt_pk_bf16_f32 v19, v21, v26
	v_lshl_add_u64 v[22:23], v[22:23], 0, v[148:149]
	global_store_dwordx4 v[22:23], v[16:19], off
	v_pk_mul_f32 v[24:25], v[88:89], v[20:21] op_sel_hi:[1,0]
	s_nop 0
	v_pk_mul_f32 v[16:17], v[92:93], v[20:21] op_sel_hi:[1,0]
	v_pk_mul_f32 v[18:19], v[94:95], v[20:21] op_sel_hi:[1,0]
	v_pk_fma_f32 v[16:17], v[14:15], v[16:17], v[128:129]
	v_pk_fma_f32 v[18:19], v[12:13], v[18:19], v[130:131]
	v_pk_mul_f32 v[20:21], v[90:91], v[20:21] op_sel_hi:[1,0]
	v_pk_fma_f32 v[24:25], v[10:11], v[24:25], v[136:137]
	v_pk_fma_f32 v[20:21], v[8:9], v[20:21], v[138:139]
	v_cndmask_b32_e32 v18, v156, v18, vcc
	v_cndmask_b32_e32 v19, v156, v19, vcc
	v_cndmask_b32_e32 v16, v156, v16, vcc
	v_cndmask_b32_e32 v17, v156, v17, vcc
	v_cndmask_b32_e32 v20, v156, v20, vcc
	v_cndmask_b32_e32 v21, v156, v21, vcc
	v_cndmask_b32_e32 v24, v156, v24, vcc
	v_cndmask_b32_e32 v25, v156, v25, vcc
	v_cvt_pk_bf16_f32 v16, v16, v17
	v_cvt_pk_bf16_f32 v17, v18, v19
	v_cvt_pk_bf16_f32 v18, v24, v25
	v_cvt_pk_bf16_f32 v19, v20, v21
	global_store_dwordx4 v[22:23], v[16:19], off offset:256
	ds_read_b32 v20, v157 offset:4736
	v_add_u32_e32 v22, 0xa0, v144
	v_ashrrev_i32_e32 v23, 31, v22
	v_lshlrev_b64 v[22:23], 12, v[22:23]
	v_lshl_add_u64 v[22:23], s[2:3], 0, v[22:23]
	s_waitcnt lgkmcnt(0)
	v_pk_mul_f32 v[16:17], v[84:85], v[20:21] op_sel_hi:[1,0]
	v_pk_mul_f32 v[18:19], v[86:87], v[20:21] op_sel_hi:[1,0]
	v_pk_fma_f32 v[16:17], v[154:155], v[16:17], v[140:141]
	v_pk_fma_f32 v[18:19], v[152:153], v[18:19], v[142:143]
	v_pk_mul_f32 v[24:25], v[80:81], v[20:21] op_sel_hi:[1,0]
	v_pk_mul_f32 v[26:27], v[82:83], v[20:21] op_sel_hi:[1,0]
	v_pk_fma_f32 v[24:25], v[150:151], v[24:25], v[132:133]
	v_pk_fma_f32 v[26:27], v[146:147], v[26:27], v[134:135]
	v_cndmask_b32_e32 v18, v156, v18, vcc
	v_cndmask_b32_e32 v19, v156, v19, vcc
	v_cndmask_b32_e32 v16, v156, v16, vcc
	v_cndmask_b32_e32 v17, v156, v17, vcc
	v_cndmask_b32_e32 v21, v156, v26, vcc
	v_cndmask_b32_e32 v26, v156, v27, vcc
	v_cndmask_b32_e32 v24, v156, v24, vcc
	v_cndmask_b32_e32 v25, v156, v25, vcc
	v_cvt_pk_bf16_f32 v16, v16, v17
	v_cvt_pk_bf16_f32 v17, v18, v19
	v_cvt_pk_bf16_f32 v18, v24, v25
	v_cvt_pk_bf16_f32 v19, v21, v26
	v_lshl_add_u64 v[22:23], v[22:23], 0, v[148:149]
	global_store_dwordx4 v[22:23], v[16:19], off
	v_pk_mul_f32 v[24:25], v[40:41], v[20:21] op_sel_hi:[1,0]
	s_nop 0
	v_pk_mul_f32 v[16:17], v[44:45], v[20:21] op_sel_hi:[1,0]
	v_pk_mul_f32 v[18:19], v[46:47], v[20:21] op_sel_hi:[1,0]
	v_pk_fma_f32 v[16:17], v[14:15], v[16:17], v[128:129]
	v_pk_fma_f32 v[18:19], v[12:13], v[18:19], v[130:131]
	v_pk_mul_f32 v[20:21], v[42:43], v[20:21] op_sel_hi:[1,0]
	v_pk_fma_f32 v[24:25], v[10:11], v[24:25], v[136:137]
	v_pk_fma_f32 v[20:21], v[8:9], v[20:21], v[138:139]
	v_cndmask_b32_e32 v18, v156, v18, vcc
	v_cndmask_b32_e32 v19, v156, v19, vcc
	v_cndmask_b32_e32 v16, v156, v16, vcc
	v_cndmask_b32_e32 v17, v156, v17, vcc
	v_cndmask_b32_e32 v20, v156, v20, vcc
	v_cndmask_b32_e32 v21, v156, v21, vcc
	v_cndmask_b32_e32 v24, v156, v24, vcc
	v_cndmask_b32_e32 v25, v156, v25, vcc
	v_cvt_pk_bf16_f32 v16, v16, v17
	v_cvt_pk_bf16_f32 v17, v18, v19
	v_cvt_pk_bf16_f32 v18, v24, v25
	v_cvt_pk_bf16_f32 v19, v20, v21
	global_store_dwordx4 v[22:23], v[16:19], off offset:256
	ds_read_b32 v20, v157 offset:4800
	v_add_u32_e32 v22, 0xb0, v144
	v_ashrrev_i32_e32 v23, 31, v22
	v_lshlrev_b64 v[22:23], 12, v[22:23]
	v_lshl_add_u64 v[22:23], s[2:3], 0, v[22:23]
	s_waitcnt lgkmcnt(0)
	v_pk_mul_f32 v[26:27], v[30:31], v[20:21] op_sel_hi:[1,0]
	v_pk_mul_f32 v[16:17], v[36:37], v[20:21] op_sel_hi:[1,0]
	v_pk_fma_f32 v[26:27], v[146:147], v[26:27], v[134:135]
	v_pk_mul_f32 v[18:19], v[38:39], v[20:21] op_sel_hi:[1,0]
	v_pk_mul_f32 v[24:25], v[28:29], v[20:21] op_sel_hi:[1,0]
	v_cndmask_b32_e32 v21, v156, v26, vcc
	v_pk_mul_f32 v[0:1], v[0:1], v[20:21] op_sel_hi:[1,0]
	v_pk_mul_f32 v[2:3], v[2:3], v[20:21] op_sel_hi:[1,0]
	v_pk_fma_f32 v[18:19], v[152:153], v[18:19], v[142:143]
	v_pk_fma_f32 v[16:17], v[154:155], v[16:17], v[140:141]
	v_pk_mul_f32 v[4:5], v[4:5], v[20:21] op_sel_hi:[1,0]
	v_pk_mul_f32 v[6:7], v[6:7], v[20:21] op_sel_hi:[1,0]
	v_pk_fma_f32 v[2:3], v[8:9], v[2:3], v[138:139]
	v_pk_fma_f32 v[0:1], v[10:11], v[0:1], v[136:137]
	v_pk_fma_f32 v[24:25], v[150:151], v[24:25], v[132:133]
	v_cndmask_b32_e32 v18, v156, v18, vcc
	v_cndmask_b32_e32 v19, v156, v19, vcc
	v_cndmask_b32_e32 v16, v156, v16, vcc
	v_cndmask_b32_e32 v17, v156, v17, vcc
	v_lshl_add_u64 v[22:23], v[22:23], 0, v[148:149]
	v_pk_fma_f32 v[6:7], v[12:13], v[6:7], v[130:131]
	v_pk_fma_f32 v[4:5], v[14:15], v[4:5], v[128:129]
	v_cndmask_b32_e32 v8, v156, v2, vcc
	v_cndmask_b32_e32 v3, v156, v3, vcc
	v_cndmask_b32_e32 v2, v156, v0, vcc
	v_cndmask_b32_e32 v26, v156, v27, vcc
	v_cndmask_b32_e32 v24, v156, v24, vcc
	v_cndmask_b32_e32 v25, v156, v25, vcc
	v_cvt_pk_bf16_f32 v16, v16, v17
	v_cvt_pk_bf16_f32 v17, v18, v19
	v_cvt_pk_bf16_f32 v18, v24, v25
	v_cvt_pk_bf16_f32 v19, v21, v26
	global_store_dwordx4 v[22:23], v[16:19], off
	v_cndmask_b32_e32 v6, v156, v6, vcc
	v_cndmask_b32_e32 v7, v156, v7, vcc
	v_cndmask_b32_e32 v4, v156, v4, vcc
	v_cndmask_b32_e32 v5, v156, v5, vcc
	v_cndmask_b32_e32 v9, v156, v1, vcc
	v_cvt_pk_bf16_f32 v0, v4, v5
	v_cvt_pk_bf16_f32 v1, v6, v7
	v_cvt_pk_bf16_f32 v2, v2, v9
	v_cvt_pk_bf16_f32 v3, v8, v3
	global_store_dwordx4 v[22:23], v[0:3], off offset:256

;     __device__ __forceinline__ void operator()(const f32x4 (&acc)[2][2][4][2], const Unit& u, int wr, int wc, int fr, int fq) const {
;     ...
;             for (int m = 0; m < 4; ++m) { bf16_t* rowp = O + (size_t)(row0 + ai * HALF + m * 16) * ldc + col0;
;                 if (ACT == 1) {
;                     const int ob = fr * 64 + 16 * fq, sw = ob ^ (((ob >> 9) & 1) << 5);
;                     rowp = O + ((size_t)(u.pm * (ldc / 64) + u.pn * 4 + (wc >> 1)) * 2 + ai) * 8192 + (((wr * 4 + m) * 2 + (wc & 1)) * 1024 + sw) / 2; }
;                 float rc[2][2], rs[2][2];
;                 if (ACT == 2) { const float pos = (float)((row0 + ai * HALF + m * 16) & 2047);
; #pragma unroll
;                     for (int n = 0; n < 2; ++n)
; #pragma unroll
;                         for (int e = 0; e < 2; ++e) { float r = pos * rinv[n][e]; r -= floorf(r); rs[n][e] = do_rope ? __builtin_amdgcn_sinf(r) : 0.f; rc[n][e] = do_rope ? __builtin_amdgcn_cosf(r) : 1.f; } }
; #pragma unroll
;                 for (int bj = 0; bj < 2; ++bj) { f32x4 v0 = acc[ai][bj][m][0], v1 = acc[ai][bj][m][1];
;                     if (ACT == 3) { const float pos = (float)((row0 + ai * HALF + m * 16) & 2047); float c3[4], s3[4];
; #pragma unroll
;                         for (int p = 0; p < 4; ++p) { float r = pos * rinv3[bj][p]; r -= floorf(r); s3[p] = rope3[bj] ? __builtin_amdgcn_sinf(r) : 0.f; c3[p] = rope3[bj] ? __builtin_amdgcn_cosf(r) : 1.f; }
;                         const f32x4 a = v0, b = v1;
;                         v0[0] = a[0] * c3[0] - a[1] * s3[0]; v0[1] = a[1] * c3[0] + a[0] * s3[0]; v0[2] = a[2] * c3[1] - a[3] * s3[1]; v0[3] = a[3] * c3[1] + a[2] * s3[1];
;                         v1[0] = b[0] * c3[2] - b[1] * s3[2]; v1[1] = b[1] * c3[2] + b[0] * s3[2]; v1[2] = b[2] * c3[3] - b[3] * s3[3]; v1[3] = b[3] * c3[3] + b[2] * s3[3]; }
;                     if (ACT == 2) { const f32x4 a = v0, b = v1;
;                         v0[0] = a[0] * rc[0][0] - a[1] * rs[0][0]; v0[1] = a[1] * rc[0][0] + a[0] * rs[0][0]; v0[2] = a[2] * rc[0][1] - a[3] * rs[0][1]; v0[3] = a[3] * rc[0][1] + a[2] * rs[0][1];
;                         v1[0] = b[0] * rc[1][0] - b[1] * rs[1][0]; v1[1] = b[1] * rc[1][0] + b[0] * rs[1][0]; v1[2] = b[2] * rc[1][1] - b[3] * rs[1][1]; v1[3] = b[3] * rc[1][1] + b[2] * rs[1][1]; }
;                     if (ACT == 1) {
; #pragma unroll
.LBB0_2844:
	v_mov_b32_e32 v148, 0
	s_lshl_b32 s53, s53, 2
	v_mbcnt_lo_u32_b32 v148, -1, v148
	v_mbcnt_hi_u32_b32 v148, -1, v148
	v_or_b32_e32 v148, s33, v148
	s_or_b32 s53, s53, s49
	v_and_b32_e32 v149, 15, v148
	v_and_b32_e32 v150, 48, v148
	v_lshlrev_b32_e32 v148, 2, v148
	s_lshl_b32 s54, s70, 7
	v_lshl_or_b32 v149, v149, 6, v150
	v_and_b32_e32 v148, 32, v148
	s_add_i32 s54, s53, s54
	s_ashr_i32 s55, s54, 31
	v_bitop3_b32 v148, v149, s50, v148 bitop3:0xde
	s_lshl_b64 s[54:55], s[54:55], 15
	v_ashrrev_i32_e32 v148, 1, v148
	s_add_u32 s70, s41, s54
	v_ashrrev_i32_e32 v149, 31, v148
	s_addc_u32 s71, s42, s55
	v_lshlrev_b64 v[150:151], 1, v[148:149]
	v_max_i32_e32 v120, 0, v120
	v_max_i32_e32 v121, 0, v121
	v_max_i32_e32 v122, 0, v122
	v_max_i32_e32 v123, 0, v123
	v_max_i32_e32 v112, 0, v112
	v_max_i32_e32 v116, 0, v116
	v_max_i32_e32 v113, 0, v113
	v_max_i32_e32 v114, 0, v114
	v_lshl_add_u64 v[152:153], s[70:71], 0, v[150:151]
	v_max_i32_e32 v124, 0, v124
	v_mul_f32_e32 v120, v120, v120
	v_max_i32_e32 v125, 0, v125
	v_mul_f32_e32 v121, v121, v121
	v_max_i32_e32 v126, 0, v126
	v_mul_f32_e32 v122, v122, v122
	v_max_i32_e32 v127, 0, v127
	v_mul_f32_e32 v123, v123, v123
	v_mul_f32_e32 v112, v112, v112
	v_mul_f32_e32 v116, v116, v116
	v_max_i32_e32 v117, 0, v117
	v_mul_f32_e32 v113, v113, v113
	v_mul_f32_e32 v114, v114, v114
	v_max_i32_e32 v115, 0, v115
	v_mul_f32_e32 v124, v124, v124
	v_mul_f32_e32 v125, v125, v125
	v_mul_f32_e32 v126, v126, v126
	v_mul_f32_e32 v127, v127, v127
	v_cvt_pk_bf16_f32 v120, v120, v121
	v_cvt_pk_bf16_f32 v121, v122, v123
	v_cvt_pk_bf16_f32 v122, v124, v125
	v_cvt_pk_bf16_f32 v123, v126, v127
	global_store_dwordx4 v[152:153], v[120:123], off
	v_mul_f32_e32 v117, v117, v117
	v_mul_f32_e32 v115, v115, v115
	v_cvt_pk_bf16_f32 v112, v112, v113
	v_cvt_pk_bf16_f32 v113, v114, v115
	v_cvt_pk_bf16_f32 v114, v116, v117
	v_add_co_u32_e32 v116, vcc, s39, v152
	v_max_i32_e32 v104, 0, v104
	v_max_i32_e32 v105, 0, v105
	v_max_i32_e32 v106, 0, v106
	v_max_i32_e32 v107, 0, v107
	v_max_i32_e32 v96, 0, v96
	v_max_i32_e32 v118, 0, v118
	v_max_i32_e32 v119, 0, v119
	v_addc_co_u32_e32 v117, vcc, 0, v153, vcc
	v_max_i32_e32 v108, 0, v108
	v_mul_f32_e32 v104, v104, v104
	v_max_i32_e32 v109, 0, v109
	v_mul_f32_e32 v105, v105, v105
	v_max_i32_e32 v110, 0, v110
	v_mul_f32_e32 v106, v106, v106
	v_max_i32_e32 v111, 0, v111
	v_mul_f32_e32 v107, v107, v107
	v_mul_f32_e32 v96, v96, v96
	v_max_i32_e32 v97, 0, v97
	v_max_i32_e32 v98, 0, v98
	v_max_i32_e32 v99, 0, v99
	v_mul_f32_e32 v118, v118, v118
	v_mul_f32_e32 v119, v119, v119
	v_cvt_pk_bf16_f32 v115, v118, v119
	global_store_dwordx4 v[116:117], v[112:115], off
	v_mul_f32_e32 v108, v108, v108
	v_mul_f32_e32 v109, v109, v109
	v_mul_f32_e32 v110, v110, v110
	v_mul_f32_e32 v111, v111, v111
	v_cvt_pk_bf16_f32 v104, v104, v105
	v_cvt_pk_bf16_f32 v105, v106, v107
	v_cvt_pk_bf16_f32 v106, v108, v109
	v_cvt_pk_bf16_f32 v107, v110, v111
	global_store_dwordx4 v[152:153], v[104:107], off offset:2048
	v_max_i32_e32 v100, 0, v100
	v_max_i32_e32 v101, 0, v101
	v_mul_f32_e32 v97, v97, v97
	v_max_i32_e32 v102, 0, v102
	v_mul_f32_e32 v98, v98, v98
	v_max_i32_e32 v103, 0, v103
	v_mul_f32_e32 v99, v99, v99
	v_cvt_pk_bf16_f32 v96, v96, v97
	v_mul_f32_e32 v100, v100, v100
	v_mul_f32_e32 v101, v101, v101
	v_mul_f32_e32 v102, v102, v102
	v_mul_f32_e32 v103, v103, v103
	v_cvt_pk_bf16_f32 v97, v98, v99
	v_cvt_pk_bf16_f32 v98, v100, v101
	v_cvt_pk_bf16_f32 v99, v102, v103
	global_store_dwordx4 v[116:117], v[96:99], off offset:2048
	v_max_i32_e32 v88, 0, v88
	v_max_i32_e32 v89, 0, v89
	v_or_b32_e32 v96, 0x800, v148
	v_ashrrev_i32_e32 v97, 31, v96
	v_lshlrev_b64 v[96:97], 1, v[96:97]
	v_max_i32_e32 v90, 0, v90
	v_max_i32_e32 v91, 0, v91
	v_max_i32_e32 v80, 0, v80
	v_max_i32_e32 v84, 0, v84
	v_max_i32_e32 v81, 0, v81
	v_max_i32_e32 v82, 0, v82
	v_lshl_add_u64 v[98:99], s[70:71], 0, v[96:97]
	v_max_i32_e32 v92, 0, v92
	v_mul_f32_e32 v88, v88, v88
	v_max_i32_e32 v93, 0, v93
	v_mul_f32_e32 v89, v89, v89
	v_max_i32_e32 v94, 0, v94
	v_mul_f32_e32 v90, v90, v90
	v_max_i32_e32 v95, 0, v95
	v_mul_f32_e32 v91, v91, v91
	v_mul_f32_e32 v80, v80, v80
	v_mul_f32_e32 v84, v84, v84
	v_max_i32_e32 v85, 0, v85
	v_mul_f32_e32 v81, v81, v81
	v_mul_f32_e32 v82, v82, v82
	v_max_i32_e32 v83, 0, v83
	v_mul_f32_e32 v92, v92, v92
	v_mul_f32_e32 v93, v93, v93
	v_mul_f32_e32 v94, v94, v94
	v_mul_f32_e32 v95, v95, v95
	v_cvt_pk_bf16_f32 v88, v88, v89
	v_cvt_pk_bf16_f32 v89, v90, v91
	v_cvt_pk_bf16_f32 v90, v92, v93
	v_cvt_pk_bf16_f32 v91, v94, v95
	global_store_dwordx4 v[98:99], v[88:91], off
	v_mul_f32_e32 v85, v85, v85
	v_mul_f32_e32 v83, v83, v83
	v_cvt_pk_bf16_f32 v80, v80, v81
	v_cvt_pk_bf16_f32 v81, v82, v83
	v_cvt_pk_bf16_f32 v82, v84, v85
	v_add_co_u32_e32 v84, vcc, s39, v98
	v_max_i32_e32 v86, 0, v86
	v_max_i32_e32 v87, 0, v87
	v_addc_co_u32_e32 v85, vcc, 0, v99, vcc
	v_mul_f32_e32 v86, v86, v86
	v_mul_f32_e32 v87, v87, v87
	v_cvt_pk_bf16_f32 v83, v86, v87
	global_store_dwordx4 v[84:85], v[80:83], off
	v_max_i32_e32 v64, 0, v64
	v_max_i32_e32 v65, 0, v65
	v_or_b32_e32 v80, 0xc00, v148
	v_ashrrev_i32_e32 v81, 31, v80
	v_lshlrev_b64 v[80:81], 1, v[80:81]
	v_max_i32_e32 v66, 0, v66
	v_max_i32_e32 v67, 0, v67
	v_max_i32_e32 v48, 0, v48
	v_max_i32_e32 v52, 0, v52
	v_max_i32_e32 v49, 0, v49
	v_max_i32_e32 v50, 0, v50
	v_lshl_add_u64 v[82:83], s[70:71], 0, v[80:81]
	v_max_i32_e32 v68, 0, v68
	v_mul_f32_e32 v64, v64, v64
	v_max_i32_e32 v69, 0, v69
	v_mul_f32_e32 v65, v65, v65
	v_max_i32_e32 v70, 0, v70
	v_mul_f32_e32 v66, v66, v66
	v_max_i32_e32 v71, 0, v71
	v_mul_f32_e32 v67, v67, v67
	v_mul_f32_e32 v48, v48, v48
	v_mul_f32_e32 v52, v52, v52
; __device__ __forceinline__ unsigned cvt_pk_bf16(float lo, float hi) { unsigned r; asm volatile("v_cvt_pk_bf16_f32 %0, %1, %2" : "=v"(r) : "v"(lo), "v"(hi)); return r; }
; #define PG8_BAR __builtin_amdgcn_s_barrier()
;     __device__ __forceinline__ void operator()(const f32x4 (&acc)[2][2][4][2], const Unit& u, int wr, int wc, int fr, int fq) const {
;     ...
;                     if (ACT == 1) {
; #pragma unroll
;                         for (int j = 0; j < 4; ++j) { const float a = __int_as_float(max(__float_as_int(v0[j]), 0)), b = __int_as_float(max(__float_as_int(v1[j]), 0)); v0[j] = a * a; v1[j] = b * b; } }
;                     u32x4 w; w.x = cvt_pk_bf16(v0[0], v0[1]); w.y = cvt_pk_bf16(v0[2], v0[3]); w.z = cvt_pk_bf16(v1[0], v1[1]); w.w = cvt_pk_bf16(v1[2], v1[3]);
;                     *(u32x4*)(rowp + (ACT == 1 ? bj * 2 * 2 * 8192 : bj * HALF)) = w; } }
; template <class Epi, class Sched, bool ALIGN_EPI = false, bool SP2 = false, bool A_TILED = false>
; __device__ __forceinline__ void gemm_phase(PG8_LAS unsigned char* lds, const Gemm g, const Sched& S, const Epi& E, const int wave_s) {
;     ...
;         if (!has_next) break;
;         cur = nxt; cA = nA; cB = nB; ++ui;
;         if constexpr (ALIGN_EPI) { if (wr == 1) PG8_BAR; }
	v_max_i32_e32 v53, 0, v53
	v_mul_f32_e32 v49, v49, v49
	v_mul_f32_e32 v50, v50, v50
	v_max_i32_e32 v51, 0, v51
	v_mul_f32_e32 v68, v68, v68
	v_mul_f32_e32 v69, v69, v69
	v_mul_f32_e32 v70, v70, v70
	v_mul_f32_e32 v71, v71, v71
	v_cvt_pk_bf16_f32 v64, v64, v65
	v_cvt_pk_bf16_f32 v65, v66, v67
	v_cvt_pk_bf16_f32 v66, v68, v69
	v_cvt_pk_bf16_f32 v67, v70, v71
	global_store_dwordx4 v[82:83], v[64:67], off
	v_mul_f32_e32 v53, v53, v53
	v_mul_f32_e32 v51, v51, v51
	v_cvt_pk_bf16_f32 v48, v48, v49
	v_cvt_pk_bf16_f32 v49, v50, v51
	v_cvt_pk_bf16_f32 v50, v52, v53
	v_add_co_u32_e32 v52, vcc, s39, v82
	v_max_i32_e32 v54, 0, v54
	v_max_i32_e32 v55, 0, v55
	v_addc_co_u32_e32 v53, vcc, 0, v83, vcc
	v_mul_f32_e32 v54, v54, v54
	v_mul_f32_e32 v55, v55, v55
	v_cvt_pk_bf16_f32 v51, v54, v55
	global_store_dwordx4 v[52:53], v[48:51], off
	s_add_u32 s70, s70, 0x4000
	s_addc_u32 s71, s71, 0
	v_max_i32_e32 v49, 0, v76
	v_max_i32_e32 v48, 0, v72
	v_mul_f32_e32 v50, v49, v49
	v_max_i32_e32 v49, 0, v73
	v_mul_f32_e32 v48, v48, v48
	v_max_i32_e32 v51, 0, v77
	v_mul_f32_e32 v49, v49, v49
	v_max_i32_e32 v54, 0, v74
	v_max_i32_e32 v64, 0, v75
	v_lshl_add_u64 v[52:53], s[70:71], 0, v[150:151]
	v_mul_f32_e32 v51, v51, v51
	v_max_i32_e32 v55, 0, v78
	v_mul_f32_e32 v54, v54, v54
	v_max_i32_e32 v65, 0, v79
	v_mul_f32_e32 v64, v64, v64
	v_cvt_pk_bf16_f32 v48, v48, v49
	v_cvt_pk_bf16_f32 v49, v54, v64
	v_mul_f32_e32 v55, v55, v55
	v_mul_f32_e32 v65, v65, v65
	v_cvt_pk_bf16_f32 v50, v50, v51
	v_cvt_pk_bf16_f32 v51, v55, v65
	global_store_dwordx4 v[52:53], v[48:51], off
	v_or_b32_e32 v112, 0x400, v148
	v_max_i32_e32 v54, 0, v58
	v_max_i32_e32 v49, 0, v60
	v_max_i32_e32 v48, 0, v56
	v_mul_f32_e32 v50, v49, v49
	v_max_i32_e32 v49, 0, v57
	v_mul_f32_e32 v48, v48, v48
	v_max_i32_e32 v51, 0, v61
	v_mul_f32_e32 v49, v49, v49
	v_max_i32_e32 v56, 0, v59
	v_add_co_u32_e32 v52, vcc, s39, v52
	v_ashrrev_i32_e32 v113, 31, v112
	v_mul_f32_e32 v51, v51, v51
	v_max_i32_e32 v55, 0, v62
	v_mul_f32_e32 v54, v54, v54
	v_max_i32_e32 v57, 0, v63
	v_mul_f32_e32 v56, v56, v56
	v_cvt_pk_bf16_f32 v48, v48, v49
	v_cvt_pk_bf16_f32 v49, v54, v56
	v_addc_co_u32_e32 v53, vcc, 0, v53, vcc
	v_max_i32_e32 v40, 0, v40
	v_max_i32_e32 v41, 0, v41
	v_max_i32_e32 v42, 0, v42
	v_max_i32_e32 v43, 0, v43
	v_max_i32_e32 v32, 0, v32
	v_max_i32_e32 v36, 0, v36
	v_max_i32_e32 v33, 0, v33
	v_max_i32_e32 v34, 0, v34
	v_mul_f32_e32 v55, v55, v55
	v_mul_f32_e32 v57, v57, v57
	v_cvt_pk_bf16_f32 v50, v50, v51
	v_cvt_pk_bf16_f32 v51, v55, v57
	global_store_dwordx4 v[52:53], v[48:51], off
	v_max_i32_e32 v44, 0, v44
	v_mul_f32_e32 v40, v40, v40
	v_lshl_add_u64 v[48:49], v[112:113], 1, s[70:71]
	v_max_i32_e32 v45, 0, v45
	v_mul_f32_e32 v41, v41, v41
	v_max_i32_e32 v46, 0, v46
	v_mul_f32_e32 v42, v42, v42
	v_max_i32_e32 v47, 0, v47
	v_mul_f32_e32 v43, v43, v43
	v_mul_f32_e32 v32, v32, v32
	v_mul_f32_e32 v36, v36, v36
	v_max_i32_e32 v37, 0, v37
	v_mul_f32_e32 v33, v33, v33
	v_mul_f32_e32 v34, v34, v34
	v_max_i32_e32 v35, 0, v35
	v_mul_f32_e32 v44, v44, v44
	v_mul_f32_e32 v45, v45, v45
	v_mul_f32_e32 v46, v46, v46
	v_mul_f32_e32 v47, v47, v47
	v_cvt_pk_bf16_f32 v40, v40, v41
	v_cvt_pk_bf16_f32 v41, v42, v43
	v_cvt_pk_bf16_f32 v42, v44, v45
	v_cvt_pk_bf16_f32 v43, v46, v47
	global_store_dwordx4 v[48:49], v[40:43], off
	v_mul_f32_e32 v37, v37, v37
	v_mul_f32_e32 v35, v35, v35
	v_cvt_pk_bf16_f32 v32, v32, v33
	v_cvt_pk_bf16_f32 v33, v34, v35
	v_cvt_pk_bf16_f32 v34, v36, v37
	v_add_co_u32_e32 v36, vcc, s39, v48
	v_max_i32_e32 v38, 0, v38
	v_max_i32_e32 v39, 0, v39
	v_addc_co_u32_e32 v37, vcc, 0, v49, vcc
	v_max_i32_e32 v24, 0, v24
	v_max_i32_e32 v25, 0, v25
	v_max_i32_e32 v26, 0, v26
	v_max_i32_e32 v27, 0, v27
	v_max_i32_e32 v16, 0, v16
	v_max_i32_e32 v20, 0, v20
	v_max_i32_e32 v17, 0, v17
	v_max_i32_e32 v18, 0, v18
	v_mul_f32_e32 v38, v38, v38
	v_mul_f32_e32 v39, v39, v39
	v_cvt_pk_bf16_f32 v35, v38, v39
	global_store_dwordx4 v[36:37], v[32:35], off
	v_max_i32_e32 v28, 0, v28
	v_mul_f32_e32 v24, v24, v24
	v_lshl_add_u64 v[32:33], s[70:71], 0, v[96:97]
	v_max_i32_e32 v29, 0, v29
	v_mul_f32_e32 v25, v25, v25
	v_max_i32_e32 v30, 0, v30
	v_mul_f32_e32 v26, v26, v26
	v_max_i32_e32 v31, 0, v31
	v_mul_f32_e32 v27, v27, v27
	v_mul_f32_e32 v16, v16, v16
	v_mul_f32_e32 v20, v20, v20
	v_max_i32_e32 v21, 0, v21
	v_mul_f32_e32 v17, v17, v17
	v_mul_f32_e32 v18, v18, v18
	v_max_i32_e32 v19, 0, v19
	v_mul_f32_e32 v28, v28, v28
	v_mul_f32_e32 v29, v29, v29
	v_mul_f32_e32 v30, v30, v30
	v_mul_f32_e32 v31, v31, v31
	v_cvt_pk_bf16_f32 v24, v24, v25
	v_cvt_pk_bf16_f32 v25, v26, v27
	v_cvt_pk_bf16_f32 v26, v28, v29
	v_cvt_pk_bf16_f32 v27, v30, v31
	global_store_dwordx4 v[32:33], v[24:27], off
	v_mul_f32_e32 v21, v21, v21
	v_mul_f32_e32 v19, v19, v19
	v_cvt_pk_bf16_f32 v16, v16, v17
	v_cvt_pk_bf16_f32 v17, v18, v19
	v_cvt_pk_bf16_f32 v18, v20, v21
	v_add_co_u32_e32 v20, vcc, s39, v32
	v_max_i32_e32 v22, 0, v22
	v_max_i32_e32 v23, 0, v23
	v_addc_co_u32_e32 v21, vcc, 0, v33, vcc
	v_max_i32_e32 v8, 0, v8
	v_max_i32_e32 v9, 0, v9
	v_max_i32_e32 v10, 0, v10
	v_max_i32_e32 v11, 0, v11
	v_max_i32_e32 v0, 0, v0
	v_max_i32_e32 v4, 0, v4
	v_max_i32_e32 v1, 0, v1
	v_max_i32_e32 v2, 0, v2
	v_mul_f32_e32 v22, v22, v22
	v_mul_f32_e32 v23, v23, v23
	v_cvt_pk_bf16_f32 v19, v22, v23
	global_store_dwordx4 v[20:21], v[16:19], off
	v_max_i32_e32 v12, 0, v12
	v_mul_f32_e32 v8, v8, v8
	v_lshl_add_u64 v[16:17], s[70:71], 0, v[80:81]
	v_max_i32_e32 v13, 0, v13
	v_mul_f32_e32 v9, v9, v9
	v_max_i32_e32 v14, 0, v14
	v_mul_f32_e32 v10, v10, v10
	v_max_i32_e32 v15, 0, v15
	v_mul_f32_e32 v11, v11, v11
	v_mul_f32_e32 v0, v0, v0
	v_mul_f32_e32 v4, v4, v4
	v_max_i32_e32 v5, 0, v5
	v_mul_f32_e32 v1, v1, v1
	v_mul_f32_e32 v2, v2, v2
	v_max_i32_e32 v3, 0, v3
	v_mul_f32_e32 v12, v12, v12
	v_mul_f32_e32 v13, v13, v13
	v_mul_f32_e32 v14, v14, v14
	v_mul_f32_e32 v15, v15, v15
	v_cvt_pk_bf16_f32 v8, v8, v9
	v_cvt_pk_bf16_f32 v9, v10, v11
	v_cvt_pk_bf16_f32 v10, v12, v13
	v_cvt_pk_bf16_f32 v11, v14, v15
	global_store_dwordx4 v[16:17], v[8:11], off
	v_mul_f32_e32 v5, v5, v5
	v_mul_f32_e32 v3, v3, v3
	v_cvt_pk_bf16_f32 v0, v0, v1
	v_cvt_pk_bf16_f32 v1, v2, v3
	v_cvt_pk_bf16_f32 v2, v4, v5
	v_add_co_u32_e32 v4, vcc, 0x10000, v16
	v_max_i32_e32 v6, 0, v6
	s_nop 0
	v_addc_co_u32_e32 v5, vcc, 0, v17, vcc
	v_max_i32_e32 v7, 0, v7
	s_andn2_b64 vcc, exec, s[2:3]
	s_mov_b64 s[2:3], -1
	v_mul_f32_e32 v6, v6, v6
	v_mul_f32_e32 v7, v7, v7
	v_cvt_pk_bf16_f32 v3, v6, v7
	global_store_dwordx4 v[4:5], v[0:3], off
	s_cbranch_vccnz .LBB0_2833
	s_andn2_b64 vcc, exec, s[6:7]
	s_cbranch_vccnz .LBB0_2832
	s_barrier
	s_branch .LBB0_2832

;     __device__ __forceinline__ void fused(f32x4 (&acc)[2][2][4][2], const Unit& un, int wr, int wc, int fr, int fq, PG8_LAS unsigned char* lds, int wid, int lane) const {
;     ...
;         const int row0 = un.pm * BM + wr * 64 + fr, col0 = un.pn * BM + wc * 32 + 8 * fq;
;         const size_t boff = (size_t)(un.pm >> 3) * bstride + col0;
;         { f32x4 gv[2][2];
; #pragma unroll
;           for (int bj = 0; bj < 2; ++bj)
; #pragma unroll
;               for (int n = 0; n < 2; ++n) gv[bj][n] = *(const f32x4*)(gate + boff + bj * HALF + n * 4);
; #pragma unroll
;           for (int ai = 0; ai < 2; ++ai)
; #pragma unroll
;               for (int m = 0; m < 4; ++m) { const size_t off = (size_t)(row0 + ai * HALF + m * 16) * ldc + col0;
; #pragma unroll
;                   for (int bj = 0; bj < 2; ++bj) {
; #pragma unroll
;                       for (int n = 0; n < 2; ++n) { f32x4 bs;
;                           if (BASE_F32) bs = *(const f32x4*)((const float*)base + off + bj * HALF + n * 4);
;                           else { const u32x2v hw = *(const u32x2v*)((const bf16_t*)base + off + bj * HALF + n * 4);
;                                  bs = (f32x4){__uint_as_float(hw.x << 16), __uint_as_float(hw.x & 0xffff0000u), __uint_as_float(hw.y << 16), __uint_as_float(hw.y & 0xffff0000u)}; }
;                           acc[ai][bj][m][n] = bs + gv[bj][n] * acc[ai][bj][m][n]; }
;                       if (out_h) { const f32x4 a0 = acc[ai][bj][m][0], a1 = acc[ai][bj][m][1]; u32x4 w; w.x = cvt_pk_bf16(a0[0], a0[1]); w.y = cvt_pk_bf16(a0[2], a0[3]); w.z = cvt_pk_bf16(a1[0], a1[1]); w.w = cvt_pk_bf16(a1[2], a1[3]);
;                           *(u32x4*)(out_h + off + bj * HALF) = w; } }
;                   asm volatile("" : "+v"(acc[ai][0][m][0]), "+v"(acc[ai][0][m][1]), "+v"(acc[ai][1][m][0]), "+v"(acc[ai][1][m][1]));
;                   asm volatile("" ::: "memory"); } }
; #pragma unroll
;         for (int ai = 0; ai < 2; ++ai)
; #pragma unroll
;             for (int m = 0; m < 4; ++m) { float s = 0.f;
; #pragma unroll
;                 for (int bj = 0; bj < 2; ++bj)
; #pragma unroll
;                     for (int n = 0; n < 2; ++n) { const f32x4 x = acc[ai][bj][m][n]; s += (x[0] * x[0] + x[1] * x[1]) + (x[2] * x[2] + x[3] * x[3]); }
;                 s += __shfl_xor(s, 16); s += __shfl_xor(s, 32);
.LBB0_2917:
	v_mov_b32_e32 v32, 0
	s_barrier
	s_lshl_b32 s6, s9, 5
	v_mbcnt_lo_u32_b32 v32, -1, v32
	s_add_u32 s2, s44, 0x1a600000
	v_mbcnt_hi_u32_b32 v32, -1, v32
	s_addc_u32 s3, s45, 0
	v_or_b32_e32 v158, s33, v32
	s_lshl_b32 s7, s4, 8
	s_lshl_b32 s14, s46, 8
	s_or_b32 s6, s7, s6
	v_lshrrev_b32_e32 v32, 1, v158
	v_and_b32_e32 v159, 15, v158
	s_add_i32 s15, s14, s8
	v_and_or_b32 v152, v32, 24, s6
	s_ashr_i32 s6, s46, 3
	v_ashrrev_i32_e32 v153, 31, v152
	v_mov_b32_e32 v32, 0x3000
	v_or_b32_e32 v156, s15, v159
	v_mad_i64_i32 v[32:33], s[6:7], s6, v32, v[152:153]
	v_ashrrev_i32_e32 v157, 31, v156
	v_lshl_add_u64 v[150:151], v[32:33], 2, s[44:45]
	v_lshlrev_b64 v[32:33], 12, v[156:157]
	v_lshl_add_u64 v[32:33], s[2:3], 0, v[32:33]
	v_lshlrev_b64 v[148:149], 1, v[152:153]
	s_mov_b32 s15, 0x16a000
	v_lshl_add_u64 v[154:155], v[32:33], 0, v[148:149]
	v_add_co_u32_e32 v132, vcc, s15, v150
	s_nop 0
	v_addc_co_u32_e32 v133, vcc, 0, v151, vcc
	s_mov_b64 s[6:7], 0x16a000
	global_load_dwordx4 v[144:147], v[132:133], off
	v_lshl_add_u64 v[132:133], v[150:151], 0, s[6:7]
	global_load_dwordx4 v[140:143], v[132:133], off offset:16
	global_load_dwordx4 v[136:139], v[132:133], off offset:512
	s_nop 0
	global_load_dwordx4 v[132:135], v[132:133], off offset:528
	v_or_b32_e32 v164, 16, v156
	v_ashrrev_i32_e32 v165, 31, v164
	v_lshlrev_b64 v[164:165], 12, v[164:165]
	v_lshl_add_u64 v[164:165], s[2:3], 0, v[164:165]
	v_lshl_add_u64 v[164:165], v[164:165], 0, v[148:149]
	s_mov_b64 s[98:99], 0x10000
	s_mov_b64 s[100:101], 0x80000
	v_lshl_add_u64 v[232:233], v[154:155], 0, 0
	v_lshl_add_u64 v[234:235], v[232:233], 0, s[98:99]
	v_lshl_add_u64 v[236:237], v[234:235], 0, s[98:99]
	v_lshl_add_u64 v[238:239], v[236:237], 0, s[98:99]
	global_load_dwordx4 v[200:203], v[232:233], off
	global_load_dwordx4 v[204:207], v[232:233], off offset:256
	global_load_dwordx4 v[208:211], v[234:235], off
	global_load_dwordx4 v[212:215], v[234:235], off offset:256
	global_load_dwordx4 v[216:219], v[236:237], off
	global_load_dwordx4 v[220:223], v[236:237], off offset:256
	global_load_dwordx4 v[224:227], v[238:239], off
	global_load_dwordx4 v[228:231], v[238:239], off offset:256
	s_waitcnt vmcnt(0) lgkmcnt(0)
	v_lshlrev_b32_e32 v160, 16, v200
	v_and_b32_e32 v161, 0xffff0000, v200
	v_lshlrev_b32_e32 v32, 16, v201
	v_and_b32_e32 v33, 0xffff0000, v201
	v_lshlrev_b32_e32 v162, 16, v202
	v_and_b32_e32 v163, 0xffff0000, v202
	v_lshlrev_b32_e32 v34, 16, v203
	v_and_b32_e32 v35, 0xffff0000, v203
	v_pk_fma_f32 v[10:11], v[10:11], v[146:147], v[32:33]
	v_pk_fma_f32 v[8:9], v[8:9], v[144:145], v[160:161]
	v_pk_fma_f32 v[14:15], v[14:15], v[142:143], v[34:35]
	v_pk_fma_f32 v[12:13], v[12:13], v[140:141], v[162:163]
	v_cvt_pk_bf16_f32 v32, v8, v9
	v_cvt_pk_bf16_f32 v33, v10, v11
	s_nop 0
	v_cvt_pk_bf16_f32 v34, v12, v13
	v_cvt_pk_bf16_f32 v35, v14, v15
	s_nop 0
	global_store_dwordx4 v[154:155], v[32:35], off
	s_nop 1
	s_nop 0
	v_lshlrev_b32_e32 v32, 16, v204
	v_and_b32_e32 v33, 0xffff0000, v204
	v_lshlrev_b32_e32 v34, 16, v205
	v_and_b32_e32 v35, 0xffff0000, v205
	v_lshlrev_b32_e32 v160, 16, v206
	v_and_b32_e32 v161, 0xffff0000, v206
	v_lshlrev_b32_e32 v162, 16, v207
	v_and_b32_e32 v163, 0xffff0000, v207
	v_pk_fma_f32 v[34:35], v[30:31], v[138:139], v[34:35]
	v_pk_fma_f32 v[32:33], v[28:29], v[136:137], v[32:33]
	v_pk_fma_f32 v[30:31], v[18:19], v[134:135], v[162:163]
	v_pk_fma_f32 v[28:29], v[16:17], v[132:133], v[160:161]
	v_cvt_pk_bf16_f32 v16, v32, v33
	v_cvt_pk_bf16_f32 v17, v34, v35
	s_nop 0
	v_cvt_pk_bf16_f32 v18, v28, v29
	v_cvt_pk_bf16_f32 v19, v30, v31
	global_store_dwordx4 v[154:155], v[16:19], off offset:256
	s_nop 1
	v_lshlrev_b32_e32 v160, 16, v208
	v_and_b32_e32 v161, 0xffff0000, v208
	v_lshlrev_b32_e32 v16, 16, v209
	v_and_b32_e32 v17, 0xffff0000, v209
	v_lshlrev_b32_e32 v162, 16, v210
	v_and_b32_e32 v163, 0xffff0000, v210
	v_lshlrev_b32_e32 v166, 16, v211
	v_and_b32_e32 v167, 0xffff0000, v211
	v_pk_fma_f32 v[18:19], v[62:63], v[146:147], v[16:17]
	v_pk_fma_f32 v[16:17], v[60:61], v[144:145], v[160:161]
	v_pk_fma_f32 v[22:23], v[22:23], v[142:143], v[166:167]
	v_pk_fma_f32 v[20:21], v[20:21], v[140:141], v[162:163]
	v_cvt_pk_bf16_f32 v60, v16, v17
	v_cvt_pk_bf16_f32 v61, v18, v19
	v_or_b32_e32 v166, 32, v156
	v_cvt_pk_bf16_f32 v62, v20, v21
	v_cvt_pk_bf16_f32 v63, v22, v23
	v_ashrrev_i32_e32 v167, 31, v166
	v_lshlrev_b64 v[166:167], 12, v[166:167]
	global_store_dwordx4 v[164:165], v[60:63], off
	v_lshl_add_u64 v[166:167], s[2:3], 0, v[166:167]
	v_lshl_add_u64 v[166:167], v[166:167], 0, v[148:149]
	v_or_b32_e32 v156, 48, v156
	v_ashrrev_i32_e32 v157, 31, v156
	v_lshlrev_b64 v[156:157], 12, v[156:157]
	v_lshl_add_u64 v[156:157], s[2:3], 0, v[156:157]
	v_lshl_add_u64 v[156:157], v[156:157], 0, v[148:149]
	s_mov_b32 s2, 0x80000
	s_nop 1
	v_lshlrev_b32_e32 v60, 16, v212
	v_and_b32_e32 v61, 0xffff0000, v212
	v_lshlrev_b32_e32 v62, 16, v213
	v_and_b32_e32 v63, 0xffff0000, v213
	v_lshlrev_b32_e32 v160, 16, v214
	v_and_b32_e32 v161, 0xffff0000, v214
	v_lshlrev_b32_e32 v162, 16, v215
	v_and_b32_e32 v163, 0xffff0000, v215
	v_pk_fma_f32 v[62:63], v[58:59], v[138:139], v[62:63]
	v_pk_fma_f32 v[60:61], v[56:57], v[136:137], v[60:61]
	v_pk_fma_f32 v[58:59], v[50:51], v[134:135], v[162:163]
	v_pk_fma_f32 v[56:57], v[48:49], v[132:133], v[160:161]
	v_cvt_pk_bf16_f32 v48, v60, v61
	v_cvt_pk_bf16_f32 v49, v62, v63
	s_nop 0
	v_cvt_pk_bf16_f32 v50, v56, v57
	v_cvt_pk_bf16_f32 v51, v58, v59
	global_store_dwordx4 v[164:165], v[48:51], off offset:256
	s_nop 1
	v_lshlrev_b32_e32 v160, 16, v216
	v_and_b32_e32 v161, 0xffff0000, v216
	v_lshlrev_b32_e32 v48, 16, v217
	v_and_b32_e32 v49, 0xffff0000, v217
; __device__ __forceinline__ unsigned cvt_pk_bf16(float lo, float hi) { unsigned r; asm volatile("v_cvt_pk_bf16_f32 %0, %1, %2" : "=v"(r) : "v"(lo), "v"(hi)); return r; }
;     __device__ __forceinline__ void fused(f32x4 (&acc)[2][2][4][2], const Unit& un, int wr, int wc, int fr, int fq, PG8_LAS unsigned char* lds, int wid, int lane) const {
;     ...
;           for (int ai = 0; ai < 2; ++ai)
; #pragma unroll
;               for (int m = 0; m < 4; ++m) { const size_t off = (size_t)(row0 + ai * HALF + m * 16) * ldc + col0;
; #pragma unroll
;                   for (int bj = 0; bj < 2; ++bj) {
; #pragma unroll
;                       for (int n = 0; n < 2; ++n) { f32x4 bs;
;                           if (BASE_F32) bs = *(const f32x4*)((const float*)base + off + bj * HALF + n * 4);
;                           else { const u32x2v hw = *(const u32x2v*)((const bf16_t*)base + off + bj * HALF + n * 4);
;                                  bs = (f32x4){__uint_as_float(hw.x << 16), __uint_as_float(hw.x & 0xffff0000u), __uint_as_float(hw.y << 16), __uint_as_float(hw.y & 0xffff0000u)}; }
;                           acc[ai][bj][m][n] = bs + gv[bj][n] * acc[ai][bj][m][n]; }
;                       if (out_h) { const f32x4 a0 = acc[ai][bj][m][0], a1 = acc[ai][bj][m][1]; u32x4 w; w.x = cvt_pk_bf16(a0[0], a0[1]); w.y = cvt_pk_bf16(a0[2], a0[3]); w.z = cvt_pk_bf16(a1[0], a1[1]); w.w = cvt_pk_bf16(a1[2], a1[3]);
;                           *(u32x4*)(out_h + off + bj * HALF) = w; } }
;                   asm volatile("" : "+v"(acc[ai][0][m][0]), "+v"(acc[ai][0][m][1]), "+v"(acc[ai][1][m][0]), "+v"(acc[ai][1][m][1]));
;                   asm volatile("" ::: "memory"); } }
	v_lshlrev_b32_e32 v162, 16, v218
	v_and_b32_e32 v163, 0xffff0000, v218
	v_lshlrev_b32_e32 v164, 16, v219
	v_and_b32_e32 v165, 0xffff0000, v219
	v_pk_fma_f32 v[50:51], v[78:79], v[146:147], v[48:49]
	v_pk_fma_f32 v[48:49], v[76:77], v[144:145], v[160:161]
	v_pk_fma_f32 v[54:55], v[54:55], v[142:143], v[164:165]
	v_pk_fma_f32 v[52:53], v[52:53], v[140:141], v[162:163]
	v_cvt_pk_bf16_f32 v76, v48, v49
	v_cvt_pk_bf16_f32 v77, v50, v51
	s_nop 0
	v_cvt_pk_bf16_f32 v78, v52, v53
	v_cvt_pk_bf16_f32 v79, v54, v55
	s_nop 0
	global_store_dwordx4 v[166:167], v[76:79], off
	s_nop 1
	s_nop 0
	v_lshlrev_b32_e32 v76, 16, v220
	v_and_b32_e32 v77, 0xffff0000, v220
	v_lshlrev_b32_e32 v78, 16, v221
	v_and_b32_e32 v79, 0xffff0000, v221
	v_lshlrev_b32_e32 v160, 16, v222
	v_and_b32_e32 v161, 0xffff0000, v222
	v_lshlrev_b32_e32 v162, 16, v223
	v_and_b32_e32 v163, 0xffff0000, v223
	v_pk_fma_f32 v[78:79], v[74:75], v[138:139], v[78:79]
	v_pk_fma_f32 v[76:77], v[72:73], v[136:137], v[76:77]
	v_pk_fma_f32 v[74:75], v[66:67], v[134:135], v[162:163]
	v_pk_fma_f32 v[72:73], v[64:65], v[132:133], v[160:161]
	v_cvt_pk_bf16_f32 v64, v76, v77
	v_cvt_pk_bf16_f32 v65, v78, v79
	s_nop 0
	v_cvt_pk_bf16_f32 v66, v72, v73
	v_cvt_pk_bf16_f32 v67, v74, v75
	global_store_dwordx4 v[166:167], v[64:67], off offset:256
	s_nop 1
	v_lshlrev_b32_e32 v160, 16, v224
	v_and_b32_e32 v161, 0xffff0000, v224
	v_lshlrev_b32_e32 v64, 16, v225
	v_and_b32_e32 v65, 0xffff0000, v225
	v_lshlrev_b32_e32 v162, 16, v226
	v_and_b32_e32 v163, 0xffff0000, v226
	v_lshlrev_b32_e32 v164, 16, v227
	v_and_b32_e32 v165, 0xffff0000, v227
	v_pk_fma_f32 v[66:67], v[130:131], v[146:147], v[64:65]
	v_pk_fma_f32 v[64:65], v[128:129], v[144:145], v[160:161]
	v_pk_fma_f32 v[70:71], v[70:71], v[142:143], v[164:165]
	v_pk_fma_f32 v[68:69], v[68:69], v[140:141], v[162:163]
	v_cvt_pk_bf16_f32 v128, v64, v65
	v_cvt_pk_bf16_f32 v129, v66, v67
	v_add_co_u32_e32 v164, vcc, s2, v154
	v_cvt_pk_bf16_f32 v130, v68, v69
	v_cvt_pk_bf16_f32 v131, v70, v71
	s_nop 0
	v_addc_co_u32_e32 v165, vcc, 0, v155, vcc
	global_store_dwordx4 v[156:157], v[128:131], off
	s_mov_b64 s[2:3], 0x80000
	s_nop 1
	v_lshlrev_b32_e32 v128, 16, v228
	v_and_b32_e32 v129, 0xffff0000, v228
	v_lshlrev_b32_e32 v130, 16, v229
	v_and_b32_e32 v131, 0xffff0000, v229
	v_lshlrev_b32_e32 v160, 16, v230
	v_and_b32_e32 v161, 0xffff0000, v230
	v_lshlrev_b32_e32 v162, 16, v231
	v_and_b32_e32 v163, 0xffff0000, v231
	v_pk_fma_f32 v[110:111], v[110:111], v[138:139], v[130:131]
	v_pk_fma_f32 v[108:109], v[108:109], v[136:137], v[128:129]
	v_pk_fma_f32 v[98:99], v[98:99], v[134:135], v[162:163]
	v_pk_fma_f32 v[96:97], v[96:97], v[132:133], v[160:161]
	v_cvt_pk_bf16_f32 v128, v108, v109
	v_cvt_pk_bf16_f32 v129, v110, v111
	s_nop 0
	v_cvt_pk_bf16_f32 v130, v96, v97
	v_cvt_pk_bf16_f32 v131, v98, v99
	global_store_dwordx4 v[156:157], v[128:131], off offset:256
	v_lshl_add_u64 v[156:157], v[154:155], 0, s[2:3]
	s_mov_b32 s2, 0x90000
	v_add_co_u32_e32 v166, vcc, s2, v154
	s_mov_b64 s[2:3], 0x90000
	s_nop 0
	v_addc_co_u32_e32 v167, vcc, 0, v155, vcc
	v_lshl_add_u64 v[232:233], v[232:233], 0, s[100:101]
	v_lshl_add_u64 v[234:235], v[234:235], 0, s[100:101]
	v_lshl_add_u64 v[236:237], v[236:237], 0, s[100:101]
	v_lshl_add_u64 v[238:239], v[238:239], 0, s[100:101]
	global_load_dwordx4 v[200:203], v[232:233], off
	global_load_dwordx4 v[204:207], v[232:233], off offset:256
	global_load_dwordx4 v[208:211], v[234:235], off
	global_load_dwordx4 v[212:215], v[234:235], off offset:256
	global_load_dwordx4 v[216:219], v[236:237], off
	global_load_dwordx4 v[220:223], v[236:237], off offset:256
	global_load_dwordx4 v[224:227], v[238:239], off
	global_load_dwordx4 v[228:231], v[238:239], off offset:256
	s_waitcnt vmcnt(0) lgkmcnt(0)
	v_lshlrev_b32_e32 v160, 16, v200
	v_and_b32_e32 v161, 0xffff0000, v200
	v_lshlrev_b32_e32 v128, 16, v201
	v_and_b32_e32 v129, 0xffff0000, v201
	v_lshlrev_b32_e32 v162, 16, v202
	v_and_b32_e32 v163, 0xffff0000, v202
	v_lshlrev_b32_e32 v130, 16, v203
	v_and_b32_e32 v131, 0xffff0000, v203
	v_pk_fma_f32 v[102:103], v[102:103], v[146:147], v[128:129]
	v_pk_fma_f32 v[100:101], v[100:101], v[144:145], v[160:161]
	v_pk_fma_f32 v[106:107], v[106:107], v[142:143], v[130:131]
	v_pk_fma_f32 v[104:105], v[104:105], v[140:141], v[162:163]
	v_cvt_pk_bf16_f32 v128, v100, v101
	v_cvt_pk_bf16_f32 v129, v102, v103
	s_nop 0
	v_cvt_pk_bf16_f32 v130, v104, v105
	v_cvt_pk_bf16_f32 v131, v106, v107
	s_nop 0
	global_store_dwordx4 v[164:165], v[128:131], off
	s_nop 1
	s_nop 0
	v_lshlrev_b32_e32 v128, 16, v204
	v_and_b32_e32 v129, 0xffff0000, v204
	v_lshlrev_b32_e32 v130, 16, v205
	v_and_b32_e32 v131, 0xffff0000, v205
	v_lshlrev_b32_e32 v160, 16, v206
	v_and_b32_e32 v161, 0xffff0000, v206
	v_lshlrev_b32_e32 v162, 16, v207
	v_and_b32_e32 v163, 0xffff0000, v207
	v_pk_fma_f32 v[126:127], v[126:127], v[138:139], v[130:131]
	v_pk_fma_f32 v[124:125], v[124:125], v[136:137], v[128:129]
	v_pk_fma_f32 v[114:115], v[114:115], v[134:135], v[162:163]
	v_pk_fma_f32 v[112:113], v[112:113], v[132:133], v[160:161]
	v_cvt_pk_bf16_f32 v128, v124, v125
	v_cvt_pk_bf16_f32 v129, v126, v127
	s_nop 0
	v_cvt_pk_bf16_f32 v130, v112, v113
	v_cvt_pk_bf16_f32 v131, v114, v115
	global_store_dwordx4 v[156:157], v[128:131], off offset:256
	v_lshl_add_u64 v[156:157], v[154:155], 0, s[2:3]
	s_mov_b32 s2, 0xa0000
	v_add_co_u32_e32 v164, vcc, s2, v154
	s_mov_b64 s[2:3], 0xa0000
	s_nop 0
	v_addc_co_u32_e32 v165, vcc, 0, v155, vcc
	s_nop 1
	v_lshlrev_b32_e32 v160, 16, v208
	v_and_b32_e32 v161, 0xffff0000, v208
	v_lshlrev_b32_e32 v128, 16, v209
	v_and_b32_e32 v129, 0xffff0000, v209
	v_lshlrev_b32_e32 v162, 16, v210
; __device__ __forceinline__ unsigned cvt_pk_bf16(float lo, float hi) { unsigned r; asm volatile("v_cvt_pk_bf16_f32 %0, %1, %2" : "=v"(r) : "v"(lo), "v"(hi)); return r; }
;     __device__ __forceinline__ void fused(f32x4 (&acc)[2][2][4][2], const Unit& un, int wr, int wc, int fr, int fq, PG8_LAS unsigned char* lds, int wid, int lane) const {
;     ...
;           for (int ai = 0; ai < 2; ++ai)
; #pragma unroll
;               for (int m = 0; m < 4; ++m) { const size_t off = (size_t)(row0 + ai * HALF + m * 16) * ldc + col0;
; #pragma unroll
;                   for (int bj = 0; bj < 2; ++bj) {
; #pragma unroll
;                       for (int n = 0; n < 2; ++n) { f32x4 bs;
;                           if (BASE_F32) bs = *(const f32x4*)((const float*)base + off + bj * HALF + n * 4);
;                           else { const u32x2v hw = *(const u32x2v*)((const bf16_t*)base + off + bj * HALF + n * 4);
;                                  bs = (f32x4){__uint_as_float(hw.x << 16), __uint_as_float(hw.x & 0xffff0000u), __uint_as_float(hw.y << 16), __uint_as_float(hw.y & 0xffff0000u)}; }
;                           acc[ai][bj][m][n] = bs + gv[bj][n] * acc[ai][bj][m][n]; }
;                       if (out_h) { const f32x4 a0 = acc[ai][bj][m][0], a1 = acc[ai][bj][m][1]; u32x4 w; w.x = cvt_pk_bf16(a0[0], a0[1]); w.y = cvt_pk_bf16(a0[2], a0[3]); w.z = cvt_pk_bf16(a1[0], a1[1]); w.w = cvt_pk_bf16(a1[2], a1[3]);
;                           *(u32x4*)(out_h + off + bj * HALF) = w; } }
;                   asm volatile("" : "+v"(acc[ai][0][m][0]), "+v"(acc[ai][0][m][1]), "+v"(acc[ai][1][m][0]), "+v"(acc[ai][1][m][1]));
;                   asm volatile("" ::: "memory"); } }
; #pragma unroll
;         for (int ai = 0; ai < 2; ++ai)
; #pragma unroll
;             for (int m = 0; m < 4; ++m) { float s = 0.f;
; #pragma unroll
;                 for (int bj = 0; bj < 2; ++bj)
; #pragma unroll
;                     for (int n = 0; n < 2; ++n) { const f32x4 x = acc[ai][bj][m][n]; s += (x[0] * x[0] + x[1] * x[1]) + (x[2] * x[2] + x[3] * x[3]); }
;                 s += __shfl_xor(s, 16); s += __shfl_xor(s, 32);
;                 if (fq == 0) P[(ai * HALF + wr * 64 + m * 16 + fr) * 4 + wc] = s; }
	v_and_b32_e32 v163, 0xffff0000, v210
	v_lshlrev_b32_e32 v130, 16, v211
	v_and_b32_e32 v131, 0xffff0000, v211
	v_pk_fma_f32 v[118:119], v[118:119], v[146:147], v[128:129]
	v_pk_fma_f32 v[116:117], v[116:117], v[144:145], v[160:161]
	v_pk_fma_f32 v[122:123], v[122:123], v[142:143], v[130:131]
	v_pk_fma_f32 v[120:121], v[120:121], v[140:141], v[162:163]
	v_cvt_pk_bf16_f32 v128, v116, v117
	v_cvt_pk_bf16_f32 v129, v118, v119
	s_nop 0
	v_cvt_pk_bf16_f32 v130, v120, v121
	v_cvt_pk_bf16_f32 v131, v122, v123
	s_nop 0
	global_store_dwordx4 v[166:167], v[128:131], off
	s_nop 1
	s_nop 0
	v_lshlrev_b32_e32 v128, 16, v212
	v_and_b32_e32 v129, 0xffff0000, v212
	v_lshlrev_b32_e32 v130, 16, v213
	v_and_b32_e32 v131, 0xffff0000, v213
	v_lshlrev_b32_e32 v160, 16, v214
	v_and_b32_e32 v161, 0xffff0000, v214
	v_lshlrev_b32_e32 v162, 16, v215
	v_and_b32_e32 v163, 0xffff0000, v215
	v_pk_fma_f32 v[94:95], v[94:95], v[138:139], v[130:131]
	v_pk_fma_f32 v[92:93], v[92:93], v[136:137], v[128:129]
	v_pk_fma_f32 v[90:91], v[90:91], v[134:135], v[162:163]
	v_pk_fma_f32 v[88:89], v[88:89], v[132:133], v[160:161]
	v_cvt_pk_bf16_f32 v128, v92, v93
	v_cvt_pk_bf16_f32 v129, v94, v95
	s_nop 0
	v_cvt_pk_bf16_f32 v130, v88, v89
	v_cvt_pk_bf16_f32 v131, v90, v91
	global_store_dwordx4 v[156:157], v[128:131], off offset:256
	v_lshl_add_u64 v[156:157], v[154:155], 0, s[2:3]
	s_mov_b32 s2, 0xb0000
	v_add_co_u32_e32 v166, vcc, s2, v154
	s_mov_b64 s[2:3], 0xb0000
	s_nop 0
	v_addc_co_u32_e32 v167, vcc, 0, v155, vcc
	s_nop 1
	v_lshlrev_b32_e32 v160, 16, v216
	v_and_b32_e32 v161, 0xffff0000, v216
	v_lshlrev_b32_e32 v128, 16, v217
	v_and_b32_e32 v129, 0xffff0000, v217
	v_lshlrev_b32_e32 v162, 16, v218
	v_and_b32_e32 v163, 0xffff0000, v218
	v_lshlrev_b32_e32 v130, 16, v219
	v_and_b32_e32 v131, 0xffff0000, v219
	v_pk_fma_f32 v[86:87], v[86:87], v[146:147], v[128:129]
	v_pk_fma_f32 v[84:85], v[84:85], v[144:145], v[160:161]
	v_pk_fma_f32 v[82:83], v[82:83], v[142:143], v[130:131]
	v_pk_fma_f32 v[80:81], v[80:81], v[140:141], v[162:163]
	v_cvt_pk_bf16_f32 v128, v84, v85
	v_cvt_pk_bf16_f32 v129, v86, v87
	s_nop 0
	v_cvt_pk_bf16_f32 v130, v80, v81
	v_cvt_pk_bf16_f32 v131, v82, v83
	s_nop 0
	global_store_dwordx4 v[164:165], v[128:131], off
	v_mul_f32_e32 v164, v29, v29
	v_mul_f32_e32 v165, v31, v31
	v_fmac_f32_e32 v164, v28, v28
	v_fmac_f32_e32 v165, v30, v30
	s_nop 1
	v_lshlrev_b32_e32 v128, 16, v220
	v_and_b32_e32 v129, 0xffff0000, v220
	v_lshlrev_b32_e32 v130, 16, v221
	v_and_b32_e32 v131, 0xffff0000, v221
	v_lshlrev_b32_e32 v160, 16, v222
	v_and_b32_e32 v161, 0xffff0000, v222
	v_lshlrev_b32_e32 v162, 16, v223
	v_and_b32_e32 v163, 0xffff0000, v223
	v_pk_fma_f32 v[46:47], v[46:47], v[138:139], v[130:131]
	v_pk_fma_f32 v[44:45], v[44:45], v[136:137], v[128:129]
	v_pk_fma_f32 v[42:43], v[42:43], v[134:135], v[162:163]
	v_pk_fma_f32 v[40:41], v[40:41], v[132:133], v[160:161]
	v_cvt_pk_bf16_f32 v128, v44, v45
	v_cvt_pk_bf16_f32 v129, v46, v47
	v_lshl_add_u64 v[160:161], v[154:155], 0, s[2:3]
	v_cvt_pk_bf16_f32 v130, v40, v41
	v_cvt_pk_bf16_f32 v131, v42, v43
	global_store_dwordx4 v[156:157], v[128:131], off offset:256
	v_mul_f32_e32 v162, v33, v33
	v_mul_f32_e32 v163, v35, v35
	v_fmac_f32_e32 v162, v32, v32
	v_fmac_f32_e32 v163, v34, v34
	s_lshl_b32 s2, s9, 2
	s_add_i32 s2, s2, 0
	s_nop 1
	v_lshlrev_b32_e32 v154, 16, v224
	v_and_b32_e32 v155, 0xffff0000, v224
	v_lshlrev_b32_e32 v128, 16, v225
	v_and_b32_e32 v129, 0xffff0000, v225
	v_lshlrev_b32_e32 v156, 16, v226
	v_and_b32_e32 v157, 0xffff0000, v226
	v_lshlrev_b32_e32 v130, 16, v227
	v_and_b32_e32 v131, 0xffff0000, v227
	v_pk_fma_f32 v[38:39], v[38:39], v[146:147], v[128:129]
	v_pk_fma_f32 v[36:37], v[36:37], v[144:145], v[154:155]
	v_pk_fma_f32 v[26:27], v[26:27], v[142:143], v[130:131]
	v_pk_fma_f32 v[24:25], v[24:25], v[140:141], v[156:157]
	v_cvt_pk_bf16_f32 v142, v36, v37
	v_cvt_pk_bf16_f32 v143, v38, v39
	v_mbcnt_lo_u32_b32 v128, -1, 0
	v_cvt_pk_bf16_f32 v144, v24, v25
	v_cvt_pk_bf16_f32 v145, v26, v27
	v_mbcnt_hi_u32_b32 v129, -1, v128
	v_mul_f32_e32 v140, v9, v9
	v_mul_f32_e32 v141, v11, v11
	v_mul_f32_e32 v146, v13, v13
	v_mul_f32_e32 v147, v15, v15
	v_and_b32_e32 v130, 64, v129
	v_fmac_f32_e32 v140, v8, v8
	v_fmac_f32_e32 v141, v10, v10
	v_fmac_f32_e32 v146, v12, v12
	v_fmac_f32_e32 v147, v14, v14
	v_xor_b32_e32 v128, 16, v129
	v_add_u32_e32 v130, 64, v130
	v_add_f32_e32 v140, v140, v141
	v_add_f32_e32 v141, v146, v147
	v_cmp_lt_i32_e32 vcc, v128, v130
	v_add_f32_e32 v146, v162, v163
	v_add_f32_e32 v140, v140, v141
	v_cndmask_b32_e32 v128, v129, v128, vcc
	v_add_f32_e32 v147, v164, v165
	v_add_f32_e32 v140, v146, v140
	v_lshlrev_b32_e32 v128, 2, v128
	v_add_f32_e32 v140, v147, v140
	ds_bpermute_b32 v141, v128, v140
	v_xor_b32_e32 v131, 32, v129
	v_cmp_lt_i32_e32 vcc, v131, v130
	global_store_dwordx4 v[166:167], v[142:145], off
	v_and_b32_e32 v130, 63, v158
	v_cndmask_b32_e32 v129, v129, v131, vcc
	v_lshlrev_b32_e32 v129, 2, v129
	s_waitcnt lgkmcnt(0)
	v_add_f32_e32 v140, v140, v141
	ds_bpermute_b32 v141, v129, v140
	v_cmp_gt_u32_e32 vcc, 16, v130
	s_waitcnt vmcnt(0)
	v_lshlrev_b32_e32 v142, 16, v228
	v_and_b32_e32 v143, 0xffff0000, v228
	v_lshlrev_b32_e32 v144, 16, v229
	v_and_b32_e32 v145, 0xffff0000, v229
	v_lshlrev_b32_e32 v146, 16, v230
	v_and_b32_e32 v147, 0xffff0000, v230
	v_lshlrev_b32_e32 v154, 16, v231
	v_and_b32_e32 v155, 0xffff0000, v231
	v_pk_fma_f32 v[6:7], v[6:7], v[138:139], v[144:145]
	v_pk_fma_f32 v[4:5], v[4:5], v[136:137], v[142:143]
	v_pk_fma_f32 v[2:3], v[2:3], v[134:135], v[154:155]
	v_pk_fma_f32 v[0:1], v[0:1], v[132:133], v[146:147]
	v_cvt_pk_bf16_f32 v132, v4, v5
	v_cvt_pk_bf16_f32 v133, v6, v7
	v_or_b32_e32 v144, s8, v159
	v_cvt_pk_bf16_f32 v134, v0, v1
	v_cvt_pk_bf16_f32 v135, v2, v3
	global_store_dwordx4 v[160:161], v[132:135], off offset:256
	v_lshl_add_u32 v131, v144, 4, s2
	s_and_saveexec_b64 s[2:3], vcc
	v_readlane_b32 s96, v254, 47
	s_cbranch_execz .LBB0_2919
	s_waitcnt lgkmcnt(0)
	v_add_f32_e32 v132, v140, v141
	ds_write_b32 v131, v132

;     __device__ __forceinline__ void fused(f32x4 (&acc)[2][2][4][2], const Unit& un, int wr, int wc, int fr, int fq, PG8_LAS unsigned char* lds, int wid, int lane) const {
;     ...
;         asm volatile("s_waitcnt lgkmcnt(0)" ::: "memory"); __builtin_amdgcn_s_barrier(); asm volatile("" ::: "memory");
;         const int row = wid * 32 + (lane & 31);
;         if (lane < 32) { const float tot = (P[row * 4 + 0] + P[row * 4 + 1]) + (P[row * 4 + 2] + P[row * 4 + 3]);
;             __hip_atomic_store(xbuf + ((size_t)(un.pm * BM + row) * 8 + un.pn), __float_as_uint(tot), __ATOMIC_RELAXED, __HIP_MEMORY_SCOPE_AGENT); }
.LBB0_2933:
	s_or_b64 exec, exec, s[2:3]
	s_add_u32 s60, s44, 0x3c740000
	s_addc_u32 s61, s45, 0
	s_lshl_b32 s1, s1, 5
	s_waitcnt lgkmcnt(0)
	s_barrier
	v_and_or_b32 v134, v158, 31, s1
	v_add_u32_e32 v128, s14, v134
	v_cmp_gt_u32_e64 s[2:3], 32, v130
	s_waitcnt lgkmcnt(0)
	v_ashrrev_i32_e32 v129, 31, v128
	s_and_saveexec_b64 s[6:7], s[2:3]
	s_cbranch_execz .LBB0_2935
	v_lshl_add_u32 v131, v134, 4, 0
	ds_read_b128 v[136:139], v131
	v_lshlrev_b64 v[132:133], 5, v[128:129]
	v_lshl_add_u64 v[132:133], s[60:61], 0, v[132:133]
	v_lshl_add_u64 v[132:133], s[4:5], 2, v[132:133]
	s_waitcnt lgkmcnt(0)
	v_mov_b32_e32 v140, v137
	v_mov_b32_e32 v141, v138
	v_mov_b32_e32 v137, v139
	v_pk_add_f32 v[136:137], v[140:141], v[136:137]
	s_nop 0
	v_pk_add_f32 v[136:137], v[136:137], v[136:137] op_sel:[0,1] op_sel_hi:[1,0]
	global_store_dword v[132:133], v136, off sc1

;     __device__ __forceinline__ void fused(f32x4 (&acc)[2][2][4][2], const Unit& un, int wr, int wc, int fr, int fq, PG8_LAS unsigned char* lds, int wid, int lane) const {
;     ...
;                 if (__builtin_amdgcn_s_memrealtime() - t0 > 2000000ull) {
;                     if (lane == 0) { unsigned expect = 0u; __hip_atomic_compare_exchange_strong(tmo + 1, &expect, code | (unsigned)(un.pm & 0xff), __ATOMIC_RELAXED, __ATOMIC_RELAXED, __HIP_MEMORY_SCOPE_AGENT);
;                                      __hip_atomic_store(tmo, 1u, __ATOMIC_RELAXED, __HIP_MEMORY_SCOPE_AGENT); }
;                     dead = true; break; }
.LBB0_2947:
	s_or_saveexec_b64 s[62:63], s[6:7]
	s_mov_b64 s[6:7], 0
	s_xor_b64 exec, exec, s[62:63]
	s_cbranch_execz .LBB0_2949
	s_and_b32 s0, s46, 0xaf
	s_or_b32 s0, s0, 0x750
	v_mov_b32_e32 v130, s0
	v_mov_b32_e32 v131, 0
	v_mov_b64_e32 v[132:133], s[44:45]
	flat_atomic_cmpswap v[132:133], v[130:131] offset:4
	s_mov_b64 s[6:7], exec
	v_mov_b32_e32 v130, 1
	global_store_dword v[132:133], v130, off sc1

; __device__ __forceinline__ unsigned cvt_pk_bf16(float lo, float hi) { unsigned r; asm volatile("v_cvt_pk_bf16_f32 %0, %1, %2" : "=v"(r) : "v"(lo), "v"(hi)); return r; }
;     __device__ __forceinline__ void fused(f32x4 (&acc)[2][2][4][2], const Unit& un, int wr, int wc, int fr, int fq, PG8_LAS unsigned char* lds, int wid, int lane) const {
;     ...
;         asm volatile("s_waitcnt lgkmcnt(0)" ::: "memory"); __builtin_amdgcn_s_barrier(); asm volatile("" ::: "memory");
;         const float qnan = __builtin_nanf("");
;         f32x4 cg[2][2], sh[2][2];
; #pragma unroll
;         for (int bj = 0; bj < 2; ++bj)
; #pragma unroll
;             for (int n = 0; n < 2; ++n) { const f32x4 g4 = *(const f32x4*)(gain + col0 + bj * HALF + n * 4);
;                 if (MODE == 0) { const f32x4 sc4 = *(const f32x4*)(scale + boff + bj * HALF + n * 4); cg[bj][n] = g4 * (sc4 + 1.0f); sh[bj][n] = *(const f32x4*)(shift + boff + bj * HALF + n * 4); }
;                 else { cg[bj][n] = g4; sh[bj][n] = (f32x4){0.f, 0.f, 0.f, 0.f}; } }
; #pragma unroll
;         for (int ai = 0; ai < 2; ++ai)
; #pragma unroll
;             for (int m = 0; m < 4; ++m) { const int r = ai * HALF + wr * 64 + m * 16 + fr; const float rs = S[r]; const size_t off = (size_t)(un.pm * BM + r) * ldc + col0;
; #pragma unroll
;                 for (int bj = 0; bj < 2; ++bj) { f32x4 y0 = (acc[ai][bj][m][0] * rs) * cg[bj][0] + sh[bj][0], y1 = (acc[ai][bj][m][1] * rs) * cg[bj][1] + sh[bj][1];
;                     if (bad) { y0 = (f32x4){qnan, qnan, qnan, qnan}; y1 = y0; }
;                     if (MODE == 0) { u32x4 w; w.x = cvt_pk_bf16(y0[0], y0[1]); w.y = cvt_pk_bf16(y0[2], y0[3]); w.z = cvt_pk_bf16(y1[0], y1[1]); w.w = cvt_pk_bf16(y1[2], y1[3]); *(u32x4*)(u + off + bj * HALF) = w; }
.LBB0_2957:
	s_or_b64 exec, exec, s[4:5]
	v_readlane_b32 s48, v254, 11
	v_readlane_b32 s52, v254, 15
	v_readlane_b32 s53, v254, 16
	s_mov_b64 s[0:1], 0x6000
	s_waitcnt lgkmcnt(0)
	s_barrier
	v_lshl_add_u64 v[128:129], v[152:153], 2, s[52:53]
	v_lshl_add_u64 v[130:131], v[128:129], 0, s[0:1]
	s_mov_b64 s[0:1], 0x192000
	v_lshl_add_u64 v[136:137], v[150:151], 0, s[0:1]
	s_mov_b64 s[0:1], 0x190000
	v_lshl_add_u64 v[138:139], v[150:151], 0, s[0:1]
	s_movk_i32 s0, 0x6000
	v_add_co_u32_e32 v128, vcc, s0, v128
	s_mov_b32 s0, 0x192000
	s_nop 0
	v_addc_co_u32_e32 v129, vcc, 0, v129, vcc
	global_load_dwordx4 v[160:163], v[128:129], off
	global_load_dwordx4 v[152:155], v[136:137], off offset:16
	v_add_co_u32_e32 v128, vcc, s0, v150
	global_load_dwordx4 v[164:167], v[136:137], off offset:512
	global_load_dwordx4 v[132:135], v[138:139], off offset:16
	global_load_dwordx4 v[168:171], v[136:137], off offset:528
	global_load_dwordx4 v[172:175], v[130:131], off offset:16
	global_load_dwordx4 v[176:179], v[130:131], off offset:512
	v_addc_co_u32_e32 v129, vcc, 0, v151, vcc
	global_load_dwordx4 v[180:183], v[130:131], off offset:528
	global_load_dwordx4 v[184:187], v[128:129], off
	s_mov_b32 s0, 0x190000
	v_add_co_u32_e32 v128, vcc, s0, v150
	v_lshl_add_u32 v157, v144, 2, 0
	s_nop 0
	v_addc_co_u32_e32 v129, vcc, 0, v151, vcc
	global_load_dwordx4 v[140:143], v[128:129], off
	s_nop 0
	global_load_dwordx4 v[128:131], v[138:139], off offset:512
	s_nop 0
	global_load_dwordx4 v[136:139], v[138:139], off offset:528
	ds_read_b32 v188, v157 offset:4096
	v_add_u32_e32 v144, s14, v144
	s_add_u32 s2, s44, 0x1e600000
	v_ashrrev_i32_e32 v145, 31, v144
	s_addc_u32 s3, s45, 0
	v_lshlrev_b64 v[146:147], 12, v[144:145]
	s_waitcnt lgkmcnt(0)
	v_pk_mul_f32 v[192:193], v[8:9], v[188:189] op_sel_hi:[1,0]
	v_pk_mul_f32 v[194:195], v[10:11], v[188:189] op_sel_hi:[1,0]
	v_lshl_add_u64 v[190:191], s[2:3], 0, v[146:147]
	v_pk_mul_f32 v[196:197], v[12:13], v[188:189] op_sel_hi:[1,0]
	v_pk_mul_f32 v[198:199], v[14:15], v[188:189] op_sel_hi:[1,0]
	v_mov_b32_e32 v156, 0x7fc00000
	v_cmp_eq_u32_e32 vcc, 0, v158
	v_pk_mul_f32 v[28:29], v[28:29], v[188:189] op_sel_hi:[1,0]
	v_pk_mul_f32 v[30:31], v[30:31], v[188:189] op_sel_hi:[1,0]
	v_pk_mul_f32 v[32:33], v[32:33], v[188:189] op_sel_hi:[1,0]
	v_pk_mul_f32 v[34:35], v[34:35], v[188:189] op_sel_hi:[1,0]
	v_readlane_b32 s49, v254, 12
	v_readlane_b32 s50, v254, 13
	v_readlane_b32 s51, v254, 14
	v_readlane_b32 s54, v254, 17
	v_readlane_b32 s55, v254, 18
	v_readlane_b32 s56, v254, 19
	v_readlane_b32 s57, v254, 20
	v_readlane_b32 s58, v254, 21
	v_readlane_b32 s59, v254, 22
	v_readlane_b32 s60, v254, 23
	v_readlane_b32 s61, v254, 24
	v_readlane_b32 s62, v254, 25
	v_readlane_b32 s63, v254, 26
	s_waitcnt vmcnt(0)
	v_pk_add_f32 v[12:13], v[166:167], 1.0 op_sel_hi:[1,0]
	v_pk_add_f32 v[8:9], v[154:155], 1.0 op_sel_hi:[1,0]
	v_pk_add_f32 v[10:11], v[152:153], 1.0 op_sel_hi:[1,0]
	v_pk_add_f32 v[152:153], v[170:171], 1.0 op_sel_hi:[1,0]
	v_pk_add_f32 v[154:155], v[168:169], 1.0 op_sel_hi:[1,0]
	v_pk_mul_f32 v[146:147], v[174:175], v[8:9]
	v_pk_mul_f32 v[150:151], v[172:173], v[10:11]
	v_pk_mul_f32 v[8:9], v[182:183], v[152:153]
	v_pk_mul_f32 v[10:11], v[180:181], v[154:155]
	v_pk_add_f32 v[152:153], v[186:187], 1.0 op_sel_hi:[1,0]
	v_pk_add_f32 v[154:155], v[184:185], 1.0 op_sel_hi:[1,0]
	v_pk_mul_f32 v[152:153], v[162:163], v[152:153]
	v_pk_mul_f32 v[154:155], v[160:161], v[154:155]
	v_pk_add_f32 v[14:15], v[164:165], 1.0 op_sel_hi:[1,0]
	v_pk_fma_f32 v[164:165], v[146:147], v[198:199], v[134:135]
	v_pk_fma_f32 v[166:167], v[150:151], v[196:197], v[132:133]
	v_pk_fma_f32 v[160:161], v[152:153], v[194:195], v[142:143]
	v_pk_fma_f32 v[162:163], v[154:155], v[192:193], v[140:141]
	v_pk_mul_f32 v[12:13], v[178:179], v[12:13]
	v_pk_mul_f32 v[14:15], v[176:177], v[14:15]
	v_cndmask_b32_e32 v145, v156, v160, vcc
	v_cndmask_b32_e32 v159, v156, v161, vcc
	v_cndmask_b32_e32 v158, v156, v162, vcc
	v_cndmask_b32_e32 v160, v156, v163, vcc
	v_cndmask_b32_e32 v161, v156, v164, vcc
	v_cndmask_b32_e32 v162, v156, v165, vcc
	v_cndmask_b32_e32 v163, v156, v166, vcc
	v_pk_fma_f32 v[30:31], v[8:9], v[30:31], v[138:139]
	v_pk_fma_f32 v[28:29], v[10:11], v[28:29], v[136:137]
	v_cndmask_b32_e32 v164, v156, v167, vcc
	v_cvt_pk_bf16_f32 v158, v158, v160
	v_cvt_pk_bf16_f32 v159, v145, v159
	v_cvt_pk_bf16_f32 v160, v163, v164
	v_cvt_pk_bf16_f32 v161, v161, v162
	v_lshl_add_u64 v[162:163], v[190:191], 0, v[148:149]
	v_pk_fma_f32 v[34:35], v[12:13], v[34:35], v[130:131]
	v_pk_fma_f32 v[32:33], v[14:15], v[32:33], v[128:129]
	v_cndmask_b32_e32 v145, v156, v30, vcc
	v_cndmask_b32_e32 v31, v156, v31, vcc
	v_cndmask_b32_e32 v30, v156, v28, vcc
	global_store_dwordx4 v[162:163], v[158:161], off
	v_cndmask_b32_e32 v34, v156, v34, vcc
	v_cndmask_b32_e32 v35, v156, v35, vcc
	v_cndmask_b32_e32 v32, v156, v32, vcc
	v_cndmask_b32_e32 v33, v156, v33, vcc
	v_cndmask_b32_e32 v158, v156, v29, vcc
	v_cvt_pk_bf16_f32 v28, v32, v33
	v_cvt_pk_bf16_f32 v29, v34, v35
	v_cvt_pk_bf16_f32 v30, v30, v158
	v_cvt_pk_bf16_f32 v31, v145, v31
	global_store_dwordx4 v[162:163], v[28:31], off offset:256
	ds_read_b32 v28, v157 offset:4160
	s_waitcnt lgkmcnt(0)
; __device__ __forceinline__ unsigned cvt_pk_bf16(float lo, float hi) { unsigned r; asm volatile("v_cvt_pk_bf16_f32 %0, %1, %2" : "=v"(r) : "v"(lo), "v"(hi)); return r; }
;     __device__ __forceinline__ void fused(f32x4 (&acc)[2][2][4][2], const Unit& un, int wr, int wc, int fr, int fq, PG8_LAS unsigned char* lds, int wid, int lane) const {
;     ...
;         for (int ai = 0; ai < 2; ++ai)
; #pragma unroll
;             for (int m = 0; m < 4; ++m) { const int r = ai * HALF + wr * 64 + m * 16 + fr; const float rs = S[r]; const size_t off = (size_t)(un.pm * BM + r) * ldc + col0;
; #pragma unroll
;                 for (int bj = 0; bj < 2; ++bj) { f32x4 y0 = (acc[ai][bj][m][0] * rs) * cg[bj][0] + sh[bj][0], y1 = (acc[ai][bj][m][1] * rs) * cg[bj][1] + sh[bj][1];
;                     if (bad) { y0 = (f32x4){qnan, qnan, qnan, qnan}; y1 = y0; }
;                     if (MODE == 0) { u32x4 w; w.x = cvt_pk_bf16(y0[0], y0[1]); w.y = cvt_pk_bf16(y0[2], y0[3]); w.z = cvt_pk_bf16(y1[0], y1[1]); w.w = cvt_pk_bf16(y1[2], y1[3]); *(u32x4*)(u + off + bj * HALF) = w; }
	v_pk_mul_f32 v[16:17], v[16:17], v[28:29] op_sel_hi:[1,0]
	v_pk_mul_f32 v[18:19], v[18:19], v[28:29] op_sel_hi:[1,0]
	v_pk_mul_f32 v[20:21], v[20:21], v[28:29] op_sel_hi:[1,0]
	v_add_u32_e32 v30, 16, v144
	v_pk_fma_f32 v[18:19], v[152:153], v[18:19], v[142:143]
	v_pk_fma_f32 v[16:17], v[154:155], v[16:17], v[140:141]
	v_pk_fma_f32 v[20:21], v[150:151], v[20:21], v[132:133]
	v_ashrrev_i32_e32 v31, 31, v30
	v_cndmask_b32_e32 v18, v156, v18, vcc
	v_cndmask_b32_e32 v16, v156, v16, vcc
	v_cndmask_b32_e32 v17, v156, v17, vcc
	v_cndmask_b32_e32 v20, v156, v20, vcc
	v_cndmask_b32_e32 v21, v156, v21, vcc
	v_pk_mul_f32 v[22:23], v[22:23], v[28:29] op_sel_hi:[1,0]
	v_cndmask_b32_e32 v19, v156, v19, vcc
	v_cvt_pk_bf16_f32 v16, v16, v17
	v_cvt_pk_bf16_f32 v17, v18, v19
	v_cvt_pk_bf16_f32 v18, v20, v21
	v_lshlrev_b64 v[20:21], 12, v[30:31]
	v_pk_fma_f32 v[22:23], v[146:147], v[22:23], v[134:135]
	v_lshl_add_u64 v[20:21], s[2:3], 0, v[20:21]
	v_cndmask_b32_e32 v22, v156, v22, vcc
	v_cndmask_b32_e32 v23, v156, v23, vcc
	v_cvt_pk_bf16_f32 v19, v22, v23
	v_lshl_add_u64 v[20:21], v[20:21], 0, v[148:149]
	global_store_dwordx4 v[20:21], v[16:19], off
	v_pk_mul_f32 v[22:23], v[56:57], v[28:29] op_sel_hi:[1,0]
	s_nop 0
	v_pk_mul_f32 v[16:17], v[60:61], v[28:29] op_sel_hi:[1,0]
	v_pk_mul_f32 v[18:19], v[62:63], v[28:29] op_sel_hi:[1,0]
	v_pk_fma_f32 v[16:17], v[14:15], v[16:17], v[128:129]
	v_pk_fma_f32 v[18:19], v[12:13], v[18:19], v[130:131]
	v_pk_mul_f32 v[28:29], v[58:59], v[28:29] op_sel_hi:[1,0]
	v_pk_fma_f32 v[22:23], v[10:11], v[22:23], v[136:137]
	v_pk_fma_f32 v[28:29], v[8:9], v[28:29], v[138:139]
	v_cndmask_b32_e32 v18, v156, v18, vcc
	v_cndmask_b32_e32 v19, v156, v19, vcc
	v_cndmask_b32_e32 v16, v156, v16, vcc
	v_cndmask_b32_e32 v17, v156, v17, vcc
	v_cndmask_b32_e32 v28, v156, v28, vcc
	v_cndmask_b32_e32 v29, v156, v29, vcc
	v_cndmask_b32_e32 v22, v156, v22, vcc
	v_cndmask_b32_e32 v23, v156, v23, vcc
	v_cvt_pk_bf16_f32 v16, v16, v17
	v_cvt_pk_bf16_f32 v17, v18, v19
	v_cvt_pk_bf16_f32 v18, v22, v23
	v_cvt_pk_bf16_f32 v19, v28, v29
	global_store_dwordx4 v[20:21], v[16:19], off offset:256
	ds_read_b32 v20, v157 offset:4224
	v_add_u32_e32 v22, 32, v144
	v_ashrrev_i32_e32 v23, 31, v22
	v_lshlrev_b64 v[22:23], 12, v[22:23]
	v_lshl_add_u64 v[22:23], s[2:3], 0, v[22:23]
	s_waitcnt lgkmcnt(0)
	v_pk_mul_f32 v[16:17], v[48:49], v[20:21] op_sel_hi:[1,0]
	v_pk_mul_f32 v[18:19], v[50:51], v[20:21] op_sel_hi:[1,0]
	v_pk_fma_f32 v[16:17], v[154:155], v[16:17], v[140:141]
	v_pk_fma_f32 v[18:19], v[152:153], v[18:19], v[142:143]
	v_pk_mul_f32 v[28:29], v[52:53], v[20:21] op_sel_hi:[1,0]
	v_pk_mul_f32 v[30:31], v[54:55], v[20:21] op_sel_hi:[1,0]
	v_pk_fma_f32 v[28:29], v[150:151], v[28:29], v[132:133]
	v_pk_fma_f32 v[30:31], v[146:147], v[30:31], v[134:135]
	v_cndmask_b32_e32 v18, v156, v18, vcc
	v_cndmask_b32_e32 v19, v156, v19, vcc
	v_cndmask_b32_e32 v16, v156, v16, vcc
	v_cndmask_b32_e32 v17, v156, v17, vcc
	v_cndmask_b32_e32 v21, v156, v30, vcc
	v_cndmask_b32_e32 v30, v156, v31, vcc
	v_cndmask_b32_e32 v28, v156, v28, vcc
	v_cndmask_b32_e32 v29, v156, v29, vcc
	v_cvt_pk_bf16_f32 v16, v16, v17
	v_cvt_pk_bf16_f32 v17, v18, v19
	v_cvt_pk_bf16_f32 v18, v28, v29
	v_cvt_pk_bf16_f32 v19, v21, v30
	v_lshl_add_u64 v[22:23], v[22:23], 0, v[148:149]
	global_store_dwordx4 v[22:23], v[16:19], off
	v_pk_mul_f32 v[28:29], v[72:73], v[20:21] op_sel_hi:[1,0]
	s_nop 0
	v_pk_mul_f32 v[16:17], v[76:77], v[20:21] op_sel_hi:[1,0]
	v_pk_mul_f32 v[18:19], v[78:79], v[20:21] op_sel_hi:[1,0]
	v_pk_fma_f32 v[16:17], v[14:15], v[16:17], v[128:129]
	v_pk_fma_f32 v[18:19], v[12:13], v[18:19], v[130:131]
	v_pk_mul_f32 v[20:21], v[74:75], v[20:21] op_sel_hi:[1,0]
	v_pk_fma_f32 v[28:29], v[10:11], v[28:29], v[136:137]
	v_pk_fma_f32 v[20:21], v[8:9], v[20:21], v[138:139]
	v_cndmask_b32_e32 v18, v156, v18, vcc
	v_cndmask_b32_e32 v19, v156, v19, vcc
	v_cndmask_b32_e32 v16, v156, v16, vcc
	v_cndmask_b32_e32 v17, v156, v17, vcc
	v_cndmask_b32_e32 v20, v156, v20, vcc
	v_cndmask_b32_e32 v21, v156, v21, vcc
	v_cndmask_b32_e32 v28, v156, v28, vcc
	v_cndmask_b32_e32 v29, v156, v29, vcc
	v_cvt_pk_bf16_f32 v16, v16, v17
	v_cvt_pk_bf16_f32 v17, v18, v19
	v_cvt_pk_bf16_f32 v18, v28, v29
	v_cvt_pk_bf16_f32 v19, v20, v21
	global_store_dwordx4 v[22:23], v[16:19], off offset:256
	ds_read_b32 v20, v157 offset:4288
	v_add_u32_e32 v22, 48, v144
	v_ashrrev_i32_e32 v23, 31, v22
	v_lshlrev_b64 v[22:23], 12, v[22:23]
	v_lshl_add_u64 v[22:23], s[2:3], 0, v[22:23]
	s_waitcnt lgkmcnt(0)
	v_pk_mul_f32 v[16:17], v[64:65], v[20:21] op_sel_hi:[1,0]
	v_pk_mul_f32 v[18:19], v[66:67], v[20:21] op_sel_hi:[1,0]
	v_pk_fma_f32 v[16:17], v[154:155], v[16:17], v[140:141]
	v_pk_fma_f32 v[18:19], v[152:153], v[18:19], v[142:143]
	v_pk_mul_f32 v[28:29], v[68:69], v[20:21] op_sel_hi:[1,0]
	v_pk_mul_f32 v[30:31], v[70:71], v[20:21] op_sel_hi:[1,0]
	v_pk_fma_f32 v[28:29], v[150:151], v[28:29], v[132:133]
	v_pk_fma_f32 v[30:31], v[146:147], v[30:31], v[134:135]
	v_cndmask_b32_e32 v18, v156, v18, vcc
	v_cndmask_b32_e32 v19, v156, v19, vcc
	v_cndmask_b32_e32 v16, v156, v16, vcc
	v_cndmask_b32_e32 v17, v156, v17, vcc
	v_cndmask_b32_e32 v21, v156, v30, vcc
	v_cndmask_b32_e32 v30, v156, v31, vcc
	v_cndmask_b32_e32 v28, v156, v28, vcc
	v_cndmask_b32_e32 v29, v156, v29, vcc
	v_cvt_pk_bf16_f32 v16, v16, v17
	v_cvt_pk_bf16_f32 v17, v18, v19
	v_cvt_pk_bf16_f32 v18, v28, v29
	v_cvt_pk_bf16_f32 v19, v21, v30
	v_lshl_add_u64 v[22:23], v[22:23], 0, v[148:149]
	global_store_dwordx4 v[22:23], v[16:19], off
	v_pk_mul_f32 v[28:29], v[96:97], v[20:21] op_sel_hi:[1,0]
	s_nop 0
	v_pk_mul_f32 v[16:17], v[108:109], v[20:21] op_sel_hi:[1,0]
	v_pk_mul_f32 v[18:19], v[110:111], v[20:21] op_sel_hi:[1,0]
	v_pk_fma_f32 v[16:17], v[14:15], v[16:17], v[128:129]
	v_pk_fma_f32 v[18:19], v[12:13], v[18:19], v[130:131]
	v_pk_mul_f32 v[20:21], v[98:99], v[20:21] op_sel_hi:[1,0]
	v_pk_fma_f32 v[28:29], v[10:11], v[28:29], v[136:137]
	v_pk_fma_f32 v[20:21], v[8:9], v[20:21], v[138:139]
	v_cndmask_b32_e32 v18, v156, v18, vcc
	v_cndmask_b32_e32 v19, v156, v19, vcc
	v_cndmask_b32_e32 v16, v156, v16, vcc
	v_cndmask_b32_e32 v17, v156, v17, vcc
	v_cndmask_b32_e32 v20, v156, v20, vcc
	v_cndmask_b32_e32 v21, v156, v21, vcc
	v_cndmask_b32_e32 v28, v156, v28, vcc
	v_cndmask_b32_e32 v29, v156, v29, vcc
	v_cvt_pk_bf16_f32 v16, v16, v17
	v_cvt_pk_bf16_f32 v17, v18, v19
	v_cvt_pk_bf16_f32 v18, v28, v29
	v_cvt_pk_bf16_f32 v19, v20, v21
	global_store_dwordx4 v[22:23], v[16:19], off offset:256
	ds_read_b32 v20, v157 offset:4608
	v_add_u32_e32 v22, 0x80, v144
	v_ashrrev_i32_e32 v23, 31, v22
	v_lshlrev_b64 v[22:23], 12, v[22:23]
	v_lshl_add_u64 v[22:23], s[2:3], 0, v[22:23]
	s_waitcnt lgkmcnt(0)
; __device__ __forceinline__ unsigned cvt_pk_bf16(float lo, float hi) { unsigned r; asm volatile("v_cvt_pk_bf16_f32 %0, %1, %2" : "=v"(r) : "v"(lo), "v"(hi)); return r; }
;     __device__ __forceinline__ void fused(f32x4 (&acc)[2][2][4][2], const Unit& un, int wr, int wc, int fr, int fq, PG8_LAS unsigned char* lds, int wid, int lane) const {
;     ...
;         for (int ai = 0; ai < 2; ++ai)
; #pragma unroll
;             for (int m = 0; m < 4; ++m) { const int r = ai * HALF + wr * 64 + m * 16 + fr; const float rs = S[r]; const size_t off = (size_t)(un.pm * BM + r) * ldc + col0;
; #pragma unroll
;                 for (int bj = 0; bj < 2; ++bj) { f32x4 y0 = (acc[ai][bj][m][0] * rs) * cg[bj][0] + sh[bj][0], y1 = (acc[ai][bj][m][1] * rs) * cg[bj][1] + sh[bj][1];
;                     if (bad) { y0 = (f32x4){qnan, qnan, qnan, qnan}; y1 = y0; }
;                     if (MODE == 0) { u32x4 w; w.x = cvt_pk_bf16(y0[0], y0[1]); w.y = cvt_pk_bf16(y0[2], y0[3]); w.z = cvt_pk_bf16(y1[0], y1[1]); w.w = cvt_pk_bf16(y1[2], y1[3]); *(u32x4*)(u + off + bj * HALF) = w; }
	v_pk_mul_f32 v[16:17], v[100:101], v[20:21] op_sel_hi:[1,0]
	v_pk_mul_f32 v[18:19], v[102:103], v[20:21] op_sel_hi:[1,0]
	v_pk_fma_f32 v[16:17], v[154:155], v[16:17], v[140:141]
	v_pk_fma_f32 v[18:19], v[152:153], v[18:19], v[142:143]
	v_pk_mul_f32 v[28:29], v[104:105], v[20:21] op_sel_hi:[1,0]
	v_pk_mul_f32 v[30:31], v[106:107], v[20:21] op_sel_hi:[1,0]
	v_pk_fma_f32 v[28:29], v[150:151], v[28:29], v[132:133]
	v_pk_fma_f32 v[30:31], v[146:147], v[30:31], v[134:135]
	v_cndmask_b32_e32 v18, v156, v18, vcc
	v_cndmask_b32_e32 v19, v156, v19, vcc
	v_cndmask_b32_e32 v16, v156, v16, vcc
	v_cndmask_b32_e32 v17, v156, v17, vcc
	v_cndmask_b32_e32 v21, v156, v30, vcc
	v_cndmask_b32_e32 v30, v156, v31, vcc
	v_cndmask_b32_e32 v28, v156, v28, vcc
	v_cndmask_b32_e32 v29, v156, v29, vcc
	v_cvt_pk_bf16_f32 v16, v16, v17
	v_cvt_pk_bf16_f32 v17, v18, v19
	v_cvt_pk_bf16_f32 v18, v28, v29
	v_cvt_pk_bf16_f32 v19, v21, v30
	v_lshl_add_u64 v[22:23], v[22:23], 0, v[148:149]
	global_store_dwordx4 v[22:23], v[16:19], off
	v_pk_mul_f32 v[28:29], v[112:113], v[20:21] op_sel_hi:[1,0]
	s_nop 0
	v_pk_mul_f32 v[16:17], v[124:125], v[20:21] op_sel_hi:[1,0]
	v_pk_mul_f32 v[18:19], v[126:127], v[20:21] op_sel_hi:[1,0]
	v_pk_fma_f32 v[16:17], v[14:15], v[16:17], v[128:129]
	v_pk_fma_f32 v[18:19], v[12:13], v[18:19], v[130:131]
	v_pk_mul_f32 v[20:21], v[114:115], v[20:21] op_sel_hi:[1,0]
	v_pk_fma_f32 v[28:29], v[10:11], v[28:29], v[136:137]
	v_pk_fma_f32 v[20:21], v[8:9], v[20:21], v[138:139]
	v_cndmask_b32_e32 v18, v156, v18, vcc
	v_cndmask_b32_e32 v19, v156, v19, vcc
	v_cndmask_b32_e32 v16, v156, v16, vcc
	v_cndmask_b32_e32 v17, v156, v17, vcc
	v_cndmask_b32_e32 v20, v156, v20, vcc
	v_cndmask_b32_e32 v21, v156, v21, vcc
	v_cndmask_b32_e32 v28, v156, v28, vcc
	v_cndmask_b32_e32 v29, v156, v29, vcc
	v_cvt_pk_bf16_f32 v16, v16, v17
	v_cvt_pk_bf16_f32 v17, v18, v19
	v_cvt_pk_bf16_f32 v18, v28, v29
	v_cvt_pk_bf16_f32 v19, v20, v21
	global_store_dwordx4 v[22:23], v[16:19], off offset:256
	ds_read_b32 v20, v157 offset:4672
	v_add_u32_e32 v22, 0x90, v144
	v_ashrrev_i32_e32 v23, 31, v22
	v_lshlrev_b64 v[22:23], 12, v[22:23]
	v_lshl_add_u64 v[22:23], s[2:3], 0, v[22:23]
	s_waitcnt lgkmcnt(0)
	v_pk_mul_f32 v[16:17], v[116:117], v[20:21] op_sel_hi:[1,0]
	v_pk_mul_f32 v[18:19], v[118:119], v[20:21] op_sel_hi:[1,0]
	v_pk_fma_f32 v[16:17], v[154:155], v[16:17], v[140:141]
	v_pk_fma_f32 v[18:19], v[152:153], v[18:19], v[142:143]
	v_pk_mul_f32 v[28:29], v[120:121], v[20:21] op_sel_hi:[1,0]
	v_pk_mul_f32 v[30:31], v[122:123], v[20:21] op_sel_hi:[1,0]
	v_pk_fma_f32 v[28:29], v[150:151], v[28:29], v[132:133]
	v_pk_fma_f32 v[30:31], v[146:147], v[30:31], v[134:135]
	v_cndmask_b32_e32 v18, v156, v18, vcc
	v_cndmask_b32_e32 v19, v156, v19, vcc
	v_cndmask_b32_e32 v16, v156, v16, vcc
	v_cndmask_b32_e32 v17, v156, v17, vcc
	v_cndmask_b32_e32 v21, v156, v30, vcc
	v_cndmask_b32_e32 v30, v156, v31, vcc
	v_cndmask_b32_e32 v28, v156, v28, vcc
	v_cndmask_b32_e32 v29, v156, v29, vcc
	v_cvt_pk_bf16_f32 v16, v16, v17
	v_cvt_pk_bf16_f32 v17, v18, v19
	v_cvt_pk_bf16_f32 v18, v28, v29
	v_cvt_pk_bf16_f32 v19, v21, v30
	v_lshl_add_u64 v[22:23], v[22:23], 0, v[148:149]
	global_store_dwordx4 v[22:23], v[16:19], off
	v_pk_mul_f32 v[28:29], v[88:89], v[20:21] op_sel_hi:[1,0]
	s_nop 0
	v_pk_mul_f32 v[16:17], v[92:93], v[20:21] op_sel_hi:[1,0]
	v_pk_mul_f32 v[18:19], v[94:95], v[20:21] op_sel_hi:[1,0]
	v_pk_fma_f32 v[16:17], v[14:15], v[16:17], v[128:129]
	v_pk_fma_f32 v[18:19], v[12:13], v[18:19], v[130:131]
	v_pk_mul_f32 v[20:21], v[90:91], v[20:21] op_sel_hi:[1,0]
	v_pk_fma_f32 v[28:29], v[10:11], v[28:29], v[136:137]
	v_pk_fma_f32 v[20:21], v[8:9], v[20:21], v[138:139]
	v_cndmask_b32_e32 v18, v156, v18, vcc
	v_cndmask_b32_e32 v19, v156, v19, vcc
	v_cndmask_b32_e32 v16, v156, v16, vcc
	v_cndmask_b32_e32 v17, v156, v17, vcc
	v_cndmask_b32_e32 v20, v156, v20, vcc
	v_cndmask_b32_e32 v21, v156, v21, vcc
	v_cndmask_b32_e32 v28, v156, v28, vcc
	v_cndmask_b32_e32 v29, v156, v29, vcc
	v_cvt_pk_bf16_f32 v16, v16, v17
	v_cvt_pk_bf16_f32 v17, v18, v19
	v_cvt_pk_bf16_f32 v18, v28, v29
	v_cvt_pk_bf16_f32 v19, v20, v21
	global_store_dwordx4 v[22:23], v[16:19], off offset:256
	ds_read_b32 v20, v157 offset:4736
	v_add_u32_e32 v22, 0xa0, v144
	v_ashrrev_i32_e32 v23, 31, v22
	v_lshlrev_b64 v[22:23], 12, v[22:23]
	v_lshl_add_u64 v[22:23], s[2:3], 0, v[22:23]
	s_waitcnt lgkmcnt(0)
; __device__ __forceinline__ unsigned cvt_pk_bf16(float lo, float hi) { unsigned r; asm volatile("v_cvt_pk_bf16_f32 %0, %1, %2" : "=v"(r) : "v"(lo), "v"(hi)); return r; }
;     __device__ __forceinline__ void fused(f32x4 (&acc)[2][2][4][2], const Unit& un, int wr, int wc, int fr, int fq, PG8_LAS unsigned char* lds, int wid, int lane) const {
;     ...
;         for (int ai = 0; ai < 2; ++ai)
; #pragma unroll
;             for (int m = 0; m < 4; ++m) { const int r = ai * HALF + wr * 64 + m * 16 + fr; const float rs = S[r]; const size_t off = (size_t)(un.pm * BM + r) * ldc + col0;
; #pragma unroll
;                 for (int bj = 0; bj < 2; ++bj) { f32x4 y0 = (acc[ai][bj][m][0] * rs) * cg[bj][0] + sh[bj][0], y1 = (acc[ai][bj][m][1] * rs) * cg[bj][1] + sh[bj][1];
;                     if (bad) { y0 = (f32x4){qnan, qnan, qnan, qnan}; y1 = y0; }
;                     if (MODE == 0) { u32x4 w; w.x = cvt_pk_bf16(y0[0], y0[1]); w.y = cvt_pk_bf16(y0[2], y0[3]); w.z = cvt_pk_bf16(y1[0], y1[1]); w.w = cvt_pk_bf16(y1[2], y1[3]); *(u32x4*)(u + off + bj * HALF) = w; }
	v_pk_mul_f32 v[16:17], v[84:85], v[20:21] op_sel_hi:[1,0]
	v_pk_mul_f32 v[18:19], v[86:87], v[20:21] op_sel_hi:[1,0]
	v_pk_fma_f32 v[16:17], v[154:155], v[16:17], v[140:141]
	v_pk_fma_f32 v[18:19], v[152:153], v[18:19], v[142:143]
	v_pk_mul_f32 v[28:29], v[80:81], v[20:21] op_sel_hi:[1,0]
	v_pk_mul_f32 v[30:31], v[82:83], v[20:21] op_sel_hi:[1,0]
	v_pk_fma_f32 v[28:29], v[150:151], v[28:29], v[132:133]
	v_pk_fma_f32 v[30:31], v[146:147], v[30:31], v[134:135]
	v_cndmask_b32_e32 v18, v156, v18, vcc
	v_cndmask_b32_e32 v19, v156, v19, vcc
	v_cndmask_b32_e32 v16, v156, v16, vcc
	v_cndmask_b32_e32 v17, v156, v17, vcc
	v_cndmask_b32_e32 v21, v156, v30, vcc
	v_cndmask_b32_e32 v30, v156, v31, vcc
	v_cndmask_b32_e32 v28, v156, v28, vcc
	v_cndmask_b32_e32 v29, v156, v29, vcc
	v_cvt_pk_bf16_f32 v16, v16, v17
	v_cvt_pk_bf16_f32 v17, v18, v19
	v_cvt_pk_bf16_f32 v18, v28, v29
	v_cvt_pk_bf16_f32 v19, v21, v30
	v_lshl_add_u64 v[22:23], v[22:23], 0, v[148:149]
	global_store_dwordx4 v[22:23], v[16:19], off
	v_pk_mul_f32 v[28:29], v[40:41], v[20:21] op_sel_hi:[1,0]
	s_nop 0
	v_pk_mul_f32 v[16:17], v[44:45], v[20:21] op_sel_hi:[1,0]
	v_pk_mul_f32 v[18:19], v[46:47], v[20:21] op_sel_hi:[1,0]
	v_pk_fma_f32 v[16:17], v[14:15], v[16:17], v[128:129]
	v_pk_fma_f32 v[18:19], v[12:13], v[18:19], v[130:131]
	v_pk_mul_f32 v[20:21], v[42:43], v[20:21] op_sel_hi:[1,0]
	v_pk_fma_f32 v[28:29], v[10:11], v[28:29], v[136:137]
	v_pk_fma_f32 v[20:21], v[8:9], v[20:21], v[138:139]
	v_cndmask_b32_e32 v18, v156, v18, vcc
	v_cndmask_b32_e32 v19, v156, v19, vcc
	v_cndmask_b32_e32 v16, v156, v16, vcc
	v_cndmask_b32_e32 v17, v156, v17, vcc
	v_cndmask_b32_e32 v20, v156, v20, vcc
	v_cndmask_b32_e32 v21, v156, v21, vcc
	v_cndmask_b32_e32 v28, v156, v28, vcc
	v_cndmask_b32_e32 v29, v156, v29, vcc
	v_cvt_pk_bf16_f32 v16, v16, v17
	v_cvt_pk_bf16_f32 v17, v18, v19
	v_cvt_pk_bf16_f32 v18, v28, v29
	v_cvt_pk_bf16_f32 v19, v20, v21
	global_store_dwordx4 v[22:23], v[16:19], off offset:256
	ds_read_b32 v20, v157 offset:4800
	v_add_u32_e32 v22, 0xb0, v144
	v_ashrrev_i32_e32 v23, 31, v22
	v_lshlrev_b64 v[22:23], 12, v[22:23]
	v_lshl_add_u64 v[22:23], s[2:3], 0, v[22:23]
	s_waitcnt lgkmcnt(0)
	v_pk_mul_f32 v[26:27], v[26:27], v[20:21] op_sel_hi:[1,0]
	v_pk_mul_f32 v[16:17], v[36:37], v[20:21] op_sel_hi:[1,0]
	v_pk_fma_f32 v[26:27], v[146:147], v[26:27], v[134:135]
	v_pk_mul_f32 v[18:19], v[38:39], v[20:21] op_sel_hi:[1,0]
	v_pk_mul_f32 v[24:25], v[24:25], v[20:21] op_sel_hi:[1,0]
	v_cndmask_b32_e32 v21, v156, v26, vcc
	v_pk_mul_f32 v[0:1], v[0:1], v[20:21] op_sel_hi:[1,0]
	v_pk_mul_f32 v[2:3], v[2:3], v[20:21] op_sel_hi:[1,0]
	v_pk_fma_f32 v[18:19], v[152:153], v[18:19], v[142:143]
	v_pk_fma_f32 v[16:17], v[154:155], v[16:17], v[140:141]
	v_pk_mul_f32 v[4:5], v[4:5], v[20:21] op_sel_hi:[1,0]
	v_pk_mul_f32 v[6:7], v[6:7], v[20:21] op_sel_hi:[1,0]
	v_pk_fma_f32 v[2:3], v[8:9], v[2:3], v[138:139]
	v_pk_fma_f32 v[0:1], v[10:11], v[0:1], v[136:137]
	v_pk_fma_f32 v[24:25], v[150:151], v[24:25], v[132:133]
	v_cndmask_b32_e32 v18, v156, v18, vcc
	v_cndmask_b32_e32 v19, v156, v19, vcc
	v_cndmask_b32_e32 v16, v156, v16, vcc
	v_cndmask_b32_e32 v17, v156, v17, vcc
	v_lshl_add_u64 v[22:23], v[22:23], 0, v[148:149]
	v_pk_fma_f32 v[6:7], v[12:13], v[6:7], v[130:131]
	v_pk_fma_f32 v[4:5], v[14:15], v[4:5], v[128:129]
	v_cndmask_b32_e32 v8, v156, v2, vcc
	v_cndmask_b32_e32 v3, v156, v3, vcc
	v_cndmask_b32_e32 v2, v156, v0, vcc
	v_cndmask_b32_e32 v26, v156, v27, vcc
	v_cndmask_b32_e32 v24, v156, v24, vcc
	v_cndmask_b32_e32 v25, v156, v25, vcc
	v_cvt_pk_bf16_f32 v16, v16, v17
	v_cvt_pk_bf16_f32 v17, v18, v19
	v_cvt_pk_bf16_f32 v18, v24, v25
	v_cvt_pk_bf16_f32 v19, v21, v26
	global_store_dwordx4 v[22:23], v[16:19], off
	v_cndmask_b32_e32 v6, v156, v6, vcc
	v_cndmask_b32_e32 v7, v156, v7, vcc
	v_cndmask_b32_e32 v4, v156, v4, vcc
	v_cndmask_b32_e32 v5, v156, v5, vcc
	v_cndmask_b32_e32 v9, v156, v1, vcc
	v_cvt_pk_bf16_f32 v0, v4, v5
	v_cvt_pk_bf16_f32 v1, v6, v7
	v_cvt_pk_bf16_f32 v2, v2, v9
	v_cvt_pk_bf16_f32 v3, v8, v3
	global_store_dwordx4 v[22:23], v[0:3], off offset:256

;     __device__ __forceinline__ void operator()(const f32x4 (&acc)[2][2][4][2], const Unit& u, int wr, int wc, int fr, int fq) const {
;     ...
; #pragma unroll
;         for (int ai = 0; ai < 2; ++ai)
; #pragma unroll
;             for (int m = 0; m < 4; ++m) { bf16_t* rowp = O + (size_t)(row0 + ai * HALF + m * 16) * ldc + col0;
;                 if (ACT == 1) {
;                     const int ob = fr * 64 + 16 * fq, sw = ob ^ (((ob >> 9) & 1) << 5);
;                     rowp = O + ((size_t)(u.pm * (ldc / 64) + u.pn * 4 + (wc >> 1)) * 2 + ai) * 8192 + (((wr * 4 + m) * 2 + (wc & 1)) * 1024 + sw) / 2; }
;                 float rc[2][2], rs[2][2];
;                 if (ACT == 2) { const float pos = (float)((row0 + ai * HALF + m * 16) & 2047);
; #pragma unroll
;                     for (int n = 0; n < 2; ++n)
; #pragma unroll
;                         for (int e = 0; e < 2; ++e) { float r = pos * rinv[n][e]; r -= floorf(r); rs[n][e] = do_rope ? __builtin_amdgcn_sinf(r) : 0.f; rc[n][e] = do_rope ? __builtin_amdgcn_cosf(r) : 1.f; } }
; #pragma unroll
;                 for (int bj = 0; bj < 2; ++bj) { f32x4 v0 = acc[ai][bj][m][0], v1 = acc[ai][bj][m][1];
;                     if (ACT == 3) { const float pos = (float)((row0 + ai * HALF + m * 16) & 2047); float c3[4], s3[4];
; #pragma unroll
;                         for (int p = 0; p < 4; ++p) { float r = pos * rinv3[bj][p]; r -= floorf(r); s3[p] = rope3[bj] ? __builtin_amdgcn_sinf(r) : 0.f; c3[p] = rope3[bj] ? __builtin_amdgcn_cosf(r) : 1.f; }
;                         const f32x4 a = v0, b = v1;
;                         v0[0] = a[0] * c3[0] - a[1] * s3[0]; v0[1] = a[1] * c3[0] + a[0] * s3[0]; v0[2] = a[2] * c3[1] - a[3] * s3[1]; v0[3] = a[3] * c3[1] + a[2] * s3[1];
;                         v1[0] = b[0] * c3[2] - b[1] * s3[2]; v1[1] = b[1] * c3[2] + b[0] * s3[2]; v1[2] = b[2] * c3[3] - b[3] * s3[3]; v1[3] = b[3] * c3[3] + b[2] * s3[3]; }
;                     if (ACT == 2) { const f32x4 a = v0, b = v1;
;                         v0[0] = a[0] * rc[0][0] - a[1] * rs[0][0]; v0[1] = a[1] * rc[0][0] + a[0] * rs[0][0]; v0[2] = a[2] * rc[0][1] - a[3] * rs[0][1]; v0[3] = a[3] * rc[0][1] + a[2] * rs[0][1];
;                         v1[0] = b[0] * rc[1][0] - b[1] * rs[1][0]; v1[1] = b[1] * rc[1][0] + b[0] * rs[1][0]; v1[2] = b[2] * rc[1][1] - b[3] * rs[1][1]; v1[3] = b[3] * rc[1][1] + b[2] * rs[1][1]; }
.LBB0_3345:
	v_mov_b32_e32 v140, 0
	s_lshl_b32 s23, s40, 8
	v_mbcnt_lo_u32_b32 v140, -1, v140
	v_mbcnt_hi_u32_b32 v140, -1, v140
	v_or_b32_e32 v140, s33, v140
	s_add_i32 s23, s23, s57
	v_and_or_b32 v152, v140, 15, s23
	s_lshl_b32 s23, s66, 8
	v_lshrrev_b32_e32 v140, 1, v140
	v_and_or_b32 v140, v140, 24, s23
	v_or_b32_e32 v140, s58, v140
	v_ashrrev_i32_e32 v141, 31, v140
	v_mov_b64_e32 v[144:145], s[6:7]
	v_mad_i64_i32 v[142:143], s[42:43], v152, s63, v[144:145]
	v_lshlrev_b64 v[146:147], 1, v[140:141]
	v_lshl_add_u64 v[140:141], v[142:143], 0, v[146:147]
	v_cvt_pk_bf16_f32 v120, v120, v121
	v_cvt_pk_bf16_f32 v121, v122, v123
	v_cvt_pk_bf16_f32 v122, v112, v113
	v_cvt_pk_bf16_f32 v123, v114, v115
	global_store_dwordx4 v[140:141], v[120:123], off
	v_cvt_pk_bf16_f32 v112, v124, v125
	v_cvt_pk_bf16_f32 v113, v126, v127
	v_cvt_pk_bf16_f32 v114, v116, v117
	v_cvt_pk_bf16_f32 v115, v118, v119
	global_store_dwordx4 v[140:141], v[112:115], off offset:256
	v_cvt_pk_bf16_f32 v104, v104, v105
	v_cvt_pk_bf16_f32 v105, v106, v107
	v_cvt_pk_bf16_f32 v106, v96, v97
	v_cvt_pk_bf16_f32 v107, v98, v99
	s_andn2_b64 vcc, exec, s[0:1]
	s_nop 0
	v_or_b32_e32 v112, 16, v152
	v_mad_i64_i32 v[112:113], s[42:43], v112, s63, v[144:145]
	v_lshl_add_u64 v[112:113], v[112:113], 0, v[146:147]
	global_store_dwordx4 v[112:113], v[104:107], off
	v_cvt_pk_bf16_f32 v96, v108, v109
	v_cvt_pk_bf16_f32 v97, v110, v111
	v_cvt_pk_bf16_f32 v98, v100, v101
	v_cvt_pk_bf16_f32 v99, v102, v103
	global_store_dwordx4 v[112:113], v[96:99], off offset:256
	v_cvt_pk_bf16_f32 v88, v88, v89
	v_cvt_pk_bf16_f32 v89, v90, v91
	v_cvt_pk_bf16_f32 v90, v80, v81
	v_cvt_pk_bf16_f32 v91, v82, v83
	s_mov_b64 s[0:1], -1
	s_nop 0
	v_or_b32_e32 v96, 32, v152
	v_mad_i64_i32 v[96:97], s[42:43], v96, s63, v[144:145]
	v_lshl_add_u64 v[96:97], v[96:97], 0, v[146:147]
	global_store_dwordx4 v[96:97], v[88:91], off
	v_cvt_pk_bf16_f32 v80, v92, v93
	v_cvt_pk_bf16_f32 v81, v94, v95
	v_cvt_pk_bf16_f32 v82, v84, v85
	v_cvt_pk_bf16_f32 v83, v86, v87
	global_store_dwordx4 v[96:97], v[80:83], off offset:256
	v_cvt_pk_bf16_f32 v56, v56, v57
	v_cvt_pk_bf16_f32 v57, v58, v59
	v_cvt_pk_bf16_f32 v58, v48, v49
	v_cvt_pk_bf16_f32 v59, v50, v51
	s_nop 1
	v_or_b32_e32 v80, 48, v152
	v_mad_i64_i32 v[80:81], s[42:43], v80, s63, v[144:145]
	v_lshl_add_u64 v[80:81], v[80:81], 0, v[146:147]
	global_store_dwordx4 v[80:81], v[56:59], off
	v_cvt_pk_bf16_f32 v48, v60, v61
	v_cvt_pk_bf16_f32 v49, v62, v63
	v_cvt_pk_bf16_f32 v50, v52, v53
	v_cvt_pk_bf16_f32 v51, v54, v55
	global_store_dwordx4 v[80:81], v[48:51], off offset:256
	s_nop 1
	v_add_u32_e32 v48, 0x80, v152
	v_mad_i64_i32 v[48:49], s[42:43], v48, s63, v[144:145]
	v_lshl_add_u64 v[52:53], v[48:49], 0, v[146:147]
	v_cvt_pk_bf16_f32 v48, v72, v73
	v_cvt_pk_bf16_f32 v49, v74, v75
	v_cvt_pk_bf16_f32 v50, v64, v65
	v_cvt_pk_bf16_f32 v51, v66, v67
	global_store_dwordx4 v[52:53], v[48:51], off
	s_nop 1
	v_cvt_pk_bf16_f32 v48, v76, v77
	v_cvt_pk_bf16_f32 v49, v78, v79
	v_cvt_pk_bf16_f32 v50, v68, v69
	v_cvt_pk_bf16_f32 v51, v70, v71
	global_store_dwordx4 v[52:53], v[48:51], off offset:256
	v_cvt_pk_bf16_f32 v40, v40, v41
	v_cvt_pk_bf16_f32 v41, v42, v43
	v_cvt_pk_bf16_f32 v42, v32, v33
	v_cvt_pk_bf16_f32 v43, v34, v35
	s_nop 1
	v_add_u32_e32 v48, 0x90, v152
	v_mad_i64_i32 v[48:49], s[42:43], v48, s63, v[144:145]
	v_lshl_add_u64 v[48:49], v[48:49], 0, v[146:147]
	global_store_dwordx4 v[48:49], v[40:43], off
	v_cvt_pk_bf16_f32 v32, v44, v45
	v_cvt_pk_bf16_f32 v33, v46, v47
	v_cvt_pk_bf16_f32 v34, v36, v37
	v_cvt_pk_bf16_f32 v35, v38, v39
	global_store_dwordx4 v[48:49], v[32:35], off offset:256
	v_cvt_pk_bf16_f32 v24, v24, v25
	v_cvt_pk_bf16_f32 v25, v26, v27
	v_cvt_pk_bf16_f32 v26, v16, v17
	v_cvt_pk_bf16_f32 v27, v18, v19
	s_nop 1
	v_add_u32_e32 v32, 0xa0, v152
	v_mad_i64_i32 v[32:33], s[42:43], v32, s63, v[144:145]
	v_lshl_add_u64 v[32:33], v[32:33], 0, v[146:147]
	global_store_dwordx4 v[32:33], v[24:27], off
	v_cvt_pk_bf16_f32 v16, v28, v29
	v_cvt_pk_bf16_f32 v17, v30, v31
	v_cvt_pk_bf16_f32 v18, v20, v21
	v_cvt_pk_bf16_f32 v19, v22, v23
	global_store_dwordx4 v[32:33], v[16:19], off offset:256
	v_cvt_pk_bf16_f32 v8, v8, v9
	v_cvt_pk_bf16_f32 v9, v10, v11
	v_cvt_pk_bf16_f32 v10, v0, v1
	v_cvt_pk_bf16_f32 v11, v2, v3
	s_nop 1
	v_add_u32_e32 v16, 0xb0, v152
	v_mad_i64_i32 v[16:17], s[42:43], v16, s63, v[144:145]
	v_lshl_add_u64 v[16:17], v[16:17], 0, v[146:147]
	global_store_dwordx4 v[16:17], v[8:11], off
	v_cvt_pk_bf16_f32 v0, v12, v13
	v_cvt_pk_bf16_f32 v1, v14, v15
	v_cvt_pk_bf16_f32 v2, v4, v5
	v_cvt_pk_bf16_f32 v3, v6, v7
	global_store_dwordx4 v[16:17], v[0:3], off offset:256
	s_cbranch_vccnz .LBB0_3338
	s_andn2_b64 vcc, exec, s[4:5]
	s_cbranch_vccnz .LBB0_3337
	s_barrier
	s_branch .LBB0_3337

; __device__ __forceinline__ unsigned cvt_pk_bf16(float lo, float hi) { unsigned r; asm volatile("v_cvt_pk_bf16_f32 %0, %1, %2" : "=v"(r) : "v"(lo), "v"(hi)); return r; }
;     __device__ __forceinline__ void fused(f32x4 (&acc)[2][2][4][2], const Unit& un, int wr, int wc, int fr, int fq, PG8_LAS unsigned char* lds, int wid, int lane) const {
;     ...
;         const int row0 = un.pm * BM + wr * 64 + fr, col0 = un.pn * BM + wc * 32 + 8 * fq;
;         const size_t boff = (size_t)(un.pm >> 3) * bstride + col0;
;         { f32x4 gv[2][2];
; #pragma unroll
;           for (int bj = 0; bj < 2; ++bj)
; #pragma unroll
;               for (int n = 0; n < 2; ++n) gv[bj][n] = *(const f32x4*)(gate + boff + bj * HALF + n * 4);
; #pragma unroll
;           for (int ai = 0; ai < 2; ++ai)
; #pragma unroll
;               for (int m = 0; m < 4; ++m) { const size_t off = (size_t)(row0 + ai * HALF + m * 16) * ldc + col0;
; #pragma unroll
;                   for (int bj = 0; bj < 2; ++bj) {
; #pragma unroll
;                       for (int n = 0; n < 2; ++n) { f32x4 bs;
;                           if (BASE_F32) bs = *(const f32x4*)((const float*)base + off + bj * HALF + n * 4);
;                           else { const u32x2v hw = *(const u32x2v*)((const bf16_t*)base + off + bj * HALF + n * 4);
;                                  bs = (f32x4){__uint_as_float(hw.x << 16), __uint_as_float(hw.x & 0xffff0000u), __uint_as_float(hw.y << 16), __uint_as_float(hw.y & 0xffff0000u)}; }
;                           acc[ai][bj][m][n] = bs + gv[bj][n] * acc[ai][bj][m][n]; }
;                       if (out_h) { const f32x4 a0 = acc[ai][bj][m][0], a1 = acc[ai][bj][m][1]; u32x4 w; w.x = cvt_pk_bf16(a0[0], a0[1]); w.y = cvt_pk_bf16(a0[2], a0[3]); w.z = cvt_pk_bf16(a1[0], a1[1]); w.w = cvt_pk_bf16(a1[2], a1[3]);
;                           *(u32x4*)(out_h + off + bj * HALF) = w; } }
;                   asm volatile("" : "+v"(acc[ai][0][m][0]), "+v"(acc[ai][0][m][1]), "+v"(acc[ai][1][m][0]), "+v"(acc[ai][1][m][1]));
;                   asm volatile("" ::: "memory"); } }
.LBB0_3611:
	v_mov_b32_e32 v32, 0
	s_barrier
	s_lshl_b32 s4, s26, 5
	v_mbcnt_lo_u32_b32 v32, -1, v32
	s_add_u32 s0, s8, 0x1a600000
	v_mbcnt_hi_u32_b32 v32, -1, v32
	s_addc_u32 s1, s9, 0
	v_or_b32_e32 v158, s33, v32
	s_lshl_b32 s5, s2, 8
	s_lshl_b32 s27, s12, 8
	s_or_b32 s4, s5, s4
	v_lshrrev_b32_e32 v32, 1, v158
	v_and_b32_e32 v159, 15, v158
	s_add_i32 s14, s27, s13
	v_and_or_b32 v152, v32, 24, s4
	s_ashr_i32 s4, s12, 3
	v_ashrrev_i32_e32 v153, 31, v152
	v_mov_b32_e32 v32, 0x3000
	v_or_b32_e32 v156, s14, v159
	v_mad_i64_i32 v[32:33], s[4:5], s4, v32, v[152:153]
	v_ashrrev_i32_e32 v157, 31, v156
	v_lshl_add_u64 v[150:151], v[32:33], 2, s[8:9]
	v_lshlrev_b64 v[32:33], 12, v[156:157]
	v_lshl_add_u64 v[32:33], s[0:1], 0, v[32:33]
	v_lshlrev_b64 v[148:149], 1, v[152:153]
	s_mov_b32 s14, 0x194000
	v_lshl_add_u64 v[154:155], v[32:33], 0, v[148:149]
	v_add_co_u32_e32 v132, vcc, s14, v150
	s_nop 0
	v_addc_co_u32_e32 v133, vcc, 0, v151, vcc
	s_mov_b64 s[4:5], 0x194000
	global_load_dwordx4 v[144:147], v[132:133], off
	v_lshl_add_u64 v[132:133], v[150:151], 0, s[4:5]
	global_load_dwordx4 v[140:143], v[132:133], off offset:16
	global_load_dwordx4 v[136:139], v[132:133], off offset:512
	s_nop 0
	global_load_dwordx4 v[132:135], v[132:133], off offset:528
	v_or_b32_e32 v164, 16, v156
	v_ashrrev_i32_e32 v165, 31, v164
	v_lshlrev_b64 v[164:165], 12, v[164:165]
	v_lshl_add_u64 v[164:165], s[0:1], 0, v[164:165]
	v_lshl_add_u64 v[164:165], v[164:165], 0, v[148:149]
	s_mov_b64 s[98:99], 0x10000
	s_mov_b64 s[100:101], 0x80000
	v_lshl_add_u64 v[232:233], v[154:155], 0, 0
	v_lshl_add_u64 v[234:235], v[232:233], 0, s[98:99]
	v_lshl_add_u64 v[236:237], v[234:235], 0, s[98:99]
	v_lshl_add_u64 v[238:239], v[236:237], 0, s[98:99]
	global_load_dwordx4 v[200:203], v[232:233], off
	global_load_dwordx4 v[204:207], v[232:233], off offset:256
	global_load_dwordx4 v[208:211], v[234:235], off
	global_load_dwordx4 v[212:215], v[234:235], off offset:256
	global_load_dwordx4 v[216:219], v[236:237], off
	global_load_dwordx4 v[220:223], v[236:237], off offset:256
	global_load_dwordx4 v[224:227], v[238:239], off
	global_load_dwordx4 v[228:231], v[238:239], off offset:256
	s_waitcnt vmcnt(0) lgkmcnt(0)
	v_lshlrev_b32_e32 v160, 16, v200
	v_and_b32_e32 v161, 0xffff0000, v200
	v_lshlrev_b32_e32 v32, 16, v201
	v_and_b32_e32 v33, 0xffff0000, v201
	v_lshlrev_b32_e32 v162, 16, v202
	v_and_b32_e32 v163, 0xffff0000, v202
	v_lshlrev_b32_e32 v34, 16, v203
	v_and_b32_e32 v35, 0xffff0000, v203
	v_pk_fma_f32 v[10:11], v[10:11], v[146:147], v[32:33]
	v_pk_fma_f32 v[8:9], v[8:9], v[144:145], v[160:161]
	v_pk_fma_f32 v[14:15], v[14:15], v[142:143], v[34:35]
	v_pk_fma_f32 v[12:13], v[12:13], v[140:141], v[162:163]
	v_cvt_pk_bf16_f32 v32, v8, v9
	v_cvt_pk_bf16_f32 v33, v10, v11
	s_nop 0
	v_cvt_pk_bf16_f32 v34, v12, v13
	v_cvt_pk_bf16_f32 v35, v14, v15
	s_nop 0
	global_store_dwordx4 v[154:155], v[32:35], off
	s_nop 1
	s_nop 0
	v_lshlrev_b32_e32 v32, 16, v204
	v_and_b32_e32 v33, 0xffff0000, v204
	v_lshlrev_b32_e32 v34, 16, v205
	v_and_b32_e32 v35, 0xffff0000, v205
	v_lshlrev_b32_e32 v160, 16, v206
	v_and_b32_e32 v161, 0xffff0000, v206
	v_lshlrev_b32_e32 v162, 16, v207
	v_and_b32_e32 v163, 0xffff0000, v207
	v_pk_fma_f32 v[34:35], v[26:27], v[138:139], v[34:35]
	v_pk_fma_f32 v[32:33], v[24:25], v[136:137], v[32:33]
	v_pk_fma_f32 v[26:27], v[18:19], v[134:135], v[162:163]
	v_pk_fma_f32 v[24:25], v[16:17], v[132:133], v[160:161]
	v_cvt_pk_bf16_f32 v16, v32, v33
	v_cvt_pk_bf16_f32 v17, v34, v35
	s_nop 0
	v_cvt_pk_bf16_f32 v18, v24, v25
	v_cvt_pk_bf16_f32 v19, v26, v27
	global_store_dwordx4 v[154:155], v[16:19], off offset:256
	s_nop 1
	v_lshlrev_b32_e32 v160, 16, v208
	v_and_b32_e32 v161, 0xffff0000, v208
	v_lshlrev_b32_e32 v16, 16, v209
	v_and_b32_e32 v17, 0xffff0000, v209
	v_lshlrev_b32_e32 v162, 16, v210
	v_and_b32_e32 v163, 0xffff0000, v210
	v_lshlrev_b32_e32 v166, 16, v211
	v_and_b32_e32 v167, 0xffff0000, v211
	v_pk_fma_f32 v[18:19], v[62:63], v[146:147], v[16:17]
	v_pk_fma_f32 v[16:17], v[60:61], v[144:145], v[160:161]
	v_pk_fma_f32 v[22:23], v[22:23], v[142:143], v[166:167]
	v_pk_fma_f32 v[20:21], v[20:21], v[140:141], v[162:163]
	v_cvt_pk_bf16_f32 v60, v16, v17
	v_cvt_pk_bf16_f32 v61, v18, v19
	v_or_b32_e32 v166, 32, v156
	v_cvt_pk_bf16_f32 v62, v20, v21
	v_cvt_pk_bf16_f32 v63, v22, v23
	v_ashrrev_i32_e32 v167, 31, v166
	v_lshlrev_b64 v[166:167], 12, v[166:167]
	global_store_dwordx4 v[164:165], v[60:63], off
	v_lshl_add_u64 v[166:167], s[0:1], 0, v[166:167]
	v_lshl_add_u64 v[166:167], v[166:167], 0, v[148:149]
	v_or_b32_e32 v156, 48, v156
	v_ashrrev_i32_e32 v157, 31, v156
	v_lshlrev_b64 v[156:157], 12, v[156:157]
	v_lshl_add_u64 v[156:157], s[0:1], 0, v[156:157]
	v_lshl_add_u64 v[156:157], v[156:157], 0, v[148:149]
	s_mov_b32 s0, 0x80000
	s_nop 1
	v_lshlrev_b32_e32 v60, 16, v212
	v_and_b32_e32 v61, 0xffff0000, v212
	v_lshlrev_b32_e32 v62, 16, v213
	v_and_b32_e32 v63, 0xffff0000, v213
	v_lshlrev_b32_e32 v160, 16, v214
	v_and_b32_e32 v161, 0xffff0000, v214
	v_lshlrev_b32_e32 v162, 16, v215
	v_and_b32_e32 v163, 0xffff0000, v215
	v_pk_fma_f32 v[62:63], v[58:59], v[138:139], v[62:63]
	v_pk_fma_f32 v[60:61], v[56:57], v[136:137], v[60:61]
	v_pk_fma_f32 v[58:59], v[50:51], v[134:135], v[162:163]
	v_pk_fma_f32 v[56:57], v[48:49], v[132:133], v[160:161]
	v_cvt_pk_bf16_f32 v48, v60, v61
	v_cvt_pk_bf16_f32 v49, v62, v63
	s_nop 0
	v_cvt_pk_bf16_f32 v50, v56, v57
	v_cvt_pk_bf16_f32 v51, v58, v59
	global_store_dwordx4 v[164:165], v[48:51], off offset:256
	s_nop 1
	v_lshlrev_b32_e32 v160, 16, v216
	v_and_b32_e32 v161, 0xffff0000, v216
	v_lshlrev_b32_e32 v48, 16, v217
	v_and_b32_e32 v49, 0xffff0000, v217
; __device__ __forceinline__ unsigned cvt_pk_bf16(float lo, float hi) { unsigned r; asm volatile("v_cvt_pk_bf16_f32 %0, %1, %2" : "=v"(r) : "v"(lo), "v"(hi)); return r; }
;     __device__ __forceinline__ void fused(f32x4 (&acc)[2][2][4][2], const Unit& un, int wr, int wc, int fr, int fq, PG8_LAS unsigned char* lds, int wid, int lane) const {
;     ...
;           for (int ai = 0; ai < 2; ++ai)
; #pragma unroll
;               for (int m = 0; m < 4; ++m) { const size_t off = (size_t)(row0 + ai * HALF + m * 16) * ldc + col0;
; #pragma unroll
;                   for (int bj = 0; bj < 2; ++bj) {
; #pragma unroll
;                       for (int n = 0; n < 2; ++n) { f32x4 bs;
;                           if (BASE_F32) bs = *(const f32x4*)((const float*)base + off + bj * HALF + n * 4);
;                           else { const u32x2v hw = *(const u32x2v*)((const bf16_t*)base + off + bj * HALF + n * 4);
;                                  bs = (f32x4){__uint_as_float(hw.x << 16), __uint_as_float(hw.x & 0xffff0000u), __uint_as_float(hw.y << 16), __uint_as_float(hw.y & 0xffff0000u)}; }
;                           acc[ai][bj][m][n] = bs + gv[bj][n] * acc[ai][bj][m][n]; }
;                       if (out_h) { const f32x4 a0 = acc[ai][bj][m][0], a1 = acc[ai][bj][m][1]; u32x4 w; w.x = cvt_pk_bf16(a0[0], a0[1]); w.y = cvt_pk_bf16(a0[2], a0[3]); w.z = cvt_pk_bf16(a1[0], a1[1]); w.w = cvt_pk_bf16(a1[2], a1[3]);
;                           *(u32x4*)(out_h + off + bj * HALF) = w; } }
;                   asm volatile("" : "+v"(acc[ai][0][m][0]), "+v"(acc[ai][0][m][1]), "+v"(acc[ai][1][m][0]), "+v"(acc[ai][1][m][1]));
;                   asm volatile("" ::: "memory"); } }
	v_lshlrev_b32_e32 v162, 16, v218
	v_and_b32_e32 v163, 0xffff0000, v218
	v_lshlrev_b32_e32 v164, 16, v219
	v_and_b32_e32 v165, 0xffff0000, v219
	v_pk_fma_f32 v[50:51], v[78:79], v[146:147], v[48:49]
	v_pk_fma_f32 v[48:49], v[76:77], v[144:145], v[160:161]
	v_pk_fma_f32 v[54:55], v[54:55], v[142:143], v[164:165]
	v_pk_fma_f32 v[52:53], v[52:53], v[140:141], v[162:163]
	v_cvt_pk_bf16_f32 v76, v48, v49
	v_cvt_pk_bf16_f32 v77, v50, v51
	s_nop 0
	v_cvt_pk_bf16_f32 v78, v52, v53
	v_cvt_pk_bf16_f32 v79, v54, v55
	s_nop 0
	global_store_dwordx4 v[166:167], v[76:79], off
	s_nop 1
	s_nop 0
	v_lshlrev_b32_e32 v76, 16, v220
	v_and_b32_e32 v77, 0xffff0000, v220
	v_lshlrev_b32_e32 v78, 16, v221
	v_and_b32_e32 v79, 0xffff0000, v221
	v_lshlrev_b32_e32 v160, 16, v222
	v_and_b32_e32 v161, 0xffff0000, v222
	v_lshlrev_b32_e32 v162, 16, v223
	v_and_b32_e32 v163, 0xffff0000, v223
	v_pk_fma_f32 v[78:79], v[74:75], v[138:139], v[78:79]
	v_pk_fma_f32 v[76:77], v[72:73], v[136:137], v[76:77]
	v_pk_fma_f32 v[74:75], v[66:67], v[134:135], v[162:163]
	v_pk_fma_f32 v[72:73], v[64:65], v[132:133], v[160:161]
	v_cvt_pk_bf16_f32 v64, v76, v77
	v_cvt_pk_bf16_f32 v65, v78, v79
	s_nop 0
	v_cvt_pk_bf16_f32 v66, v72, v73
	v_cvt_pk_bf16_f32 v67, v74, v75
	global_store_dwordx4 v[166:167], v[64:67], off offset:256
	s_nop 1
	v_lshlrev_b32_e32 v160, 16, v224
	v_and_b32_e32 v161, 0xffff0000, v224
	v_lshlrev_b32_e32 v64, 16, v225
	v_and_b32_e32 v65, 0xffff0000, v225
	v_lshlrev_b32_e32 v162, 16, v226
	v_and_b32_e32 v163, 0xffff0000, v226
	v_lshlrev_b32_e32 v164, 16, v227
	v_and_b32_e32 v165, 0xffff0000, v227
	v_pk_fma_f32 v[66:67], v[130:131], v[146:147], v[64:65]
	v_pk_fma_f32 v[64:65], v[128:129], v[144:145], v[160:161]
	v_pk_fma_f32 v[70:71], v[70:71], v[142:143], v[164:165]
	v_pk_fma_f32 v[68:69], v[68:69], v[140:141], v[162:163]
	v_cvt_pk_bf16_f32 v128, v64, v65
	v_cvt_pk_bf16_f32 v129, v66, v67
	v_add_co_u32_e32 v164, vcc, s0, v154
	v_cvt_pk_bf16_f32 v130, v68, v69
	v_cvt_pk_bf16_f32 v131, v70, v71
	s_nop 0
	v_addc_co_u32_e32 v165, vcc, 0, v155, vcc
	global_store_dwordx4 v[156:157], v[128:131], off
	s_mov_b64 s[0:1], 0x80000
	s_nop 1
	v_lshlrev_b32_e32 v128, 16, v228
	v_and_b32_e32 v129, 0xffff0000, v228
	v_lshlrev_b32_e32 v130, 16, v229
	v_and_b32_e32 v131, 0xffff0000, v229
	v_lshlrev_b32_e32 v160, 16, v230
	v_and_b32_e32 v161, 0xffff0000, v230
	v_lshlrev_b32_e32 v162, 16, v231
	v_and_b32_e32 v163, 0xffff0000, v231
	v_pk_fma_f32 v[110:111], v[110:111], v[138:139], v[130:131]
	v_pk_fma_f32 v[108:109], v[108:109], v[136:137], v[128:129]
	v_pk_fma_f32 v[98:99], v[98:99], v[134:135], v[162:163]
	v_pk_fma_f32 v[96:97], v[96:97], v[132:133], v[160:161]
	v_cvt_pk_bf16_f32 v128, v108, v109
	v_cvt_pk_bf16_f32 v129, v110, v111
	s_nop 0
	v_cvt_pk_bf16_f32 v130, v96, v97
	v_cvt_pk_bf16_f32 v131, v98, v99
	global_store_dwordx4 v[156:157], v[128:131], off offset:256
	v_lshl_add_u64 v[156:157], v[154:155], 0, s[0:1]
	s_mov_b32 s0, 0x90000
	v_add_co_u32_e32 v166, vcc, s0, v154
	s_mov_b64 s[0:1], 0x90000
	s_nop 0
	v_addc_co_u32_e32 v167, vcc, 0, v155, vcc
	v_lshl_add_u64 v[232:233], v[232:233], 0, s[100:101]
	v_lshl_add_u64 v[234:235], v[234:235], 0, s[100:101]
	v_lshl_add_u64 v[236:237], v[236:237], 0, s[100:101]
	v_lshl_add_u64 v[238:239], v[238:239], 0, s[100:101]
	global_load_dwordx4 v[200:203], v[232:233], off
	global_load_dwordx4 v[204:207], v[232:233], off offset:256
	global_load_dwordx4 v[208:211], v[234:235], off
	global_load_dwordx4 v[212:215], v[234:235], off offset:256
	global_load_dwordx4 v[216:219], v[236:237], off
	global_load_dwordx4 v[220:223], v[236:237], off offset:256
	global_load_dwordx4 v[224:227], v[238:239], off
	global_load_dwordx4 v[228:231], v[238:239], off offset:256
	s_waitcnt vmcnt(0) lgkmcnt(0)
	v_lshlrev_b32_e32 v160, 16, v200
	v_and_b32_e32 v161, 0xffff0000, v200
	v_lshlrev_b32_e32 v128, 16, v201
	v_and_b32_e32 v129, 0xffff0000, v201
	v_lshlrev_b32_e32 v162, 16, v202
	v_and_b32_e32 v163, 0xffff0000, v202
	v_lshlrev_b32_e32 v130, 16, v203
	v_and_b32_e32 v131, 0xffff0000, v203
	v_pk_fma_f32 v[102:103], v[102:103], v[146:147], v[128:129]
	v_pk_fma_f32 v[100:101], v[100:101], v[144:145], v[160:161]
	v_pk_fma_f32 v[106:107], v[106:107], v[142:143], v[130:131]
	v_pk_fma_f32 v[104:105], v[104:105], v[140:141], v[162:163]
	v_cvt_pk_bf16_f32 v128, v100, v101
	v_cvt_pk_bf16_f32 v129, v102, v103
	s_nop 0
	v_cvt_pk_bf16_f32 v130, v104, v105
	v_cvt_pk_bf16_f32 v131, v106, v107
	s_nop 0
	global_store_dwordx4 v[164:165], v[128:131], off
	s_nop 1
	s_nop 0
	v_lshlrev_b32_e32 v128, 16, v204
	v_and_b32_e32 v129, 0xffff0000, v204
	v_lshlrev_b32_e32 v130, 16, v205
	v_and_b32_e32 v131, 0xffff0000, v205
	v_lshlrev_b32_e32 v160, 16, v206
	v_and_b32_e32 v161, 0xffff0000, v206
	v_lshlrev_b32_e32 v162, 16, v207
	v_and_b32_e32 v163, 0xffff0000, v207
	v_pk_fma_f32 v[126:127], v[126:127], v[138:139], v[130:131]
	v_pk_fma_f32 v[124:125], v[124:125], v[136:137], v[128:129]
	v_pk_fma_f32 v[114:115], v[114:115], v[134:135], v[162:163]
	v_pk_fma_f32 v[112:113], v[112:113], v[132:133], v[160:161]
	v_cvt_pk_bf16_f32 v128, v124, v125
	v_cvt_pk_bf16_f32 v129, v126, v127
	s_nop 0
	v_cvt_pk_bf16_f32 v130, v112, v113
	v_cvt_pk_bf16_f32 v131, v114, v115
	global_store_dwordx4 v[156:157], v[128:131], off offset:256
	v_lshl_add_u64 v[156:157], v[154:155], 0, s[0:1]
	s_mov_b32 s0, 0xa0000
	v_add_co_u32_e32 v164, vcc, s0, v154
	s_mov_b64 s[0:1], 0xa0000
	s_nop 0
	v_addc_co_u32_e32 v165, vcc, 0, v155, vcc
	s_nop 1
	v_lshlrev_b32_e32 v160, 16, v208
	v_and_b32_e32 v161, 0xffff0000, v208
	v_lshlrev_b32_e32 v128, 16, v209
	v_and_b32_e32 v129, 0xffff0000, v209
	v_lshlrev_b32_e32 v162, 16, v210
; __device__ __forceinline__ unsigned cvt_pk_bf16(float lo, float hi) { unsigned r; asm volatile("v_cvt_pk_bf16_f32 %0, %1, %2" : "=v"(r) : "v"(lo), "v"(hi)); return r; }
;     __device__ __forceinline__ void fused(f32x4 (&acc)[2][2][4][2], const Unit& un, int wr, int wc, int fr, int fq, PG8_LAS unsigned char* lds, int wid, int lane) const {
;     ...
;           for (int ai = 0; ai < 2; ++ai)
; #pragma unroll
;               for (int m = 0; m < 4; ++m) { const size_t off = (size_t)(row0 + ai * HALF + m * 16) * ldc + col0;
; #pragma unroll
;                   for (int bj = 0; bj < 2; ++bj) {
; #pragma unroll
;                       for (int n = 0; n < 2; ++n) { f32x4 bs;
;                           if (BASE_F32) bs = *(const f32x4*)((const float*)base + off + bj * HALF + n * 4);
;                           else { const u32x2v hw = *(const u32x2v*)((const bf16_t*)base + off + bj * HALF + n * 4);
;                                  bs = (f32x4){__uint_as_float(hw.x << 16), __uint_as_float(hw.x & 0xffff0000u), __uint_as_float(hw.y << 16), __uint_as_float(hw.y & 0xffff0000u)}; }
;                           acc[ai][bj][m][n] = bs + gv[bj][n] * acc[ai][bj][m][n]; }
;                       if (out_h) { const f32x4 a0 = acc[ai][bj][m][0], a1 = acc[ai][bj][m][1]; u32x4 w; w.x = cvt_pk_bf16(a0[0], a0[1]); w.y = cvt_pk_bf16(a0[2], a0[3]); w.z = cvt_pk_bf16(a1[0], a1[1]); w.w = cvt_pk_bf16(a1[2], a1[3]);
;                           *(u32x4*)(out_h + off + bj * HALF) = w; } }
;                   asm volatile("" : "+v"(acc[ai][0][m][0]), "+v"(acc[ai][0][m][1]), "+v"(acc[ai][1][m][0]), "+v"(acc[ai][1][m][1]));
;                   asm volatile("" ::: "memory"); } }
; #pragma unroll
;         for (int ai = 0; ai < 2; ++ai)
; #pragma unroll
;             for (int m = 0; m < 4; ++m) { float s = 0.f;
; #pragma unroll
;                 for (int bj = 0; bj < 2; ++bj)
; #pragma unroll
;                     for (int n = 0; n < 2; ++n) { const f32x4 x = acc[ai][bj][m][n]; s += (x[0] * x[0] + x[1] * x[1]) + (x[2] * x[2] + x[3] * x[3]); }
;                 s += __shfl_xor(s, 16); s += __shfl_xor(s, 32);
;                 if (fq == 0) P[(ai * HALF + wr * 64 + m * 16 + fr) * 4 + wc] = s; }
	v_and_b32_e32 v163, 0xffff0000, v210
	v_lshlrev_b32_e32 v130, 16, v211
	v_and_b32_e32 v131, 0xffff0000, v211
	v_pk_fma_f32 v[118:119], v[118:119], v[146:147], v[128:129]
	v_pk_fma_f32 v[116:117], v[116:117], v[144:145], v[160:161]
	v_pk_fma_f32 v[122:123], v[122:123], v[142:143], v[130:131]
	v_pk_fma_f32 v[120:121], v[120:121], v[140:141], v[162:163]
	v_cvt_pk_bf16_f32 v128, v116, v117
	v_cvt_pk_bf16_f32 v129, v118, v119
	s_nop 0
	v_cvt_pk_bf16_f32 v130, v120, v121
	v_cvt_pk_bf16_f32 v131, v122, v123
	s_nop 0
	global_store_dwordx4 v[166:167], v[128:131], off
	s_nop 1
	s_nop 0
	v_lshlrev_b32_e32 v128, 16, v212
	v_and_b32_e32 v129, 0xffff0000, v212
	v_lshlrev_b32_e32 v130, 16, v213
	v_and_b32_e32 v131, 0xffff0000, v213
	v_lshlrev_b32_e32 v160, 16, v214
	v_and_b32_e32 v161, 0xffff0000, v214
	v_lshlrev_b32_e32 v162, 16, v215
	v_and_b32_e32 v163, 0xffff0000, v215
	v_pk_fma_f32 v[94:95], v[94:95], v[138:139], v[130:131]
	v_pk_fma_f32 v[92:93], v[92:93], v[136:137], v[128:129]
	v_pk_fma_f32 v[90:91], v[90:91], v[134:135], v[162:163]
	v_pk_fma_f32 v[88:89], v[88:89], v[132:133], v[160:161]
	v_cvt_pk_bf16_f32 v128, v92, v93
	v_cvt_pk_bf16_f32 v129, v94, v95
	s_nop 0
	v_cvt_pk_bf16_f32 v130, v88, v89
	v_cvt_pk_bf16_f32 v131, v90, v91
	global_store_dwordx4 v[156:157], v[128:131], off offset:256
	v_lshl_add_u64 v[156:157], v[154:155], 0, s[0:1]
	s_mov_b32 s0, 0xb0000
	v_add_co_u32_e32 v166, vcc, s0, v154
	s_mov_b64 s[0:1], 0xb0000
	s_nop 0
	v_addc_co_u32_e32 v167, vcc, 0, v155, vcc
	s_nop 1
	v_lshlrev_b32_e32 v160, 16, v216
	v_and_b32_e32 v161, 0xffff0000, v216
	v_lshlrev_b32_e32 v128, 16, v217
	v_and_b32_e32 v129, 0xffff0000, v217
	v_lshlrev_b32_e32 v162, 16, v218
	v_and_b32_e32 v163, 0xffff0000, v218
	v_lshlrev_b32_e32 v130, 16, v219
	v_and_b32_e32 v131, 0xffff0000, v219
	v_pk_fma_f32 v[86:87], v[86:87], v[146:147], v[128:129]
	v_pk_fma_f32 v[84:85], v[84:85], v[144:145], v[160:161]
	v_pk_fma_f32 v[82:83], v[82:83], v[142:143], v[130:131]
	v_pk_fma_f32 v[80:81], v[80:81], v[140:141], v[162:163]
	v_cvt_pk_bf16_f32 v128, v84, v85
	v_cvt_pk_bf16_f32 v129, v86, v87
	s_nop 0
	v_cvt_pk_bf16_f32 v130, v80, v81
	v_cvt_pk_bf16_f32 v131, v82, v83
	s_nop 0
	global_store_dwordx4 v[164:165], v[128:131], off
	v_mul_f32_e32 v164, v25, v25
	v_mul_f32_e32 v165, v27, v27
	v_fmac_f32_e32 v164, v24, v24
	v_fmac_f32_e32 v165, v26, v26
	s_nop 1
	v_lshlrev_b32_e32 v128, 16, v220
	v_and_b32_e32 v129, 0xffff0000, v220
	v_lshlrev_b32_e32 v130, 16, v221
	v_and_b32_e32 v131, 0xffff0000, v221
	v_lshlrev_b32_e32 v160, 16, v222
	v_and_b32_e32 v161, 0xffff0000, v222
	v_lshlrev_b32_e32 v162, 16, v223
	v_and_b32_e32 v163, 0xffff0000, v223
	v_pk_fma_f32 v[46:47], v[46:47], v[138:139], v[130:131]
	v_pk_fma_f32 v[44:45], v[44:45], v[136:137], v[128:129]
	v_pk_fma_f32 v[42:43], v[42:43], v[134:135], v[162:163]
	v_pk_fma_f32 v[40:41], v[40:41], v[132:133], v[160:161]
	v_cvt_pk_bf16_f32 v128, v44, v45
	v_cvt_pk_bf16_f32 v129, v46, v47
	v_lshl_add_u64 v[160:161], v[154:155], 0, s[0:1]
	v_cvt_pk_bf16_f32 v130, v40, v41
	v_cvt_pk_bf16_f32 v131, v42, v43
	global_store_dwordx4 v[156:157], v[128:131], off offset:256
	v_mul_f32_e32 v162, v33, v33
	v_mul_f32_e32 v163, v35, v35
	v_fmac_f32_e32 v162, v32, v32
	v_fmac_f32_e32 v163, v34, v34
	s_lshl_b32 s0, s26, 2
	s_add_i32 s0, s0, 0
	s_nop 1
	v_lshlrev_b32_e32 v154, 16, v224
	v_and_b32_e32 v155, 0xffff0000, v224
	v_lshlrev_b32_e32 v128, 16, v225
	v_and_b32_e32 v129, 0xffff0000, v225
	v_lshlrev_b32_e32 v156, 16, v226
	v_and_b32_e32 v157, 0xffff0000, v226
	v_lshlrev_b32_e32 v130, 16, v227
	v_and_b32_e32 v131, 0xffff0000, v227
	v_pk_fma_f32 v[38:39], v[38:39], v[146:147], v[128:129]
	v_pk_fma_f32 v[36:37], v[36:37], v[144:145], v[154:155]
	v_pk_fma_f32 v[30:31], v[30:31], v[142:143], v[130:131]
	v_pk_fma_f32 v[28:29], v[28:29], v[140:141], v[156:157]
	v_cvt_pk_bf16_f32 v142, v36, v37
	v_cvt_pk_bf16_f32 v143, v38, v39
	v_mbcnt_lo_u32_b32 v128, -1, 0
	v_cvt_pk_bf16_f32 v144, v28, v29
	v_cvt_pk_bf16_f32 v145, v30, v31
	v_mbcnt_hi_u32_b32 v129, -1, v128
	v_mul_f32_e32 v140, v9, v9
	v_mul_f32_e32 v141, v11, v11
	v_mul_f32_e32 v146, v13, v13
	v_mul_f32_e32 v147, v15, v15
	v_and_b32_e32 v130, 64, v129
	v_fmac_f32_e32 v140, v8, v8
	v_fmac_f32_e32 v141, v10, v10
	v_fmac_f32_e32 v146, v12, v12
	v_fmac_f32_e32 v147, v14, v14
	v_xor_b32_e32 v128, 16, v129
	v_add_u32_e32 v130, 64, v130
	v_add_f32_e32 v140, v140, v141
	v_add_f32_e32 v141, v146, v147
	v_cmp_lt_i32_e32 vcc, v128, v130
	v_add_f32_e32 v146, v162, v163
	v_add_f32_e32 v140, v140, v141
	v_cndmask_b32_e32 v128, v129, v128, vcc
	v_add_f32_e32 v147, v164, v165
	v_add_f32_e32 v140, v146, v140
	v_lshlrev_b32_e32 v128, 2, v128
	v_add_f32_e32 v140, v147, v140
	ds_bpermute_b32 v141, v128, v140
	v_xor_b32_e32 v131, 32, v129
	v_cmp_lt_i32_e32 vcc, v131, v130
	global_store_dwordx4 v[166:167], v[142:145], off
	v_and_b32_e32 v130, 63, v158
	v_cndmask_b32_e32 v129, v129, v131, vcc
	v_lshlrev_b32_e32 v129, 2, v129
	s_waitcnt lgkmcnt(0)
	v_add_f32_e32 v140, v140, v141
	ds_bpermute_b32 v141, v129, v140
	v_cmp_gt_u32_e32 vcc, 16, v130
	s_waitcnt vmcnt(0)
	v_lshlrev_b32_e32 v142, 16, v228
	v_and_b32_e32 v143, 0xffff0000, v228
	v_lshlrev_b32_e32 v144, 16, v229
	v_and_b32_e32 v145, 0xffff0000, v229
	v_lshlrev_b32_e32 v146, 16, v230
	v_and_b32_e32 v147, 0xffff0000, v230
	v_lshlrev_b32_e32 v154, 16, v231
	v_and_b32_e32 v155, 0xffff0000, v231
	v_pk_fma_f32 v[6:7], v[6:7], v[138:139], v[144:145]
	v_pk_fma_f32 v[4:5], v[4:5], v[136:137], v[142:143]
	v_pk_fma_f32 v[2:3], v[2:3], v[134:135], v[154:155]
	v_pk_fma_f32 v[0:1], v[0:1], v[132:133], v[146:147]
	v_cvt_pk_bf16_f32 v132, v4, v5
	v_cvt_pk_bf16_f32 v133, v6, v7
	v_or_b32_e32 v144, s13, v159
	v_cvt_pk_bf16_f32 v134, v0, v1
	v_cvt_pk_bf16_f32 v135, v2, v3
	global_store_dwordx4 v[160:161], v[132:135], off offset:256
	v_lshl_add_u32 v131, v144, 4, s0
	s_and_saveexec_b64 s[0:1], vcc
	v_readlane_b32 s96, v254, 47
	s_cbranch_execz .LBB0_3613
	s_waitcnt lgkmcnt(0)
	v_add_f32_e32 v132, v140, v141
	ds_write_b32 v131, v132

;     __device__ __forceinline__ void fused(f32x4 (&acc)[2][2][4][2], const Unit& un, int wr, int wc, int fr, int fq, PG8_LAS unsigned char* lds, int wid, int lane) const {
;     ...
;         asm volatile("s_waitcnt lgkmcnt(0)" ::: "memory"); __builtin_amdgcn_s_barrier(); asm volatile("" ::: "memory");
;         const int row = wid * 32 + (lane & 31);
;         if (lane < 32) { const float tot = (P[row * 4 + 0] + P[row * 4 + 1]) + (P[row * 4 + 2] + P[row * 4 + 3]);
;             __hip_atomic_store(xbuf + ((size_t)(un.pm * BM + row) * 8 + un.pn), __float_as_uint(tot), __ATOMIC_RELAXED, __HIP_MEMORY_SCOPE_AGENT); }
.LBB0_3627:
	s_or_b64 exec, exec, s[0:1]
	s_add_u32 s14, s8, 0x3c780000
	s_addc_u32 s15, s9, 0
	s_lshl_b32 s0, s25, 5
	s_waitcnt lgkmcnt(0)
	s_barrier
	v_and_or_b32 v134, v158, 31, s0
	v_add_u32_e32 v128, s27, v134
	v_cmp_gt_u32_e64 s[0:1], 32, v130
	s_waitcnt lgkmcnt(0)
	v_ashrrev_i32_e32 v129, 31, v128
	s_and_saveexec_b64 s[4:5], s[0:1]
	s_cbranch_execz .LBB0_3629
	v_lshl_add_u32 v131, v134, 4, 0
	ds_read_b128 v[136:139], v131
	v_lshlrev_b64 v[132:133], 5, v[128:129]
	v_lshl_add_u64 v[132:133], s[14:15], 0, v[132:133]
	v_lshl_add_u64 v[132:133], s[2:3], 2, v[132:133]
	s_waitcnt lgkmcnt(0)
	v_mov_b32_e32 v140, v137
	v_mov_b32_e32 v141, v138
	v_mov_b32_e32 v137, v139
	v_pk_add_f32 v[136:137], v[140:141], v[136:137]
	s_nop 0
	v_pk_add_f32 v[136:137], v[136:137], v[136:137] op_sel:[0,1] op_sel_hi:[1,0]
	global_store_dword v[132:133], v136, off sc1

;     __device__ __forceinline__ void fused(f32x4 (&acc)[2][2][4][2], const Unit& un, int wr, int wc, int fr, int fq, PG8_LAS unsigned char* lds, int wid, int lane) const {
;     ...
;         if (wid == 0) {
;             bool dead = false; const unsigned long long t0 = __builtin_amdgcn_s_memrealtime();
;             for (;;) {
;                 if ((unsigned)__builtin_amdgcn_readfirstlane(__hip_atomic_load(cnt + 64 * un.pm, __ATOMIC_RELAXED, __HIP_MEMORY_SCOPE_AGENT)) >= 64u) break;
;                 if (__builtin_amdgcn_s_memrealtime() - t0 > 2000000ull) {
;                     if (lane == 0) { unsigned expect = 0u; __hip_atomic_compare_exchange_strong(tmo + 1, &expect, code | (unsigned)(un.pm & 0xff), __ATOMIC_RELAXED, __ATOMIC_RELAXED, __HIP_MEMORY_SCOPE_AGENT);
;                                      __hip_atomic_store(tmo, 1u, __ATOMIC_RELAXED, __HIP_MEMORY_SCOPE_AGENT); }
;                     dead = true; break; }
;                 __builtin_amdgcn_s_sleep(2);
;             }
.LBB0_3635:
	global_load_dword v135, v[130:131], off sc1
	s_mov_b64 s[20:21], -1
	s_mov_b64 s[22:23], -1
	s_waitcnt vmcnt(0) lgkmcnt(0)
	v_readfirstlane_b32 s13, v135
	s_cmp_gt_u32 s13, 63
	s_cbranch_scc1 .LBB0_3634
	s_memrealtime s[20:21]
	s_waitcnt lgkmcnt(0)
	s_sub_u32 s20, s20, s16
	s_subb_u32 s21, s21, s17
	v_cmp_lt_u64_e32 vcc, s[20:21], v[132:133]
	s_cbranch_vccz .LBB0_3633
	s_mov_b64 s[22:23], 0
	s_sleep 2
	s_branch .LBB0_3633

;     __device__ __forceinline__ void fused(f32x4 (&acc)[2][2][4][2], const Unit& un, int wr, int wc, int fr, int fq, PG8_LAS unsigned char* lds, int wid, int lane) const {
;     ...
;                 if (__builtin_amdgcn_s_memrealtime() - t0 > 2000000ull) {
;                     if (lane == 0) { unsigned expect = 0u; __hip_atomic_compare_exchange_strong(tmo + 1, &expect, code | (unsigned)(un.pm & 0xff), __ATOMIC_RELAXED, __ATOMIC_RELAXED, __HIP_MEMORY_SCOPE_AGENT);
;                                      __hip_atomic_store(tmo, 1u, __ATOMIC_RELAXED, __HIP_MEMORY_SCOPE_AGENT); }
;                     dead = true; break; }
.LBB0_3641:
	s_or_saveexec_b64 s[16:17], s[4:5]
	s_mov_b64 s[4:5], 0
	s_xor_b64 exec, exec, s[16:17]
	s_cbranch_execz .LBB0_3643
	s_and_b32 s12, s12, 0x9f
	s_or_b32 s12, s12, 0x760
	v_mov_b32_e32 v130, s12
	v_mov_b32_e32 v131, 0
	v_mov_b64_e32 v[132:133], s[8:9]
	flat_atomic_cmpswap v[132:133], v[130:131] offset:4
	s_mov_b64 s[4:5], exec
	v_mov_b32_e32 v130, 1
	global_store_dword v[132:133], v130, off sc1

;     __device__ __forceinline__ void fused(f32x4 (&acc)[2][2][4][2], const Unit& un, int wr, int wc, int fr, int fq, PG8_LAS unsigned char* lds, int wid, int lane) const {
;     ...
;         asm volatile("s_waitcnt vmcnt(0) lgkmcnt(0)" ::: "memory"); __builtin_amdgcn_s_barrier(); asm volatile("" ::: "memory");
;         const bool bad = flag[0] != 0u;
;         if (lane < 32) { const unsigned* slot = xbuf + (size_t)(un.pm * BM + row) * 8; float q = 0.f;
; #pragma unroll
;             for (int t = 0; t < 8; ++t) q += __uint_as_float(__hip_atomic_load(slot + t, __ATOMIC_RELAXED, __HIP_MEMORY_SCOPE_AGENT));
;             S[row] = 1.0f / sqrtf(q * (1.0f / 2048.0f) + eps); }
;         asm volatile("s_waitcnt lgkmcnt(0)" ::: "memory"); __builtin_amdgcn_s_barrier(); asm volatile("" ::: "memory");
;         const float qnan = __builtin_nanf("");
;         f32x4 cg[2][2], sh[2][2];
; #pragma unroll
;         for (int bj = 0; bj < 2; ++bj)
; #pragma unroll
;             for (int n = 0; n < 2; ++n) { const f32x4 g4 = *(const f32x4*)(gain + col0 + bj * HALF + n * 4);
;                 if (MODE == 0) { const f32x4 sc4 = *(const f32x4*)(scale + boff + bj * HALF + n * 4); cg[bj][n] = g4 * (sc4 + 1.0f); sh[bj][n] = *(const f32x4*)(shift + boff + bj * HALF + n * 4); }
;                 else { cg[bj][n] = g4; sh[bj][n] = (f32x4){0.f, 0.f, 0.f, 0.f}; } }
; #pragma unroll
;         for (int ai = 0; ai < 2; ++ai)
; #pragma unroll
;             for (int m = 0; m < 4; ++m) { const int r = ai * HALF + wr * 64 + m * 16 + fr; const float rs = S[r]; const size_t off = (size_t)(un.pm * BM + r) * ldc + col0;
; #pragma unroll
;                 for (int bj = 0; bj < 2; ++bj) { f32x4 y0 = (acc[ai][bj][m][0] * rs) * cg[bj][0] + sh[bj][0], y1 = (acc[ai][bj][m][1] * rs) * cg[bj][1] + sh[bj][1];
.LBB0_3649:
	s_waitcnt vmcnt(0) lgkmcnt(0)
	s_barrier
	v_mov_b32_e32 v130, 0
	ds_read_b32 v158, v130 offset:5120
	s_and_saveexec_b64 s[2:3], s[0:1]
	s_cbranch_execz .LBB0_3651
	v_lshlrev_b64 v[128:129], 5, v[128:129]
	v_lshl_add_u64 v[128:129], s[14:15], 0, v[128:129]
	global_load_dword v130, v[128:129], off sc1
	global_load_dword v131, v[128:129], off offset:4 sc1
	global_load_dword v132, v[128:129], off offset:8 sc1
	global_load_dword v133, v[128:129], off offset:12 sc1
	global_load_dword v135, v[128:129], off offset:16 sc1
	global_load_dword v136, v[128:129], off offset:20 sc1
	global_load_dword v137, v[128:129], off offset:24 sc1
	s_nop 0
	global_load_dword v128, v[128:129], off offset:28 sc1
	v_mov_b32_e32 v129, 0x358637bd
	s_mov_b32 s0, 0xf800000
	s_waitcnt vmcnt(0) lgkmcnt(0)
	v_add_f32_e32 v130, 0, v130
	v_add_f32_e32 v130, v130, v131
	v_add_f32_e32 v130, v130, v132
	v_add_f32_e32 v130, v130, v133
	v_add_f32_e32 v130, v130, v135
	v_add_f32_e32 v130, v130, v136
	v_add_f32_e32 v130, v130, v137
	v_add_f32_e32 v128, v130, v128
	v_fmac_f32_e32 v129, 0x3a000000, v128
	v_mul_f32_e32 v128, 0x4f800000, v129
	v_cmp_gt_f32_e32 vcc, s0, v129
	v_mov_b32_e32 v130, 0x260
	s_nop 0
	v_cndmask_b32_e32 v128, v129, v128, vcc
	v_sqrt_f32_e32 v129, v128
	s_nop 0
	v_add_u32_e32 v131, -1, v129
	v_add_u32_e32 v132, 1, v129
	v_fma_f32 v133, -v131, v129, v128
	v_fma_f32 v135, -v132, v129, v128
	v_cmp_ge_f32_e64 s[0:1], 0, v133
	s_nop 1
	v_cndmask_b32_e64 v129, v129, v131, s[0:1]
	v_cmp_lt_f32_e64 s[0:1], 0, v135
	s_nop 1
	v_cndmask_b32_e64 v129, v129, v132, s[0:1]
	v_mul_f32_e32 v131, 0x37800000, v129
	v_cndmask_b32_e32 v129, v129, v131, vcc
	v_cmp_class_f32_e32 vcc, v128, v130
	s_nop 1
	v_cndmask_b32_e32 v128, v129, v128, vcc
	v_div_scale_f32 v129, s[0:1], v128, v128, 1.0
	v_rcp_f32_e32 v130, v129
	v_div_scale_f32 v131, vcc, 1.0, v128, 1.0
	v_fma_f32 v132, -v129, v130, 1.0
	v_fmac_f32_e32 v130, v132, v130
	v_mul_f32_e32 v132, v131, v130
	v_fma_f32 v133, -v129, v132, v131
	v_fmac_f32_e32 v132, v133, v130
	v_fma_f32 v129, -v129, v132, v131
	v_div_fmas_f32 v129, v129, v130, v132
	v_div_fixup_f32 v128, v129, v128, 1.0
	v_lshl_add_u32 v129, v134, 2, 0
	ds_write_b32 v129, v128 offset:4096
.LBB0_3651:
	s_or_b64 exec, exec, s[2:3]
	v_readlane_b32 s36, v254, 11
	v_readlane_b32 s42, v254, 17
	v_readlane_b32 s43, v254, 18
	s_mov_b64 s[0:1], 0x6000
	s_waitcnt lgkmcnt(0)
	s_barrier
	v_lshl_add_u64 v[128:129], v[152:153], 2, s[42:43]
	v_lshl_add_u64 v[130:131], v[128:129], 0, s[0:1]
	s_mov_b64 s[0:1], 0x198000
	v_lshl_add_u64 v[136:137], v[150:151], 0, s[0:1]
	s_mov_b64 s[0:1], 0x196000
	v_lshl_add_u64 v[138:139], v[150:151], 0, s[0:1]
	s_movk_i32 s0, 0x6000
	v_add_co_u32_e32 v128, vcc, s0, v128
	s_mov_b32 s0, 0x198000
	s_nop 0
	v_addc_co_u32_e32 v129, vcc, 0, v129, vcc
	global_load_dwordx4 v[160:163], v[128:129], off
	global_load_dwordx4 v[152:155], v[136:137], off offset:16
	v_add_co_u32_e32 v128, vcc, s0, v150
	global_load_dwordx4 v[164:167], v[136:137], off offset:512
	global_load_dwordx4 v[132:135], v[138:139], off offset:16
	global_load_dwordx4 v[168:171], v[136:137], off offset:528
	global_load_dwordx4 v[172:175], v[130:131], off offset:16
	global_load_dwordx4 v[176:179], v[130:131], off offset:512
	v_addc_co_u32_e32 v129, vcc, 0, v151, vcc
	global_load_dwordx4 v[180:183], v[130:131], off offset:528
	global_load_dwordx4 v[184:187], v[128:129], off
	s_mov_b32 s0, 0x196000
	v_add_co_u32_e32 v128, vcc, s0, v150
	v_lshl_add_u32 v157, v144, 2, 0
	s_nop 0
	v_addc_co_u32_e32 v129, vcc, 0, v151, vcc
	global_load_dwordx4 v[140:143], v[128:129], off
	s_nop 0
	global_load_dwordx4 v[128:131], v[138:139], off offset:512
	s_nop 0
	global_load_dwordx4 v[136:139], v[138:139], off offset:528
	ds_read_b32 v188, v157 offset:4096
	v_add_u32_e32 v144, s27, v144
	s_add_u32 s0, s8, 0x1e600000
	v_ashrrev_i32_e32 v145, 31, v144
	s_addc_u32 s1, s9, 0
	v_lshlrev_b64 v[146:147], 12, v[144:145]
	s_waitcnt lgkmcnt(0)
	v_pk_mul_f32 v[192:193], v[8:9], v[188:189] op_sel_hi:[1,0]
	v_pk_mul_f32 v[194:195], v[10:11], v[188:189] op_sel_hi:[1,0]
	v_lshl_add_u64 v[190:191], s[0:1], 0, v[146:147]
	v_pk_mul_f32 v[196:197], v[12:13], v[188:189] op_sel_hi:[1,0]
	v_pk_mul_f32 v[198:199], v[14:15], v[188:189] op_sel_hi:[1,0]
	v_mov_b32_e32 v156, 0x7fc00000
	v_cmp_eq_u32_e32 vcc, 0, v158
	v_pk_mul_f32 v[24:25], v[24:25], v[188:189] op_sel_hi:[1,0]
	v_pk_mul_f32 v[26:27], v[26:27], v[188:189] op_sel_hi:[1,0]
	v_pk_mul_f32 v[32:33], v[32:33], v[188:189] op_sel_hi:[1,0]
	v_pk_mul_f32 v[34:35], v[34:35], v[188:189] op_sel_hi:[1,0]
	v_readlane_b32 s37, v254, 12
	v_readlane_b32 s38, v254, 13
	v_readlane_b32 s39, v254, 14
	v_readlane_b32 s40, v254, 15
	v_readlane_b32 s41, v254, 16
	v_readlane_b32 s44, v254, 19
	v_readlane_b32 s45, v254, 20
	v_readlane_b32 s46, v254, 21
	v_readlane_b32 s47, v254, 22
	v_readlane_b32 s48, v254, 23
	v_readlane_b32 s49, v254, 24
	v_readlane_b32 s50, v254, 25
	v_readlane_b32 s51, v254, 26
	s_waitcnt vmcnt(0)
; __device__ __forceinline__ unsigned cvt_pk_bf16(float lo, float hi) { unsigned r; asm volatile("v_cvt_pk_bf16_f32 %0, %1, %2" : "=v"(r) : "v"(lo), "v"(hi)); return r; }
;     __device__ __forceinline__ void fused(f32x4 (&acc)[2][2][4][2], const Unit& un, int wr, int wc, int fr, int fq, PG8_LAS unsigned char* lds, int wid, int lane) const {
;     ...
;         for (int ai = 0; ai < 2; ++ai)
; #pragma unroll
;             for (int m = 0; m < 4; ++m) { const int r = ai * HALF + wr * 64 + m * 16 + fr; const float rs = S[r]; const size_t off = (size_t)(un.pm * BM + r) * ldc + col0;
; #pragma unroll
;                 for (int bj = 0; bj < 2; ++bj) { f32x4 y0 = (acc[ai][bj][m][0] * rs) * cg[bj][0] + sh[bj][0], y1 = (acc[ai][bj][m][1] * rs) * cg[bj][1] + sh[bj][1];
;                     if (bad) { y0 = (f32x4){qnan, qnan, qnan, qnan}; y1 = y0; }
;                     if (MODE == 0) { u32x4 w; w.x = cvt_pk_bf16(y0[0], y0[1]); w.y = cvt_pk_bf16(y0[2], y0[3]); w.z = cvt_pk_bf16(y1[0], y1[1]); w.w = cvt_pk_bf16(y1[2], y1[3]); *(u32x4*)(u + off + bj * HALF) = w; }
	v_pk_add_f32 v[12:13], v[166:167], 1.0 op_sel_hi:[1,0]
	v_pk_add_f32 v[8:9], v[154:155], 1.0 op_sel_hi:[1,0]
	v_pk_add_f32 v[10:11], v[152:153], 1.0 op_sel_hi:[1,0]
	v_pk_add_f32 v[152:153], v[170:171], 1.0 op_sel_hi:[1,0]
	v_pk_add_f32 v[154:155], v[168:169], 1.0 op_sel_hi:[1,0]
	v_pk_mul_f32 v[146:147], v[174:175], v[8:9]
	v_pk_mul_f32 v[150:151], v[172:173], v[10:11]
	v_pk_mul_f32 v[8:9], v[182:183], v[152:153]
	v_pk_mul_f32 v[10:11], v[180:181], v[154:155]
	v_pk_add_f32 v[152:153], v[186:187], 1.0 op_sel_hi:[1,0]
	v_pk_add_f32 v[154:155], v[184:185], 1.0 op_sel_hi:[1,0]
	v_pk_mul_f32 v[152:153], v[162:163], v[152:153]
	v_pk_mul_f32 v[154:155], v[160:161], v[154:155]
	v_pk_add_f32 v[14:15], v[164:165], 1.0 op_sel_hi:[1,0]
	v_pk_fma_f32 v[164:165], v[146:147], v[198:199], v[134:135]
	v_pk_fma_f32 v[166:167], v[150:151], v[196:197], v[132:133]
	v_pk_fma_f32 v[160:161], v[152:153], v[194:195], v[142:143]
	v_pk_fma_f32 v[162:163], v[154:155], v[192:193], v[140:141]
	v_pk_mul_f32 v[12:13], v[178:179], v[12:13]
	v_pk_mul_f32 v[14:15], v[176:177], v[14:15]
	v_cndmask_b32_e32 v145, v156, v160, vcc
	v_cndmask_b32_e32 v159, v156, v161, vcc
	v_cndmask_b32_e32 v158, v156, v162, vcc
	v_cndmask_b32_e32 v160, v156, v163, vcc
	v_cndmask_b32_e32 v161, v156, v164, vcc
	v_cndmask_b32_e32 v162, v156, v165, vcc
	v_cndmask_b32_e32 v163, v156, v166, vcc
	v_pk_fma_f32 v[26:27], v[8:9], v[26:27], v[138:139]
	v_pk_fma_f32 v[24:25], v[10:11], v[24:25], v[136:137]
	v_cndmask_b32_e32 v164, v156, v167, vcc
	v_cvt_pk_bf16_f32 v158, v158, v160
	v_cvt_pk_bf16_f32 v159, v145, v159
	v_cvt_pk_bf16_f32 v160, v163, v164
	v_cvt_pk_bf16_f32 v161, v161, v162
	v_lshl_add_u64 v[162:163], v[190:191], 0, v[148:149]
	v_pk_fma_f32 v[34:35], v[12:13], v[34:35], v[130:131]
	v_pk_fma_f32 v[32:33], v[14:15], v[32:33], v[128:129]
	v_cndmask_b32_e32 v145, v156, v26, vcc
	v_cndmask_b32_e32 v27, v156, v27, vcc
	v_cndmask_b32_e32 v26, v156, v24, vcc
	global_store_dwordx4 v[162:163], v[158:161], off
	v_cndmask_b32_e32 v34, v156, v34, vcc
	v_cndmask_b32_e32 v35, v156, v35, vcc
	v_cndmask_b32_e32 v32, v156, v32, vcc
	v_cndmask_b32_e32 v33, v156, v33, vcc
	v_cndmask_b32_e32 v158, v156, v25, vcc
	v_cvt_pk_bf16_f32 v24, v32, v33
	v_cvt_pk_bf16_f32 v25, v34, v35
	v_cvt_pk_bf16_f32 v26, v26, v158
	v_cvt_pk_bf16_f32 v27, v145, v27
	global_store_dwordx4 v[162:163], v[24:27], off offset:256
	ds_read_b32 v24, v157 offset:4160
	s_waitcnt lgkmcnt(0)
	v_pk_mul_f32 v[16:17], v[16:17], v[24:25] op_sel_hi:[1,0]
	v_pk_mul_f32 v[18:19], v[18:19], v[24:25] op_sel_hi:[1,0]
	v_pk_mul_f32 v[20:21], v[20:21], v[24:25] op_sel_hi:[1,0]
	v_add_u32_e32 v26, 16, v144
	v_pk_fma_f32 v[18:19], v[152:153], v[18:19], v[142:143]
	v_pk_fma_f32 v[16:17], v[154:155], v[16:17], v[140:141]
	v_pk_fma_f32 v[20:21], v[150:151], v[20:21], v[132:133]
	v_ashrrev_i32_e32 v27, 31, v26
	v_cndmask_b32_e32 v18, v156, v18, vcc
	v_cndmask_b32_e32 v16, v156, v16, vcc
	v_cndmask_b32_e32 v17, v156, v17, vcc
	v_cndmask_b32_e32 v20, v156, v20, vcc
	v_cndmask_b32_e32 v21, v156, v21, vcc
	v_pk_mul_f32 v[22:23], v[22:23], v[24:25] op_sel_hi:[1,0]
	v_cndmask_b32_e32 v19, v156, v19, vcc
	v_cvt_pk_bf16_f32 v16, v16, v17
	v_cvt_pk_bf16_f32 v17, v18, v19
	v_cvt_pk_bf16_f32 v18, v20, v21
	v_lshlrev_b64 v[20:21], 12, v[26:27]
	v_pk_fma_f32 v[22:23], v[146:147], v[22:23], v[134:135]
	v_lshl_add_u64 v[20:21], s[0:1], 0, v[20:21]
	v_cndmask_b32_e32 v22, v156, v22, vcc
	v_cndmask_b32_e32 v23, v156, v23, vcc
	v_cvt_pk_bf16_f32 v19, v22, v23
	v_lshl_add_u64 v[20:21], v[20:21], 0, v[148:149]
	global_store_dwordx4 v[20:21], v[16:19], off
	v_pk_mul_f32 v[22:23], v[56:57], v[24:25] op_sel_hi:[1,0]
	s_nop 0
	v_pk_mul_f32 v[16:17], v[60:61], v[24:25] op_sel_hi:[1,0]
	v_pk_mul_f32 v[18:19], v[62:63], v[24:25] op_sel_hi:[1,0]
	v_pk_fma_f32 v[16:17], v[14:15], v[16:17], v[128:129]
	v_pk_fma_f32 v[18:19], v[12:13], v[18:19], v[130:131]
	v_pk_mul_f32 v[24:25], v[58:59], v[24:25] op_sel_hi:[1,0]
	v_pk_fma_f32 v[22:23], v[10:11], v[22:23], v[136:137]
	v_pk_fma_f32 v[24:25], v[8:9], v[24:25], v[138:139]
	v_cndmask_b32_e32 v18, v156, v18, vcc
	v_cndmask_b32_e32 v19, v156, v19, vcc
	v_cndmask_b32_e32 v16, v156, v16, vcc
	v_cndmask_b32_e32 v17, v156, v17, vcc
	v_cndmask_b32_e32 v24, v156, v24, vcc
	v_cndmask_b32_e32 v25, v156, v25, vcc
	v_cndmask_b32_e32 v22, v156, v22, vcc
	v_cndmask_b32_e32 v23, v156, v23, vcc
	v_cvt_pk_bf16_f32 v16, v16, v17
	v_cvt_pk_bf16_f32 v17, v18, v19
	v_cvt_pk_bf16_f32 v18, v22, v23
	v_cvt_pk_bf16_f32 v19, v24, v25
	global_store_dwordx4 v[20:21], v[16:19], off offset:256
	ds_read_b32 v20, v157 offset:4224
	v_add_u32_e32 v22, 32, v144
	v_ashrrev_i32_e32 v23, 31, v22
	v_lshlrev_b64 v[22:23], 12, v[22:23]
	v_lshl_add_u64 v[22:23], s[0:1], 0, v[22:23]
	s_waitcnt lgkmcnt(0)
; __device__ __forceinline__ unsigned cvt_pk_bf16(float lo, float hi) { unsigned r; asm volatile("v_cvt_pk_bf16_f32 %0, %1, %2" : "=v"(r) : "v"(lo), "v"(hi)); return r; }
;     __device__ __forceinline__ void fused(f32x4 (&acc)[2][2][4][2], const Unit& un, int wr, int wc, int fr, int fq, PG8_LAS unsigned char* lds, int wid, int lane) const {
;     ...
;         for (int ai = 0; ai < 2; ++ai)
; #pragma unroll
;             for (int m = 0; m < 4; ++m) { const int r = ai * HALF + wr * 64 + m * 16 + fr; const float rs = S[r]; const size_t off = (size_t)(un.pm * BM + r) * ldc + col0;
; #pragma unroll
;                 for (int bj = 0; bj < 2; ++bj) { f32x4 y0 = (acc[ai][bj][m][0] * rs) * cg[bj][0] + sh[bj][0], y1 = (acc[ai][bj][m][1] * rs) * cg[bj][1] + sh[bj][1];
;                     if (bad) { y0 = (f32x4){qnan, qnan, qnan, qnan}; y1 = y0; }
;                     if (MODE == 0) { u32x4 w; w.x = cvt_pk_bf16(y0[0], y0[1]); w.y = cvt_pk_bf16(y0[2], y0[3]); w.z = cvt_pk_bf16(y1[0], y1[1]); w.w = cvt_pk_bf16(y1[2], y1[3]); *(u32x4*)(u + off + bj * HALF) = w; }
	v_pk_mul_f32 v[16:17], v[48:49], v[20:21] op_sel_hi:[1,0]
	v_pk_mul_f32 v[18:19], v[50:51], v[20:21] op_sel_hi:[1,0]
	v_pk_fma_f32 v[16:17], v[154:155], v[16:17], v[140:141]
	v_pk_fma_f32 v[18:19], v[152:153], v[18:19], v[142:143]
	v_pk_mul_f32 v[24:25], v[52:53], v[20:21] op_sel_hi:[1,0]
	v_pk_mul_f32 v[26:27], v[54:55], v[20:21] op_sel_hi:[1,0]
	v_pk_fma_f32 v[24:25], v[150:151], v[24:25], v[132:133]
	v_pk_fma_f32 v[26:27], v[146:147], v[26:27], v[134:135]
	v_cndmask_b32_e32 v18, v156, v18, vcc
	v_cndmask_b32_e32 v19, v156, v19, vcc
	v_cndmask_b32_e32 v16, v156, v16, vcc
	v_cndmask_b32_e32 v17, v156, v17, vcc
	v_cndmask_b32_e32 v21, v156, v26, vcc
	v_cndmask_b32_e32 v26, v156, v27, vcc
	v_cndmask_b32_e32 v24, v156, v24, vcc
	v_cndmask_b32_e32 v25, v156, v25, vcc
	v_cvt_pk_bf16_f32 v16, v16, v17
	v_cvt_pk_bf16_f32 v17, v18, v19
	v_cvt_pk_bf16_f32 v18, v24, v25
	v_cvt_pk_bf16_f32 v19, v21, v26
	v_lshl_add_u64 v[22:23], v[22:23], 0, v[148:149]
	global_store_dwordx4 v[22:23], v[16:19], off
	v_pk_mul_f32 v[24:25], v[72:73], v[20:21] op_sel_hi:[1,0]
	s_nop 0
	v_pk_mul_f32 v[16:17], v[76:77], v[20:21] op_sel_hi:[1,0]
	v_pk_mul_f32 v[18:19], v[78:79], v[20:21] op_sel_hi:[1,0]
	v_pk_fma_f32 v[16:17], v[14:15], v[16:17], v[128:129]
	v_pk_fma_f32 v[18:19], v[12:13], v[18:19], v[130:131]
	v_pk_mul_f32 v[20:21], v[74:75], v[20:21] op_sel_hi:[1,0]
	v_pk_fma_f32 v[24:25], v[10:11], v[24:25], v[136:137]
	v_pk_fma_f32 v[20:21], v[8:9], v[20:21], v[138:139]
	v_cndmask_b32_e32 v18, v156, v18, vcc
	v_cndmask_b32_e32 v19, v156, v19, vcc
	v_cndmask_b32_e32 v16, v156, v16, vcc
	v_cndmask_b32_e32 v17, v156, v17, vcc
	v_cndmask_b32_e32 v20, v156, v20, vcc
	v_cndmask_b32_e32 v21, v156, v21, vcc
	v_cndmask_b32_e32 v24, v156, v24, vcc
	v_cndmask_b32_e32 v25, v156, v25, vcc
	v_cvt_pk_bf16_f32 v16, v16, v17
	v_cvt_pk_bf16_f32 v17, v18, v19
	v_cvt_pk_bf16_f32 v18, v24, v25
	v_cvt_pk_bf16_f32 v19, v20, v21
	global_store_dwordx4 v[22:23], v[16:19], off offset:256
	ds_read_b32 v20, v157 offset:4288
	v_add_u32_e32 v22, 48, v144
	v_ashrrev_i32_e32 v23, 31, v22
	v_lshlrev_b64 v[22:23], 12, v[22:23]
	v_lshl_add_u64 v[22:23], s[0:1], 0, v[22:23]
	s_waitcnt lgkmcnt(0)
	v_pk_mul_f32 v[16:17], v[64:65], v[20:21] op_sel_hi:[1,0]
	v_pk_mul_f32 v[18:19], v[66:67], v[20:21] op_sel_hi:[1,0]
	v_pk_fma_f32 v[16:17], v[154:155], v[16:17], v[140:141]
	v_pk_fma_f32 v[18:19], v[152:153], v[18:19], v[142:143]
	v_pk_mul_f32 v[24:25], v[68:69], v[20:21] op_sel_hi:[1,0]
	v_pk_mul_f32 v[26:27], v[70:71], v[20:21] op_sel_hi:[1,0]
	v_pk_fma_f32 v[24:25], v[150:151], v[24:25], v[132:133]
	v_pk_fma_f32 v[26:27], v[146:147], v[26:27], v[134:135]
	v_cndmask_b32_e32 v18, v156, v18, vcc
	v_cndmask_b32_e32 v19, v156, v19, vcc
	v_cndmask_b32_e32 v16, v156, v16, vcc
	v_cndmask_b32_e32 v17, v156, v17, vcc
	v_cndmask_b32_e32 v21, v156, v26, vcc
	v_cndmask_b32_e32 v26, v156, v27, vcc
	v_cndmask_b32_e32 v24, v156, v24, vcc
	v_cndmask_b32_e32 v25, v156, v25, vcc
	v_cvt_pk_bf16_f32 v16, v16, v17
	v_cvt_pk_bf16_f32 v17, v18, v19
	v_cvt_pk_bf16_f32 v18, v24, v25
	v_cvt_pk_bf16_f32 v19, v21, v26
	v_lshl_add_u64 v[22:23], v[22:23], 0, v[148:149]
	global_store_dwordx4 v[22:23], v[16:19], off
	v_pk_mul_f32 v[24:25], v[96:97], v[20:21] op_sel_hi:[1,0]
	s_nop 0
	v_pk_mul_f32 v[16:17], v[108:109], v[20:21] op_sel_hi:[1,0]
	v_pk_mul_f32 v[18:19], v[110:111], v[20:21] op_sel_hi:[1,0]
	v_pk_fma_f32 v[16:17], v[14:15], v[16:17], v[128:129]
	v_pk_fma_f32 v[18:19], v[12:13], v[18:19], v[130:131]
	v_pk_mul_f32 v[20:21], v[98:99], v[20:21] op_sel_hi:[1,0]
	v_pk_fma_f32 v[24:25], v[10:11], v[24:25], v[136:137]
	v_pk_fma_f32 v[20:21], v[8:9], v[20:21], v[138:139]
	v_cndmask_b32_e32 v18, v156, v18, vcc
	v_cndmask_b32_e32 v19, v156, v19, vcc
	v_cndmask_b32_e32 v16, v156, v16, vcc
	v_cndmask_b32_e32 v17, v156, v17, vcc
	v_cndmask_b32_e32 v20, v156, v20, vcc
	v_cndmask_b32_e32 v21, v156, v21, vcc
	v_cndmask_b32_e32 v24, v156, v24, vcc
	v_cndmask_b32_e32 v25, v156, v25, vcc
	v_cvt_pk_bf16_f32 v16, v16, v17
	v_cvt_pk_bf16_f32 v17, v18, v19
	v_cvt_pk_bf16_f32 v18, v24, v25
	v_cvt_pk_bf16_f32 v19, v20, v21
	global_store_dwordx4 v[22:23], v[16:19], off offset:256
	ds_read_b32 v20, v157 offset:4608
	v_add_u32_e32 v22, 0x80, v144
	v_ashrrev_i32_e32 v23, 31, v22
	v_lshlrev_b64 v[22:23], 12, v[22:23]
	v_lshl_add_u64 v[22:23], s[0:1], 0, v[22:23]
	s_waitcnt lgkmcnt(0)
	v_pk_mul_f32 v[16:17], v[100:101], v[20:21] op_sel_hi:[1,0]
	v_pk_mul_f32 v[18:19], v[102:103], v[20:21] op_sel_hi:[1,0]
	v_pk_fma_f32 v[16:17], v[154:155], v[16:17], v[140:141]
	v_pk_fma_f32 v[18:19], v[152:153], v[18:19], v[142:143]
	v_pk_mul_f32 v[24:25], v[104:105], v[20:21] op_sel_hi:[1,0]
	v_pk_mul_f32 v[26:27], v[106:107], v[20:21] op_sel_hi:[1,0]
	v_pk_fma_f32 v[24:25], v[150:151], v[24:25], v[132:133]
	v_pk_fma_f32 v[26:27], v[146:147], v[26:27], v[134:135]
	v_cndmask_b32_e32 v18, v156, v18, vcc
	v_cndmask_b32_e32 v19, v156, v19, vcc
	v_cndmask_b32_e32 v16, v156, v16, vcc
	v_cndmask_b32_e32 v17, v156, v17, vcc
	v_cndmask_b32_e32 v21, v156, v26, vcc
	v_cndmask_b32_e32 v26, v156, v27, vcc
	v_cndmask_b32_e32 v24, v156, v24, vcc
	v_cndmask_b32_e32 v25, v156, v25, vcc
	v_cvt_pk_bf16_f32 v16, v16, v17
	v_cvt_pk_bf16_f32 v17, v18, v19
	v_cvt_pk_bf16_f32 v18, v24, v25
	v_cvt_pk_bf16_f32 v19, v21, v26
	v_lshl_add_u64 v[22:23], v[22:23], 0, v[148:149]
	global_store_dwordx4 v[22:23], v[16:19], off
	v_pk_mul_f32 v[24:25], v[112:113], v[20:21] op_sel_hi:[1,0]
	s_nop 0
	v_pk_mul_f32 v[16:17], v[124:125], v[20:21] op_sel_hi:[1,0]
	v_pk_mul_f32 v[18:19], v[126:127], v[20:21] op_sel_hi:[1,0]
	v_pk_fma_f32 v[16:17], v[14:15], v[16:17], v[128:129]
	v_pk_fma_f32 v[18:19], v[12:13], v[18:19], v[130:131]
	v_pk_mul_f32 v[20:21], v[114:115], v[20:21] op_sel_hi:[1,0]
	v_pk_fma_f32 v[24:25], v[10:11], v[24:25], v[136:137]
	v_pk_fma_f32 v[20:21], v[8:9], v[20:21], v[138:139]
	v_cndmask_b32_e32 v18, v156, v18, vcc
	v_cndmask_b32_e32 v19, v156, v19, vcc
	v_cndmask_b32_e32 v16, v156, v16, vcc
	v_cndmask_b32_e32 v17, v156, v17, vcc
	v_cndmask_b32_e32 v20, v156, v20, vcc
	v_cndmask_b32_e32 v21, v156, v21, vcc
	v_cndmask_b32_e32 v24, v156, v24, vcc
	v_cndmask_b32_e32 v25, v156, v25, vcc
	v_cvt_pk_bf16_f32 v16, v16, v17
	v_cvt_pk_bf16_f32 v17, v18, v19
	v_cvt_pk_bf16_f32 v18, v24, v25
	v_cvt_pk_bf16_f32 v19, v20, v21
	global_store_dwordx4 v[22:23], v[16:19], off offset:256
	ds_read_b32 v20, v157 offset:4672
	v_add_u32_e32 v22, 0x90, v144
	v_ashrrev_i32_e32 v23, 31, v22
	v_lshlrev_b64 v[22:23], 12, v[22:23]
	v_lshl_add_u64 v[22:23], s[0:1], 0, v[22:23]
	s_waitcnt lgkmcnt(0)
; __device__ __forceinline__ unsigned cvt_pk_bf16(float lo, float hi) { unsigned r; asm volatile("v_cvt_pk_bf16_f32 %0, %1, %2" : "=v"(r) : "v"(lo), "v"(hi)); return r; }
;     __device__ __forceinline__ void fused(f32x4 (&acc)[2][2][4][2], const Unit& un, int wr, int wc, int fr, int fq, PG8_LAS unsigned char* lds, int wid, int lane) const {
;     ...
;         for (int ai = 0; ai < 2; ++ai)
; #pragma unroll
;             for (int m = 0; m < 4; ++m) { const int r = ai * HALF + wr * 64 + m * 16 + fr; const float rs = S[r]; const size_t off = (size_t)(un.pm * BM + r) * ldc + col0;
; #pragma unroll
;                 for (int bj = 0; bj < 2; ++bj) { f32x4 y0 = (acc[ai][bj][m][0] * rs) * cg[bj][0] + sh[bj][0], y1 = (acc[ai][bj][m][1] * rs) * cg[bj][1] + sh[bj][1];
;                     if (bad) { y0 = (f32x4){qnan, qnan, qnan, qnan}; y1 = y0; }
;                     if (MODE == 0) { u32x4 w; w.x = cvt_pk_bf16(y0[0], y0[1]); w.y = cvt_pk_bf16(y0[2], y0[3]); w.z = cvt_pk_bf16(y1[0], y1[1]); w.w = cvt_pk_bf16(y1[2], y1[3]); *(u32x4*)(u + off + bj * HALF) = w; }
	v_pk_mul_f32 v[16:17], v[116:117], v[20:21] op_sel_hi:[1,0]
	v_pk_mul_f32 v[18:19], v[118:119], v[20:21] op_sel_hi:[1,0]
	v_pk_fma_f32 v[16:17], v[154:155], v[16:17], v[140:141]
	v_pk_fma_f32 v[18:19], v[152:153], v[18:19], v[142:143]
	v_pk_mul_f32 v[24:25], v[120:121], v[20:21] op_sel_hi:[1,0]
	v_pk_mul_f32 v[26:27], v[122:123], v[20:21] op_sel_hi:[1,0]
	v_pk_fma_f32 v[24:25], v[150:151], v[24:25], v[132:133]
	v_pk_fma_f32 v[26:27], v[146:147], v[26:27], v[134:135]
	v_cndmask_b32_e32 v18, v156, v18, vcc
	v_cndmask_b32_e32 v19, v156, v19, vcc
	v_cndmask_b32_e32 v16, v156, v16, vcc
	v_cndmask_b32_e32 v17, v156, v17, vcc
	v_cndmask_b32_e32 v21, v156, v26, vcc
	v_cndmask_b32_e32 v26, v156, v27, vcc
	v_cndmask_b32_e32 v24, v156, v24, vcc
	v_cndmask_b32_e32 v25, v156, v25, vcc
	v_cvt_pk_bf16_f32 v16, v16, v17
	v_cvt_pk_bf16_f32 v17, v18, v19
	v_cvt_pk_bf16_f32 v18, v24, v25
	v_cvt_pk_bf16_f32 v19, v21, v26
	v_lshl_add_u64 v[22:23], v[22:23], 0, v[148:149]
	global_store_dwordx4 v[22:23], v[16:19], off
	v_pk_mul_f32 v[24:25], v[88:89], v[20:21] op_sel_hi:[1,0]
	s_nop 0
	v_pk_mul_f32 v[16:17], v[92:93], v[20:21] op_sel_hi:[1,0]
	v_pk_mul_f32 v[18:19], v[94:95], v[20:21] op_sel_hi:[1,0]
	v_pk_fma_f32 v[16:17], v[14:15], v[16:17], v[128:129]
	v_pk_fma_f32 v[18:19], v[12:13], v[18:19], v[130:131]
	v_pk_mul_f32 v[20:21], v[90:91], v[20:21] op_sel_hi:[1,0]
	v_pk_fma_f32 v[24:25], v[10:11], v[24:25], v[136:137]
	v_pk_fma_f32 v[20:21], v[8:9], v[20:21], v[138:139]
	v_cndmask_b32_e32 v18, v156, v18, vcc
	v_cndmask_b32_e32 v19, v156, v19, vcc
	v_cndmask_b32_e32 v16, v156, v16, vcc
	v_cndmask_b32_e32 v17, v156, v17, vcc
	v_cndmask_b32_e32 v20, v156, v20, vcc
	v_cndmask_b32_e32 v21, v156, v21, vcc
	v_cndmask_b32_e32 v24, v156, v24, vcc
	v_cndmask_b32_e32 v25, v156, v25, vcc
	v_cvt_pk_bf16_f32 v16, v16, v17
	v_cvt_pk_bf16_f32 v17, v18, v19
	v_cvt_pk_bf16_f32 v18, v24, v25
	v_cvt_pk_bf16_f32 v19, v20, v21
	global_store_dwordx4 v[22:23], v[16:19], off offset:256
	ds_read_b32 v20, v157 offset:4736
	v_add_u32_e32 v22, 0xa0, v144
	v_ashrrev_i32_e32 v23, 31, v22
	v_lshlrev_b64 v[22:23], 12, v[22:23]
	v_lshl_add_u64 v[22:23], s[0:1], 0, v[22:23]
	s_waitcnt lgkmcnt(0)
	v_pk_mul_f32 v[16:17], v[84:85], v[20:21] op_sel_hi:[1,0]
	v_pk_mul_f32 v[18:19], v[86:87], v[20:21] op_sel_hi:[1,0]
	v_pk_fma_f32 v[16:17], v[154:155], v[16:17], v[140:141]
	v_pk_fma_f32 v[18:19], v[152:153], v[18:19], v[142:143]
	v_pk_mul_f32 v[24:25], v[80:81], v[20:21] op_sel_hi:[1,0]
	v_pk_mul_f32 v[26:27], v[82:83], v[20:21] op_sel_hi:[1,0]
	v_pk_fma_f32 v[24:25], v[150:151], v[24:25], v[132:133]
	v_pk_fma_f32 v[26:27], v[146:147], v[26:27], v[134:135]
	v_cndmask_b32_e32 v18, v156, v18, vcc
	v_cndmask_b32_e32 v19, v156, v19, vcc
	v_cndmask_b32_e32 v16, v156, v16, vcc
	v_cndmask_b32_e32 v17, v156, v17, vcc
	v_cndmask_b32_e32 v21, v156, v26, vcc
	v_cndmask_b32_e32 v26, v156, v27, vcc
	v_cndmask_b32_e32 v24, v156, v24, vcc
	v_cndmask_b32_e32 v25, v156, v25, vcc
	v_cvt_pk_bf16_f32 v16, v16, v17
	v_cvt_pk_bf16_f32 v17, v18, v19
	v_cvt_pk_bf16_f32 v18, v24, v25
	v_cvt_pk_bf16_f32 v19, v21, v26
	v_lshl_add_u64 v[22:23], v[22:23], 0, v[148:149]
	global_store_dwordx4 v[22:23], v[16:19], off
	v_pk_mul_f32 v[24:25], v[40:41], v[20:21] op_sel_hi:[1,0]
	s_nop 0
	v_pk_mul_f32 v[16:17], v[44:45], v[20:21] op_sel_hi:[1,0]
	v_pk_mul_f32 v[18:19], v[46:47], v[20:21] op_sel_hi:[1,0]
	v_pk_fma_f32 v[16:17], v[14:15], v[16:17], v[128:129]
	v_pk_fma_f32 v[18:19], v[12:13], v[18:19], v[130:131]
	v_pk_mul_f32 v[20:21], v[42:43], v[20:21] op_sel_hi:[1,0]
	v_pk_fma_f32 v[24:25], v[10:11], v[24:25], v[136:137]
	v_pk_fma_f32 v[20:21], v[8:9], v[20:21], v[138:139]
	v_cndmask_b32_e32 v18, v156, v18, vcc
	v_cndmask_b32_e32 v19, v156, v19, vcc
	v_cndmask_b32_e32 v16, v156, v16, vcc
	v_cndmask_b32_e32 v17, v156, v17, vcc
	v_cndmask_b32_e32 v20, v156, v20, vcc
	v_cndmask_b32_e32 v21, v156, v21, vcc
	v_cndmask_b32_e32 v24, v156, v24, vcc
	v_cndmask_b32_e32 v25, v156, v25, vcc
	v_cvt_pk_bf16_f32 v16, v16, v17
	v_cvt_pk_bf16_f32 v17, v18, v19
	v_cvt_pk_bf16_f32 v18, v24, v25
	v_cvt_pk_bf16_f32 v19, v20, v21
	global_store_dwordx4 v[22:23], v[16:19], off offset:256
	ds_read_b32 v20, v157 offset:4800
	v_add_u32_e32 v22, 0xb0, v144
	v_ashrrev_i32_e32 v23, 31, v22
	v_lshlrev_b64 v[22:23], 12, v[22:23]
	v_lshl_add_u64 v[22:23], s[0:1], 0, v[22:23]
	s_waitcnt lgkmcnt(0)
	v_pk_mul_f32 v[26:27], v[30:31], v[20:21] op_sel_hi:[1,0]
	v_pk_mul_f32 v[16:17], v[36:37], v[20:21] op_sel_hi:[1,0]
	v_pk_fma_f32 v[26:27], v[146:147], v[26:27], v[134:135]
	v_pk_mul_f32 v[18:19], v[38:39], v[20:21] op_sel_hi:[1,0]
	v_pk_mul_f32 v[24:25], v[28:29], v[20:21] op_sel_hi:[1,0]
	v_cndmask_b32_e32 v21, v156, v26, vcc
	v_pk_mul_f32 v[0:1], v[0:1], v[20:21] op_sel_hi:[1,0]
	v_pk_mul_f32 v[2:3], v[2:3], v[20:21] op_sel_hi:[1,0]
	v_pk_fma_f32 v[18:19], v[152:153], v[18:19], v[142:143]
	v_pk_fma_f32 v[16:17], v[154:155], v[16:17], v[140:141]
	v_pk_mul_f32 v[4:5], v[4:5], v[20:21] op_sel_hi:[1,0]
	v_pk_mul_f32 v[6:7], v[6:7], v[20:21] op_sel_hi:[1,0]
	v_pk_fma_f32 v[2:3], v[8:9], v[2:3], v[138:139]
	v_pk_fma_f32 v[0:1], v[10:11], v[0:1], v[136:137]
	v_pk_fma_f32 v[24:25], v[150:151], v[24:25], v[132:133]
	v_cndmask_b32_e32 v18, v156, v18, vcc
	v_cndmask_b32_e32 v19, v156, v19, vcc
	v_cndmask_b32_e32 v16, v156, v16, vcc
	v_cndmask_b32_e32 v17, v156, v17, vcc
	v_lshl_add_u64 v[22:23], v[22:23], 0, v[148:149]
	v_pk_fma_f32 v[6:7], v[12:13], v[6:7], v[130:131]
	v_pk_fma_f32 v[4:5], v[14:15], v[4:5], v[128:129]
	v_cndmask_b32_e32 v8, v156, v2, vcc
	v_cndmask_b32_e32 v3, v156, v3, vcc
	v_cndmask_b32_e32 v2, v156, v0, vcc
	v_cndmask_b32_e32 v26, v156, v27, vcc
	v_cndmask_b32_e32 v24, v156, v24, vcc
	v_cndmask_b32_e32 v25, v156, v25, vcc
	v_cvt_pk_bf16_f32 v16, v16, v17
	v_cvt_pk_bf16_f32 v17, v18, v19
	v_cvt_pk_bf16_f32 v18, v24, v25
	v_cvt_pk_bf16_f32 v19, v21, v26
	global_store_dwordx4 v[22:23], v[16:19], off
	v_cndmask_b32_e32 v6, v156, v6, vcc
	v_cndmask_b32_e32 v7, v156, v7, vcc
	v_cndmask_b32_e32 v4, v156, v4, vcc
	v_cndmask_b32_e32 v5, v156, v5, vcc
	v_cndmask_b32_e32 v9, v156, v1, vcc
	v_cvt_pk_bf16_f32 v0, v4, v5
	v_cvt_pk_bf16_f32 v1, v6, v7
	v_cvt_pk_bf16_f32 v2, v2, v9
	v_cvt_pk_bf16_f32 v3, v8, v3
	global_store_dwordx4 v[22:23], v[0:3], off offset:256

;     __device__ __forceinline__ void operator()(const f32x4 (&acc)[2][2][4][2], const Unit& u, int wr, int wc, int fr, int fq) const {
;     ...
; #pragma unroll
;         for (int ai = 0; ai < 2; ++ai)
; #pragma unroll
;             for (int m = 0; m < 4; ++m) { bf16_t* rowp = O + (size_t)(row0 + ai * HALF + m * 16) * ldc + col0;
;                 if (ACT == 1) {
;                     const int ob = fr * 64 + 16 * fq, sw = ob ^ (((ob >> 9) & 1) << 5);
;                     rowp = O + ((size_t)(u.pm * (ldc / 64) + u.pn * 4 + (wc >> 1)) * 2 + ai) * 8192 + (((wr * 4 + m) * 2 + (wc & 1)) * 1024 + sw) / 2; }
;                 float rc[2][2], rs[2][2];
;                 if (ACT == 2) { const float pos = (float)((row0 + ai * HALF + m * 16) & 2047);
; #pragma unroll
;                     for (int n = 0; n < 2; ++n)
; #pragma unroll
;                         for (int e = 0; e < 2; ++e) { float r = pos * rinv[n][e]; r -= floorf(r); rs[n][e] = do_rope ? __builtin_amdgcn_sinf(r) : 0.f; rc[n][e] = do_rope ? __builtin_amdgcn_cosf(r) : 1.f; } }
; #pragma unroll
;                 for (int bj = 0; bj < 2; ++bj) { f32x4 v0 = acc[ai][bj][m][0], v1 = acc[ai][bj][m][1];
;                     if (ACT == 3) { const float pos = (float)((row0 + ai * HALF + m * 16) & 2047); float c3[4], s3[4];
; #pragma unroll
;                         for (int p = 0; p < 4; ++p) { float r = pos * rinv3[bj][p]; r -= floorf(r); s3[p] = rope3[bj] ? __builtin_amdgcn_sinf(r) : 0.f; c3[p] = rope3[bj] ? __builtin_amdgcn_cosf(r) : 1.f; }
;                         const f32x4 a = v0, b = v1;
;                         v0[0] = a[0] * c3[0] - a[1] * s3[0]; v0[1] = a[1] * c3[0] + a[0] * s3[0]; v0[2] = a[2] * c3[1] - a[3] * s3[1]; v0[3] = a[3] * c3[1] + a[2] * s3[1];
;                         v1[0] = b[0] * c3[2] - b[1] * s3[2]; v1[1] = b[1] * c3[2] + b[0] * s3[2]; v1[2] = b[2] * c3[3] - b[3] * s3[3]; v1[3] = b[3] * c3[3] + b[2] * s3[3]; }
;                     if (ACT == 2) { const f32x4 a = v0, b = v1;
;                         v0[0] = a[0] * rc[0][0] - a[1] * rs[0][0]; v0[1] = a[1] * rc[0][0] + a[0] * rs[0][0]; v0[2] = a[2] * rc[0][1] - a[3] * rs[0][1]; v0[3] = a[3] * rc[0][1] + a[2] * rs[0][1];
;                         v1[0] = b[0] * rc[1][0] - b[1] * rs[1][0]; v1[1] = b[1] * rc[1][0] + b[0] * rs[1][0]; v1[2] = b[2] * rc[1][1] - b[3] * rs[1][1]; v1[3] = b[3] * rc[1][1] + b[2] * rs[1][1]; }
.LBB0_3723:
	v_mov_b32_e32 v148, 0
	s_lshl_b32 s17, s25, 2
	v_mbcnt_lo_u32_b32 v148, -1, v148
	v_mbcnt_hi_u32_b32 v148, -1, v148
	v_or_b32_e32 v148, s33, v148
	s_or_b32 s17, s17, s58
	v_and_b32_e32 v149, 15, v148
	v_and_b32_e32 v150, 48, v148
	v_lshlrev_b32_e32 v148, 2, v148
	s_lshl_b32 s19, s24, 7
	v_lshl_or_b32 v149, v149, 6, v150
	v_and_b32_e32 v148, 32, v148
	s_add_i32 s24, s17, s19
	s_ashr_i32 s25, s24, 31
	v_bitop3_b32 v148, v149, s59, v148 bitop3:0xde
	s_lshl_b64 s[24:25], s[24:25], 15
	v_ashrrev_i32_e32 v148, 1, v148
	s_add_u32 s24, s54, s24
	v_ashrrev_i32_e32 v149, 31, v148
	s_addc_u32 s25, s55, s25
	v_lshlrev_b64 v[150:151], 1, v[148:149]
	v_max_i32_e32 v120, 0, v120
	v_max_i32_e32 v121, 0, v121
	v_max_i32_e32 v122, 0, v122
	v_max_i32_e32 v123, 0, v123
	v_max_i32_e32 v112, 0, v112
	v_max_i32_e32 v116, 0, v116
	v_max_i32_e32 v113, 0, v113
	v_max_i32_e32 v114, 0, v114
	v_lshl_add_u64 v[152:153], s[24:25], 0, v[150:151]
	v_max_i32_e32 v124, 0, v124
	v_mul_f32_e32 v120, v120, v120
	v_max_i32_e32 v125, 0, v125
	v_mul_f32_e32 v121, v121, v121
	v_max_i32_e32 v126, 0, v126
	v_mul_f32_e32 v122, v122, v122
	v_max_i32_e32 v127, 0, v127
	v_mul_f32_e32 v123, v123, v123
	v_mul_f32_e32 v112, v112, v112
	v_mul_f32_e32 v116, v116, v116
	v_max_i32_e32 v117, 0, v117
	v_mul_f32_e32 v113, v113, v113
	v_mul_f32_e32 v114, v114, v114
	v_max_i32_e32 v115, 0, v115
	v_mul_f32_e32 v124, v124, v124
	v_mul_f32_e32 v125, v125, v125
	v_mul_f32_e32 v126, v126, v126
	v_mul_f32_e32 v127, v127, v127
	v_cvt_pk_bf16_f32 v120, v120, v121
	v_cvt_pk_bf16_f32 v121, v122, v123
	v_cvt_pk_bf16_f32 v122, v124, v125
	v_cvt_pk_bf16_f32 v123, v126, v127
	global_store_dwordx4 v[152:153], v[120:123], off
	v_mul_f32_e32 v117, v117, v117
	v_mul_f32_e32 v115, v115, v115
	v_cvt_pk_bf16_f32 v112, v112, v113
	v_cvt_pk_bf16_f32 v113, v114, v115
	v_cvt_pk_bf16_f32 v114, v116, v117
	v_add_co_u32_e32 v116, vcc, s52, v152
	v_max_i32_e32 v104, 0, v104
	v_max_i32_e32 v105, 0, v105
	v_max_i32_e32 v106, 0, v106
	v_max_i32_e32 v107, 0, v107
	v_max_i32_e32 v96, 0, v96
	v_max_i32_e32 v118, 0, v118
	v_max_i32_e32 v119, 0, v119
	v_addc_co_u32_e32 v117, vcc, 0, v153, vcc
	v_max_i32_e32 v108, 0, v108
	v_mul_f32_e32 v104, v104, v104
	v_max_i32_e32 v109, 0, v109
	v_mul_f32_e32 v105, v105, v105
	v_max_i32_e32 v110, 0, v110
	v_mul_f32_e32 v106, v106, v106
	v_max_i32_e32 v111, 0, v111
	v_mul_f32_e32 v107, v107, v107
	v_mul_f32_e32 v96, v96, v96
	v_max_i32_e32 v97, 0, v97
	v_max_i32_e32 v98, 0, v98
	v_max_i32_e32 v99, 0, v99
	v_mul_f32_e32 v118, v118, v118
	v_mul_f32_e32 v119, v119, v119
	v_cvt_pk_bf16_f32 v115, v118, v119
	global_store_dwordx4 v[116:117], v[112:115], off
	v_mul_f32_e32 v108, v108, v108
	v_mul_f32_e32 v109, v109, v109
	v_mul_f32_e32 v110, v110, v110
	v_mul_f32_e32 v111, v111, v111
	v_cvt_pk_bf16_f32 v104, v104, v105
	v_cvt_pk_bf16_f32 v105, v106, v107
	v_cvt_pk_bf16_f32 v106, v108, v109
	v_cvt_pk_bf16_f32 v107, v110, v111
	global_store_dwordx4 v[152:153], v[104:107], off offset:2048
	v_max_i32_e32 v100, 0, v100
	v_max_i32_e32 v101, 0, v101
	v_mul_f32_e32 v97, v97, v97
	v_max_i32_e32 v102, 0, v102
	v_mul_f32_e32 v98, v98, v98
	v_max_i32_e32 v103, 0, v103
	v_mul_f32_e32 v99, v99, v99
	v_cvt_pk_bf16_f32 v96, v96, v97
	v_mul_f32_e32 v100, v100, v100
	v_mul_f32_e32 v101, v101, v101
	v_mul_f32_e32 v102, v102, v102
	v_mul_f32_e32 v103, v103, v103
	v_cvt_pk_bf16_f32 v97, v98, v99
	v_cvt_pk_bf16_f32 v98, v100, v101
	v_cvt_pk_bf16_f32 v99, v102, v103
	global_store_dwordx4 v[116:117], v[96:99], off offset:2048
	v_max_i32_e32 v88, 0, v88
	v_max_i32_e32 v89, 0, v89
	v_or_b32_e32 v96, 0x800, v148
	v_ashrrev_i32_e32 v97, 31, v96
	v_lshlrev_b64 v[96:97], 1, v[96:97]
	v_max_i32_e32 v90, 0, v90
	v_max_i32_e32 v91, 0, v91
	v_max_i32_e32 v80, 0, v80
	v_max_i32_e32 v84, 0, v84
	v_max_i32_e32 v81, 0, v81
	v_max_i32_e32 v82, 0, v82
	v_lshl_add_u64 v[98:99], s[24:25], 0, v[96:97]
	v_max_i32_e32 v92, 0, v92
	v_mul_f32_e32 v88, v88, v88
	v_max_i32_e32 v93, 0, v93
	v_mul_f32_e32 v89, v89, v89
	v_max_i32_e32 v94, 0, v94
	v_mul_f32_e32 v90, v90, v90
	v_max_i32_e32 v95, 0, v95
	v_mul_f32_e32 v91, v91, v91
	v_mul_f32_e32 v80, v80, v80
	v_mul_f32_e32 v84, v84, v84
	v_max_i32_e32 v85, 0, v85
	v_mul_f32_e32 v81, v81, v81
	v_mul_f32_e32 v82, v82, v82
	v_max_i32_e32 v83, 0, v83
	v_mul_f32_e32 v92, v92, v92
	v_mul_f32_e32 v93, v93, v93
	v_mul_f32_e32 v94, v94, v94
	v_mul_f32_e32 v95, v95, v95
	v_cvt_pk_bf16_f32 v88, v88, v89
	v_cvt_pk_bf16_f32 v89, v90, v91
	v_cvt_pk_bf16_f32 v90, v92, v93
	v_cvt_pk_bf16_f32 v91, v94, v95
	global_store_dwordx4 v[98:99], v[88:91], off
	v_mul_f32_e32 v85, v85, v85
	v_mul_f32_e32 v83, v83, v83
	v_cvt_pk_bf16_f32 v80, v80, v81
	v_cvt_pk_bf16_f32 v81, v82, v83
	v_cvt_pk_bf16_f32 v82, v84, v85
	v_add_co_u32_e32 v84, vcc, s52, v98
	v_max_i32_e32 v86, 0, v86
	v_max_i32_e32 v87, 0, v87
	v_addc_co_u32_e32 v85, vcc, 0, v99, vcc
	v_mul_f32_e32 v86, v86, v86
	v_mul_f32_e32 v87, v87, v87
	v_cvt_pk_bf16_f32 v83, v86, v87
	global_store_dwordx4 v[84:85], v[80:83], off
	v_max_i32_e32 v64, 0, v64
	v_max_i32_e32 v65, 0, v65
	v_or_b32_e32 v80, 0xc00, v148
	v_ashrrev_i32_e32 v81, 31, v80
	v_lshlrev_b64 v[80:81], 1, v[80:81]
	v_max_i32_e32 v66, 0, v66
	v_max_i32_e32 v67, 0, v67
	v_max_i32_e32 v48, 0, v48
	v_max_i32_e32 v52, 0, v52
	v_max_i32_e32 v49, 0, v49
	v_max_i32_e32 v50, 0, v50
	v_lshl_add_u64 v[82:83], s[24:25], 0, v[80:81]
	v_max_i32_e32 v68, 0, v68
	v_mul_f32_e32 v64, v64, v64
	v_max_i32_e32 v69, 0, v69
	v_mul_f32_e32 v65, v65, v65
	v_max_i32_e32 v70, 0, v70
	v_mul_f32_e32 v66, v66, v66
	v_max_i32_e32 v71, 0, v71
	v_mul_f32_e32 v67, v67, v67
	v_mul_f32_e32 v48, v48, v48
	v_mul_f32_e32 v52, v52, v52
;     __device__ __forceinline__ void operator()(const f32x4 (&acc)[2][2][4][2], const Unit& u, int wr, int wc, int fr, int fq) const {
;     ...
; #pragma unroll
;         for (int ai = 0; ai < 2; ++ai)
; #pragma unroll
;             for (int m = 0; m < 4; ++m) { bf16_t* rowp = O + (size_t)(row0 + ai * HALF + m * 16) * ldc + col0;
;                 if (ACT == 1) {
;                     const int ob = fr * 64 + 16 * fq, sw = ob ^ (((ob >> 9) & 1) << 5);
;                     rowp = O + ((size_t)(u.pm * (ldc / 64) + u.pn * 4 + (wc >> 1)) * 2 + ai) * 8192 + (((wr * 4 + m) * 2 + (wc & 1)) * 1024 + sw) / 2; }
;                 float rc[2][2], rs[2][2];
;                 if (ACT == 2) { const float pos = (float)((row0 + ai * HALF + m * 16) & 2047);
; #pragma unroll
;                     for (int n = 0; n < 2; ++n)
; #pragma unroll
;                         for (int e = 0; e < 2; ++e) { float r = pos * rinv[n][e]; r -= floorf(r); rs[n][e] = do_rope ? __builtin_amdgcn_sinf(r) : 0.f; rc[n][e] = do_rope ? __builtin_amdgcn_cosf(r) : 1.f; } }
; #pragma unroll
;                 for (int bj = 0; bj < 2; ++bj) { f32x4 v0 = acc[ai][bj][m][0], v1 = acc[ai][bj][m][1];
;                     if (ACT == 3) { const float pos = (float)((row0 + ai * HALF + m * 16) & 2047); float c3[4], s3[4];
; #pragma unroll
;                         for (int p = 0; p < 4; ++p) { float r = pos * rinv3[bj][p]; r -= floorf(r); s3[p] = rope3[bj] ? __builtin_amdgcn_sinf(r) : 0.f; c3[p] = rope3[bj] ? __builtin_amdgcn_cosf(r) : 1.f; }
;                         const f32x4 a = v0, b = v1;
;                         v0[0] = a[0] * c3[0] - a[1] * s3[0]; v0[1] = a[1] * c3[0] + a[0] * s3[0]; v0[2] = a[2] * c3[1] - a[3] * s3[1]; v0[3] = a[3] * c3[1] + a[2] * s3[1];
;                         v1[0] = b[0] * c3[2] - b[1] * s3[2]; v1[1] = b[1] * c3[2] + b[0] * s3[2]; v1[2] = b[2] * c3[3] - b[3] * s3[3]; v1[3] = b[3] * c3[3] + b[2] * s3[3]; }
;                     if (ACT == 2) { const f32x4 a = v0, b = v1;
;                         v0[0] = a[0] * rc[0][0] - a[1] * rs[0][0]; v0[1] = a[1] * rc[0][0] + a[0] * rs[0][0]; v0[2] = a[2] * rc[0][1] - a[3] * rs[0][1]; v0[3] = a[3] * rc[0][1] + a[2] * rs[0][1];
;                         v1[0] = b[0] * rc[1][0] - b[1] * rs[1][0]; v1[1] = b[1] * rc[1][0] + b[0] * rs[1][0]; v1[2] = b[2] * rc[1][1] - b[3] * rs[1][1]; v1[3] = b[3] * rc[1][1] + b[2] * rs[1][1]; }
	v_max_i32_e32 v53, 0, v53
	v_mul_f32_e32 v49, v49, v49
	v_mul_f32_e32 v50, v50, v50
	v_max_i32_e32 v51, 0, v51
	v_mul_f32_e32 v68, v68, v68
	v_mul_f32_e32 v69, v69, v69
	v_mul_f32_e32 v70, v70, v70
	v_mul_f32_e32 v71, v71, v71
	v_cvt_pk_bf16_f32 v64, v64, v65
	v_cvt_pk_bf16_f32 v65, v66, v67
	v_cvt_pk_bf16_f32 v66, v68, v69
	v_cvt_pk_bf16_f32 v67, v70, v71
	global_store_dwordx4 v[82:83], v[64:67], off
	v_mul_f32_e32 v53, v53, v53
	v_mul_f32_e32 v51, v51, v51
	v_cvt_pk_bf16_f32 v48, v48, v49
	v_cvt_pk_bf16_f32 v49, v50, v51
	v_cvt_pk_bf16_f32 v50, v52, v53
	v_add_co_u32_e32 v52, vcc, s52, v82
	v_max_i32_e32 v54, 0, v54
	v_max_i32_e32 v55, 0, v55
	v_addc_co_u32_e32 v53, vcc, 0, v83, vcc
	v_mul_f32_e32 v54, v54, v54
	v_mul_f32_e32 v55, v55, v55
	v_cvt_pk_bf16_f32 v51, v54, v55
	global_store_dwordx4 v[52:53], v[48:51], off
	s_add_u32 s24, s24, 0x4000
	s_addc_u32 s25, s25, 0
	v_max_i32_e32 v49, 0, v76
	v_max_i32_e32 v48, 0, v72
	v_mul_f32_e32 v50, v49, v49
	v_max_i32_e32 v49, 0, v73
	v_mul_f32_e32 v48, v48, v48
	v_max_i32_e32 v51, 0, v77
	v_mul_f32_e32 v49, v49, v49
	v_max_i32_e32 v54, 0, v74
	v_max_i32_e32 v64, 0, v75
	v_lshl_add_u64 v[52:53], s[24:25], 0, v[150:151]
	v_mul_f32_e32 v51, v51, v51
	v_max_i32_e32 v55, 0, v78
	v_mul_f32_e32 v54, v54, v54
	v_max_i32_e32 v65, 0, v79
	v_mul_f32_e32 v64, v64, v64
	v_cvt_pk_bf16_f32 v48, v48, v49
	v_cvt_pk_bf16_f32 v49, v54, v64
	v_mul_f32_e32 v55, v55, v55
	v_mul_f32_e32 v65, v65, v65
	v_cvt_pk_bf16_f32 v50, v50, v51
	v_cvt_pk_bf16_f32 v51, v55, v65
	global_store_dwordx4 v[52:53], v[48:51], off
	v_or_b32_e32 v112, 0x400, v148
	v_max_i32_e32 v54, 0, v58
	v_max_i32_e32 v49, 0, v60
	v_max_i32_e32 v48, 0, v56
	v_mul_f32_e32 v50, v49, v49
	v_max_i32_e32 v49, 0, v57
	v_mul_f32_e32 v48, v48, v48
	v_max_i32_e32 v51, 0, v61
	v_mul_f32_e32 v49, v49, v49
	v_max_i32_e32 v56, 0, v59
	v_add_co_u32_e32 v52, vcc, s52, v52
	v_ashrrev_i32_e32 v113, 31, v112
	v_mul_f32_e32 v51, v51, v51
	v_max_i32_e32 v55, 0, v62
	v_mul_f32_e32 v54, v54, v54
	v_max_i32_e32 v57, 0, v63
	v_mul_f32_e32 v56, v56, v56
	v_cvt_pk_bf16_f32 v48, v48, v49
	v_cvt_pk_bf16_f32 v49, v54, v56
	v_addc_co_u32_e32 v53, vcc, 0, v53, vcc
	v_max_i32_e32 v40, 0, v40
	v_max_i32_e32 v41, 0, v41
	v_max_i32_e32 v42, 0, v42
	v_max_i32_e32 v43, 0, v43
	v_max_i32_e32 v32, 0, v32
	v_max_i32_e32 v36, 0, v36
	v_max_i32_e32 v33, 0, v33
	v_max_i32_e32 v34, 0, v34
	v_mul_f32_e32 v55, v55, v55
	v_mul_f32_e32 v57, v57, v57
	v_cvt_pk_bf16_f32 v50, v50, v51
	v_cvt_pk_bf16_f32 v51, v55, v57
	global_store_dwordx4 v[52:53], v[48:51], off
	v_max_i32_e32 v44, 0, v44
	v_mul_f32_e32 v40, v40, v40
	v_lshl_add_u64 v[48:49], v[112:113], 1, s[24:25]
	v_max_i32_e32 v45, 0, v45
	v_mul_f32_e32 v41, v41, v41
	v_max_i32_e32 v46, 0, v46
	v_mul_f32_e32 v42, v42, v42
	v_max_i32_e32 v47, 0, v47
	v_mul_f32_e32 v43, v43, v43
	v_mul_f32_e32 v32, v32, v32
	v_mul_f32_e32 v36, v36, v36
	v_max_i32_e32 v37, 0, v37
	v_mul_f32_e32 v33, v33, v33
	v_mul_f32_e32 v34, v34, v34
	v_max_i32_e32 v35, 0, v35
	v_mul_f32_e32 v44, v44, v44
	v_mul_f32_e32 v45, v45, v45
	v_mul_f32_e32 v46, v46, v46
	v_mul_f32_e32 v47, v47, v47
	v_cvt_pk_bf16_f32 v40, v40, v41
	v_cvt_pk_bf16_f32 v41, v42, v43
	v_cvt_pk_bf16_f32 v42, v44, v45
	v_cvt_pk_bf16_f32 v43, v46, v47
	global_store_dwordx4 v[48:49], v[40:43], off
	v_mul_f32_e32 v37, v37, v37
	v_mul_f32_e32 v35, v35, v35
	v_cvt_pk_bf16_f32 v32, v32, v33
	v_cvt_pk_bf16_f32 v33, v34, v35
	v_cvt_pk_bf16_f32 v34, v36, v37
	v_add_co_u32_e32 v36, vcc, s52, v48
	v_max_i32_e32 v38, 0, v38
	v_max_i32_e32 v39, 0, v39
	v_addc_co_u32_e32 v37, vcc, 0, v49, vcc
	v_max_i32_e32 v24, 0, v24
	v_max_i32_e32 v25, 0, v25
	v_max_i32_e32 v26, 0, v26
	v_max_i32_e32 v27, 0, v27
	v_max_i32_e32 v16, 0, v16
	v_max_i32_e32 v20, 0, v20
	v_max_i32_e32 v17, 0, v17
	v_max_i32_e32 v18, 0, v18
	v_mul_f32_e32 v38, v38, v38
	v_mul_f32_e32 v39, v39, v39
	v_cvt_pk_bf16_f32 v35, v38, v39
	global_store_dwordx4 v[36:37], v[32:35], off
	v_max_i32_e32 v28, 0, v28
	v_mul_f32_e32 v24, v24, v24
	v_lshl_add_u64 v[32:33], s[24:25], 0, v[96:97]
	v_max_i32_e32 v29, 0, v29
	v_mul_f32_e32 v25, v25, v25
	v_max_i32_e32 v30, 0, v30
	v_mul_f32_e32 v26, v26, v26
	v_max_i32_e32 v31, 0, v31
	v_mul_f32_e32 v27, v27, v27
	v_mul_f32_e32 v16, v16, v16
	v_mul_f32_e32 v20, v20, v20
	v_max_i32_e32 v21, 0, v21
	v_mul_f32_e32 v17, v17, v17
	v_mul_f32_e32 v18, v18, v18
	v_max_i32_e32 v19, 0, v19
	v_mul_f32_e32 v28, v28, v28
	v_mul_f32_e32 v29, v29, v29
	v_mul_f32_e32 v30, v30, v30
	v_mul_f32_e32 v31, v31, v31
	v_cvt_pk_bf16_f32 v24, v24, v25
	v_cvt_pk_bf16_f32 v25, v26, v27
	v_cvt_pk_bf16_f32 v26, v28, v29
	v_cvt_pk_bf16_f32 v27, v30, v31
	global_store_dwordx4 v[32:33], v[24:27], off
	v_mul_f32_e32 v21, v21, v21
	v_mul_f32_e32 v19, v19, v19
	v_cvt_pk_bf16_f32 v16, v16, v17
	v_cvt_pk_bf16_f32 v17, v18, v19
	v_cvt_pk_bf16_f32 v18, v20, v21
	v_add_co_u32_e32 v20, vcc, s52, v32
	v_max_i32_e32 v22, 0, v22
	v_max_i32_e32 v23, 0, v23
	v_addc_co_u32_e32 v21, vcc, 0, v33, vcc
	v_max_i32_e32 v8, 0, v8
	v_max_i32_e32 v9, 0, v9
	v_max_i32_e32 v10, 0, v10
	v_max_i32_e32 v11, 0, v11
	v_max_i32_e32 v0, 0, v0
	v_max_i32_e32 v4, 0, v4
	v_max_i32_e32 v1, 0, v1
	v_max_i32_e32 v2, 0, v2
	v_mul_f32_e32 v22, v22, v22
	v_mul_f32_e32 v23, v23, v23
	v_cvt_pk_bf16_f32 v19, v22, v23
	global_store_dwordx4 v[20:21], v[16:19], off
	v_max_i32_e32 v12, 0, v12
	v_mul_f32_e32 v8, v8, v8
	v_lshl_add_u64 v[16:17], s[24:25], 0, v[80:81]
	v_max_i32_e32 v13, 0, v13
	v_mul_f32_e32 v9, v9, v9
	v_max_i32_e32 v14, 0, v14
	v_mul_f32_e32 v10, v10, v10
	v_max_i32_e32 v15, 0, v15
	v_mul_f32_e32 v11, v11, v11
	v_mul_f32_e32 v0, v0, v0
	v_mul_f32_e32 v4, v4, v4
	v_max_i32_e32 v5, 0, v5
	v_mul_f32_e32 v1, v1, v1
	v_mul_f32_e32 v2, v2, v2
	v_max_i32_e32 v3, 0, v3
	v_mul_f32_e32 v12, v12, v12
	v_mul_f32_e32 v13, v13, v13
	v_mul_f32_e32 v14, v14, v14
	v_mul_f32_e32 v15, v15, v15
	v_cvt_pk_bf16_f32 v8, v8, v9
	v_cvt_pk_bf16_f32 v9, v10, v11
	v_cvt_pk_bf16_f32 v10, v12, v13
	v_cvt_pk_bf16_f32 v11, v14, v15
	global_store_dwordx4 v[16:17], v[8:11], off
	v_mul_f32_e32 v5, v5, v5
	v_mul_f32_e32 v3, v3, v3
	v_cvt_pk_bf16_f32 v0, v0, v1
	v_cvt_pk_bf16_f32 v1, v2, v3
	v_cvt_pk_bf16_f32 v2, v4, v5
	v_add_co_u32_e32 v4, vcc, 0x10000, v16
	v_max_i32_e32 v6, 0, v6
	s_nop 0
	v_addc_co_u32_e32 v5, vcc, 0, v17, vcc
	v_max_i32_e32 v7, 0, v7
	s_andn2_b64 vcc, exec, s[0:1]
	s_mov_b64 s[0:1], -1
	v_mul_f32_e32 v6, v6, v6
	v_mul_f32_e32 v7, v7, v7
	v_cvt_pk_bf16_f32 v3, v6, v7
	global_store_dwordx4 v[4:5], v[0:3], off
	s_cbranch_vccnz .LBB0_3712
	s_andn2_b64 vcc, exec, s[4:5]
	s_cbranch_vccnz .LBB0_3711
	s_barrier
	s_branch .LBB0_3711

; __device__ __forceinline__ unsigned cvt_pk_bf16(float lo, float hi) { unsigned r; asm volatile("v_cvt_pk_bf16_f32 %0, %1, %2" : "=v"(r) : "v"(lo), "v"(hi)); return r; }
;     __device__ __forceinline__ void fused(f32x4 (&acc)[2][2][4][2], const Unit& un, int wr, int wc, int fr, int fq, PG8_LAS unsigned char* lds, int wid, int lane) const {
;     ...
;         const int row0 = un.pm * BM + wr * 64 + fr, col0 = un.pn * BM + wc * 32 + 8 * fq;
;         const size_t boff = (size_t)(un.pm >> 3) * bstride + col0;
;         { f32x4 gv[2][2];
; #pragma unroll
;           for (int bj = 0; bj < 2; ++bj)
; #pragma unroll
;               for (int n = 0; n < 2; ++n) gv[bj][n] = *(const f32x4*)(gate + boff + bj * HALF + n * 4);
; #pragma unroll
;           for (int ai = 0; ai < 2; ++ai)
; #pragma unroll
;               for (int m = 0; m < 4; ++m) { const size_t off = (size_t)(row0 + ai * HALF + m * 16) * ldc + col0;
; #pragma unroll
;                   for (int bj = 0; bj < 2; ++bj) {
; #pragma unroll
;                       for (int n = 0; n < 2; ++n) { f32x4 bs;
;                           if (BASE_F32) bs = *(const f32x4*)((const float*)base + off + bj * HALF + n * 4);
;                           else { const u32x2v hw = *(const u32x2v*)((const bf16_t*)base + off + bj * HALF + n * 4);
;                                  bs = (f32x4){__uint_as_float(hw.x << 16), __uint_as_float(hw.x & 0xffff0000u), __uint_as_float(hw.y << 16), __uint_as_float(hw.y & 0xffff0000u)}; }
;                           acc[ai][bj][m][n] = bs + gv[bj][n] * acc[ai][bj][m][n]; }
;                       if (out_h) { const f32x4 a0 = acc[ai][bj][m][0], a1 = acc[ai][bj][m][1]; u32x4 w; w.x = cvt_pk_bf16(a0[0], a0[1]); w.y = cvt_pk_bf16(a0[2], a0[3]); w.z = cvt_pk_bf16(a1[0], a1[1]); w.w = cvt_pk_bf16(a1[2], a1[3]);
;                           *(u32x4*)(out_h + off + bj * HALF) = w; } }
;                   asm volatile("" : "+v"(acc[ai][0][m][0]), "+v"(acc[ai][0][m][1]), "+v"(acc[ai][1][m][0]), "+v"(acc[ai][1][m][1]));
;                   asm volatile("" ::: "memory"); } }
.LBB0_3796:
	v_mov_b32_e32 v128, 0
	v_readlane_b32 s12, v254, 43
	s_barrier
	s_lshl_b32 s4, s24, 5
	v_readlane_b32 s14, v254, 45
	v_mbcnt_lo_u32_b32 v128, -1, v128
	v_readlane_b32 s15, v254, 46
	s_add_u32 s0, s14, 0x1a600000
	v_mbcnt_hi_u32_b32 v128, -1, v128
	s_addc_u32 s1, s15, 0
	v_or_b32_e32 v152, s33, v128
	s_lshl_b32 s20, s8, 8
	s_lshl_b32 s12, s2, 8
	s_add_i32 s5, s20, s9
	v_and_b32_e32 v153, 15, v152
	s_or_b32 s4, s12, s4
	v_lshrrev_b32_e32 v128, 1, v152
	v_and_or_b32 v144, v128, 24, s4
	v_or_b32_e32 v148, s5, v153
	s_ashr_i32 s4, s8, 3
	v_ashrrev_i32_e32 v149, 31, v148
	s_mul_hi_i32 s5, s4, 0xc000
	s_mul_i32 s4, s4, 0xc000
	v_ashrrev_i32_e32 v145, 31, v144
	v_lshlrev_b64 v[128:129], 12, v[148:149]
	s_add_u32 s4, s14, s4
	v_lshl_add_u64 v[128:129], s[0:1], 0, v[128:129]
	v_lshlrev_b64 v[150:151], 1, v[144:145]
	s_addc_u32 s5, s15, s5
	v_lshl_add_u64 v[146:147], v[128:129], 0, v[150:151]
	v_lshl_add_u64 v[128:129], v[144:145], 2, s[4:5]
	s_mov_b32 s12, 0x19a000
	s_mov_b64 s[4:5], 0x19a000
	v_add_co_u32_e32 v130, vcc, s12, v128
	v_addc_co_u32_e32 v131, vcc, 0, v129, vcc
	v_lshl_add_u64 v[128:129], v[128:129], 0, s[4:5]
	global_load_dwordx4 v[136:139], v[130:131], off
	global_load_dwordx4 v[140:143], v[128:129], off offset:16
	global_load_dwordx4 v[132:135], v[128:129], off offset:512
	s_nop 0
	global_load_dwordx4 v[128:131], v[128:129], off offset:528
	v_or_b32_e32 v162, 16, v148
	v_ashrrev_i32_e32 v163, 31, v162
	v_lshlrev_b64 v[162:163], 12, v[162:163]
	v_lshl_add_u64 v[162:163], s[0:1], 0, v[162:163]
	v_lshl_add_u64 v[162:163], v[162:163], 0, v[150:151]
	v_readlane_b32 s13, v254, 44
	s_mov_b64 s[98:99], 0x10000
	s_mov_b64 s[100:101], 0x80000
	v_lshl_add_u64 v[204:205], v[146:147], 0, 0
	v_lshl_add_u64 v[206:207], v[204:205], 0, s[98:99]
	v_lshl_add_u64 v[208:209], v[206:207], 0, s[98:99]
	v_lshl_add_u64 v[210:211], v[208:209], 0, s[98:99]
	global_load_dwordx4 v[172:175], v[204:205], off
	global_load_dwordx4 v[176:179], v[204:205], off offset:256
	global_load_dwordx4 v[180:183], v[206:207], off
	global_load_dwordx4 v[184:187], v[206:207], off offset:256
	global_load_dwordx4 v[188:191], v[208:209], off
	global_load_dwordx4 v[192:195], v[208:209], off offset:256
	global_load_dwordx4 v[196:199], v[210:211], off
	global_load_dwordx4 v[200:203], v[210:211], off offset:256
	s_waitcnt vmcnt(0) lgkmcnt(0)
	v_lshlrev_b32_e32 v164, 16, v172
	v_and_b32_e32 v165, 0xffff0000, v172
	v_lshlrev_b32_e32 v154, 16, v173
	v_and_b32_e32 v155, 0xffff0000, v173
	v_lshlrev_b32_e32 v166, 16, v174
	v_and_b32_e32 v167, 0xffff0000, v174
	v_lshlrev_b32_e32 v156, 16, v175
	v_and_b32_e32 v157, 0xffff0000, v175
	v_lshlrev_b32_e32 v168, 16, v176
	v_and_b32_e32 v169, 0xffff0000, v176
	v_lshlrev_b32_e32 v158, 16, v177
	v_and_b32_e32 v159, 0xffff0000, v177
	v_lshlrev_b32_e32 v170, 16, v178
	v_and_b32_e32 v171, 0xffff0000, v178
	v_lshlrev_b32_e32 v160, 16, v179
	v_and_b32_e32 v161, 0xffff0000, v179
	v_pk_fma_f32 v[34:35], v[34:35], v[138:139], v[154:155]
	v_pk_fma_f32 v[32:33], v[32:33], v[136:137], v[164:165]
	v_pk_fma_f32 v[38:39], v[38:39], v[142:143], v[156:157]
	v_pk_fma_f32 v[36:37], v[36:37], v[140:141], v[166:167]
	v_pk_fma_f32 v[42:43], v[42:43], v[134:135], v[158:159]
	v_pk_fma_f32 v[40:41], v[40:41], v[132:133], v[168:169]
	v_pk_fma_f32 v[46:47], v[46:47], v[130:131], v[160:161]
	v_pk_fma_f32 v[44:45], v[44:45], v[128:129], v[170:171]
	s_nop 0
	v_or_b32_e32 v162, 32, v148
	v_ashrrev_i32_e32 v163, 31, v162
	v_lshlrev_b64 v[162:163], 12, v[162:163]
	v_lshl_add_u64 v[162:163], s[0:1], 0, v[162:163]
	v_lshl_add_u64 v[162:163], v[162:163], 0, v[150:151]
	v_or_b32_e32 v148, 48, v148
	v_ashrrev_i32_e32 v149, 31, v148
	v_lshlrev_b64 v[148:149], 12, v[148:149]
	v_lshl_add_u64 v[148:149], s[0:1], 0, v[148:149]
	s_mov_b32 s0, 0x80000
	s_nop 1
	v_lshlrev_b32_e32 v164, 16, v180
	v_and_b32_e32 v165, 0xffff0000, v180
	v_lshlrev_b32_e32 v154, 16, v181
	v_and_b32_e32 v155, 0xffff0000, v181
	v_lshlrev_b32_e32 v166, 16, v182
	v_and_b32_e32 v167, 0xffff0000, v182
	v_lshlrev_b32_e32 v156, 16, v183
	v_and_b32_e32 v157, 0xffff0000, v183
	v_lshlrev_b32_e32 v168, 16, v184
	v_and_b32_e32 v169, 0xffff0000, v184
	v_lshlrev_b32_e32 v158, 16, v185
	v_and_b32_e32 v159, 0xffff0000, v185
	v_lshlrev_b32_e32 v170, 16, v186
	v_and_b32_e32 v171, 0xffff0000, v186
	v_lshlrev_b32_e32 v160, 16, v187
	v_and_b32_e32 v161, 0xffff0000, v187
	v_pk_fma_f32 v[78:79], v[78:79], v[138:139], v[154:155]
	v_pk_fma_f32 v[76:77], v[76:77], v[136:137], v[164:165]
	v_pk_fma_f32 v[82:83], v[82:83], v[142:143], v[156:157]
	v_pk_fma_f32 v[80:81], v[80:81], v[140:141], v[166:167]
	v_pk_fma_f32 v[70:71], v[70:71], v[134:135], v[158:159]
	v_pk_fma_f32 v[68:69], v[68:69], v[132:133], v[168:169]
	v_pk_fma_f32 v[66:67], v[66:67], v[130:131], v[160:161]
	v_pk_fma_f32 v[64:65], v[64:65], v[128:129], v[170:171]
	s_nop 0
	v_lshl_add_u64 v[162:163], v[148:149], 0, v[150:151]
	s_nop 1
	v_lshlrev_b32_e32 v148, 16, v188
	v_and_b32_e32 v149, 0xffff0000, v188
	v_lshlrev_b32_e32 v150, 16, v189
	v_and_b32_e32 v151, 0xffff0000, v189
	v_lshlrev_b32_e32 v154, 16, v190
	v_and_b32_e32 v155, 0xffff0000, v190
	v_lshlrev_b32_e32 v156, 16, v191
	v_and_b32_e32 v157, 0xffff0000, v191
	v_lshlrev_b32_e32 v164, 16, v192
	v_and_b32_e32 v165, 0xffff0000, v192
	v_lshlrev_b32_e32 v158, 16, v193
	v_and_b32_e32 v159, 0xffff0000, v193
	v_lshlrev_b32_e32 v166, 16, v194
	v_and_b32_e32 v167, 0xffff0000, v194
	v_lshlrev_b32_e32 v160, 16, v195
	v_and_b32_e32 v161, 0xffff0000, v195
	v_pk_fma_f32 v[94:95], v[94:95], v[138:139], v[150:151]
	v_pk_fma_f32 v[92:93], v[92:93], v[136:137], v[148:149]
	v_pk_fma_f32 v[86:87], v[86:87], v[142:143], v[156:157]
; __device__ __forceinline__ unsigned cvt_pk_bf16(float lo, float hi) { unsigned r; asm volatile("v_cvt_pk_bf16_f32 %0, %1, %2" : "=v"(r) : "v"(lo), "v"(hi)); return r; }
;     __device__ __forceinline__ void fused(f32x4 (&acc)[2][2][4][2], const Unit& un, int wr, int wc, int fr, int fq, PG8_LAS unsigned char* lds, int wid, int lane) const {
;     ...
;           for (int ai = 0; ai < 2; ++ai)
; #pragma unroll
;               for (int m = 0; m < 4; ++m) { const size_t off = (size_t)(row0 + ai * HALF + m * 16) * ldc + col0;
; #pragma unroll
;                   for (int bj = 0; bj < 2; ++bj) {
; #pragma unroll
;                       for (int n = 0; n < 2; ++n) { f32x4 bs;
;                           if (BASE_F32) bs = *(const f32x4*)((const float*)base + off + bj * HALF + n * 4);
;                           else { const u32x2v hw = *(const u32x2v*)((const bf16_t*)base + off + bj * HALF + n * 4);
;                                  bs = (f32x4){__uint_as_float(hw.x << 16), __uint_as_float(hw.x & 0xffff0000u), __uint_as_float(hw.y << 16), __uint_as_float(hw.y & 0xffff0000u)}; }
;                           acc[ai][bj][m][n] = bs + gv[bj][n] * acc[ai][bj][m][n]; }
;                       if (out_h) { const f32x4 a0 = acc[ai][bj][m][0], a1 = acc[ai][bj][m][1]; u32x4 w; w.x = cvt_pk_bf16(a0[0], a0[1]); w.y = cvt_pk_bf16(a0[2], a0[3]); w.z = cvt_pk_bf16(a1[0], a1[1]); w.w = cvt_pk_bf16(a1[2], a1[3]);
;                           *(u32x4*)(out_h + off + bj * HALF) = w; } }
;                   asm volatile("" : "+v"(acc[ai][0][m][0]), "+v"(acc[ai][0][m][1]), "+v"(acc[ai][1][m][0]), "+v"(acc[ai][1][m][1]));
;                   asm volatile("" ::: "memory"); } }
	v_pk_fma_f32 v[84:85], v[84:85], v[140:141], v[154:155]
	v_pk_fma_f32 v[62:63], v[62:63], v[134:135], v[158:159]
	v_pk_fma_f32 v[60:61], v[60:61], v[132:133], v[164:165]
	v_pk_fma_f32 v[58:59], v[58:59], v[130:131], v[160:161]
	v_pk_fma_f32 v[56:57], v[56:57], v[128:129], v[166:167]
	v_add_co_u32_e32 v158, vcc, s0, v146
	s_mov_b64 s[0:1], 0x80000
	v_addc_co_u32_e32 v159, vcc, 0, v147, vcc
	s_nop 1
	v_lshlrev_b32_e32 v160, 16, v196
	v_and_b32_e32 v161, 0xffff0000, v196
	v_lshlrev_b32_e32 v148, 16, v197
	v_and_b32_e32 v149, 0xffff0000, v197
	v_lshlrev_b32_e32 v162, 16, v198
	v_and_b32_e32 v163, 0xffff0000, v198
	v_lshlrev_b32_e32 v150, 16, v199
	v_and_b32_e32 v151, 0xffff0000, v199
	v_lshlrev_b32_e32 v164, 16, v200
	v_and_b32_e32 v165, 0xffff0000, v200
	v_lshlrev_b32_e32 v154, 16, v201
	v_and_b32_e32 v155, 0xffff0000, v201
	v_lshlrev_b32_e32 v166, 16, v202
	v_and_b32_e32 v167, 0xffff0000, v202
	v_lshlrev_b32_e32 v156, 16, v203
	v_and_b32_e32 v157, 0xffff0000, v203
	v_pk_fma_f32 v[110:111], v[110:111], v[138:139], v[148:149]
	v_pk_fma_f32 v[108:109], v[108:109], v[136:137], v[160:161]
	v_pk_fma_f32 v[106:107], v[106:107], v[142:143], v[150:151]
	v_pk_fma_f32 v[104:105], v[104:105], v[140:141], v[162:163]
	v_pk_fma_f32 v[102:103], v[102:103], v[134:135], v[154:155]
	v_pk_fma_f32 v[100:101], v[100:101], v[132:133], v[164:165]
	v_pk_fma_f32 v[98:99], v[98:99], v[130:131], v[156:157]
	v_pk_fma_f32 v[96:97], v[96:97], v[128:129], v[166:167]
	v_lshl_add_u64 v[154:155], v[146:147], 0, s[0:1]
	s_mov_b32 s0, 0x90000
	v_add_co_u32_e32 v158, vcc, s0, v146
	s_mov_b64 s[0:1], 0x90000
	s_nop 0
	v_addc_co_u32_e32 v159, vcc, 0, v147, vcc
	v_lshl_add_u64 v[204:205], v[204:205], 0, s[100:101]
	v_lshl_add_u64 v[206:207], v[206:207], 0, s[100:101]
	v_lshl_add_u64 v[208:209], v[208:209], 0, s[100:101]
	v_lshl_add_u64 v[210:211], v[210:211], 0, s[100:101]
	global_load_dwordx4 v[172:175], v[204:205], off
	global_load_dwordx4 v[176:179], v[204:205], off offset:256
	global_load_dwordx4 v[180:183], v[206:207], off
	global_load_dwordx4 v[184:187], v[206:207], off offset:256
	global_load_dwordx4 v[188:191], v[208:209], off
	global_load_dwordx4 v[192:195], v[208:209], off offset:256
	global_load_dwordx4 v[196:199], v[210:211], off
	global_load_dwordx4 v[200:203], v[210:211], off offset:256
	s_waitcnt vmcnt(0) lgkmcnt(0)
; __device__ __forceinline__ unsigned cvt_pk_bf16(float lo, float hi) { unsigned r; asm volatile("v_cvt_pk_bf16_f32 %0, %1, %2" : "=v"(r) : "v"(lo), "v"(hi)); return r; }
;     __device__ __forceinline__ void fused(f32x4 (&acc)[2][2][4][2], const Unit& un, int wr, int wc, int fr, int fq, PG8_LAS unsigned char* lds, int wid, int lane) const {
;     ...
;           for (int ai = 0; ai < 2; ++ai)
; #pragma unroll
;               for (int m = 0; m < 4; ++m) { const size_t off = (size_t)(row0 + ai * HALF + m * 16) * ldc + col0;
; #pragma unroll
;                   for (int bj = 0; bj < 2; ++bj) {
; #pragma unroll
;                       for (int n = 0; n < 2; ++n) { f32x4 bs;
;                           if (BASE_F32) bs = *(const f32x4*)((const float*)base + off + bj * HALF + n * 4);
;                           else { const u32x2v hw = *(const u32x2v*)((const bf16_t*)base + off + bj * HALF + n * 4);
;                                  bs = (f32x4){__uint_as_float(hw.x << 16), __uint_as_float(hw.x & 0xffff0000u), __uint_as_float(hw.y << 16), __uint_as_float(hw.y & 0xffff0000u)}; }
;                           acc[ai][bj][m][n] = bs + gv[bj][n] * acc[ai][bj][m][n]; }
;                       if (out_h) { const f32x4 a0 = acc[ai][bj][m][0], a1 = acc[ai][bj][m][1]; u32x4 w; w.x = cvt_pk_bf16(a0[0], a0[1]); w.y = cvt_pk_bf16(a0[2], a0[3]); w.z = cvt_pk_bf16(a1[0], a1[1]); w.w = cvt_pk_bf16(a1[2], a1[3]);
;                           *(u32x4*)(out_h + off + bj * HALF) = w; } }
;                   asm volatile("" : "+v"(acc[ai][0][m][0]), "+v"(acc[ai][0][m][1]), "+v"(acc[ai][1][m][0]), "+v"(acc[ai][1][m][1]));
;                   asm volatile("" ::: "memory"); } }
; #pragma unroll
;         for (int ai = 0; ai < 2; ++ai)
; #pragma unroll
;             for (int m = 0; m < 4; ++m) { float s = 0.f;
; #pragma unroll
;                 for (int bj = 0; bj < 2; ++bj)
; #pragma unroll
;                     for (int n = 0; n < 2; ++n) { const f32x4 x = acc[ai][bj][m][n]; s += (x[0] * x[0] + x[1] * x[1]) + (x[2] * x[2] + x[3] * x[3]); }
;                 s += __shfl_xor(s, 16); s += __shfl_xor(s, 32);
;                 if (fq == 0) P[(ai * HALF + wr * 64 + m * 16 + fr) * 4 + wc] = s; }
	v_lshlrev_b32_e32 v160, 16, v172
	v_and_b32_e32 v161, 0xffff0000, v172
	v_lshlrev_b32_e32 v148, 16, v173
	v_and_b32_e32 v149, 0xffff0000, v173
	v_lshlrev_b32_e32 v162, 16, v174
	v_and_b32_e32 v163, 0xffff0000, v174
	v_lshlrev_b32_e32 v150, 16, v175
	v_and_b32_e32 v151, 0xffff0000, v175
	v_lshlrev_b32_e32 v164, 16, v176
	v_and_b32_e32 v165, 0xffff0000, v176
	v_lshlrev_b32_e32 v154, 16, v177
	v_and_b32_e32 v155, 0xffff0000, v177
	v_lshlrev_b32_e32 v166, 16, v178
	v_and_b32_e32 v167, 0xffff0000, v178
	v_lshlrev_b32_e32 v156, 16, v179
	v_and_b32_e32 v157, 0xffff0000, v179
	v_pk_fma_f32 v[126:127], v[126:127], v[138:139], v[148:149]
	v_pk_fma_f32 v[124:125], v[124:125], v[136:137], v[160:161]
	v_pk_fma_f32 v[122:123], v[122:123], v[142:143], v[150:151]
	v_pk_fma_f32 v[120:121], v[120:121], v[140:141], v[162:163]
	v_pk_fma_f32 v[118:119], v[118:119], v[134:135], v[154:155]
	v_pk_fma_f32 v[116:117], v[116:117], v[132:133], v[164:165]
	v_pk_fma_f32 v[114:115], v[114:115], v[130:131], v[156:157]
	v_pk_fma_f32 v[112:113], v[112:113], v[128:129], v[166:167]
	v_lshl_add_u64 v[154:155], v[146:147], 0, s[0:1]
	s_mov_b32 s0, 0xa0000
	v_add_co_u32_e32 v158, vcc, s0, v146
	s_mov_b64 s[0:1], 0xa0000
	s_nop 0
	v_addc_co_u32_e32 v159, vcc, 0, v147, vcc
	s_nop 1
	v_lshlrev_b32_e32 v160, 16, v180
	v_and_b32_e32 v161, 0xffff0000, v180
	v_lshlrev_b32_e32 v148, 16, v181
	v_and_b32_e32 v149, 0xffff0000, v181
	v_lshlrev_b32_e32 v162, 16, v182
	v_and_b32_e32 v163, 0xffff0000, v182
	v_lshlrev_b32_e32 v150, 16, v183
	v_and_b32_e32 v151, 0xffff0000, v183
	v_lshlrev_b32_e32 v164, 16, v184
	v_and_b32_e32 v165, 0xffff0000, v184
	v_lshlrev_b32_e32 v154, 16, v185
	v_and_b32_e32 v155, 0xffff0000, v185
	v_lshlrev_b32_e32 v166, 16, v186
	v_and_b32_e32 v167, 0xffff0000, v186
	v_lshlrev_b32_e32 v156, 16, v187
	v_and_b32_e32 v157, 0xffff0000, v187
	v_pk_fma_f32 v[90:91], v[90:91], v[138:139], v[148:149]
	v_pk_fma_f32 v[88:89], v[88:89], v[136:137], v[160:161]
	v_pk_fma_f32 v[74:75], v[74:75], v[142:143], v[150:151]
	v_pk_fma_f32 v[72:73], v[72:73], v[140:141], v[162:163]
	v_pk_fma_f32 v[54:55], v[54:55], v[134:135], v[154:155]
	v_pk_fma_f32 v[52:53], v[52:53], v[132:133], v[164:165]
	v_pk_fma_f32 v[50:51], v[50:51], v[130:131], v[156:157]
	v_pk_fma_f32 v[48:49], v[48:49], v[128:129], v[166:167]
	v_lshl_add_u64 v[154:155], v[146:147], 0, s[0:1]
	s_mov_b32 s0, 0xb0000
	v_add_co_u32_e32 v158, vcc, s0, v146
	s_mov_b64 s[0:1], 0xb0000
	s_nop 0
	v_addc_co_u32_e32 v159, vcc, 0, v147, vcc
	v_lshl_add_u64 v[146:147], v[146:147], 0, s[0:1]
	s_lshl_b32 s0, s24, 2
	s_add_i32 s0, s0, 0
	s_nop 1
	v_lshlrev_b32_e32 v160, 16, v188
	v_and_b32_e32 v161, 0xffff0000, v188
	v_lshlrev_b32_e32 v148, 16, v189
	v_and_b32_e32 v149, 0xffff0000, v189
	v_lshlrev_b32_e32 v162, 16, v190
	v_and_b32_e32 v163, 0xffff0000, v190
	v_lshlrev_b32_e32 v150, 16, v191
	v_and_b32_e32 v151, 0xffff0000, v191
	v_lshlrev_b32_e32 v164, 16, v192
	v_and_b32_e32 v165, 0xffff0000, v192
	v_lshlrev_b32_e32 v154, 16, v193
	v_and_b32_e32 v155, 0xffff0000, v193
	v_lshlrev_b32_e32 v166, 16, v194
	v_and_b32_e32 v167, 0xffff0000, v194
	v_lshlrev_b32_e32 v156, 16, v195
	v_and_b32_e32 v157, 0xffff0000, v195
	v_pk_fma_f32 v[30:31], v[30:31], v[138:139], v[148:149]
	v_pk_fma_f32 v[28:29], v[28:29], v[136:137], v[160:161]
	v_pk_fma_f32 v[26:27], v[26:27], v[142:143], v[150:151]
	v_pk_fma_f32 v[24:25], v[24:25], v[140:141], v[162:163]
	v_pk_fma_f32 v[22:23], v[22:23], v[134:135], v[154:155]
	v_pk_fma_f32 v[20:21], v[20:21], v[132:133], v[164:165]
	v_pk_fma_f32 v[18:19], v[18:19], v[130:131], v[156:157]
	v_pk_fma_f32 v[16:17], v[16:17], v[128:129], v[166:167]
	v_mul_f32_e32 v151, v35, v35
	v_mul_f32_e32 v162, v37, v37
	v_mbcnt_lo_u32_b32 v146, -1, 0
	v_mbcnt_hi_u32_b32 v146, -1, v146
	v_and_b32_e32 v148, 64, v146
	v_xor_b32_e32 v147, 16, v146
	v_add_u32_e32 v150, 64, v148
	v_cmp_lt_i32_e32 vcc, v147, v150
	v_mul_f32_e32 v163, v39, v39
	v_mul_f32_e32 v164, v41, v41
	v_cndmask_b32_e32 v147, v146, v147, vcc
	v_lshlrev_b32_e32 v148, 2, v147
	v_mul_f32_e32 v147, v33, v33
	v_mul_f32_e32 v165, v43, v43
	v_fmac_f32_e32 v147, v32, v32
	v_fmac_f32_e32 v151, v34, v34
	v_fmac_f32_e32 v162, v36, v36
	v_fmac_f32_e32 v163, v38, v38
	v_mul_f32_e32 v166, v45, v45
	v_mul_f32_e32 v167, v47, v47
	v_fmac_f32_e32 v164, v40, v40
	v_fmac_f32_e32 v165, v42, v42
	v_add_f32_e32 v147, v147, v151
	v_add_f32_e32 v151, v162, v163
	v_fmac_f32_e32 v166, v44, v44
	v_fmac_f32_e32 v167, v46, v46
	v_add_f32_e32 v162, v164, v165
	v_add_f32_e32 v147, v147, v151
	v_add_f32_e32 v163, v166, v167
	v_add_f32_e32 v147, v162, v147
	v_add_f32_e32 v151, v163, v147
	ds_bpermute_b32 v162, v148, v151
	v_xor_b32_e32 v149, 32, v146
	v_cmp_lt_i32_e32 vcc, v149, v150
	v_and_b32_e32 v147, 63, v152
	s_waitcnt lgkmcnt(0)
	v_add_f32_e32 v150, v151, v162
	v_cndmask_b32_e32 v146, v146, v149, vcc
	v_lshlrev_b32_e32 v149, 2, v146
	ds_bpermute_b32 v151, v149, v150
	v_or_b32_e32 v146, s9, v153
	v_cmp_gt_u32_e32 vcc, 16, v147
	s_waitcnt vmcnt(0)
	v_lshlrev_b32_e32 v162, 16, v196
	v_and_b32_e32 v163, 0xffff0000, v196
	v_lshlrev_b32_e32 v154, 16, v197
	v_and_b32_e32 v155, 0xffff0000, v197
	v_lshlrev_b32_e32 v164, 16, v198
	v_and_b32_e32 v165, 0xffff0000, v198
	v_lshlrev_b32_e32 v156, 16, v199
	v_and_b32_e32 v157, 0xffff0000, v199
	v_lshlrev_b32_e32 v166, 16, v200
	v_and_b32_e32 v167, 0xffff0000, v200
	v_lshlrev_b32_e32 v158, 16, v201
	v_and_b32_e32 v159, 0xffff0000, v201
	v_lshlrev_b32_e32 v168, 16, v202
	v_and_b32_e32 v169, 0xffff0000, v202
	v_lshlrev_b32_e32 v160, 16, v203
	v_and_b32_e32 v161, 0xffff0000, v203
	v_pk_fma_f32 v[14:15], v[14:15], v[138:139], v[154:155]
	v_pk_fma_f32 v[12:13], v[12:13], v[136:137], v[162:163]
	v_pk_fma_f32 v[10:11], v[10:11], v[142:143], v[156:157]
	v_pk_fma_f32 v[8:9], v[8:9], v[140:141], v[164:165]
	v_pk_fma_f32 v[6:7], v[6:7], v[134:135], v[158:159]
	v_pk_fma_f32 v[4:5], v[4:5], v[132:133], v[166:167]
	v_pk_fma_f32 v[2:3], v[2:3], v[130:131], v[160:161]
	v_pk_fma_f32 v[0:1], v[0:1], v[128:129], v[168:169]
	v_lshl_add_u32 v128, v146, 4, s0
	s_and_saveexec_b64 s[0:1], vcc
	s_cbranch_execz .LBB0_3798
	s_waitcnt lgkmcnt(0)
	v_add_f32_e32 v129, v150, v151
	ds_write_b32 v128, v129

;     __device__ __forceinline__ void fused(f32x4 (&acc)[2][2][4][2], const Unit& un, int wr, int wc, int fr, int fq, PG8_LAS unsigned char* lds, int wid, int lane) const {
;     ...
;         asm volatile("s_waitcnt lgkmcnt(0)" ::: "memory"); __builtin_amdgcn_s_barrier(); asm volatile("" ::: "memory");
;         const int row = wid * 32 + (lane & 31);
;         if (lane < 32) { const float tot = (P[row * 4 + 0] + P[row * 4 + 1]) + (P[row * 4 + 2] + P[row * 4 + 3]);
;             __hip_atomic_store(xbuf + ((size_t)(un.pm * BM + row) * 8 + un.pn), __float_as_uint(tot), __ATOMIC_RELAXED, __HIP_MEMORY_SCOPE_AGENT); }
.LBB0_3812:
	s_or_b64 exec, exec, s[0:1]
	v_readlane_b32 s12, v254, 43
	v_readlane_b32 s14, v254, 45
	v_readlane_b32 s13, v254, 44
	v_readlane_b32 s15, v254, 46
	s_add_u32 s12, s14, 0x3c7c0000
	s_addc_u32 s13, s15, 0
	s_lshl_b32 s0, s23, 5
	s_waitcnt lgkmcnt(0)
	s_barrier
	v_and_or_b32 v134, v152, 31, s0
	v_add_u32_e32 v128, s20, v134
	v_cmp_gt_u32_e64 s[0:1], 32, v147
	v_ashrrev_i32_e32 v129, 31, v128
	s_and_saveexec_b64 s[4:5], s[0:1]
	s_cbranch_execz .LBB0_3814
	s_waitcnt lgkmcnt(0)
	v_lshl_add_u32 v130, v134, 4, 0
	ds_read_b128 v[130:133], v130
	v_lshlrev_b64 v[136:137], 5, v[128:129]
	v_lshl_add_u64 v[136:137], s[12:13], 0, v[136:137]
	s_waitcnt lgkmcnt(0)
	v_mov_b32_e32 v138, v131
	v_mov_b32_e32 v139, v132
	v_mov_b32_e32 v131, v133
	v_pk_add_f32 v[130:131], v[138:139], v[130:131]
	v_lshl_add_u64 v[132:133], s[2:3], 2, v[136:137]
	v_pk_add_f32 v[130:131], v[130:131], v[130:131] op_sel:[0,1] op_sel_hi:[1,0]
	global_store_dword v[132:133], v130, off sc1

;     __device__ __forceinline__ void fused(f32x4 (&acc)[2][2][4][2], const Unit& un, int wr, int wc, int fr, int fq, PG8_LAS unsigned char* lds, int wid, int lane) const {
;     ...
;         if (wid == 0) {
;             bool dead = false; const unsigned long long t0 = __builtin_amdgcn_s_memrealtime();
;             for (;;) {
;                 if ((unsigned)__builtin_amdgcn_readfirstlane(__hip_atomic_load(cnt + 64 * un.pm, __ATOMIC_RELAXED, __HIP_MEMORY_SCOPE_AGENT)) >= 64u) break;
;                 if (__builtin_amdgcn_s_memrealtime() - t0 > 2000000ull) {
;                     if (lane == 0) { unsigned expect = 0u; __hip_atomic_compare_exchange_strong(tmo + 1, &expect, code | (unsigned)(un.pm & 0xff), __ATOMIC_RELAXED, __ATOMIC_RELAXED, __HIP_MEMORY_SCOPE_AGENT);
;                                      __hip_atomic_store(tmo, 1u, __ATOMIC_RELAXED, __HIP_MEMORY_SCOPE_AGENT); }
;                     dead = true; break; }
;                 __builtin_amdgcn_s_sleep(2);
;             }
.LBB0_3820:
	global_load_dword v135, v[130:131], off sc1
	s_mov_b64 s[16:17], -1
	s_mov_b64 s[18:19], -1
	s_waitcnt vmcnt(0) lgkmcnt(0)
	v_readfirstlane_b32 s9, v135
	s_cmp_gt_u32 s9, 63
	s_cbranch_scc1 .LBB0_3819
	s_memrealtime s[16:17]
	s_waitcnt lgkmcnt(0)
	s_sub_u32 s16, s16, s14
	s_subb_u32 s17, s17, s15
	v_cmp_lt_u64_e32 vcc, s[16:17], v[132:133]
	s_cbranch_vccz .LBB0_3818
	s_mov_b64 s[18:19], 0
	s_sleep 2
	s_branch .LBB0_3818

;     __device__ __forceinline__ void fused(f32x4 (&acc)[2][2][4][2], const Unit& un, int wr, int wc, int fr, int fq, PG8_LAS unsigned char* lds, int wid, int lane) const {
;     ...
;                 if (__builtin_amdgcn_s_memrealtime() - t0 > 2000000ull) {
;                     if (lane == 0) { unsigned expect = 0u; __hip_atomic_compare_exchange_strong(tmo + 1, &expect, code | (unsigned)(un.pm & 0xff), __ATOMIC_RELAXED, __ATOMIC_RELAXED, __HIP_MEMORY_SCOPE_AGENT);
;                                      __hip_atomic_store(tmo, 1u, __ATOMIC_RELAXED, __HIP_MEMORY_SCOPE_AGENT); }
;                     dead = true; break; }
.LBB0_3826:
	s_or_saveexec_b64 s[14:15], s[4:5]
	s_mov_b64 s[4:5], 0
	s_xor_b64 exec, exec, s[14:15]
	s_cbranch_execz .LBB0_3828
	s_and_b32 s8, s8, 0x8f
	v_readlane_b32 s16, v254, 43
	s_or_b32 s8, s8, 0x770
	v_readlane_b32 s18, v254, 45
	v_readlane_b32 s19, v254, 46
	v_mov_b32_e32 v130, s8
	v_mov_b32_e32 v131, 0
	v_mov_b64_e32 v[132:133], s[18:19]
	flat_atomic_cmpswap v[132:133], v[130:131] offset:4
	s_mov_b64 s[4:5], exec
	v_mov_b32_e32 v130, 1
	v_readlane_b32 s17, v254, 44
	global_store_dword v[132:133], v130, off sc1

;     __device__ __forceinline__ void fused(f32x4 (&acc)[2][2][4][2], const Unit& un, int wr, int wc, int fr, int fq, PG8_LAS unsigned char* lds, int wid, int lane) const {
;     ...
;         asm volatile("s_waitcnt vmcnt(0) lgkmcnt(0)" ::: "memory"); __builtin_amdgcn_s_barrier(); asm volatile("" ::: "memory");
;         const bool bad = flag[0] != 0u;
;         if (lane < 32) { const unsigned* slot = xbuf + (size_t)(un.pm * BM + row) * 8; float q = 0.f;
; #pragma unroll
;             for (int t = 0; t < 8; ++t) q += __uint_as_float(__hip_atomic_load(slot + t, __ATOMIC_RELAXED, __HIP_MEMORY_SCOPE_AGENT));
;             S[row] = 1.0f / sqrtf(q * (1.0f / 2048.0f) + eps); }
.LBB0_3834:
	s_waitcnt vmcnt(0) lgkmcnt(0)
	s_barrier
	s_waitcnt lgkmcnt(0)
	v_mov_b32_e32 v130, 0
	ds_read_b32 v149, v130 offset:5120
	s_and_saveexec_b64 s[2:3], s[0:1]
	s_cbranch_execz .LBB0_3836
	v_lshlrev_b64 v[128:129], 5, v[128:129]
	v_lshl_add_u64 v[128:129], s[12:13], 0, v[128:129]
	global_load_dword v130, v[128:129], off sc1
	global_load_dword v131, v[128:129], off offset:4 sc1
	global_load_dword v132, v[128:129], off offset:8 sc1
	global_load_dword v133, v[128:129], off offset:12 sc1
	global_load_dword v135, v[128:129], off offset:16 sc1
	global_load_dword v136, v[128:129], off offset:20 sc1
	global_load_dword v137, v[128:129], off offset:24 sc1
	s_nop 0
	global_load_dword v128, v[128:129], off offset:28 sc1
	v_mov_b32_e32 v129, 0x358637bd
	s_mov_b32 s0, 0xf800000
	s_waitcnt vmcnt(0) lgkmcnt(0)
	v_add_f32_e32 v130, 0, v130
	v_add_f32_e32 v130, v130, v131
	v_add_f32_e32 v130, v130, v132
	v_add_f32_e32 v130, v130, v133
	v_add_f32_e32 v130, v130, v135
	v_add_f32_e32 v130, v130, v136
	v_add_f32_e32 v130, v130, v137
	v_add_f32_e32 v128, v130, v128
	v_fmac_f32_e32 v129, 0x3a000000, v128
	v_mul_f32_e32 v128, 0x4f800000, v129
	v_cmp_gt_f32_e32 vcc, s0, v129
	v_mov_b32_e32 v130, 0x260
	s_nop 0
	v_cndmask_b32_e32 v128, v129, v128, vcc
	v_sqrt_f32_e32 v129, v128
	s_nop 0
	v_add_u32_e32 v131, -1, v129
	v_add_u32_e32 v132, 1, v129
	v_fma_f32 v133, -v131, v129, v128
	v_fma_f32 v135, -v132, v129, v128
	v_cmp_ge_f32_e64 s[0:1], 0, v133
	s_nop 1
	v_cndmask_b32_e64 v129, v129, v131, s[0:1]
	v_cmp_lt_f32_e64 s[0:1], 0, v135
	s_nop 1
	v_cndmask_b32_e64 v129, v129, v132, s[0:1]
	v_mul_f32_e32 v131, 0x37800000, v129
	v_cndmask_b32_e32 v129, v129, v131, vcc
	v_cmp_class_f32_e32 vcc, v128, v130
	s_nop 1
	v_cndmask_b32_e32 v128, v129, v128, vcc
	v_div_scale_f32 v129, s[0:1], v128, v128, 1.0
	v_rcp_f32_e32 v130, v129
	v_div_scale_f32 v131, vcc, 1.0, v128, 1.0
	v_fma_f32 v132, -v129, v130, 1.0
	v_fmac_f32_e32 v130, v132, v130
	v_mul_f32_e32 v132, v131, v130
	v_fma_f32 v133, -v129, v132, v131
	v_fmac_f32_e32 v132, v133, v130
	v_fma_f32 v129, -v129, v132, v131
	v_div_fmas_f32 v129, v129, v130, v132
	v_div_fixup_f32 v128, v129, v128, 1.0
	v_lshl_add_u32 v129, v134, 2, 0
	ds_write_b32 v129, v128 offset:4096
